# same as previous best, with the original hipcc blocks kept as a fallback path for gridDim.x != 256
# baseline (speedup 1.0000x reference)
; __device__ __forceinline__ float bf_lo(unsigned w) { return __uint_as_float(w << 16); }
; __device__ __forceinline__ float bf_hi(unsigned w) { return __uint_as_float(w & 0xffff0000u); }
; template <bool BF> __device__ __forceinline__ void prep_rows(const float* xp, const float* xs, const bf16* hb, const float* g, const float* MOD, int shoff, int scoff, bf16* U, int gw, int NGW, int lane) {
;     constexpr int R = 4;
;     for (int mb = gw; mb < MT; mb += R * NGW) {
;         f32x4 v[R][4]; float s[R];
; #pragma unroll
;         for (int r = 0; r < R; ++r) { const int m = mb + r * NGW; const int mc = m < MT ? m : mb;
; #pragma unroll
;             for (int j = 0; j < 4; ++j) {
;                 if (BF) { const v2u a0 = *(const v2u*)(hb + (size_t)mc * DM + 4 * lane + 256 * j);
;                     v[r][j].x = pg8::bf_lo(a0.x); v[r][j].y = pg8::bf_hi(a0.x); v[r][j].z = pg8::bf_lo(a0.y); v[r][j].w = pg8::bf_hi(a0.y); }
;                 else { const float* xr = mc < MP ? xp + (size_t)mc * DM : xs + (size_t)(mc - MP) * DM; v[r][j] = *(const f32x4*)(xr + 4 * lane + 256 * j); } } }
.LBB0_106:
	s_cmp_lt_i32 s78, 2
	s_cselect_b64 s[2:3], -1, 0
	s_and_b64 s[12:13], s[2:3], s[0:1]
	s_andn2_b64 vcc, exec, s[12:13]
	s_cbranch_vccnz .LBB0_122
	s_mov_b64 s[2:3], s[72:73]
	s_load_dwordx2 s[0:1], s[2:3], 0x90
	s_load_dwordx2 s[4:5], s[2:3], 0xe8
	v_mov_b32_e32 v0, v254
	s_lshl_b32 s33, s96, 3
	v_readfirstlane_b32 s44, v0
	s_ashr_i32 s43, s44, 6
	s_add_i32 s42, s43, s33
	s_cmp_gt_i32 s42, 0x17fff
	v_and_b32_e32 v94, 63, v0
	s_cbranch_scc1 .LBB0_116
	s_cmp_eq_u32 s70, 0x100
	s_cbranch_scc0 .Lorig_prep1
	s_load_dwordx2 s[6:7], s[72:73], 0x38
	s_load_dwordx2 s[10:11], s[72:73], 0x0
	s_load_dwordx2 s[14:15], s[72:73], 0x8
	s_load_dwordx2 s[8:9], s[72:73], 0xe8
	v_and_b32_e32 v82, 63, v254
	v_lshlrev_b32_e32 v80, 5, v82
	v_add_u32_e32 v81, 0x1000, v80
	v_xor_b32_e32 v83, 1, v82
	v_xor_b32_e32 v84, 2, v82
	v_xor_b32_e32 v85, 4, v82
	v_xor_b32_e32 v86, 8, v82
	v_xor_b32_e32 v87, 16, v82
	v_xor_b32_e32 v88, 32, v82
	v_lshlrev_b32_e32 v83, 2, v83
	v_lshlrev_b32_e32 v84, 2, v84
	v_lshlrev_b32_e32 v85, 2, v85
	v_lshlrev_b32_e32 v86, 2, v86
	v_lshlrev_b32_e32 v87, 2, v87
	v_lshlrev_b32_e32 v88, 2, v88
	v_lshlrev_b32_e32 v82, 4, v82
	v_mov_b32_e32 v89, 0x358637bd
	v_mov_b32_e32 v90, 0x260
	s_mov_b32 s54, 0xf800000
	v_readfirstlane_b32 s45, v254
	s_nop 3
	s_lshl_b32 s50, s96, 3
	s_lshr_b32 s45, s45, 6
	s_add_i32 s45, s45, s50
	s_waitcnt lgkmcnt(0)
	s_lshl_b32 s50, s45, 12
	s_add_u32 s16, s10, s50
	s_addc_u32 s17, s11, 0
	s_add_u32 s18, s14, s50
	s_addc_u32 s19, s15, 0
	s_lshl_b32 s50, s45, 11
	s_add_u32 s20, s8, s50
	s_addc_u32 s21, s9, 0
	s_add_u32 s20, s20, 0x3000000
	s_addc_u32 s21, s21, 0
	global_load_dwordx4 v[64:67], v80, s[6:7] offset:0
	global_load_dwordx4 v[68:71], v80, s[6:7] offset:16
	global_load_dwordx4 v[72:75], v80, s[6:7] offset:2048
	global_load_dwordx4 v[76:79], v80, s[6:7] offset:2064
	s_mov_b64 s[24:25], s[16:17]
	s_add_u32 s26, s16, 0x800000
	s_addc_u32 s27, s17, 0
	s_add_u32 s28, s16, 0x1000000
	s_addc_u32 s29, s17, 0
	s_add_u32 s30, s16, 0x1800000
	s_addc_u32 s31, s17, 0
	global_load_dwordx4 v[0:3], v80, s[24:25] offset:0
	global_load_dwordx4 v[4:7], v80, s[24:25] offset:16
	global_load_dwordx4 v[8:11], v80, s[24:25] offset:2048
	global_load_dwordx4 v[12:15], v80, s[24:25] offset:2064
	global_load_dwordx4 v[16:19], v80, s[26:27] offset:0
	global_load_dwordx4 v[20:23], v80, s[26:27] offset:16
	global_load_dwordx4 v[24:27], v80, s[26:27] offset:2048
	global_load_dwordx4 v[28:31], v80, s[26:27] offset:2064
	global_load_dwordx4 v[32:35], v80, s[28:29] offset:0
	global_load_dwordx4 v[36:39], v80, s[28:29] offset:16
	global_load_dwordx4 v[40:43], v80, s[28:29] offset:2048
	global_load_dwordx4 v[44:47], v80, s[28:29] offset:2064
	global_load_dwordx4 v[48:51], v80, s[30:31] offset:0
	global_load_dwordx4 v[52:55], v80, s[30:31] offset:16
	global_load_dwordx4 v[56:59], v80, s[30:31] offset:2048
	global_load_dwordx4 v[60:63], v80, s[30:31] offset:2064
	s_mov_b64 s[34:35], s[8:9]
	s_mov_b64 s[36:37], s[8:9]
	global_load_dwordx4 v[176:179], v80, s[34:35] offset:0
	global_load_dwordx4 v[180:183], v80, s[34:35] offset:16
	global_load_dwordx4 v[184:187], v80, s[34:35] offset:2048
	global_load_dwordx4 v[188:191], v80, s[34:35] offset:2064
	global_load_dwordx4 v[160:163], v81, s[34:35] offset:0
	global_load_dwordx4 v[164:167], v81, s[34:35] offset:16
	global_load_dwordx4 v[168:171], v81, s[34:35] offset:2048
	global_load_dwordx4 v[172:175], v81, s[34:35] offset:2064
	global_load_dwordx4 v[208:211], v80, s[36:37] offset:0
	global_load_dwordx4 v[212:215], v80, s[36:37] offset:16
	global_load_dwordx4 v[216:219], v80, s[36:37] offset:2048
	global_load_dwordx4 v[220:223], v80, s[36:37] offset:2064
	global_load_dwordx4 v[192:195], v81, s[36:37] offset:0
	global_load_dwordx4 v[196:199], v81, s[36:37] offset:16
	global_load_dwordx4 v[200:203], v81, s[36:37] offset:2048
	global_load_dwordx4 v[204:207], v81, s[36:37] offset:2064
	s_add_u32 s24, s16, 0x2000000
	s_addc_u32 s25, s17, 0
	s_add_u32 s26, s16, 0x2800000
	s_addc_u32 s27, s17, 0
	s_add_u32 s28, s16, 0x3000000
	s_addc_u32 s29, s17, 0
	s_add_u32 s30, s16, 0x3800000
	s_addc_u32 s31, s17, 0
	global_load_dwordx4 v[96:99], v80, s[24:25] offset:0
	global_load_dwordx4 v[100:103], v80, s[24:25] offset:16
	global_load_dwordx4 v[104:107], v80, s[24:25] offset:2048
	global_load_dwordx4 v[108:111], v80, s[24:25] offset:2064
	global_load_dwordx4 v[112:115], v80, s[26:27] offset:0
	global_load_dwordx4 v[116:119], v80, s[26:27] offset:16
	global_load_dwordx4 v[120:123], v80, s[26:27] offset:2048
	global_load_dwordx4 v[124:127], v80, s[26:27] offset:2064
	global_load_dwordx4 v[128:131], v80, s[28:29] offset:0
	global_load_dwordx4 v[132:135], v80, s[28:29] offset:16
	global_load_dwordx4 v[136:139], v80, s[28:29] offset:2048
	global_load_dwordx4 v[140:143], v80, s[28:29] offset:2064
	global_load_dwordx4 v[144:147], v80, s[30:31] offset:0
	global_load_dwordx4 v[148:151], v80, s[30:31] offset:16
	global_load_dwordx4 v[152:155], v80, s[30:31] offset:2048
	global_load_dwordx4 v[156:159], v80, s[30:31] offset:2064
	s_waitcnt vmcnt(32)
; template <bool BF> __device__ __forceinline__ void prep_rows(const float* xp, const float* xs, const bf16* hb, const float* g, const float* MOD, int shoff, int scoff, bf16* U, int gw, int NGW, int lane) {
;     ...
; #pragma unroll
;         for (int r = 0; r < R; ++r) { float t = 0.f;
; #pragma unroll
;             for (int j = 0; j < 4; ++j) t += (v[r][j].x * v[r][j].x + v[r][j].y * v[r][j].y) + (v[r][j].z * v[r][j].z + v[r][j].w * v[r][j].w);
;             s[r] = t; }
; #pragma unroll
;         for (int o = 1; o < 64; o <<= 1) {
; #pragma unroll
;             for (int r = 0; r < R; ++r) s[r] += __shfl_xor(s[r], o); }
; #pragma unroll
;         for (int r = 0; r < R; ++r) { const int m = mb + r * NGW; if (m < MT) {
;             const float rstd = 1.0f / sqrtf(s[r] * (1.0f / DM) + RMS_EPS);
	v_pk_mul_f32 v[240:241], v[0:1], v[0:1]
	v_pk_mul_f32 v[242:243], v[16:17], v[16:17]
	v_pk_mul_f32 v[244:245], v[32:33], v[32:33]
	v_pk_mul_f32 v[246:247], v[48:49], v[48:49]
	v_pk_fma_f32 v[240:241], v[2:3], v[2:3], v[240:241]
	v_pk_fma_f32 v[242:243], v[18:19], v[18:19], v[242:243]
	v_pk_fma_f32 v[244:245], v[34:35], v[34:35], v[244:245]
	v_pk_fma_f32 v[246:247], v[50:51], v[50:51], v[246:247]
	v_pk_fma_f32 v[240:241], v[4:5], v[4:5], v[240:241]
	v_pk_fma_f32 v[242:243], v[20:21], v[20:21], v[242:243]
	v_pk_fma_f32 v[244:245], v[36:37], v[36:37], v[244:245]
	v_pk_fma_f32 v[246:247], v[52:53], v[52:53], v[246:247]
	v_pk_fma_f32 v[240:241], v[6:7], v[6:7], v[240:241]
	v_pk_fma_f32 v[242:243], v[22:23], v[22:23], v[242:243]
	v_pk_fma_f32 v[244:245], v[38:39], v[38:39], v[244:245]
	v_pk_fma_f32 v[246:247], v[54:55], v[54:55], v[246:247]
	v_pk_fma_f32 v[240:241], v[8:9], v[8:9], v[240:241]
	v_pk_fma_f32 v[242:243], v[24:25], v[24:25], v[242:243]
	v_pk_fma_f32 v[244:245], v[40:41], v[40:41], v[244:245]
	v_pk_fma_f32 v[246:247], v[56:57], v[56:57], v[246:247]
	v_pk_fma_f32 v[240:241], v[10:11], v[10:11], v[240:241]
	v_pk_fma_f32 v[242:243], v[26:27], v[26:27], v[242:243]
	v_pk_fma_f32 v[244:245], v[42:43], v[42:43], v[244:245]
	v_pk_fma_f32 v[246:247], v[58:59], v[58:59], v[246:247]
	v_pk_fma_f32 v[240:241], v[12:13], v[12:13], v[240:241]
	v_pk_fma_f32 v[242:243], v[28:29], v[28:29], v[242:243]
	v_pk_fma_f32 v[244:245], v[44:45], v[44:45], v[244:245]
	v_pk_fma_f32 v[246:247], v[60:61], v[60:61], v[246:247]
	v_pk_fma_f32 v[240:241], v[14:15], v[14:15], v[240:241]
	v_pk_fma_f32 v[242:243], v[30:31], v[30:31], v[242:243]
	v_pk_fma_f32 v[244:245], v[46:47], v[46:47], v[244:245]
	v_pk_fma_f32 v[246:247], v[62:63], v[62:63], v[246:247]
	v_add_f32_e32 v224, v240, v241
	v_add_f32_e32 v225, v242, v243
	v_add_f32_e32 v226, v244, v245
	v_add_f32_e32 v227, v246, v247
	ds_bpermute_b32 v228, v83, v224
	ds_bpermute_b32 v229, v83, v225
	ds_bpermute_b32 v230, v83, v226
	ds_bpermute_b32 v231, v83, v227
	s_waitcnt lgkmcnt(0)
	v_add_f32_e32 v224, v224, v228
	v_add_f32_e32 v225, v225, v229
	v_add_f32_e32 v226, v226, v230
	v_add_f32_e32 v227, v227, v231
	ds_bpermute_b32 v228, v84, v224
	ds_bpermute_b32 v229, v84, v225
	ds_bpermute_b32 v230, v84, v226
	ds_bpermute_b32 v231, v84, v227
	s_waitcnt lgkmcnt(0)
	v_add_f32_e32 v224, v224, v228
	v_add_f32_e32 v225, v225, v229
	v_add_f32_e32 v226, v226, v230
	v_add_f32_e32 v227, v227, v231
	ds_bpermute_b32 v228, v85, v224
	ds_bpermute_b32 v229, v85, v225
	ds_bpermute_b32 v230, v85, v226
	ds_bpermute_b32 v231, v85, v227
	s_waitcnt lgkmcnt(0)
	v_add_f32_e32 v224, v224, v228
	v_add_f32_e32 v225, v225, v229
	v_add_f32_e32 v226, v226, v230
	v_add_f32_e32 v227, v227, v231
	ds_bpermute_b32 v228, v86, v224
	ds_bpermute_b32 v229, v86, v225
	ds_bpermute_b32 v230, v86, v226
	ds_bpermute_b32 v231, v86, v227
	s_waitcnt lgkmcnt(0)
	v_add_f32_e32 v224, v224, v228
	v_add_f32_e32 v225, v225, v229
	v_add_f32_e32 v226, v226, v230
	v_add_f32_e32 v227, v227, v231
	ds_bpermute_b32 v228, v87, v224
	ds_bpermute_b32 v229, v87, v225
	ds_bpermute_b32 v230, v87, v226
	ds_bpermute_b32 v231, v87, v227
	s_waitcnt lgkmcnt(0)
	v_add_f32_e32 v224, v224, v228
	v_add_f32_e32 v225, v225, v229
	v_add_f32_e32 v226, v226, v230
	v_add_f32_e32 v227, v227, v231
	ds_bpermute_b32 v228, v88, v224
	ds_bpermute_b32 v229, v88, v225
	ds_bpermute_b32 v230, v88, v226
	ds_bpermute_b32 v231, v88, v227
	s_waitcnt lgkmcnt(0)
	v_add_f32_e32 v224, v224, v228
	v_add_f32_e32 v225, v225, v229
	v_add_f32_e32 v226, v226, v230
	v_add_f32_e32 v227, v227, v231
	v_fmamk_f32 v240, v224, 0x3a800000, v89
	v_mul_f32_e32 v241, 0x4f800000, v240
	v_cmp_gt_f32_e32 vcc, s54, v240
	s_nop 1
	v_cndmask_b32_e32 v247, v240, v241, vcc
	v_sqrt_f32_e32 v242, v247
	s_nop 1
	v_add_u32_e32 v243, -1, v242
	v_add_u32_e32 v244, 1, v242
	v_fma_f32 v245, -v243, v242, v247
	v_fma_f32 v246, -v244, v242, v247
	v_cmp_ge_f32_e64 s[52:53], 0, v245
	s_nop 1
	v_cndmask_b32_e64 v242, v242, v243, s[52:53]
	v_cmp_lt_f32_e64 s[52:53], 0, v246
	s_nop 1
	v_cndmask_b32_e64 v242, v242, v244, s[52:53]
	v_mul_f32_e32 v243, 0x37800000, v242
	v_cndmask_b32_e32 v242, v242, v243, vcc
	v_cmp_class_f32_e32 vcc, v247, v90
	s_nop 1
	v_cndmask_b32_e32 v247, v242, v247, vcc
	v_div_scale_f32 v248, s[52:53], v247, v247, 1.0
	v_rcp_f32_e32 v249, v248
	v_div_scale_f32 v228, vcc, 1.0, v247, 1.0
	s_nop 0
	v_fma_f32 v229, -v248, v249, 1.0
	v_fmac_f32_e32 v249, v229, v249
	v_mul_f32_e32 v230, v228, v249
	v_fma_f32 v229, -v248, v230, v228
	v_fmac_f32_e32 v230, v229, v249
	v_fma_f32 v248, -v248, v230, v228
	v_div_fmas_f32 v248, v248, v249, v230
	v_div_fixup_f32 v232, v248, v247, 1.0
	v_fmamk_f32 v240, v225, 0x3a800000, v89
	v_mul_f32_e32 v241, 0x4f800000, v240
	v_cmp_gt_f32_e32 vcc, s54, v240
	s_nop 1
	v_cndmask_b32_e32 v247, v240, v241, vcc
	v_sqrt_f32_e32 v242, v247
	s_nop 1
	v_add_u32_e32 v243, -1, v242
	v_add_u32_e32 v244, 1, v242
	v_fma_f32 v245, -v243, v242, v247
	v_fma_f32 v246, -v244, v242, v247
	v_cmp_ge_f32_e64 s[52:53], 0, v245
	s_nop 1
	v_cndmask_b32_e64 v242, v242, v243, s[52:53]
	v_cmp_lt_f32_e64 s[52:53], 0, v246
	s_nop 1
	v_cndmask_b32_e64 v242, v242, v244, s[52:53]
	v_mul_f32_e32 v243, 0x37800000, v242
	v_cndmask_b32_e32 v242, v242, v243, vcc
	v_cmp_class_f32_e32 vcc, v247, v90
	s_nop 1
	v_cndmask_b32_e32 v247, v242, v247, vcc
	v_div_scale_f32 v248, s[52:53], v247, v247, 1.0
	v_rcp_f32_e32 v249, v248
	v_div_scale_f32 v228, vcc, 1.0, v247, 1.0
	s_nop 0
	v_fma_f32 v229, -v248, v249, 1.0
	v_fmac_f32_e32 v249, v229, v249
	v_mul_f32_e32 v230, v228, v249
	v_fma_f32 v229, -v248, v230, v228
	v_fmac_f32_e32 v230, v229, v249
; __device__ __forceinline__ unsigned pk2(float lo, float hi) { return pg8::cvt_pk_bf16(lo, hi); }
; template <bool BF> __device__ __forceinline__ void prep_rows(const float* xp, const float* xs, const bf16* hb, const float* g, const float* MOD, int shoff, int scoff, bf16* U, int gw, int NGW, int lane) {
;     ...
;             const float rstd = 1.0f / sqrtf(s[r] * (1.0f / DM) + RMS_EPS);
;             const float* mr = MOD + (size_t)(m < MP ? (m >> 13) : 8 + ((m - MP) >> 12)) * 6144;
; #pragma unroll
;             for (int j = 0; j < 4; ++j) { const int c = 4 * lane + 256 * j;
;                 const f32x4 gg = *(const f32x4*)(g + c), sc = *(const f32x4*)(mr + scoff + c), sh = *(const f32x4*)(mr + shoff + c);
;                 const f32x4 o = v[r][j] * rstd * gg * (sc + 1.0f) + sh; v2u w; w.x = pk2(o.x, o.y); w.y = pk2(o.z, o.w); *(v2u*)(U + (size_t)m * DM + c) = w; } } }
	v_fma_f32 v248, -v248, v230, v228
	v_div_fmas_f32 v248, v248, v249, v230
	v_div_fixup_f32 v234, v248, v247, 1.0
	v_fmamk_f32 v240, v226, 0x3a800000, v89
	v_mul_f32_e32 v241, 0x4f800000, v240
	v_cmp_gt_f32_e32 vcc, s54, v240
	s_nop 1
	v_cndmask_b32_e32 v247, v240, v241, vcc
	v_sqrt_f32_e32 v242, v247
	s_nop 1
	v_add_u32_e32 v243, -1, v242
	v_add_u32_e32 v244, 1, v242
	v_fma_f32 v245, -v243, v242, v247
	v_fma_f32 v246, -v244, v242, v247
	v_cmp_ge_f32_e64 s[52:53], 0, v245
	s_nop 1
	v_cndmask_b32_e64 v242, v242, v243, s[52:53]
	v_cmp_lt_f32_e64 s[52:53], 0, v246
	s_nop 1
	v_cndmask_b32_e64 v242, v242, v244, s[52:53]
	v_mul_f32_e32 v243, 0x37800000, v242
	v_cndmask_b32_e32 v242, v242, v243, vcc
	v_cmp_class_f32_e32 vcc, v247, v90
	s_nop 1
	v_cndmask_b32_e32 v247, v242, v247, vcc
	v_div_scale_f32 v248, s[52:53], v247, v247, 1.0
	v_rcp_f32_e32 v249, v248
	v_div_scale_f32 v228, vcc, 1.0, v247, 1.0
	s_nop 0
	v_fma_f32 v229, -v248, v249, 1.0
	v_fmac_f32_e32 v249, v229, v249
	v_mul_f32_e32 v230, v228, v249
	v_fma_f32 v229, -v248, v230, v228
	v_fmac_f32_e32 v230, v229, v249
	v_fma_f32 v248, -v248, v230, v228
	v_div_fmas_f32 v248, v248, v249, v230
	v_div_fixup_f32 v236, v248, v247, 1.0
	v_fmamk_f32 v240, v227, 0x3a800000, v89
	v_mul_f32_e32 v241, 0x4f800000, v240
	v_cmp_gt_f32_e32 vcc, s54, v240
	s_nop 1
	v_cndmask_b32_e32 v247, v240, v241, vcc
	v_sqrt_f32_e32 v242, v247
	s_nop 1
	v_add_u32_e32 v243, -1, v242
	v_add_u32_e32 v244, 1, v242
	v_fma_f32 v245, -v243, v242, v247
	v_fma_f32 v246, -v244, v242, v247
	v_cmp_ge_f32_e64 s[52:53], 0, v245
	s_nop 1
	v_cndmask_b32_e64 v242, v242, v243, s[52:53]
	v_cmp_lt_f32_e64 s[52:53], 0, v246
	s_nop 1
	v_cndmask_b32_e64 v242, v242, v244, s[52:53]
	v_mul_f32_e32 v243, 0x37800000, v242
	v_cndmask_b32_e32 v242, v242, v243, vcc
	v_cmp_class_f32_e32 vcc, v247, v90
	s_nop 1
	v_cndmask_b32_e32 v247, v242, v247, vcc
	v_div_scale_f32 v248, s[52:53], v247, v247, 1.0
	v_rcp_f32_e32 v249, v248
	v_div_scale_f32 v228, vcc, 1.0, v247, 1.0
	s_nop 0
	v_fma_f32 v229, -v248, v249, 1.0
	v_fmac_f32_e32 v249, v229, v249
	v_mul_f32_e32 v230, v228, v249
	v_fma_f32 v229, -v248, v230, v228
	v_fmac_f32_e32 v230, v229, v249
	v_fma_f32 v248, -v248, v230, v228
	v_div_fmas_f32 v248, v248, v249, v230
	v_div_fixup_f32 v238, v248, v247, 1.0
	s_waitcnt vmcnt(16)
	v_pk_add_f32 v[160:161], v[160:161], 1.0 op_sel_hi:[1,0]
	v_pk_add_f32 v[162:163], v[162:163], 1.0 op_sel_hi:[1,0]
	v_pk_add_f32 v[164:165], v[164:165], 1.0 op_sel_hi:[1,0]
	v_pk_add_f32 v[166:167], v[166:167], 1.0 op_sel_hi:[1,0]
	v_pk_add_f32 v[168:169], v[168:169], 1.0 op_sel_hi:[1,0]
	v_pk_add_f32 v[170:171], v[170:171], 1.0 op_sel_hi:[1,0]
	v_pk_add_f32 v[172:173], v[172:173], 1.0 op_sel_hi:[1,0]
	v_pk_add_f32 v[174:175], v[174:175], 1.0 op_sel_hi:[1,0]
	v_pk_add_f32 v[192:193], v[192:193], 1.0 op_sel_hi:[1,0]
	v_pk_add_f32 v[194:195], v[194:195], 1.0 op_sel_hi:[1,0]
	v_pk_add_f32 v[196:197], v[196:197], 1.0 op_sel_hi:[1,0]
	v_pk_add_f32 v[198:199], v[198:199], 1.0 op_sel_hi:[1,0]
	v_pk_add_f32 v[200:201], v[200:201], 1.0 op_sel_hi:[1,0]
	v_pk_add_f32 v[202:203], v[202:203], 1.0 op_sel_hi:[1,0]
	v_pk_add_f32 v[204:205], v[204:205], 1.0 op_sel_hi:[1,0]
	v_pk_add_f32 v[206:207], v[206:207], 1.0 op_sel_hi:[1,0]
	s_mov_b64 s[38:39], s[20:21]
	s_add_u32 s40, s20, 0x400000
	s_addc_u32 s41, s21, 0
	s_add_u32 s46, s20, 0x800000
	s_addc_u32 s47, s21, 0
	s_add_u32 s48, s20, 0xc00000
	s_addc_u32 s49, s21, 0
	v_pk_mul_f32 v[0:1], v[0:1], v[232:233] op_sel_hi:[1,0]
	v_pk_mul_f32 v[2:3], v[2:3], v[232:233] op_sel_hi:[1,0]
	v_pk_mul_f32 v[0:1], v[64:65], v[0:1]
	v_pk_mul_f32 v[2:3], v[66:67], v[2:3]
	v_pk_fma_f32 v[0:1], v[160:161], v[0:1], v[176:177]
	v_pk_fma_f32 v[2:3], v[162:163], v[2:3], v[178:179]
	v_cvt_pk_bf16_f32 v244, v0, v1
	v_cvt_pk_bf16_f32 v245, v2, v3
	v_pk_mul_f32 v[4:5], v[4:5], v[232:233] op_sel_hi:[1,0]
	v_pk_mul_f32 v[6:7], v[6:7], v[232:233] op_sel_hi:[1,0]
	v_pk_mul_f32 v[4:5], v[68:69], v[4:5]
	v_pk_mul_f32 v[6:7], v[70:71], v[6:7]
	v_pk_fma_f32 v[4:5], v[164:165], v[4:5], v[180:181]
	v_pk_fma_f32 v[6:7], v[166:167], v[6:7], v[182:183]
	v_cvt_pk_bf16_f32 v246, v4, v5
	v_cvt_pk_bf16_f32 v247, v6, v7
	global_store_dwordx4 v82, v[244:247], s[38:39] offset:0
	v_pk_mul_f32 v[8:9], v[8:9], v[232:233] op_sel_hi:[1,0]
	v_pk_mul_f32 v[10:11], v[10:11], v[232:233] op_sel_hi:[1,0]
	v_pk_mul_f32 v[8:9], v[72:73], v[8:9]
	v_pk_mul_f32 v[10:11], v[74:75], v[10:11]
	v_pk_fma_f32 v[8:9], v[168:169], v[8:9], v[184:185]
	v_pk_fma_f32 v[10:11], v[170:171], v[10:11], v[186:187]
	v_cvt_pk_bf16_f32 v240, v8, v9
	v_cvt_pk_bf16_f32 v241, v10, v11
	v_pk_mul_f32 v[12:13], v[12:13], v[232:233] op_sel_hi:[1,0]
	v_pk_mul_f32 v[14:15], v[14:15], v[232:233] op_sel_hi:[1,0]
	v_pk_mul_f32 v[12:13], v[76:77], v[12:13]
	v_pk_mul_f32 v[14:15], v[78:79], v[14:15]
	v_pk_fma_f32 v[12:13], v[172:173], v[12:13], v[188:189]
	v_pk_fma_f32 v[14:15], v[174:175], v[14:15], v[190:191]
	v_cvt_pk_bf16_f32 v242, v12, v13
	v_cvt_pk_bf16_f32 v243, v14, v15
	global_store_dwordx4 v82, v[240:243], s[38:39] offset:1024
	v_pk_mul_f32 v[16:17], v[16:17], v[234:235] op_sel_hi:[1,0]
	v_pk_mul_f32 v[18:19], v[18:19], v[234:235] op_sel_hi:[1,0]
	v_pk_mul_f32 v[16:17], v[64:65], v[16:17]
	v_pk_mul_f32 v[18:19], v[66:67], v[18:19]
	v_pk_fma_f32 v[16:17], v[160:161], v[16:17], v[176:177]
	v_pk_fma_f32 v[18:19], v[162:163], v[18:19], v[178:179]
	v_cvt_pk_bf16_f32 v244, v16, v17
	v_cvt_pk_bf16_f32 v245, v18, v19
	v_pk_mul_f32 v[20:21], v[20:21], v[234:235] op_sel_hi:[1,0]
	v_pk_mul_f32 v[22:23], v[22:23], v[234:235] op_sel_hi:[1,0]
	v_pk_mul_f32 v[20:21], v[68:69], v[20:21]
	v_pk_mul_f32 v[22:23], v[70:71], v[22:23]
; __device__ __forceinline__ float bf_lo(unsigned w) { return __uint_as_float(w << 16); }
; __device__ __forceinline__ float bf_hi(unsigned w) { return __uint_as_float(w & 0xffff0000u); }
; __device__ __forceinline__ unsigned pk2(float lo, float hi) { return pg8::cvt_pk_bf16(lo, hi); }
; template <bool BF> __device__ __forceinline__ void prep_rows(const float* xp, const float* xs, const bf16* hb, const float* g, const float* MOD, int shoff, int scoff, bf16* U, int gw, int NGW, int lane) {
;     ...
;         for (int r = 0; r < R; ++r) { const int m = mb + r * NGW; const int mc = m < MT ? m : mb;
; #pragma unroll
;             for (int j = 0; j < 4; ++j) {
;                 if (BF) { const v2u a0 = *(const v2u*)(hb + (size_t)mc * DM + 4 * lane + 256 * j);
;                     v[r][j].x = pg8::bf_lo(a0.x); v[r][j].y = pg8::bf_hi(a0.x); v[r][j].z = pg8::bf_lo(a0.y); v[r][j].w = pg8::bf_hi(a0.y); }
;                 else { const float* xr = mc < MP ? xp + (size_t)mc * DM : xs + (size_t)(mc - MP) * DM; v[r][j] = *(const f32x4*)(xr + 4 * lane + 256 * j); } } }
;     ...
;             const float* mr = MOD + (size_t)(m < MP ? (m >> 13) : 8 + ((m - MP) >> 12)) * 6144;
; #pragma unroll
;             for (int j = 0; j < 4; ++j) { const int c = 4 * lane + 256 * j;
;                 const f32x4 gg = *(const f32x4*)(g + c), sc = *(const f32x4*)(mr + scoff + c), sh = *(const f32x4*)(mr + shoff + c);
;                 const f32x4 o = v[r][j] * rstd * gg * (sc + 1.0f) + sh; v2u w; w.x = pk2(o.x, o.y); w.y = pk2(o.z, o.w); *(v2u*)(U + (size_t)m * DM + c) = w; } } }
	v_pk_fma_f32 v[20:21], v[164:165], v[20:21], v[180:181]
	v_pk_fma_f32 v[22:23], v[166:167], v[22:23], v[182:183]
	v_cvt_pk_bf16_f32 v246, v20, v21
	v_cvt_pk_bf16_f32 v247, v22, v23
	global_store_dwordx4 v82, v[244:247], s[40:41] offset:0
	v_pk_mul_f32 v[24:25], v[24:25], v[234:235] op_sel_hi:[1,0]
	v_pk_mul_f32 v[26:27], v[26:27], v[234:235] op_sel_hi:[1,0]
	v_pk_mul_f32 v[24:25], v[72:73], v[24:25]
	v_pk_mul_f32 v[26:27], v[74:75], v[26:27]
	v_pk_fma_f32 v[24:25], v[168:169], v[24:25], v[184:185]
	v_pk_fma_f32 v[26:27], v[170:171], v[26:27], v[186:187]
	v_cvt_pk_bf16_f32 v240, v24, v25
	v_cvt_pk_bf16_f32 v241, v26, v27
	v_pk_mul_f32 v[28:29], v[28:29], v[234:235] op_sel_hi:[1,0]
	v_pk_mul_f32 v[30:31], v[30:31], v[234:235] op_sel_hi:[1,0]
	v_pk_mul_f32 v[28:29], v[76:77], v[28:29]
	v_pk_mul_f32 v[30:31], v[78:79], v[30:31]
	v_pk_fma_f32 v[28:29], v[172:173], v[28:29], v[188:189]
	v_pk_fma_f32 v[30:31], v[174:175], v[30:31], v[190:191]
	v_cvt_pk_bf16_f32 v242, v28, v29
	v_cvt_pk_bf16_f32 v243, v30, v31
	global_store_dwordx4 v82, v[240:243], s[40:41] offset:1024
	v_pk_mul_f32 v[32:33], v[32:33], v[236:237] op_sel_hi:[1,0]
	v_pk_mul_f32 v[34:35], v[34:35], v[236:237] op_sel_hi:[1,0]
	v_pk_mul_f32 v[32:33], v[64:65], v[32:33]
	v_pk_mul_f32 v[34:35], v[66:67], v[34:35]
	v_pk_fma_f32 v[32:33], v[192:193], v[32:33], v[208:209]
	v_pk_fma_f32 v[34:35], v[194:195], v[34:35], v[210:211]
	v_cvt_pk_bf16_f32 v244, v32, v33
	v_cvt_pk_bf16_f32 v245, v34, v35
	v_pk_mul_f32 v[36:37], v[36:37], v[236:237] op_sel_hi:[1,0]
	v_pk_mul_f32 v[38:39], v[38:39], v[236:237] op_sel_hi:[1,0]
	v_pk_mul_f32 v[36:37], v[68:69], v[36:37]
	v_pk_mul_f32 v[38:39], v[70:71], v[38:39]
	v_pk_fma_f32 v[36:37], v[196:197], v[36:37], v[212:213]
	v_pk_fma_f32 v[38:39], v[198:199], v[38:39], v[214:215]
	v_cvt_pk_bf16_f32 v246, v36, v37
	v_cvt_pk_bf16_f32 v247, v38, v39
	global_store_dwordx4 v82, v[244:247], s[46:47] offset:0
	v_pk_mul_f32 v[40:41], v[40:41], v[236:237] op_sel_hi:[1,0]
	v_pk_mul_f32 v[42:43], v[42:43], v[236:237] op_sel_hi:[1,0]
	v_pk_mul_f32 v[40:41], v[72:73], v[40:41]
	v_pk_mul_f32 v[42:43], v[74:75], v[42:43]
	v_pk_fma_f32 v[40:41], v[200:201], v[40:41], v[216:217]
	v_pk_fma_f32 v[42:43], v[202:203], v[42:43], v[218:219]
	v_cvt_pk_bf16_f32 v240, v40, v41
	v_cvt_pk_bf16_f32 v241, v42, v43
	v_pk_mul_f32 v[44:45], v[44:45], v[236:237] op_sel_hi:[1,0]
	v_pk_mul_f32 v[46:47], v[46:47], v[236:237] op_sel_hi:[1,0]
	v_pk_mul_f32 v[44:45], v[76:77], v[44:45]
	v_pk_mul_f32 v[46:47], v[78:79], v[46:47]
	v_pk_fma_f32 v[44:45], v[204:205], v[44:45], v[220:221]
	v_pk_fma_f32 v[46:47], v[206:207], v[46:47], v[222:223]
	v_cvt_pk_bf16_f32 v242, v44, v45
	v_cvt_pk_bf16_f32 v243, v46, v47
	global_store_dwordx4 v82, v[240:243], s[46:47] offset:1024
	v_pk_mul_f32 v[48:49], v[48:49], v[238:239] op_sel_hi:[1,0]
	v_pk_mul_f32 v[50:51], v[50:51], v[238:239] op_sel_hi:[1,0]
	v_pk_mul_f32 v[48:49], v[64:65], v[48:49]
	v_pk_mul_f32 v[50:51], v[66:67], v[50:51]
	v_pk_fma_f32 v[48:49], v[192:193], v[48:49], v[208:209]
	v_pk_fma_f32 v[50:51], v[194:195], v[50:51], v[210:211]
	v_cvt_pk_bf16_f32 v244, v48, v49
	v_cvt_pk_bf16_f32 v245, v50, v51
	v_pk_mul_f32 v[52:53], v[52:53], v[238:239] op_sel_hi:[1,0]
	v_pk_mul_f32 v[54:55], v[54:55], v[238:239] op_sel_hi:[1,0]
	v_pk_mul_f32 v[52:53], v[68:69], v[52:53]
	v_pk_mul_f32 v[54:55], v[70:71], v[54:55]
	v_pk_fma_f32 v[52:53], v[196:197], v[52:53], v[212:213]
	v_pk_fma_f32 v[54:55], v[198:199], v[54:55], v[214:215]
	v_cvt_pk_bf16_f32 v246, v52, v53
	v_cvt_pk_bf16_f32 v247, v54, v55
	global_store_dwordx4 v82, v[244:247], s[48:49] offset:0
	v_pk_mul_f32 v[56:57], v[56:57], v[238:239] op_sel_hi:[1,0]
	v_pk_mul_f32 v[58:59], v[58:59], v[238:239] op_sel_hi:[1,0]
	v_pk_mul_f32 v[56:57], v[72:73], v[56:57]
	v_pk_mul_f32 v[58:59], v[74:75], v[58:59]
	v_pk_fma_f32 v[56:57], v[200:201], v[56:57], v[216:217]
	v_pk_fma_f32 v[58:59], v[202:203], v[58:59], v[218:219]
	v_cvt_pk_bf16_f32 v240, v56, v57
	v_cvt_pk_bf16_f32 v241, v58, v59
	v_pk_mul_f32 v[60:61], v[60:61], v[238:239] op_sel_hi:[1,0]
	v_pk_mul_f32 v[62:63], v[62:63], v[238:239] op_sel_hi:[1,0]
	v_pk_mul_f32 v[60:61], v[76:77], v[60:61]
	v_pk_mul_f32 v[62:63], v[78:79], v[62:63]
	v_pk_fma_f32 v[60:61], v[204:205], v[60:61], v[220:221]
	v_pk_fma_f32 v[62:63], v[206:207], v[62:63], v[222:223]
	v_cvt_pk_bf16_f32 v242, v60, v61
	v_cvt_pk_bf16_f32 v243, v62, v63
	global_store_dwordx4 v82, v[240:243], s[48:49] offset:1024
	s_add_u32 s34, s8, 0x6000
	s_addc_u32 s35, s9, 0
	s_add_u32 s36, s8, 0x6000
	s_addc_u32 s37, s9, 0
	global_load_dwordx4 v[176:179], v80, s[34:35] offset:0
	global_load_dwordx4 v[180:183], v80, s[34:35] offset:16
	global_load_dwordx4 v[184:187], v80, s[34:35] offset:2048
	global_load_dwordx4 v[188:191], v80, s[34:35] offset:2064
	global_load_dwordx4 v[160:163], v81, s[34:35] offset:0
	global_load_dwordx4 v[164:167], v81, s[34:35] offset:16
	global_load_dwordx4 v[168:171], v81, s[34:35] offset:2048
	global_load_dwordx4 v[172:175], v81, s[34:35] offset:2064
	global_load_dwordx4 v[208:211], v80, s[36:37] offset:0
	global_load_dwordx4 v[212:215], v80, s[36:37] offset:16
	global_load_dwordx4 v[216:219], v80, s[36:37] offset:2048
	global_load_dwordx4 v[220:223], v80, s[36:37] offset:2064
	global_load_dwordx4 v[192:195], v81, s[36:37] offset:0
	global_load_dwordx4 v[196:199], v81, s[36:37] offset:16
	global_load_dwordx4 v[200:203], v81, s[36:37] offset:2048
	global_load_dwordx4 v[204:207], v81, s[36:37] offset:2064
	s_add_u32 s24, s16, 0x4000000
	s_addc_u32 s25, s17, 0
	s_add_u32 s26, s16, 0x4800000
	s_addc_u32 s27, s17, 0
	s_add_u32 s28, s16, 0x5000000
	s_addc_u32 s29, s17, 0
	s_add_u32 s30, s16, 0x5800000
	s_addc_u32 s31, s17, 0
	global_load_dwordx4 v[0:3], v80, s[24:25] offset:0
	global_load_dwordx4 v[4:7], v80, s[24:25] offset:16
	global_load_dwordx4 v[8:11], v80, s[24:25] offset:2048
	global_load_dwordx4 v[12:15], v80, s[24:25] offset:2064
	global_load_dwordx4 v[16:19], v80, s[26:27] offset:0
	global_load_dwordx4 v[20:23], v80, s[26:27] offset:16
	global_load_dwordx4 v[24:27], v80, s[26:27] offset:2048
	global_load_dwordx4 v[28:31], v80, s[26:27] offset:2064
	global_load_dwordx4 v[32:35], v80, s[28:29] offset:0
	global_load_dwordx4 v[36:39], v80, s[28:29] offset:16
	global_load_dwordx4 v[40:43], v80, s[28:29] offset:2048
	global_load_dwordx4 v[44:47], v80, s[28:29] offset:2064
	global_load_dwordx4 v[48:51], v80, s[30:31] offset:0
	global_load_dwordx4 v[52:55], v80, s[30:31] offset:16
	global_load_dwordx4 v[56:59], v80, s[30:31] offset:2048
	global_load_dwordx4 v[60:63], v80, s[30:31] offset:2064
	s_waitcnt vmcnt(40)
; template <bool BF> __device__ __forceinline__ void prep_rows(const float* xp, const float* xs, const bf16* hb, const float* g, const float* MOD, int shoff, int scoff, bf16* U, int gw, int NGW, int lane) {
;     ...
;         for (int r = 0; r < R; ++r) { float t = 0.f;
; #pragma unroll
;             for (int j = 0; j < 4; ++j) t += (v[r][j].x * v[r][j].x + v[r][j].y * v[r][j].y) + (v[r][j].z * v[r][j].z + v[r][j].w * v[r][j].w);
;             s[r] = t; }
; #pragma unroll
;         for (int o = 1; o < 64; o <<= 1) {
; #pragma unroll
;             for (int r = 0; r < R; ++r) s[r] += __shfl_xor(s[r], o); }
; #pragma unroll
;         for (int r = 0; r < R; ++r) { const int m = mb + r * NGW; if (m < MT) {
;             const float rstd = 1.0f / sqrtf(s[r] * (1.0f / DM) + RMS_EPS);
	v_pk_mul_f32 v[240:241], v[96:97], v[96:97]
	v_pk_mul_f32 v[242:243], v[112:113], v[112:113]
	v_pk_mul_f32 v[244:245], v[128:129], v[128:129]
	v_pk_mul_f32 v[246:247], v[144:145], v[144:145]
	v_pk_fma_f32 v[240:241], v[98:99], v[98:99], v[240:241]
	v_pk_fma_f32 v[242:243], v[114:115], v[114:115], v[242:243]
	v_pk_fma_f32 v[244:245], v[130:131], v[130:131], v[244:245]
	v_pk_fma_f32 v[246:247], v[146:147], v[146:147], v[246:247]
	v_pk_fma_f32 v[240:241], v[100:101], v[100:101], v[240:241]
	v_pk_fma_f32 v[242:243], v[116:117], v[116:117], v[242:243]
	v_pk_fma_f32 v[244:245], v[132:133], v[132:133], v[244:245]
	v_pk_fma_f32 v[246:247], v[148:149], v[148:149], v[246:247]
	v_pk_fma_f32 v[240:241], v[102:103], v[102:103], v[240:241]
	v_pk_fma_f32 v[242:243], v[118:119], v[118:119], v[242:243]
	v_pk_fma_f32 v[244:245], v[134:135], v[134:135], v[244:245]
	v_pk_fma_f32 v[246:247], v[150:151], v[150:151], v[246:247]
	v_pk_fma_f32 v[240:241], v[104:105], v[104:105], v[240:241]
	v_pk_fma_f32 v[242:243], v[120:121], v[120:121], v[242:243]
	v_pk_fma_f32 v[244:245], v[136:137], v[136:137], v[244:245]
	v_pk_fma_f32 v[246:247], v[152:153], v[152:153], v[246:247]
	v_pk_fma_f32 v[240:241], v[106:107], v[106:107], v[240:241]
	v_pk_fma_f32 v[242:243], v[122:123], v[122:123], v[242:243]
	v_pk_fma_f32 v[244:245], v[138:139], v[138:139], v[244:245]
	v_pk_fma_f32 v[246:247], v[154:155], v[154:155], v[246:247]
	v_pk_fma_f32 v[240:241], v[108:109], v[108:109], v[240:241]
	v_pk_fma_f32 v[242:243], v[124:125], v[124:125], v[242:243]
	v_pk_fma_f32 v[244:245], v[140:141], v[140:141], v[244:245]
	v_pk_fma_f32 v[246:247], v[156:157], v[156:157], v[246:247]
	v_pk_fma_f32 v[240:241], v[110:111], v[110:111], v[240:241]
	v_pk_fma_f32 v[242:243], v[126:127], v[126:127], v[242:243]
	v_pk_fma_f32 v[244:245], v[142:143], v[142:143], v[244:245]
	v_pk_fma_f32 v[246:247], v[158:159], v[158:159], v[246:247]
	v_add_f32_e32 v224, v240, v241
	v_add_f32_e32 v225, v242, v243
	v_add_f32_e32 v226, v244, v245
	v_add_f32_e32 v227, v246, v247
	ds_bpermute_b32 v228, v83, v224
	ds_bpermute_b32 v229, v83, v225
	ds_bpermute_b32 v230, v83, v226
	ds_bpermute_b32 v231, v83, v227
	s_waitcnt lgkmcnt(0)
	v_add_f32_e32 v224, v224, v228
	v_add_f32_e32 v225, v225, v229
	v_add_f32_e32 v226, v226, v230
	v_add_f32_e32 v227, v227, v231
	ds_bpermute_b32 v228, v84, v224
	ds_bpermute_b32 v229, v84, v225
	ds_bpermute_b32 v230, v84, v226
	ds_bpermute_b32 v231, v84, v227
	s_waitcnt lgkmcnt(0)
	v_add_f32_e32 v224, v224, v228
	v_add_f32_e32 v225, v225, v229
	v_add_f32_e32 v226, v226, v230
	v_add_f32_e32 v227, v227, v231
	ds_bpermute_b32 v228, v85, v224
	ds_bpermute_b32 v229, v85, v225
	ds_bpermute_b32 v230, v85, v226
	ds_bpermute_b32 v231, v85, v227
	s_waitcnt lgkmcnt(0)
	v_add_f32_e32 v224, v224, v228
	v_add_f32_e32 v225, v225, v229
	v_add_f32_e32 v226, v226, v230
	v_add_f32_e32 v227, v227, v231
	ds_bpermute_b32 v228, v86, v224
	ds_bpermute_b32 v229, v86, v225
	ds_bpermute_b32 v230, v86, v226
	ds_bpermute_b32 v231, v86, v227
	s_waitcnt lgkmcnt(0)
	v_add_f32_e32 v224, v224, v228
	v_add_f32_e32 v225, v225, v229
	v_add_f32_e32 v226, v226, v230
	v_add_f32_e32 v227, v227, v231
	ds_bpermute_b32 v228, v87, v224
	ds_bpermute_b32 v229, v87, v225
	ds_bpermute_b32 v230, v87, v226
	ds_bpermute_b32 v231, v87, v227
	s_waitcnt lgkmcnt(0)
	v_add_f32_e32 v224, v224, v228
	v_add_f32_e32 v225, v225, v229
	v_add_f32_e32 v226, v226, v230
	v_add_f32_e32 v227, v227, v231
	ds_bpermute_b32 v228, v88, v224
	ds_bpermute_b32 v229, v88, v225
	ds_bpermute_b32 v230, v88, v226
	ds_bpermute_b32 v231, v88, v227
	s_waitcnt lgkmcnt(0)
	v_add_f32_e32 v224, v224, v228
	v_add_f32_e32 v225, v225, v229
	v_add_f32_e32 v226, v226, v230
	v_add_f32_e32 v227, v227, v231
	v_fmamk_f32 v240, v224, 0x3a800000, v89
	v_mul_f32_e32 v241, 0x4f800000, v240
	v_cmp_gt_f32_e32 vcc, s54, v240
	s_nop 1
	v_cndmask_b32_e32 v247, v240, v241, vcc
	v_sqrt_f32_e32 v242, v247
	s_nop 1
	v_add_u32_e32 v243, -1, v242
	v_add_u32_e32 v244, 1, v242
	v_fma_f32 v245, -v243, v242, v247
	v_fma_f32 v246, -v244, v242, v247
	v_cmp_ge_f32_e64 s[52:53], 0, v245
	s_nop 1
	v_cndmask_b32_e64 v242, v242, v243, s[52:53]
	v_cmp_lt_f32_e64 s[52:53], 0, v246
	s_nop 1
	v_cndmask_b32_e64 v242, v242, v244, s[52:53]
	v_mul_f32_e32 v243, 0x37800000, v242
	v_cndmask_b32_e32 v242, v242, v243, vcc
	v_cmp_class_f32_e32 vcc, v247, v90
	s_nop 1
	v_cndmask_b32_e32 v247, v242, v247, vcc
	v_div_scale_f32 v248, s[52:53], v247, v247, 1.0
	v_rcp_f32_e32 v249, v248
	v_div_scale_f32 v228, vcc, 1.0, v247, 1.0
	s_nop 0
	v_fma_f32 v229, -v248, v249, 1.0
	v_fmac_f32_e32 v249, v229, v249
	v_mul_f32_e32 v230, v228, v249
	v_fma_f32 v229, -v248, v230, v228
	v_fmac_f32_e32 v230, v229, v249
	v_fma_f32 v248, -v248, v230, v228
	v_div_fmas_f32 v248, v248, v249, v230
	v_div_fixup_f32 v232, v248, v247, 1.0
	v_fmamk_f32 v240, v225, 0x3a800000, v89
	v_mul_f32_e32 v241, 0x4f800000, v240
	v_cmp_gt_f32_e32 vcc, s54, v240
	s_nop 1
	v_cndmask_b32_e32 v247, v240, v241, vcc
	v_sqrt_f32_e32 v242, v247
	s_nop 1
	v_add_u32_e32 v243, -1, v242
	v_add_u32_e32 v244, 1, v242
	v_fma_f32 v245, -v243, v242, v247
	v_fma_f32 v246, -v244, v242, v247
	v_cmp_ge_f32_e64 s[52:53], 0, v245
	s_nop 1
	v_cndmask_b32_e64 v242, v242, v243, s[52:53]
	v_cmp_lt_f32_e64 s[52:53], 0, v246
	s_nop 1
	v_cndmask_b32_e64 v242, v242, v244, s[52:53]
	v_mul_f32_e32 v243, 0x37800000, v242
	v_cndmask_b32_e32 v242, v242, v243, vcc
	v_cmp_class_f32_e32 vcc, v247, v90
	s_nop 1
	v_cndmask_b32_e32 v247, v242, v247, vcc
	v_div_scale_f32 v248, s[52:53], v247, v247, 1.0
	v_rcp_f32_e32 v249, v248
	v_div_scale_f32 v228, vcc, 1.0, v247, 1.0
	s_nop 0
	v_fma_f32 v229, -v248, v249, 1.0
; __device__ __forceinline__ unsigned pk2(float lo, float hi) { return pg8::cvt_pk_bf16(lo, hi); }
; template <bool BF> __device__ __forceinline__ void prep_rows(const float* xp, const float* xs, const bf16* hb, const float* g, const float* MOD, int shoff, int scoff, bf16* U, int gw, int NGW, int lane) {
;     ...
;             const float rstd = 1.0f / sqrtf(s[r] * (1.0f / DM) + RMS_EPS);
;             const float* mr = MOD + (size_t)(m < MP ? (m >> 13) : 8 + ((m - MP) >> 12)) * 6144;
; #pragma unroll
;             for (int j = 0; j < 4; ++j) { const int c = 4 * lane + 256 * j;
;                 const f32x4 gg = *(const f32x4*)(g + c), sc = *(const f32x4*)(mr + scoff + c), sh = *(const f32x4*)(mr + shoff + c);
;                 const f32x4 o = v[r][j] * rstd * gg * (sc + 1.0f) + sh; v2u w; w.x = pk2(o.x, o.y); w.y = pk2(o.z, o.w); *(v2u*)(U + (size_t)m * DM + c) = w; } } }
	v_fmac_f32_e32 v249, v229, v249
	v_mul_f32_e32 v230, v228, v249
	v_fma_f32 v229, -v248, v230, v228
	v_fmac_f32_e32 v230, v229, v249
	v_fma_f32 v248, -v248, v230, v228
	v_div_fmas_f32 v248, v248, v249, v230
	v_div_fixup_f32 v234, v248, v247, 1.0
	v_fmamk_f32 v240, v226, 0x3a800000, v89
	v_mul_f32_e32 v241, 0x4f800000, v240
	v_cmp_gt_f32_e32 vcc, s54, v240
	s_nop 1
	v_cndmask_b32_e32 v247, v240, v241, vcc
	v_sqrt_f32_e32 v242, v247
	s_nop 1
	v_add_u32_e32 v243, -1, v242
	v_add_u32_e32 v244, 1, v242
	v_fma_f32 v245, -v243, v242, v247
	v_fma_f32 v246, -v244, v242, v247
	v_cmp_ge_f32_e64 s[52:53], 0, v245
	s_nop 1
	v_cndmask_b32_e64 v242, v242, v243, s[52:53]
	v_cmp_lt_f32_e64 s[52:53], 0, v246
	s_nop 1
	v_cndmask_b32_e64 v242, v242, v244, s[52:53]
	v_mul_f32_e32 v243, 0x37800000, v242
	v_cndmask_b32_e32 v242, v242, v243, vcc
	v_cmp_class_f32_e32 vcc, v247, v90
	s_nop 1
	v_cndmask_b32_e32 v247, v242, v247, vcc
	v_div_scale_f32 v248, s[52:53], v247, v247, 1.0
	v_rcp_f32_e32 v249, v248
	v_div_scale_f32 v228, vcc, 1.0, v247, 1.0
	s_nop 0
	v_fma_f32 v229, -v248, v249, 1.0
	v_fmac_f32_e32 v249, v229, v249
	v_mul_f32_e32 v230, v228, v249
	v_fma_f32 v229, -v248, v230, v228
	v_fmac_f32_e32 v230, v229, v249
	v_fma_f32 v248, -v248, v230, v228
	v_div_fmas_f32 v248, v248, v249, v230
	v_div_fixup_f32 v236, v248, v247, 1.0
	v_fmamk_f32 v240, v227, 0x3a800000, v89
	v_mul_f32_e32 v241, 0x4f800000, v240
	v_cmp_gt_f32_e32 vcc, s54, v240
	s_nop 1
	v_cndmask_b32_e32 v247, v240, v241, vcc
	v_sqrt_f32_e32 v242, v247
	s_nop 1
	v_add_u32_e32 v243, -1, v242
	v_add_u32_e32 v244, 1, v242
	v_fma_f32 v245, -v243, v242, v247
	v_fma_f32 v246, -v244, v242, v247
	v_cmp_ge_f32_e64 s[52:53], 0, v245
	s_nop 1
	v_cndmask_b32_e64 v242, v242, v243, s[52:53]
	v_cmp_lt_f32_e64 s[52:53], 0, v246
	s_nop 1
	v_cndmask_b32_e64 v242, v242, v244, s[52:53]
	v_mul_f32_e32 v243, 0x37800000, v242
	v_cndmask_b32_e32 v242, v242, v243, vcc
	v_cmp_class_f32_e32 vcc, v247, v90
	s_nop 1
	v_cndmask_b32_e32 v247, v242, v247, vcc
	v_div_scale_f32 v248, s[52:53], v247, v247, 1.0
	v_rcp_f32_e32 v249, v248
	v_div_scale_f32 v228, vcc, 1.0, v247, 1.0
	s_nop 0
	v_fma_f32 v229, -v248, v249, 1.0
	v_fmac_f32_e32 v249, v229, v249
	v_mul_f32_e32 v230, v228, v249
	v_fma_f32 v229, -v248, v230, v228
	v_fmac_f32_e32 v230, v229, v249
	v_fma_f32 v248, -v248, v230, v228
	v_div_fmas_f32 v248, v248, v249, v230
	v_div_fixup_f32 v238, v248, v247, 1.0
	s_waitcnt vmcnt(16)
	v_pk_add_f32 v[160:161], v[160:161], 1.0 op_sel_hi:[1,0]
	v_pk_add_f32 v[162:163], v[162:163], 1.0 op_sel_hi:[1,0]
	v_pk_add_f32 v[164:165], v[164:165], 1.0 op_sel_hi:[1,0]
	v_pk_add_f32 v[166:167], v[166:167], 1.0 op_sel_hi:[1,0]
	v_pk_add_f32 v[168:169], v[168:169], 1.0 op_sel_hi:[1,0]
	v_pk_add_f32 v[170:171], v[170:171], 1.0 op_sel_hi:[1,0]
	v_pk_add_f32 v[172:173], v[172:173], 1.0 op_sel_hi:[1,0]
	v_pk_add_f32 v[174:175], v[174:175], 1.0 op_sel_hi:[1,0]
	v_pk_add_f32 v[192:193], v[192:193], 1.0 op_sel_hi:[1,0]
	v_pk_add_f32 v[194:195], v[194:195], 1.0 op_sel_hi:[1,0]
	v_pk_add_f32 v[196:197], v[196:197], 1.0 op_sel_hi:[1,0]
	v_pk_add_f32 v[198:199], v[198:199], 1.0 op_sel_hi:[1,0]
	v_pk_add_f32 v[200:201], v[200:201], 1.0 op_sel_hi:[1,0]
	v_pk_add_f32 v[202:203], v[202:203], 1.0 op_sel_hi:[1,0]
	v_pk_add_f32 v[204:205], v[204:205], 1.0 op_sel_hi:[1,0]
	v_pk_add_f32 v[206:207], v[206:207], 1.0 op_sel_hi:[1,0]
	s_add_u32 s38, s20, 0x1000000
	s_addc_u32 s39, s21, 0
	s_add_u32 s40, s20, 0x1400000
	s_addc_u32 s41, s21, 0
	s_add_u32 s46, s20, 0x1800000
	s_addc_u32 s47, s21, 0
	s_add_u32 s48, s20, 0x1c00000
	s_addc_u32 s49, s21, 0
	v_pk_mul_f32 v[96:97], v[96:97], v[232:233] op_sel_hi:[1,0]
	v_pk_mul_f32 v[98:99], v[98:99], v[232:233] op_sel_hi:[1,0]
	v_pk_mul_f32 v[96:97], v[64:65], v[96:97]
	v_pk_mul_f32 v[98:99], v[66:67], v[98:99]
	v_pk_fma_f32 v[96:97], v[160:161], v[96:97], v[176:177]
	v_pk_fma_f32 v[98:99], v[162:163], v[98:99], v[178:179]
	v_cvt_pk_bf16_f32 v244, v96, v97
	v_cvt_pk_bf16_f32 v245, v98, v99
	v_pk_mul_f32 v[100:101], v[100:101], v[232:233] op_sel_hi:[1,0]
	v_pk_mul_f32 v[102:103], v[102:103], v[232:233] op_sel_hi:[1,0]
	v_pk_mul_f32 v[100:101], v[68:69], v[100:101]
	v_pk_mul_f32 v[102:103], v[70:71], v[102:103]
	v_pk_fma_f32 v[100:101], v[164:165], v[100:101], v[180:181]
	v_pk_fma_f32 v[102:103], v[166:167], v[102:103], v[182:183]
	v_cvt_pk_bf16_f32 v246, v100, v101
	v_cvt_pk_bf16_f32 v247, v102, v103
	global_store_dwordx4 v82, v[244:247], s[38:39] offset:0
	v_pk_mul_f32 v[104:105], v[104:105], v[232:233] op_sel_hi:[1,0]
	v_pk_mul_f32 v[106:107], v[106:107], v[232:233] op_sel_hi:[1,0]
	v_pk_mul_f32 v[104:105], v[72:73], v[104:105]
	v_pk_mul_f32 v[106:107], v[74:75], v[106:107]
	v_pk_fma_f32 v[104:105], v[168:169], v[104:105], v[184:185]
	v_pk_fma_f32 v[106:107], v[170:171], v[106:107], v[186:187]
	v_cvt_pk_bf16_f32 v240, v104, v105
	v_cvt_pk_bf16_f32 v241, v106, v107
	v_pk_mul_f32 v[108:109], v[108:109], v[232:233] op_sel_hi:[1,0]
	v_pk_mul_f32 v[110:111], v[110:111], v[232:233] op_sel_hi:[1,0]
	v_pk_mul_f32 v[108:109], v[76:77], v[108:109]
	v_pk_mul_f32 v[110:111], v[78:79], v[110:111]
	v_pk_fma_f32 v[108:109], v[172:173], v[108:109], v[188:189]
	v_pk_fma_f32 v[110:111], v[174:175], v[110:111], v[190:191]
	v_cvt_pk_bf16_f32 v242, v108, v109
	v_cvt_pk_bf16_f32 v243, v110, v111
	global_store_dwordx4 v82, v[240:243], s[38:39] offset:1024
	v_pk_mul_f32 v[112:113], v[112:113], v[234:235] op_sel_hi:[1,0]
	v_pk_mul_f32 v[114:115], v[114:115], v[234:235] op_sel_hi:[1,0]
	v_pk_mul_f32 v[112:113], v[64:65], v[112:113]
	v_pk_mul_f32 v[114:115], v[66:67], v[114:115]
	v_pk_fma_f32 v[112:113], v[160:161], v[112:113], v[176:177]
; __device__ __forceinline__ float bf_lo(unsigned w) { return __uint_as_float(w << 16); }
; __device__ __forceinline__ float bf_hi(unsigned w) { return __uint_as_float(w & 0xffff0000u); }
; __device__ __forceinline__ unsigned pk2(float lo, float hi) { return pg8::cvt_pk_bf16(lo, hi); }
; template <bool BF> __device__ __forceinline__ void prep_rows(const float* xp, const float* xs, const bf16* hb, const float* g, const float* MOD, int shoff, int scoff, bf16* U, int gw, int NGW, int lane) {
;     ...
;         for (int r = 0; r < R; ++r) { const int m = mb + r * NGW; const int mc = m < MT ? m : mb;
; #pragma unroll
;             for (int j = 0; j < 4; ++j) {
;                 if (BF) { const v2u a0 = *(const v2u*)(hb + (size_t)mc * DM + 4 * lane + 256 * j);
;                     v[r][j].x = pg8::bf_lo(a0.x); v[r][j].y = pg8::bf_hi(a0.x); v[r][j].z = pg8::bf_lo(a0.y); v[r][j].w = pg8::bf_hi(a0.y); }
;                 else { const float* xr = mc < MP ? xp + (size_t)mc * DM : xs + (size_t)(mc - MP) * DM; v[r][j] = *(const f32x4*)(xr + 4 * lane + 256 * j); } } }
;     ...
; #pragma unroll
;             for (int j = 0; j < 4; ++j) { const int c = 4 * lane + 256 * j;
;                 const f32x4 gg = *(const f32x4*)(g + c), sc = *(const f32x4*)(mr + scoff + c), sh = *(const f32x4*)(mr + shoff + c);
;                 const f32x4 o = v[r][j] * rstd * gg * (sc + 1.0f) + sh; v2u w; w.x = pk2(o.x, o.y); w.y = pk2(o.z, o.w); *(v2u*)(U + (size_t)m * DM + c) = w; } } }
	v_pk_fma_f32 v[114:115], v[162:163], v[114:115], v[178:179]
	v_cvt_pk_bf16_f32 v244, v112, v113
	v_cvt_pk_bf16_f32 v245, v114, v115
	v_pk_mul_f32 v[116:117], v[116:117], v[234:235] op_sel_hi:[1,0]
	v_pk_mul_f32 v[118:119], v[118:119], v[234:235] op_sel_hi:[1,0]
	v_pk_mul_f32 v[116:117], v[68:69], v[116:117]
	v_pk_mul_f32 v[118:119], v[70:71], v[118:119]
	v_pk_fma_f32 v[116:117], v[164:165], v[116:117], v[180:181]
	v_pk_fma_f32 v[118:119], v[166:167], v[118:119], v[182:183]
	v_cvt_pk_bf16_f32 v246, v116, v117
	v_cvt_pk_bf16_f32 v247, v118, v119
	global_store_dwordx4 v82, v[244:247], s[40:41] offset:0
	v_pk_mul_f32 v[120:121], v[120:121], v[234:235] op_sel_hi:[1,0]
	v_pk_mul_f32 v[122:123], v[122:123], v[234:235] op_sel_hi:[1,0]
	v_pk_mul_f32 v[120:121], v[72:73], v[120:121]
	v_pk_mul_f32 v[122:123], v[74:75], v[122:123]
	v_pk_fma_f32 v[120:121], v[168:169], v[120:121], v[184:185]
	v_pk_fma_f32 v[122:123], v[170:171], v[122:123], v[186:187]
	v_cvt_pk_bf16_f32 v240, v120, v121
	v_cvt_pk_bf16_f32 v241, v122, v123
	v_pk_mul_f32 v[124:125], v[124:125], v[234:235] op_sel_hi:[1,0]
	v_pk_mul_f32 v[126:127], v[126:127], v[234:235] op_sel_hi:[1,0]
	v_pk_mul_f32 v[124:125], v[76:77], v[124:125]
	v_pk_mul_f32 v[126:127], v[78:79], v[126:127]
	v_pk_fma_f32 v[124:125], v[172:173], v[124:125], v[188:189]
	v_pk_fma_f32 v[126:127], v[174:175], v[126:127], v[190:191]
	v_cvt_pk_bf16_f32 v242, v124, v125
	v_cvt_pk_bf16_f32 v243, v126, v127
	global_store_dwordx4 v82, v[240:243], s[40:41] offset:1024
	v_pk_mul_f32 v[128:129], v[128:129], v[236:237] op_sel_hi:[1,0]
	v_pk_mul_f32 v[130:131], v[130:131], v[236:237] op_sel_hi:[1,0]
	v_pk_mul_f32 v[128:129], v[64:65], v[128:129]
	v_pk_mul_f32 v[130:131], v[66:67], v[130:131]
	v_pk_fma_f32 v[128:129], v[192:193], v[128:129], v[208:209]
	v_pk_fma_f32 v[130:131], v[194:195], v[130:131], v[210:211]
	v_cvt_pk_bf16_f32 v244, v128, v129
	v_cvt_pk_bf16_f32 v245, v130, v131
	v_pk_mul_f32 v[132:133], v[132:133], v[236:237] op_sel_hi:[1,0]
	v_pk_mul_f32 v[134:135], v[134:135], v[236:237] op_sel_hi:[1,0]
	v_pk_mul_f32 v[132:133], v[68:69], v[132:133]
	v_pk_mul_f32 v[134:135], v[70:71], v[134:135]
	v_pk_fma_f32 v[132:133], v[196:197], v[132:133], v[212:213]
	v_pk_fma_f32 v[134:135], v[198:199], v[134:135], v[214:215]
	v_cvt_pk_bf16_f32 v246, v132, v133
	v_cvt_pk_bf16_f32 v247, v134, v135
	global_store_dwordx4 v82, v[244:247], s[46:47] offset:0
	v_pk_mul_f32 v[136:137], v[136:137], v[236:237] op_sel_hi:[1,0]
	v_pk_mul_f32 v[138:139], v[138:139], v[236:237] op_sel_hi:[1,0]
	v_pk_mul_f32 v[136:137], v[72:73], v[136:137]
	v_pk_mul_f32 v[138:139], v[74:75], v[138:139]
	v_pk_fma_f32 v[136:137], v[200:201], v[136:137], v[216:217]
	v_pk_fma_f32 v[138:139], v[202:203], v[138:139], v[218:219]
	v_cvt_pk_bf16_f32 v240, v136, v137
	v_cvt_pk_bf16_f32 v241, v138, v139
	v_pk_mul_f32 v[140:141], v[140:141], v[236:237] op_sel_hi:[1,0]
	v_pk_mul_f32 v[142:143], v[142:143], v[236:237] op_sel_hi:[1,0]
	v_pk_mul_f32 v[140:141], v[76:77], v[140:141]
	v_pk_mul_f32 v[142:143], v[78:79], v[142:143]
	v_pk_fma_f32 v[140:141], v[204:205], v[140:141], v[220:221]
	v_pk_fma_f32 v[142:143], v[206:207], v[142:143], v[222:223]
	v_cvt_pk_bf16_f32 v242, v140, v141
	v_cvt_pk_bf16_f32 v243, v142, v143
	global_store_dwordx4 v82, v[240:243], s[46:47] offset:1024
	v_pk_mul_f32 v[144:145], v[144:145], v[238:239] op_sel_hi:[1,0]
	v_pk_mul_f32 v[146:147], v[146:147], v[238:239] op_sel_hi:[1,0]
	v_pk_mul_f32 v[144:145], v[64:65], v[144:145]
	v_pk_mul_f32 v[146:147], v[66:67], v[146:147]
	v_pk_fma_f32 v[144:145], v[192:193], v[144:145], v[208:209]
	v_pk_fma_f32 v[146:147], v[194:195], v[146:147], v[210:211]
	v_cvt_pk_bf16_f32 v244, v144, v145
	v_cvt_pk_bf16_f32 v245, v146, v147
	v_pk_mul_f32 v[148:149], v[148:149], v[238:239] op_sel_hi:[1,0]
	v_pk_mul_f32 v[150:151], v[150:151], v[238:239] op_sel_hi:[1,0]
	v_pk_mul_f32 v[148:149], v[68:69], v[148:149]
	v_pk_mul_f32 v[150:151], v[70:71], v[150:151]
	v_pk_fma_f32 v[148:149], v[196:197], v[148:149], v[212:213]
	v_pk_fma_f32 v[150:151], v[198:199], v[150:151], v[214:215]
	v_cvt_pk_bf16_f32 v246, v148, v149
	v_cvt_pk_bf16_f32 v247, v150, v151
	global_store_dwordx4 v82, v[244:247], s[48:49] offset:0
	v_pk_mul_f32 v[152:153], v[152:153], v[238:239] op_sel_hi:[1,0]
	v_pk_mul_f32 v[154:155], v[154:155], v[238:239] op_sel_hi:[1,0]
	v_pk_mul_f32 v[152:153], v[72:73], v[152:153]
	v_pk_mul_f32 v[154:155], v[74:75], v[154:155]
	v_pk_fma_f32 v[152:153], v[200:201], v[152:153], v[216:217]
	v_pk_fma_f32 v[154:155], v[202:203], v[154:155], v[218:219]
	v_cvt_pk_bf16_f32 v240, v152, v153
	v_cvt_pk_bf16_f32 v241, v154, v155
	v_pk_mul_f32 v[156:157], v[156:157], v[238:239] op_sel_hi:[1,0]
	v_pk_mul_f32 v[158:159], v[158:159], v[238:239] op_sel_hi:[1,0]
	v_pk_mul_f32 v[156:157], v[76:77], v[156:157]
	v_pk_mul_f32 v[158:159], v[78:79], v[158:159]
	v_pk_fma_f32 v[156:157], v[204:205], v[156:157], v[220:221]
	v_pk_fma_f32 v[158:159], v[206:207], v[158:159], v[222:223]
	v_cvt_pk_bf16_f32 v242, v156, v157
	v_cvt_pk_bf16_f32 v243, v158, v159
	global_store_dwordx4 v82, v[240:243], s[48:49] offset:1024
	s_add_u32 s34, s8, 0xc000
	s_addc_u32 s35, s9, 0
	s_add_u32 s36, s8, 0xc000
	s_addc_u32 s37, s9, 0
	global_load_dwordx4 v[176:179], v80, s[34:35] offset:0
	global_load_dwordx4 v[180:183], v80, s[34:35] offset:16
	global_load_dwordx4 v[184:187], v80, s[34:35] offset:2048
	global_load_dwordx4 v[188:191], v80, s[34:35] offset:2064
	global_load_dwordx4 v[160:163], v81, s[34:35] offset:0
	global_load_dwordx4 v[164:167], v81, s[34:35] offset:16
	global_load_dwordx4 v[168:171], v81, s[34:35] offset:2048
	global_load_dwordx4 v[172:175], v81, s[34:35] offset:2064
; __device__ __forceinline__ float bf_lo(unsigned w) { return __uint_as_float(w << 16); }
; __device__ __forceinline__ float bf_hi(unsigned w) { return __uint_as_float(w & 0xffff0000u); }
; template <bool BF> __device__ __forceinline__ void prep_rows(const float* xp, const float* xs, const bf16* hb, const float* g, const float* MOD, int shoff, int scoff, bf16* U, int gw, int NGW, int lane) {
;     ...
;         for (int r = 0; r < R; ++r) { const int m = mb + r * NGW; const int mc = m < MT ? m : mb;
; #pragma unroll
;             for (int j = 0; j < 4; ++j) {
;                 if (BF) { const v2u a0 = *(const v2u*)(hb + (size_t)mc * DM + 4 * lane + 256 * j);
;                     v[r][j].x = pg8::bf_lo(a0.x); v[r][j].y = pg8::bf_hi(a0.x); v[r][j].z = pg8::bf_lo(a0.y); v[r][j].w = pg8::bf_hi(a0.y); }
;                 else { const float* xr = mc < MP ? xp + (size_t)mc * DM : xs + (size_t)(mc - MP) * DM; v[r][j] = *(const f32x4*)(xr + 4 * lane + 256 * j); } } }
; #pragma unroll
;         for (int r = 0; r < R; ++r) { float t = 0.f;
; #pragma unroll
;             for (int j = 0; j < 4; ++j) t += (v[r][j].x * v[r][j].x + v[r][j].y * v[r][j].y) + (v[r][j].z * v[r][j].z + v[r][j].w * v[r][j].w);
;             s[r] = t; }
; #pragma unroll
;         for (int o = 1; o < 64; o <<= 1) {
; #pragma unroll
;             for (int r = 0; r < R; ++r) s[r] += __shfl_xor(s[r], o); }
; #pragma unroll
	global_load_dwordx4 v[208:211], v80, s[36:37] offset:0
	global_load_dwordx4 v[212:215], v80, s[36:37] offset:16
	global_load_dwordx4 v[216:219], v80, s[36:37] offset:2048
	global_load_dwordx4 v[220:223], v80, s[36:37] offset:2064
	global_load_dwordx4 v[192:195], v81, s[36:37] offset:0
	global_load_dwordx4 v[196:199], v81, s[36:37] offset:16
	global_load_dwordx4 v[200:203], v81, s[36:37] offset:2048
	global_load_dwordx4 v[204:207], v81, s[36:37] offset:2064
	s_add_u32 s24, s16, 0x6000000
	s_addc_u32 s25, s17, 0
	s_add_u32 s26, s16, 0x6800000
	s_addc_u32 s27, s17, 0
	s_add_u32 s28, s16, 0x7000000
	s_addc_u32 s29, s17, 0
	s_add_u32 s30, s16, 0x7800000
	s_addc_u32 s31, s17, 0
	global_load_dwordx4 v[96:99], v80, s[24:25] offset:0
	global_load_dwordx4 v[100:103], v80, s[24:25] offset:16
	global_load_dwordx4 v[104:107], v80, s[24:25] offset:2048
	global_load_dwordx4 v[108:111], v80, s[24:25] offset:2064
	global_load_dwordx4 v[112:115], v80, s[26:27] offset:0
	global_load_dwordx4 v[116:119], v80, s[26:27] offset:16
	global_load_dwordx4 v[120:123], v80, s[26:27] offset:2048
	global_load_dwordx4 v[124:127], v80, s[26:27] offset:2064
	global_load_dwordx4 v[128:131], v80, s[28:29] offset:0
	global_load_dwordx4 v[132:135], v80, s[28:29] offset:16
	global_load_dwordx4 v[136:139], v80, s[28:29] offset:2048
	global_load_dwordx4 v[140:143], v80, s[28:29] offset:2064
	global_load_dwordx4 v[144:147], v80, s[30:31] offset:0
	global_load_dwordx4 v[148:151], v80, s[30:31] offset:16
	global_load_dwordx4 v[152:155], v80, s[30:31] offset:2048
	global_load_dwordx4 v[156:159], v80, s[30:31] offset:2064
	s_waitcnt vmcnt(40)
	v_pk_mul_f32 v[240:241], v[0:1], v[0:1]
	v_pk_mul_f32 v[242:243], v[16:17], v[16:17]
	v_pk_mul_f32 v[244:245], v[32:33], v[32:33]
	v_pk_mul_f32 v[246:247], v[48:49], v[48:49]
	v_pk_fma_f32 v[240:241], v[2:3], v[2:3], v[240:241]
	v_pk_fma_f32 v[242:243], v[18:19], v[18:19], v[242:243]
	v_pk_fma_f32 v[244:245], v[34:35], v[34:35], v[244:245]
	v_pk_fma_f32 v[246:247], v[50:51], v[50:51], v[246:247]
	v_pk_fma_f32 v[240:241], v[4:5], v[4:5], v[240:241]
	v_pk_fma_f32 v[242:243], v[20:21], v[20:21], v[242:243]
	v_pk_fma_f32 v[244:245], v[36:37], v[36:37], v[244:245]
	v_pk_fma_f32 v[246:247], v[52:53], v[52:53], v[246:247]
	v_pk_fma_f32 v[240:241], v[6:7], v[6:7], v[240:241]
	v_pk_fma_f32 v[242:243], v[22:23], v[22:23], v[242:243]
	v_pk_fma_f32 v[244:245], v[38:39], v[38:39], v[244:245]
	v_pk_fma_f32 v[246:247], v[54:55], v[54:55], v[246:247]
	v_pk_fma_f32 v[240:241], v[8:9], v[8:9], v[240:241]
	v_pk_fma_f32 v[242:243], v[24:25], v[24:25], v[242:243]
	v_pk_fma_f32 v[244:245], v[40:41], v[40:41], v[244:245]
	v_pk_fma_f32 v[246:247], v[56:57], v[56:57], v[246:247]
	v_pk_fma_f32 v[240:241], v[10:11], v[10:11], v[240:241]
	v_pk_fma_f32 v[242:243], v[26:27], v[26:27], v[242:243]
	v_pk_fma_f32 v[244:245], v[42:43], v[42:43], v[244:245]
	v_pk_fma_f32 v[246:247], v[58:59], v[58:59], v[246:247]
	v_pk_fma_f32 v[240:241], v[12:13], v[12:13], v[240:241]
	v_pk_fma_f32 v[242:243], v[28:29], v[28:29], v[242:243]
	v_pk_fma_f32 v[244:245], v[44:45], v[44:45], v[244:245]
	v_pk_fma_f32 v[246:247], v[60:61], v[60:61], v[246:247]
	v_pk_fma_f32 v[240:241], v[14:15], v[14:15], v[240:241]
	v_pk_fma_f32 v[242:243], v[30:31], v[30:31], v[242:243]
	v_pk_fma_f32 v[244:245], v[46:47], v[46:47], v[244:245]
	v_pk_fma_f32 v[246:247], v[62:63], v[62:63], v[246:247]
	v_add_f32_e32 v224, v240, v241
	v_add_f32_e32 v225, v242, v243
	v_add_f32_e32 v226, v244, v245
	v_add_f32_e32 v227, v246, v247
	ds_bpermute_b32 v228, v83, v224
	ds_bpermute_b32 v229, v83, v225
	ds_bpermute_b32 v230, v83, v226
	ds_bpermute_b32 v231, v83, v227
	s_waitcnt lgkmcnt(0)
	v_add_f32_e32 v224, v224, v228
	v_add_f32_e32 v225, v225, v229
	v_add_f32_e32 v226, v226, v230
	v_add_f32_e32 v227, v227, v231
	ds_bpermute_b32 v228, v84, v224
	ds_bpermute_b32 v229, v84, v225
	ds_bpermute_b32 v230, v84, v226
	ds_bpermute_b32 v231, v84, v227
	s_waitcnt lgkmcnt(0)
	v_add_f32_e32 v224, v224, v228
	v_add_f32_e32 v225, v225, v229
	v_add_f32_e32 v226, v226, v230
	v_add_f32_e32 v227, v227, v231
	ds_bpermute_b32 v228, v85, v224
	ds_bpermute_b32 v229, v85, v225
	ds_bpermute_b32 v230, v85, v226
	ds_bpermute_b32 v231, v85, v227
	s_waitcnt lgkmcnt(0)
	v_add_f32_e32 v224, v224, v228
	v_add_f32_e32 v225, v225, v229
	v_add_f32_e32 v226, v226, v230
	v_add_f32_e32 v227, v227, v231
	ds_bpermute_b32 v228, v86, v224
	ds_bpermute_b32 v229, v86, v225
	ds_bpermute_b32 v230, v86, v226
	ds_bpermute_b32 v231, v86, v227
	s_waitcnt lgkmcnt(0)
	v_add_f32_e32 v224, v224, v228
	v_add_f32_e32 v225, v225, v229
	v_add_f32_e32 v226, v226, v230
	v_add_f32_e32 v227, v227, v231
	ds_bpermute_b32 v228, v87, v224
	ds_bpermute_b32 v229, v87, v225
	ds_bpermute_b32 v230, v87, v226
	ds_bpermute_b32 v231, v87, v227
	s_waitcnt lgkmcnt(0)
	v_add_f32_e32 v224, v224, v228
	v_add_f32_e32 v225, v225, v229
	v_add_f32_e32 v226, v226, v230
	v_add_f32_e32 v227, v227, v231
	ds_bpermute_b32 v228, v88, v224
	ds_bpermute_b32 v229, v88, v225
	ds_bpermute_b32 v230, v88, v226
	ds_bpermute_b32 v231, v88, v227
	s_waitcnt lgkmcnt(0)
; template <bool BF> __device__ __forceinline__ void prep_rows(const float* xp, const float* xs, const bf16* hb, const float* g, const float* MOD, int shoff, int scoff, bf16* U, int gw, int NGW, int lane) {
;     ...
;             for (int r = 0; r < R; ++r) s[r] += __shfl_xor(s[r], o); }
; #pragma unroll
;         for (int r = 0; r < R; ++r) { const int m = mb + r * NGW; if (m < MT) {
;             const float rstd = 1.0f / sqrtf(s[r] * (1.0f / DM) + RMS_EPS);
	v_add_f32_e32 v224, v224, v228
	v_add_f32_e32 v225, v225, v229
	v_add_f32_e32 v226, v226, v230
	v_add_f32_e32 v227, v227, v231
	v_fmamk_f32 v240, v224, 0x3a800000, v89
	v_mul_f32_e32 v241, 0x4f800000, v240
	v_cmp_gt_f32_e32 vcc, s54, v240
	s_nop 1
	v_cndmask_b32_e32 v247, v240, v241, vcc
	v_sqrt_f32_e32 v242, v247
	s_nop 1
	v_add_u32_e32 v243, -1, v242
	v_add_u32_e32 v244, 1, v242
	v_fma_f32 v245, -v243, v242, v247
	v_fma_f32 v246, -v244, v242, v247
	v_cmp_ge_f32_e64 s[52:53], 0, v245
	s_nop 1
	v_cndmask_b32_e64 v242, v242, v243, s[52:53]
	v_cmp_lt_f32_e64 s[52:53], 0, v246
	s_nop 1
	v_cndmask_b32_e64 v242, v242, v244, s[52:53]
	v_mul_f32_e32 v243, 0x37800000, v242
	v_cndmask_b32_e32 v242, v242, v243, vcc
	v_cmp_class_f32_e32 vcc, v247, v90
	s_nop 1
	v_cndmask_b32_e32 v247, v242, v247, vcc
	v_div_scale_f32 v248, s[52:53], v247, v247, 1.0
	v_rcp_f32_e32 v249, v248
	v_div_scale_f32 v228, vcc, 1.0, v247, 1.0
	s_nop 0
	v_fma_f32 v229, -v248, v249, 1.0
	v_fmac_f32_e32 v249, v229, v249
	v_mul_f32_e32 v230, v228, v249
	v_fma_f32 v229, -v248, v230, v228
	v_fmac_f32_e32 v230, v229, v249
	v_fma_f32 v248, -v248, v230, v228
	v_div_fmas_f32 v248, v248, v249, v230
	v_div_fixup_f32 v232, v248, v247, 1.0
	v_fmamk_f32 v240, v225, 0x3a800000, v89
	v_mul_f32_e32 v241, 0x4f800000, v240
	v_cmp_gt_f32_e32 vcc, s54, v240
	s_nop 1
	v_cndmask_b32_e32 v247, v240, v241, vcc
	v_sqrt_f32_e32 v242, v247
	s_nop 1
	v_add_u32_e32 v243, -1, v242
	v_add_u32_e32 v244, 1, v242
	v_fma_f32 v245, -v243, v242, v247
	v_fma_f32 v246, -v244, v242, v247
	v_cmp_ge_f32_e64 s[52:53], 0, v245
	s_nop 1
	v_cndmask_b32_e64 v242, v242, v243, s[52:53]
	v_cmp_lt_f32_e64 s[52:53], 0, v246
	s_nop 1
	v_cndmask_b32_e64 v242, v242, v244, s[52:53]
	v_mul_f32_e32 v243, 0x37800000, v242
	v_cndmask_b32_e32 v242, v242, v243, vcc
	v_cmp_class_f32_e32 vcc, v247, v90
	s_nop 1
	v_cndmask_b32_e32 v247, v242, v247, vcc
	v_div_scale_f32 v248, s[52:53], v247, v247, 1.0
	v_rcp_f32_e32 v249, v248
	v_div_scale_f32 v228, vcc, 1.0, v247, 1.0
	s_nop 0
	v_fma_f32 v229, -v248, v249, 1.0
	v_fmac_f32_e32 v249, v229, v249
	v_mul_f32_e32 v230, v228, v249
	v_fma_f32 v229, -v248, v230, v228
	v_fmac_f32_e32 v230, v229, v249
	v_fma_f32 v248, -v248, v230, v228
	v_div_fmas_f32 v248, v248, v249, v230
	v_div_fixup_f32 v234, v248, v247, 1.0
	v_fmamk_f32 v240, v226, 0x3a800000, v89
	v_mul_f32_e32 v241, 0x4f800000, v240
	v_cmp_gt_f32_e32 vcc, s54, v240
	s_nop 1
	v_cndmask_b32_e32 v247, v240, v241, vcc
	v_sqrt_f32_e32 v242, v247
	s_nop 1
	v_add_u32_e32 v243, -1, v242
	v_add_u32_e32 v244, 1, v242
	v_fma_f32 v245, -v243, v242, v247
	v_fma_f32 v246, -v244, v242, v247
	v_cmp_ge_f32_e64 s[52:53], 0, v245
	s_nop 1
	v_cndmask_b32_e64 v242, v242, v243, s[52:53]
	v_cmp_lt_f32_e64 s[52:53], 0, v246
	s_nop 1
	v_cndmask_b32_e64 v242, v242, v244, s[52:53]
	v_mul_f32_e32 v243, 0x37800000, v242
	v_cndmask_b32_e32 v242, v242, v243, vcc
	v_cmp_class_f32_e32 vcc, v247, v90
	s_nop 1
	v_cndmask_b32_e32 v247, v242, v247, vcc
	v_div_scale_f32 v248, s[52:53], v247, v247, 1.0
	v_rcp_f32_e32 v249, v248
	v_div_scale_f32 v228, vcc, 1.0, v247, 1.0
	s_nop 0
	v_fma_f32 v229, -v248, v249, 1.0
	v_fmac_f32_e32 v249, v229, v249
	v_mul_f32_e32 v230, v228, v249
	v_fma_f32 v229, -v248, v230, v228
	v_fmac_f32_e32 v230, v229, v249
	v_fma_f32 v248, -v248, v230, v228
	v_div_fmas_f32 v248, v248, v249, v230
	v_div_fixup_f32 v236, v248, v247, 1.0
	v_fmamk_f32 v240, v227, 0x3a800000, v89
	v_mul_f32_e32 v241, 0x4f800000, v240
	v_cmp_gt_f32_e32 vcc, s54, v240
	s_nop 1
	v_cndmask_b32_e32 v247, v240, v241, vcc
	v_sqrt_f32_e32 v242, v247
	s_nop 1
	v_add_u32_e32 v243, -1, v242
	v_add_u32_e32 v244, 1, v242
	v_fma_f32 v245, -v243, v242, v247
	v_fma_f32 v246, -v244, v242, v247
	v_cmp_ge_f32_e64 s[52:53], 0, v245
	s_nop 1
	v_cndmask_b32_e64 v242, v242, v243, s[52:53]
	v_cmp_lt_f32_e64 s[52:53], 0, v246
	s_nop 1
	v_cndmask_b32_e64 v242, v242, v244, s[52:53]
	v_mul_f32_e32 v243, 0x37800000, v242
	v_cndmask_b32_e32 v242, v242, v243, vcc
	v_cmp_class_f32_e32 vcc, v247, v90
	s_nop 1
	v_cndmask_b32_e32 v247, v242, v247, vcc
	v_div_scale_f32 v248, s[52:53], v247, v247, 1.0
	v_rcp_f32_e32 v249, v248
	v_div_scale_f32 v228, vcc, 1.0, v247, 1.0
	s_nop 0
	v_fma_f32 v229, -v248, v249, 1.0
	v_fmac_f32_e32 v249, v229, v249
	v_mul_f32_e32 v230, v228, v249
	v_fma_f32 v229, -v248, v230, v228
	v_fmac_f32_e32 v230, v229, v249
	v_fma_f32 v248, -v248, v230, v228
	v_div_fmas_f32 v248, v248, v249, v230
	v_div_fixup_f32 v238, v248, v247, 1.0
	s_waitcnt vmcnt(16)
; __device__ __forceinline__ unsigned pk2(float lo, float hi) { return pg8::cvt_pk_bf16(lo, hi); }
; template <bool BF> __device__ __forceinline__ void prep_rows(const float* xp, const float* xs, const bf16* hb, const float* g, const float* MOD, int shoff, int scoff, bf16* U, int gw, int NGW, int lane) {
;     ...
;                 const f32x4 gg = *(const f32x4*)(g + c), sc = *(const f32x4*)(mr + scoff + c), sh = *(const f32x4*)(mr + shoff + c);
;                 const f32x4 o = v[r][j] * rstd * gg * (sc + 1.0f) + sh; v2u w; w.x = pk2(o.x, o.y); w.y = pk2(o.z, o.w); *(v2u*)(U + (size_t)m * DM + c) = w; } } }
	v_pk_add_f32 v[160:161], v[160:161], 1.0 op_sel_hi:[1,0]
	v_pk_add_f32 v[162:163], v[162:163], 1.0 op_sel_hi:[1,0]
	v_pk_add_f32 v[164:165], v[164:165], 1.0 op_sel_hi:[1,0]
	v_pk_add_f32 v[166:167], v[166:167], 1.0 op_sel_hi:[1,0]
	v_pk_add_f32 v[168:169], v[168:169], 1.0 op_sel_hi:[1,0]
	v_pk_add_f32 v[170:171], v[170:171], 1.0 op_sel_hi:[1,0]
	v_pk_add_f32 v[172:173], v[172:173], 1.0 op_sel_hi:[1,0]
	v_pk_add_f32 v[174:175], v[174:175], 1.0 op_sel_hi:[1,0]
	v_pk_add_f32 v[192:193], v[192:193], 1.0 op_sel_hi:[1,0]
	v_pk_add_f32 v[194:195], v[194:195], 1.0 op_sel_hi:[1,0]
	v_pk_add_f32 v[196:197], v[196:197], 1.0 op_sel_hi:[1,0]
	v_pk_add_f32 v[198:199], v[198:199], 1.0 op_sel_hi:[1,0]
	v_pk_add_f32 v[200:201], v[200:201], 1.0 op_sel_hi:[1,0]
	v_pk_add_f32 v[202:203], v[202:203], 1.0 op_sel_hi:[1,0]
	v_pk_add_f32 v[204:205], v[204:205], 1.0 op_sel_hi:[1,0]
	v_pk_add_f32 v[206:207], v[206:207], 1.0 op_sel_hi:[1,0]
	s_add_u32 s38, s20, 0x2000000
	s_addc_u32 s39, s21, 0
	s_add_u32 s40, s20, 0x2400000
	s_addc_u32 s41, s21, 0
	s_add_u32 s46, s20, 0x2800000
	s_addc_u32 s47, s21, 0
	s_add_u32 s48, s20, 0x2c00000
	s_addc_u32 s49, s21, 0
	v_pk_mul_f32 v[0:1], v[0:1], v[232:233] op_sel_hi:[1,0]
	v_pk_mul_f32 v[2:3], v[2:3], v[232:233] op_sel_hi:[1,0]
	v_pk_mul_f32 v[0:1], v[64:65], v[0:1]
	v_pk_mul_f32 v[2:3], v[66:67], v[2:3]
	v_pk_fma_f32 v[0:1], v[160:161], v[0:1], v[176:177]
	v_pk_fma_f32 v[2:3], v[162:163], v[2:3], v[178:179]
	v_cvt_pk_bf16_f32 v244, v0, v1
	v_cvt_pk_bf16_f32 v245, v2, v3
	v_pk_mul_f32 v[4:5], v[4:5], v[232:233] op_sel_hi:[1,0]
	v_pk_mul_f32 v[6:7], v[6:7], v[232:233] op_sel_hi:[1,0]
	v_pk_mul_f32 v[4:5], v[68:69], v[4:5]
	v_pk_mul_f32 v[6:7], v[70:71], v[6:7]
	v_pk_fma_f32 v[4:5], v[164:165], v[4:5], v[180:181]
	v_pk_fma_f32 v[6:7], v[166:167], v[6:7], v[182:183]
	v_cvt_pk_bf16_f32 v246, v4, v5
	v_cvt_pk_bf16_f32 v247, v6, v7
	global_store_dwordx4 v82, v[244:247], s[38:39] offset:0
	v_pk_mul_f32 v[8:9], v[8:9], v[232:233] op_sel_hi:[1,0]
	v_pk_mul_f32 v[10:11], v[10:11], v[232:233] op_sel_hi:[1,0]
	v_pk_mul_f32 v[8:9], v[72:73], v[8:9]
	v_pk_mul_f32 v[10:11], v[74:75], v[10:11]
	v_pk_fma_f32 v[8:9], v[168:169], v[8:9], v[184:185]
	v_pk_fma_f32 v[10:11], v[170:171], v[10:11], v[186:187]
	v_cvt_pk_bf16_f32 v240, v8, v9
	v_cvt_pk_bf16_f32 v241, v10, v11
	v_pk_mul_f32 v[12:13], v[12:13], v[232:233] op_sel_hi:[1,0]
	v_pk_mul_f32 v[14:15], v[14:15], v[232:233] op_sel_hi:[1,0]
	v_pk_mul_f32 v[12:13], v[76:77], v[12:13]
	v_pk_mul_f32 v[14:15], v[78:79], v[14:15]
	v_pk_fma_f32 v[12:13], v[172:173], v[12:13], v[188:189]
	v_pk_fma_f32 v[14:15], v[174:175], v[14:15], v[190:191]
	v_cvt_pk_bf16_f32 v242, v12, v13
	v_cvt_pk_bf16_f32 v243, v14, v15
	global_store_dwordx4 v82, v[240:243], s[38:39] offset:1024
	v_pk_mul_f32 v[16:17], v[16:17], v[234:235] op_sel_hi:[1,0]
	v_pk_mul_f32 v[18:19], v[18:19], v[234:235] op_sel_hi:[1,0]
	v_pk_mul_f32 v[16:17], v[64:65], v[16:17]
	v_pk_mul_f32 v[18:19], v[66:67], v[18:19]
	v_pk_fma_f32 v[16:17], v[160:161], v[16:17], v[176:177]
	v_pk_fma_f32 v[18:19], v[162:163], v[18:19], v[178:179]
	v_cvt_pk_bf16_f32 v244, v16, v17
	v_cvt_pk_bf16_f32 v245, v18, v19
	v_pk_mul_f32 v[20:21], v[20:21], v[234:235] op_sel_hi:[1,0]
	v_pk_mul_f32 v[22:23], v[22:23], v[234:235] op_sel_hi:[1,0]
	v_pk_mul_f32 v[20:21], v[68:69], v[20:21]
	v_pk_mul_f32 v[22:23], v[70:71], v[22:23]
	v_pk_fma_f32 v[20:21], v[164:165], v[20:21], v[180:181]
	v_pk_fma_f32 v[22:23], v[166:167], v[22:23], v[182:183]
	v_cvt_pk_bf16_f32 v246, v20, v21
	v_cvt_pk_bf16_f32 v247, v22, v23
	global_store_dwordx4 v82, v[244:247], s[40:41] offset:0
	v_pk_mul_f32 v[24:25], v[24:25], v[234:235] op_sel_hi:[1,0]
	v_pk_mul_f32 v[26:27], v[26:27], v[234:235] op_sel_hi:[1,0]
	v_pk_mul_f32 v[24:25], v[72:73], v[24:25]
	v_pk_mul_f32 v[26:27], v[74:75], v[26:27]
	v_pk_fma_f32 v[24:25], v[168:169], v[24:25], v[184:185]
	v_pk_fma_f32 v[26:27], v[170:171], v[26:27], v[186:187]
	v_cvt_pk_bf16_f32 v240, v24, v25
	v_cvt_pk_bf16_f32 v241, v26, v27
	v_pk_mul_f32 v[28:29], v[28:29], v[234:235] op_sel_hi:[1,0]
	v_pk_mul_f32 v[30:31], v[30:31], v[234:235] op_sel_hi:[1,0]
	v_pk_mul_f32 v[28:29], v[76:77], v[28:29]
	v_pk_mul_f32 v[30:31], v[78:79], v[30:31]
	v_pk_fma_f32 v[28:29], v[172:173], v[28:29], v[188:189]
	v_pk_fma_f32 v[30:31], v[174:175], v[30:31], v[190:191]
	v_cvt_pk_bf16_f32 v242, v28, v29
	v_cvt_pk_bf16_f32 v243, v30, v31
	global_store_dwordx4 v82, v[240:243], s[40:41] offset:1024
	v_pk_mul_f32 v[32:33], v[32:33], v[236:237] op_sel_hi:[1,0]
	v_pk_mul_f32 v[34:35], v[34:35], v[236:237] op_sel_hi:[1,0]
	v_pk_mul_f32 v[32:33], v[64:65], v[32:33]
	v_pk_mul_f32 v[34:35], v[66:67], v[34:35]
	v_pk_fma_f32 v[32:33], v[192:193], v[32:33], v[208:209]
	v_pk_fma_f32 v[34:35], v[194:195], v[34:35], v[210:211]
	v_cvt_pk_bf16_f32 v244, v32, v33
	v_cvt_pk_bf16_f32 v245, v34, v35
	v_pk_mul_f32 v[36:37], v[36:37], v[236:237] op_sel_hi:[1,0]
	v_pk_mul_f32 v[38:39], v[38:39], v[236:237] op_sel_hi:[1,0]
	v_pk_mul_f32 v[36:37], v[68:69], v[36:37]
	v_pk_mul_f32 v[38:39], v[70:71], v[38:39]
	v_pk_fma_f32 v[36:37], v[196:197], v[36:37], v[212:213]
	v_pk_fma_f32 v[38:39], v[198:199], v[38:39], v[214:215]
	v_cvt_pk_bf16_f32 v246, v36, v37
	v_cvt_pk_bf16_f32 v247, v38, v39
	global_store_dwordx4 v82, v[244:247], s[46:47] offset:0
	v_pk_mul_f32 v[40:41], v[40:41], v[236:237] op_sel_hi:[1,0]
	v_pk_mul_f32 v[42:43], v[42:43], v[236:237] op_sel_hi:[1,0]
	v_pk_mul_f32 v[40:41], v[72:73], v[40:41]
	v_pk_mul_f32 v[42:43], v[74:75], v[42:43]
	v_pk_fma_f32 v[40:41], v[200:201], v[40:41], v[216:217]
	v_pk_fma_f32 v[42:43], v[202:203], v[42:43], v[218:219]
	v_cvt_pk_bf16_f32 v240, v40, v41
; __device__ __forceinline__ float bf_lo(unsigned w) { return __uint_as_float(w << 16); }
; __device__ __forceinline__ float bf_hi(unsigned w) { return __uint_as_float(w & 0xffff0000u); }
; __device__ __forceinline__ unsigned pk2(float lo, float hi) { return pg8::cvt_pk_bf16(lo, hi); }
; template <bool BF> __device__ __forceinline__ void prep_rows(const float* xp, const float* xs, const bf16* hb, const float* g, const float* MOD, int shoff, int scoff, bf16* U, int gw, int NGW, int lane) {
;     ...
;         for (int r = 0; r < R; ++r) { const int m = mb + r * NGW; const int mc = m < MT ? m : mb;
; #pragma unroll
;             for (int j = 0; j < 4; ++j) {
;                 if (BF) { const v2u a0 = *(const v2u*)(hb + (size_t)mc * DM + 4 * lane + 256 * j);
;                     v[r][j].x = pg8::bf_lo(a0.x); v[r][j].y = pg8::bf_hi(a0.x); v[r][j].z = pg8::bf_lo(a0.y); v[r][j].w = pg8::bf_hi(a0.y); }
;                 else { const float* xr = mc < MP ? xp + (size_t)mc * DM : xs + (size_t)(mc - MP) * DM; v[r][j] = *(const f32x4*)(xr + 4 * lane + 256 * j); } } }
; #pragma unroll
;         for (int r = 0; r < R; ++r) { float t = 0.f;
; #pragma unroll
;             for (int j = 0; j < 4; ++j) t += (v[r][j].x * v[r][j].x + v[r][j].y * v[r][j].y) + (v[r][j].z * v[r][j].z + v[r][j].w * v[r][j].w);
;             s[r] = t; }
; #pragma unroll
;         for (int o = 1; o < 64; o <<= 1) {
; #pragma unroll
;             for (int r = 0; r < R; ++r) s[r] += __shfl_xor(s[r], o); }
; #pragma unroll
;     ...
;                 const f32x4 o = v[r][j] * rstd * gg * (sc + 1.0f) + sh; v2u w; w.x = pk2(o.x, o.y); w.y = pk2(o.z, o.w); *(v2u*)(U + (size_t)m * DM + c) = w; } } }
	v_cvt_pk_bf16_f32 v241, v42, v43
	v_pk_mul_f32 v[44:45], v[44:45], v[236:237] op_sel_hi:[1,0]
	v_pk_mul_f32 v[46:47], v[46:47], v[236:237] op_sel_hi:[1,0]
	v_pk_mul_f32 v[44:45], v[76:77], v[44:45]
	v_pk_mul_f32 v[46:47], v[78:79], v[46:47]
	v_pk_fma_f32 v[44:45], v[204:205], v[44:45], v[220:221]
	v_pk_fma_f32 v[46:47], v[206:207], v[46:47], v[222:223]
	v_cvt_pk_bf16_f32 v242, v44, v45
	v_cvt_pk_bf16_f32 v243, v46, v47
	global_store_dwordx4 v82, v[240:243], s[46:47] offset:1024
	v_pk_mul_f32 v[48:49], v[48:49], v[238:239] op_sel_hi:[1,0]
	v_pk_mul_f32 v[50:51], v[50:51], v[238:239] op_sel_hi:[1,0]
	v_pk_mul_f32 v[48:49], v[64:65], v[48:49]
	v_pk_mul_f32 v[50:51], v[66:67], v[50:51]
	v_pk_fma_f32 v[48:49], v[192:193], v[48:49], v[208:209]
	v_pk_fma_f32 v[50:51], v[194:195], v[50:51], v[210:211]
	v_cvt_pk_bf16_f32 v244, v48, v49
	v_cvt_pk_bf16_f32 v245, v50, v51
	v_pk_mul_f32 v[52:53], v[52:53], v[238:239] op_sel_hi:[1,0]
	v_pk_mul_f32 v[54:55], v[54:55], v[238:239] op_sel_hi:[1,0]
	v_pk_mul_f32 v[52:53], v[68:69], v[52:53]
	v_pk_mul_f32 v[54:55], v[70:71], v[54:55]
	v_pk_fma_f32 v[52:53], v[196:197], v[52:53], v[212:213]
	v_pk_fma_f32 v[54:55], v[198:199], v[54:55], v[214:215]
	v_cvt_pk_bf16_f32 v246, v52, v53
	v_cvt_pk_bf16_f32 v247, v54, v55
	global_store_dwordx4 v82, v[244:247], s[48:49] offset:0
	v_pk_mul_f32 v[56:57], v[56:57], v[238:239] op_sel_hi:[1,0]
	v_pk_mul_f32 v[58:59], v[58:59], v[238:239] op_sel_hi:[1,0]
	v_pk_mul_f32 v[56:57], v[72:73], v[56:57]
	v_pk_mul_f32 v[58:59], v[74:75], v[58:59]
	v_pk_fma_f32 v[56:57], v[200:201], v[56:57], v[216:217]
	v_pk_fma_f32 v[58:59], v[202:203], v[58:59], v[218:219]
	v_cvt_pk_bf16_f32 v240, v56, v57
	v_cvt_pk_bf16_f32 v241, v58, v59
	v_pk_mul_f32 v[60:61], v[60:61], v[238:239] op_sel_hi:[1,0]
	v_pk_mul_f32 v[62:63], v[62:63], v[238:239] op_sel_hi:[1,0]
	v_pk_mul_f32 v[60:61], v[76:77], v[60:61]
	v_pk_mul_f32 v[62:63], v[78:79], v[62:63]
	v_pk_fma_f32 v[60:61], v[204:205], v[60:61], v[220:221]
	v_pk_fma_f32 v[62:63], v[206:207], v[62:63], v[222:223]
	v_cvt_pk_bf16_f32 v242, v60, v61
	v_cvt_pk_bf16_f32 v243, v62, v63
	global_store_dwordx4 v82, v[240:243], s[48:49] offset:1024
	s_add_u32 s34, s8, 0x12000
	s_addc_u32 s35, s9, 0
	s_add_u32 s36, s8, 0x12000
	s_addc_u32 s37, s9, 0
	global_load_dwordx4 v[176:179], v80, s[34:35] offset:0
	global_load_dwordx4 v[180:183], v80, s[34:35] offset:16
	global_load_dwordx4 v[184:187], v80, s[34:35] offset:2048
	global_load_dwordx4 v[188:191], v80, s[34:35] offset:2064
	global_load_dwordx4 v[160:163], v81, s[34:35] offset:0
	global_load_dwordx4 v[164:167], v81, s[34:35] offset:16
	global_load_dwordx4 v[168:171], v81, s[34:35] offset:2048
	global_load_dwordx4 v[172:175], v81, s[34:35] offset:2064
	global_load_dwordx4 v[208:211], v80, s[36:37] offset:0
	global_load_dwordx4 v[212:215], v80, s[36:37] offset:16
	global_load_dwordx4 v[216:219], v80, s[36:37] offset:2048
	global_load_dwordx4 v[220:223], v80, s[36:37] offset:2064
	global_load_dwordx4 v[192:195], v81, s[36:37] offset:0
	global_load_dwordx4 v[196:199], v81, s[36:37] offset:16
	global_load_dwordx4 v[200:203], v81, s[36:37] offset:2048
	global_load_dwordx4 v[204:207], v81, s[36:37] offset:2064
	s_add_u32 s24, s16, 0x8000000
	s_addc_u32 s25, s17, 0
	s_add_u32 s26, s16, 0x8800000
	s_addc_u32 s27, s17, 0
	s_add_u32 s28, s16, 0x9000000
	s_addc_u32 s29, s17, 0
	s_add_u32 s30, s16, 0x9800000
	s_addc_u32 s31, s17, 0
	global_load_dwordx4 v[0:3], v80, s[24:25] offset:0
	global_load_dwordx4 v[4:7], v80, s[24:25] offset:16
	global_load_dwordx4 v[8:11], v80, s[24:25] offset:2048
	global_load_dwordx4 v[12:15], v80, s[24:25] offset:2064
	global_load_dwordx4 v[16:19], v80, s[26:27] offset:0
	global_load_dwordx4 v[20:23], v80, s[26:27] offset:16
	global_load_dwordx4 v[24:27], v80, s[26:27] offset:2048
	global_load_dwordx4 v[28:31], v80, s[26:27] offset:2064
	global_load_dwordx4 v[32:35], v80, s[28:29] offset:0
	global_load_dwordx4 v[36:39], v80, s[28:29] offset:16
	global_load_dwordx4 v[40:43], v80, s[28:29] offset:2048
	global_load_dwordx4 v[44:47], v80, s[28:29] offset:2064
	global_load_dwordx4 v[48:51], v80, s[30:31] offset:0
	global_load_dwordx4 v[52:55], v80, s[30:31] offset:16
	global_load_dwordx4 v[56:59], v80, s[30:31] offset:2048
	global_load_dwordx4 v[60:63], v80, s[30:31] offset:2064
	s_waitcnt vmcnt(40)
	v_pk_mul_f32 v[240:241], v[96:97], v[96:97]
	v_pk_mul_f32 v[242:243], v[112:113], v[112:113]
	v_pk_mul_f32 v[244:245], v[128:129], v[128:129]
	v_pk_mul_f32 v[246:247], v[144:145], v[144:145]
	v_pk_fma_f32 v[240:241], v[98:99], v[98:99], v[240:241]
	v_pk_fma_f32 v[242:243], v[114:115], v[114:115], v[242:243]
	v_pk_fma_f32 v[244:245], v[130:131], v[130:131], v[244:245]
	v_pk_fma_f32 v[246:247], v[146:147], v[146:147], v[246:247]
	v_pk_fma_f32 v[240:241], v[100:101], v[100:101], v[240:241]
	v_pk_fma_f32 v[242:243], v[116:117], v[116:117], v[242:243]
	v_pk_fma_f32 v[244:245], v[132:133], v[132:133], v[244:245]
	v_pk_fma_f32 v[246:247], v[148:149], v[148:149], v[246:247]
	v_pk_fma_f32 v[240:241], v[102:103], v[102:103], v[240:241]
	v_pk_fma_f32 v[242:243], v[118:119], v[118:119], v[242:243]
	v_pk_fma_f32 v[244:245], v[134:135], v[134:135], v[244:245]
	v_pk_fma_f32 v[246:247], v[150:151], v[150:151], v[246:247]
	v_pk_fma_f32 v[240:241], v[104:105], v[104:105], v[240:241]
	v_pk_fma_f32 v[242:243], v[120:121], v[120:121], v[242:243]
	v_pk_fma_f32 v[244:245], v[136:137], v[136:137], v[244:245]
	v_pk_fma_f32 v[246:247], v[152:153], v[152:153], v[246:247]
	v_pk_fma_f32 v[240:241], v[106:107], v[106:107], v[240:241]
	v_pk_fma_f32 v[242:243], v[122:123], v[122:123], v[242:243]
	v_pk_fma_f32 v[244:245], v[138:139], v[138:139], v[244:245]
	v_pk_fma_f32 v[246:247], v[154:155], v[154:155], v[246:247]
	v_pk_fma_f32 v[240:241], v[108:109], v[108:109], v[240:241]
	v_pk_fma_f32 v[242:243], v[124:125], v[124:125], v[242:243]
	v_pk_fma_f32 v[244:245], v[140:141], v[140:141], v[244:245]
	v_pk_fma_f32 v[246:247], v[156:157], v[156:157], v[246:247]
	v_pk_fma_f32 v[240:241], v[110:111], v[110:111], v[240:241]
	v_pk_fma_f32 v[242:243], v[126:127], v[126:127], v[242:243]
	v_pk_fma_f32 v[244:245], v[142:143], v[142:143], v[244:245]
	v_pk_fma_f32 v[246:247], v[158:159], v[158:159], v[246:247]
	v_add_f32_e32 v224, v240, v241
	v_add_f32_e32 v225, v242, v243
	v_add_f32_e32 v226, v244, v245
	v_add_f32_e32 v227, v246, v247
	ds_bpermute_b32 v228, v83, v224
	ds_bpermute_b32 v229, v83, v225
	ds_bpermute_b32 v230, v83, v226
	ds_bpermute_b32 v231, v83, v227
	s_waitcnt lgkmcnt(0)
; template <bool BF> __device__ __forceinline__ void prep_rows(const float* xp, const float* xs, const bf16* hb, const float* g, const float* MOD, int shoff, int scoff, bf16* U, int gw, int NGW, int lane) {
;     ...
;             for (int r = 0; r < R; ++r) s[r] += __shfl_xor(s[r], o); }
; #pragma unroll
;         for (int r = 0; r < R; ++r) { const int m = mb + r * NGW; if (m < MT) {
;             const float rstd = 1.0f / sqrtf(s[r] * (1.0f / DM) + RMS_EPS);
	v_add_f32_e32 v224, v224, v228
	v_add_f32_e32 v225, v225, v229
	v_add_f32_e32 v226, v226, v230
	v_add_f32_e32 v227, v227, v231
	ds_bpermute_b32 v228, v84, v224
	ds_bpermute_b32 v229, v84, v225
	ds_bpermute_b32 v230, v84, v226
	ds_bpermute_b32 v231, v84, v227
	s_waitcnt lgkmcnt(0)
	v_add_f32_e32 v224, v224, v228
	v_add_f32_e32 v225, v225, v229
	v_add_f32_e32 v226, v226, v230
	v_add_f32_e32 v227, v227, v231
	ds_bpermute_b32 v228, v85, v224
	ds_bpermute_b32 v229, v85, v225
	ds_bpermute_b32 v230, v85, v226
	ds_bpermute_b32 v231, v85, v227
	s_waitcnt lgkmcnt(0)
	v_add_f32_e32 v224, v224, v228
	v_add_f32_e32 v225, v225, v229
	v_add_f32_e32 v226, v226, v230
	v_add_f32_e32 v227, v227, v231
	ds_bpermute_b32 v228, v86, v224
	ds_bpermute_b32 v229, v86, v225
	ds_bpermute_b32 v230, v86, v226
	ds_bpermute_b32 v231, v86, v227
	s_waitcnt lgkmcnt(0)
	v_add_f32_e32 v224, v224, v228
	v_add_f32_e32 v225, v225, v229
	v_add_f32_e32 v226, v226, v230
	v_add_f32_e32 v227, v227, v231
	ds_bpermute_b32 v228, v87, v224
	ds_bpermute_b32 v229, v87, v225
	ds_bpermute_b32 v230, v87, v226
	ds_bpermute_b32 v231, v87, v227
	s_waitcnt lgkmcnt(0)
	v_add_f32_e32 v224, v224, v228
	v_add_f32_e32 v225, v225, v229
	v_add_f32_e32 v226, v226, v230
	v_add_f32_e32 v227, v227, v231
	ds_bpermute_b32 v228, v88, v224
	ds_bpermute_b32 v229, v88, v225
	ds_bpermute_b32 v230, v88, v226
	ds_bpermute_b32 v231, v88, v227
	s_waitcnt lgkmcnt(0)
	v_add_f32_e32 v224, v224, v228
	v_add_f32_e32 v225, v225, v229
	v_add_f32_e32 v226, v226, v230
	v_add_f32_e32 v227, v227, v231
	v_fmamk_f32 v240, v224, 0x3a800000, v89
	v_mul_f32_e32 v241, 0x4f800000, v240
	v_cmp_gt_f32_e32 vcc, s54, v240
	s_nop 1
	v_cndmask_b32_e32 v247, v240, v241, vcc
	v_sqrt_f32_e32 v242, v247
	s_nop 1
	v_add_u32_e32 v243, -1, v242
	v_add_u32_e32 v244, 1, v242
	v_fma_f32 v245, -v243, v242, v247
	v_fma_f32 v246, -v244, v242, v247
	v_cmp_ge_f32_e64 s[52:53], 0, v245
	s_nop 1
	v_cndmask_b32_e64 v242, v242, v243, s[52:53]
	v_cmp_lt_f32_e64 s[52:53], 0, v246
	s_nop 1
	v_cndmask_b32_e64 v242, v242, v244, s[52:53]
	v_mul_f32_e32 v243, 0x37800000, v242
	v_cndmask_b32_e32 v242, v242, v243, vcc
	v_cmp_class_f32_e32 vcc, v247, v90
	s_nop 1
	v_cndmask_b32_e32 v247, v242, v247, vcc
	v_div_scale_f32 v248, s[52:53], v247, v247, 1.0
	v_rcp_f32_e32 v249, v248
	v_div_scale_f32 v228, vcc, 1.0, v247, 1.0
	s_nop 0
	v_fma_f32 v229, -v248, v249, 1.0
	v_fmac_f32_e32 v249, v229, v249
	v_mul_f32_e32 v230, v228, v249
	v_fma_f32 v229, -v248, v230, v228
	v_fmac_f32_e32 v230, v229, v249
	v_fma_f32 v248, -v248, v230, v228
	v_div_fmas_f32 v248, v248, v249, v230
	v_div_fixup_f32 v232, v248, v247, 1.0
	v_fmamk_f32 v240, v225, 0x3a800000, v89
	v_mul_f32_e32 v241, 0x4f800000, v240
	v_cmp_gt_f32_e32 vcc, s54, v240
	s_nop 1
	v_cndmask_b32_e32 v247, v240, v241, vcc
	v_sqrt_f32_e32 v242, v247
	s_nop 1
	v_add_u32_e32 v243, -1, v242
	v_add_u32_e32 v244, 1, v242
	v_fma_f32 v245, -v243, v242, v247
	v_fma_f32 v246, -v244, v242, v247
	v_cmp_ge_f32_e64 s[52:53], 0, v245
	s_nop 1
	v_cndmask_b32_e64 v242, v242, v243, s[52:53]
	v_cmp_lt_f32_e64 s[52:53], 0, v246
	s_nop 1
	v_cndmask_b32_e64 v242, v242, v244, s[52:53]
	v_mul_f32_e32 v243, 0x37800000, v242
	v_cndmask_b32_e32 v242, v242, v243, vcc
	v_cmp_class_f32_e32 vcc, v247, v90
	s_nop 1
	v_cndmask_b32_e32 v247, v242, v247, vcc
	v_div_scale_f32 v248, s[52:53], v247, v247, 1.0
	v_rcp_f32_e32 v249, v248
	v_div_scale_f32 v228, vcc, 1.0, v247, 1.0
	s_nop 0
	v_fma_f32 v229, -v248, v249, 1.0
	v_fmac_f32_e32 v249, v229, v249
	v_mul_f32_e32 v230, v228, v249
	v_fma_f32 v229, -v248, v230, v228
	v_fmac_f32_e32 v230, v229, v249
	v_fma_f32 v248, -v248, v230, v228
	v_div_fmas_f32 v248, v248, v249, v230
	v_div_fixup_f32 v234, v248, v247, 1.0
	v_fmamk_f32 v240, v226, 0x3a800000, v89
	v_mul_f32_e32 v241, 0x4f800000, v240
	v_cmp_gt_f32_e32 vcc, s54, v240
	s_nop 1
	v_cndmask_b32_e32 v247, v240, v241, vcc
	v_sqrt_f32_e32 v242, v247
	s_nop 1
	v_add_u32_e32 v243, -1, v242
	v_add_u32_e32 v244, 1, v242
	v_fma_f32 v245, -v243, v242, v247
	v_fma_f32 v246, -v244, v242, v247
	v_cmp_ge_f32_e64 s[52:53], 0, v245
	s_nop 1
	v_cndmask_b32_e64 v242, v242, v243, s[52:53]
	v_cmp_lt_f32_e64 s[52:53], 0, v246
	s_nop 1
	v_cndmask_b32_e64 v242, v242, v244, s[52:53]
	v_mul_f32_e32 v243, 0x37800000, v242
	v_cndmask_b32_e32 v242, v242, v243, vcc
	v_cmp_class_f32_e32 vcc, v247, v90
	s_nop 1
	v_cndmask_b32_e32 v247, v242, v247, vcc
	v_div_scale_f32 v248, s[52:53], v247, v247, 1.0
	v_rcp_f32_e32 v249, v248
	v_div_scale_f32 v228, vcc, 1.0, v247, 1.0
	s_nop 0
	v_fma_f32 v229, -v248, v249, 1.0
	v_fmac_f32_e32 v249, v229, v249
	v_mul_f32_e32 v230, v228, v249
	v_fma_f32 v229, -v248, v230, v228
	v_fmac_f32_e32 v230, v229, v249
	v_fma_f32 v248, -v248, v230, v228
	v_div_fmas_f32 v248, v248, v249, v230
	v_div_fixup_f32 v236, v248, v247, 1.0
	v_fmamk_f32 v240, v227, 0x3a800000, v89
	v_mul_f32_e32 v241, 0x4f800000, v240
	v_cmp_gt_f32_e32 vcc, s54, v240
	s_nop 1
	v_cndmask_b32_e32 v247, v240, v241, vcc
	v_sqrt_f32_e32 v242, v247
	s_nop 1
	v_add_u32_e32 v243, -1, v242
	v_add_u32_e32 v244, 1, v242
	v_fma_f32 v245, -v243, v242, v247
	v_fma_f32 v246, -v244, v242, v247
	v_cmp_ge_f32_e64 s[52:53], 0, v245
	s_nop 1
	v_cndmask_b32_e64 v242, v242, v243, s[52:53]
	v_cmp_lt_f32_e64 s[52:53], 0, v246
	s_nop 1
	v_cndmask_b32_e64 v242, v242, v244, s[52:53]
	v_mul_f32_e32 v243, 0x37800000, v242
	v_cndmask_b32_e32 v242, v242, v243, vcc
	v_cmp_class_f32_e32 vcc, v247, v90
	s_nop 1
	v_cndmask_b32_e32 v247, v242, v247, vcc
	v_div_scale_f32 v248, s[52:53], v247, v247, 1.0
	v_rcp_f32_e32 v249, v248
	v_div_scale_f32 v228, vcc, 1.0, v247, 1.0
	s_nop 0
	v_fma_f32 v229, -v248, v249, 1.0
	v_fmac_f32_e32 v249, v229, v249
	v_mul_f32_e32 v230, v228, v249
	v_fma_f32 v229, -v248, v230, v228
	v_fmac_f32_e32 v230, v229, v249
	v_fma_f32 v248, -v248, v230, v228
	v_div_fmas_f32 v248, v248, v249, v230
	v_div_fixup_f32 v238, v248, v247, 1.0
	s_waitcnt vmcnt(16)
; __device__ __forceinline__ unsigned pk2(float lo, float hi) { return pg8::cvt_pk_bf16(lo, hi); }
; template <bool BF> __device__ __forceinline__ void prep_rows(const float* xp, const float* xs, const bf16* hb, const float* g, const float* MOD, int shoff, int scoff, bf16* U, int gw, int NGW, int lane) {
;     ...
;                 const f32x4 gg = *(const f32x4*)(g + c), sc = *(const f32x4*)(mr + scoff + c), sh = *(const f32x4*)(mr + shoff + c);
;                 const f32x4 o = v[r][j] * rstd * gg * (sc + 1.0f) + sh; v2u w; w.x = pk2(o.x, o.y); w.y = pk2(o.z, o.w); *(v2u*)(U + (size_t)m * DM + c) = w; } } }
	v_pk_add_f32 v[160:161], v[160:161], 1.0 op_sel_hi:[1,0]
	v_pk_add_f32 v[162:163], v[162:163], 1.0 op_sel_hi:[1,0]
	v_pk_add_f32 v[164:165], v[164:165], 1.0 op_sel_hi:[1,0]
	v_pk_add_f32 v[166:167], v[166:167], 1.0 op_sel_hi:[1,0]
	v_pk_add_f32 v[168:169], v[168:169], 1.0 op_sel_hi:[1,0]
	v_pk_add_f32 v[170:171], v[170:171], 1.0 op_sel_hi:[1,0]
	v_pk_add_f32 v[172:173], v[172:173], 1.0 op_sel_hi:[1,0]
	v_pk_add_f32 v[174:175], v[174:175], 1.0 op_sel_hi:[1,0]
	v_pk_add_f32 v[192:193], v[192:193], 1.0 op_sel_hi:[1,0]
	v_pk_add_f32 v[194:195], v[194:195], 1.0 op_sel_hi:[1,0]
	v_pk_add_f32 v[196:197], v[196:197], 1.0 op_sel_hi:[1,0]
	v_pk_add_f32 v[198:199], v[198:199], 1.0 op_sel_hi:[1,0]
	v_pk_add_f32 v[200:201], v[200:201], 1.0 op_sel_hi:[1,0]
	v_pk_add_f32 v[202:203], v[202:203], 1.0 op_sel_hi:[1,0]
	v_pk_add_f32 v[204:205], v[204:205], 1.0 op_sel_hi:[1,0]
	v_pk_add_f32 v[206:207], v[206:207], 1.0 op_sel_hi:[1,0]
	s_add_u32 s38, s20, 0x3000000
	s_addc_u32 s39, s21, 0
	s_add_u32 s40, s20, 0x3400000
	s_addc_u32 s41, s21, 0
	s_add_u32 s46, s20, 0x3800000
	s_addc_u32 s47, s21, 0
	s_add_u32 s48, s20, 0x3c00000
	s_addc_u32 s49, s21, 0
	v_pk_mul_f32 v[96:97], v[96:97], v[232:233] op_sel_hi:[1,0]
	v_pk_mul_f32 v[98:99], v[98:99], v[232:233] op_sel_hi:[1,0]
	v_pk_mul_f32 v[96:97], v[64:65], v[96:97]
	v_pk_mul_f32 v[98:99], v[66:67], v[98:99]
	v_pk_fma_f32 v[96:97], v[160:161], v[96:97], v[176:177]
	v_pk_fma_f32 v[98:99], v[162:163], v[98:99], v[178:179]
	v_cvt_pk_bf16_f32 v244, v96, v97
	v_cvt_pk_bf16_f32 v245, v98, v99
	v_pk_mul_f32 v[100:101], v[100:101], v[232:233] op_sel_hi:[1,0]
	v_pk_mul_f32 v[102:103], v[102:103], v[232:233] op_sel_hi:[1,0]
	v_pk_mul_f32 v[100:101], v[68:69], v[100:101]
	v_pk_mul_f32 v[102:103], v[70:71], v[102:103]
	v_pk_fma_f32 v[100:101], v[164:165], v[100:101], v[180:181]
	v_pk_fma_f32 v[102:103], v[166:167], v[102:103], v[182:183]
	v_cvt_pk_bf16_f32 v246, v100, v101
	v_cvt_pk_bf16_f32 v247, v102, v103
	global_store_dwordx4 v82, v[244:247], s[38:39] offset:0
	v_pk_mul_f32 v[104:105], v[104:105], v[232:233] op_sel_hi:[1,0]
	v_pk_mul_f32 v[106:107], v[106:107], v[232:233] op_sel_hi:[1,0]
	v_pk_mul_f32 v[104:105], v[72:73], v[104:105]
	v_pk_mul_f32 v[106:107], v[74:75], v[106:107]
	v_pk_fma_f32 v[104:105], v[168:169], v[104:105], v[184:185]
	v_pk_fma_f32 v[106:107], v[170:171], v[106:107], v[186:187]
	v_cvt_pk_bf16_f32 v240, v104, v105
	v_cvt_pk_bf16_f32 v241, v106, v107
	v_pk_mul_f32 v[108:109], v[108:109], v[232:233] op_sel_hi:[1,0]
	v_pk_mul_f32 v[110:111], v[110:111], v[232:233] op_sel_hi:[1,0]
	v_pk_mul_f32 v[108:109], v[76:77], v[108:109]
	v_pk_mul_f32 v[110:111], v[78:79], v[110:111]
	v_pk_fma_f32 v[108:109], v[172:173], v[108:109], v[188:189]
	v_pk_fma_f32 v[110:111], v[174:175], v[110:111], v[190:191]
	v_cvt_pk_bf16_f32 v242, v108, v109
	v_cvt_pk_bf16_f32 v243, v110, v111
	global_store_dwordx4 v82, v[240:243], s[38:39] offset:1024
	v_pk_mul_f32 v[112:113], v[112:113], v[234:235] op_sel_hi:[1,0]
	v_pk_mul_f32 v[114:115], v[114:115], v[234:235] op_sel_hi:[1,0]
	v_pk_mul_f32 v[112:113], v[64:65], v[112:113]
	v_pk_mul_f32 v[114:115], v[66:67], v[114:115]
	v_pk_fma_f32 v[112:113], v[160:161], v[112:113], v[176:177]
	v_pk_fma_f32 v[114:115], v[162:163], v[114:115], v[178:179]
	v_cvt_pk_bf16_f32 v244, v112, v113
	v_cvt_pk_bf16_f32 v245, v114, v115
	v_pk_mul_f32 v[116:117], v[116:117], v[234:235] op_sel_hi:[1,0]
	v_pk_mul_f32 v[118:119], v[118:119], v[234:235] op_sel_hi:[1,0]
	v_pk_mul_f32 v[116:117], v[68:69], v[116:117]
	v_pk_mul_f32 v[118:119], v[70:71], v[118:119]
	v_pk_fma_f32 v[116:117], v[164:165], v[116:117], v[180:181]
	v_pk_fma_f32 v[118:119], v[166:167], v[118:119], v[182:183]
	v_cvt_pk_bf16_f32 v246, v116, v117
	v_cvt_pk_bf16_f32 v247, v118, v119
	global_store_dwordx4 v82, v[244:247], s[40:41] offset:0
	v_pk_mul_f32 v[120:121], v[120:121], v[234:235] op_sel_hi:[1,0]
	v_pk_mul_f32 v[122:123], v[122:123], v[234:235] op_sel_hi:[1,0]
	v_pk_mul_f32 v[120:121], v[72:73], v[120:121]
	v_pk_mul_f32 v[122:123], v[74:75], v[122:123]
	v_pk_fma_f32 v[120:121], v[168:169], v[120:121], v[184:185]
	v_pk_fma_f32 v[122:123], v[170:171], v[122:123], v[186:187]
	v_cvt_pk_bf16_f32 v240, v120, v121
	v_cvt_pk_bf16_f32 v241, v122, v123
	v_pk_mul_f32 v[124:125], v[124:125], v[234:235] op_sel_hi:[1,0]
	v_pk_mul_f32 v[126:127], v[126:127], v[234:235] op_sel_hi:[1,0]
	v_pk_mul_f32 v[124:125], v[76:77], v[124:125]
	v_pk_mul_f32 v[126:127], v[78:79], v[126:127]
	v_pk_fma_f32 v[124:125], v[172:173], v[124:125], v[188:189]
	v_pk_fma_f32 v[126:127], v[174:175], v[126:127], v[190:191]
	v_cvt_pk_bf16_f32 v242, v124, v125
	v_cvt_pk_bf16_f32 v243, v126, v127
	global_store_dwordx4 v82, v[240:243], s[40:41] offset:1024
	v_pk_mul_f32 v[128:129], v[128:129], v[236:237] op_sel_hi:[1,0]
	v_pk_mul_f32 v[130:131], v[130:131], v[236:237] op_sel_hi:[1,0]
	v_pk_mul_f32 v[128:129], v[64:65], v[128:129]
	v_pk_mul_f32 v[130:131], v[66:67], v[130:131]
	v_pk_fma_f32 v[128:129], v[192:193], v[128:129], v[208:209]
	v_pk_fma_f32 v[130:131], v[194:195], v[130:131], v[210:211]
	v_cvt_pk_bf16_f32 v244, v128, v129
	v_cvt_pk_bf16_f32 v245, v130, v131
	v_pk_mul_f32 v[132:133], v[132:133], v[236:237] op_sel_hi:[1,0]
	v_pk_mul_f32 v[134:135], v[134:135], v[236:237] op_sel_hi:[1,0]
	v_pk_mul_f32 v[132:133], v[68:69], v[132:133]
	v_pk_mul_f32 v[134:135], v[70:71], v[134:135]
	v_pk_fma_f32 v[132:133], v[196:197], v[132:133], v[212:213]
	v_pk_fma_f32 v[134:135], v[198:199], v[134:135], v[214:215]
	v_cvt_pk_bf16_f32 v246, v132, v133
	v_cvt_pk_bf16_f32 v247, v134, v135
	global_store_dwordx4 v82, v[244:247], s[46:47] offset:0
	v_pk_mul_f32 v[136:137], v[136:137], v[236:237] op_sel_hi:[1,0]
; __device__ __forceinline__ float bf_lo(unsigned w) { return __uint_as_float(w << 16); }
; __device__ __forceinline__ float bf_hi(unsigned w) { return __uint_as_float(w & 0xffff0000u); }
; __device__ __forceinline__ unsigned pk2(float lo, float hi) { return pg8::cvt_pk_bf16(lo, hi); }
; template <bool BF> __device__ __forceinline__ void prep_rows(const float* xp, const float* xs, const bf16* hb, const float* g, const float* MOD, int shoff, int scoff, bf16* U, int gw, int NGW, int lane) {
;     ...
;         for (int r = 0; r < R; ++r) { const int m = mb + r * NGW; const int mc = m < MT ? m : mb;
; #pragma unroll
;             for (int j = 0; j < 4; ++j) {
;                 if (BF) { const v2u a0 = *(const v2u*)(hb + (size_t)mc * DM + 4 * lane + 256 * j);
;                     v[r][j].x = pg8::bf_lo(a0.x); v[r][j].y = pg8::bf_hi(a0.x); v[r][j].z = pg8::bf_lo(a0.y); v[r][j].w = pg8::bf_hi(a0.y); }
;                 else { const float* xr = mc < MP ? xp + (size_t)mc * DM : xs + (size_t)(mc - MP) * DM; v[r][j] = *(const f32x4*)(xr + 4 * lane + 256 * j); } } }
;     ...
;                 const f32x4 o = v[r][j] * rstd * gg * (sc + 1.0f) + sh; v2u w; w.x = pk2(o.x, o.y); w.y = pk2(o.z, o.w); *(v2u*)(U + (size_t)m * DM + c) = w; } } }
	v_pk_mul_f32 v[138:139], v[138:139], v[236:237] op_sel_hi:[1,0]
	v_pk_mul_f32 v[136:137], v[72:73], v[136:137]
	v_pk_mul_f32 v[138:139], v[74:75], v[138:139]
	v_pk_fma_f32 v[136:137], v[200:201], v[136:137], v[216:217]
	v_pk_fma_f32 v[138:139], v[202:203], v[138:139], v[218:219]
	v_cvt_pk_bf16_f32 v240, v136, v137
	v_cvt_pk_bf16_f32 v241, v138, v139
	v_pk_mul_f32 v[140:141], v[140:141], v[236:237] op_sel_hi:[1,0]
	v_pk_mul_f32 v[142:143], v[142:143], v[236:237] op_sel_hi:[1,0]
	v_pk_mul_f32 v[140:141], v[76:77], v[140:141]
	v_pk_mul_f32 v[142:143], v[78:79], v[142:143]
	v_pk_fma_f32 v[140:141], v[204:205], v[140:141], v[220:221]
	v_pk_fma_f32 v[142:143], v[206:207], v[142:143], v[222:223]
	v_cvt_pk_bf16_f32 v242, v140, v141
	v_cvt_pk_bf16_f32 v243, v142, v143
	global_store_dwordx4 v82, v[240:243], s[46:47] offset:1024
	v_pk_mul_f32 v[144:145], v[144:145], v[238:239] op_sel_hi:[1,0]
	v_pk_mul_f32 v[146:147], v[146:147], v[238:239] op_sel_hi:[1,0]
	v_pk_mul_f32 v[144:145], v[64:65], v[144:145]
	v_pk_mul_f32 v[146:147], v[66:67], v[146:147]
	v_pk_fma_f32 v[144:145], v[192:193], v[144:145], v[208:209]
	v_pk_fma_f32 v[146:147], v[194:195], v[146:147], v[210:211]
	v_cvt_pk_bf16_f32 v244, v144, v145
	v_cvt_pk_bf16_f32 v245, v146, v147
	v_pk_mul_f32 v[148:149], v[148:149], v[238:239] op_sel_hi:[1,0]
	v_pk_mul_f32 v[150:151], v[150:151], v[238:239] op_sel_hi:[1,0]
	v_pk_mul_f32 v[148:149], v[68:69], v[148:149]
	v_pk_mul_f32 v[150:151], v[70:71], v[150:151]
	v_pk_fma_f32 v[148:149], v[196:197], v[148:149], v[212:213]
	v_pk_fma_f32 v[150:151], v[198:199], v[150:151], v[214:215]
	v_cvt_pk_bf16_f32 v246, v148, v149
	v_cvt_pk_bf16_f32 v247, v150, v151
	global_store_dwordx4 v82, v[244:247], s[48:49] offset:0
	v_pk_mul_f32 v[152:153], v[152:153], v[238:239] op_sel_hi:[1,0]
	v_pk_mul_f32 v[154:155], v[154:155], v[238:239] op_sel_hi:[1,0]
	v_pk_mul_f32 v[152:153], v[72:73], v[152:153]
	v_pk_mul_f32 v[154:155], v[74:75], v[154:155]
	v_pk_fma_f32 v[152:153], v[200:201], v[152:153], v[216:217]
	v_pk_fma_f32 v[154:155], v[202:203], v[154:155], v[218:219]
	v_cvt_pk_bf16_f32 v240, v152, v153
	v_cvt_pk_bf16_f32 v241, v154, v155
	v_pk_mul_f32 v[156:157], v[156:157], v[238:239] op_sel_hi:[1,0]
	v_pk_mul_f32 v[158:159], v[158:159], v[238:239] op_sel_hi:[1,0]
	v_pk_mul_f32 v[156:157], v[76:77], v[156:157]
	v_pk_mul_f32 v[158:159], v[78:79], v[158:159]
	v_pk_fma_f32 v[156:157], v[204:205], v[156:157], v[220:221]
	v_pk_fma_f32 v[158:159], v[206:207], v[158:159], v[222:223]
	v_cvt_pk_bf16_f32 v242, v156, v157
	v_cvt_pk_bf16_f32 v243, v158, v159
	global_store_dwordx4 v82, v[240:243], s[48:49] offset:1024
	s_add_u32 s34, s8, 0x18000
	s_addc_u32 s35, s9, 0
	s_add_u32 s36, s8, 0x18000
	s_addc_u32 s37, s9, 0
	global_load_dwordx4 v[176:179], v80, s[34:35] offset:0
	global_load_dwordx4 v[180:183], v80, s[34:35] offset:16
	global_load_dwordx4 v[184:187], v80, s[34:35] offset:2048
	global_load_dwordx4 v[188:191], v80, s[34:35] offset:2064
	global_load_dwordx4 v[160:163], v81, s[34:35] offset:0
	global_load_dwordx4 v[164:167], v81, s[34:35] offset:16
	global_load_dwordx4 v[168:171], v81, s[34:35] offset:2048
	global_load_dwordx4 v[172:175], v81, s[34:35] offset:2064
	global_load_dwordx4 v[208:211], v80, s[36:37] offset:0
	global_load_dwordx4 v[212:215], v80, s[36:37] offset:16
	global_load_dwordx4 v[216:219], v80, s[36:37] offset:2048
	global_load_dwordx4 v[220:223], v80, s[36:37] offset:2064
	global_load_dwordx4 v[192:195], v81, s[36:37] offset:0
	global_load_dwordx4 v[196:199], v81, s[36:37] offset:16
	global_load_dwordx4 v[200:203], v81, s[36:37] offset:2048
	global_load_dwordx4 v[204:207], v81, s[36:37] offset:2064
	s_add_u32 s24, s16, 0xa000000
	s_addc_u32 s25, s17, 0
	s_add_u32 s26, s16, 0xa800000
	s_addc_u32 s27, s17, 0
	s_add_u32 s28, s16, 0xb000000
	s_addc_u32 s29, s17, 0
	s_add_u32 s30, s16, 0xb800000
	s_addc_u32 s31, s17, 0
	global_load_dwordx4 v[96:99], v80, s[24:25] offset:0
	global_load_dwordx4 v[100:103], v80, s[24:25] offset:16
	global_load_dwordx4 v[104:107], v80, s[24:25] offset:2048
	global_load_dwordx4 v[108:111], v80, s[24:25] offset:2064
	global_load_dwordx4 v[112:115], v80, s[26:27] offset:0
	global_load_dwordx4 v[116:119], v80, s[26:27] offset:16
	global_load_dwordx4 v[120:123], v80, s[26:27] offset:2048
	global_load_dwordx4 v[124:127], v80, s[26:27] offset:2064
	global_load_dwordx4 v[128:131], v80, s[28:29] offset:0
	global_load_dwordx4 v[132:135], v80, s[28:29] offset:16
	global_load_dwordx4 v[136:139], v80, s[28:29] offset:2048
	global_load_dwordx4 v[140:143], v80, s[28:29] offset:2064
	global_load_dwordx4 v[144:147], v80, s[30:31] offset:0
	global_load_dwordx4 v[148:151], v80, s[30:31] offset:16
	global_load_dwordx4 v[152:155], v80, s[30:31] offset:2048
	global_load_dwordx4 v[156:159], v80, s[30:31] offset:2064
	s_waitcnt vmcnt(40)
; template <bool BF> __device__ __forceinline__ void prep_rows(const float* xp, const float* xs, const bf16* hb, const float* g, const float* MOD, int shoff, int scoff, bf16* U, int gw, int NGW, int lane) {
;     ...
;         for (int r = 0; r < R; ++r) { float t = 0.f;
; #pragma unroll
;             for (int j = 0; j < 4; ++j) t += (v[r][j].x * v[r][j].x + v[r][j].y * v[r][j].y) + (v[r][j].z * v[r][j].z + v[r][j].w * v[r][j].w);
;             s[r] = t; }
; #pragma unroll
;         for (int o = 1; o < 64; o <<= 1) {
; #pragma unroll
;             for (int r = 0; r < R; ++r) s[r] += __shfl_xor(s[r], o); }
; #pragma unroll
;         for (int r = 0; r < R; ++r) { const int m = mb + r * NGW; if (m < MT) {
;             const float rstd = 1.0f / sqrtf(s[r] * (1.0f / DM) + RMS_EPS);
	v_pk_mul_f32 v[240:241], v[0:1], v[0:1]
	v_pk_mul_f32 v[242:243], v[16:17], v[16:17]
	v_pk_mul_f32 v[244:245], v[32:33], v[32:33]
	v_pk_mul_f32 v[246:247], v[48:49], v[48:49]
	v_pk_fma_f32 v[240:241], v[2:3], v[2:3], v[240:241]
	v_pk_fma_f32 v[242:243], v[18:19], v[18:19], v[242:243]
	v_pk_fma_f32 v[244:245], v[34:35], v[34:35], v[244:245]
	v_pk_fma_f32 v[246:247], v[50:51], v[50:51], v[246:247]
	v_pk_fma_f32 v[240:241], v[4:5], v[4:5], v[240:241]
	v_pk_fma_f32 v[242:243], v[20:21], v[20:21], v[242:243]
	v_pk_fma_f32 v[244:245], v[36:37], v[36:37], v[244:245]
	v_pk_fma_f32 v[246:247], v[52:53], v[52:53], v[246:247]
	v_pk_fma_f32 v[240:241], v[6:7], v[6:7], v[240:241]
	v_pk_fma_f32 v[242:243], v[22:23], v[22:23], v[242:243]
	v_pk_fma_f32 v[244:245], v[38:39], v[38:39], v[244:245]
	v_pk_fma_f32 v[246:247], v[54:55], v[54:55], v[246:247]
	v_pk_fma_f32 v[240:241], v[8:9], v[8:9], v[240:241]
	v_pk_fma_f32 v[242:243], v[24:25], v[24:25], v[242:243]
	v_pk_fma_f32 v[244:245], v[40:41], v[40:41], v[244:245]
	v_pk_fma_f32 v[246:247], v[56:57], v[56:57], v[246:247]
	v_pk_fma_f32 v[240:241], v[10:11], v[10:11], v[240:241]
	v_pk_fma_f32 v[242:243], v[26:27], v[26:27], v[242:243]
	v_pk_fma_f32 v[244:245], v[42:43], v[42:43], v[244:245]
	v_pk_fma_f32 v[246:247], v[58:59], v[58:59], v[246:247]
	v_pk_fma_f32 v[240:241], v[12:13], v[12:13], v[240:241]
	v_pk_fma_f32 v[242:243], v[28:29], v[28:29], v[242:243]
	v_pk_fma_f32 v[244:245], v[44:45], v[44:45], v[244:245]
	v_pk_fma_f32 v[246:247], v[60:61], v[60:61], v[246:247]
	v_pk_fma_f32 v[240:241], v[14:15], v[14:15], v[240:241]
	v_pk_fma_f32 v[242:243], v[30:31], v[30:31], v[242:243]
	v_pk_fma_f32 v[244:245], v[46:47], v[46:47], v[244:245]
	v_pk_fma_f32 v[246:247], v[62:63], v[62:63], v[246:247]
	v_add_f32_e32 v224, v240, v241
	v_add_f32_e32 v225, v242, v243
	v_add_f32_e32 v226, v244, v245
	v_add_f32_e32 v227, v246, v247
	ds_bpermute_b32 v228, v83, v224
	ds_bpermute_b32 v229, v83, v225
	ds_bpermute_b32 v230, v83, v226
	ds_bpermute_b32 v231, v83, v227
	s_waitcnt lgkmcnt(0)
	v_add_f32_e32 v224, v224, v228
	v_add_f32_e32 v225, v225, v229
	v_add_f32_e32 v226, v226, v230
	v_add_f32_e32 v227, v227, v231
	ds_bpermute_b32 v228, v84, v224
	ds_bpermute_b32 v229, v84, v225
	ds_bpermute_b32 v230, v84, v226
	ds_bpermute_b32 v231, v84, v227
	s_waitcnt lgkmcnt(0)
	v_add_f32_e32 v224, v224, v228
	v_add_f32_e32 v225, v225, v229
	v_add_f32_e32 v226, v226, v230
	v_add_f32_e32 v227, v227, v231
	ds_bpermute_b32 v228, v85, v224
	ds_bpermute_b32 v229, v85, v225
	ds_bpermute_b32 v230, v85, v226
	ds_bpermute_b32 v231, v85, v227
	s_waitcnt lgkmcnt(0)
	v_add_f32_e32 v224, v224, v228
	v_add_f32_e32 v225, v225, v229
	v_add_f32_e32 v226, v226, v230
	v_add_f32_e32 v227, v227, v231
	ds_bpermute_b32 v228, v86, v224
	ds_bpermute_b32 v229, v86, v225
	ds_bpermute_b32 v230, v86, v226
	ds_bpermute_b32 v231, v86, v227
	s_waitcnt lgkmcnt(0)
	v_add_f32_e32 v224, v224, v228
	v_add_f32_e32 v225, v225, v229
	v_add_f32_e32 v226, v226, v230
	v_add_f32_e32 v227, v227, v231
	ds_bpermute_b32 v228, v87, v224
	ds_bpermute_b32 v229, v87, v225
	ds_bpermute_b32 v230, v87, v226
	ds_bpermute_b32 v231, v87, v227
	s_waitcnt lgkmcnt(0)
	v_add_f32_e32 v224, v224, v228
	v_add_f32_e32 v225, v225, v229
	v_add_f32_e32 v226, v226, v230
	v_add_f32_e32 v227, v227, v231
	ds_bpermute_b32 v228, v88, v224
	ds_bpermute_b32 v229, v88, v225
	ds_bpermute_b32 v230, v88, v226
	ds_bpermute_b32 v231, v88, v227
	s_waitcnt lgkmcnt(0)
	v_add_f32_e32 v224, v224, v228
	v_add_f32_e32 v225, v225, v229
	v_add_f32_e32 v226, v226, v230
	v_add_f32_e32 v227, v227, v231
	v_fmamk_f32 v240, v224, 0x3a800000, v89
	v_mul_f32_e32 v241, 0x4f800000, v240
	v_cmp_gt_f32_e32 vcc, s54, v240
	s_nop 1
	v_cndmask_b32_e32 v247, v240, v241, vcc
	v_sqrt_f32_e32 v242, v247
	s_nop 1
	v_add_u32_e32 v243, -1, v242
	v_add_u32_e32 v244, 1, v242
	v_fma_f32 v245, -v243, v242, v247
	v_fma_f32 v246, -v244, v242, v247
	v_cmp_ge_f32_e64 s[52:53], 0, v245
	s_nop 1
	v_cndmask_b32_e64 v242, v242, v243, s[52:53]
	v_cmp_lt_f32_e64 s[52:53], 0, v246
	s_nop 1
	v_cndmask_b32_e64 v242, v242, v244, s[52:53]
	v_mul_f32_e32 v243, 0x37800000, v242
	v_cndmask_b32_e32 v242, v242, v243, vcc
	v_cmp_class_f32_e32 vcc, v247, v90
	s_nop 1
	v_cndmask_b32_e32 v247, v242, v247, vcc
	v_div_scale_f32 v248, s[52:53], v247, v247, 1.0
	v_rcp_f32_e32 v249, v248
	v_div_scale_f32 v228, vcc, 1.0, v247, 1.0
	s_nop 0
	v_fma_f32 v229, -v248, v249, 1.0
	v_fmac_f32_e32 v249, v229, v249
	v_mul_f32_e32 v230, v228, v249
	v_fma_f32 v229, -v248, v230, v228
	v_fmac_f32_e32 v230, v229, v249
	v_fma_f32 v248, -v248, v230, v228
	v_div_fmas_f32 v248, v248, v249, v230
	v_div_fixup_f32 v232, v248, v247, 1.0
	v_fmamk_f32 v240, v225, 0x3a800000, v89
	v_mul_f32_e32 v241, 0x4f800000, v240
	v_cmp_gt_f32_e32 vcc, s54, v240
	s_nop 1
	v_cndmask_b32_e32 v247, v240, v241, vcc
	v_sqrt_f32_e32 v242, v247
	s_nop 1
	v_add_u32_e32 v243, -1, v242
	v_add_u32_e32 v244, 1, v242
	v_fma_f32 v245, -v243, v242, v247
	v_fma_f32 v246, -v244, v242, v247
	v_cmp_ge_f32_e64 s[52:53], 0, v245
	s_nop 1
	v_cndmask_b32_e64 v242, v242, v243, s[52:53]
	v_cmp_lt_f32_e64 s[52:53], 0, v246
	s_nop 1
	v_cndmask_b32_e64 v242, v242, v244, s[52:53]
	v_mul_f32_e32 v243, 0x37800000, v242
	v_cndmask_b32_e32 v242, v242, v243, vcc
	v_cmp_class_f32_e32 vcc, v247, v90
	s_nop 1
	v_cndmask_b32_e32 v247, v242, v247, vcc
	v_div_scale_f32 v248, s[52:53], v247, v247, 1.0
	v_rcp_f32_e32 v249, v248
	v_div_scale_f32 v228, vcc, 1.0, v247, 1.0
	s_nop 0
	v_fma_f32 v229, -v248, v249, 1.0
	v_fmac_f32_e32 v249, v229, v249
	v_mul_f32_e32 v230, v228, v249
	v_fma_f32 v229, -v248, v230, v228
	v_fmac_f32_e32 v230, v229, v249
; __device__ __forceinline__ unsigned pk2(float lo, float hi) { return pg8::cvt_pk_bf16(lo, hi); }
; template <bool BF> __device__ __forceinline__ void prep_rows(const float* xp, const float* xs, const bf16* hb, const float* g, const float* MOD, int shoff, int scoff, bf16* U, int gw, int NGW, int lane) {
;     ...
;             const float rstd = 1.0f / sqrtf(s[r] * (1.0f / DM) + RMS_EPS);
;             const float* mr = MOD + (size_t)(m < MP ? (m >> 13) : 8 + ((m - MP) >> 12)) * 6144;
; #pragma unroll
;             for (int j = 0; j < 4; ++j) { const int c = 4 * lane + 256 * j;
;                 const f32x4 gg = *(const f32x4*)(g + c), sc = *(const f32x4*)(mr + scoff + c), sh = *(const f32x4*)(mr + shoff + c);
;                 const f32x4 o = v[r][j] * rstd * gg * (sc + 1.0f) + sh; v2u w; w.x = pk2(o.x, o.y); w.y = pk2(o.z, o.w); *(v2u*)(U + (size_t)m * DM + c) = w; } } }
	v_fma_f32 v248, -v248, v230, v228
	v_div_fmas_f32 v248, v248, v249, v230
	v_div_fixup_f32 v234, v248, v247, 1.0
	v_fmamk_f32 v240, v226, 0x3a800000, v89
	v_mul_f32_e32 v241, 0x4f800000, v240
	v_cmp_gt_f32_e32 vcc, s54, v240
	s_nop 1
	v_cndmask_b32_e32 v247, v240, v241, vcc
	v_sqrt_f32_e32 v242, v247
	s_nop 1
	v_add_u32_e32 v243, -1, v242
	v_add_u32_e32 v244, 1, v242
	v_fma_f32 v245, -v243, v242, v247
	v_fma_f32 v246, -v244, v242, v247
	v_cmp_ge_f32_e64 s[52:53], 0, v245
	s_nop 1
	v_cndmask_b32_e64 v242, v242, v243, s[52:53]
	v_cmp_lt_f32_e64 s[52:53], 0, v246
	s_nop 1
	v_cndmask_b32_e64 v242, v242, v244, s[52:53]
	v_mul_f32_e32 v243, 0x37800000, v242
	v_cndmask_b32_e32 v242, v242, v243, vcc
	v_cmp_class_f32_e32 vcc, v247, v90
	s_nop 1
	v_cndmask_b32_e32 v247, v242, v247, vcc
	v_div_scale_f32 v248, s[52:53], v247, v247, 1.0
	v_rcp_f32_e32 v249, v248
	v_div_scale_f32 v228, vcc, 1.0, v247, 1.0
	s_nop 0
	v_fma_f32 v229, -v248, v249, 1.0
	v_fmac_f32_e32 v249, v229, v249
	v_mul_f32_e32 v230, v228, v249
	v_fma_f32 v229, -v248, v230, v228
	v_fmac_f32_e32 v230, v229, v249
	v_fma_f32 v248, -v248, v230, v228
	v_div_fmas_f32 v248, v248, v249, v230
	v_div_fixup_f32 v236, v248, v247, 1.0
	v_fmamk_f32 v240, v227, 0x3a800000, v89
	v_mul_f32_e32 v241, 0x4f800000, v240
	v_cmp_gt_f32_e32 vcc, s54, v240
	s_nop 1
	v_cndmask_b32_e32 v247, v240, v241, vcc
	v_sqrt_f32_e32 v242, v247
	s_nop 1
	v_add_u32_e32 v243, -1, v242
	v_add_u32_e32 v244, 1, v242
	v_fma_f32 v245, -v243, v242, v247
	v_fma_f32 v246, -v244, v242, v247
	v_cmp_ge_f32_e64 s[52:53], 0, v245
	s_nop 1
	v_cndmask_b32_e64 v242, v242, v243, s[52:53]
	v_cmp_lt_f32_e64 s[52:53], 0, v246
	s_nop 1
	v_cndmask_b32_e64 v242, v242, v244, s[52:53]
	v_mul_f32_e32 v243, 0x37800000, v242
	v_cndmask_b32_e32 v242, v242, v243, vcc
	v_cmp_class_f32_e32 vcc, v247, v90
	s_nop 1
	v_cndmask_b32_e32 v247, v242, v247, vcc
	v_div_scale_f32 v248, s[52:53], v247, v247, 1.0
	v_rcp_f32_e32 v249, v248
	v_div_scale_f32 v228, vcc, 1.0, v247, 1.0
	s_nop 0
	v_fma_f32 v229, -v248, v249, 1.0
	v_fmac_f32_e32 v249, v229, v249
	v_mul_f32_e32 v230, v228, v249
	v_fma_f32 v229, -v248, v230, v228
	v_fmac_f32_e32 v230, v229, v249
	v_fma_f32 v248, -v248, v230, v228
	v_div_fmas_f32 v248, v248, v249, v230
	v_div_fixup_f32 v238, v248, v247, 1.0
	s_waitcnt vmcnt(16)
	v_pk_add_f32 v[160:161], v[160:161], 1.0 op_sel_hi:[1,0]
	v_pk_add_f32 v[162:163], v[162:163], 1.0 op_sel_hi:[1,0]
	v_pk_add_f32 v[164:165], v[164:165], 1.0 op_sel_hi:[1,0]
	v_pk_add_f32 v[166:167], v[166:167], 1.0 op_sel_hi:[1,0]
	v_pk_add_f32 v[168:169], v[168:169], 1.0 op_sel_hi:[1,0]
	v_pk_add_f32 v[170:171], v[170:171], 1.0 op_sel_hi:[1,0]
	v_pk_add_f32 v[172:173], v[172:173], 1.0 op_sel_hi:[1,0]
	v_pk_add_f32 v[174:175], v[174:175], 1.0 op_sel_hi:[1,0]
	v_pk_add_f32 v[192:193], v[192:193], 1.0 op_sel_hi:[1,0]
	v_pk_add_f32 v[194:195], v[194:195], 1.0 op_sel_hi:[1,0]
	v_pk_add_f32 v[196:197], v[196:197], 1.0 op_sel_hi:[1,0]
	v_pk_add_f32 v[198:199], v[198:199], 1.0 op_sel_hi:[1,0]
	v_pk_add_f32 v[200:201], v[200:201], 1.0 op_sel_hi:[1,0]
	v_pk_add_f32 v[202:203], v[202:203], 1.0 op_sel_hi:[1,0]
	v_pk_add_f32 v[204:205], v[204:205], 1.0 op_sel_hi:[1,0]
	v_pk_add_f32 v[206:207], v[206:207], 1.0 op_sel_hi:[1,0]
	s_add_u32 s38, s20, 0x4000000
	s_addc_u32 s39, s21, 0
	s_add_u32 s40, s20, 0x4400000
	s_addc_u32 s41, s21, 0
	s_add_u32 s46, s20, 0x4800000
	s_addc_u32 s47, s21, 0
	s_add_u32 s48, s20, 0x4c00000
	s_addc_u32 s49, s21, 0
	v_pk_mul_f32 v[0:1], v[0:1], v[232:233] op_sel_hi:[1,0]
	v_pk_mul_f32 v[2:3], v[2:3], v[232:233] op_sel_hi:[1,0]
	v_pk_mul_f32 v[0:1], v[64:65], v[0:1]
	v_pk_mul_f32 v[2:3], v[66:67], v[2:3]
	v_pk_fma_f32 v[0:1], v[160:161], v[0:1], v[176:177]
	v_pk_fma_f32 v[2:3], v[162:163], v[2:3], v[178:179]
	v_cvt_pk_bf16_f32 v244, v0, v1
	v_cvt_pk_bf16_f32 v245, v2, v3
	v_pk_mul_f32 v[4:5], v[4:5], v[232:233] op_sel_hi:[1,0]
	v_pk_mul_f32 v[6:7], v[6:7], v[232:233] op_sel_hi:[1,0]
	v_pk_mul_f32 v[4:5], v[68:69], v[4:5]
	v_pk_mul_f32 v[6:7], v[70:71], v[6:7]
	v_pk_fma_f32 v[4:5], v[164:165], v[4:5], v[180:181]
	v_pk_fma_f32 v[6:7], v[166:167], v[6:7], v[182:183]
	v_cvt_pk_bf16_f32 v246, v4, v5
	v_cvt_pk_bf16_f32 v247, v6, v7
	global_store_dwordx4 v82, v[244:247], s[38:39] offset:0
	v_pk_mul_f32 v[8:9], v[8:9], v[232:233] op_sel_hi:[1,0]
	v_pk_mul_f32 v[10:11], v[10:11], v[232:233] op_sel_hi:[1,0]
	v_pk_mul_f32 v[8:9], v[72:73], v[8:9]
	v_pk_mul_f32 v[10:11], v[74:75], v[10:11]
	v_pk_fma_f32 v[8:9], v[168:169], v[8:9], v[184:185]
	v_pk_fma_f32 v[10:11], v[170:171], v[10:11], v[186:187]
	v_cvt_pk_bf16_f32 v240, v8, v9
	v_cvt_pk_bf16_f32 v241, v10, v11
	v_pk_mul_f32 v[12:13], v[12:13], v[232:233] op_sel_hi:[1,0]
	v_pk_mul_f32 v[14:15], v[14:15], v[232:233] op_sel_hi:[1,0]
	v_pk_mul_f32 v[12:13], v[76:77], v[12:13]
	v_pk_mul_f32 v[14:15], v[78:79], v[14:15]
	v_pk_fma_f32 v[12:13], v[172:173], v[12:13], v[188:189]
	v_pk_fma_f32 v[14:15], v[174:175], v[14:15], v[190:191]
	v_cvt_pk_bf16_f32 v242, v12, v13
	v_cvt_pk_bf16_f32 v243, v14, v15
	global_store_dwordx4 v82, v[240:243], s[38:39] offset:1024
	v_pk_mul_f32 v[16:17], v[16:17], v[234:235] op_sel_hi:[1,0]
	v_pk_mul_f32 v[18:19], v[18:19], v[234:235] op_sel_hi:[1,0]
	v_pk_mul_f32 v[16:17], v[64:65], v[16:17]
	v_pk_mul_f32 v[18:19], v[66:67], v[18:19]
	v_pk_fma_f32 v[16:17], v[160:161], v[16:17], v[176:177]
	v_pk_fma_f32 v[18:19], v[162:163], v[18:19], v[178:179]
	v_cvt_pk_bf16_f32 v244, v16, v17
	v_cvt_pk_bf16_f32 v245, v18, v19
	v_pk_mul_f32 v[20:21], v[20:21], v[234:235] op_sel_hi:[1,0]
	v_pk_mul_f32 v[22:23], v[22:23], v[234:235] op_sel_hi:[1,0]
	v_pk_mul_f32 v[20:21], v[68:69], v[20:21]
	v_pk_mul_f32 v[22:23], v[70:71], v[22:23]
; __device__ __forceinline__ float bf_lo(unsigned w) { return __uint_as_float(w << 16); }
; __device__ __forceinline__ float bf_hi(unsigned w) { return __uint_as_float(w & 0xffff0000u); }
; __device__ __forceinline__ unsigned pk2(float lo, float hi) { return pg8::cvt_pk_bf16(lo, hi); }
; template <bool BF> __device__ __forceinline__ void prep_rows(const float* xp, const float* xs, const bf16* hb, const float* g, const float* MOD, int shoff, int scoff, bf16* U, int gw, int NGW, int lane) {
;     ...
;         for (int r = 0; r < R; ++r) { const int m = mb + r * NGW; const int mc = m < MT ? m : mb;
; #pragma unroll
;             for (int j = 0; j < 4; ++j) {
;                 if (BF) { const v2u a0 = *(const v2u*)(hb + (size_t)mc * DM + 4 * lane + 256 * j);
;                     v[r][j].x = pg8::bf_lo(a0.x); v[r][j].y = pg8::bf_hi(a0.x); v[r][j].z = pg8::bf_lo(a0.y); v[r][j].w = pg8::bf_hi(a0.y); }
;                 else { const float* xr = mc < MP ? xp + (size_t)mc * DM : xs + (size_t)(mc - MP) * DM; v[r][j] = *(const f32x4*)(xr + 4 * lane + 256 * j); } } }
;     ...
;                 const f32x4 o = v[r][j] * rstd * gg * (sc + 1.0f) + sh; v2u w; w.x = pk2(o.x, o.y); w.y = pk2(o.z, o.w); *(v2u*)(U + (size_t)m * DM + c) = w; } } }
	v_pk_fma_f32 v[20:21], v[164:165], v[20:21], v[180:181]
	v_pk_fma_f32 v[22:23], v[166:167], v[22:23], v[182:183]
	v_cvt_pk_bf16_f32 v246, v20, v21
	v_cvt_pk_bf16_f32 v247, v22, v23
	global_store_dwordx4 v82, v[244:247], s[40:41] offset:0
	v_pk_mul_f32 v[24:25], v[24:25], v[234:235] op_sel_hi:[1,0]
	v_pk_mul_f32 v[26:27], v[26:27], v[234:235] op_sel_hi:[1,0]
	v_pk_mul_f32 v[24:25], v[72:73], v[24:25]
	v_pk_mul_f32 v[26:27], v[74:75], v[26:27]
	v_pk_fma_f32 v[24:25], v[168:169], v[24:25], v[184:185]
	v_pk_fma_f32 v[26:27], v[170:171], v[26:27], v[186:187]
	v_cvt_pk_bf16_f32 v240, v24, v25
	v_cvt_pk_bf16_f32 v241, v26, v27
	v_pk_mul_f32 v[28:29], v[28:29], v[234:235] op_sel_hi:[1,0]
	v_pk_mul_f32 v[30:31], v[30:31], v[234:235] op_sel_hi:[1,0]
	v_pk_mul_f32 v[28:29], v[76:77], v[28:29]
	v_pk_mul_f32 v[30:31], v[78:79], v[30:31]
	v_pk_fma_f32 v[28:29], v[172:173], v[28:29], v[188:189]
	v_pk_fma_f32 v[30:31], v[174:175], v[30:31], v[190:191]
	v_cvt_pk_bf16_f32 v242, v28, v29
	v_cvt_pk_bf16_f32 v243, v30, v31
	global_store_dwordx4 v82, v[240:243], s[40:41] offset:1024
	v_pk_mul_f32 v[32:33], v[32:33], v[236:237] op_sel_hi:[1,0]
	v_pk_mul_f32 v[34:35], v[34:35], v[236:237] op_sel_hi:[1,0]
	v_pk_mul_f32 v[32:33], v[64:65], v[32:33]
	v_pk_mul_f32 v[34:35], v[66:67], v[34:35]
	v_pk_fma_f32 v[32:33], v[192:193], v[32:33], v[208:209]
	v_pk_fma_f32 v[34:35], v[194:195], v[34:35], v[210:211]
	v_cvt_pk_bf16_f32 v244, v32, v33
	v_cvt_pk_bf16_f32 v245, v34, v35
	v_pk_mul_f32 v[36:37], v[36:37], v[236:237] op_sel_hi:[1,0]
	v_pk_mul_f32 v[38:39], v[38:39], v[236:237] op_sel_hi:[1,0]
	v_pk_mul_f32 v[36:37], v[68:69], v[36:37]
	v_pk_mul_f32 v[38:39], v[70:71], v[38:39]
	v_pk_fma_f32 v[36:37], v[196:197], v[36:37], v[212:213]
	v_pk_fma_f32 v[38:39], v[198:199], v[38:39], v[214:215]
	v_cvt_pk_bf16_f32 v246, v36, v37
	v_cvt_pk_bf16_f32 v247, v38, v39
	global_store_dwordx4 v82, v[244:247], s[46:47] offset:0
	v_pk_mul_f32 v[40:41], v[40:41], v[236:237] op_sel_hi:[1,0]
	v_pk_mul_f32 v[42:43], v[42:43], v[236:237] op_sel_hi:[1,0]
	v_pk_mul_f32 v[40:41], v[72:73], v[40:41]
	v_pk_mul_f32 v[42:43], v[74:75], v[42:43]
	v_pk_fma_f32 v[40:41], v[200:201], v[40:41], v[216:217]
	v_pk_fma_f32 v[42:43], v[202:203], v[42:43], v[218:219]
	v_cvt_pk_bf16_f32 v240, v40, v41
	v_cvt_pk_bf16_f32 v241, v42, v43
	v_pk_mul_f32 v[44:45], v[44:45], v[236:237] op_sel_hi:[1,0]
	v_pk_mul_f32 v[46:47], v[46:47], v[236:237] op_sel_hi:[1,0]
	v_pk_mul_f32 v[44:45], v[76:77], v[44:45]
	v_pk_mul_f32 v[46:47], v[78:79], v[46:47]
	v_pk_fma_f32 v[44:45], v[204:205], v[44:45], v[220:221]
	v_pk_fma_f32 v[46:47], v[206:207], v[46:47], v[222:223]
	v_cvt_pk_bf16_f32 v242, v44, v45
	v_cvt_pk_bf16_f32 v243, v46, v47
	global_store_dwordx4 v82, v[240:243], s[46:47] offset:1024
	v_pk_mul_f32 v[48:49], v[48:49], v[238:239] op_sel_hi:[1,0]
	v_pk_mul_f32 v[50:51], v[50:51], v[238:239] op_sel_hi:[1,0]
	v_pk_mul_f32 v[48:49], v[64:65], v[48:49]
	v_pk_mul_f32 v[50:51], v[66:67], v[50:51]
	v_pk_fma_f32 v[48:49], v[192:193], v[48:49], v[208:209]
	v_pk_fma_f32 v[50:51], v[194:195], v[50:51], v[210:211]
	v_cvt_pk_bf16_f32 v244, v48, v49
	v_cvt_pk_bf16_f32 v245, v50, v51
	v_pk_mul_f32 v[52:53], v[52:53], v[238:239] op_sel_hi:[1,0]
	v_pk_mul_f32 v[54:55], v[54:55], v[238:239] op_sel_hi:[1,0]
	v_pk_mul_f32 v[52:53], v[68:69], v[52:53]
	v_pk_mul_f32 v[54:55], v[70:71], v[54:55]
	v_pk_fma_f32 v[52:53], v[196:197], v[52:53], v[212:213]
	v_pk_fma_f32 v[54:55], v[198:199], v[54:55], v[214:215]
	v_cvt_pk_bf16_f32 v246, v52, v53
	v_cvt_pk_bf16_f32 v247, v54, v55
	global_store_dwordx4 v82, v[244:247], s[48:49] offset:0
	v_pk_mul_f32 v[56:57], v[56:57], v[238:239] op_sel_hi:[1,0]
	v_pk_mul_f32 v[58:59], v[58:59], v[238:239] op_sel_hi:[1,0]
	v_pk_mul_f32 v[56:57], v[72:73], v[56:57]
	v_pk_mul_f32 v[58:59], v[74:75], v[58:59]
	v_pk_fma_f32 v[56:57], v[200:201], v[56:57], v[216:217]
	v_pk_fma_f32 v[58:59], v[202:203], v[58:59], v[218:219]
	v_cvt_pk_bf16_f32 v240, v56, v57
	v_cvt_pk_bf16_f32 v241, v58, v59
	v_pk_mul_f32 v[60:61], v[60:61], v[238:239] op_sel_hi:[1,0]
	v_pk_mul_f32 v[62:63], v[62:63], v[238:239] op_sel_hi:[1,0]
	v_pk_mul_f32 v[60:61], v[76:77], v[60:61]
	v_pk_mul_f32 v[62:63], v[78:79], v[62:63]
	v_pk_fma_f32 v[60:61], v[204:205], v[60:61], v[220:221]
	v_pk_fma_f32 v[62:63], v[206:207], v[62:63], v[222:223]
	v_cvt_pk_bf16_f32 v242, v60, v61
	v_cvt_pk_bf16_f32 v243, v62, v63
	global_store_dwordx4 v82, v[240:243], s[48:49] offset:1024
	s_add_u32 s34, s8, 0x1e000
	s_addc_u32 s35, s9, 0
	s_add_u32 s36, s8, 0x1e000
	s_addc_u32 s37, s9, 0
	global_load_dwordx4 v[176:179], v80, s[34:35] offset:0
	global_load_dwordx4 v[180:183], v80, s[34:35] offset:16
	global_load_dwordx4 v[184:187], v80, s[34:35] offset:2048
	global_load_dwordx4 v[188:191], v80, s[34:35] offset:2064
	global_load_dwordx4 v[160:163], v81, s[34:35] offset:0
	global_load_dwordx4 v[164:167], v81, s[34:35] offset:16
	global_load_dwordx4 v[168:171], v81, s[34:35] offset:2048
	global_load_dwordx4 v[172:175], v81, s[34:35] offset:2064
	global_load_dwordx4 v[208:211], v80, s[36:37] offset:0
	global_load_dwordx4 v[212:215], v80, s[36:37] offset:16
	global_load_dwordx4 v[216:219], v80, s[36:37] offset:2048
	global_load_dwordx4 v[220:223], v80, s[36:37] offset:2064
	global_load_dwordx4 v[192:195], v81, s[36:37] offset:0
	global_load_dwordx4 v[196:199], v81, s[36:37] offset:16
	global_load_dwordx4 v[200:203], v81, s[36:37] offset:2048
	global_load_dwordx4 v[204:207], v81, s[36:37] offset:2064
	s_add_u32 s24, s16, 0xc000000
	s_addc_u32 s25, s17, 0
	s_add_u32 s26, s16, 0xc800000
	s_addc_u32 s27, s17, 0
	s_add_u32 s28, s16, 0xd000000
	s_addc_u32 s29, s17, 0
	s_add_u32 s30, s16, 0xd800000
	s_addc_u32 s31, s17, 0
	global_load_dwordx4 v[0:3], v80, s[24:25] offset:0
	global_load_dwordx4 v[4:7], v80, s[24:25] offset:16
	global_load_dwordx4 v[8:11], v80, s[24:25] offset:2048
	global_load_dwordx4 v[12:15], v80, s[24:25] offset:2064
	global_load_dwordx4 v[16:19], v80, s[26:27] offset:0
	global_load_dwordx4 v[20:23], v80, s[26:27] offset:16
	global_load_dwordx4 v[24:27], v80, s[26:27] offset:2048
	global_load_dwordx4 v[28:31], v80, s[26:27] offset:2064
	global_load_dwordx4 v[32:35], v80, s[28:29] offset:0
	global_load_dwordx4 v[36:39], v80, s[28:29] offset:16
	global_load_dwordx4 v[40:43], v80, s[28:29] offset:2048
	global_load_dwordx4 v[44:47], v80, s[28:29] offset:2064
	global_load_dwordx4 v[48:51], v80, s[30:31] offset:0
	global_load_dwordx4 v[52:55], v80, s[30:31] offset:16
	global_load_dwordx4 v[56:59], v80, s[30:31] offset:2048
	global_load_dwordx4 v[60:63], v80, s[30:31] offset:2064
	s_waitcnt vmcnt(40)
; template <bool BF> __device__ __forceinline__ void prep_rows(const float* xp, const float* xs, const bf16* hb, const float* g, const float* MOD, int shoff, int scoff, bf16* U, int gw, int NGW, int lane) {
;     ...
;         for (int r = 0; r < R; ++r) { float t = 0.f;
; #pragma unroll
;             for (int j = 0; j < 4; ++j) t += (v[r][j].x * v[r][j].x + v[r][j].y * v[r][j].y) + (v[r][j].z * v[r][j].z + v[r][j].w * v[r][j].w);
;             s[r] = t; }
; #pragma unroll
;         for (int o = 1; o < 64; o <<= 1) {
; #pragma unroll
;             for (int r = 0; r < R; ++r) s[r] += __shfl_xor(s[r], o); }
; #pragma unroll
;         for (int r = 0; r < R; ++r) { const int m = mb + r * NGW; if (m < MT) {
;             const float rstd = 1.0f / sqrtf(s[r] * (1.0f / DM) + RMS_EPS);
	v_pk_mul_f32 v[240:241], v[96:97], v[96:97]
	v_pk_mul_f32 v[242:243], v[112:113], v[112:113]
	v_pk_mul_f32 v[244:245], v[128:129], v[128:129]
	v_pk_mul_f32 v[246:247], v[144:145], v[144:145]
	v_pk_fma_f32 v[240:241], v[98:99], v[98:99], v[240:241]
	v_pk_fma_f32 v[242:243], v[114:115], v[114:115], v[242:243]
	v_pk_fma_f32 v[244:245], v[130:131], v[130:131], v[244:245]
	v_pk_fma_f32 v[246:247], v[146:147], v[146:147], v[246:247]
	v_pk_fma_f32 v[240:241], v[100:101], v[100:101], v[240:241]
	v_pk_fma_f32 v[242:243], v[116:117], v[116:117], v[242:243]
	v_pk_fma_f32 v[244:245], v[132:133], v[132:133], v[244:245]
	v_pk_fma_f32 v[246:247], v[148:149], v[148:149], v[246:247]
	v_pk_fma_f32 v[240:241], v[102:103], v[102:103], v[240:241]
	v_pk_fma_f32 v[242:243], v[118:119], v[118:119], v[242:243]
	v_pk_fma_f32 v[244:245], v[134:135], v[134:135], v[244:245]
	v_pk_fma_f32 v[246:247], v[150:151], v[150:151], v[246:247]
	v_pk_fma_f32 v[240:241], v[104:105], v[104:105], v[240:241]
	v_pk_fma_f32 v[242:243], v[120:121], v[120:121], v[242:243]
	v_pk_fma_f32 v[244:245], v[136:137], v[136:137], v[244:245]
	v_pk_fma_f32 v[246:247], v[152:153], v[152:153], v[246:247]
	v_pk_fma_f32 v[240:241], v[106:107], v[106:107], v[240:241]
	v_pk_fma_f32 v[242:243], v[122:123], v[122:123], v[242:243]
	v_pk_fma_f32 v[244:245], v[138:139], v[138:139], v[244:245]
	v_pk_fma_f32 v[246:247], v[154:155], v[154:155], v[246:247]
	v_pk_fma_f32 v[240:241], v[108:109], v[108:109], v[240:241]
	v_pk_fma_f32 v[242:243], v[124:125], v[124:125], v[242:243]
	v_pk_fma_f32 v[244:245], v[140:141], v[140:141], v[244:245]
	v_pk_fma_f32 v[246:247], v[156:157], v[156:157], v[246:247]
	v_pk_fma_f32 v[240:241], v[110:111], v[110:111], v[240:241]
	v_pk_fma_f32 v[242:243], v[126:127], v[126:127], v[242:243]
	v_pk_fma_f32 v[244:245], v[142:143], v[142:143], v[244:245]
	v_pk_fma_f32 v[246:247], v[158:159], v[158:159], v[246:247]
	v_add_f32_e32 v224, v240, v241
	v_add_f32_e32 v225, v242, v243
	v_add_f32_e32 v226, v244, v245
	v_add_f32_e32 v227, v246, v247
	ds_bpermute_b32 v228, v83, v224
	ds_bpermute_b32 v229, v83, v225
	ds_bpermute_b32 v230, v83, v226
	ds_bpermute_b32 v231, v83, v227
	s_waitcnt lgkmcnt(0)
	v_add_f32_e32 v224, v224, v228
	v_add_f32_e32 v225, v225, v229
	v_add_f32_e32 v226, v226, v230
	v_add_f32_e32 v227, v227, v231
	ds_bpermute_b32 v228, v84, v224
	ds_bpermute_b32 v229, v84, v225
	ds_bpermute_b32 v230, v84, v226
	ds_bpermute_b32 v231, v84, v227
	s_waitcnt lgkmcnt(0)
	v_add_f32_e32 v224, v224, v228
	v_add_f32_e32 v225, v225, v229
	v_add_f32_e32 v226, v226, v230
	v_add_f32_e32 v227, v227, v231
	ds_bpermute_b32 v228, v85, v224
	ds_bpermute_b32 v229, v85, v225
	ds_bpermute_b32 v230, v85, v226
	ds_bpermute_b32 v231, v85, v227
	s_waitcnt lgkmcnt(0)
	v_add_f32_e32 v224, v224, v228
	v_add_f32_e32 v225, v225, v229
	v_add_f32_e32 v226, v226, v230
	v_add_f32_e32 v227, v227, v231
	ds_bpermute_b32 v228, v86, v224
	ds_bpermute_b32 v229, v86, v225
	ds_bpermute_b32 v230, v86, v226
	ds_bpermute_b32 v231, v86, v227
	s_waitcnt lgkmcnt(0)
	v_add_f32_e32 v224, v224, v228
	v_add_f32_e32 v225, v225, v229
	v_add_f32_e32 v226, v226, v230
	v_add_f32_e32 v227, v227, v231
	ds_bpermute_b32 v228, v87, v224
	ds_bpermute_b32 v229, v87, v225
	ds_bpermute_b32 v230, v87, v226
	ds_bpermute_b32 v231, v87, v227
	s_waitcnt lgkmcnt(0)
	v_add_f32_e32 v224, v224, v228
	v_add_f32_e32 v225, v225, v229
	v_add_f32_e32 v226, v226, v230
	v_add_f32_e32 v227, v227, v231
	ds_bpermute_b32 v228, v88, v224
	ds_bpermute_b32 v229, v88, v225
	ds_bpermute_b32 v230, v88, v226
	ds_bpermute_b32 v231, v88, v227
	s_waitcnt lgkmcnt(0)
	v_add_f32_e32 v224, v224, v228
	v_add_f32_e32 v225, v225, v229
	v_add_f32_e32 v226, v226, v230
	v_add_f32_e32 v227, v227, v231
	v_fmamk_f32 v240, v224, 0x3a800000, v89
	v_mul_f32_e32 v241, 0x4f800000, v240
	v_cmp_gt_f32_e32 vcc, s54, v240
	s_nop 1
	v_cndmask_b32_e32 v247, v240, v241, vcc
	v_sqrt_f32_e32 v242, v247
	s_nop 1
	v_add_u32_e32 v243, -1, v242
	v_add_u32_e32 v244, 1, v242
	v_fma_f32 v245, -v243, v242, v247
	v_fma_f32 v246, -v244, v242, v247
	v_cmp_ge_f32_e64 s[52:53], 0, v245
	s_nop 1
	v_cndmask_b32_e64 v242, v242, v243, s[52:53]
	v_cmp_lt_f32_e64 s[52:53], 0, v246
	s_nop 1
	v_cndmask_b32_e64 v242, v242, v244, s[52:53]
	v_mul_f32_e32 v243, 0x37800000, v242
	v_cndmask_b32_e32 v242, v242, v243, vcc
	v_cmp_class_f32_e32 vcc, v247, v90
	s_nop 1
	v_cndmask_b32_e32 v247, v242, v247, vcc
	v_div_scale_f32 v248, s[52:53], v247, v247, 1.0
	v_rcp_f32_e32 v249, v248
	v_div_scale_f32 v228, vcc, 1.0, v247, 1.0
	s_nop 0
	v_fma_f32 v229, -v248, v249, 1.0
	v_fmac_f32_e32 v249, v229, v249
	v_mul_f32_e32 v230, v228, v249
	v_fma_f32 v229, -v248, v230, v228
	v_fmac_f32_e32 v230, v229, v249
	v_fma_f32 v248, -v248, v230, v228
	v_div_fmas_f32 v248, v248, v249, v230
	v_div_fixup_f32 v232, v248, v247, 1.0
	v_fmamk_f32 v240, v225, 0x3a800000, v89
	v_mul_f32_e32 v241, 0x4f800000, v240
	v_cmp_gt_f32_e32 vcc, s54, v240
	s_nop 1
	v_cndmask_b32_e32 v247, v240, v241, vcc
	v_sqrt_f32_e32 v242, v247
	s_nop 1
	v_add_u32_e32 v243, -1, v242
	v_add_u32_e32 v244, 1, v242
	v_fma_f32 v245, -v243, v242, v247
	v_fma_f32 v246, -v244, v242, v247
	v_cmp_ge_f32_e64 s[52:53], 0, v245
	s_nop 1
	v_cndmask_b32_e64 v242, v242, v243, s[52:53]
	v_cmp_lt_f32_e64 s[52:53], 0, v246
	s_nop 1
	v_cndmask_b32_e64 v242, v242, v244, s[52:53]
	v_mul_f32_e32 v243, 0x37800000, v242
	v_cndmask_b32_e32 v242, v242, v243, vcc
	v_cmp_class_f32_e32 vcc, v247, v90
	s_nop 1
	v_cndmask_b32_e32 v247, v242, v247, vcc
	v_div_scale_f32 v248, s[52:53], v247, v247, 1.0
	v_rcp_f32_e32 v249, v248
	v_div_scale_f32 v228, vcc, 1.0, v247, 1.0
	s_nop 0
	v_fma_f32 v229, -v248, v249, 1.0
; __device__ __forceinline__ unsigned pk2(float lo, float hi) { return pg8::cvt_pk_bf16(lo, hi); }
; template <bool BF> __device__ __forceinline__ void prep_rows(const float* xp, const float* xs, const bf16* hb, const float* g, const float* MOD, int shoff, int scoff, bf16* U, int gw, int NGW, int lane) {
;     ...
;             const float rstd = 1.0f / sqrtf(s[r] * (1.0f / DM) + RMS_EPS);
;             const float* mr = MOD + (size_t)(m < MP ? (m >> 13) : 8 + ((m - MP) >> 12)) * 6144;
; #pragma unroll
;             for (int j = 0; j < 4; ++j) { const int c = 4 * lane + 256 * j;
;                 const f32x4 gg = *(const f32x4*)(g + c), sc = *(const f32x4*)(mr + scoff + c), sh = *(const f32x4*)(mr + shoff + c);
;                 const f32x4 o = v[r][j] * rstd * gg * (sc + 1.0f) + sh; v2u w; w.x = pk2(o.x, o.y); w.y = pk2(o.z, o.w); *(v2u*)(U + (size_t)m * DM + c) = w; } } }
	v_fmac_f32_e32 v249, v229, v249
	v_mul_f32_e32 v230, v228, v249
	v_fma_f32 v229, -v248, v230, v228
	v_fmac_f32_e32 v230, v229, v249
	v_fma_f32 v248, -v248, v230, v228
	v_div_fmas_f32 v248, v248, v249, v230
	v_div_fixup_f32 v234, v248, v247, 1.0
	v_fmamk_f32 v240, v226, 0x3a800000, v89
	v_mul_f32_e32 v241, 0x4f800000, v240
	v_cmp_gt_f32_e32 vcc, s54, v240
	s_nop 1
	v_cndmask_b32_e32 v247, v240, v241, vcc
	v_sqrt_f32_e32 v242, v247
	s_nop 1
	v_add_u32_e32 v243, -1, v242
	v_add_u32_e32 v244, 1, v242
	v_fma_f32 v245, -v243, v242, v247
	v_fma_f32 v246, -v244, v242, v247
	v_cmp_ge_f32_e64 s[52:53], 0, v245
	s_nop 1
	v_cndmask_b32_e64 v242, v242, v243, s[52:53]
	v_cmp_lt_f32_e64 s[52:53], 0, v246
	s_nop 1
	v_cndmask_b32_e64 v242, v242, v244, s[52:53]
	v_mul_f32_e32 v243, 0x37800000, v242
	v_cndmask_b32_e32 v242, v242, v243, vcc
	v_cmp_class_f32_e32 vcc, v247, v90
	s_nop 1
	v_cndmask_b32_e32 v247, v242, v247, vcc
	v_div_scale_f32 v248, s[52:53], v247, v247, 1.0
	v_rcp_f32_e32 v249, v248
	v_div_scale_f32 v228, vcc, 1.0, v247, 1.0
	s_nop 0
	v_fma_f32 v229, -v248, v249, 1.0
	v_fmac_f32_e32 v249, v229, v249
	v_mul_f32_e32 v230, v228, v249
	v_fma_f32 v229, -v248, v230, v228
	v_fmac_f32_e32 v230, v229, v249
	v_fma_f32 v248, -v248, v230, v228
	v_div_fmas_f32 v248, v248, v249, v230
	v_div_fixup_f32 v236, v248, v247, 1.0
	v_fmamk_f32 v240, v227, 0x3a800000, v89
	v_mul_f32_e32 v241, 0x4f800000, v240
	v_cmp_gt_f32_e32 vcc, s54, v240
	s_nop 1
	v_cndmask_b32_e32 v247, v240, v241, vcc
	v_sqrt_f32_e32 v242, v247
	s_nop 1
	v_add_u32_e32 v243, -1, v242
	v_add_u32_e32 v244, 1, v242
	v_fma_f32 v245, -v243, v242, v247
	v_fma_f32 v246, -v244, v242, v247
	v_cmp_ge_f32_e64 s[52:53], 0, v245
	s_nop 1
	v_cndmask_b32_e64 v242, v242, v243, s[52:53]
	v_cmp_lt_f32_e64 s[52:53], 0, v246
	s_nop 1
	v_cndmask_b32_e64 v242, v242, v244, s[52:53]
	v_mul_f32_e32 v243, 0x37800000, v242
	v_cndmask_b32_e32 v242, v242, v243, vcc
	v_cmp_class_f32_e32 vcc, v247, v90
	s_nop 1
	v_cndmask_b32_e32 v247, v242, v247, vcc
	v_div_scale_f32 v248, s[52:53], v247, v247, 1.0
	v_rcp_f32_e32 v249, v248
	v_div_scale_f32 v228, vcc, 1.0, v247, 1.0
	s_nop 0
	v_fma_f32 v229, -v248, v249, 1.0
	v_fmac_f32_e32 v249, v229, v249
	v_mul_f32_e32 v230, v228, v249
	v_fma_f32 v229, -v248, v230, v228
	v_fmac_f32_e32 v230, v229, v249
	v_fma_f32 v248, -v248, v230, v228
	v_div_fmas_f32 v248, v248, v249, v230
	v_div_fixup_f32 v238, v248, v247, 1.0
	s_waitcnt vmcnt(16)
	v_pk_add_f32 v[160:161], v[160:161], 1.0 op_sel_hi:[1,0]
	v_pk_add_f32 v[162:163], v[162:163], 1.0 op_sel_hi:[1,0]
	v_pk_add_f32 v[164:165], v[164:165], 1.0 op_sel_hi:[1,0]
	v_pk_add_f32 v[166:167], v[166:167], 1.0 op_sel_hi:[1,0]
	v_pk_add_f32 v[168:169], v[168:169], 1.0 op_sel_hi:[1,0]
	v_pk_add_f32 v[170:171], v[170:171], 1.0 op_sel_hi:[1,0]
	v_pk_add_f32 v[172:173], v[172:173], 1.0 op_sel_hi:[1,0]
	v_pk_add_f32 v[174:175], v[174:175], 1.0 op_sel_hi:[1,0]
	v_pk_add_f32 v[192:193], v[192:193], 1.0 op_sel_hi:[1,0]
	v_pk_add_f32 v[194:195], v[194:195], 1.0 op_sel_hi:[1,0]
	v_pk_add_f32 v[196:197], v[196:197], 1.0 op_sel_hi:[1,0]
	v_pk_add_f32 v[198:199], v[198:199], 1.0 op_sel_hi:[1,0]
	v_pk_add_f32 v[200:201], v[200:201], 1.0 op_sel_hi:[1,0]
	v_pk_add_f32 v[202:203], v[202:203], 1.0 op_sel_hi:[1,0]
	v_pk_add_f32 v[204:205], v[204:205], 1.0 op_sel_hi:[1,0]
	v_pk_add_f32 v[206:207], v[206:207], 1.0 op_sel_hi:[1,0]
	s_add_u32 s38, s20, 0x5000000
	s_addc_u32 s39, s21, 0
	s_add_u32 s40, s20, 0x5400000
	s_addc_u32 s41, s21, 0
	s_add_u32 s46, s20, 0x5800000
	s_addc_u32 s47, s21, 0
	s_add_u32 s48, s20, 0x5c00000
	s_addc_u32 s49, s21, 0
	v_pk_mul_f32 v[96:97], v[96:97], v[232:233] op_sel_hi:[1,0]
	v_pk_mul_f32 v[98:99], v[98:99], v[232:233] op_sel_hi:[1,0]
	v_pk_mul_f32 v[96:97], v[64:65], v[96:97]
	v_pk_mul_f32 v[98:99], v[66:67], v[98:99]
	v_pk_fma_f32 v[96:97], v[160:161], v[96:97], v[176:177]
	v_pk_fma_f32 v[98:99], v[162:163], v[98:99], v[178:179]
	v_cvt_pk_bf16_f32 v244, v96, v97
	v_cvt_pk_bf16_f32 v245, v98, v99
	v_pk_mul_f32 v[100:101], v[100:101], v[232:233] op_sel_hi:[1,0]
	v_pk_mul_f32 v[102:103], v[102:103], v[232:233] op_sel_hi:[1,0]
	v_pk_mul_f32 v[100:101], v[68:69], v[100:101]
	v_pk_mul_f32 v[102:103], v[70:71], v[102:103]
	v_pk_fma_f32 v[100:101], v[164:165], v[100:101], v[180:181]
	v_pk_fma_f32 v[102:103], v[166:167], v[102:103], v[182:183]
	v_cvt_pk_bf16_f32 v246, v100, v101
	v_cvt_pk_bf16_f32 v247, v102, v103
	global_store_dwordx4 v82, v[244:247], s[38:39] offset:0
	v_pk_mul_f32 v[104:105], v[104:105], v[232:233] op_sel_hi:[1,0]
	v_pk_mul_f32 v[106:107], v[106:107], v[232:233] op_sel_hi:[1,0]
	v_pk_mul_f32 v[104:105], v[72:73], v[104:105]
	v_pk_mul_f32 v[106:107], v[74:75], v[106:107]
	v_pk_fma_f32 v[104:105], v[168:169], v[104:105], v[184:185]
	v_pk_fma_f32 v[106:107], v[170:171], v[106:107], v[186:187]
	v_cvt_pk_bf16_f32 v240, v104, v105
	v_cvt_pk_bf16_f32 v241, v106, v107
	v_pk_mul_f32 v[108:109], v[108:109], v[232:233] op_sel_hi:[1,0]
	v_pk_mul_f32 v[110:111], v[110:111], v[232:233] op_sel_hi:[1,0]
	v_pk_mul_f32 v[108:109], v[76:77], v[108:109]
	v_pk_mul_f32 v[110:111], v[78:79], v[110:111]
	v_pk_fma_f32 v[108:109], v[172:173], v[108:109], v[188:189]
	v_pk_fma_f32 v[110:111], v[174:175], v[110:111], v[190:191]
	v_cvt_pk_bf16_f32 v242, v108, v109
	v_cvt_pk_bf16_f32 v243, v110, v111
	global_store_dwordx4 v82, v[240:243], s[38:39] offset:1024
	v_pk_mul_f32 v[112:113], v[112:113], v[234:235] op_sel_hi:[1,0]
	v_pk_mul_f32 v[114:115], v[114:115], v[234:235] op_sel_hi:[1,0]
	v_pk_mul_f32 v[112:113], v[64:65], v[112:113]
	v_pk_mul_f32 v[114:115], v[66:67], v[114:115]
	v_pk_fma_f32 v[112:113], v[160:161], v[112:113], v[176:177]
; __device__ __forceinline__ float bf_lo(unsigned w) { return __uint_as_float(w << 16); }
; __device__ __forceinline__ float bf_hi(unsigned w) { return __uint_as_float(w & 0xffff0000u); }
; __device__ __forceinline__ unsigned pk2(float lo, float hi) { return pg8::cvt_pk_bf16(lo, hi); }
; template <bool BF> __device__ __forceinline__ void prep_rows(const float* xp, const float* xs, const bf16* hb, const float* g, const float* MOD, int shoff, int scoff, bf16* U, int gw, int NGW, int lane) {
;     ...
;         for (int r = 0; r < R; ++r) { const int m = mb + r * NGW; const int mc = m < MT ? m : mb;
; #pragma unroll
;             for (int j = 0; j < 4; ++j) {
;                 if (BF) { const v2u a0 = *(const v2u*)(hb + (size_t)mc * DM + 4 * lane + 256 * j);
;                     v[r][j].x = pg8::bf_lo(a0.x); v[r][j].y = pg8::bf_hi(a0.x); v[r][j].z = pg8::bf_lo(a0.y); v[r][j].w = pg8::bf_hi(a0.y); }
;                 else { const float* xr = mc < MP ? xp + (size_t)mc * DM : xs + (size_t)(mc - MP) * DM; v[r][j] = *(const f32x4*)(xr + 4 * lane + 256 * j); } } }
;     ...
;                 const f32x4 o = v[r][j] * rstd * gg * (sc + 1.0f) + sh; v2u w; w.x = pk2(o.x, o.y); w.y = pk2(o.z, o.w); *(v2u*)(U + (size_t)m * DM + c) = w; } } }
	v_pk_fma_f32 v[114:115], v[162:163], v[114:115], v[178:179]
	v_cvt_pk_bf16_f32 v244, v112, v113
	v_cvt_pk_bf16_f32 v245, v114, v115
	v_pk_mul_f32 v[116:117], v[116:117], v[234:235] op_sel_hi:[1,0]
	v_pk_mul_f32 v[118:119], v[118:119], v[234:235] op_sel_hi:[1,0]
	v_pk_mul_f32 v[116:117], v[68:69], v[116:117]
	v_pk_mul_f32 v[118:119], v[70:71], v[118:119]
	v_pk_fma_f32 v[116:117], v[164:165], v[116:117], v[180:181]
	v_pk_fma_f32 v[118:119], v[166:167], v[118:119], v[182:183]
	v_cvt_pk_bf16_f32 v246, v116, v117
	v_cvt_pk_bf16_f32 v247, v118, v119
	global_store_dwordx4 v82, v[244:247], s[40:41] offset:0
	v_pk_mul_f32 v[120:121], v[120:121], v[234:235] op_sel_hi:[1,0]
	v_pk_mul_f32 v[122:123], v[122:123], v[234:235] op_sel_hi:[1,0]
	v_pk_mul_f32 v[120:121], v[72:73], v[120:121]
	v_pk_mul_f32 v[122:123], v[74:75], v[122:123]
	v_pk_fma_f32 v[120:121], v[168:169], v[120:121], v[184:185]
	v_pk_fma_f32 v[122:123], v[170:171], v[122:123], v[186:187]
	v_cvt_pk_bf16_f32 v240, v120, v121
	v_cvt_pk_bf16_f32 v241, v122, v123
	v_pk_mul_f32 v[124:125], v[124:125], v[234:235] op_sel_hi:[1,0]
	v_pk_mul_f32 v[126:127], v[126:127], v[234:235] op_sel_hi:[1,0]
	v_pk_mul_f32 v[124:125], v[76:77], v[124:125]
	v_pk_mul_f32 v[126:127], v[78:79], v[126:127]
	v_pk_fma_f32 v[124:125], v[172:173], v[124:125], v[188:189]
	v_pk_fma_f32 v[126:127], v[174:175], v[126:127], v[190:191]
	v_cvt_pk_bf16_f32 v242, v124, v125
	v_cvt_pk_bf16_f32 v243, v126, v127
	global_store_dwordx4 v82, v[240:243], s[40:41] offset:1024
	v_pk_mul_f32 v[128:129], v[128:129], v[236:237] op_sel_hi:[1,0]
	v_pk_mul_f32 v[130:131], v[130:131], v[236:237] op_sel_hi:[1,0]
	v_pk_mul_f32 v[128:129], v[64:65], v[128:129]
	v_pk_mul_f32 v[130:131], v[66:67], v[130:131]
	v_pk_fma_f32 v[128:129], v[192:193], v[128:129], v[208:209]
	v_pk_fma_f32 v[130:131], v[194:195], v[130:131], v[210:211]
	v_cvt_pk_bf16_f32 v244, v128, v129
	v_cvt_pk_bf16_f32 v245, v130, v131
	v_pk_mul_f32 v[132:133], v[132:133], v[236:237] op_sel_hi:[1,0]
	v_pk_mul_f32 v[134:135], v[134:135], v[236:237] op_sel_hi:[1,0]
	v_pk_mul_f32 v[132:133], v[68:69], v[132:133]
	v_pk_mul_f32 v[134:135], v[70:71], v[134:135]
	v_pk_fma_f32 v[132:133], v[196:197], v[132:133], v[212:213]
	v_pk_fma_f32 v[134:135], v[198:199], v[134:135], v[214:215]
	v_cvt_pk_bf16_f32 v246, v132, v133
	v_cvt_pk_bf16_f32 v247, v134, v135
	global_store_dwordx4 v82, v[244:247], s[46:47] offset:0
	v_pk_mul_f32 v[136:137], v[136:137], v[236:237] op_sel_hi:[1,0]
	v_pk_mul_f32 v[138:139], v[138:139], v[236:237] op_sel_hi:[1,0]
	v_pk_mul_f32 v[136:137], v[72:73], v[136:137]
	v_pk_mul_f32 v[138:139], v[74:75], v[138:139]
	v_pk_fma_f32 v[136:137], v[200:201], v[136:137], v[216:217]
	v_pk_fma_f32 v[138:139], v[202:203], v[138:139], v[218:219]
	v_cvt_pk_bf16_f32 v240, v136, v137
	v_cvt_pk_bf16_f32 v241, v138, v139
	v_pk_mul_f32 v[140:141], v[140:141], v[236:237] op_sel_hi:[1,0]
	v_pk_mul_f32 v[142:143], v[142:143], v[236:237] op_sel_hi:[1,0]
	v_pk_mul_f32 v[140:141], v[76:77], v[140:141]
	v_pk_mul_f32 v[142:143], v[78:79], v[142:143]
	v_pk_fma_f32 v[140:141], v[204:205], v[140:141], v[220:221]
	v_pk_fma_f32 v[142:143], v[206:207], v[142:143], v[222:223]
	v_cvt_pk_bf16_f32 v242, v140, v141
	v_cvt_pk_bf16_f32 v243, v142, v143
	global_store_dwordx4 v82, v[240:243], s[46:47] offset:1024
	v_pk_mul_f32 v[144:145], v[144:145], v[238:239] op_sel_hi:[1,0]
	v_pk_mul_f32 v[146:147], v[146:147], v[238:239] op_sel_hi:[1,0]
	v_pk_mul_f32 v[144:145], v[64:65], v[144:145]
	v_pk_mul_f32 v[146:147], v[66:67], v[146:147]
	v_pk_fma_f32 v[144:145], v[192:193], v[144:145], v[208:209]
	v_pk_fma_f32 v[146:147], v[194:195], v[146:147], v[210:211]
	v_cvt_pk_bf16_f32 v244, v144, v145
	v_cvt_pk_bf16_f32 v245, v146, v147
	v_pk_mul_f32 v[148:149], v[148:149], v[238:239] op_sel_hi:[1,0]
	v_pk_mul_f32 v[150:151], v[150:151], v[238:239] op_sel_hi:[1,0]
	v_pk_mul_f32 v[148:149], v[68:69], v[148:149]
	v_pk_mul_f32 v[150:151], v[70:71], v[150:151]
	v_pk_fma_f32 v[148:149], v[196:197], v[148:149], v[212:213]
	v_pk_fma_f32 v[150:151], v[198:199], v[150:151], v[214:215]
	v_cvt_pk_bf16_f32 v246, v148, v149
	v_cvt_pk_bf16_f32 v247, v150, v151
	global_store_dwordx4 v82, v[244:247], s[48:49] offset:0
	v_pk_mul_f32 v[152:153], v[152:153], v[238:239] op_sel_hi:[1,0]
	v_pk_mul_f32 v[154:155], v[154:155], v[238:239] op_sel_hi:[1,0]
	v_pk_mul_f32 v[152:153], v[72:73], v[152:153]
	v_pk_mul_f32 v[154:155], v[74:75], v[154:155]
	v_pk_fma_f32 v[152:153], v[200:201], v[152:153], v[216:217]
	v_pk_fma_f32 v[154:155], v[202:203], v[154:155], v[218:219]
	v_cvt_pk_bf16_f32 v240, v152, v153
	v_cvt_pk_bf16_f32 v241, v154, v155
	v_pk_mul_f32 v[156:157], v[156:157], v[238:239] op_sel_hi:[1,0]
	v_pk_mul_f32 v[158:159], v[158:159], v[238:239] op_sel_hi:[1,0]
	v_pk_mul_f32 v[156:157], v[76:77], v[156:157]
	v_pk_mul_f32 v[158:159], v[78:79], v[158:159]
	v_pk_fma_f32 v[156:157], v[204:205], v[156:157], v[220:221]
	v_pk_fma_f32 v[158:159], v[206:207], v[158:159], v[222:223]
	v_cvt_pk_bf16_f32 v242, v156, v157
	v_cvt_pk_bf16_f32 v243, v158, v159
	global_store_dwordx4 v82, v[240:243], s[48:49] offset:1024
	s_add_u32 s34, s8, 0x24000
	s_addc_u32 s35, s9, 0
	s_add_u32 s36, s8, 0x24000
	s_addc_u32 s37, s9, 0
	global_load_dwordx4 v[176:179], v80, s[34:35] offset:0
	global_load_dwordx4 v[180:183], v80, s[34:35] offset:16
	global_load_dwordx4 v[184:187], v80, s[34:35] offset:2048
	global_load_dwordx4 v[188:191], v80, s[34:35] offset:2064
	global_load_dwordx4 v[160:163], v81, s[34:35] offset:0
	global_load_dwordx4 v[164:167], v81, s[34:35] offset:16
	global_load_dwordx4 v[168:171], v81, s[34:35] offset:2048
	global_load_dwordx4 v[172:175], v81, s[34:35] offset:2064
; __device__ __forceinline__ float bf_lo(unsigned w) { return __uint_as_float(w << 16); }
; __device__ __forceinline__ float bf_hi(unsigned w) { return __uint_as_float(w & 0xffff0000u); }
; template <bool BF> __device__ __forceinline__ void prep_rows(const float* xp, const float* xs, const bf16* hb, const float* g, const float* MOD, int shoff, int scoff, bf16* U, int gw, int NGW, int lane) {
;     ...
;         for (int r = 0; r < R; ++r) { const int m = mb + r * NGW; const int mc = m < MT ? m : mb;
; #pragma unroll
;             for (int j = 0; j < 4; ++j) {
;                 if (BF) { const v2u a0 = *(const v2u*)(hb + (size_t)mc * DM + 4 * lane + 256 * j);
;                     v[r][j].x = pg8::bf_lo(a0.x); v[r][j].y = pg8::bf_hi(a0.x); v[r][j].z = pg8::bf_lo(a0.y); v[r][j].w = pg8::bf_hi(a0.y); }
;                 else { const float* xr = mc < MP ? xp + (size_t)mc * DM : xs + (size_t)(mc - MP) * DM; v[r][j] = *(const f32x4*)(xr + 4 * lane + 256 * j); } } }
; #pragma unroll
;         for (int r = 0; r < R; ++r) { float t = 0.f;
; #pragma unroll
;             for (int j = 0; j < 4; ++j) t += (v[r][j].x * v[r][j].x + v[r][j].y * v[r][j].y) + (v[r][j].z * v[r][j].z + v[r][j].w * v[r][j].w);
;             s[r] = t; }
; #pragma unroll
;         for (int o = 1; o < 64; o <<= 1) {
; #pragma unroll
;             for (int r = 0; r < R; ++r) s[r] += __shfl_xor(s[r], o); }
; #pragma unroll
	global_load_dwordx4 v[208:211], v80, s[36:37] offset:0
	global_load_dwordx4 v[212:215], v80, s[36:37] offset:16
	global_load_dwordx4 v[216:219], v80, s[36:37] offset:2048
	global_load_dwordx4 v[220:223], v80, s[36:37] offset:2064
	global_load_dwordx4 v[192:195], v81, s[36:37] offset:0
	global_load_dwordx4 v[196:199], v81, s[36:37] offset:16
	global_load_dwordx4 v[200:203], v81, s[36:37] offset:2048
	global_load_dwordx4 v[204:207], v81, s[36:37] offset:2064
	s_add_u32 s24, s16, 0xe000000
	s_addc_u32 s25, s17, 0
	s_add_u32 s26, s16, 0xe800000
	s_addc_u32 s27, s17, 0
	s_add_u32 s28, s16, 0xf000000
	s_addc_u32 s29, s17, 0
	s_add_u32 s30, s16, 0xf800000
	s_addc_u32 s31, s17, 0
	global_load_dwordx4 v[96:99], v80, s[24:25] offset:0
	global_load_dwordx4 v[100:103], v80, s[24:25] offset:16
	global_load_dwordx4 v[104:107], v80, s[24:25] offset:2048
	global_load_dwordx4 v[108:111], v80, s[24:25] offset:2064
	global_load_dwordx4 v[112:115], v80, s[26:27] offset:0
	global_load_dwordx4 v[116:119], v80, s[26:27] offset:16
	global_load_dwordx4 v[120:123], v80, s[26:27] offset:2048
	global_load_dwordx4 v[124:127], v80, s[26:27] offset:2064
	global_load_dwordx4 v[128:131], v80, s[28:29] offset:0
	global_load_dwordx4 v[132:135], v80, s[28:29] offset:16
	global_load_dwordx4 v[136:139], v80, s[28:29] offset:2048
	global_load_dwordx4 v[140:143], v80, s[28:29] offset:2064
	global_load_dwordx4 v[144:147], v80, s[30:31] offset:0
	global_load_dwordx4 v[148:151], v80, s[30:31] offset:16
	global_load_dwordx4 v[152:155], v80, s[30:31] offset:2048
	global_load_dwordx4 v[156:159], v80, s[30:31] offset:2064
	s_waitcnt vmcnt(40)
	v_pk_mul_f32 v[240:241], v[0:1], v[0:1]
	v_pk_mul_f32 v[242:243], v[16:17], v[16:17]
	v_pk_mul_f32 v[244:245], v[32:33], v[32:33]
	v_pk_mul_f32 v[246:247], v[48:49], v[48:49]
	v_pk_fma_f32 v[240:241], v[2:3], v[2:3], v[240:241]
	v_pk_fma_f32 v[242:243], v[18:19], v[18:19], v[242:243]
	v_pk_fma_f32 v[244:245], v[34:35], v[34:35], v[244:245]
	v_pk_fma_f32 v[246:247], v[50:51], v[50:51], v[246:247]
	v_pk_fma_f32 v[240:241], v[4:5], v[4:5], v[240:241]
	v_pk_fma_f32 v[242:243], v[20:21], v[20:21], v[242:243]
	v_pk_fma_f32 v[244:245], v[36:37], v[36:37], v[244:245]
	v_pk_fma_f32 v[246:247], v[52:53], v[52:53], v[246:247]
	v_pk_fma_f32 v[240:241], v[6:7], v[6:7], v[240:241]
	v_pk_fma_f32 v[242:243], v[22:23], v[22:23], v[242:243]
	v_pk_fma_f32 v[244:245], v[38:39], v[38:39], v[244:245]
	v_pk_fma_f32 v[246:247], v[54:55], v[54:55], v[246:247]
	v_pk_fma_f32 v[240:241], v[8:9], v[8:9], v[240:241]
	v_pk_fma_f32 v[242:243], v[24:25], v[24:25], v[242:243]
	v_pk_fma_f32 v[244:245], v[40:41], v[40:41], v[244:245]
	v_pk_fma_f32 v[246:247], v[56:57], v[56:57], v[246:247]
	v_pk_fma_f32 v[240:241], v[10:11], v[10:11], v[240:241]
	v_pk_fma_f32 v[242:243], v[26:27], v[26:27], v[242:243]
	v_pk_fma_f32 v[244:245], v[42:43], v[42:43], v[244:245]
	v_pk_fma_f32 v[246:247], v[58:59], v[58:59], v[246:247]
	v_pk_fma_f32 v[240:241], v[12:13], v[12:13], v[240:241]
	v_pk_fma_f32 v[242:243], v[28:29], v[28:29], v[242:243]
	v_pk_fma_f32 v[244:245], v[44:45], v[44:45], v[244:245]
	v_pk_fma_f32 v[246:247], v[60:61], v[60:61], v[246:247]
	v_pk_fma_f32 v[240:241], v[14:15], v[14:15], v[240:241]
	v_pk_fma_f32 v[242:243], v[30:31], v[30:31], v[242:243]
	v_pk_fma_f32 v[244:245], v[46:47], v[46:47], v[244:245]
	v_pk_fma_f32 v[246:247], v[62:63], v[62:63], v[246:247]
	v_add_f32_e32 v224, v240, v241
	v_add_f32_e32 v225, v242, v243
	v_add_f32_e32 v226, v244, v245
	v_add_f32_e32 v227, v246, v247
	ds_bpermute_b32 v228, v83, v224
	ds_bpermute_b32 v229, v83, v225
	ds_bpermute_b32 v230, v83, v226
	ds_bpermute_b32 v231, v83, v227
	s_waitcnt lgkmcnt(0)
	v_add_f32_e32 v224, v224, v228
	v_add_f32_e32 v225, v225, v229
	v_add_f32_e32 v226, v226, v230
	v_add_f32_e32 v227, v227, v231
	ds_bpermute_b32 v228, v84, v224
	ds_bpermute_b32 v229, v84, v225
	ds_bpermute_b32 v230, v84, v226
	ds_bpermute_b32 v231, v84, v227
	s_waitcnt lgkmcnt(0)
	v_add_f32_e32 v224, v224, v228
	v_add_f32_e32 v225, v225, v229
	v_add_f32_e32 v226, v226, v230
	v_add_f32_e32 v227, v227, v231
	ds_bpermute_b32 v228, v85, v224
	ds_bpermute_b32 v229, v85, v225
	ds_bpermute_b32 v230, v85, v226
	ds_bpermute_b32 v231, v85, v227
	s_waitcnt lgkmcnt(0)
	v_add_f32_e32 v224, v224, v228
	v_add_f32_e32 v225, v225, v229
	v_add_f32_e32 v226, v226, v230
	v_add_f32_e32 v227, v227, v231
	ds_bpermute_b32 v228, v86, v224
	ds_bpermute_b32 v229, v86, v225
	ds_bpermute_b32 v230, v86, v226
	ds_bpermute_b32 v231, v86, v227
	s_waitcnt lgkmcnt(0)
	v_add_f32_e32 v224, v224, v228
	v_add_f32_e32 v225, v225, v229
	v_add_f32_e32 v226, v226, v230
	v_add_f32_e32 v227, v227, v231
	ds_bpermute_b32 v228, v87, v224
	ds_bpermute_b32 v229, v87, v225
	ds_bpermute_b32 v230, v87, v226
	ds_bpermute_b32 v231, v87, v227
	s_waitcnt lgkmcnt(0)
	v_add_f32_e32 v224, v224, v228
	v_add_f32_e32 v225, v225, v229
	v_add_f32_e32 v226, v226, v230
	v_add_f32_e32 v227, v227, v231
	ds_bpermute_b32 v228, v88, v224
	ds_bpermute_b32 v229, v88, v225
	ds_bpermute_b32 v230, v88, v226
	ds_bpermute_b32 v231, v88, v227
	s_waitcnt lgkmcnt(0)
; template <bool BF> __device__ __forceinline__ void prep_rows(const float* xp, const float* xs, const bf16* hb, const float* g, const float* MOD, int shoff, int scoff, bf16* U, int gw, int NGW, int lane) {
;     ...
;             for (int r = 0; r < R; ++r) s[r] += __shfl_xor(s[r], o); }
; #pragma unroll
;         for (int r = 0; r < R; ++r) { const int m = mb + r * NGW; if (m < MT) {
;             const float rstd = 1.0f / sqrtf(s[r] * (1.0f / DM) + RMS_EPS);
	v_add_f32_e32 v224, v224, v228
	v_add_f32_e32 v225, v225, v229
	v_add_f32_e32 v226, v226, v230
	v_add_f32_e32 v227, v227, v231
	v_fmamk_f32 v240, v224, 0x3a800000, v89
	v_mul_f32_e32 v241, 0x4f800000, v240
	v_cmp_gt_f32_e32 vcc, s54, v240
	s_nop 1
	v_cndmask_b32_e32 v247, v240, v241, vcc
	v_sqrt_f32_e32 v242, v247
	s_nop 1
	v_add_u32_e32 v243, -1, v242
	v_add_u32_e32 v244, 1, v242
	v_fma_f32 v245, -v243, v242, v247
	v_fma_f32 v246, -v244, v242, v247
	v_cmp_ge_f32_e64 s[52:53], 0, v245
	s_nop 1
	v_cndmask_b32_e64 v242, v242, v243, s[52:53]
	v_cmp_lt_f32_e64 s[52:53], 0, v246
	s_nop 1
	v_cndmask_b32_e64 v242, v242, v244, s[52:53]
	v_mul_f32_e32 v243, 0x37800000, v242
	v_cndmask_b32_e32 v242, v242, v243, vcc
	v_cmp_class_f32_e32 vcc, v247, v90
	s_nop 1
	v_cndmask_b32_e32 v247, v242, v247, vcc
	v_div_scale_f32 v248, s[52:53], v247, v247, 1.0
	v_rcp_f32_e32 v249, v248
	v_div_scale_f32 v228, vcc, 1.0, v247, 1.0
	s_nop 0
	v_fma_f32 v229, -v248, v249, 1.0
	v_fmac_f32_e32 v249, v229, v249
	v_mul_f32_e32 v230, v228, v249
	v_fma_f32 v229, -v248, v230, v228
	v_fmac_f32_e32 v230, v229, v249
	v_fma_f32 v248, -v248, v230, v228
	v_div_fmas_f32 v248, v248, v249, v230
	v_div_fixup_f32 v232, v248, v247, 1.0
	v_fmamk_f32 v240, v225, 0x3a800000, v89
	v_mul_f32_e32 v241, 0x4f800000, v240
	v_cmp_gt_f32_e32 vcc, s54, v240
	s_nop 1
	v_cndmask_b32_e32 v247, v240, v241, vcc
	v_sqrt_f32_e32 v242, v247
	s_nop 1
	v_add_u32_e32 v243, -1, v242
	v_add_u32_e32 v244, 1, v242
	v_fma_f32 v245, -v243, v242, v247
	v_fma_f32 v246, -v244, v242, v247
	v_cmp_ge_f32_e64 s[52:53], 0, v245
	s_nop 1
	v_cndmask_b32_e64 v242, v242, v243, s[52:53]
	v_cmp_lt_f32_e64 s[52:53], 0, v246
	s_nop 1
	v_cndmask_b32_e64 v242, v242, v244, s[52:53]
	v_mul_f32_e32 v243, 0x37800000, v242
	v_cndmask_b32_e32 v242, v242, v243, vcc
	v_cmp_class_f32_e32 vcc, v247, v90
	s_nop 1
	v_cndmask_b32_e32 v247, v242, v247, vcc
	v_div_scale_f32 v248, s[52:53], v247, v247, 1.0
	v_rcp_f32_e32 v249, v248
	v_div_scale_f32 v228, vcc, 1.0, v247, 1.0
	s_nop 0
	v_fma_f32 v229, -v248, v249, 1.0
	v_fmac_f32_e32 v249, v229, v249
	v_mul_f32_e32 v230, v228, v249
	v_fma_f32 v229, -v248, v230, v228
	v_fmac_f32_e32 v230, v229, v249
	v_fma_f32 v248, -v248, v230, v228
	v_div_fmas_f32 v248, v248, v249, v230
	v_div_fixup_f32 v234, v248, v247, 1.0
	v_fmamk_f32 v240, v226, 0x3a800000, v89
	v_mul_f32_e32 v241, 0x4f800000, v240
	v_cmp_gt_f32_e32 vcc, s54, v240
	s_nop 1
	v_cndmask_b32_e32 v247, v240, v241, vcc
	v_sqrt_f32_e32 v242, v247
	s_nop 1
	v_add_u32_e32 v243, -1, v242
	v_add_u32_e32 v244, 1, v242
	v_fma_f32 v245, -v243, v242, v247
	v_fma_f32 v246, -v244, v242, v247
	v_cmp_ge_f32_e64 s[52:53], 0, v245
	s_nop 1
	v_cndmask_b32_e64 v242, v242, v243, s[52:53]
	v_cmp_lt_f32_e64 s[52:53], 0, v246
	s_nop 1
	v_cndmask_b32_e64 v242, v242, v244, s[52:53]
	v_mul_f32_e32 v243, 0x37800000, v242
	v_cndmask_b32_e32 v242, v242, v243, vcc
	v_cmp_class_f32_e32 vcc, v247, v90
	s_nop 1
	v_cndmask_b32_e32 v247, v242, v247, vcc
	v_div_scale_f32 v248, s[52:53], v247, v247, 1.0
	v_rcp_f32_e32 v249, v248
	v_div_scale_f32 v228, vcc, 1.0, v247, 1.0
	s_nop 0
	v_fma_f32 v229, -v248, v249, 1.0
	v_fmac_f32_e32 v249, v229, v249
	v_mul_f32_e32 v230, v228, v249
	v_fma_f32 v229, -v248, v230, v228
	v_fmac_f32_e32 v230, v229, v249
	v_fma_f32 v248, -v248, v230, v228
	v_div_fmas_f32 v248, v248, v249, v230
	v_div_fixup_f32 v236, v248, v247, 1.0
	v_fmamk_f32 v240, v227, 0x3a800000, v89
	v_mul_f32_e32 v241, 0x4f800000, v240
	v_cmp_gt_f32_e32 vcc, s54, v240
	s_nop 1
	v_cndmask_b32_e32 v247, v240, v241, vcc
	v_sqrt_f32_e32 v242, v247
	s_nop 1
	v_add_u32_e32 v243, -1, v242
	v_add_u32_e32 v244, 1, v242
	v_fma_f32 v245, -v243, v242, v247
	v_fma_f32 v246, -v244, v242, v247
	v_cmp_ge_f32_e64 s[52:53], 0, v245
	s_nop 1
	v_cndmask_b32_e64 v242, v242, v243, s[52:53]
	v_cmp_lt_f32_e64 s[52:53], 0, v246
	s_nop 1
	v_cndmask_b32_e64 v242, v242, v244, s[52:53]
	v_mul_f32_e32 v243, 0x37800000, v242
	v_cndmask_b32_e32 v242, v242, v243, vcc
	v_cmp_class_f32_e32 vcc, v247, v90
	s_nop 1
	v_cndmask_b32_e32 v247, v242, v247, vcc
	v_div_scale_f32 v248, s[52:53], v247, v247, 1.0
	v_rcp_f32_e32 v249, v248
	v_div_scale_f32 v228, vcc, 1.0, v247, 1.0
	s_nop 0
	v_fma_f32 v229, -v248, v249, 1.0
	v_fmac_f32_e32 v249, v229, v249
	v_mul_f32_e32 v230, v228, v249
	v_fma_f32 v229, -v248, v230, v228
	v_fmac_f32_e32 v230, v229, v249
	v_fma_f32 v248, -v248, v230, v228
	v_div_fmas_f32 v248, v248, v249, v230
	v_div_fixup_f32 v238, v248, v247, 1.0
	s_waitcnt vmcnt(16)
; __device__ __forceinline__ unsigned pk2(float lo, float hi) { return pg8::cvt_pk_bf16(lo, hi); }
; template <bool BF> __device__ __forceinline__ void prep_rows(const float* xp, const float* xs, const bf16* hb, const float* g, const float* MOD, int shoff, int scoff, bf16* U, int gw, int NGW, int lane) {
;     ...
;                 const f32x4 gg = *(const f32x4*)(g + c), sc = *(const f32x4*)(mr + scoff + c), sh = *(const f32x4*)(mr + shoff + c);
;                 const f32x4 o = v[r][j] * rstd * gg * (sc + 1.0f) + sh; v2u w; w.x = pk2(o.x, o.y); w.y = pk2(o.z, o.w); *(v2u*)(U + (size_t)m * DM + c) = w; } } }
	v_pk_add_f32 v[160:161], v[160:161], 1.0 op_sel_hi:[1,0]
	v_pk_add_f32 v[162:163], v[162:163], 1.0 op_sel_hi:[1,0]
	v_pk_add_f32 v[164:165], v[164:165], 1.0 op_sel_hi:[1,0]
	v_pk_add_f32 v[166:167], v[166:167], 1.0 op_sel_hi:[1,0]
	v_pk_add_f32 v[168:169], v[168:169], 1.0 op_sel_hi:[1,0]
	v_pk_add_f32 v[170:171], v[170:171], 1.0 op_sel_hi:[1,0]
	v_pk_add_f32 v[172:173], v[172:173], 1.0 op_sel_hi:[1,0]
	v_pk_add_f32 v[174:175], v[174:175], 1.0 op_sel_hi:[1,0]
	v_pk_add_f32 v[192:193], v[192:193], 1.0 op_sel_hi:[1,0]
	v_pk_add_f32 v[194:195], v[194:195], 1.0 op_sel_hi:[1,0]
	v_pk_add_f32 v[196:197], v[196:197], 1.0 op_sel_hi:[1,0]
	v_pk_add_f32 v[198:199], v[198:199], 1.0 op_sel_hi:[1,0]
	v_pk_add_f32 v[200:201], v[200:201], 1.0 op_sel_hi:[1,0]
	v_pk_add_f32 v[202:203], v[202:203], 1.0 op_sel_hi:[1,0]
	v_pk_add_f32 v[204:205], v[204:205], 1.0 op_sel_hi:[1,0]
	v_pk_add_f32 v[206:207], v[206:207], 1.0 op_sel_hi:[1,0]
	s_add_u32 s38, s20, 0x6000000
	s_addc_u32 s39, s21, 0
	s_add_u32 s40, s20, 0x6400000
	s_addc_u32 s41, s21, 0
	s_add_u32 s46, s20, 0x6800000
	s_addc_u32 s47, s21, 0
	s_add_u32 s48, s20, 0x6c00000
	s_addc_u32 s49, s21, 0
	v_pk_mul_f32 v[0:1], v[0:1], v[232:233] op_sel_hi:[1,0]
	v_pk_mul_f32 v[2:3], v[2:3], v[232:233] op_sel_hi:[1,0]
	v_pk_mul_f32 v[0:1], v[64:65], v[0:1]
	v_pk_mul_f32 v[2:3], v[66:67], v[2:3]
	v_pk_fma_f32 v[0:1], v[160:161], v[0:1], v[176:177]
	v_pk_fma_f32 v[2:3], v[162:163], v[2:3], v[178:179]
	v_cvt_pk_bf16_f32 v244, v0, v1
	v_cvt_pk_bf16_f32 v245, v2, v3
	v_pk_mul_f32 v[4:5], v[4:5], v[232:233] op_sel_hi:[1,0]
	v_pk_mul_f32 v[6:7], v[6:7], v[232:233] op_sel_hi:[1,0]
	v_pk_mul_f32 v[4:5], v[68:69], v[4:5]
	v_pk_mul_f32 v[6:7], v[70:71], v[6:7]
	v_pk_fma_f32 v[4:5], v[164:165], v[4:5], v[180:181]
	v_pk_fma_f32 v[6:7], v[166:167], v[6:7], v[182:183]
	v_cvt_pk_bf16_f32 v246, v4, v5
	v_cvt_pk_bf16_f32 v247, v6, v7
	global_store_dwordx4 v82, v[244:247], s[38:39] offset:0
	v_pk_mul_f32 v[8:9], v[8:9], v[232:233] op_sel_hi:[1,0]
	v_pk_mul_f32 v[10:11], v[10:11], v[232:233] op_sel_hi:[1,0]
	v_pk_mul_f32 v[8:9], v[72:73], v[8:9]
	v_pk_mul_f32 v[10:11], v[74:75], v[10:11]
	v_pk_fma_f32 v[8:9], v[168:169], v[8:9], v[184:185]
	v_pk_fma_f32 v[10:11], v[170:171], v[10:11], v[186:187]
	v_cvt_pk_bf16_f32 v240, v8, v9
	v_cvt_pk_bf16_f32 v241, v10, v11
	v_pk_mul_f32 v[12:13], v[12:13], v[232:233] op_sel_hi:[1,0]
	v_pk_mul_f32 v[14:15], v[14:15], v[232:233] op_sel_hi:[1,0]
	v_pk_mul_f32 v[12:13], v[76:77], v[12:13]
	v_pk_mul_f32 v[14:15], v[78:79], v[14:15]
	v_pk_fma_f32 v[12:13], v[172:173], v[12:13], v[188:189]
	v_pk_fma_f32 v[14:15], v[174:175], v[14:15], v[190:191]
	v_cvt_pk_bf16_f32 v242, v12, v13
	v_cvt_pk_bf16_f32 v243, v14, v15
	global_store_dwordx4 v82, v[240:243], s[38:39] offset:1024
	v_pk_mul_f32 v[16:17], v[16:17], v[234:235] op_sel_hi:[1,0]
	v_pk_mul_f32 v[18:19], v[18:19], v[234:235] op_sel_hi:[1,0]
	v_pk_mul_f32 v[16:17], v[64:65], v[16:17]
	v_pk_mul_f32 v[18:19], v[66:67], v[18:19]
	v_pk_fma_f32 v[16:17], v[160:161], v[16:17], v[176:177]
	v_pk_fma_f32 v[18:19], v[162:163], v[18:19], v[178:179]
	v_cvt_pk_bf16_f32 v244, v16, v17
	v_cvt_pk_bf16_f32 v245, v18, v19
	v_pk_mul_f32 v[20:21], v[20:21], v[234:235] op_sel_hi:[1,0]
	v_pk_mul_f32 v[22:23], v[22:23], v[234:235] op_sel_hi:[1,0]
	v_pk_mul_f32 v[20:21], v[68:69], v[20:21]
	v_pk_mul_f32 v[22:23], v[70:71], v[22:23]
	v_pk_fma_f32 v[20:21], v[164:165], v[20:21], v[180:181]
	v_pk_fma_f32 v[22:23], v[166:167], v[22:23], v[182:183]
	v_cvt_pk_bf16_f32 v246, v20, v21
	v_cvt_pk_bf16_f32 v247, v22, v23
	global_store_dwordx4 v82, v[244:247], s[40:41] offset:0
	v_pk_mul_f32 v[24:25], v[24:25], v[234:235] op_sel_hi:[1,0]
	v_pk_mul_f32 v[26:27], v[26:27], v[234:235] op_sel_hi:[1,0]
	v_pk_mul_f32 v[24:25], v[72:73], v[24:25]
	v_pk_mul_f32 v[26:27], v[74:75], v[26:27]
	v_pk_fma_f32 v[24:25], v[168:169], v[24:25], v[184:185]
	v_pk_fma_f32 v[26:27], v[170:171], v[26:27], v[186:187]
	v_cvt_pk_bf16_f32 v240, v24, v25
	v_cvt_pk_bf16_f32 v241, v26, v27
	v_pk_mul_f32 v[28:29], v[28:29], v[234:235] op_sel_hi:[1,0]
	v_pk_mul_f32 v[30:31], v[30:31], v[234:235] op_sel_hi:[1,0]
	v_pk_mul_f32 v[28:29], v[76:77], v[28:29]
	v_pk_mul_f32 v[30:31], v[78:79], v[30:31]
	v_pk_fma_f32 v[28:29], v[172:173], v[28:29], v[188:189]
	v_pk_fma_f32 v[30:31], v[174:175], v[30:31], v[190:191]
	v_cvt_pk_bf16_f32 v242, v28, v29
	v_cvt_pk_bf16_f32 v243, v30, v31
	global_store_dwordx4 v82, v[240:243], s[40:41] offset:1024
	v_pk_mul_f32 v[32:33], v[32:33], v[236:237] op_sel_hi:[1,0]
	v_pk_mul_f32 v[34:35], v[34:35], v[236:237] op_sel_hi:[1,0]
	v_pk_mul_f32 v[32:33], v[64:65], v[32:33]
	v_pk_mul_f32 v[34:35], v[66:67], v[34:35]
	v_pk_fma_f32 v[32:33], v[192:193], v[32:33], v[208:209]
	v_pk_fma_f32 v[34:35], v[194:195], v[34:35], v[210:211]
	v_cvt_pk_bf16_f32 v244, v32, v33
	v_cvt_pk_bf16_f32 v245, v34, v35
	v_pk_mul_f32 v[36:37], v[36:37], v[236:237] op_sel_hi:[1,0]
	v_pk_mul_f32 v[38:39], v[38:39], v[236:237] op_sel_hi:[1,0]
	v_pk_mul_f32 v[36:37], v[68:69], v[36:37]
	v_pk_mul_f32 v[38:39], v[70:71], v[38:39]
	v_pk_fma_f32 v[36:37], v[196:197], v[36:37], v[212:213]
	v_pk_fma_f32 v[38:39], v[198:199], v[38:39], v[214:215]
	v_cvt_pk_bf16_f32 v246, v36, v37
	v_cvt_pk_bf16_f32 v247, v38, v39
	global_store_dwordx4 v82, v[244:247], s[46:47] offset:0
	v_pk_mul_f32 v[40:41], v[40:41], v[236:237] op_sel_hi:[1,0]
	v_pk_mul_f32 v[42:43], v[42:43], v[236:237] op_sel_hi:[1,0]
	v_pk_mul_f32 v[40:41], v[72:73], v[40:41]
	v_pk_mul_f32 v[42:43], v[74:75], v[42:43]
	v_pk_fma_f32 v[40:41], v[200:201], v[40:41], v[216:217]
	v_pk_fma_f32 v[42:43], v[202:203], v[42:43], v[218:219]
	v_cvt_pk_bf16_f32 v240, v40, v41
; __device__ __forceinline__ float bf_lo(unsigned w) { return __uint_as_float(w << 16); }
; __device__ __forceinline__ float bf_hi(unsigned w) { return __uint_as_float(w & 0xffff0000u); }
; __device__ __forceinline__ unsigned pk2(float lo, float hi) { return pg8::cvt_pk_bf16(lo, hi); }
; template <bool BF> __device__ __forceinline__ void prep_rows(const float* xp, const float* xs, const bf16* hb, const float* g, const float* MOD, int shoff, int scoff, bf16* U, int gw, int NGW, int lane) {
;     ...
;         for (int r = 0; r < R; ++r) { const int m = mb + r * NGW; const int mc = m < MT ? m : mb;
; #pragma unroll
;             for (int j = 0; j < 4; ++j) {
;                 if (BF) { const v2u a0 = *(const v2u*)(hb + (size_t)mc * DM + 4 * lane + 256 * j);
;                     v[r][j].x = pg8::bf_lo(a0.x); v[r][j].y = pg8::bf_hi(a0.x); v[r][j].z = pg8::bf_lo(a0.y); v[r][j].w = pg8::bf_hi(a0.y); }
;                 else { const float* xr = mc < MP ? xp + (size_t)mc * DM : xs + (size_t)(mc - MP) * DM; v[r][j] = *(const f32x4*)(xr + 4 * lane + 256 * j); } } }
; #pragma unroll
;         for (int r = 0; r < R; ++r) { float t = 0.f;
; #pragma unroll
;             for (int j = 0; j < 4; ++j) t += (v[r][j].x * v[r][j].x + v[r][j].y * v[r][j].y) + (v[r][j].z * v[r][j].z + v[r][j].w * v[r][j].w);
;             s[r] = t; }
; #pragma unroll
;         for (int o = 1; o < 64; o <<= 1) {
; #pragma unroll
;             for (int r = 0; r < R; ++r) s[r] += __shfl_xor(s[r], o); }
; #pragma unroll
;     ...
;                 const f32x4 o = v[r][j] * rstd * gg * (sc + 1.0f) + sh; v2u w; w.x = pk2(o.x, o.y); w.y = pk2(o.z, o.w); *(v2u*)(U + (size_t)m * DM + c) = w; } } }
	v_cvt_pk_bf16_f32 v241, v42, v43
	v_pk_mul_f32 v[44:45], v[44:45], v[236:237] op_sel_hi:[1,0]
	v_pk_mul_f32 v[46:47], v[46:47], v[236:237] op_sel_hi:[1,0]
	v_pk_mul_f32 v[44:45], v[76:77], v[44:45]
	v_pk_mul_f32 v[46:47], v[78:79], v[46:47]
	v_pk_fma_f32 v[44:45], v[204:205], v[44:45], v[220:221]
	v_pk_fma_f32 v[46:47], v[206:207], v[46:47], v[222:223]
	v_cvt_pk_bf16_f32 v242, v44, v45
	v_cvt_pk_bf16_f32 v243, v46, v47
	global_store_dwordx4 v82, v[240:243], s[46:47] offset:1024
	v_pk_mul_f32 v[48:49], v[48:49], v[238:239] op_sel_hi:[1,0]
	v_pk_mul_f32 v[50:51], v[50:51], v[238:239] op_sel_hi:[1,0]
	v_pk_mul_f32 v[48:49], v[64:65], v[48:49]
	v_pk_mul_f32 v[50:51], v[66:67], v[50:51]
	v_pk_fma_f32 v[48:49], v[192:193], v[48:49], v[208:209]
	v_pk_fma_f32 v[50:51], v[194:195], v[50:51], v[210:211]
	v_cvt_pk_bf16_f32 v244, v48, v49
	v_cvt_pk_bf16_f32 v245, v50, v51
	v_pk_mul_f32 v[52:53], v[52:53], v[238:239] op_sel_hi:[1,0]
	v_pk_mul_f32 v[54:55], v[54:55], v[238:239] op_sel_hi:[1,0]
	v_pk_mul_f32 v[52:53], v[68:69], v[52:53]
	v_pk_mul_f32 v[54:55], v[70:71], v[54:55]
	v_pk_fma_f32 v[52:53], v[196:197], v[52:53], v[212:213]
	v_pk_fma_f32 v[54:55], v[198:199], v[54:55], v[214:215]
	v_cvt_pk_bf16_f32 v246, v52, v53
	v_cvt_pk_bf16_f32 v247, v54, v55
	global_store_dwordx4 v82, v[244:247], s[48:49] offset:0
	v_pk_mul_f32 v[56:57], v[56:57], v[238:239] op_sel_hi:[1,0]
	v_pk_mul_f32 v[58:59], v[58:59], v[238:239] op_sel_hi:[1,0]
	v_pk_mul_f32 v[56:57], v[72:73], v[56:57]
	v_pk_mul_f32 v[58:59], v[74:75], v[58:59]
	v_pk_fma_f32 v[56:57], v[200:201], v[56:57], v[216:217]
	v_pk_fma_f32 v[58:59], v[202:203], v[58:59], v[218:219]
	v_cvt_pk_bf16_f32 v240, v56, v57
	v_cvt_pk_bf16_f32 v241, v58, v59
	v_pk_mul_f32 v[60:61], v[60:61], v[238:239] op_sel_hi:[1,0]
	v_pk_mul_f32 v[62:63], v[62:63], v[238:239] op_sel_hi:[1,0]
	v_pk_mul_f32 v[60:61], v[76:77], v[60:61]
	v_pk_mul_f32 v[62:63], v[78:79], v[62:63]
	v_pk_fma_f32 v[60:61], v[204:205], v[60:61], v[220:221]
	v_pk_fma_f32 v[62:63], v[206:207], v[62:63], v[222:223]
	v_cvt_pk_bf16_f32 v242, v60, v61
	v_cvt_pk_bf16_f32 v243, v62, v63
	global_store_dwordx4 v82, v[240:243], s[48:49] offset:1024
	s_add_u32 s34, s8, 0x2a000
	s_addc_u32 s35, s9, 0
	s_add_u32 s36, s8, 0x2a000
	s_addc_u32 s37, s9, 0
	global_load_dwordx4 v[176:179], v80, s[34:35] offset:0
	global_load_dwordx4 v[180:183], v80, s[34:35] offset:16
	global_load_dwordx4 v[184:187], v80, s[34:35] offset:2048
	global_load_dwordx4 v[188:191], v80, s[34:35] offset:2064
	global_load_dwordx4 v[160:163], v81, s[34:35] offset:0
	global_load_dwordx4 v[164:167], v81, s[34:35] offset:16
	global_load_dwordx4 v[168:171], v81, s[34:35] offset:2048
	global_load_dwordx4 v[172:175], v81, s[34:35] offset:2064
	global_load_dwordx4 v[208:211], v80, s[36:37] offset:0
	global_load_dwordx4 v[212:215], v80, s[36:37] offset:16
	global_load_dwordx4 v[216:219], v80, s[36:37] offset:2048
	global_load_dwordx4 v[220:223], v80, s[36:37] offset:2064
	global_load_dwordx4 v[192:195], v81, s[36:37] offset:0
	global_load_dwordx4 v[196:199], v81, s[36:37] offset:16
	global_load_dwordx4 v[200:203], v81, s[36:37] offset:2048
	global_load_dwordx4 v[204:207], v81, s[36:37] offset:2064
	s_mov_b64 s[24:25], s[18:19]
	s_add_u32 s26, s18, 0x800000
	s_addc_u32 s27, s19, 0
	s_add_u32 s28, s18, 0x1000000
	s_addc_u32 s29, s19, 0
	s_add_u32 s30, s18, 0x1800000
	s_addc_u32 s31, s19, 0
	global_load_dwordx4 v[0:3], v80, s[24:25] offset:0
	global_load_dwordx4 v[4:7], v80, s[24:25] offset:16
	global_load_dwordx4 v[8:11], v80, s[24:25] offset:2048
	global_load_dwordx4 v[12:15], v80, s[24:25] offset:2064
	global_load_dwordx4 v[16:19], v80, s[26:27] offset:0
	global_load_dwordx4 v[20:23], v80, s[26:27] offset:16
	global_load_dwordx4 v[24:27], v80, s[26:27] offset:2048
	global_load_dwordx4 v[28:31], v80, s[26:27] offset:2064
	global_load_dwordx4 v[32:35], v80, s[28:29] offset:0
	global_load_dwordx4 v[36:39], v80, s[28:29] offset:16
	global_load_dwordx4 v[40:43], v80, s[28:29] offset:2048
	global_load_dwordx4 v[44:47], v80, s[28:29] offset:2064
	global_load_dwordx4 v[48:51], v80, s[30:31] offset:0
	global_load_dwordx4 v[52:55], v80, s[30:31] offset:16
	global_load_dwordx4 v[56:59], v80, s[30:31] offset:2048
	global_load_dwordx4 v[60:63], v80, s[30:31] offset:2064
	s_waitcnt vmcnt(40)
	v_pk_mul_f32 v[240:241], v[96:97], v[96:97]
	v_pk_mul_f32 v[242:243], v[112:113], v[112:113]
	v_pk_mul_f32 v[244:245], v[128:129], v[128:129]
	v_pk_mul_f32 v[246:247], v[144:145], v[144:145]
	v_pk_fma_f32 v[240:241], v[98:99], v[98:99], v[240:241]
	v_pk_fma_f32 v[242:243], v[114:115], v[114:115], v[242:243]
	v_pk_fma_f32 v[244:245], v[130:131], v[130:131], v[244:245]
	v_pk_fma_f32 v[246:247], v[146:147], v[146:147], v[246:247]
	v_pk_fma_f32 v[240:241], v[100:101], v[100:101], v[240:241]
	v_pk_fma_f32 v[242:243], v[116:117], v[116:117], v[242:243]
	v_pk_fma_f32 v[244:245], v[132:133], v[132:133], v[244:245]
	v_pk_fma_f32 v[246:247], v[148:149], v[148:149], v[246:247]
	v_pk_fma_f32 v[240:241], v[102:103], v[102:103], v[240:241]
	v_pk_fma_f32 v[242:243], v[118:119], v[118:119], v[242:243]
	v_pk_fma_f32 v[244:245], v[134:135], v[134:135], v[244:245]
	v_pk_fma_f32 v[246:247], v[150:151], v[150:151], v[246:247]
	v_pk_fma_f32 v[240:241], v[104:105], v[104:105], v[240:241]
	v_pk_fma_f32 v[242:243], v[120:121], v[120:121], v[242:243]
	v_pk_fma_f32 v[244:245], v[136:137], v[136:137], v[244:245]
	v_pk_fma_f32 v[246:247], v[152:153], v[152:153], v[246:247]
	v_pk_fma_f32 v[240:241], v[106:107], v[106:107], v[240:241]
	v_pk_fma_f32 v[242:243], v[122:123], v[122:123], v[242:243]
	v_pk_fma_f32 v[244:245], v[138:139], v[138:139], v[244:245]
	v_pk_fma_f32 v[246:247], v[154:155], v[154:155], v[246:247]
	v_pk_fma_f32 v[240:241], v[108:109], v[108:109], v[240:241]
	v_pk_fma_f32 v[242:243], v[124:125], v[124:125], v[242:243]
	v_pk_fma_f32 v[244:245], v[140:141], v[140:141], v[244:245]
	v_pk_fma_f32 v[246:247], v[156:157], v[156:157], v[246:247]
	v_pk_fma_f32 v[240:241], v[110:111], v[110:111], v[240:241]
	v_pk_fma_f32 v[242:243], v[126:127], v[126:127], v[242:243]
	v_pk_fma_f32 v[244:245], v[142:143], v[142:143], v[244:245]
	v_pk_fma_f32 v[246:247], v[158:159], v[158:159], v[246:247]
	v_add_f32_e32 v224, v240, v241
	v_add_f32_e32 v225, v242, v243
	v_add_f32_e32 v226, v244, v245
	v_add_f32_e32 v227, v246, v247
	ds_bpermute_b32 v228, v83, v224
	ds_bpermute_b32 v229, v83, v225
	ds_bpermute_b32 v230, v83, v226
	ds_bpermute_b32 v231, v83, v227
	s_waitcnt lgkmcnt(0)
; template <bool BF> __device__ __forceinline__ void prep_rows(const float* xp, const float* xs, const bf16* hb, const float* g, const float* MOD, int shoff, int scoff, bf16* U, int gw, int NGW, int lane) {
;     ...
;             for (int r = 0; r < R; ++r) s[r] += __shfl_xor(s[r], o); }
; #pragma unroll
;         for (int r = 0; r < R; ++r) { const int m = mb + r * NGW; if (m < MT) {
;             const float rstd = 1.0f / sqrtf(s[r] * (1.0f / DM) + RMS_EPS);
	v_add_f32_e32 v224, v224, v228
	v_add_f32_e32 v225, v225, v229
	v_add_f32_e32 v226, v226, v230
	v_add_f32_e32 v227, v227, v231
	ds_bpermute_b32 v228, v84, v224
	ds_bpermute_b32 v229, v84, v225
	ds_bpermute_b32 v230, v84, v226
	ds_bpermute_b32 v231, v84, v227
	s_waitcnt lgkmcnt(0)
	v_add_f32_e32 v224, v224, v228
	v_add_f32_e32 v225, v225, v229
	v_add_f32_e32 v226, v226, v230
	v_add_f32_e32 v227, v227, v231
	ds_bpermute_b32 v228, v85, v224
	ds_bpermute_b32 v229, v85, v225
	ds_bpermute_b32 v230, v85, v226
	ds_bpermute_b32 v231, v85, v227
	s_waitcnt lgkmcnt(0)
	v_add_f32_e32 v224, v224, v228
	v_add_f32_e32 v225, v225, v229
	v_add_f32_e32 v226, v226, v230
	v_add_f32_e32 v227, v227, v231
	ds_bpermute_b32 v228, v86, v224
	ds_bpermute_b32 v229, v86, v225
	ds_bpermute_b32 v230, v86, v226
	ds_bpermute_b32 v231, v86, v227
	s_waitcnt lgkmcnt(0)
	v_add_f32_e32 v224, v224, v228
	v_add_f32_e32 v225, v225, v229
	v_add_f32_e32 v226, v226, v230
	v_add_f32_e32 v227, v227, v231
	ds_bpermute_b32 v228, v87, v224
	ds_bpermute_b32 v229, v87, v225
	ds_bpermute_b32 v230, v87, v226
	ds_bpermute_b32 v231, v87, v227
	s_waitcnt lgkmcnt(0)
	v_add_f32_e32 v224, v224, v228
	v_add_f32_e32 v225, v225, v229
	v_add_f32_e32 v226, v226, v230
	v_add_f32_e32 v227, v227, v231
	ds_bpermute_b32 v228, v88, v224
	ds_bpermute_b32 v229, v88, v225
	ds_bpermute_b32 v230, v88, v226
	ds_bpermute_b32 v231, v88, v227
	s_waitcnt lgkmcnt(0)
	v_add_f32_e32 v224, v224, v228
	v_add_f32_e32 v225, v225, v229
	v_add_f32_e32 v226, v226, v230
	v_add_f32_e32 v227, v227, v231
	v_fmamk_f32 v240, v224, 0x3a800000, v89
	v_mul_f32_e32 v241, 0x4f800000, v240
	v_cmp_gt_f32_e32 vcc, s54, v240
	s_nop 1
	v_cndmask_b32_e32 v247, v240, v241, vcc
	v_sqrt_f32_e32 v242, v247
	s_nop 1
	v_add_u32_e32 v243, -1, v242
	v_add_u32_e32 v244, 1, v242
	v_fma_f32 v245, -v243, v242, v247
	v_fma_f32 v246, -v244, v242, v247
	v_cmp_ge_f32_e64 s[52:53], 0, v245
	s_nop 1
	v_cndmask_b32_e64 v242, v242, v243, s[52:53]
	v_cmp_lt_f32_e64 s[52:53], 0, v246
	s_nop 1
	v_cndmask_b32_e64 v242, v242, v244, s[52:53]
	v_mul_f32_e32 v243, 0x37800000, v242
	v_cndmask_b32_e32 v242, v242, v243, vcc
	v_cmp_class_f32_e32 vcc, v247, v90
	s_nop 1
	v_cndmask_b32_e32 v247, v242, v247, vcc
	v_div_scale_f32 v248, s[52:53], v247, v247, 1.0
	v_rcp_f32_e32 v249, v248
	v_div_scale_f32 v228, vcc, 1.0, v247, 1.0
	s_nop 0
	v_fma_f32 v229, -v248, v249, 1.0
	v_fmac_f32_e32 v249, v229, v249
	v_mul_f32_e32 v230, v228, v249
	v_fma_f32 v229, -v248, v230, v228
	v_fmac_f32_e32 v230, v229, v249
	v_fma_f32 v248, -v248, v230, v228
	v_div_fmas_f32 v248, v248, v249, v230
	v_div_fixup_f32 v232, v248, v247, 1.0
	v_fmamk_f32 v240, v225, 0x3a800000, v89
	v_mul_f32_e32 v241, 0x4f800000, v240
	v_cmp_gt_f32_e32 vcc, s54, v240
	s_nop 1
	v_cndmask_b32_e32 v247, v240, v241, vcc
	v_sqrt_f32_e32 v242, v247
	s_nop 1
	v_add_u32_e32 v243, -1, v242
	v_add_u32_e32 v244, 1, v242
	v_fma_f32 v245, -v243, v242, v247
	v_fma_f32 v246, -v244, v242, v247
	v_cmp_ge_f32_e64 s[52:53], 0, v245
	s_nop 1
	v_cndmask_b32_e64 v242, v242, v243, s[52:53]
	v_cmp_lt_f32_e64 s[52:53], 0, v246
	s_nop 1
	v_cndmask_b32_e64 v242, v242, v244, s[52:53]
	v_mul_f32_e32 v243, 0x37800000, v242
	v_cndmask_b32_e32 v242, v242, v243, vcc
	v_cmp_class_f32_e32 vcc, v247, v90
	s_nop 1
	v_cndmask_b32_e32 v247, v242, v247, vcc
	v_div_scale_f32 v248, s[52:53], v247, v247, 1.0
	v_rcp_f32_e32 v249, v248
	v_div_scale_f32 v228, vcc, 1.0, v247, 1.0
	s_nop 0
	v_fma_f32 v229, -v248, v249, 1.0
	v_fmac_f32_e32 v249, v229, v249
	v_mul_f32_e32 v230, v228, v249
	v_fma_f32 v229, -v248, v230, v228
	v_fmac_f32_e32 v230, v229, v249
	v_fma_f32 v248, -v248, v230, v228
	v_div_fmas_f32 v248, v248, v249, v230
	v_div_fixup_f32 v234, v248, v247, 1.0
	v_fmamk_f32 v240, v226, 0x3a800000, v89
	v_mul_f32_e32 v241, 0x4f800000, v240
	v_cmp_gt_f32_e32 vcc, s54, v240
	s_nop 1
	v_cndmask_b32_e32 v247, v240, v241, vcc
	v_sqrt_f32_e32 v242, v247
	s_nop 1
	v_add_u32_e32 v243, -1, v242
	v_add_u32_e32 v244, 1, v242
	v_fma_f32 v245, -v243, v242, v247
	v_fma_f32 v246, -v244, v242, v247
	v_cmp_ge_f32_e64 s[52:53], 0, v245
	s_nop 1
	v_cndmask_b32_e64 v242, v242, v243, s[52:53]
	v_cmp_lt_f32_e64 s[52:53], 0, v246
	s_nop 1
	v_cndmask_b32_e64 v242, v242, v244, s[52:53]
	v_mul_f32_e32 v243, 0x37800000, v242
	v_cndmask_b32_e32 v242, v242, v243, vcc
	v_cmp_class_f32_e32 vcc, v247, v90
	s_nop 1
	v_cndmask_b32_e32 v247, v242, v247, vcc
	v_div_scale_f32 v248, s[52:53], v247, v247, 1.0
	v_rcp_f32_e32 v249, v248
	v_div_scale_f32 v228, vcc, 1.0, v247, 1.0
	s_nop 0
	v_fma_f32 v229, -v248, v249, 1.0
	v_fmac_f32_e32 v249, v229, v249
	v_mul_f32_e32 v230, v228, v249
	v_fma_f32 v229, -v248, v230, v228
	v_fmac_f32_e32 v230, v229, v249
	v_fma_f32 v248, -v248, v230, v228
	v_div_fmas_f32 v248, v248, v249, v230
	v_div_fixup_f32 v236, v248, v247, 1.0
	v_fmamk_f32 v240, v227, 0x3a800000, v89
	v_mul_f32_e32 v241, 0x4f800000, v240
	v_cmp_gt_f32_e32 vcc, s54, v240
	s_nop 1
	v_cndmask_b32_e32 v247, v240, v241, vcc
	v_sqrt_f32_e32 v242, v247
	s_nop 1
	v_add_u32_e32 v243, -1, v242
	v_add_u32_e32 v244, 1, v242
	v_fma_f32 v245, -v243, v242, v247
	v_fma_f32 v246, -v244, v242, v247
	v_cmp_ge_f32_e64 s[52:53], 0, v245
	s_nop 1
	v_cndmask_b32_e64 v242, v242, v243, s[52:53]
	v_cmp_lt_f32_e64 s[52:53], 0, v246
	s_nop 1
	v_cndmask_b32_e64 v242, v242, v244, s[52:53]
	v_mul_f32_e32 v243, 0x37800000, v242
	v_cndmask_b32_e32 v242, v242, v243, vcc
	v_cmp_class_f32_e32 vcc, v247, v90
	s_nop 1
	v_cndmask_b32_e32 v247, v242, v247, vcc
	v_div_scale_f32 v248, s[52:53], v247, v247, 1.0
	v_rcp_f32_e32 v249, v248
	v_div_scale_f32 v228, vcc, 1.0, v247, 1.0
	s_nop 0
	v_fma_f32 v229, -v248, v249, 1.0
	v_fmac_f32_e32 v249, v229, v249
	v_mul_f32_e32 v230, v228, v249
	v_fma_f32 v229, -v248, v230, v228
	v_fmac_f32_e32 v230, v229, v249
	v_fma_f32 v248, -v248, v230, v228
	v_div_fmas_f32 v248, v248, v249, v230
	v_div_fixup_f32 v238, v248, v247, 1.0
	s_waitcnt vmcnt(16)
; __device__ __forceinline__ unsigned pk2(float lo, float hi) { return pg8::cvt_pk_bf16(lo, hi); }
; template <bool BF> __device__ __forceinline__ void prep_rows(const float* xp, const float* xs, const bf16* hb, const float* g, const float* MOD, int shoff, int scoff, bf16* U, int gw, int NGW, int lane) {
;     ...
;                 const f32x4 gg = *(const f32x4*)(g + c), sc = *(const f32x4*)(mr + scoff + c), sh = *(const f32x4*)(mr + shoff + c);
;                 const f32x4 o = v[r][j] * rstd * gg * (sc + 1.0f) + sh; v2u w; w.x = pk2(o.x, o.y); w.y = pk2(o.z, o.w); *(v2u*)(U + (size_t)m * DM + c) = w; } } }
	v_pk_add_f32 v[160:161], v[160:161], 1.0 op_sel_hi:[1,0]
	v_pk_add_f32 v[162:163], v[162:163], 1.0 op_sel_hi:[1,0]
	v_pk_add_f32 v[164:165], v[164:165], 1.0 op_sel_hi:[1,0]
	v_pk_add_f32 v[166:167], v[166:167], 1.0 op_sel_hi:[1,0]
	v_pk_add_f32 v[168:169], v[168:169], 1.0 op_sel_hi:[1,0]
	v_pk_add_f32 v[170:171], v[170:171], 1.0 op_sel_hi:[1,0]
	v_pk_add_f32 v[172:173], v[172:173], 1.0 op_sel_hi:[1,0]
	v_pk_add_f32 v[174:175], v[174:175], 1.0 op_sel_hi:[1,0]
	v_pk_add_f32 v[192:193], v[192:193], 1.0 op_sel_hi:[1,0]
	v_pk_add_f32 v[194:195], v[194:195], 1.0 op_sel_hi:[1,0]
	v_pk_add_f32 v[196:197], v[196:197], 1.0 op_sel_hi:[1,0]
	v_pk_add_f32 v[198:199], v[198:199], 1.0 op_sel_hi:[1,0]
	v_pk_add_f32 v[200:201], v[200:201], 1.0 op_sel_hi:[1,0]
	v_pk_add_f32 v[202:203], v[202:203], 1.0 op_sel_hi:[1,0]
	v_pk_add_f32 v[204:205], v[204:205], 1.0 op_sel_hi:[1,0]
	v_pk_add_f32 v[206:207], v[206:207], 1.0 op_sel_hi:[1,0]
	s_add_u32 s38, s20, 0x7000000
	s_addc_u32 s39, s21, 0
	s_add_u32 s40, s20, 0x7400000
	s_addc_u32 s41, s21, 0
	s_add_u32 s46, s20, 0x7800000
	s_addc_u32 s47, s21, 0
	s_add_u32 s48, s20, 0x7c00000
	s_addc_u32 s49, s21, 0
	v_pk_mul_f32 v[96:97], v[96:97], v[232:233] op_sel_hi:[1,0]
	v_pk_mul_f32 v[98:99], v[98:99], v[232:233] op_sel_hi:[1,0]
	v_pk_mul_f32 v[96:97], v[64:65], v[96:97]
	v_pk_mul_f32 v[98:99], v[66:67], v[98:99]
	v_pk_fma_f32 v[96:97], v[160:161], v[96:97], v[176:177]
	v_pk_fma_f32 v[98:99], v[162:163], v[98:99], v[178:179]
	v_cvt_pk_bf16_f32 v244, v96, v97
	v_cvt_pk_bf16_f32 v245, v98, v99
	v_pk_mul_f32 v[100:101], v[100:101], v[232:233] op_sel_hi:[1,0]
	v_pk_mul_f32 v[102:103], v[102:103], v[232:233] op_sel_hi:[1,0]
	v_pk_mul_f32 v[100:101], v[68:69], v[100:101]
	v_pk_mul_f32 v[102:103], v[70:71], v[102:103]
	v_pk_fma_f32 v[100:101], v[164:165], v[100:101], v[180:181]
	v_pk_fma_f32 v[102:103], v[166:167], v[102:103], v[182:183]
	v_cvt_pk_bf16_f32 v246, v100, v101
	v_cvt_pk_bf16_f32 v247, v102, v103
	global_store_dwordx4 v82, v[244:247], s[38:39] offset:0
	v_pk_mul_f32 v[104:105], v[104:105], v[232:233] op_sel_hi:[1,0]
	v_pk_mul_f32 v[106:107], v[106:107], v[232:233] op_sel_hi:[1,0]
	v_pk_mul_f32 v[104:105], v[72:73], v[104:105]
	v_pk_mul_f32 v[106:107], v[74:75], v[106:107]
	v_pk_fma_f32 v[104:105], v[168:169], v[104:105], v[184:185]
	v_pk_fma_f32 v[106:107], v[170:171], v[106:107], v[186:187]
	v_cvt_pk_bf16_f32 v240, v104, v105
	v_cvt_pk_bf16_f32 v241, v106, v107
	v_pk_mul_f32 v[108:109], v[108:109], v[232:233] op_sel_hi:[1,0]
	v_pk_mul_f32 v[110:111], v[110:111], v[232:233] op_sel_hi:[1,0]
	v_pk_mul_f32 v[108:109], v[76:77], v[108:109]
	v_pk_mul_f32 v[110:111], v[78:79], v[110:111]
	v_pk_fma_f32 v[108:109], v[172:173], v[108:109], v[188:189]
	v_pk_fma_f32 v[110:111], v[174:175], v[110:111], v[190:191]
	v_cvt_pk_bf16_f32 v242, v108, v109
	v_cvt_pk_bf16_f32 v243, v110, v111
	global_store_dwordx4 v82, v[240:243], s[38:39] offset:1024
	v_pk_mul_f32 v[112:113], v[112:113], v[234:235] op_sel_hi:[1,0]
	v_pk_mul_f32 v[114:115], v[114:115], v[234:235] op_sel_hi:[1,0]
	v_pk_mul_f32 v[112:113], v[64:65], v[112:113]
	v_pk_mul_f32 v[114:115], v[66:67], v[114:115]
	v_pk_fma_f32 v[112:113], v[160:161], v[112:113], v[176:177]
	v_pk_fma_f32 v[114:115], v[162:163], v[114:115], v[178:179]
	v_cvt_pk_bf16_f32 v244, v112, v113
	v_cvt_pk_bf16_f32 v245, v114, v115
	v_pk_mul_f32 v[116:117], v[116:117], v[234:235] op_sel_hi:[1,0]
	v_pk_mul_f32 v[118:119], v[118:119], v[234:235] op_sel_hi:[1,0]
	v_pk_mul_f32 v[116:117], v[68:69], v[116:117]
	v_pk_mul_f32 v[118:119], v[70:71], v[118:119]
	v_pk_fma_f32 v[116:117], v[164:165], v[116:117], v[180:181]
	v_pk_fma_f32 v[118:119], v[166:167], v[118:119], v[182:183]
	v_cvt_pk_bf16_f32 v246, v116, v117
	v_cvt_pk_bf16_f32 v247, v118, v119
	global_store_dwordx4 v82, v[244:247], s[40:41] offset:0
	v_pk_mul_f32 v[120:121], v[120:121], v[234:235] op_sel_hi:[1,0]
	v_pk_mul_f32 v[122:123], v[122:123], v[234:235] op_sel_hi:[1,0]
	v_pk_mul_f32 v[120:121], v[72:73], v[120:121]
	v_pk_mul_f32 v[122:123], v[74:75], v[122:123]
	v_pk_fma_f32 v[120:121], v[168:169], v[120:121], v[184:185]
	v_pk_fma_f32 v[122:123], v[170:171], v[122:123], v[186:187]
	v_cvt_pk_bf16_f32 v240, v120, v121
	v_cvt_pk_bf16_f32 v241, v122, v123
	v_pk_mul_f32 v[124:125], v[124:125], v[234:235] op_sel_hi:[1,0]
	v_pk_mul_f32 v[126:127], v[126:127], v[234:235] op_sel_hi:[1,0]
	v_pk_mul_f32 v[124:125], v[76:77], v[124:125]
	v_pk_mul_f32 v[126:127], v[78:79], v[126:127]
	v_pk_fma_f32 v[124:125], v[172:173], v[124:125], v[188:189]
	v_pk_fma_f32 v[126:127], v[174:175], v[126:127], v[190:191]
	v_cvt_pk_bf16_f32 v242, v124, v125
	v_cvt_pk_bf16_f32 v243, v126, v127
	global_store_dwordx4 v82, v[240:243], s[40:41] offset:1024
	v_pk_mul_f32 v[128:129], v[128:129], v[236:237] op_sel_hi:[1,0]
	v_pk_mul_f32 v[130:131], v[130:131], v[236:237] op_sel_hi:[1,0]
	v_pk_mul_f32 v[128:129], v[64:65], v[128:129]
	v_pk_mul_f32 v[130:131], v[66:67], v[130:131]
	v_pk_fma_f32 v[128:129], v[192:193], v[128:129], v[208:209]
	v_pk_fma_f32 v[130:131], v[194:195], v[130:131], v[210:211]
	v_cvt_pk_bf16_f32 v244, v128, v129
	v_cvt_pk_bf16_f32 v245, v130, v131
	v_pk_mul_f32 v[132:133], v[132:133], v[236:237] op_sel_hi:[1,0]
	v_pk_mul_f32 v[134:135], v[134:135], v[236:237] op_sel_hi:[1,0]
	v_pk_mul_f32 v[132:133], v[68:69], v[132:133]
	v_pk_mul_f32 v[134:135], v[70:71], v[134:135]
	v_pk_fma_f32 v[132:133], v[196:197], v[132:133], v[212:213]
	v_pk_fma_f32 v[134:135], v[198:199], v[134:135], v[214:215]
	v_cvt_pk_bf16_f32 v246, v132, v133
	v_cvt_pk_bf16_f32 v247, v134, v135
	global_store_dwordx4 v82, v[244:247], s[46:47] offset:0
	v_pk_mul_f32 v[136:137], v[136:137], v[236:237] op_sel_hi:[1,0]
; __device__ __forceinline__ float bf_lo(unsigned w) { return __uint_as_float(w << 16); }
; __device__ __forceinline__ float bf_hi(unsigned w) { return __uint_as_float(w & 0xffff0000u); }
; __device__ __forceinline__ unsigned pk2(float lo, float hi) { return pg8::cvt_pk_bf16(lo, hi); }
; template <bool BF> __device__ __forceinline__ void prep_rows(const float* xp, const float* xs, const bf16* hb, const float* g, const float* MOD, int shoff, int scoff, bf16* U, int gw, int NGW, int lane) {
;     ...
;         for (int r = 0; r < R; ++r) { const int m = mb + r * NGW; const int mc = m < MT ? m : mb;
; #pragma unroll
;             for (int j = 0; j < 4; ++j) {
;                 if (BF) { const v2u a0 = *(const v2u*)(hb + (size_t)mc * DM + 4 * lane + 256 * j);
;                     v[r][j].x = pg8::bf_lo(a0.x); v[r][j].y = pg8::bf_hi(a0.x); v[r][j].z = pg8::bf_lo(a0.y); v[r][j].w = pg8::bf_hi(a0.y); }
;                 else { const float* xr = mc < MP ? xp + (size_t)mc * DM : xs + (size_t)(mc - MP) * DM; v[r][j] = *(const f32x4*)(xr + 4 * lane + 256 * j); } } }
;     ...
;         for (int r = 0; r < R; ++r) { const int m = mb + r * NGW; if (m < MT) {
;             const float rstd = 1.0f / sqrtf(s[r] * (1.0f / DM) + RMS_EPS);
;             const float* mr = MOD + (size_t)(m < MP ? (m >> 13) : 8 + ((m - MP) >> 12)) * 6144;
; #pragma unroll
;             for (int j = 0; j < 4; ++j) { const int c = 4 * lane + 256 * j;
;                 const f32x4 gg = *(const f32x4*)(g + c), sc = *(const f32x4*)(mr + scoff + c), sh = *(const f32x4*)(mr + shoff + c);
;                 const f32x4 o = v[r][j] * rstd * gg * (sc + 1.0f) + sh; v2u w; w.x = pk2(o.x, o.y); w.y = pk2(o.z, o.w); *(v2u*)(U + (size_t)m * DM + c) = w; } } }
	v_pk_mul_f32 v[138:139], v[138:139], v[236:237] op_sel_hi:[1,0]
	v_pk_mul_f32 v[136:137], v[72:73], v[136:137]
	v_pk_mul_f32 v[138:139], v[74:75], v[138:139]
	v_pk_fma_f32 v[136:137], v[200:201], v[136:137], v[216:217]
	v_pk_fma_f32 v[138:139], v[202:203], v[138:139], v[218:219]
	v_cvt_pk_bf16_f32 v240, v136, v137
	v_cvt_pk_bf16_f32 v241, v138, v139
	v_pk_mul_f32 v[140:141], v[140:141], v[236:237] op_sel_hi:[1,0]
	v_pk_mul_f32 v[142:143], v[142:143], v[236:237] op_sel_hi:[1,0]
	v_pk_mul_f32 v[140:141], v[76:77], v[140:141]
	v_pk_mul_f32 v[142:143], v[78:79], v[142:143]
	v_pk_fma_f32 v[140:141], v[204:205], v[140:141], v[220:221]
	v_pk_fma_f32 v[142:143], v[206:207], v[142:143], v[222:223]
	v_cvt_pk_bf16_f32 v242, v140, v141
	v_cvt_pk_bf16_f32 v243, v142, v143
	global_store_dwordx4 v82, v[240:243], s[46:47] offset:1024
	v_pk_mul_f32 v[144:145], v[144:145], v[238:239] op_sel_hi:[1,0]
	v_pk_mul_f32 v[146:147], v[146:147], v[238:239] op_sel_hi:[1,0]
	v_pk_mul_f32 v[144:145], v[64:65], v[144:145]
	v_pk_mul_f32 v[146:147], v[66:67], v[146:147]
	v_pk_fma_f32 v[144:145], v[192:193], v[144:145], v[208:209]
	v_pk_fma_f32 v[146:147], v[194:195], v[146:147], v[210:211]
	v_cvt_pk_bf16_f32 v244, v144, v145
	v_cvt_pk_bf16_f32 v245, v146, v147
	v_pk_mul_f32 v[148:149], v[148:149], v[238:239] op_sel_hi:[1,0]
	v_pk_mul_f32 v[150:151], v[150:151], v[238:239] op_sel_hi:[1,0]
	v_pk_mul_f32 v[148:149], v[68:69], v[148:149]
	v_pk_mul_f32 v[150:151], v[70:71], v[150:151]
	v_pk_fma_f32 v[148:149], v[196:197], v[148:149], v[212:213]
	v_pk_fma_f32 v[150:151], v[198:199], v[150:151], v[214:215]
	v_cvt_pk_bf16_f32 v246, v148, v149
	v_cvt_pk_bf16_f32 v247, v150, v151
	global_store_dwordx4 v82, v[244:247], s[48:49] offset:0
	v_pk_mul_f32 v[152:153], v[152:153], v[238:239] op_sel_hi:[1,0]
	v_pk_mul_f32 v[154:155], v[154:155], v[238:239] op_sel_hi:[1,0]
	v_pk_mul_f32 v[152:153], v[72:73], v[152:153]
	v_pk_mul_f32 v[154:155], v[74:75], v[154:155]
	v_pk_fma_f32 v[152:153], v[200:201], v[152:153], v[216:217]
	v_pk_fma_f32 v[154:155], v[202:203], v[154:155], v[218:219]
	v_cvt_pk_bf16_f32 v240, v152, v153
	v_cvt_pk_bf16_f32 v241, v154, v155
	v_pk_mul_f32 v[156:157], v[156:157], v[238:239] op_sel_hi:[1,0]
	v_pk_mul_f32 v[158:159], v[158:159], v[238:239] op_sel_hi:[1,0]
	v_pk_mul_f32 v[156:157], v[76:77], v[156:157]
	v_pk_mul_f32 v[158:159], v[78:79], v[158:159]
	v_pk_fma_f32 v[156:157], v[204:205], v[156:157], v[220:221]
	v_pk_fma_f32 v[158:159], v[206:207], v[158:159], v[222:223]
	v_cvt_pk_bf16_f32 v242, v156, v157
	v_cvt_pk_bf16_f32 v243, v158, v159
	global_store_dwordx4 v82, v[240:243], s[48:49] offset:1024
	s_add_u32 s34, s8, 0x30000
	s_addc_u32 s35, s9, 0
	s_add_u32 s36, s8, 0x36000
	s_addc_u32 s37, s9, 0
	global_load_dwordx4 v[176:179], v80, s[34:35] offset:0
	global_load_dwordx4 v[180:183], v80, s[34:35] offset:16
	global_load_dwordx4 v[184:187], v80, s[34:35] offset:2048
	global_load_dwordx4 v[188:191], v80, s[34:35] offset:2064
	global_load_dwordx4 v[160:163], v81, s[34:35] offset:0
	global_load_dwordx4 v[164:167], v81, s[34:35] offset:16
	global_load_dwordx4 v[168:171], v81, s[34:35] offset:2048
	global_load_dwordx4 v[172:175], v81, s[34:35] offset:2064
	global_load_dwordx4 v[208:211], v80, s[36:37] offset:0
	global_load_dwordx4 v[212:215], v80, s[36:37] offset:16
	global_load_dwordx4 v[216:219], v80, s[36:37] offset:2048
	global_load_dwordx4 v[220:223], v80, s[36:37] offset:2064
	global_load_dwordx4 v[192:195], v81, s[36:37] offset:0
	global_load_dwordx4 v[196:199], v81, s[36:37] offset:16
	global_load_dwordx4 v[200:203], v81, s[36:37] offset:2048
	global_load_dwordx4 v[204:207], v81, s[36:37] offset:2064
	s_add_u32 s24, s18, 0x2000000
	s_addc_u32 s25, s19, 0
	s_add_u32 s26, s18, 0x2800000
	s_addc_u32 s27, s19, 0
	s_add_u32 s28, s18, 0x3000000
	s_addc_u32 s29, s19, 0
	s_add_u32 s30, s18, 0x3800000
	s_addc_u32 s31, s19, 0
	global_load_dwordx4 v[96:99], v80, s[24:25] offset:0
	global_load_dwordx4 v[100:103], v80, s[24:25] offset:16
	global_load_dwordx4 v[104:107], v80, s[24:25] offset:2048
	global_load_dwordx4 v[108:111], v80, s[24:25] offset:2064
	global_load_dwordx4 v[112:115], v80, s[26:27] offset:0
	global_load_dwordx4 v[116:119], v80, s[26:27] offset:16
	global_load_dwordx4 v[120:123], v80, s[26:27] offset:2048
	global_load_dwordx4 v[124:127], v80, s[26:27] offset:2064
	global_load_dwordx4 v[128:131], v80, s[28:29] offset:0
	global_load_dwordx4 v[132:135], v80, s[28:29] offset:16
	global_load_dwordx4 v[136:139], v80, s[28:29] offset:2048
	global_load_dwordx4 v[140:143], v80, s[28:29] offset:2064
	global_load_dwordx4 v[144:147], v80, s[30:31] offset:0
	global_load_dwordx4 v[148:151], v80, s[30:31] offset:16
	global_load_dwordx4 v[152:155], v80, s[30:31] offset:2048
	global_load_dwordx4 v[156:159], v80, s[30:31] offset:2064
	s_waitcnt vmcnt(40)
; template <bool BF> __device__ __forceinline__ void prep_rows(const float* xp, const float* xs, const bf16* hb, const float* g, const float* MOD, int shoff, int scoff, bf16* U, int gw, int NGW, int lane) {
;     ...
;         for (int r = 0; r < R; ++r) { float t = 0.f;
; #pragma unroll
;             for (int j = 0; j < 4; ++j) t += (v[r][j].x * v[r][j].x + v[r][j].y * v[r][j].y) + (v[r][j].z * v[r][j].z + v[r][j].w * v[r][j].w);
;             s[r] = t; }
; #pragma unroll
;         for (int o = 1; o < 64; o <<= 1) {
; #pragma unroll
;             for (int r = 0; r < R; ++r) s[r] += __shfl_xor(s[r], o); }
; #pragma unroll
;         for (int r = 0; r < R; ++r) { const int m = mb + r * NGW; if (m < MT) {
;             const float rstd = 1.0f / sqrtf(s[r] * (1.0f / DM) + RMS_EPS);
	v_pk_mul_f32 v[240:241], v[0:1], v[0:1]
	v_pk_mul_f32 v[242:243], v[16:17], v[16:17]
	v_pk_mul_f32 v[244:245], v[32:33], v[32:33]
	v_pk_mul_f32 v[246:247], v[48:49], v[48:49]
	v_pk_fma_f32 v[240:241], v[2:3], v[2:3], v[240:241]
	v_pk_fma_f32 v[242:243], v[18:19], v[18:19], v[242:243]
	v_pk_fma_f32 v[244:245], v[34:35], v[34:35], v[244:245]
	v_pk_fma_f32 v[246:247], v[50:51], v[50:51], v[246:247]
	v_pk_fma_f32 v[240:241], v[4:5], v[4:5], v[240:241]
	v_pk_fma_f32 v[242:243], v[20:21], v[20:21], v[242:243]
	v_pk_fma_f32 v[244:245], v[36:37], v[36:37], v[244:245]
	v_pk_fma_f32 v[246:247], v[52:53], v[52:53], v[246:247]
	v_pk_fma_f32 v[240:241], v[6:7], v[6:7], v[240:241]
	v_pk_fma_f32 v[242:243], v[22:23], v[22:23], v[242:243]
	v_pk_fma_f32 v[244:245], v[38:39], v[38:39], v[244:245]
	v_pk_fma_f32 v[246:247], v[54:55], v[54:55], v[246:247]
	v_pk_fma_f32 v[240:241], v[8:9], v[8:9], v[240:241]
	v_pk_fma_f32 v[242:243], v[24:25], v[24:25], v[242:243]
	v_pk_fma_f32 v[244:245], v[40:41], v[40:41], v[244:245]
	v_pk_fma_f32 v[246:247], v[56:57], v[56:57], v[246:247]
	v_pk_fma_f32 v[240:241], v[10:11], v[10:11], v[240:241]
	v_pk_fma_f32 v[242:243], v[26:27], v[26:27], v[242:243]
	v_pk_fma_f32 v[244:245], v[42:43], v[42:43], v[244:245]
	v_pk_fma_f32 v[246:247], v[58:59], v[58:59], v[246:247]
	v_pk_fma_f32 v[240:241], v[12:13], v[12:13], v[240:241]
	v_pk_fma_f32 v[242:243], v[28:29], v[28:29], v[242:243]
	v_pk_fma_f32 v[244:245], v[44:45], v[44:45], v[244:245]
	v_pk_fma_f32 v[246:247], v[60:61], v[60:61], v[246:247]
	v_pk_fma_f32 v[240:241], v[14:15], v[14:15], v[240:241]
	v_pk_fma_f32 v[242:243], v[30:31], v[30:31], v[242:243]
	v_pk_fma_f32 v[244:245], v[46:47], v[46:47], v[244:245]
	v_pk_fma_f32 v[246:247], v[62:63], v[62:63], v[246:247]
	v_add_f32_e32 v224, v240, v241
	v_add_f32_e32 v225, v242, v243
	v_add_f32_e32 v226, v244, v245
	v_add_f32_e32 v227, v246, v247
	ds_bpermute_b32 v228, v83, v224
	ds_bpermute_b32 v229, v83, v225
	ds_bpermute_b32 v230, v83, v226
	ds_bpermute_b32 v231, v83, v227
	s_waitcnt lgkmcnt(0)
	v_add_f32_e32 v224, v224, v228
	v_add_f32_e32 v225, v225, v229
	v_add_f32_e32 v226, v226, v230
	v_add_f32_e32 v227, v227, v231
	ds_bpermute_b32 v228, v84, v224
	ds_bpermute_b32 v229, v84, v225
	ds_bpermute_b32 v230, v84, v226
	ds_bpermute_b32 v231, v84, v227
	s_waitcnt lgkmcnt(0)
	v_add_f32_e32 v224, v224, v228
	v_add_f32_e32 v225, v225, v229
	v_add_f32_e32 v226, v226, v230
	v_add_f32_e32 v227, v227, v231
	ds_bpermute_b32 v228, v85, v224
	ds_bpermute_b32 v229, v85, v225
	ds_bpermute_b32 v230, v85, v226
	ds_bpermute_b32 v231, v85, v227
	s_waitcnt lgkmcnt(0)
	v_add_f32_e32 v224, v224, v228
	v_add_f32_e32 v225, v225, v229
	v_add_f32_e32 v226, v226, v230
	v_add_f32_e32 v227, v227, v231
	ds_bpermute_b32 v228, v86, v224
	ds_bpermute_b32 v229, v86, v225
	ds_bpermute_b32 v230, v86, v226
	ds_bpermute_b32 v231, v86, v227
	s_waitcnt lgkmcnt(0)
	v_add_f32_e32 v224, v224, v228
	v_add_f32_e32 v225, v225, v229
	v_add_f32_e32 v226, v226, v230
	v_add_f32_e32 v227, v227, v231
	ds_bpermute_b32 v228, v87, v224
	ds_bpermute_b32 v229, v87, v225
	ds_bpermute_b32 v230, v87, v226
	ds_bpermute_b32 v231, v87, v227
	s_waitcnt lgkmcnt(0)
	v_add_f32_e32 v224, v224, v228
	v_add_f32_e32 v225, v225, v229
	v_add_f32_e32 v226, v226, v230
	v_add_f32_e32 v227, v227, v231
	ds_bpermute_b32 v228, v88, v224
	ds_bpermute_b32 v229, v88, v225
	ds_bpermute_b32 v230, v88, v226
	ds_bpermute_b32 v231, v88, v227
	s_waitcnt lgkmcnt(0)
	v_add_f32_e32 v224, v224, v228
	v_add_f32_e32 v225, v225, v229
	v_add_f32_e32 v226, v226, v230
	v_add_f32_e32 v227, v227, v231
	v_fmamk_f32 v240, v224, 0x3a800000, v89
	v_mul_f32_e32 v241, 0x4f800000, v240
	v_cmp_gt_f32_e32 vcc, s54, v240
	s_nop 1
	v_cndmask_b32_e32 v247, v240, v241, vcc
	v_sqrt_f32_e32 v242, v247
	s_nop 1
	v_add_u32_e32 v243, -1, v242
	v_add_u32_e32 v244, 1, v242
	v_fma_f32 v245, -v243, v242, v247
	v_fma_f32 v246, -v244, v242, v247
	v_cmp_ge_f32_e64 s[52:53], 0, v245
	s_nop 1
	v_cndmask_b32_e64 v242, v242, v243, s[52:53]
	v_cmp_lt_f32_e64 s[52:53], 0, v246
	s_nop 1
	v_cndmask_b32_e64 v242, v242, v244, s[52:53]
	v_mul_f32_e32 v243, 0x37800000, v242
	v_cndmask_b32_e32 v242, v242, v243, vcc
	v_cmp_class_f32_e32 vcc, v247, v90
	s_nop 1
	v_cndmask_b32_e32 v247, v242, v247, vcc
	v_div_scale_f32 v248, s[52:53], v247, v247, 1.0
	v_rcp_f32_e32 v249, v248
	v_div_scale_f32 v228, vcc, 1.0, v247, 1.0
	s_nop 0
	v_fma_f32 v229, -v248, v249, 1.0
	v_fmac_f32_e32 v249, v229, v249
	v_mul_f32_e32 v230, v228, v249
	v_fma_f32 v229, -v248, v230, v228
	v_fmac_f32_e32 v230, v229, v249
	v_fma_f32 v248, -v248, v230, v228
	v_div_fmas_f32 v248, v248, v249, v230
	v_div_fixup_f32 v232, v248, v247, 1.0
	v_fmamk_f32 v240, v225, 0x3a800000, v89
	v_mul_f32_e32 v241, 0x4f800000, v240
	v_cmp_gt_f32_e32 vcc, s54, v240
	s_nop 1
	v_cndmask_b32_e32 v247, v240, v241, vcc
	v_sqrt_f32_e32 v242, v247
	s_nop 1
	v_add_u32_e32 v243, -1, v242
	v_add_u32_e32 v244, 1, v242
	v_fma_f32 v245, -v243, v242, v247
	v_fma_f32 v246, -v244, v242, v247
	v_cmp_ge_f32_e64 s[52:53], 0, v245
	s_nop 1
	v_cndmask_b32_e64 v242, v242, v243, s[52:53]
	v_cmp_lt_f32_e64 s[52:53], 0, v246
	s_nop 1
	v_cndmask_b32_e64 v242, v242, v244, s[52:53]
	v_mul_f32_e32 v243, 0x37800000, v242
	v_cndmask_b32_e32 v242, v242, v243, vcc
	v_cmp_class_f32_e32 vcc, v247, v90
	s_nop 1
	v_cndmask_b32_e32 v247, v242, v247, vcc
	v_div_scale_f32 v248, s[52:53], v247, v247, 1.0
	v_rcp_f32_e32 v249, v248
	v_div_scale_f32 v228, vcc, 1.0, v247, 1.0
	s_nop 0
	v_fma_f32 v229, -v248, v249, 1.0
	v_fmac_f32_e32 v249, v229, v249
	v_mul_f32_e32 v230, v228, v249
	v_fma_f32 v229, -v248, v230, v228
	v_fmac_f32_e32 v230, v229, v249
; __device__ __forceinline__ unsigned pk2(float lo, float hi) { return pg8::cvt_pk_bf16(lo, hi); }
; template <bool BF> __device__ __forceinline__ void prep_rows(const float* xp, const float* xs, const bf16* hb, const float* g, const float* MOD, int shoff, int scoff, bf16* U, int gw, int NGW, int lane) {
;     ...
;             const float rstd = 1.0f / sqrtf(s[r] * (1.0f / DM) + RMS_EPS);
;             const float* mr = MOD + (size_t)(m < MP ? (m >> 13) : 8 + ((m - MP) >> 12)) * 6144;
; #pragma unroll
;             for (int j = 0; j < 4; ++j) { const int c = 4 * lane + 256 * j;
;                 const f32x4 gg = *(const f32x4*)(g + c), sc = *(const f32x4*)(mr + scoff + c), sh = *(const f32x4*)(mr + shoff + c);
;                 const f32x4 o = v[r][j] * rstd * gg * (sc + 1.0f) + sh; v2u w; w.x = pk2(o.x, o.y); w.y = pk2(o.z, o.w); *(v2u*)(U + (size_t)m * DM + c) = w; } } }
	v_fma_f32 v248, -v248, v230, v228
	v_div_fmas_f32 v248, v248, v249, v230
	v_div_fixup_f32 v234, v248, v247, 1.0
	v_fmamk_f32 v240, v226, 0x3a800000, v89
	v_mul_f32_e32 v241, 0x4f800000, v240
	v_cmp_gt_f32_e32 vcc, s54, v240
	s_nop 1
	v_cndmask_b32_e32 v247, v240, v241, vcc
	v_sqrt_f32_e32 v242, v247
	s_nop 1
	v_add_u32_e32 v243, -1, v242
	v_add_u32_e32 v244, 1, v242
	v_fma_f32 v245, -v243, v242, v247
	v_fma_f32 v246, -v244, v242, v247
	v_cmp_ge_f32_e64 s[52:53], 0, v245
	s_nop 1
	v_cndmask_b32_e64 v242, v242, v243, s[52:53]
	v_cmp_lt_f32_e64 s[52:53], 0, v246
	s_nop 1
	v_cndmask_b32_e64 v242, v242, v244, s[52:53]
	v_mul_f32_e32 v243, 0x37800000, v242
	v_cndmask_b32_e32 v242, v242, v243, vcc
	v_cmp_class_f32_e32 vcc, v247, v90
	s_nop 1
	v_cndmask_b32_e32 v247, v242, v247, vcc
	v_div_scale_f32 v248, s[52:53], v247, v247, 1.0
	v_rcp_f32_e32 v249, v248
	v_div_scale_f32 v228, vcc, 1.0, v247, 1.0
	s_nop 0
	v_fma_f32 v229, -v248, v249, 1.0
	v_fmac_f32_e32 v249, v229, v249
	v_mul_f32_e32 v230, v228, v249
	v_fma_f32 v229, -v248, v230, v228
	v_fmac_f32_e32 v230, v229, v249
	v_fma_f32 v248, -v248, v230, v228
	v_div_fmas_f32 v248, v248, v249, v230
	v_div_fixup_f32 v236, v248, v247, 1.0
	v_fmamk_f32 v240, v227, 0x3a800000, v89
	v_mul_f32_e32 v241, 0x4f800000, v240
	v_cmp_gt_f32_e32 vcc, s54, v240
	s_nop 1
	v_cndmask_b32_e32 v247, v240, v241, vcc
	v_sqrt_f32_e32 v242, v247
	s_nop 1
	v_add_u32_e32 v243, -1, v242
	v_add_u32_e32 v244, 1, v242
	v_fma_f32 v245, -v243, v242, v247
	v_fma_f32 v246, -v244, v242, v247
	v_cmp_ge_f32_e64 s[52:53], 0, v245
	s_nop 1
	v_cndmask_b32_e64 v242, v242, v243, s[52:53]
	v_cmp_lt_f32_e64 s[52:53], 0, v246
	s_nop 1
	v_cndmask_b32_e64 v242, v242, v244, s[52:53]
	v_mul_f32_e32 v243, 0x37800000, v242
	v_cndmask_b32_e32 v242, v242, v243, vcc
	v_cmp_class_f32_e32 vcc, v247, v90
	s_nop 1
	v_cndmask_b32_e32 v247, v242, v247, vcc
	v_div_scale_f32 v248, s[52:53], v247, v247, 1.0
	v_rcp_f32_e32 v249, v248
	v_div_scale_f32 v228, vcc, 1.0, v247, 1.0
	s_nop 0
	v_fma_f32 v229, -v248, v249, 1.0
	v_fmac_f32_e32 v249, v229, v249
	v_mul_f32_e32 v230, v228, v249
	v_fma_f32 v229, -v248, v230, v228
	v_fmac_f32_e32 v230, v229, v249
	v_fma_f32 v248, -v248, v230, v228
	v_div_fmas_f32 v248, v248, v249, v230
	v_div_fixup_f32 v238, v248, v247, 1.0
	s_waitcnt vmcnt(16)
	v_pk_add_f32 v[160:161], v[160:161], 1.0 op_sel_hi:[1,0]
	v_pk_add_f32 v[162:163], v[162:163], 1.0 op_sel_hi:[1,0]
	v_pk_add_f32 v[164:165], v[164:165], 1.0 op_sel_hi:[1,0]
	v_pk_add_f32 v[166:167], v[166:167], 1.0 op_sel_hi:[1,0]
	v_pk_add_f32 v[168:169], v[168:169], 1.0 op_sel_hi:[1,0]
	v_pk_add_f32 v[170:171], v[170:171], 1.0 op_sel_hi:[1,0]
	v_pk_add_f32 v[172:173], v[172:173], 1.0 op_sel_hi:[1,0]
	v_pk_add_f32 v[174:175], v[174:175], 1.0 op_sel_hi:[1,0]
	v_pk_add_f32 v[192:193], v[192:193], 1.0 op_sel_hi:[1,0]
	v_pk_add_f32 v[194:195], v[194:195], 1.0 op_sel_hi:[1,0]
	v_pk_add_f32 v[196:197], v[196:197], 1.0 op_sel_hi:[1,0]
	v_pk_add_f32 v[198:199], v[198:199], 1.0 op_sel_hi:[1,0]
	v_pk_add_f32 v[200:201], v[200:201], 1.0 op_sel_hi:[1,0]
	v_pk_add_f32 v[202:203], v[202:203], 1.0 op_sel_hi:[1,0]
	v_pk_add_f32 v[204:205], v[204:205], 1.0 op_sel_hi:[1,0]
	v_pk_add_f32 v[206:207], v[206:207], 1.0 op_sel_hi:[1,0]
	s_add_u32 s38, s20, 0x8000000
	s_addc_u32 s39, s21, 0
	s_add_u32 s40, s20, 0x8400000
	s_addc_u32 s41, s21, 0
	s_add_u32 s46, s20, 0x8800000
	s_addc_u32 s47, s21, 0
	s_add_u32 s48, s20, 0x8c00000
	s_addc_u32 s49, s21, 0
	v_pk_mul_f32 v[0:1], v[0:1], v[232:233] op_sel_hi:[1,0]
	v_pk_mul_f32 v[2:3], v[2:3], v[232:233] op_sel_hi:[1,0]
	v_pk_mul_f32 v[0:1], v[64:65], v[0:1]
	v_pk_mul_f32 v[2:3], v[66:67], v[2:3]
	v_pk_fma_f32 v[0:1], v[160:161], v[0:1], v[176:177]
	v_pk_fma_f32 v[2:3], v[162:163], v[2:3], v[178:179]
	v_cvt_pk_bf16_f32 v244, v0, v1
	v_cvt_pk_bf16_f32 v245, v2, v3
	v_pk_mul_f32 v[4:5], v[4:5], v[232:233] op_sel_hi:[1,0]
	v_pk_mul_f32 v[6:7], v[6:7], v[232:233] op_sel_hi:[1,0]
	v_pk_mul_f32 v[4:5], v[68:69], v[4:5]
	v_pk_mul_f32 v[6:7], v[70:71], v[6:7]
	v_pk_fma_f32 v[4:5], v[164:165], v[4:5], v[180:181]
	v_pk_fma_f32 v[6:7], v[166:167], v[6:7], v[182:183]
	v_cvt_pk_bf16_f32 v246, v4, v5
	v_cvt_pk_bf16_f32 v247, v6, v7
	global_store_dwordx4 v82, v[244:247], s[38:39] offset:0
	v_pk_mul_f32 v[8:9], v[8:9], v[232:233] op_sel_hi:[1,0]
	v_pk_mul_f32 v[10:11], v[10:11], v[232:233] op_sel_hi:[1,0]
	v_pk_mul_f32 v[8:9], v[72:73], v[8:9]
	v_pk_mul_f32 v[10:11], v[74:75], v[10:11]
	v_pk_fma_f32 v[8:9], v[168:169], v[8:9], v[184:185]
	v_pk_fma_f32 v[10:11], v[170:171], v[10:11], v[186:187]
	v_cvt_pk_bf16_f32 v240, v8, v9
	v_cvt_pk_bf16_f32 v241, v10, v11
	v_pk_mul_f32 v[12:13], v[12:13], v[232:233] op_sel_hi:[1,0]
	v_pk_mul_f32 v[14:15], v[14:15], v[232:233] op_sel_hi:[1,0]
	v_pk_mul_f32 v[12:13], v[76:77], v[12:13]
	v_pk_mul_f32 v[14:15], v[78:79], v[14:15]
	v_pk_fma_f32 v[12:13], v[172:173], v[12:13], v[188:189]
	v_pk_fma_f32 v[14:15], v[174:175], v[14:15], v[190:191]
	v_cvt_pk_bf16_f32 v242, v12, v13
	v_cvt_pk_bf16_f32 v243, v14, v15
	global_store_dwordx4 v82, v[240:243], s[38:39] offset:1024
	v_pk_mul_f32 v[16:17], v[16:17], v[234:235] op_sel_hi:[1,0]
	v_pk_mul_f32 v[18:19], v[18:19], v[234:235] op_sel_hi:[1,0]
	v_pk_mul_f32 v[16:17], v[64:65], v[16:17]
	v_pk_mul_f32 v[18:19], v[66:67], v[18:19]
	v_pk_fma_f32 v[16:17], v[160:161], v[16:17], v[176:177]
	v_pk_fma_f32 v[18:19], v[162:163], v[18:19], v[178:179]
	v_cvt_pk_bf16_f32 v244, v16, v17
	v_cvt_pk_bf16_f32 v245, v18, v19
	v_pk_mul_f32 v[20:21], v[20:21], v[234:235] op_sel_hi:[1,0]
	v_pk_mul_f32 v[22:23], v[22:23], v[234:235] op_sel_hi:[1,0]
	v_pk_mul_f32 v[20:21], v[68:69], v[20:21]
	v_pk_mul_f32 v[22:23], v[70:71], v[22:23]
; __device__ __forceinline__ float bf_lo(unsigned w) { return __uint_as_float(w << 16); }
; __device__ __forceinline__ float bf_hi(unsigned w) { return __uint_as_float(w & 0xffff0000u); }
; __device__ __forceinline__ unsigned pk2(float lo, float hi) { return pg8::cvt_pk_bf16(lo, hi); }
; template <bool BF> __device__ __forceinline__ void prep_rows(const float* xp, const float* xs, const bf16* hb, const float* g, const float* MOD, int shoff, int scoff, bf16* U, int gw, int NGW, int lane) {
;     ...
;         for (int r = 0; r < R; ++r) { const int m = mb + r * NGW; const int mc = m < MT ? m : mb;
; #pragma unroll
;             for (int j = 0; j < 4; ++j) {
;                 if (BF) { const v2u a0 = *(const v2u*)(hb + (size_t)mc * DM + 4 * lane + 256 * j);
;                     v[r][j].x = pg8::bf_lo(a0.x); v[r][j].y = pg8::bf_hi(a0.x); v[r][j].z = pg8::bf_lo(a0.y); v[r][j].w = pg8::bf_hi(a0.y); }
;                 else { const float* xr = mc < MP ? xp + (size_t)mc * DM : xs + (size_t)(mc - MP) * DM; v[r][j] = *(const f32x4*)(xr + 4 * lane + 256 * j); } } }
;     ...
;             for (int j = 0; j < 4; ++j) { const int c = 4 * lane + 256 * j;
;                 const f32x4 gg = *(const f32x4*)(g + c), sc = *(const f32x4*)(mr + scoff + c), sh = *(const f32x4*)(mr + shoff + c);
;                 const f32x4 o = v[r][j] * rstd * gg * (sc + 1.0f) + sh; v2u w; w.x = pk2(o.x, o.y); w.y = pk2(o.z, o.w); *(v2u*)(U + (size_t)m * DM + c) = w; } } }
	v_pk_fma_f32 v[20:21], v[164:165], v[20:21], v[180:181]
	v_pk_fma_f32 v[22:23], v[166:167], v[22:23], v[182:183]
	v_cvt_pk_bf16_f32 v246, v20, v21
	v_cvt_pk_bf16_f32 v247, v22, v23
	global_store_dwordx4 v82, v[244:247], s[40:41] offset:0
	v_pk_mul_f32 v[24:25], v[24:25], v[234:235] op_sel_hi:[1,0]
	v_pk_mul_f32 v[26:27], v[26:27], v[234:235] op_sel_hi:[1,0]
	v_pk_mul_f32 v[24:25], v[72:73], v[24:25]
	v_pk_mul_f32 v[26:27], v[74:75], v[26:27]
	v_pk_fma_f32 v[24:25], v[168:169], v[24:25], v[184:185]
	v_pk_fma_f32 v[26:27], v[170:171], v[26:27], v[186:187]
	v_cvt_pk_bf16_f32 v240, v24, v25
	v_cvt_pk_bf16_f32 v241, v26, v27
	v_pk_mul_f32 v[28:29], v[28:29], v[234:235] op_sel_hi:[1,0]
	v_pk_mul_f32 v[30:31], v[30:31], v[234:235] op_sel_hi:[1,0]
	v_pk_mul_f32 v[28:29], v[76:77], v[28:29]
	v_pk_mul_f32 v[30:31], v[78:79], v[30:31]
	v_pk_fma_f32 v[28:29], v[172:173], v[28:29], v[188:189]
	v_pk_fma_f32 v[30:31], v[174:175], v[30:31], v[190:191]
	v_cvt_pk_bf16_f32 v242, v28, v29
	v_cvt_pk_bf16_f32 v243, v30, v31
	global_store_dwordx4 v82, v[240:243], s[40:41] offset:1024
	v_pk_mul_f32 v[32:33], v[32:33], v[236:237] op_sel_hi:[1,0]
	v_pk_mul_f32 v[34:35], v[34:35], v[236:237] op_sel_hi:[1,0]
	v_pk_mul_f32 v[32:33], v[64:65], v[32:33]
	v_pk_mul_f32 v[34:35], v[66:67], v[34:35]
	v_pk_fma_f32 v[32:33], v[192:193], v[32:33], v[208:209]
	v_pk_fma_f32 v[34:35], v[194:195], v[34:35], v[210:211]
	v_cvt_pk_bf16_f32 v244, v32, v33
	v_cvt_pk_bf16_f32 v245, v34, v35
	v_pk_mul_f32 v[36:37], v[36:37], v[236:237] op_sel_hi:[1,0]
	v_pk_mul_f32 v[38:39], v[38:39], v[236:237] op_sel_hi:[1,0]
	v_pk_mul_f32 v[36:37], v[68:69], v[36:37]
	v_pk_mul_f32 v[38:39], v[70:71], v[38:39]
	v_pk_fma_f32 v[36:37], v[196:197], v[36:37], v[212:213]
	v_pk_fma_f32 v[38:39], v[198:199], v[38:39], v[214:215]
	v_cvt_pk_bf16_f32 v246, v36, v37
	v_cvt_pk_bf16_f32 v247, v38, v39
	global_store_dwordx4 v82, v[244:247], s[46:47] offset:0
	v_pk_mul_f32 v[40:41], v[40:41], v[236:237] op_sel_hi:[1,0]
	v_pk_mul_f32 v[42:43], v[42:43], v[236:237] op_sel_hi:[1,0]
	v_pk_mul_f32 v[40:41], v[72:73], v[40:41]
	v_pk_mul_f32 v[42:43], v[74:75], v[42:43]
	v_pk_fma_f32 v[40:41], v[200:201], v[40:41], v[216:217]
	v_pk_fma_f32 v[42:43], v[202:203], v[42:43], v[218:219]
	v_cvt_pk_bf16_f32 v240, v40, v41
	v_cvt_pk_bf16_f32 v241, v42, v43
	v_pk_mul_f32 v[44:45], v[44:45], v[236:237] op_sel_hi:[1,0]
	v_pk_mul_f32 v[46:47], v[46:47], v[236:237] op_sel_hi:[1,0]
	v_pk_mul_f32 v[44:45], v[76:77], v[44:45]
	v_pk_mul_f32 v[46:47], v[78:79], v[46:47]
	v_pk_fma_f32 v[44:45], v[204:205], v[44:45], v[220:221]
	v_pk_fma_f32 v[46:47], v[206:207], v[46:47], v[222:223]
	v_cvt_pk_bf16_f32 v242, v44, v45
	v_cvt_pk_bf16_f32 v243, v46, v47
	global_store_dwordx4 v82, v[240:243], s[46:47] offset:1024
	v_pk_mul_f32 v[48:49], v[48:49], v[238:239] op_sel_hi:[1,0]
	v_pk_mul_f32 v[50:51], v[50:51], v[238:239] op_sel_hi:[1,0]
	v_pk_mul_f32 v[48:49], v[64:65], v[48:49]
	v_pk_mul_f32 v[50:51], v[66:67], v[50:51]
	v_pk_fma_f32 v[48:49], v[192:193], v[48:49], v[208:209]
	v_pk_fma_f32 v[50:51], v[194:195], v[50:51], v[210:211]
	v_cvt_pk_bf16_f32 v244, v48, v49
	v_cvt_pk_bf16_f32 v245, v50, v51
	v_pk_mul_f32 v[52:53], v[52:53], v[238:239] op_sel_hi:[1,0]
	v_pk_mul_f32 v[54:55], v[54:55], v[238:239] op_sel_hi:[1,0]
	v_pk_mul_f32 v[52:53], v[68:69], v[52:53]
	v_pk_mul_f32 v[54:55], v[70:71], v[54:55]
	v_pk_fma_f32 v[52:53], v[196:197], v[52:53], v[212:213]
	v_pk_fma_f32 v[54:55], v[198:199], v[54:55], v[214:215]
	v_cvt_pk_bf16_f32 v246, v52, v53
	v_cvt_pk_bf16_f32 v247, v54, v55
	global_store_dwordx4 v82, v[244:247], s[48:49] offset:0
	v_pk_mul_f32 v[56:57], v[56:57], v[238:239] op_sel_hi:[1,0]
	v_pk_mul_f32 v[58:59], v[58:59], v[238:239] op_sel_hi:[1,0]
	v_pk_mul_f32 v[56:57], v[72:73], v[56:57]
	v_pk_mul_f32 v[58:59], v[74:75], v[58:59]
	v_pk_fma_f32 v[56:57], v[200:201], v[56:57], v[216:217]
	v_pk_fma_f32 v[58:59], v[202:203], v[58:59], v[218:219]
	v_cvt_pk_bf16_f32 v240, v56, v57
	v_cvt_pk_bf16_f32 v241, v58, v59
	v_pk_mul_f32 v[60:61], v[60:61], v[238:239] op_sel_hi:[1,0]
	v_pk_mul_f32 v[62:63], v[62:63], v[238:239] op_sel_hi:[1,0]
	v_pk_mul_f32 v[60:61], v[76:77], v[60:61]
	v_pk_mul_f32 v[62:63], v[78:79], v[62:63]
	v_pk_fma_f32 v[60:61], v[204:205], v[60:61], v[220:221]
	v_pk_fma_f32 v[62:63], v[206:207], v[62:63], v[222:223]
	v_cvt_pk_bf16_f32 v242, v60, v61
	v_cvt_pk_bf16_f32 v243, v62, v63
	global_store_dwordx4 v82, v[240:243], s[48:49] offset:1024
	s_add_u32 s34, s8, 0x3c000
	s_addc_u32 s35, s9, 0
	s_add_u32 s36, s8, 0x42000
	s_addc_u32 s37, s9, 0
	global_load_dwordx4 v[176:179], v80, s[34:35] offset:0
	global_load_dwordx4 v[180:183], v80, s[34:35] offset:16
	global_load_dwordx4 v[184:187], v80, s[34:35] offset:2048
	global_load_dwordx4 v[188:191], v80, s[34:35] offset:2064
	global_load_dwordx4 v[160:163], v81, s[34:35] offset:0
	global_load_dwordx4 v[164:167], v81, s[34:35] offset:16
	global_load_dwordx4 v[168:171], v81, s[34:35] offset:2048
	global_load_dwordx4 v[172:175], v81, s[34:35] offset:2064
	global_load_dwordx4 v[208:211], v80, s[36:37] offset:0
	global_load_dwordx4 v[212:215], v80, s[36:37] offset:16
	global_load_dwordx4 v[216:219], v80, s[36:37] offset:2048
	global_load_dwordx4 v[220:223], v80, s[36:37] offset:2064
	global_load_dwordx4 v[192:195], v81, s[36:37] offset:0
	global_load_dwordx4 v[196:199], v81, s[36:37] offset:16
	global_load_dwordx4 v[200:203], v81, s[36:37] offset:2048
	global_load_dwordx4 v[204:207], v81, s[36:37] offset:2064
	s_add_u32 s24, s18, 0x4000000
	s_addc_u32 s25, s19, 0
	s_add_u32 s26, s18, 0x4800000
	s_addc_u32 s27, s19, 0
	s_add_u32 s28, s18, 0x5000000
	s_addc_u32 s29, s19, 0
	s_add_u32 s30, s18, 0x5800000
	s_addc_u32 s31, s19, 0
	global_load_dwordx4 v[0:3], v80, s[24:25] offset:0
	global_load_dwordx4 v[4:7], v80, s[24:25] offset:16
	global_load_dwordx4 v[8:11], v80, s[24:25] offset:2048
	global_load_dwordx4 v[12:15], v80, s[24:25] offset:2064
	global_load_dwordx4 v[16:19], v80, s[26:27] offset:0
	global_load_dwordx4 v[20:23], v80, s[26:27] offset:16
	global_load_dwordx4 v[24:27], v80, s[26:27] offset:2048
	global_load_dwordx4 v[28:31], v80, s[26:27] offset:2064
	global_load_dwordx4 v[32:35], v80, s[28:29] offset:0
	global_load_dwordx4 v[36:39], v80, s[28:29] offset:16
	global_load_dwordx4 v[40:43], v80, s[28:29] offset:2048
	global_load_dwordx4 v[44:47], v80, s[28:29] offset:2064
	global_load_dwordx4 v[48:51], v80, s[30:31] offset:0
	global_load_dwordx4 v[52:55], v80, s[30:31] offset:16
	global_load_dwordx4 v[56:59], v80, s[30:31] offset:2048
	global_load_dwordx4 v[60:63], v80, s[30:31] offset:2064
	s_waitcnt vmcnt(40)
; template <bool BF> __device__ __forceinline__ void prep_rows(const float* xp, const float* xs, const bf16* hb, const float* g, const float* MOD, int shoff, int scoff, bf16* U, int gw, int NGW, int lane) {
;     ...
;         for (int r = 0; r < R; ++r) { float t = 0.f;
; #pragma unroll
;             for (int j = 0; j < 4; ++j) t += (v[r][j].x * v[r][j].x + v[r][j].y * v[r][j].y) + (v[r][j].z * v[r][j].z + v[r][j].w * v[r][j].w);
;             s[r] = t; }
; #pragma unroll
;         for (int o = 1; o < 64; o <<= 1) {
; #pragma unroll
;             for (int r = 0; r < R; ++r) s[r] += __shfl_xor(s[r], o); }
; #pragma unroll
;         for (int r = 0; r < R; ++r) { const int m = mb + r * NGW; if (m < MT) {
;             const float rstd = 1.0f / sqrtf(s[r] * (1.0f / DM) + RMS_EPS);
	v_pk_mul_f32 v[240:241], v[96:97], v[96:97]
	v_pk_mul_f32 v[242:243], v[112:113], v[112:113]
	v_pk_mul_f32 v[244:245], v[128:129], v[128:129]
	v_pk_mul_f32 v[246:247], v[144:145], v[144:145]
	v_pk_fma_f32 v[240:241], v[98:99], v[98:99], v[240:241]
	v_pk_fma_f32 v[242:243], v[114:115], v[114:115], v[242:243]
	v_pk_fma_f32 v[244:245], v[130:131], v[130:131], v[244:245]
	v_pk_fma_f32 v[246:247], v[146:147], v[146:147], v[246:247]
	v_pk_fma_f32 v[240:241], v[100:101], v[100:101], v[240:241]
	v_pk_fma_f32 v[242:243], v[116:117], v[116:117], v[242:243]
	v_pk_fma_f32 v[244:245], v[132:133], v[132:133], v[244:245]
	v_pk_fma_f32 v[246:247], v[148:149], v[148:149], v[246:247]
	v_pk_fma_f32 v[240:241], v[102:103], v[102:103], v[240:241]
	v_pk_fma_f32 v[242:243], v[118:119], v[118:119], v[242:243]
	v_pk_fma_f32 v[244:245], v[134:135], v[134:135], v[244:245]
	v_pk_fma_f32 v[246:247], v[150:151], v[150:151], v[246:247]
	v_pk_fma_f32 v[240:241], v[104:105], v[104:105], v[240:241]
	v_pk_fma_f32 v[242:243], v[120:121], v[120:121], v[242:243]
	v_pk_fma_f32 v[244:245], v[136:137], v[136:137], v[244:245]
	v_pk_fma_f32 v[246:247], v[152:153], v[152:153], v[246:247]
	v_pk_fma_f32 v[240:241], v[106:107], v[106:107], v[240:241]
	v_pk_fma_f32 v[242:243], v[122:123], v[122:123], v[242:243]
	v_pk_fma_f32 v[244:245], v[138:139], v[138:139], v[244:245]
	v_pk_fma_f32 v[246:247], v[154:155], v[154:155], v[246:247]
	v_pk_fma_f32 v[240:241], v[108:109], v[108:109], v[240:241]
	v_pk_fma_f32 v[242:243], v[124:125], v[124:125], v[242:243]
	v_pk_fma_f32 v[244:245], v[140:141], v[140:141], v[244:245]
	v_pk_fma_f32 v[246:247], v[156:157], v[156:157], v[246:247]
	v_pk_fma_f32 v[240:241], v[110:111], v[110:111], v[240:241]
	v_pk_fma_f32 v[242:243], v[126:127], v[126:127], v[242:243]
	v_pk_fma_f32 v[244:245], v[142:143], v[142:143], v[244:245]
	v_pk_fma_f32 v[246:247], v[158:159], v[158:159], v[246:247]
	v_add_f32_e32 v224, v240, v241
	v_add_f32_e32 v225, v242, v243
	v_add_f32_e32 v226, v244, v245
	v_add_f32_e32 v227, v246, v247
	ds_bpermute_b32 v228, v83, v224
	ds_bpermute_b32 v229, v83, v225
	ds_bpermute_b32 v230, v83, v226
	ds_bpermute_b32 v231, v83, v227
	s_waitcnt lgkmcnt(0)
	v_add_f32_e32 v224, v224, v228
	v_add_f32_e32 v225, v225, v229
	v_add_f32_e32 v226, v226, v230
	v_add_f32_e32 v227, v227, v231
	ds_bpermute_b32 v228, v84, v224
	ds_bpermute_b32 v229, v84, v225
	ds_bpermute_b32 v230, v84, v226
	ds_bpermute_b32 v231, v84, v227
	s_waitcnt lgkmcnt(0)
	v_add_f32_e32 v224, v224, v228
	v_add_f32_e32 v225, v225, v229
	v_add_f32_e32 v226, v226, v230
	v_add_f32_e32 v227, v227, v231
	ds_bpermute_b32 v228, v85, v224
	ds_bpermute_b32 v229, v85, v225
	ds_bpermute_b32 v230, v85, v226
	ds_bpermute_b32 v231, v85, v227
	s_waitcnt lgkmcnt(0)
	v_add_f32_e32 v224, v224, v228
	v_add_f32_e32 v225, v225, v229
	v_add_f32_e32 v226, v226, v230
	v_add_f32_e32 v227, v227, v231
	ds_bpermute_b32 v228, v86, v224
	ds_bpermute_b32 v229, v86, v225
	ds_bpermute_b32 v230, v86, v226
	ds_bpermute_b32 v231, v86, v227
	s_waitcnt lgkmcnt(0)
	v_add_f32_e32 v224, v224, v228
	v_add_f32_e32 v225, v225, v229
	v_add_f32_e32 v226, v226, v230
	v_add_f32_e32 v227, v227, v231
	ds_bpermute_b32 v228, v87, v224
	ds_bpermute_b32 v229, v87, v225
	ds_bpermute_b32 v230, v87, v226
	ds_bpermute_b32 v231, v87, v227
	s_waitcnt lgkmcnt(0)
	v_add_f32_e32 v224, v224, v228
	v_add_f32_e32 v225, v225, v229
	v_add_f32_e32 v226, v226, v230
	v_add_f32_e32 v227, v227, v231
	ds_bpermute_b32 v228, v88, v224
	ds_bpermute_b32 v229, v88, v225
	ds_bpermute_b32 v230, v88, v226
	ds_bpermute_b32 v231, v88, v227
	s_waitcnt lgkmcnt(0)
	v_add_f32_e32 v224, v224, v228
	v_add_f32_e32 v225, v225, v229
	v_add_f32_e32 v226, v226, v230
	v_add_f32_e32 v227, v227, v231
	v_fmamk_f32 v240, v224, 0x3a800000, v89
	v_mul_f32_e32 v241, 0x4f800000, v240
	v_cmp_gt_f32_e32 vcc, s54, v240
	s_nop 1
	v_cndmask_b32_e32 v247, v240, v241, vcc
	v_sqrt_f32_e32 v242, v247
	s_nop 1
	v_add_u32_e32 v243, -1, v242
	v_add_u32_e32 v244, 1, v242
	v_fma_f32 v245, -v243, v242, v247
	v_fma_f32 v246, -v244, v242, v247
	v_cmp_ge_f32_e64 s[52:53], 0, v245
	s_nop 1
	v_cndmask_b32_e64 v242, v242, v243, s[52:53]
	v_cmp_lt_f32_e64 s[52:53], 0, v246
	s_nop 1
	v_cndmask_b32_e64 v242, v242, v244, s[52:53]
	v_mul_f32_e32 v243, 0x37800000, v242
	v_cndmask_b32_e32 v242, v242, v243, vcc
	v_cmp_class_f32_e32 vcc, v247, v90
	s_nop 1
	v_cndmask_b32_e32 v247, v242, v247, vcc
	v_div_scale_f32 v248, s[52:53], v247, v247, 1.0
	v_rcp_f32_e32 v249, v248
	v_div_scale_f32 v228, vcc, 1.0, v247, 1.0
	s_nop 0
	v_fma_f32 v229, -v248, v249, 1.0
	v_fmac_f32_e32 v249, v229, v249
	v_mul_f32_e32 v230, v228, v249
	v_fma_f32 v229, -v248, v230, v228
	v_fmac_f32_e32 v230, v229, v249
	v_fma_f32 v248, -v248, v230, v228
	v_div_fmas_f32 v248, v248, v249, v230
	v_div_fixup_f32 v232, v248, v247, 1.0
	v_fmamk_f32 v240, v225, 0x3a800000, v89
	v_mul_f32_e32 v241, 0x4f800000, v240
	v_cmp_gt_f32_e32 vcc, s54, v240
	s_nop 1
	v_cndmask_b32_e32 v247, v240, v241, vcc
	v_sqrt_f32_e32 v242, v247
	s_nop 1
	v_add_u32_e32 v243, -1, v242
	v_add_u32_e32 v244, 1, v242
	v_fma_f32 v245, -v243, v242, v247
	v_fma_f32 v246, -v244, v242, v247
	v_cmp_ge_f32_e64 s[52:53], 0, v245
	s_nop 1
	v_cndmask_b32_e64 v242, v242, v243, s[52:53]
	v_cmp_lt_f32_e64 s[52:53], 0, v246
	s_nop 1
	v_cndmask_b32_e64 v242, v242, v244, s[52:53]
	v_mul_f32_e32 v243, 0x37800000, v242
	v_cndmask_b32_e32 v242, v242, v243, vcc
	v_cmp_class_f32_e32 vcc, v247, v90
	s_nop 1
	v_cndmask_b32_e32 v247, v242, v247, vcc
	v_div_scale_f32 v248, s[52:53], v247, v247, 1.0
	v_rcp_f32_e32 v249, v248
	v_div_scale_f32 v228, vcc, 1.0, v247, 1.0
	s_nop 0
	v_fma_f32 v229, -v248, v249, 1.0
; __device__ __forceinline__ unsigned pk2(float lo, float hi) { return pg8::cvt_pk_bf16(lo, hi); }
; template <bool BF> __device__ __forceinline__ void prep_rows(const float* xp, const float* xs, const bf16* hb, const float* g, const float* MOD, int shoff, int scoff, bf16* U, int gw, int NGW, int lane) {
;     ...
;             const float rstd = 1.0f / sqrtf(s[r] * (1.0f / DM) + RMS_EPS);
;             const float* mr = MOD + (size_t)(m < MP ? (m >> 13) : 8 + ((m - MP) >> 12)) * 6144;
; #pragma unroll
;             for (int j = 0; j < 4; ++j) { const int c = 4 * lane + 256 * j;
;                 const f32x4 gg = *(const f32x4*)(g + c), sc = *(const f32x4*)(mr + scoff + c), sh = *(const f32x4*)(mr + shoff + c);
;                 const f32x4 o = v[r][j] * rstd * gg * (sc + 1.0f) + sh; v2u w; w.x = pk2(o.x, o.y); w.y = pk2(o.z, o.w); *(v2u*)(U + (size_t)m * DM + c) = w; } } }
	v_fmac_f32_e32 v249, v229, v249
	v_mul_f32_e32 v230, v228, v249
	v_fma_f32 v229, -v248, v230, v228
	v_fmac_f32_e32 v230, v229, v249
	v_fma_f32 v248, -v248, v230, v228
	v_div_fmas_f32 v248, v248, v249, v230
	v_div_fixup_f32 v234, v248, v247, 1.0
	v_fmamk_f32 v240, v226, 0x3a800000, v89
	v_mul_f32_e32 v241, 0x4f800000, v240
	v_cmp_gt_f32_e32 vcc, s54, v240
	s_nop 1
	v_cndmask_b32_e32 v247, v240, v241, vcc
	v_sqrt_f32_e32 v242, v247
	s_nop 1
	v_add_u32_e32 v243, -1, v242
	v_add_u32_e32 v244, 1, v242
	v_fma_f32 v245, -v243, v242, v247
	v_fma_f32 v246, -v244, v242, v247
	v_cmp_ge_f32_e64 s[52:53], 0, v245
	s_nop 1
	v_cndmask_b32_e64 v242, v242, v243, s[52:53]
	v_cmp_lt_f32_e64 s[52:53], 0, v246
	s_nop 1
	v_cndmask_b32_e64 v242, v242, v244, s[52:53]
	v_mul_f32_e32 v243, 0x37800000, v242
	v_cndmask_b32_e32 v242, v242, v243, vcc
	v_cmp_class_f32_e32 vcc, v247, v90
	s_nop 1
	v_cndmask_b32_e32 v247, v242, v247, vcc
	v_div_scale_f32 v248, s[52:53], v247, v247, 1.0
	v_rcp_f32_e32 v249, v248
	v_div_scale_f32 v228, vcc, 1.0, v247, 1.0
	s_nop 0
	v_fma_f32 v229, -v248, v249, 1.0
	v_fmac_f32_e32 v249, v229, v249
	v_mul_f32_e32 v230, v228, v249
	v_fma_f32 v229, -v248, v230, v228
	v_fmac_f32_e32 v230, v229, v249
	v_fma_f32 v248, -v248, v230, v228
	v_div_fmas_f32 v248, v248, v249, v230
	v_div_fixup_f32 v236, v248, v247, 1.0
	v_fmamk_f32 v240, v227, 0x3a800000, v89
	v_mul_f32_e32 v241, 0x4f800000, v240
	v_cmp_gt_f32_e32 vcc, s54, v240
	s_nop 1
	v_cndmask_b32_e32 v247, v240, v241, vcc
	v_sqrt_f32_e32 v242, v247
	s_nop 1
	v_add_u32_e32 v243, -1, v242
	v_add_u32_e32 v244, 1, v242
	v_fma_f32 v245, -v243, v242, v247
	v_fma_f32 v246, -v244, v242, v247
	v_cmp_ge_f32_e64 s[52:53], 0, v245
	s_nop 1
	v_cndmask_b32_e64 v242, v242, v243, s[52:53]
	v_cmp_lt_f32_e64 s[52:53], 0, v246
	s_nop 1
	v_cndmask_b32_e64 v242, v242, v244, s[52:53]
	v_mul_f32_e32 v243, 0x37800000, v242
	v_cndmask_b32_e32 v242, v242, v243, vcc
	v_cmp_class_f32_e32 vcc, v247, v90
	s_nop 1
	v_cndmask_b32_e32 v247, v242, v247, vcc
	v_div_scale_f32 v248, s[52:53], v247, v247, 1.0
	v_rcp_f32_e32 v249, v248
	v_div_scale_f32 v228, vcc, 1.0, v247, 1.0
	s_nop 0
	v_fma_f32 v229, -v248, v249, 1.0
	v_fmac_f32_e32 v249, v229, v249
	v_mul_f32_e32 v230, v228, v249
	v_fma_f32 v229, -v248, v230, v228
	v_fmac_f32_e32 v230, v229, v249
	v_fma_f32 v248, -v248, v230, v228
	v_div_fmas_f32 v248, v248, v249, v230
	v_div_fixup_f32 v238, v248, v247, 1.0
	s_waitcnt vmcnt(16)
	v_pk_add_f32 v[160:161], v[160:161], 1.0 op_sel_hi:[1,0]
	v_pk_add_f32 v[162:163], v[162:163], 1.0 op_sel_hi:[1,0]
	v_pk_add_f32 v[164:165], v[164:165], 1.0 op_sel_hi:[1,0]
	v_pk_add_f32 v[166:167], v[166:167], 1.0 op_sel_hi:[1,0]
	v_pk_add_f32 v[168:169], v[168:169], 1.0 op_sel_hi:[1,0]
	v_pk_add_f32 v[170:171], v[170:171], 1.0 op_sel_hi:[1,0]
	v_pk_add_f32 v[172:173], v[172:173], 1.0 op_sel_hi:[1,0]
	v_pk_add_f32 v[174:175], v[174:175], 1.0 op_sel_hi:[1,0]
	v_pk_add_f32 v[192:193], v[192:193], 1.0 op_sel_hi:[1,0]
	v_pk_add_f32 v[194:195], v[194:195], 1.0 op_sel_hi:[1,0]
	v_pk_add_f32 v[196:197], v[196:197], 1.0 op_sel_hi:[1,0]
	v_pk_add_f32 v[198:199], v[198:199], 1.0 op_sel_hi:[1,0]
	v_pk_add_f32 v[200:201], v[200:201], 1.0 op_sel_hi:[1,0]
	v_pk_add_f32 v[202:203], v[202:203], 1.0 op_sel_hi:[1,0]
	v_pk_add_f32 v[204:205], v[204:205], 1.0 op_sel_hi:[1,0]
	v_pk_add_f32 v[206:207], v[206:207], 1.0 op_sel_hi:[1,0]
	s_add_u32 s38, s20, 0x9000000
	s_addc_u32 s39, s21, 0
	s_add_u32 s40, s20, 0x9400000
	s_addc_u32 s41, s21, 0
	s_add_u32 s46, s20, 0x9800000
	s_addc_u32 s47, s21, 0
	s_add_u32 s48, s20, 0x9c00000
	s_addc_u32 s49, s21, 0
	v_pk_mul_f32 v[96:97], v[96:97], v[232:233] op_sel_hi:[1,0]
	v_pk_mul_f32 v[98:99], v[98:99], v[232:233] op_sel_hi:[1,0]
	v_pk_mul_f32 v[96:97], v[64:65], v[96:97]
	v_pk_mul_f32 v[98:99], v[66:67], v[98:99]
	v_pk_fma_f32 v[96:97], v[160:161], v[96:97], v[176:177]
	v_pk_fma_f32 v[98:99], v[162:163], v[98:99], v[178:179]
	v_cvt_pk_bf16_f32 v244, v96, v97
	v_cvt_pk_bf16_f32 v245, v98, v99
	v_pk_mul_f32 v[100:101], v[100:101], v[232:233] op_sel_hi:[1,0]
	v_pk_mul_f32 v[102:103], v[102:103], v[232:233] op_sel_hi:[1,0]
	v_pk_mul_f32 v[100:101], v[68:69], v[100:101]
	v_pk_mul_f32 v[102:103], v[70:71], v[102:103]
	v_pk_fma_f32 v[100:101], v[164:165], v[100:101], v[180:181]
	v_pk_fma_f32 v[102:103], v[166:167], v[102:103], v[182:183]
	v_cvt_pk_bf16_f32 v246, v100, v101
	v_cvt_pk_bf16_f32 v247, v102, v103
	global_store_dwordx4 v82, v[244:247], s[38:39] offset:0
	v_pk_mul_f32 v[104:105], v[104:105], v[232:233] op_sel_hi:[1,0]
	v_pk_mul_f32 v[106:107], v[106:107], v[232:233] op_sel_hi:[1,0]
	v_pk_mul_f32 v[104:105], v[72:73], v[104:105]
	v_pk_mul_f32 v[106:107], v[74:75], v[106:107]
	v_pk_fma_f32 v[104:105], v[168:169], v[104:105], v[184:185]
	v_pk_fma_f32 v[106:107], v[170:171], v[106:107], v[186:187]
	v_cvt_pk_bf16_f32 v240, v104, v105
	v_cvt_pk_bf16_f32 v241, v106, v107
	v_pk_mul_f32 v[108:109], v[108:109], v[232:233] op_sel_hi:[1,0]
	v_pk_mul_f32 v[110:111], v[110:111], v[232:233] op_sel_hi:[1,0]
	v_pk_mul_f32 v[108:109], v[76:77], v[108:109]
	v_pk_mul_f32 v[110:111], v[78:79], v[110:111]
	v_pk_fma_f32 v[108:109], v[172:173], v[108:109], v[188:189]
	v_pk_fma_f32 v[110:111], v[174:175], v[110:111], v[190:191]
	v_cvt_pk_bf16_f32 v242, v108, v109
	v_cvt_pk_bf16_f32 v243, v110, v111
	global_store_dwordx4 v82, v[240:243], s[38:39] offset:1024
	v_pk_mul_f32 v[112:113], v[112:113], v[234:235] op_sel_hi:[1,0]
	v_pk_mul_f32 v[114:115], v[114:115], v[234:235] op_sel_hi:[1,0]
	v_pk_mul_f32 v[112:113], v[64:65], v[112:113]
	v_pk_mul_f32 v[114:115], v[66:67], v[114:115]
	v_pk_fma_f32 v[112:113], v[160:161], v[112:113], v[176:177]
; __device__ __forceinline__ float bf_lo(unsigned w) { return __uint_as_float(w << 16); }
; __device__ __forceinline__ float bf_hi(unsigned w) { return __uint_as_float(w & 0xffff0000u); }
; __device__ __forceinline__ unsigned pk2(float lo, float hi) { return pg8::cvt_pk_bf16(lo, hi); }
; template <bool BF> __device__ __forceinline__ void prep_rows(const float* xp, const float* xs, const bf16* hb, const float* g, const float* MOD, int shoff, int scoff, bf16* U, int gw, int NGW, int lane) {
;     ...
;         for (int r = 0; r < R; ++r) { const int m = mb + r * NGW; const int mc = m < MT ? m : mb;
; #pragma unroll
;             for (int j = 0; j < 4; ++j) {
;                 if (BF) { const v2u a0 = *(const v2u*)(hb + (size_t)mc * DM + 4 * lane + 256 * j);
;                     v[r][j].x = pg8::bf_lo(a0.x); v[r][j].y = pg8::bf_hi(a0.x); v[r][j].z = pg8::bf_lo(a0.y); v[r][j].w = pg8::bf_hi(a0.y); }
;                 else { const float* xr = mc < MP ? xp + (size_t)mc * DM : xs + (size_t)(mc - MP) * DM; v[r][j] = *(const f32x4*)(xr + 4 * lane + 256 * j); } } }
;     ...
;             for (int j = 0; j < 4; ++j) { const int c = 4 * lane + 256 * j;
;                 const f32x4 gg = *(const f32x4*)(g + c), sc = *(const f32x4*)(mr + scoff + c), sh = *(const f32x4*)(mr + shoff + c);
;                 const f32x4 o = v[r][j] * rstd * gg * (sc + 1.0f) + sh; v2u w; w.x = pk2(o.x, o.y); w.y = pk2(o.z, o.w); *(v2u*)(U + (size_t)m * DM + c) = w; } } }
	v_pk_fma_f32 v[114:115], v[162:163], v[114:115], v[178:179]
	v_cvt_pk_bf16_f32 v244, v112, v113
	v_cvt_pk_bf16_f32 v245, v114, v115
	v_pk_mul_f32 v[116:117], v[116:117], v[234:235] op_sel_hi:[1,0]
	v_pk_mul_f32 v[118:119], v[118:119], v[234:235] op_sel_hi:[1,0]
	v_pk_mul_f32 v[116:117], v[68:69], v[116:117]
	v_pk_mul_f32 v[118:119], v[70:71], v[118:119]
	v_pk_fma_f32 v[116:117], v[164:165], v[116:117], v[180:181]
	v_pk_fma_f32 v[118:119], v[166:167], v[118:119], v[182:183]
	v_cvt_pk_bf16_f32 v246, v116, v117
	v_cvt_pk_bf16_f32 v247, v118, v119
	global_store_dwordx4 v82, v[244:247], s[40:41] offset:0
	v_pk_mul_f32 v[120:121], v[120:121], v[234:235] op_sel_hi:[1,0]
	v_pk_mul_f32 v[122:123], v[122:123], v[234:235] op_sel_hi:[1,0]
	v_pk_mul_f32 v[120:121], v[72:73], v[120:121]
	v_pk_mul_f32 v[122:123], v[74:75], v[122:123]
	v_pk_fma_f32 v[120:121], v[168:169], v[120:121], v[184:185]
	v_pk_fma_f32 v[122:123], v[170:171], v[122:123], v[186:187]
	v_cvt_pk_bf16_f32 v240, v120, v121
	v_cvt_pk_bf16_f32 v241, v122, v123
	v_pk_mul_f32 v[124:125], v[124:125], v[234:235] op_sel_hi:[1,0]
	v_pk_mul_f32 v[126:127], v[126:127], v[234:235] op_sel_hi:[1,0]
	v_pk_mul_f32 v[124:125], v[76:77], v[124:125]
	v_pk_mul_f32 v[126:127], v[78:79], v[126:127]
	v_pk_fma_f32 v[124:125], v[172:173], v[124:125], v[188:189]
	v_pk_fma_f32 v[126:127], v[174:175], v[126:127], v[190:191]
	v_cvt_pk_bf16_f32 v242, v124, v125
	v_cvt_pk_bf16_f32 v243, v126, v127
	global_store_dwordx4 v82, v[240:243], s[40:41] offset:1024
	v_pk_mul_f32 v[128:129], v[128:129], v[236:237] op_sel_hi:[1,0]
	v_pk_mul_f32 v[130:131], v[130:131], v[236:237] op_sel_hi:[1,0]
	v_pk_mul_f32 v[128:129], v[64:65], v[128:129]
	v_pk_mul_f32 v[130:131], v[66:67], v[130:131]
	v_pk_fma_f32 v[128:129], v[192:193], v[128:129], v[208:209]
	v_pk_fma_f32 v[130:131], v[194:195], v[130:131], v[210:211]
	v_cvt_pk_bf16_f32 v244, v128, v129
	v_cvt_pk_bf16_f32 v245, v130, v131
	v_pk_mul_f32 v[132:133], v[132:133], v[236:237] op_sel_hi:[1,0]
	v_pk_mul_f32 v[134:135], v[134:135], v[236:237] op_sel_hi:[1,0]
	v_pk_mul_f32 v[132:133], v[68:69], v[132:133]
	v_pk_mul_f32 v[134:135], v[70:71], v[134:135]
	v_pk_fma_f32 v[132:133], v[196:197], v[132:133], v[212:213]
	v_pk_fma_f32 v[134:135], v[198:199], v[134:135], v[214:215]
	v_cvt_pk_bf16_f32 v246, v132, v133
	v_cvt_pk_bf16_f32 v247, v134, v135
	global_store_dwordx4 v82, v[244:247], s[46:47] offset:0
	v_pk_mul_f32 v[136:137], v[136:137], v[236:237] op_sel_hi:[1,0]
	v_pk_mul_f32 v[138:139], v[138:139], v[236:237] op_sel_hi:[1,0]
	v_pk_mul_f32 v[136:137], v[72:73], v[136:137]
	v_pk_mul_f32 v[138:139], v[74:75], v[138:139]
	v_pk_fma_f32 v[136:137], v[200:201], v[136:137], v[216:217]
	v_pk_fma_f32 v[138:139], v[202:203], v[138:139], v[218:219]
	v_cvt_pk_bf16_f32 v240, v136, v137
	v_cvt_pk_bf16_f32 v241, v138, v139
	v_pk_mul_f32 v[140:141], v[140:141], v[236:237] op_sel_hi:[1,0]
	v_pk_mul_f32 v[142:143], v[142:143], v[236:237] op_sel_hi:[1,0]
	v_pk_mul_f32 v[140:141], v[76:77], v[140:141]
	v_pk_mul_f32 v[142:143], v[78:79], v[142:143]
	v_pk_fma_f32 v[140:141], v[204:205], v[140:141], v[220:221]
	v_pk_fma_f32 v[142:143], v[206:207], v[142:143], v[222:223]
	v_cvt_pk_bf16_f32 v242, v140, v141
	v_cvt_pk_bf16_f32 v243, v142, v143
	global_store_dwordx4 v82, v[240:243], s[46:47] offset:1024
	v_pk_mul_f32 v[144:145], v[144:145], v[238:239] op_sel_hi:[1,0]
	v_pk_mul_f32 v[146:147], v[146:147], v[238:239] op_sel_hi:[1,0]
	v_pk_mul_f32 v[144:145], v[64:65], v[144:145]
	v_pk_mul_f32 v[146:147], v[66:67], v[146:147]
	v_pk_fma_f32 v[144:145], v[192:193], v[144:145], v[208:209]
	v_pk_fma_f32 v[146:147], v[194:195], v[146:147], v[210:211]
	v_cvt_pk_bf16_f32 v244, v144, v145
	v_cvt_pk_bf16_f32 v245, v146, v147
	v_pk_mul_f32 v[148:149], v[148:149], v[238:239] op_sel_hi:[1,0]
	v_pk_mul_f32 v[150:151], v[150:151], v[238:239] op_sel_hi:[1,0]
	v_pk_mul_f32 v[148:149], v[68:69], v[148:149]
	v_pk_mul_f32 v[150:151], v[70:71], v[150:151]
	v_pk_fma_f32 v[148:149], v[196:197], v[148:149], v[212:213]
	v_pk_fma_f32 v[150:151], v[198:199], v[150:151], v[214:215]
	v_cvt_pk_bf16_f32 v246, v148, v149
	v_cvt_pk_bf16_f32 v247, v150, v151
	global_store_dwordx4 v82, v[244:247], s[48:49] offset:0
	v_pk_mul_f32 v[152:153], v[152:153], v[238:239] op_sel_hi:[1,0]
	v_pk_mul_f32 v[154:155], v[154:155], v[238:239] op_sel_hi:[1,0]
	v_pk_mul_f32 v[152:153], v[72:73], v[152:153]
	v_pk_mul_f32 v[154:155], v[74:75], v[154:155]
	v_pk_fma_f32 v[152:153], v[200:201], v[152:153], v[216:217]
	v_pk_fma_f32 v[154:155], v[202:203], v[154:155], v[218:219]
	v_cvt_pk_bf16_f32 v240, v152, v153
	v_cvt_pk_bf16_f32 v241, v154, v155
	v_pk_mul_f32 v[156:157], v[156:157], v[238:239] op_sel_hi:[1,0]
	v_pk_mul_f32 v[158:159], v[158:159], v[238:239] op_sel_hi:[1,0]
	v_pk_mul_f32 v[156:157], v[76:77], v[156:157]
	v_pk_mul_f32 v[158:159], v[78:79], v[158:159]
	v_pk_fma_f32 v[156:157], v[204:205], v[156:157], v[220:221]
	v_pk_fma_f32 v[158:159], v[206:207], v[158:159], v[222:223]
	v_cvt_pk_bf16_f32 v242, v156, v157
	v_cvt_pk_bf16_f32 v243, v158, v159
	global_store_dwordx4 v82, v[240:243], s[48:49] offset:1024
	s_add_u32 s34, s8, 0x48000
	s_addc_u32 s35, s9, 0
	s_add_u32 s36, s8, 0x4e000
	s_addc_u32 s37, s9, 0
	global_load_dwordx4 v[176:179], v80, s[34:35] offset:0
	global_load_dwordx4 v[180:183], v80, s[34:35] offset:16
	global_load_dwordx4 v[184:187], v80, s[34:35] offset:2048
	global_load_dwordx4 v[188:191], v80, s[34:35] offset:2064
	global_load_dwordx4 v[160:163], v81, s[34:35] offset:0
	global_load_dwordx4 v[164:167], v81, s[34:35] offset:16
	global_load_dwordx4 v[168:171], v81, s[34:35] offset:2048
	global_load_dwordx4 v[172:175], v81, s[34:35] offset:2064
; __device__ __forceinline__ float bf_lo(unsigned w) { return __uint_as_float(w << 16); }
; __device__ __forceinline__ float bf_hi(unsigned w) { return __uint_as_float(w & 0xffff0000u); }
; template <bool BF> __device__ __forceinline__ void prep_rows(const float* xp, const float* xs, const bf16* hb, const float* g, const float* MOD, int shoff, int scoff, bf16* U, int gw, int NGW, int lane) {
;     ...
;         for (int r = 0; r < R; ++r) { const int m = mb + r * NGW; const int mc = m < MT ? m : mb;
; #pragma unroll
;             for (int j = 0; j < 4; ++j) {
;                 if (BF) { const v2u a0 = *(const v2u*)(hb + (size_t)mc * DM + 4 * lane + 256 * j);
;                     v[r][j].x = pg8::bf_lo(a0.x); v[r][j].y = pg8::bf_hi(a0.x); v[r][j].z = pg8::bf_lo(a0.y); v[r][j].w = pg8::bf_hi(a0.y); }
;                 else { const float* xr = mc < MP ? xp + (size_t)mc * DM : xs + (size_t)(mc - MP) * DM; v[r][j] = *(const f32x4*)(xr + 4 * lane + 256 * j); } } }
; #pragma unroll
;         for (int r = 0; r < R; ++r) { float t = 0.f;
; #pragma unroll
;             for (int j = 0; j < 4; ++j) t += (v[r][j].x * v[r][j].x + v[r][j].y * v[r][j].y) + (v[r][j].z * v[r][j].z + v[r][j].w * v[r][j].w);
;             s[r] = t; }
; #pragma unroll
;         for (int o = 1; o < 64; o <<= 1) {
; #pragma unroll
;             for (int r = 0; r < R; ++r) s[r] += __shfl_xor(s[r], o); }
; #pragma unroll
	global_load_dwordx4 v[208:211], v80, s[36:37] offset:0
	global_load_dwordx4 v[212:215], v80, s[36:37] offset:16
	global_load_dwordx4 v[216:219], v80, s[36:37] offset:2048
	global_load_dwordx4 v[220:223], v80, s[36:37] offset:2064
	global_load_dwordx4 v[192:195], v81, s[36:37] offset:0
	global_load_dwordx4 v[196:199], v81, s[36:37] offset:16
	global_load_dwordx4 v[200:203], v81, s[36:37] offset:2048
	global_load_dwordx4 v[204:207], v81, s[36:37] offset:2064
	s_add_u32 s24, s18, 0x6000000
	s_addc_u32 s25, s19, 0
	s_add_u32 s26, s18, 0x6800000
	s_addc_u32 s27, s19, 0
	s_add_u32 s28, s18, 0x7000000
	s_addc_u32 s29, s19, 0
	s_add_u32 s30, s18, 0x7800000
	s_addc_u32 s31, s19, 0
	global_load_dwordx4 v[96:99], v80, s[24:25] offset:0
	global_load_dwordx4 v[100:103], v80, s[24:25] offset:16
	global_load_dwordx4 v[104:107], v80, s[24:25] offset:2048
	global_load_dwordx4 v[108:111], v80, s[24:25] offset:2064
	global_load_dwordx4 v[112:115], v80, s[26:27] offset:0
	global_load_dwordx4 v[116:119], v80, s[26:27] offset:16
	global_load_dwordx4 v[120:123], v80, s[26:27] offset:2048
	global_load_dwordx4 v[124:127], v80, s[26:27] offset:2064
	global_load_dwordx4 v[128:131], v80, s[28:29] offset:0
	global_load_dwordx4 v[132:135], v80, s[28:29] offset:16
	global_load_dwordx4 v[136:139], v80, s[28:29] offset:2048
	global_load_dwordx4 v[140:143], v80, s[28:29] offset:2064
	global_load_dwordx4 v[144:147], v80, s[30:31] offset:0
	global_load_dwordx4 v[148:151], v80, s[30:31] offset:16
	global_load_dwordx4 v[152:155], v80, s[30:31] offset:2048
	global_load_dwordx4 v[156:159], v80, s[30:31] offset:2064
	s_waitcnt vmcnt(40)
	v_pk_mul_f32 v[240:241], v[0:1], v[0:1]
	v_pk_mul_f32 v[242:243], v[16:17], v[16:17]
	v_pk_mul_f32 v[244:245], v[32:33], v[32:33]
	v_pk_mul_f32 v[246:247], v[48:49], v[48:49]
	v_pk_fma_f32 v[240:241], v[2:3], v[2:3], v[240:241]
	v_pk_fma_f32 v[242:243], v[18:19], v[18:19], v[242:243]
	v_pk_fma_f32 v[244:245], v[34:35], v[34:35], v[244:245]
	v_pk_fma_f32 v[246:247], v[50:51], v[50:51], v[246:247]
	v_pk_fma_f32 v[240:241], v[4:5], v[4:5], v[240:241]
	v_pk_fma_f32 v[242:243], v[20:21], v[20:21], v[242:243]
	v_pk_fma_f32 v[244:245], v[36:37], v[36:37], v[244:245]
	v_pk_fma_f32 v[246:247], v[52:53], v[52:53], v[246:247]
	v_pk_fma_f32 v[240:241], v[6:7], v[6:7], v[240:241]
	v_pk_fma_f32 v[242:243], v[22:23], v[22:23], v[242:243]
	v_pk_fma_f32 v[244:245], v[38:39], v[38:39], v[244:245]
	v_pk_fma_f32 v[246:247], v[54:55], v[54:55], v[246:247]
	v_pk_fma_f32 v[240:241], v[8:9], v[8:9], v[240:241]
	v_pk_fma_f32 v[242:243], v[24:25], v[24:25], v[242:243]
	v_pk_fma_f32 v[244:245], v[40:41], v[40:41], v[244:245]
	v_pk_fma_f32 v[246:247], v[56:57], v[56:57], v[246:247]
	v_pk_fma_f32 v[240:241], v[10:11], v[10:11], v[240:241]
	v_pk_fma_f32 v[242:243], v[26:27], v[26:27], v[242:243]
	v_pk_fma_f32 v[244:245], v[42:43], v[42:43], v[244:245]
	v_pk_fma_f32 v[246:247], v[58:59], v[58:59], v[246:247]
	v_pk_fma_f32 v[240:241], v[12:13], v[12:13], v[240:241]
	v_pk_fma_f32 v[242:243], v[28:29], v[28:29], v[242:243]
	v_pk_fma_f32 v[244:245], v[44:45], v[44:45], v[244:245]
	v_pk_fma_f32 v[246:247], v[60:61], v[60:61], v[246:247]
	v_pk_fma_f32 v[240:241], v[14:15], v[14:15], v[240:241]
	v_pk_fma_f32 v[242:243], v[30:31], v[30:31], v[242:243]
	v_pk_fma_f32 v[244:245], v[46:47], v[46:47], v[244:245]
	v_pk_fma_f32 v[246:247], v[62:63], v[62:63], v[246:247]
	v_add_f32_e32 v224, v240, v241
	v_add_f32_e32 v225, v242, v243
	v_add_f32_e32 v226, v244, v245
	v_add_f32_e32 v227, v246, v247
	ds_bpermute_b32 v228, v83, v224
	ds_bpermute_b32 v229, v83, v225
	ds_bpermute_b32 v230, v83, v226
	ds_bpermute_b32 v231, v83, v227
	s_waitcnt lgkmcnt(0)
	v_add_f32_e32 v224, v224, v228
	v_add_f32_e32 v225, v225, v229
	v_add_f32_e32 v226, v226, v230
	v_add_f32_e32 v227, v227, v231
	ds_bpermute_b32 v228, v84, v224
	ds_bpermute_b32 v229, v84, v225
	ds_bpermute_b32 v230, v84, v226
	ds_bpermute_b32 v231, v84, v227
	s_waitcnt lgkmcnt(0)
	v_add_f32_e32 v224, v224, v228
	v_add_f32_e32 v225, v225, v229
	v_add_f32_e32 v226, v226, v230
	v_add_f32_e32 v227, v227, v231
	ds_bpermute_b32 v228, v85, v224
	ds_bpermute_b32 v229, v85, v225
	ds_bpermute_b32 v230, v85, v226
	ds_bpermute_b32 v231, v85, v227
	s_waitcnt lgkmcnt(0)
	v_add_f32_e32 v224, v224, v228
	v_add_f32_e32 v225, v225, v229
	v_add_f32_e32 v226, v226, v230
	v_add_f32_e32 v227, v227, v231
	ds_bpermute_b32 v228, v86, v224
	ds_bpermute_b32 v229, v86, v225
	ds_bpermute_b32 v230, v86, v226
	ds_bpermute_b32 v231, v86, v227
	s_waitcnt lgkmcnt(0)
	v_add_f32_e32 v224, v224, v228
	v_add_f32_e32 v225, v225, v229
	v_add_f32_e32 v226, v226, v230
	v_add_f32_e32 v227, v227, v231
	ds_bpermute_b32 v228, v87, v224
	ds_bpermute_b32 v229, v87, v225
	ds_bpermute_b32 v230, v87, v226
	ds_bpermute_b32 v231, v87, v227
	s_waitcnt lgkmcnt(0)
	v_add_f32_e32 v224, v224, v228
	v_add_f32_e32 v225, v225, v229
	v_add_f32_e32 v226, v226, v230
	v_add_f32_e32 v227, v227, v231
	ds_bpermute_b32 v228, v88, v224
	ds_bpermute_b32 v229, v88, v225
	ds_bpermute_b32 v230, v88, v226
	ds_bpermute_b32 v231, v88, v227
	s_waitcnt lgkmcnt(0)
; template <bool BF> __device__ __forceinline__ void prep_rows(const float* xp, const float* xs, const bf16* hb, const float* g, const float* MOD, int shoff, int scoff, bf16* U, int gw, int NGW, int lane) {
;     ...
;             const float rstd = 1.0f / sqrtf(s[r] * (1.0f / DM) + RMS_EPS);
;             const float* mr = MOD + (size_t)(m < MP ? (m >> 13) : 8 + ((m - MP) >> 12)) * 6144;
; #pragma unroll
;             for (int j = 0; j < 4; ++j) { const int c = 4 * lane + 256 * j;
;                 const f32x4 gg = *(const f32x4*)(g + c), sc = *(const f32x4*)(mr + scoff + c), sh = *(const f32x4*)(mr + shoff + c);
	v_add_f32_e32 v224, v224, v228
	v_add_f32_e32 v225, v225, v229
	v_add_f32_e32 v226, v226, v230
	v_add_f32_e32 v227, v227, v231
	v_fmamk_f32 v240, v224, 0x3a800000, v89
	v_mul_f32_e32 v241, 0x4f800000, v240
	v_cmp_gt_f32_e32 vcc, s54, v240
	s_nop 1
	v_cndmask_b32_e32 v247, v240, v241, vcc
	v_sqrt_f32_e32 v242, v247
	s_nop 1
	v_add_u32_e32 v243, -1, v242
	v_add_u32_e32 v244, 1, v242
	v_fma_f32 v245, -v243, v242, v247
	v_fma_f32 v246, -v244, v242, v247
	v_cmp_ge_f32_e64 s[52:53], 0, v245
	s_nop 1
	v_cndmask_b32_e64 v242, v242, v243, s[52:53]
	v_cmp_lt_f32_e64 s[52:53], 0, v246
	s_nop 1
	v_cndmask_b32_e64 v242, v242, v244, s[52:53]
	v_mul_f32_e32 v243, 0x37800000, v242
	v_cndmask_b32_e32 v242, v242, v243, vcc
	v_cmp_class_f32_e32 vcc, v247, v90
	s_nop 1
	v_cndmask_b32_e32 v247, v242, v247, vcc
	v_div_scale_f32 v248, s[52:53], v247, v247, 1.0
	v_rcp_f32_e32 v249, v248
	v_div_scale_f32 v228, vcc, 1.0, v247, 1.0
	s_nop 0
	v_fma_f32 v229, -v248, v249, 1.0
	v_fmac_f32_e32 v249, v229, v249
	v_mul_f32_e32 v230, v228, v249
	v_fma_f32 v229, -v248, v230, v228
	v_fmac_f32_e32 v230, v229, v249
	v_fma_f32 v248, -v248, v230, v228
	v_div_fmas_f32 v248, v248, v249, v230
	v_div_fixup_f32 v232, v248, v247, 1.0
	v_fmamk_f32 v240, v225, 0x3a800000, v89
	v_mul_f32_e32 v241, 0x4f800000, v240
	v_cmp_gt_f32_e32 vcc, s54, v240
	s_nop 1
	v_cndmask_b32_e32 v247, v240, v241, vcc
	v_sqrt_f32_e32 v242, v247
	s_nop 1
	v_add_u32_e32 v243, -1, v242
	v_add_u32_e32 v244, 1, v242
	v_fma_f32 v245, -v243, v242, v247
	v_fma_f32 v246, -v244, v242, v247
	v_cmp_ge_f32_e64 s[52:53], 0, v245
	s_nop 1
	v_cndmask_b32_e64 v242, v242, v243, s[52:53]
	v_cmp_lt_f32_e64 s[52:53], 0, v246
	s_nop 1
	v_cndmask_b32_e64 v242, v242, v244, s[52:53]
	v_mul_f32_e32 v243, 0x37800000, v242
	v_cndmask_b32_e32 v242, v242, v243, vcc
	v_cmp_class_f32_e32 vcc, v247, v90
	s_nop 1
	v_cndmask_b32_e32 v247, v242, v247, vcc
	v_div_scale_f32 v248, s[52:53], v247, v247, 1.0
	v_rcp_f32_e32 v249, v248
	v_div_scale_f32 v228, vcc, 1.0, v247, 1.0
	s_nop 0
	v_fma_f32 v229, -v248, v249, 1.0
	v_fmac_f32_e32 v249, v229, v249
	v_mul_f32_e32 v230, v228, v249
	v_fma_f32 v229, -v248, v230, v228
	v_fmac_f32_e32 v230, v229, v249
	v_fma_f32 v248, -v248, v230, v228
	v_div_fmas_f32 v248, v248, v249, v230
	v_div_fixup_f32 v234, v248, v247, 1.0
	v_fmamk_f32 v240, v226, 0x3a800000, v89
	v_mul_f32_e32 v241, 0x4f800000, v240
	v_cmp_gt_f32_e32 vcc, s54, v240
	s_nop 1
	v_cndmask_b32_e32 v247, v240, v241, vcc
	v_sqrt_f32_e32 v242, v247
	s_nop 1
	v_add_u32_e32 v243, -1, v242
	v_add_u32_e32 v244, 1, v242
	v_fma_f32 v245, -v243, v242, v247
	v_fma_f32 v246, -v244, v242, v247
	v_cmp_ge_f32_e64 s[52:53], 0, v245
	s_nop 1
	v_cndmask_b32_e64 v242, v242, v243, s[52:53]
	v_cmp_lt_f32_e64 s[52:53], 0, v246
	s_nop 1
	v_cndmask_b32_e64 v242, v242, v244, s[52:53]
	v_mul_f32_e32 v243, 0x37800000, v242
	v_cndmask_b32_e32 v242, v242, v243, vcc
	v_cmp_class_f32_e32 vcc, v247, v90
	s_nop 1
	v_cndmask_b32_e32 v247, v242, v247, vcc
	v_div_scale_f32 v248, s[52:53], v247, v247, 1.0
	v_rcp_f32_e32 v249, v248
	v_div_scale_f32 v228, vcc, 1.0, v247, 1.0
	s_nop 0
	v_fma_f32 v229, -v248, v249, 1.0
	v_fmac_f32_e32 v249, v229, v249
	v_mul_f32_e32 v230, v228, v249
	v_fma_f32 v229, -v248, v230, v228
	v_fmac_f32_e32 v230, v229, v249
	v_fma_f32 v248, -v248, v230, v228
	v_div_fmas_f32 v248, v248, v249, v230
	v_div_fixup_f32 v236, v248, v247, 1.0
	v_fmamk_f32 v240, v227, 0x3a800000, v89
	v_mul_f32_e32 v241, 0x4f800000, v240
	v_cmp_gt_f32_e32 vcc, s54, v240
	s_nop 1
	v_cndmask_b32_e32 v247, v240, v241, vcc
	v_sqrt_f32_e32 v242, v247
	s_nop 1
	v_add_u32_e32 v243, -1, v242
	v_add_u32_e32 v244, 1, v242
	v_fma_f32 v245, -v243, v242, v247
	v_fma_f32 v246, -v244, v242, v247
	v_cmp_ge_f32_e64 s[52:53], 0, v245
	s_nop 1
	v_cndmask_b32_e64 v242, v242, v243, s[52:53]
	v_cmp_lt_f32_e64 s[52:53], 0, v246
	s_nop 1
	v_cndmask_b32_e64 v242, v242, v244, s[52:53]
	v_mul_f32_e32 v243, 0x37800000, v242
	v_cndmask_b32_e32 v242, v242, v243, vcc
	v_cmp_class_f32_e32 vcc, v247, v90
	s_nop 1
	v_cndmask_b32_e32 v247, v242, v247, vcc
	v_div_scale_f32 v248, s[52:53], v247, v247, 1.0
	v_rcp_f32_e32 v249, v248
	v_div_scale_f32 v228, vcc, 1.0, v247, 1.0
	s_nop 0
	v_fma_f32 v229, -v248, v249, 1.0
	v_fmac_f32_e32 v249, v229, v249
	v_mul_f32_e32 v230, v228, v249
	v_fma_f32 v229, -v248, v230, v228
	v_fmac_f32_e32 v230, v229, v249
	v_fma_f32 v248, -v248, v230, v228
	v_div_fmas_f32 v248, v248, v249, v230
	v_div_fixup_f32 v238, v248, v247, 1.0
	s_waitcnt vmcnt(16)
; __device__ __forceinline__ unsigned pk2(float lo, float hi) { return pg8::cvt_pk_bf16(lo, hi); }
; template <bool BF> __device__ __forceinline__ void prep_rows(const float* xp, const float* xs, const bf16* hb, const float* g, const float* MOD, int shoff, int scoff, bf16* U, int gw, int NGW, int lane) {
;     ...
;             for (int j = 0; j < 4; ++j) { const int c = 4 * lane + 256 * j;
;                 const f32x4 gg = *(const f32x4*)(g + c), sc = *(const f32x4*)(mr + scoff + c), sh = *(const f32x4*)(mr + shoff + c);
;                 const f32x4 o = v[r][j] * rstd * gg * (sc + 1.0f) + sh; v2u w; w.x = pk2(o.x, o.y); w.y = pk2(o.z, o.w); *(v2u*)(U + (size_t)m * DM + c) = w; } } }
	v_pk_add_f32 v[160:161], v[160:161], 1.0 op_sel_hi:[1,0]
	v_pk_add_f32 v[162:163], v[162:163], 1.0 op_sel_hi:[1,0]
	v_pk_add_f32 v[164:165], v[164:165], 1.0 op_sel_hi:[1,0]
	v_pk_add_f32 v[166:167], v[166:167], 1.0 op_sel_hi:[1,0]
	v_pk_add_f32 v[168:169], v[168:169], 1.0 op_sel_hi:[1,0]
	v_pk_add_f32 v[170:171], v[170:171], 1.0 op_sel_hi:[1,0]
	v_pk_add_f32 v[172:173], v[172:173], 1.0 op_sel_hi:[1,0]
	v_pk_add_f32 v[174:175], v[174:175], 1.0 op_sel_hi:[1,0]
	v_pk_add_f32 v[192:193], v[192:193], 1.0 op_sel_hi:[1,0]
	v_pk_add_f32 v[194:195], v[194:195], 1.0 op_sel_hi:[1,0]
	v_pk_add_f32 v[196:197], v[196:197], 1.0 op_sel_hi:[1,0]
	v_pk_add_f32 v[198:199], v[198:199], 1.0 op_sel_hi:[1,0]
	v_pk_add_f32 v[200:201], v[200:201], 1.0 op_sel_hi:[1,0]
	v_pk_add_f32 v[202:203], v[202:203], 1.0 op_sel_hi:[1,0]
	v_pk_add_f32 v[204:205], v[204:205], 1.0 op_sel_hi:[1,0]
	v_pk_add_f32 v[206:207], v[206:207], 1.0 op_sel_hi:[1,0]
	s_add_u32 s38, s20, 0xa000000
	s_addc_u32 s39, s21, 0
	s_add_u32 s40, s20, 0xa400000
	s_addc_u32 s41, s21, 0
	s_add_u32 s46, s20, 0xa800000
	s_addc_u32 s47, s21, 0
	s_add_u32 s48, s20, 0xac00000
	s_addc_u32 s49, s21, 0
	v_pk_mul_f32 v[0:1], v[0:1], v[232:233] op_sel_hi:[1,0]
	v_pk_mul_f32 v[2:3], v[2:3], v[232:233] op_sel_hi:[1,0]
	v_pk_mul_f32 v[0:1], v[64:65], v[0:1]
	v_pk_mul_f32 v[2:3], v[66:67], v[2:3]
	v_pk_fma_f32 v[0:1], v[160:161], v[0:1], v[176:177]
	v_pk_fma_f32 v[2:3], v[162:163], v[2:3], v[178:179]
	v_cvt_pk_bf16_f32 v244, v0, v1
	v_cvt_pk_bf16_f32 v245, v2, v3
	v_pk_mul_f32 v[4:5], v[4:5], v[232:233] op_sel_hi:[1,0]
	v_pk_mul_f32 v[6:7], v[6:7], v[232:233] op_sel_hi:[1,0]
	v_pk_mul_f32 v[4:5], v[68:69], v[4:5]
	v_pk_mul_f32 v[6:7], v[70:71], v[6:7]
	v_pk_fma_f32 v[4:5], v[164:165], v[4:5], v[180:181]
	v_pk_fma_f32 v[6:7], v[166:167], v[6:7], v[182:183]
	v_cvt_pk_bf16_f32 v246, v4, v5
	v_cvt_pk_bf16_f32 v247, v6, v7
	global_store_dwordx4 v82, v[244:247], s[38:39] offset:0
	v_pk_mul_f32 v[8:9], v[8:9], v[232:233] op_sel_hi:[1,0]
	v_pk_mul_f32 v[10:11], v[10:11], v[232:233] op_sel_hi:[1,0]
	v_pk_mul_f32 v[8:9], v[72:73], v[8:9]
	v_pk_mul_f32 v[10:11], v[74:75], v[10:11]
	v_pk_fma_f32 v[8:9], v[168:169], v[8:9], v[184:185]
	v_pk_fma_f32 v[10:11], v[170:171], v[10:11], v[186:187]
	v_cvt_pk_bf16_f32 v240, v8, v9
	v_cvt_pk_bf16_f32 v241, v10, v11
	v_pk_mul_f32 v[12:13], v[12:13], v[232:233] op_sel_hi:[1,0]
	v_pk_mul_f32 v[14:15], v[14:15], v[232:233] op_sel_hi:[1,0]
	v_pk_mul_f32 v[12:13], v[76:77], v[12:13]
	v_pk_mul_f32 v[14:15], v[78:79], v[14:15]
	v_pk_fma_f32 v[12:13], v[172:173], v[12:13], v[188:189]
	v_pk_fma_f32 v[14:15], v[174:175], v[14:15], v[190:191]
	v_cvt_pk_bf16_f32 v242, v12, v13
	v_cvt_pk_bf16_f32 v243, v14, v15
	global_store_dwordx4 v82, v[240:243], s[38:39] offset:1024
	v_pk_mul_f32 v[16:17], v[16:17], v[234:235] op_sel_hi:[1,0]
	v_pk_mul_f32 v[18:19], v[18:19], v[234:235] op_sel_hi:[1,0]
	v_pk_mul_f32 v[16:17], v[64:65], v[16:17]
	v_pk_mul_f32 v[18:19], v[66:67], v[18:19]
	v_pk_fma_f32 v[16:17], v[160:161], v[16:17], v[176:177]
	v_pk_fma_f32 v[18:19], v[162:163], v[18:19], v[178:179]
	v_cvt_pk_bf16_f32 v244, v16, v17
	v_cvt_pk_bf16_f32 v245, v18, v19
	v_pk_mul_f32 v[20:21], v[20:21], v[234:235] op_sel_hi:[1,0]
	v_pk_mul_f32 v[22:23], v[22:23], v[234:235] op_sel_hi:[1,0]
	v_pk_mul_f32 v[20:21], v[68:69], v[20:21]
	v_pk_mul_f32 v[22:23], v[70:71], v[22:23]
	v_pk_fma_f32 v[20:21], v[164:165], v[20:21], v[180:181]
	v_pk_fma_f32 v[22:23], v[166:167], v[22:23], v[182:183]
	v_cvt_pk_bf16_f32 v246, v20, v21
	v_cvt_pk_bf16_f32 v247, v22, v23
	global_store_dwordx4 v82, v[244:247], s[40:41] offset:0
	v_pk_mul_f32 v[24:25], v[24:25], v[234:235] op_sel_hi:[1,0]
	v_pk_mul_f32 v[26:27], v[26:27], v[234:235] op_sel_hi:[1,0]
	v_pk_mul_f32 v[24:25], v[72:73], v[24:25]
	v_pk_mul_f32 v[26:27], v[74:75], v[26:27]
	v_pk_fma_f32 v[24:25], v[168:169], v[24:25], v[184:185]
	v_pk_fma_f32 v[26:27], v[170:171], v[26:27], v[186:187]
	v_cvt_pk_bf16_f32 v240, v24, v25
	v_cvt_pk_bf16_f32 v241, v26, v27
	v_pk_mul_f32 v[28:29], v[28:29], v[234:235] op_sel_hi:[1,0]
	v_pk_mul_f32 v[30:31], v[30:31], v[234:235] op_sel_hi:[1,0]
	v_pk_mul_f32 v[28:29], v[76:77], v[28:29]
	v_pk_mul_f32 v[30:31], v[78:79], v[30:31]
	v_pk_fma_f32 v[28:29], v[172:173], v[28:29], v[188:189]
	v_pk_fma_f32 v[30:31], v[174:175], v[30:31], v[190:191]
	v_cvt_pk_bf16_f32 v242, v28, v29
	v_cvt_pk_bf16_f32 v243, v30, v31
	global_store_dwordx4 v82, v[240:243], s[40:41] offset:1024
	v_pk_mul_f32 v[32:33], v[32:33], v[236:237] op_sel_hi:[1,0]
	v_pk_mul_f32 v[34:35], v[34:35], v[236:237] op_sel_hi:[1,0]
	v_pk_mul_f32 v[32:33], v[64:65], v[32:33]
	v_pk_mul_f32 v[34:35], v[66:67], v[34:35]
	v_pk_fma_f32 v[32:33], v[192:193], v[32:33], v[208:209]
	v_pk_fma_f32 v[34:35], v[194:195], v[34:35], v[210:211]
	v_cvt_pk_bf16_f32 v244, v32, v33
	v_cvt_pk_bf16_f32 v245, v34, v35
	v_pk_mul_f32 v[36:37], v[36:37], v[236:237] op_sel_hi:[1,0]
	v_pk_mul_f32 v[38:39], v[38:39], v[236:237] op_sel_hi:[1,0]
	v_pk_mul_f32 v[36:37], v[68:69], v[36:37]
	v_pk_mul_f32 v[38:39], v[70:71], v[38:39]
	v_pk_fma_f32 v[36:37], v[196:197], v[36:37], v[212:213]
	v_pk_fma_f32 v[38:39], v[198:199], v[38:39], v[214:215]
	v_cvt_pk_bf16_f32 v246, v36, v37
	v_cvt_pk_bf16_f32 v247, v38, v39
	global_store_dwordx4 v82, v[244:247], s[46:47] offset:0
	v_pk_mul_f32 v[40:41], v[40:41], v[236:237] op_sel_hi:[1,0]
	v_pk_mul_f32 v[42:43], v[42:43], v[236:237] op_sel_hi:[1,0]
	v_pk_mul_f32 v[40:41], v[72:73], v[40:41]
	v_pk_mul_f32 v[42:43], v[74:75], v[42:43]
	v_pk_fma_f32 v[40:41], v[200:201], v[40:41], v[216:217]
	v_pk_fma_f32 v[42:43], v[202:203], v[42:43], v[218:219]
	v_cvt_pk_bf16_f32 v240, v40, v41
; __device__ __forceinline__ unsigned pk2(float lo, float hi) { return pg8::cvt_pk_bf16(lo, hi); }
; template <bool BF> __device__ __forceinline__ void prep_rows(const float* xp, const float* xs, const bf16* hb, const float* g, const float* MOD, int shoff, int scoff, bf16* U, int gw, int NGW, int lane) {
;     ...
;         for (int r = 0; r < R; ++r) { float t = 0.f;
; #pragma unroll
;             for (int j = 0; j < 4; ++j) t += (v[r][j].x * v[r][j].x + v[r][j].y * v[r][j].y) + (v[r][j].z * v[r][j].z + v[r][j].w * v[r][j].w);
;             s[r] = t; }
; #pragma unroll
;         for (int o = 1; o < 64; o <<= 1) {
; #pragma unroll
;             for (int r = 0; r < R; ++r) s[r] += __shfl_xor(s[r], o); }
; #pragma unroll
;     ...
;             for (int j = 0; j < 4; ++j) { const int c = 4 * lane + 256 * j;
;                 const f32x4 gg = *(const f32x4*)(g + c), sc = *(const f32x4*)(mr + scoff + c), sh = *(const f32x4*)(mr + shoff + c);
;                 const f32x4 o = v[r][j] * rstd * gg * (sc + 1.0f) + sh; v2u w; w.x = pk2(o.x, o.y); w.y = pk2(o.z, o.w); *(v2u*)(U + (size_t)m * DM + c) = w; } } }
	v_cvt_pk_bf16_f32 v241, v42, v43
	v_pk_mul_f32 v[44:45], v[44:45], v[236:237] op_sel_hi:[1,0]
	v_pk_mul_f32 v[46:47], v[46:47], v[236:237] op_sel_hi:[1,0]
	v_pk_mul_f32 v[44:45], v[76:77], v[44:45]
	v_pk_mul_f32 v[46:47], v[78:79], v[46:47]
	v_pk_fma_f32 v[44:45], v[204:205], v[44:45], v[220:221]
	v_pk_fma_f32 v[46:47], v[206:207], v[46:47], v[222:223]
	v_cvt_pk_bf16_f32 v242, v44, v45
	v_cvt_pk_bf16_f32 v243, v46, v47
	global_store_dwordx4 v82, v[240:243], s[46:47] offset:1024
	v_pk_mul_f32 v[48:49], v[48:49], v[238:239] op_sel_hi:[1,0]
	v_pk_mul_f32 v[50:51], v[50:51], v[238:239] op_sel_hi:[1,0]
	v_pk_mul_f32 v[48:49], v[64:65], v[48:49]
	v_pk_mul_f32 v[50:51], v[66:67], v[50:51]
	v_pk_fma_f32 v[48:49], v[192:193], v[48:49], v[208:209]
	v_pk_fma_f32 v[50:51], v[194:195], v[50:51], v[210:211]
	v_cvt_pk_bf16_f32 v244, v48, v49
	v_cvt_pk_bf16_f32 v245, v50, v51
	v_pk_mul_f32 v[52:53], v[52:53], v[238:239] op_sel_hi:[1,0]
	v_pk_mul_f32 v[54:55], v[54:55], v[238:239] op_sel_hi:[1,0]
	v_pk_mul_f32 v[52:53], v[68:69], v[52:53]
	v_pk_mul_f32 v[54:55], v[70:71], v[54:55]
	v_pk_fma_f32 v[52:53], v[196:197], v[52:53], v[212:213]
	v_pk_fma_f32 v[54:55], v[198:199], v[54:55], v[214:215]
	v_cvt_pk_bf16_f32 v246, v52, v53
	v_cvt_pk_bf16_f32 v247, v54, v55
	global_store_dwordx4 v82, v[244:247], s[48:49] offset:0
	v_pk_mul_f32 v[56:57], v[56:57], v[238:239] op_sel_hi:[1,0]
	v_pk_mul_f32 v[58:59], v[58:59], v[238:239] op_sel_hi:[1,0]
	v_pk_mul_f32 v[56:57], v[72:73], v[56:57]
	v_pk_mul_f32 v[58:59], v[74:75], v[58:59]
	v_pk_fma_f32 v[56:57], v[200:201], v[56:57], v[216:217]
	v_pk_fma_f32 v[58:59], v[202:203], v[58:59], v[218:219]
	v_cvt_pk_bf16_f32 v240, v56, v57
	v_cvt_pk_bf16_f32 v241, v58, v59
	v_pk_mul_f32 v[60:61], v[60:61], v[238:239] op_sel_hi:[1,0]
	v_pk_mul_f32 v[62:63], v[62:63], v[238:239] op_sel_hi:[1,0]
	v_pk_mul_f32 v[60:61], v[76:77], v[60:61]
	v_pk_mul_f32 v[62:63], v[78:79], v[62:63]
	v_pk_fma_f32 v[60:61], v[204:205], v[60:61], v[220:221]
	v_pk_fma_f32 v[62:63], v[206:207], v[62:63], v[222:223]
	v_cvt_pk_bf16_f32 v242, v60, v61
	v_cvt_pk_bf16_f32 v243, v62, v63
	global_store_dwordx4 v82, v[240:243], s[48:49] offset:1024
	s_add_u32 s34, s8, 0x54000
	s_addc_u32 s35, s9, 0
	s_add_u32 s36, s8, 0x5a000
	s_addc_u32 s37, s9, 0
	global_load_dwordx4 v[176:179], v80, s[34:35] offset:0
	global_load_dwordx4 v[180:183], v80, s[34:35] offset:16
	global_load_dwordx4 v[184:187], v80, s[34:35] offset:2048
	global_load_dwordx4 v[188:191], v80, s[34:35] offset:2064
	global_load_dwordx4 v[160:163], v81, s[34:35] offset:0
	global_load_dwordx4 v[164:167], v81, s[34:35] offset:16
	global_load_dwordx4 v[168:171], v81, s[34:35] offset:2048
	global_load_dwordx4 v[172:175], v81, s[34:35] offset:2064
	global_load_dwordx4 v[208:211], v80, s[36:37] offset:0
	global_load_dwordx4 v[212:215], v80, s[36:37] offset:16
	global_load_dwordx4 v[216:219], v80, s[36:37] offset:2048
	global_load_dwordx4 v[220:223], v80, s[36:37] offset:2064
	global_load_dwordx4 v[192:195], v81, s[36:37] offset:0
	global_load_dwordx4 v[196:199], v81, s[36:37] offset:16
	global_load_dwordx4 v[200:203], v81, s[36:37] offset:2048
	global_load_dwordx4 v[204:207], v81, s[36:37] offset:2064
	s_waitcnt vmcnt(24)
	v_pk_mul_f32 v[240:241], v[96:97], v[96:97]
	v_pk_mul_f32 v[242:243], v[112:113], v[112:113]
	v_pk_mul_f32 v[244:245], v[128:129], v[128:129]
	v_pk_mul_f32 v[246:247], v[144:145], v[144:145]
	v_pk_fma_f32 v[240:241], v[98:99], v[98:99], v[240:241]
	v_pk_fma_f32 v[242:243], v[114:115], v[114:115], v[242:243]
	v_pk_fma_f32 v[244:245], v[130:131], v[130:131], v[244:245]
	v_pk_fma_f32 v[246:247], v[146:147], v[146:147], v[246:247]
	v_pk_fma_f32 v[240:241], v[100:101], v[100:101], v[240:241]
	v_pk_fma_f32 v[242:243], v[116:117], v[116:117], v[242:243]
	v_pk_fma_f32 v[244:245], v[132:133], v[132:133], v[244:245]
	v_pk_fma_f32 v[246:247], v[148:149], v[148:149], v[246:247]
	v_pk_fma_f32 v[240:241], v[102:103], v[102:103], v[240:241]
	v_pk_fma_f32 v[242:243], v[118:119], v[118:119], v[242:243]
	v_pk_fma_f32 v[244:245], v[134:135], v[134:135], v[244:245]
	v_pk_fma_f32 v[246:247], v[150:151], v[150:151], v[246:247]
	v_pk_fma_f32 v[240:241], v[104:105], v[104:105], v[240:241]
	v_pk_fma_f32 v[242:243], v[120:121], v[120:121], v[242:243]
	v_pk_fma_f32 v[244:245], v[136:137], v[136:137], v[244:245]
	v_pk_fma_f32 v[246:247], v[152:153], v[152:153], v[246:247]
	v_pk_fma_f32 v[240:241], v[106:107], v[106:107], v[240:241]
	v_pk_fma_f32 v[242:243], v[122:123], v[122:123], v[242:243]
	v_pk_fma_f32 v[244:245], v[138:139], v[138:139], v[244:245]
	v_pk_fma_f32 v[246:247], v[154:155], v[154:155], v[246:247]
	v_pk_fma_f32 v[240:241], v[108:109], v[108:109], v[240:241]
	v_pk_fma_f32 v[242:243], v[124:125], v[124:125], v[242:243]
	v_pk_fma_f32 v[244:245], v[140:141], v[140:141], v[244:245]
	v_pk_fma_f32 v[246:247], v[156:157], v[156:157], v[246:247]
	v_pk_fma_f32 v[240:241], v[110:111], v[110:111], v[240:241]
	v_pk_fma_f32 v[242:243], v[126:127], v[126:127], v[242:243]
	v_pk_fma_f32 v[244:245], v[142:143], v[142:143], v[244:245]
	v_pk_fma_f32 v[246:247], v[158:159], v[158:159], v[246:247]
	v_add_f32_e32 v224, v240, v241
	v_add_f32_e32 v225, v242, v243
	v_add_f32_e32 v226, v244, v245
	v_add_f32_e32 v227, v246, v247
	ds_bpermute_b32 v228, v83, v224
	ds_bpermute_b32 v229, v83, v225
	ds_bpermute_b32 v230, v83, v226
	ds_bpermute_b32 v231, v83, v227
	s_waitcnt lgkmcnt(0)
	v_add_f32_e32 v224, v224, v228
	v_add_f32_e32 v225, v225, v229
	v_add_f32_e32 v226, v226, v230
	v_add_f32_e32 v227, v227, v231
	ds_bpermute_b32 v228, v84, v224
	ds_bpermute_b32 v229, v84, v225
	ds_bpermute_b32 v230, v84, v226
	ds_bpermute_b32 v231, v84, v227
	s_waitcnt lgkmcnt(0)
; template <bool BF> __device__ __forceinline__ void prep_rows(const float* xp, const float* xs, const bf16* hb, const float* g, const float* MOD, int shoff, int scoff, bf16* U, int gw, int NGW, int lane) {
;     ...
;         for (int o = 1; o < 64; o <<= 1) {
; #pragma unroll
;             for (int r = 0; r < R; ++r) s[r] += __shfl_xor(s[r], o); }
; #pragma unroll
;         for (int r = 0; r < R; ++r) { const int m = mb + r * NGW; if (m < MT) {
;             const float rstd = 1.0f / sqrtf(s[r] * (1.0f / DM) + RMS_EPS);
	v_add_f32_e32 v224, v224, v228
	v_add_f32_e32 v225, v225, v229
	v_add_f32_e32 v226, v226, v230
	v_add_f32_e32 v227, v227, v231
	ds_bpermute_b32 v228, v85, v224
	ds_bpermute_b32 v229, v85, v225
	ds_bpermute_b32 v230, v85, v226
	ds_bpermute_b32 v231, v85, v227
	s_waitcnt lgkmcnt(0)
	v_add_f32_e32 v224, v224, v228
	v_add_f32_e32 v225, v225, v229
	v_add_f32_e32 v226, v226, v230
	v_add_f32_e32 v227, v227, v231
	ds_bpermute_b32 v228, v86, v224
	ds_bpermute_b32 v229, v86, v225
	ds_bpermute_b32 v230, v86, v226
	ds_bpermute_b32 v231, v86, v227
	s_waitcnt lgkmcnt(0)
	v_add_f32_e32 v224, v224, v228
	v_add_f32_e32 v225, v225, v229
	v_add_f32_e32 v226, v226, v230
	v_add_f32_e32 v227, v227, v231
	ds_bpermute_b32 v228, v87, v224
	ds_bpermute_b32 v229, v87, v225
	ds_bpermute_b32 v230, v87, v226
	ds_bpermute_b32 v231, v87, v227
	s_waitcnt lgkmcnt(0)
	v_add_f32_e32 v224, v224, v228
	v_add_f32_e32 v225, v225, v229
	v_add_f32_e32 v226, v226, v230
	v_add_f32_e32 v227, v227, v231
	ds_bpermute_b32 v228, v88, v224
	ds_bpermute_b32 v229, v88, v225
	ds_bpermute_b32 v230, v88, v226
	ds_bpermute_b32 v231, v88, v227
	s_waitcnt lgkmcnt(0)
	v_add_f32_e32 v224, v224, v228
	v_add_f32_e32 v225, v225, v229
	v_add_f32_e32 v226, v226, v230
	v_add_f32_e32 v227, v227, v231
	v_fmamk_f32 v240, v224, 0x3a800000, v89
	v_mul_f32_e32 v241, 0x4f800000, v240
	v_cmp_gt_f32_e32 vcc, s54, v240
	s_nop 1
	v_cndmask_b32_e32 v247, v240, v241, vcc
	v_sqrt_f32_e32 v242, v247
	s_nop 1
	v_add_u32_e32 v243, -1, v242
	v_add_u32_e32 v244, 1, v242
	v_fma_f32 v245, -v243, v242, v247
	v_fma_f32 v246, -v244, v242, v247
	v_cmp_ge_f32_e64 s[52:53], 0, v245
	s_nop 1
	v_cndmask_b32_e64 v242, v242, v243, s[52:53]
	v_cmp_lt_f32_e64 s[52:53], 0, v246
	s_nop 1
	v_cndmask_b32_e64 v242, v242, v244, s[52:53]
	v_mul_f32_e32 v243, 0x37800000, v242
	v_cndmask_b32_e32 v242, v242, v243, vcc
	v_cmp_class_f32_e32 vcc, v247, v90
	s_nop 1
	v_cndmask_b32_e32 v247, v242, v247, vcc
	v_div_scale_f32 v248, s[52:53], v247, v247, 1.0
	v_rcp_f32_e32 v249, v248
	v_div_scale_f32 v228, vcc, 1.0, v247, 1.0
	s_nop 0
	v_fma_f32 v229, -v248, v249, 1.0
	v_fmac_f32_e32 v249, v229, v249
	v_mul_f32_e32 v230, v228, v249
	v_fma_f32 v229, -v248, v230, v228
	v_fmac_f32_e32 v230, v229, v249
	v_fma_f32 v248, -v248, v230, v228
	v_div_fmas_f32 v248, v248, v249, v230
	v_div_fixup_f32 v232, v248, v247, 1.0
	v_fmamk_f32 v240, v225, 0x3a800000, v89
	v_mul_f32_e32 v241, 0x4f800000, v240
	v_cmp_gt_f32_e32 vcc, s54, v240
	s_nop 1
	v_cndmask_b32_e32 v247, v240, v241, vcc
	v_sqrt_f32_e32 v242, v247
	s_nop 1
	v_add_u32_e32 v243, -1, v242
	v_add_u32_e32 v244, 1, v242
	v_fma_f32 v245, -v243, v242, v247
	v_fma_f32 v246, -v244, v242, v247
	v_cmp_ge_f32_e64 s[52:53], 0, v245
	s_nop 1
	v_cndmask_b32_e64 v242, v242, v243, s[52:53]
	v_cmp_lt_f32_e64 s[52:53], 0, v246
	s_nop 1
	v_cndmask_b32_e64 v242, v242, v244, s[52:53]
	v_mul_f32_e32 v243, 0x37800000, v242
	v_cndmask_b32_e32 v242, v242, v243, vcc
	v_cmp_class_f32_e32 vcc, v247, v90
	s_nop 1
	v_cndmask_b32_e32 v247, v242, v247, vcc
	v_div_scale_f32 v248, s[52:53], v247, v247, 1.0
	v_rcp_f32_e32 v249, v248
	v_div_scale_f32 v228, vcc, 1.0, v247, 1.0
	s_nop 0
	v_fma_f32 v229, -v248, v249, 1.0
	v_fmac_f32_e32 v249, v229, v249
	v_mul_f32_e32 v230, v228, v249
	v_fma_f32 v229, -v248, v230, v228
	v_fmac_f32_e32 v230, v229, v249
	v_fma_f32 v248, -v248, v230, v228
	v_div_fmas_f32 v248, v248, v249, v230
	v_div_fixup_f32 v234, v248, v247, 1.0
	v_fmamk_f32 v240, v226, 0x3a800000, v89
	v_mul_f32_e32 v241, 0x4f800000, v240
	v_cmp_gt_f32_e32 vcc, s54, v240
	s_nop 1
	v_cndmask_b32_e32 v247, v240, v241, vcc
	v_sqrt_f32_e32 v242, v247
	s_nop 1
	v_add_u32_e32 v243, -1, v242
	v_add_u32_e32 v244, 1, v242
	v_fma_f32 v245, -v243, v242, v247
	v_fma_f32 v246, -v244, v242, v247
	v_cmp_ge_f32_e64 s[52:53], 0, v245
	s_nop 1
	v_cndmask_b32_e64 v242, v242, v243, s[52:53]
	v_cmp_lt_f32_e64 s[52:53], 0, v246
	s_nop 1
	v_cndmask_b32_e64 v242, v242, v244, s[52:53]
	v_mul_f32_e32 v243, 0x37800000, v242
	v_cndmask_b32_e32 v242, v242, v243, vcc
	v_cmp_class_f32_e32 vcc, v247, v90
	s_nop 1
	v_cndmask_b32_e32 v247, v242, v247, vcc
	v_div_scale_f32 v248, s[52:53], v247, v247, 1.0
	v_rcp_f32_e32 v249, v248
	v_div_scale_f32 v228, vcc, 1.0, v247, 1.0
	s_nop 0
	v_fma_f32 v229, -v248, v249, 1.0
	v_fmac_f32_e32 v249, v229, v249
	v_mul_f32_e32 v230, v228, v249
	v_fma_f32 v229, -v248, v230, v228
	v_fmac_f32_e32 v230, v229, v249
	v_fma_f32 v248, -v248, v230, v228
	v_div_fmas_f32 v248, v248, v249, v230
	v_div_fixup_f32 v236, v248, v247, 1.0
	v_fmamk_f32 v240, v227, 0x3a800000, v89
	v_mul_f32_e32 v241, 0x4f800000, v240
	v_cmp_gt_f32_e32 vcc, s54, v240
	s_nop 1
	v_cndmask_b32_e32 v247, v240, v241, vcc
	v_sqrt_f32_e32 v242, v247
	s_nop 1
	v_add_u32_e32 v243, -1, v242
	v_add_u32_e32 v244, 1, v242
	v_fma_f32 v245, -v243, v242, v247
	v_fma_f32 v246, -v244, v242, v247
	v_cmp_ge_f32_e64 s[52:53], 0, v245
	s_nop 1
	v_cndmask_b32_e64 v242, v242, v243, s[52:53]
	v_cmp_lt_f32_e64 s[52:53], 0, v246
	s_nop 1
	v_cndmask_b32_e64 v242, v242, v244, s[52:53]
	v_mul_f32_e32 v243, 0x37800000, v242
	v_cndmask_b32_e32 v242, v242, v243, vcc
	v_cmp_class_f32_e32 vcc, v247, v90
	s_nop 1
	v_cndmask_b32_e32 v247, v242, v247, vcc
	v_div_scale_f32 v248, s[52:53], v247, v247, 1.0
	v_rcp_f32_e32 v249, v248
	v_div_scale_f32 v228, vcc, 1.0, v247, 1.0
	s_nop 0
	v_fma_f32 v229, -v248, v249, 1.0
	v_fmac_f32_e32 v249, v229, v249
	v_mul_f32_e32 v230, v228, v249
	v_fma_f32 v229, -v248, v230, v228
	v_fmac_f32_e32 v230, v229, v249
	v_fma_f32 v248, -v248, v230, v228
	v_div_fmas_f32 v248, v248, v249, v230
	v_div_fixup_f32 v238, v248, v247, 1.0
	s_waitcnt vmcnt(0)
; __device__ __forceinline__ unsigned pk2(float lo, float hi) { return pg8::cvt_pk_bf16(lo, hi); }
; template <bool BF> __device__ __forceinline__ void prep_rows(const float* xp, const float* xs, const bf16* hb, const float* g, const float* MOD, int shoff, int scoff, bf16* U, int gw, int NGW, int lane) {
;     ...
;             for (int j = 0; j < 4; ++j) { const int c = 4 * lane + 256 * j;
;                 const f32x4 gg = *(const f32x4*)(g + c), sc = *(const f32x4*)(mr + scoff + c), sh = *(const f32x4*)(mr + shoff + c);
;                 const f32x4 o = v[r][j] * rstd * gg * (sc + 1.0f) + sh; v2u w; w.x = pk2(o.x, o.y); w.y = pk2(o.z, o.w); *(v2u*)(U + (size_t)m * DM + c) = w; } } }
	v_pk_add_f32 v[160:161], v[160:161], 1.0 op_sel_hi:[1,0]
	v_pk_add_f32 v[162:163], v[162:163], 1.0 op_sel_hi:[1,0]
	v_pk_add_f32 v[164:165], v[164:165], 1.0 op_sel_hi:[1,0]
	v_pk_add_f32 v[166:167], v[166:167], 1.0 op_sel_hi:[1,0]
	v_pk_add_f32 v[168:169], v[168:169], 1.0 op_sel_hi:[1,0]
	v_pk_add_f32 v[170:171], v[170:171], 1.0 op_sel_hi:[1,0]
	v_pk_add_f32 v[172:173], v[172:173], 1.0 op_sel_hi:[1,0]
	v_pk_add_f32 v[174:175], v[174:175], 1.0 op_sel_hi:[1,0]
	v_pk_add_f32 v[192:193], v[192:193], 1.0 op_sel_hi:[1,0]
	v_pk_add_f32 v[194:195], v[194:195], 1.0 op_sel_hi:[1,0]
	v_pk_add_f32 v[196:197], v[196:197], 1.0 op_sel_hi:[1,0]
	v_pk_add_f32 v[198:199], v[198:199], 1.0 op_sel_hi:[1,0]
	v_pk_add_f32 v[200:201], v[200:201], 1.0 op_sel_hi:[1,0]
	v_pk_add_f32 v[202:203], v[202:203], 1.0 op_sel_hi:[1,0]
	v_pk_add_f32 v[204:205], v[204:205], 1.0 op_sel_hi:[1,0]
	v_pk_add_f32 v[206:207], v[206:207], 1.0 op_sel_hi:[1,0]
	s_add_u32 s38, s20, 0xb000000
	s_addc_u32 s39, s21, 0
	s_add_u32 s40, s20, 0xb400000
	s_addc_u32 s41, s21, 0
	s_add_u32 s46, s20, 0xb800000
	s_addc_u32 s47, s21, 0
	s_add_u32 s48, s20, 0xbc00000
	s_addc_u32 s49, s21, 0
	v_pk_mul_f32 v[96:97], v[96:97], v[232:233] op_sel_hi:[1,0]
	v_pk_mul_f32 v[98:99], v[98:99], v[232:233] op_sel_hi:[1,0]
	v_pk_mul_f32 v[96:97], v[64:65], v[96:97]
	v_pk_mul_f32 v[98:99], v[66:67], v[98:99]
	v_pk_fma_f32 v[96:97], v[160:161], v[96:97], v[176:177]
	v_pk_fma_f32 v[98:99], v[162:163], v[98:99], v[178:179]
	v_cvt_pk_bf16_f32 v244, v96, v97
	v_cvt_pk_bf16_f32 v245, v98, v99
	v_pk_mul_f32 v[100:101], v[100:101], v[232:233] op_sel_hi:[1,0]
	v_pk_mul_f32 v[102:103], v[102:103], v[232:233] op_sel_hi:[1,0]
	v_pk_mul_f32 v[100:101], v[68:69], v[100:101]
	v_pk_mul_f32 v[102:103], v[70:71], v[102:103]
	v_pk_fma_f32 v[100:101], v[164:165], v[100:101], v[180:181]
	v_pk_fma_f32 v[102:103], v[166:167], v[102:103], v[182:183]
	v_cvt_pk_bf16_f32 v246, v100, v101
	v_cvt_pk_bf16_f32 v247, v102, v103
	global_store_dwordx4 v82, v[244:247], s[38:39] offset:0
	v_pk_mul_f32 v[104:105], v[104:105], v[232:233] op_sel_hi:[1,0]
	v_pk_mul_f32 v[106:107], v[106:107], v[232:233] op_sel_hi:[1,0]
	v_pk_mul_f32 v[104:105], v[72:73], v[104:105]
	v_pk_mul_f32 v[106:107], v[74:75], v[106:107]
	v_pk_fma_f32 v[104:105], v[168:169], v[104:105], v[184:185]
	v_pk_fma_f32 v[106:107], v[170:171], v[106:107], v[186:187]
	v_cvt_pk_bf16_f32 v240, v104, v105
	v_cvt_pk_bf16_f32 v241, v106, v107
	v_pk_mul_f32 v[108:109], v[108:109], v[232:233] op_sel_hi:[1,0]
	v_pk_mul_f32 v[110:111], v[110:111], v[232:233] op_sel_hi:[1,0]
	v_pk_mul_f32 v[108:109], v[76:77], v[108:109]
	v_pk_mul_f32 v[110:111], v[78:79], v[110:111]
	v_pk_fma_f32 v[108:109], v[172:173], v[108:109], v[188:189]
	v_pk_fma_f32 v[110:111], v[174:175], v[110:111], v[190:191]
	v_cvt_pk_bf16_f32 v242, v108, v109
	v_cvt_pk_bf16_f32 v243, v110, v111
	global_store_dwordx4 v82, v[240:243], s[38:39] offset:1024
	v_pk_mul_f32 v[112:113], v[112:113], v[234:235] op_sel_hi:[1,0]
	v_pk_mul_f32 v[114:115], v[114:115], v[234:235] op_sel_hi:[1,0]
	v_pk_mul_f32 v[112:113], v[64:65], v[112:113]
	v_pk_mul_f32 v[114:115], v[66:67], v[114:115]
	v_pk_fma_f32 v[112:113], v[160:161], v[112:113], v[176:177]
	v_pk_fma_f32 v[114:115], v[162:163], v[114:115], v[178:179]
	v_cvt_pk_bf16_f32 v244, v112, v113
	v_cvt_pk_bf16_f32 v245, v114, v115
	v_pk_mul_f32 v[116:117], v[116:117], v[234:235] op_sel_hi:[1,0]
	v_pk_mul_f32 v[118:119], v[118:119], v[234:235] op_sel_hi:[1,0]
	v_pk_mul_f32 v[116:117], v[68:69], v[116:117]
	v_pk_mul_f32 v[118:119], v[70:71], v[118:119]
	v_pk_fma_f32 v[116:117], v[164:165], v[116:117], v[180:181]
	v_pk_fma_f32 v[118:119], v[166:167], v[118:119], v[182:183]
	v_cvt_pk_bf16_f32 v246, v116, v117
	v_cvt_pk_bf16_f32 v247, v118, v119
	global_store_dwordx4 v82, v[244:247], s[40:41] offset:0
	v_pk_mul_f32 v[120:121], v[120:121], v[234:235] op_sel_hi:[1,0]
	v_pk_mul_f32 v[122:123], v[122:123], v[234:235] op_sel_hi:[1,0]
	v_pk_mul_f32 v[120:121], v[72:73], v[120:121]
	v_pk_mul_f32 v[122:123], v[74:75], v[122:123]
	v_pk_fma_f32 v[120:121], v[168:169], v[120:121], v[184:185]
	v_pk_fma_f32 v[122:123], v[170:171], v[122:123], v[186:187]
	v_cvt_pk_bf16_f32 v240, v120, v121
	v_cvt_pk_bf16_f32 v241, v122, v123
	v_pk_mul_f32 v[124:125], v[124:125], v[234:235] op_sel_hi:[1,0]
	v_pk_mul_f32 v[126:127], v[126:127], v[234:235] op_sel_hi:[1,0]
	v_pk_mul_f32 v[124:125], v[76:77], v[124:125]
	v_pk_mul_f32 v[126:127], v[78:79], v[126:127]
	v_pk_fma_f32 v[124:125], v[172:173], v[124:125], v[188:189]
	v_pk_fma_f32 v[126:127], v[174:175], v[126:127], v[190:191]
	v_cvt_pk_bf16_f32 v242, v124, v125
	v_cvt_pk_bf16_f32 v243, v126, v127
	global_store_dwordx4 v82, v[240:243], s[40:41] offset:1024
	v_pk_mul_f32 v[128:129], v[128:129], v[236:237] op_sel_hi:[1,0]
	v_pk_mul_f32 v[130:131], v[130:131], v[236:237] op_sel_hi:[1,0]
	v_pk_mul_f32 v[128:129], v[64:65], v[128:129]
	v_pk_mul_f32 v[130:131], v[66:67], v[130:131]
	v_pk_fma_f32 v[128:129], v[192:193], v[128:129], v[208:209]
	v_pk_fma_f32 v[130:131], v[194:195], v[130:131], v[210:211]
	v_cvt_pk_bf16_f32 v244, v128, v129
	v_cvt_pk_bf16_f32 v245, v130, v131
	v_pk_mul_f32 v[132:133], v[132:133], v[236:237] op_sel_hi:[1,0]
	v_pk_mul_f32 v[134:135], v[134:135], v[236:237] op_sel_hi:[1,0]
; __device__ __forceinline__ unsigned pk2(float lo, float hi) { return pg8::cvt_pk_bf16(lo, hi); }
; template <bool BF> __device__ __forceinline__ void prep_rows(const float* xp, const float* xs, const bf16* hb, const float* g, const float* MOD, int shoff, int scoff, bf16* U, int gw, int NGW, int lane) {
;     constexpr int R = 4;
;     for (int mb = gw; mb < MT; mb += R * NGW) {
;         f32x4 v[R][4]; float s[R];
; #pragma unroll
;         for (int r = 0; r < R; ++r) { const int m = mb + r * NGW; const int mc = m < MT ? m : mb;
;     ...
;             for (int j = 0; j < 4; ++j) { const int c = 4 * lane + 256 * j;
;                 const f32x4 gg = *(const f32x4*)(g + c), sc = *(const f32x4*)(mr + scoff + c), sh = *(const f32x4*)(mr + shoff + c);
;                 const f32x4 o = v[r][j] * rstd * gg * (sc + 1.0f) + sh; v2u w; w.x = pk2(o.x, o.y); w.y = pk2(o.z, o.w); *(v2u*)(U + (size_t)m * DM + c) = w; } } }
	v_pk_mul_f32 v[132:133], v[68:69], v[132:133]
	v_pk_mul_f32 v[134:135], v[70:71], v[134:135]
	v_pk_fma_f32 v[132:133], v[196:197], v[132:133], v[212:213]
	v_pk_fma_f32 v[134:135], v[198:199], v[134:135], v[214:215]
	v_cvt_pk_bf16_f32 v246, v132, v133
	v_cvt_pk_bf16_f32 v247, v134, v135
	global_store_dwordx4 v82, v[244:247], s[46:47] offset:0
	v_pk_mul_f32 v[136:137], v[136:137], v[236:237] op_sel_hi:[1,0]
	v_pk_mul_f32 v[138:139], v[138:139], v[236:237] op_sel_hi:[1,0]
	v_pk_mul_f32 v[136:137], v[72:73], v[136:137]
	v_pk_mul_f32 v[138:139], v[74:75], v[138:139]
	v_pk_fma_f32 v[136:137], v[200:201], v[136:137], v[216:217]
	v_pk_fma_f32 v[138:139], v[202:203], v[138:139], v[218:219]
	v_cvt_pk_bf16_f32 v240, v136, v137
	v_cvt_pk_bf16_f32 v241, v138, v139
	v_pk_mul_f32 v[140:141], v[140:141], v[236:237] op_sel_hi:[1,0]
	v_pk_mul_f32 v[142:143], v[142:143], v[236:237] op_sel_hi:[1,0]
	v_pk_mul_f32 v[140:141], v[76:77], v[140:141]
	v_pk_mul_f32 v[142:143], v[78:79], v[142:143]
	v_pk_fma_f32 v[140:141], v[204:205], v[140:141], v[220:221]
	v_pk_fma_f32 v[142:143], v[206:207], v[142:143], v[222:223]
	v_cvt_pk_bf16_f32 v242, v140, v141
	v_cvt_pk_bf16_f32 v243, v142, v143
	global_store_dwordx4 v82, v[240:243], s[46:47] offset:1024
	v_pk_mul_f32 v[144:145], v[144:145], v[238:239] op_sel_hi:[1,0]
	v_pk_mul_f32 v[146:147], v[146:147], v[238:239] op_sel_hi:[1,0]
	v_pk_mul_f32 v[144:145], v[64:65], v[144:145]
	v_pk_mul_f32 v[146:147], v[66:67], v[146:147]
	v_pk_fma_f32 v[144:145], v[192:193], v[144:145], v[208:209]
	v_pk_fma_f32 v[146:147], v[194:195], v[146:147], v[210:211]
	v_cvt_pk_bf16_f32 v244, v144, v145
	v_cvt_pk_bf16_f32 v245, v146, v147
	v_pk_mul_f32 v[148:149], v[148:149], v[238:239] op_sel_hi:[1,0]
	v_pk_mul_f32 v[150:151], v[150:151], v[238:239] op_sel_hi:[1,0]
	v_pk_mul_f32 v[148:149], v[68:69], v[148:149]
	v_pk_mul_f32 v[150:151], v[70:71], v[150:151]
	v_pk_fma_f32 v[148:149], v[196:197], v[148:149], v[212:213]
	v_pk_fma_f32 v[150:151], v[198:199], v[150:151], v[214:215]
	v_cvt_pk_bf16_f32 v246, v148, v149
	v_cvt_pk_bf16_f32 v247, v150, v151
	global_store_dwordx4 v82, v[244:247], s[48:49] offset:0
	v_pk_mul_f32 v[152:153], v[152:153], v[238:239] op_sel_hi:[1,0]
	v_pk_mul_f32 v[154:155], v[154:155], v[238:239] op_sel_hi:[1,0]
	v_pk_mul_f32 v[152:153], v[72:73], v[152:153]
	v_pk_mul_f32 v[154:155], v[74:75], v[154:155]
	v_pk_fma_f32 v[152:153], v[200:201], v[152:153], v[216:217]
	v_pk_fma_f32 v[154:155], v[202:203], v[154:155], v[218:219]
	v_cvt_pk_bf16_f32 v240, v152, v153
	v_cvt_pk_bf16_f32 v241, v154, v155
	v_pk_mul_f32 v[156:157], v[156:157], v[238:239] op_sel_hi:[1,0]
	v_pk_mul_f32 v[158:159], v[158:159], v[238:239] op_sel_hi:[1,0]
	v_pk_mul_f32 v[156:157], v[76:77], v[156:157]
	v_pk_mul_f32 v[158:159], v[78:79], v[158:159]
	v_pk_fma_f32 v[156:157], v[204:205], v[156:157], v[220:221]
	v_pk_fma_f32 v[158:159], v[206:207], v[158:159], v[222:223]
	v_cvt_pk_bf16_f32 v242, v156, v157
	v_cvt_pk_bf16_f32 v243, v158, v159
	global_store_dwordx4 v82, v[240:243], s[48:49] offset:1024
	s_branch .LBB0_116
.Lorig_prep1:
	s_load_dwordx4 s[8:11], s[2:3], 0x0
	s_load_dwordx2 s[6:7], s[2:3], 0x38
	v_mbcnt_lo_u32_b32 v1, -1, 0
	v_mbcnt_hi_u32_b32 v1, -1, v1
	v_and_b32_e32 v2, 64, v1
	v_add_u32_e32 v2, 64, v2
	v_xor_b32_e32 v3, 1, v1
	v_mov_b32_e32 v65, 0
	v_cmp_lt_i32_e32 vcc, v3, v2
	v_lshlrev_b32_e32 v64, 4, v94
	s_waitcnt lgkmcnt(0)
	v_lshl_add_u64 v[66:67], s[6:7], 0, v[64:65]
	v_cndmask_b32_e32 v3, v1, v3, vcc
	v_lshlrev_b32_e32 v64, 3, v94
	v_lshlrev_b32_e32 v73, 2, v3
	v_xor_b32_e32 v3, 2, v1
	v_lshl_add_u64 v[8:9], s[4:5], 0, v[64:65]
	s_mov_b64 s[2:3], 0x3000000
	v_cmp_lt_i32_e32 vcc, v3, v2
	v_lshl_add_u64 v[68:69], v[8:9], 0, s[2:3]
	s_add_i32 s2, s42, s81
	v_cndmask_b32_e32 v3, v1, v3, vcc
	s_ashr_i32 s3, s2, 31
	s_lshl_b32 s14, s70, 5
	v_lshlrev_b32_e32 v74, 2, v3
	v_xor_b32_e32 v3, 4, v1
	s_lshl_b32 s45, s70, 4
	s_lshl_b64 s[2:3], s[2:3], 11
	v_cmp_lt_i32_e32 vcc, v3, v2
	s_add_u32 s18, s4, s2
	s_addc_u32 s19, s5, s3
	v_cndmask_b32_e32 v3, v1, v3, vcc
	s_ashr_i32 s15, s14, 31
	v_lshlrev_b32_e32 v75, 2, v3
	v_xor_b32_e32 v3, 8, v1
	s_lshl_b64 s[20:21], s[14:15], 11
	s_ashr_i32 s3, s43, 31
	s_ashr_i32 s6, s33, 31
	v_cmp_lt_i32_e32 vcc, v3, v2
	s_add_u32 s2, s43, s33
	s_addc_u32 s3, s3, s6
	v_cndmask_b32_e32 v3, v1, v3, vcc
	v_lshlrev_b32_e32 v76, 2, v3
	v_xor_b32_e32 v3, 16, v1
	s_lshl_b64 s[6:7], s[2:3], 12
	v_cmp_lt_i32_e32 vcc, v3, v2
	s_add_u32 s47, s8, s6
	s_addc_u32 s48, s9, s7
	v_cndmask_b32_e32 v3, v1, v3, vcc
	s_lshl_b64 s[22:23], s[14:15], 12
	s_lshl_b64 s[2:3], s[2:3], 11
	v_lshlrev_b32_e32 v77, 2, v3
	v_xor_b32_e32 v3, 32, v1
	s_add_u32 s2, s4, s2
	v_lshlrev_b32_e32 v0, 2, v94
	v_cmp_lt_i32_e32 vcc, v3, v2
	s_addc_u32 s3, s5, s3
	v_or_b32_e32 v2, 0x100, v0
	v_cndmask_b32_e32 v1, v1, v3, vcc
	v_or_b32_e32 v4, 0x200, v0
	v_or_b32_e32 v6, 0x300, v0
	s_add_u32 s24, s2, 0x3000400
	s_mov_b32 s17, 0
	v_lshlrev_b32_e32 v78, 2, v1
	s_mul_i32 s46, s70, 24
	s_addc_u32 s25, s3, 0
	v_lshlrev_b32_e32 v79, 2, v0
	v_mov_b32_e32 v80, 0x358637bd
	s_mov_b32 s15, 0xf800000
	v_mov_b32_e32 v81, 0x260
	v_lshlrev_b32_e32 v82, 2, v2
	v_lshlrev_b32_e32 v83, 2, v4
	v_lshlrev_b32_e32 v84, 2, v6
	s_mov_b32 s49, 0x3000000
	s_mov_b32 s50, s42
	s_branch .LBB0_110

; __device__ __forceinline__ void kraw_items(const Args& a, int gw, int NGW, int lane) {
;     const float* H3 = (const float*)(a.ws + WS_H3); float* KR = (float*)(a.ws + WS_KRAW);
;     for (int it = gw; it < 192 * 32; it += NGW) {
;         const int pg = it >> 5, cgp = it & 31, p = pg * 64 + lane, c0 = cgp * 48;
;         float h[64];
; #pragma unroll
;         for (int q = 0; q < 16; ++q) { const f32x4 t = *(const f32x4*)(H3 + (size_t)p * 64 + 4 * q); h[4 * q] = t.x; h[4 * q + 1] = t.y; h[4 * q + 2] = t.z; h[4 * q + 3] = t.w; }
;         const int grp = p >= LP, tpos = p - grp * LP, L = grp ? LS : LP;
;         const float tt = (float)tpos * (1.0f / (float)(L - 1));
; #pragma unroll 1
;         for (int cb = 0; cb < 4; ++cb) {
;             const float* wr = a.in[I_FWOUT] + lane * 1536 + c0 + 12 * cb;
;             const f32x4 w0 = *(const f32x4*)(wr), w1 = *(const f32x4*)(wr + 4), w2 = *(const f32x4*)(wr + 8);
;             float wv[12] = {w0.x, w0.y, w0.z, w0.w, w1.x, w1.y, w1.z, w1.w, w2.x, w2.y, w2.z, w2.w};
.LBB0_116:
	s_cmp_eq_u32 s70, 0x100
	s_cbranch_scc0 .Lorig_kraw
	s_load_dwordx2 s[6:7], s[72:73], 0x90
	s_load_dwordx2 s[8:9], s[72:73], 0xe8
	v_and_b32_e32 v119, 63, v254
	v_and_b32_e32 v112, 31, v119
	v_lshrrev_b32_e32 v113, 5, v119
	v_lshlrev_b32_e32 v114, 8, v112
	v_lshl_add_u32 v114, v113, 7, v114
	v_mul_u32_u24_e32 v115, 0x30000, v113
	v_lshl_add_u32 v115, v112, 2, v115
	v_lshlrev_b32_e32 v118, 2, v113
	v_readfirstlane_b32 s16, v254
	s_nop 3
	s_lshl_b32 s30, s96, 3
	s_lshr_b32 s16, s16, 6
	s_add_i32 s16, s16, s30
	v_mov_b32_e32 v120, 0xc0447cbd
	s_waitcnt lgkmcnt(0)
	s_add_u32 s10, s8, 0x100000
	s_addc_u32 s11, s9, 0
	s_add_u32 s14, s8, 0x37000000
	s_addc_u32 s15, s9, 0
	s_mov_b32 s17, s16
	s_lshr_b32 s18, s17, 4
	s_and_b32 s19, s17, 15
	s_lshl_b32 s20, s18, 5
	s_mul_i32 s21, s19, 0x60
	s_lshl_b32 s30, s20, 8
	s_add_u32 s24, s10, s30
	s_addc_u32 s25, s11, 0
	global_load_dwordx4 v[0:3], v114, s[24:25] offset:0
	global_load_dwordx4 v[4:7], v114, s[24:25] offset:16
	global_load_dwordx4 v[8:11], v114, s[24:25] offset:32
	global_load_dwordx4 v[12:15], v114, s[24:25] offset:48
	global_load_dwordx4 v[16:19], v114, s[24:25] offset:64
	global_load_dwordx4 v[20:23], v114, s[24:25] offset:80
	global_load_dwordx4 v[24:27], v114, s[24:25] offset:96
	global_load_dwordx4 v[28:31], v114, s[24:25] offset:112
	s_add_i32 s30, s21, 0
	s_lshl_b32 s30, s30, 2
	s_add_u32 s26, s6, s30
	s_addc_u32 s27, s7, 0
	global_load_dword v64, v115, s[26:27]
	s_add_u32 s26, s26, 0x1800
	s_addc_u32 s27, s27, 0
	global_load_dword v65, v115, s[26:27]
	s_add_u32 s26, s26, 0x1800
	s_addc_u32 s27, s27, 0
	global_load_dword v66, v115, s[26:27]
	s_add_u32 s26, s26, 0x1800
	s_addc_u32 s27, s27, 0
	global_load_dword v67, v115, s[26:27]
	s_add_u32 s26, s26, 0x1800
	s_addc_u32 s27, s27, 0
	global_load_dword v68, v115, s[26:27]
	s_add_u32 s26, s26, 0x1800
	s_addc_u32 s27, s27, 0
	global_load_dword v69, v115, s[26:27]
	s_add_u32 s26, s26, 0x1800
	s_addc_u32 s27, s27, 0
	global_load_dword v70, v115, s[26:27]
	s_add_u32 s26, s26, 0x1800
	s_addc_u32 s27, s27, 0
	global_load_dword v71, v115, s[26:27]
	s_add_u32 s26, s26, 0x1800
	s_addc_u32 s27, s27, 0
	global_load_dword v72, v115, s[26:27]
	s_add_u32 s26, s26, 0x1800
	s_addc_u32 s27, s27, 0
	global_load_dword v73, v115, s[26:27]
	s_add_u32 s26, s26, 0x1800
	s_addc_u32 s27, s27, 0
	global_load_dword v74, v115, s[26:27]
	s_add_u32 s26, s26, 0x1800
	s_addc_u32 s27, s27, 0
	global_load_dword v75, v115, s[26:27]
	s_add_u32 s26, s26, 0x1800
	s_addc_u32 s27, s27, 0
	global_load_dword v76, v115, s[26:27]
	s_add_u32 s26, s26, 0x1800
	s_addc_u32 s27, s27, 0
	global_load_dword v77, v115, s[26:27]
	s_add_u32 s26, s26, 0x1800
	s_addc_u32 s27, s27, 0
	global_load_dword v78, v115, s[26:27]
	s_add_u32 s26, s26, 0x1800
	s_addc_u32 s27, s27, 0
	global_load_dword v79, v115, s[26:27]
	s_add_u32 s26, s26, 0x1800
	s_addc_u32 s27, s27, 0
	global_load_dword v80, v115, s[26:27]
	s_add_u32 s26, s26, 0x1800
	s_addc_u32 s27, s27, 0
	global_load_dword v81, v115, s[26:27]
	s_add_u32 s26, s26, 0x1800
	s_addc_u32 s27, s27, 0
	global_load_dword v82, v115, s[26:27]
	s_add_u32 s26, s26, 0x1800
	s_addc_u32 s27, s27, 0
	global_load_dword v83, v115, s[26:27]
	s_add_u32 s26, s26, 0x1800
	s_addc_u32 s27, s27, 0
	global_load_dword v84, v115, s[26:27]
	s_add_u32 s26, s26, 0x1800
	s_addc_u32 s27, s27, 0
	global_load_dword v85, v115, s[26:27]
	s_add_u32 s26, s26, 0x1800
	s_addc_u32 s27, s27, 0
	global_load_dword v86, v115, s[26:27]
	s_add_u32 s26, s26, 0x1800
	s_addc_u32 s27, s27, 0
	global_load_dword v87, v115, s[26:27]
	s_add_u32 s26, s26, 0x1800
	s_addc_u32 s27, s27, 0
	global_load_dword v88, v115, s[26:27]
	s_add_u32 s26, s26, 0x1800
	s_addc_u32 s27, s27, 0
	global_load_dword v89, v115, s[26:27]
	s_add_u32 s26, s26, 0x1800
	s_addc_u32 s27, s27, 0
	global_load_dword v90, v115, s[26:27]
	s_add_u32 s26, s26, 0x1800
	s_addc_u32 s27, s27, 0
	global_load_dword v91, v115, s[26:27]
	s_add_u32 s26, s26, 0x1800
	s_addc_u32 s27, s27, 0
	global_load_dword v92, v115, s[26:27]
	s_add_u32 s26, s26, 0x1800
	s_addc_u32 s27, s27, 0
	global_load_dword v93, v115, s[26:27]
	s_add_u32 s26, s26, 0x1800
	s_addc_u32 s27, s27, 0
	global_load_dword v94, v115, s[26:27]
	s_add_u32 s26, s26, 0x1800
	s_addc_u32 s27, s27, 0
	global_load_dword v95, v115, s[26:27]
	s_add_i32 s28, s21, 0
	s_sub_i32 s29, s28, 0x300
	s_cmp_ge_u32 s28, 0x300
	s_cselect_b32 s29, s29, s28
	s_mul_i32 s30, s28, 0xc000
	s_lshl_b32 s35, s20, 2
	s_add_u32 s30, s30, s35
	s_add_u32 s34, s14, s30
	s_addc_u32 s35, s15, 0
	s_mov_b32 s22, 0xb9000400
	s_cmp_ge_u32 s20, 0x2000
	s_cselect_b32 s22, 0xb9800801, s22
	s_and_b32 s30, s20, 0x1fff
	v_add_u32_e32 v119, s30, v112
	v_cvt_f32_u32_e32 v119, v119
	v_mul_f32_e32 v117, s22, v119
	s_add_i32 s30, s21, 32
	s_lshl_b32 s30, s30, 2
	s_add_u32 s26, s6, s30
	s_addc_u32 s27, s7, 0
	global_load_dword v128, v115, s[26:27]
	s_add_u32 s26, s26, 0x1800
	s_addc_u32 s27, s27, 0
	global_load_dword v129, v115, s[26:27]
	s_add_u32 s26, s26, 0x1800
	s_addc_u32 s27, s27, 0
	global_load_dword v130, v115, s[26:27]
	s_add_u32 s26, s26, 0x1800
	s_addc_u32 s27, s27, 0
	global_load_dword v131, v115, s[26:27]
	s_add_u32 s26, s26, 0x1800
	s_addc_u32 s27, s27, 0
	global_load_dword v132, v115, s[26:27]
	s_add_u32 s26, s26, 0x1800
	s_addc_u32 s27, s27, 0
	global_load_dword v133, v115, s[26:27]
	s_add_u32 s26, s26, 0x1800
	s_addc_u32 s27, s27, 0
	global_load_dword v134, v115, s[26:27]
	s_add_u32 s26, s26, 0x1800
	s_addc_u32 s27, s27, 0
	global_load_dword v135, v115, s[26:27]
	s_add_u32 s26, s26, 0x1800
	s_addc_u32 s27, s27, 0
	global_load_dword v136, v115, s[26:27]
	s_add_u32 s26, s26, 0x1800
	s_addc_u32 s27, s27, 0
; __device__ __forceinline__ void kraw_items(const Args& a, int gw, int NGW, int lane) {
;     ...
;         float h[64];
; #pragma unroll
;         for (int q = 0; q < 16; ++q) { const f32x4 t = *(const f32x4*)(H3 + (size_t)p * 64 + 4 * q); h[4 * q] = t.x; h[4 * q + 1] = t.y; h[4 * q + 2] = t.z; h[4 * q + 3] = t.w; }
;         const int grp = p >= LP, tpos = p - grp * LP, L = grp ? LS : LP;
;         const float tt = (float)tpos * (1.0f / (float)(L - 1));
; #pragma unroll 1
;         for (int cb = 0; cb < 4; ++cb) {
;             const float* wr = a.in[I_FWOUT] + lane * 1536 + c0 + 12 * cb;
;             const f32x4 w0 = *(const f32x4*)(wr), w1 = *(const f32x4*)(wr + 4), w2 = *(const f32x4*)(wr + 8);
;             float wv[12] = {w0.x, w0.y, w0.z, w0.w, w1.x, w1.y, w1.z, w1.w, w2.x, w2.y, w2.z, w2.w};
; #pragma unroll
;             for (int ci = 0; ci < 12; ++ci) { const int c = c0 + 12 * cb + ci;
;                 float acc = 0.f;
; #pragma unroll
;                 for (int jj = 0; jj < 64; ++jj) acc += h[jj] * __builtin_bit_cast(float, __builtin_amdgcn_readlane(__builtin_bit_cast(int, wv[ci]), jj));
;                 const int cm = c % 768;
;                 const float delta = fabsf(-3.0701134573253945f + (float)cm * ((-15.350567286626973f + 3.0701134573253945f) / 767.0f));
;                 KR[(size_t)c * (LP + LS) + p] = acc * __expf(-tt * delta); }
	global_load_dword v137, v115, s[26:27]
	s_add_u32 s26, s26, 0x1800
	s_addc_u32 s27, s27, 0
	global_load_dword v138, v115, s[26:27]
	s_add_u32 s26, s26, 0x1800
	s_addc_u32 s27, s27, 0
	global_load_dword v139, v115, s[26:27]
	s_add_u32 s26, s26, 0x1800
	s_addc_u32 s27, s27, 0
	global_load_dword v140, v115, s[26:27]
	s_add_u32 s26, s26, 0x1800
	s_addc_u32 s27, s27, 0
	global_load_dword v141, v115, s[26:27]
	s_add_u32 s26, s26, 0x1800
	s_addc_u32 s27, s27, 0
	global_load_dword v142, v115, s[26:27]
	s_add_u32 s26, s26, 0x1800
	s_addc_u32 s27, s27, 0
	global_load_dword v143, v115, s[26:27]
	s_add_u32 s26, s26, 0x1800
	s_addc_u32 s27, s27, 0
	global_load_dword v144, v115, s[26:27]
	s_add_u32 s26, s26, 0x1800
	s_addc_u32 s27, s27, 0
	global_load_dword v145, v115, s[26:27]
	s_add_u32 s26, s26, 0x1800
	s_addc_u32 s27, s27, 0
	global_load_dword v146, v115, s[26:27]
	s_add_u32 s26, s26, 0x1800
	s_addc_u32 s27, s27, 0
	global_load_dword v147, v115, s[26:27]
	s_add_u32 s26, s26, 0x1800
	s_addc_u32 s27, s27, 0
	global_load_dword v148, v115, s[26:27]
	s_add_u32 s26, s26, 0x1800
	s_addc_u32 s27, s27, 0
	global_load_dword v149, v115, s[26:27]
	s_add_u32 s26, s26, 0x1800
	s_addc_u32 s27, s27, 0
	global_load_dword v150, v115, s[26:27]
	s_add_u32 s26, s26, 0x1800
	s_addc_u32 s27, s27, 0
	global_load_dword v151, v115, s[26:27]
	s_add_u32 s26, s26, 0x1800
	s_addc_u32 s27, s27, 0
	global_load_dword v152, v115, s[26:27]
	s_add_u32 s26, s26, 0x1800
	s_addc_u32 s27, s27, 0
	global_load_dword v153, v115, s[26:27]
	s_add_u32 s26, s26, 0x1800
	s_addc_u32 s27, s27, 0
	global_load_dword v154, v115, s[26:27]
	s_add_u32 s26, s26, 0x1800
	s_addc_u32 s27, s27, 0
	global_load_dword v155, v115, s[26:27]
	s_add_u32 s26, s26, 0x1800
	s_addc_u32 s27, s27, 0
	global_load_dword v156, v115, s[26:27]
	s_add_u32 s26, s26, 0x1800
	s_addc_u32 s27, s27, 0
	global_load_dword v157, v115, s[26:27]
	s_add_u32 s26, s26, 0x1800
	s_addc_u32 s27, s27, 0
	global_load_dword v158, v115, s[26:27]
	s_add_u32 s26, s26, 0x1800
	s_addc_u32 s27, s27, 0
	global_load_dword v159, v115, s[26:27]
	s_waitcnt vmcnt(32)
	v_mfma_f32_32x32x2_f32 v[96:111], v64, v0, 0
	v_mfma_f32_32x32x2_f32 v[96:111], v65, v1, v[96:111]
	v_mfma_f32_32x32x2_f32 v[96:111], v66, v2, v[96:111]
	v_mfma_f32_32x32x2_f32 v[96:111], v67, v3, v[96:111]
	v_mfma_f32_32x32x2_f32 v[96:111], v68, v4, v[96:111]
	v_mfma_f32_32x32x2_f32 v[96:111], v69, v5, v[96:111]
	v_mfma_f32_32x32x2_f32 v[96:111], v70, v6, v[96:111]
	v_mfma_f32_32x32x2_f32 v[96:111], v71, v7, v[96:111]
	v_mfma_f32_32x32x2_f32 v[96:111], v72, v8, v[96:111]
	v_mfma_f32_32x32x2_f32 v[96:111], v73, v9, v[96:111]
	v_mfma_f32_32x32x2_f32 v[96:111], v74, v10, v[96:111]
	v_mfma_f32_32x32x2_f32 v[96:111], v75, v11, v[96:111]
	v_mfma_f32_32x32x2_f32 v[96:111], v76, v12, v[96:111]
	v_mfma_f32_32x32x2_f32 v[96:111], v77, v13, v[96:111]
	v_mfma_f32_32x32x2_f32 v[96:111], v78, v14, v[96:111]
	v_mfma_f32_32x32x2_f32 v[96:111], v79, v15, v[96:111]
	v_mfma_f32_32x32x2_f32 v[96:111], v80, v16, v[96:111]
	v_mfma_f32_32x32x2_f32 v[96:111], v81, v17, v[96:111]
	v_mfma_f32_32x32x2_f32 v[96:111], v82, v18, v[96:111]
	v_mfma_f32_32x32x2_f32 v[96:111], v83, v19, v[96:111]
	v_mfma_f32_32x32x2_f32 v[96:111], v84, v20, v[96:111]
	v_mfma_f32_32x32x2_f32 v[96:111], v85, v21, v[96:111]
	v_mfma_f32_32x32x2_f32 v[96:111], v86, v22, v[96:111]
	v_mfma_f32_32x32x2_f32 v[96:111], v87, v23, v[96:111]
	v_mfma_f32_32x32x2_f32 v[96:111], v88, v24, v[96:111]
	v_mfma_f32_32x32x2_f32 v[96:111], v89, v25, v[96:111]
	v_mfma_f32_32x32x2_f32 v[96:111], v90, v26, v[96:111]
	v_mfma_f32_32x32x2_f32 v[96:111], v91, v27, v[96:111]
	v_mfma_f32_32x32x2_f32 v[96:111], v92, v28, v[96:111]
	v_mfma_f32_32x32x2_f32 v[96:111], v93, v29, v[96:111]
	v_mfma_f32_32x32x2_f32 v[96:111], v94, v30, v[96:111]
	v_mfma_f32_32x32x2_f32 v[96:111], v95, v31, v[96:111]
	s_add_i32 s30, s29, 0
	v_add_u32_e32 v119, s30, v118
	v_cvt_f32_u32_e32 v119, v119
	v_fmamk_f32 v119, v119, 0xbc83298c, v120
	v_mul_f32_e64 v119, v117, |v119|
	v_mul_f32_e32 v119, 0x3fb8aa3b, v119
	v_exp_f32_e32 v160, v119
	s_add_i32 s30, s29, 1
	v_add_u32_e32 v119, s30, v118
	v_cvt_f32_u32_e32 v119, v119
	v_fmamk_f32 v119, v119, 0xbc83298c, v120
	v_mul_f32_e64 v119, v117, |v119|
	v_mul_f32_e32 v119, 0x3fb8aa3b, v119
	v_exp_f32_e32 v161, v119
	s_add_i32 s30, s29, 2
	v_add_u32_e32 v119, s30, v118
	v_cvt_f32_u32_e32 v119, v119
	v_fmamk_f32 v119, v119, 0xbc83298c, v120
	v_mul_f32_e64 v119, v117, |v119|
	v_mul_f32_e32 v119, 0x3fb8aa3b, v119
	v_exp_f32_e32 v162, v119
	s_add_i32 s30, s29, 3
	v_add_u32_e32 v119, s30, v118
	v_cvt_f32_u32_e32 v119, v119
	v_fmamk_f32 v119, v119, 0xbc83298c, v120
	v_mul_f32_e64 v119, v117, |v119|
	v_mul_f32_e32 v119, 0x3fb8aa3b, v119
	v_exp_f32_e32 v163, v119
	s_add_i32 s30, s29, 8
	v_add_u32_e32 v119, s30, v118
	v_cvt_f32_u32_e32 v119, v119
	v_fmamk_f32 v119, v119, 0xbc83298c, v120
	v_mul_f32_e64 v119, v117, |v119|
	v_mul_f32_e32 v119, 0x3fb8aa3b, v119
	v_exp_f32_e32 v164, v119
	s_add_i32 s30, s29, 9
	v_add_u32_e32 v119, s30, v118
	v_cvt_f32_u32_e32 v119, v119
	v_fmamk_f32 v119, v119, 0xbc83298c, v120
	v_mul_f32_e64 v119, v117, |v119|
	v_mul_f32_e32 v119, 0x3fb8aa3b, v119
	v_exp_f32_e32 v165, v119
	s_add_i32 s30, s29, 10
	v_add_u32_e32 v119, s30, v118
	v_cvt_f32_u32_e32 v119, v119
	v_fmamk_f32 v119, v119, 0xbc83298c, v120
	v_mul_f32_e64 v119, v117, |v119|
	v_mul_f32_e32 v119, 0x3fb8aa3b, v119
	v_exp_f32_e32 v166, v119
	s_add_i32 s30, s29, 11
	v_add_u32_e32 v119, s30, v118
	v_cvt_f32_u32_e32 v119, v119
	v_fmamk_f32 v119, v119, 0xbc83298c, v120
	v_mul_f32_e64 v119, v117, |v119|
	v_mul_f32_e32 v119, 0x3fb8aa3b, v119
	v_exp_f32_e32 v167, v119
	s_add_i32 s30, s29, 16
; __device__ __forceinline__ void kraw_items(const Args& a, int gw, int NGW, int lane) {
;     ...
;             for (int ci = 0; ci < 12; ++ci) { const int c = c0 + 12 * cb + ci;
;                 float acc = 0.f;
; #pragma unroll
;                 for (int jj = 0; jj < 64; ++jj) acc += h[jj] * __builtin_bit_cast(float, __builtin_amdgcn_readlane(__builtin_bit_cast(int, wv[ci]), jj));
;                 const int cm = c % 768;
;                 const float delta = fabsf(-3.0701134573253945f + (float)cm * ((-15.350567286626973f + 3.0701134573253945f) / 767.0f));
;                 KR[(size_t)c * (LP + LS) + p] = acc * __expf(-tt * delta); }
	v_add_u32_e32 v119, s30, v118
	v_cvt_f32_u32_e32 v119, v119
	v_fmamk_f32 v119, v119, 0xbc83298c, v120
	v_mul_f32_e64 v119, v117, |v119|
	v_mul_f32_e32 v119, 0x3fb8aa3b, v119
	v_exp_f32_e32 v168, v119
	s_add_i32 s30, s29, 17
	v_add_u32_e32 v119, s30, v118
	v_cvt_f32_u32_e32 v119, v119
	v_fmamk_f32 v119, v119, 0xbc83298c, v120
	v_mul_f32_e64 v119, v117, |v119|
	v_mul_f32_e32 v119, 0x3fb8aa3b, v119
	v_exp_f32_e32 v169, v119
	s_add_i32 s30, s29, 18
	v_add_u32_e32 v119, s30, v118
	v_cvt_f32_u32_e32 v119, v119
	v_fmamk_f32 v119, v119, 0xbc83298c, v120
	v_mul_f32_e64 v119, v117, |v119|
	v_mul_f32_e32 v119, 0x3fb8aa3b, v119
	v_exp_f32_e32 v170, v119
	s_add_i32 s30, s29, 19
	v_add_u32_e32 v119, s30, v118
	v_cvt_f32_u32_e32 v119, v119
	v_fmamk_f32 v119, v119, 0xbc83298c, v120
	v_mul_f32_e64 v119, v117, |v119|
	v_mul_f32_e32 v119, 0x3fb8aa3b, v119
	v_exp_f32_e32 v171, v119
	s_add_i32 s30, s29, 24
	v_add_u32_e32 v119, s30, v118
	v_cvt_f32_u32_e32 v119, v119
	v_fmamk_f32 v119, v119, 0xbc83298c, v120
	v_mul_f32_e64 v119, v117, |v119|
	v_mul_f32_e32 v119, 0x3fb8aa3b, v119
	v_exp_f32_e32 v172, v119
	s_add_i32 s30, s29, 25
	v_add_u32_e32 v119, s30, v118
	v_cvt_f32_u32_e32 v119, v119
	v_fmamk_f32 v119, v119, 0xbc83298c, v120
	v_mul_f32_e64 v119, v117, |v119|
	v_mul_f32_e32 v119, 0x3fb8aa3b, v119
	v_exp_f32_e32 v173, v119
	s_add_i32 s30, s29, 26
	v_add_u32_e32 v119, s30, v118
	v_cvt_f32_u32_e32 v119, v119
	v_fmamk_f32 v119, v119, 0xbc83298c, v120
	v_mul_f32_e64 v119, v117, |v119|
	v_mul_f32_e32 v119, 0x3fb8aa3b, v119
	v_exp_f32_e32 v174, v119
	s_add_i32 s30, s29, 27
	v_add_u32_e32 v119, s30, v118
	v_cvt_f32_u32_e32 v119, v119
	v_fmamk_f32 v119, v119, 0xbc83298c, v120
	v_mul_f32_e64 v119, v117, |v119|
	v_mul_f32_e32 v119, 0x3fb8aa3b, v119
	v_exp_f32_e32 v175, v119
	s_nop 7
	v_mul_f32_e32 v176, v96, v160
	s_mov_b64 s[36:37], s[34:35]
	global_store_dword v115, v176, s[36:37]
	v_mul_f32_e32 v177, v97, v161
	s_add_u32 s36, s34, 0xc000
	s_addc_u32 s37, s35, 0
	global_store_dword v115, v177, s[36:37]
	v_mul_f32_e32 v178, v98, v162
	s_add_u32 s36, s34, 0x18000
	s_addc_u32 s37, s35, 0
	global_store_dword v115, v178, s[36:37]
	v_mul_f32_e32 v179, v99, v163
	s_add_u32 s36, s34, 0x24000
	s_addc_u32 s37, s35, 0
	global_store_dword v115, v179, s[36:37]
	v_mul_f32_e32 v180, v100, v164
	s_add_u32 s36, s34, 0x60000
	s_addc_u32 s37, s35, 0
	global_store_dword v115, v180, s[36:37]
	v_mul_f32_e32 v181, v101, v165
	s_add_u32 s36, s34, 0x6c000
	s_addc_u32 s37, s35, 0
	global_store_dword v115, v181, s[36:37]
	v_mul_f32_e32 v182, v102, v166
	s_add_u32 s36, s34, 0x78000
	s_addc_u32 s37, s35, 0
	global_store_dword v115, v182, s[36:37]
	v_mul_f32_e32 v183, v103, v167
	s_add_u32 s36, s34, 0x84000
	s_addc_u32 s37, s35, 0
	global_store_dword v115, v183, s[36:37]
	v_mul_f32_e32 v184, v104, v168
	s_add_u32 s36, s34, 0xc0000
	s_addc_u32 s37, s35, 0
	global_store_dword v115, v184, s[36:37]
	v_mul_f32_e32 v185, v105, v169
	s_add_u32 s36, s34, 0xcc000
	s_addc_u32 s37, s35, 0
	global_store_dword v115, v185, s[36:37]
	v_mul_f32_e32 v186, v106, v170
	s_add_u32 s36, s34, 0xd8000
	s_addc_u32 s37, s35, 0
	global_store_dword v115, v186, s[36:37]
	v_mul_f32_e32 v187, v107, v171
	s_add_u32 s36, s34, 0xe4000
	s_addc_u32 s37, s35, 0
	global_store_dword v115, v187, s[36:37]
	v_mul_f32_e32 v188, v108, v172
	s_add_u32 s36, s34, 0x120000
	s_addc_u32 s37, s35, 0
	global_store_dword v115, v188, s[36:37]
	v_mul_f32_e32 v189, v109, v173
	s_add_u32 s36, s34, 0x12c000
	s_addc_u32 s37, s35, 0
	global_store_dword v115, v189, s[36:37]
	v_mul_f32_e32 v190, v110, v174
	s_add_u32 s36, s34, 0x138000
	s_addc_u32 s37, s35, 0
	global_store_dword v115, v190, s[36:37]
	v_mul_f32_e32 v191, v111, v175
	s_add_u32 s36, s34, 0x144000
	s_addc_u32 s37, s35, 0
	global_store_dword v115, v191, s[36:37]
	s_add_i32 s28, s21, 32
	s_sub_i32 s29, s28, 0x300
	s_cmp_ge_u32 s28, 0x300
	s_cselect_b32 s29, s29, s28
	s_mul_i32 s30, s28, 0xc000
	s_lshl_b32 s35, s20, 2
	s_add_u32 s30, s30, s35
	s_add_u32 s34, s14, s30
	s_addc_u32 s35, s15, 0
	s_add_i32 s30, s21, 64
	s_lshl_b32 s30, s30, 2
	s_add_u32 s26, s6, s30
	s_addc_u32 s27, s7, 0
	global_load_dword v64, v115, s[26:27]
	s_add_u32 s26, s26, 0x1800
	s_addc_u32 s27, s27, 0
	global_load_dword v65, v115, s[26:27]
	s_add_u32 s26, s26, 0x1800
	s_addc_u32 s27, s27, 0
	global_load_dword v66, v115, s[26:27]
	s_add_u32 s26, s26, 0x1800
	s_addc_u32 s27, s27, 0
	global_load_dword v67, v115, s[26:27]
	s_add_u32 s26, s26, 0x1800
	s_addc_u32 s27, s27, 0
	global_load_dword v68, v115, s[26:27]
	s_add_u32 s26, s26, 0x1800
	s_addc_u32 s27, s27, 0
	global_load_dword v69, v115, s[26:27]
	s_add_u32 s26, s26, 0x1800
	s_addc_u32 s27, s27, 0
	global_load_dword v70, v115, s[26:27]
	s_add_u32 s26, s26, 0x1800
	s_addc_u32 s27, s27, 0
	global_load_dword v71, v115, s[26:27]
	s_add_u32 s26, s26, 0x1800
	s_addc_u32 s27, s27, 0
	global_load_dword v72, v115, s[26:27]
	s_add_u32 s26, s26, 0x1800
	s_addc_u32 s27, s27, 0
	global_load_dword v73, v115, s[26:27]
	s_add_u32 s26, s26, 0x1800
	s_addc_u32 s27, s27, 0
	global_load_dword v74, v115, s[26:27]
	s_add_u32 s26, s26, 0x1800
	s_addc_u32 s27, s27, 0
	global_load_dword v75, v115, s[26:27]
	s_add_u32 s26, s26, 0x1800
	s_addc_u32 s27, s27, 0
	global_load_dword v76, v115, s[26:27]
	s_add_u32 s26, s26, 0x1800
	s_addc_u32 s27, s27, 0
	global_load_dword v77, v115, s[26:27]
	s_add_u32 s26, s26, 0x1800
	s_addc_u32 s27, s27, 0
	global_load_dword v78, v115, s[26:27]
	s_add_u32 s26, s26, 0x1800
	s_addc_u32 s27, s27, 0
	global_load_dword v79, v115, s[26:27]
	s_add_u32 s26, s26, 0x1800
	s_addc_u32 s27, s27, 0
	global_load_dword v80, v115, s[26:27]
	s_add_u32 s26, s26, 0x1800
	s_addc_u32 s27, s27, 0
	global_load_dword v81, v115, s[26:27]
	s_add_u32 s26, s26, 0x1800
	s_addc_u32 s27, s27, 0
	global_load_dword v82, v115, s[26:27]
	s_add_u32 s26, s26, 0x1800
	s_addc_u32 s27, s27, 0
	global_load_dword v83, v115, s[26:27]
	s_add_u32 s26, s26, 0x1800
	s_addc_u32 s27, s27, 0
	global_load_dword v84, v115, s[26:27]
	s_add_u32 s26, s26, 0x1800
	s_addc_u32 s27, s27, 0
	global_load_dword v85, v115, s[26:27]
	s_add_u32 s26, s26, 0x1800
	s_addc_u32 s27, s27, 0
	global_load_dword v86, v115, s[26:27]
	s_add_u32 s26, s26, 0x1800
	s_addc_u32 s27, s27, 0
	global_load_dword v87, v115, s[26:27]
	s_add_u32 s26, s26, 0x1800
	s_addc_u32 s27, s27, 0
	global_load_dword v88, v115, s[26:27]
	s_add_u32 s26, s26, 0x1800
	s_addc_u32 s27, s27, 0
	global_load_dword v89, v115, s[26:27]
	s_add_u32 s26, s26, 0x1800
	s_addc_u32 s27, s27, 0
	global_load_dword v90, v115, s[26:27]
	s_add_u32 s26, s26, 0x1800
	s_addc_u32 s27, s27, 0
	global_load_dword v91, v115, s[26:27]
	s_add_u32 s26, s26, 0x1800
	s_addc_u32 s27, s27, 0
	global_load_dword v92, v115, s[26:27]
	s_add_u32 s26, s26, 0x1800
	s_addc_u32 s27, s27, 0
	global_load_dword v93, v115, s[26:27]
	s_add_u32 s26, s26, 0x1800
	s_addc_u32 s27, s27, 0
	global_load_dword v94, v115, s[26:27]
	s_add_u32 s26, s26, 0x1800
	s_addc_u32 s27, s27, 0
	global_load_dword v95, v115, s[26:27]
	s_waitcnt vmcnt(48)
; __device__ __forceinline__ void kraw_items(const Args& a, int gw, int NGW, int lane) {
;     ...
;             for (int ci = 0; ci < 12; ++ci) { const int c = c0 + 12 * cb + ci;
;                 float acc = 0.f;
; #pragma unroll
;                 for (int jj = 0; jj < 64; ++jj) acc += h[jj] * __builtin_bit_cast(float, __builtin_amdgcn_readlane(__builtin_bit_cast(int, wv[ci]), jj));
;                 const int cm = c % 768;
;                 const float delta = fabsf(-3.0701134573253945f + (float)cm * ((-15.350567286626973f + 3.0701134573253945f) / 767.0f));
;                 KR[(size_t)c * (LP + LS) + p] = acc * __expf(-tt * delta); }
	v_mfma_f32_32x32x2_f32 v[96:111], v128, v0, 0
	v_mfma_f32_32x32x2_f32 v[96:111], v129, v1, v[96:111]
	v_mfma_f32_32x32x2_f32 v[96:111], v130, v2, v[96:111]
	v_mfma_f32_32x32x2_f32 v[96:111], v131, v3, v[96:111]
	v_mfma_f32_32x32x2_f32 v[96:111], v132, v4, v[96:111]
	v_mfma_f32_32x32x2_f32 v[96:111], v133, v5, v[96:111]
	v_mfma_f32_32x32x2_f32 v[96:111], v134, v6, v[96:111]
	v_mfma_f32_32x32x2_f32 v[96:111], v135, v7, v[96:111]
	v_mfma_f32_32x32x2_f32 v[96:111], v136, v8, v[96:111]
	v_mfma_f32_32x32x2_f32 v[96:111], v137, v9, v[96:111]
	v_mfma_f32_32x32x2_f32 v[96:111], v138, v10, v[96:111]
	v_mfma_f32_32x32x2_f32 v[96:111], v139, v11, v[96:111]
	v_mfma_f32_32x32x2_f32 v[96:111], v140, v12, v[96:111]
	v_mfma_f32_32x32x2_f32 v[96:111], v141, v13, v[96:111]
	v_mfma_f32_32x32x2_f32 v[96:111], v142, v14, v[96:111]
	v_mfma_f32_32x32x2_f32 v[96:111], v143, v15, v[96:111]
	v_mfma_f32_32x32x2_f32 v[96:111], v144, v16, v[96:111]
	v_mfma_f32_32x32x2_f32 v[96:111], v145, v17, v[96:111]
	v_mfma_f32_32x32x2_f32 v[96:111], v146, v18, v[96:111]
	v_mfma_f32_32x32x2_f32 v[96:111], v147, v19, v[96:111]
	v_mfma_f32_32x32x2_f32 v[96:111], v148, v20, v[96:111]
	v_mfma_f32_32x32x2_f32 v[96:111], v149, v21, v[96:111]
	v_mfma_f32_32x32x2_f32 v[96:111], v150, v22, v[96:111]
	v_mfma_f32_32x32x2_f32 v[96:111], v151, v23, v[96:111]
	v_mfma_f32_32x32x2_f32 v[96:111], v152, v24, v[96:111]
	v_mfma_f32_32x32x2_f32 v[96:111], v153, v25, v[96:111]
	v_mfma_f32_32x32x2_f32 v[96:111], v154, v26, v[96:111]
	v_mfma_f32_32x32x2_f32 v[96:111], v155, v27, v[96:111]
	v_mfma_f32_32x32x2_f32 v[96:111], v156, v28, v[96:111]
	v_mfma_f32_32x32x2_f32 v[96:111], v157, v29, v[96:111]
	v_mfma_f32_32x32x2_f32 v[96:111], v158, v30, v[96:111]
	v_mfma_f32_32x32x2_f32 v[96:111], v159, v31, v[96:111]
	s_add_i32 s30, s29, 0
	v_add_u32_e32 v119, s30, v118
	v_cvt_f32_u32_e32 v119, v119
	v_fmamk_f32 v119, v119, 0xbc83298c, v120
	v_mul_f32_e64 v119, v117, |v119|
	v_mul_f32_e32 v119, 0x3fb8aa3b, v119
	v_exp_f32_e32 v160, v119
	s_add_i32 s30, s29, 1
	v_add_u32_e32 v119, s30, v118
	v_cvt_f32_u32_e32 v119, v119
	v_fmamk_f32 v119, v119, 0xbc83298c, v120
	v_mul_f32_e64 v119, v117, |v119|
	v_mul_f32_e32 v119, 0x3fb8aa3b, v119
	v_exp_f32_e32 v161, v119
	s_add_i32 s30, s29, 2
	v_add_u32_e32 v119, s30, v118
	v_cvt_f32_u32_e32 v119, v119
	v_fmamk_f32 v119, v119, 0xbc83298c, v120
	v_mul_f32_e64 v119, v117, |v119|
	v_mul_f32_e32 v119, 0x3fb8aa3b, v119
	v_exp_f32_e32 v162, v119
	s_add_i32 s30, s29, 3
	v_add_u32_e32 v119, s30, v118
	v_cvt_f32_u32_e32 v119, v119
	v_fmamk_f32 v119, v119, 0xbc83298c, v120
	v_mul_f32_e64 v119, v117, |v119|
	v_mul_f32_e32 v119, 0x3fb8aa3b, v119
	v_exp_f32_e32 v163, v119
	s_add_i32 s30, s29, 8
	v_add_u32_e32 v119, s30, v118
	v_cvt_f32_u32_e32 v119, v119
	v_fmamk_f32 v119, v119, 0xbc83298c, v120
	v_mul_f32_e64 v119, v117, |v119|
	v_mul_f32_e32 v119, 0x3fb8aa3b, v119
	v_exp_f32_e32 v164, v119
	s_add_i32 s30, s29, 9
	v_add_u32_e32 v119, s30, v118
	v_cvt_f32_u32_e32 v119, v119
	v_fmamk_f32 v119, v119, 0xbc83298c, v120
	v_mul_f32_e64 v119, v117, |v119|
	v_mul_f32_e32 v119, 0x3fb8aa3b, v119
	v_exp_f32_e32 v165, v119
	s_add_i32 s30, s29, 10
	v_add_u32_e32 v119, s30, v118
	v_cvt_f32_u32_e32 v119, v119
	v_fmamk_f32 v119, v119, 0xbc83298c, v120
	v_mul_f32_e64 v119, v117, |v119|
	v_mul_f32_e32 v119, 0x3fb8aa3b, v119
	v_exp_f32_e32 v166, v119
	s_add_i32 s30, s29, 11
	v_add_u32_e32 v119, s30, v118
	v_cvt_f32_u32_e32 v119, v119
	v_fmamk_f32 v119, v119, 0xbc83298c, v120
	v_mul_f32_e64 v119, v117, |v119|
	v_mul_f32_e32 v119, 0x3fb8aa3b, v119
	v_exp_f32_e32 v167, v119
	s_add_i32 s30, s29, 16
	v_add_u32_e32 v119, s30, v118
	v_cvt_f32_u32_e32 v119, v119
	v_fmamk_f32 v119, v119, 0xbc83298c, v120
	v_mul_f32_e64 v119, v117, |v119|
	v_mul_f32_e32 v119, 0x3fb8aa3b, v119
	v_exp_f32_e32 v168, v119
	s_add_i32 s30, s29, 17
	v_add_u32_e32 v119, s30, v118
	v_cvt_f32_u32_e32 v119, v119
	v_fmamk_f32 v119, v119, 0xbc83298c, v120
	v_mul_f32_e64 v119, v117, |v119|
	v_mul_f32_e32 v119, 0x3fb8aa3b, v119
	v_exp_f32_e32 v169, v119
	s_add_i32 s30, s29, 18
	v_add_u32_e32 v119, s30, v118
	v_cvt_f32_u32_e32 v119, v119
	v_fmamk_f32 v119, v119, 0xbc83298c, v120
	v_mul_f32_e64 v119, v117, |v119|
	v_mul_f32_e32 v119, 0x3fb8aa3b, v119
	v_exp_f32_e32 v170, v119
	s_add_i32 s30, s29, 19
	v_add_u32_e32 v119, s30, v118
	v_cvt_f32_u32_e32 v119, v119
	v_fmamk_f32 v119, v119, 0xbc83298c, v120
	v_mul_f32_e64 v119, v117, |v119|
	v_mul_f32_e32 v119, 0x3fb8aa3b, v119
	v_exp_f32_e32 v171, v119
	s_add_i32 s30, s29, 24
	v_add_u32_e32 v119, s30, v118
	v_cvt_f32_u32_e32 v119, v119
	v_fmamk_f32 v119, v119, 0xbc83298c, v120
	v_mul_f32_e64 v119, v117, |v119|
	v_mul_f32_e32 v119, 0x3fb8aa3b, v119
	v_exp_f32_e32 v172, v119
	s_add_i32 s30, s29, 25
	v_add_u32_e32 v119, s30, v118
	v_cvt_f32_u32_e32 v119, v119
	v_fmamk_f32 v119, v119, 0xbc83298c, v120
	v_mul_f32_e64 v119, v117, |v119|
	v_mul_f32_e32 v119, 0x3fb8aa3b, v119
	v_exp_f32_e32 v173, v119
	s_add_i32 s30, s29, 26
	v_add_u32_e32 v119, s30, v118
	v_cvt_f32_u32_e32 v119, v119
	v_fmamk_f32 v119, v119, 0xbc83298c, v120
	v_mul_f32_e64 v119, v117, |v119|
	v_mul_f32_e32 v119, 0x3fb8aa3b, v119
	v_exp_f32_e32 v174, v119
	s_add_i32 s30, s29, 27
	v_add_u32_e32 v119, s30, v118
	v_cvt_f32_u32_e32 v119, v119
	v_fmamk_f32 v119, v119, 0xbc83298c, v120
	v_mul_f32_e64 v119, v117, |v119|
	v_mul_f32_e32 v119, 0x3fb8aa3b, v119
	v_exp_f32_e32 v175, v119
	s_nop 7
	v_mul_f32_e32 v176, v96, v160
	s_mov_b64 s[36:37], s[34:35]
	global_store_dword v115, v176, s[36:37]
	v_mul_f32_e32 v177, v97, v161
	s_add_u32 s36, s34, 0xc000
	s_addc_u32 s37, s35, 0
	global_store_dword v115, v177, s[36:37]
	v_mul_f32_e32 v178, v98, v162
; __device__ __forceinline__ void kraw_items(const Args& a, int gw, int NGW, int lane) {
;     ...
;     for (int it = gw; it < 192 * 32; it += NGW) {
;         const int pg = it >> 5, cgp = it & 31, p = pg * 64 + lane, c0 = cgp * 48;
;         float h[64];
; #pragma unroll
;         for (int q = 0; q < 16; ++q) { const f32x4 t = *(const f32x4*)(H3 + (size_t)p * 64 + 4 * q); h[4 * q] = t.x; h[4 * q + 1] = t.y; h[4 * q + 2] = t.z; h[4 * q + 3] = t.w; }
;     ...
;             for (int ci = 0; ci < 12; ++ci) { const int c = c0 + 12 * cb + ci;
;                 float acc = 0.f;
; #pragma unroll
;                 for (int jj = 0; jj < 64; ++jj) acc += h[jj] * __builtin_bit_cast(float, __builtin_amdgcn_readlane(__builtin_bit_cast(int, wv[ci]), jj));
;                 const int cm = c % 768;
;                 const float delta = fabsf(-3.0701134573253945f + (float)cm * ((-15.350567286626973f + 3.0701134573253945f) / 767.0f));
;                 KR[(size_t)c * (LP + LS) + p] = acc * __expf(-tt * delta); }
	s_add_u32 s36, s34, 0x18000
	s_addc_u32 s37, s35, 0
	global_store_dword v115, v178, s[36:37]
	v_mul_f32_e32 v179, v99, v163
	s_add_u32 s36, s34, 0x24000
	s_addc_u32 s37, s35, 0
	global_store_dword v115, v179, s[36:37]
	v_mul_f32_e32 v180, v100, v164
	s_add_u32 s36, s34, 0x60000
	s_addc_u32 s37, s35, 0
	global_store_dword v115, v180, s[36:37]
	v_mul_f32_e32 v181, v101, v165
	s_add_u32 s36, s34, 0x6c000
	s_addc_u32 s37, s35, 0
	global_store_dword v115, v181, s[36:37]
	v_mul_f32_e32 v182, v102, v166
	s_add_u32 s36, s34, 0x78000
	s_addc_u32 s37, s35, 0
	global_store_dword v115, v182, s[36:37]
	v_mul_f32_e32 v183, v103, v167
	s_add_u32 s36, s34, 0x84000
	s_addc_u32 s37, s35, 0
	global_store_dword v115, v183, s[36:37]
	v_mul_f32_e32 v184, v104, v168
	s_add_u32 s36, s34, 0xc0000
	s_addc_u32 s37, s35, 0
	global_store_dword v115, v184, s[36:37]
	v_mul_f32_e32 v185, v105, v169
	s_add_u32 s36, s34, 0xcc000
	s_addc_u32 s37, s35, 0
	global_store_dword v115, v185, s[36:37]
	v_mul_f32_e32 v186, v106, v170
	s_add_u32 s36, s34, 0xd8000
	s_addc_u32 s37, s35, 0
	global_store_dword v115, v186, s[36:37]
	v_mul_f32_e32 v187, v107, v171
	s_add_u32 s36, s34, 0xe4000
	s_addc_u32 s37, s35, 0
	global_store_dword v115, v187, s[36:37]
	v_mul_f32_e32 v188, v108, v172
	s_add_u32 s36, s34, 0x120000
	s_addc_u32 s37, s35, 0
	global_store_dword v115, v188, s[36:37]
	v_mul_f32_e32 v189, v109, v173
	s_add_u32 s36, s34, 0x12c000
	s_addc_u32 s37, s35, 0
	global_store_dword v115, v189, s[36:37]
	v_mul_f32_e32 v190, v110, v174
	s_add_u32 s36, s34, 0x138000
	s_addc_u32 s37, s35, 0
	global_store_dword v115, v190, s[36:37]
	v_mul_f32_e32 v191, v111, v175
	s_add_u32 s36, s34, 0x144000
	s_addc_u32 s37, s35, 0
	global_store_dword v115, v191, s[36:37]
	s_add_i32 s28, s21, 64
	s_sub_i32 s29, s28, 0x300
	s_cmp_ge_u32 s28, 0x300
	s_cselect_b32 s29, s29, s28
	s_mul_i32 s30, s28, 0xc000
	s_lshl_b32 s35, s20, 2
	s_add_u32 s30, s30, s35
	s_add_u32 s34, s14, s30
	s_addc_u32 s35, s15, 0
	s_add_i32 s17, s16, 0x800
	s_lshr_b32 s18, s17, 4
	s_and_b32 s19, s17, 15
	s_lshl_b32 s20, s18, 5
	s_mul_i32 s21, s19, 0x60
	s_lshl_b32 s30, s20, 8
	s_add_u32 s24, s10, s30
	s_addc_u32 s25, s11, 0
	global_load_dwordx4 v[32:35], v114, s[24:25] offset:0
	global_load_dwordx4 v[36:39], v114, s[24:25] offset:16
	global_load_dwordx4 v[40:43], v114, s[24:25] offset:32
	global_load_dwordx4 v[44:47], v114, s[24:25] offset:48
	global_load_dwordx4 v[48:51], v114, s[24:25] offset:64
	global_load_dwordx4 v[52:55], v114, s[24:25] offset:80
	global_load_dwordx4 v[56:59], v114, s[24:25] offset:96
	global_load_dwordx4 v[60:63], v114, s[24:25] offset:112
	s_add_i32 s30, s21, 0
	s_lshl_b32 s30, s30, 2
	s_add_u32 s26, s6, s30
	s_addc_u32 s27, s7, 0
	global_load_dword v128, v115, s[26:27]
	s_add_u32 s26, s26, 0x1800
	s_addc_u32 s27, s27, 0
	global_load_dword v129, v115, s[26:27]
	s_add_u32 s26, s26, 0x1800
	s_addc_u32 s27, s27, 0
	global_load_dword v130, v115, s[26:27]
	s_add_u32 s26, s26, 0x1800
	s_addc_u32 s27, s27, 0
	global_load_dword v131, v115, s[26:27]
	s_add_u32 s26, s26, 0x1800
	s_addc_u32 s27, s27, 0
	global_load_dword v132, v115, s[26:27]
	s_add_u32 s26, s26, 0x1800
	s_addc_u32 s27, s27, 0
	global_load_dword v133, v115, s[26:27]
	s_add_u32 s26, s26, 0x1800
	s_addc_u32 s27, s27, 0
	global_load_dword v134, v115, s[26:27]
	s_add_u32 s26, s26, 0x1800
	s_addc_u32 s27, s27, 0
	global_load_dword v135, v115, s[26:27]
	s_add_u32 s26, s26, 0x1800
	s_addc_u32 s27, s27, 0
	global_load_dword v136, v115, s[26:27]
	s_add_u32 s26, s26, 0x1800
	s_addc_u32 s27, s27, 0
	global_load_dword v137, v115, s[26:27]
	s_add_u32 s26, s26, 0x1800
	s_addc_u32 s27, s27, 0
	global_load_dword v138, v115, s[26:27]
	s_add_u32 s26, s26, 0x1800
	s_addc_u32 s27, s27, 0
	global_load_dword v139, v115, s[26:27]
	s_add_u32 s26, s26, 0x1800
	s_addc_u32 s27, s27, 0
	global_load_dword v140, v115, s[26:27]
	s_add_u32 s26, s26, 0x1800
	s_addc_u32 s27, s27, 0
	global_load_dword v141, v115, s[26:27]
	s_add_u32 s26, s26, 0x1800
	s_addc_u32 s27, s27, 0
	global_load_dword v142, v115, s[26:27]
	s_add_u32 s26, s26, 0x1800
	s_addc_u32 s27, s27, 0
	global_load_dword v143, v115, s[26:27]
	s_add_u32 s26, s26, 0x1800
	s_addc_u32 s27, s27, 0
	global_load_dword v144, v115, s[26:27]
	s_add_u32 s26, s26, 0x1800
	s_addc_u32 s27, s27, 0
	global_load_dword v145, v115, s[26:27]
	s_add_u32 s26, s26, 0x1800
	s_addc_u32 s27, s27, 0
	global_load_dword v146, v115, s[26:27]
	s_add_u32 s26, s26, 0x1800
	s_addc_u32 s27, s27, 0
	global_load_dword v147, v115, s[26:27]
	s_add_u32 s26, s26, 0x1800
	s_addc_u32 s27, s27, 0
	global_load_dword v148, v115, s[26:27]
	s_add_u32 s26, s26, 0x1800
	s_addc_u32 s27, s27, 0
	global_load_dword v149, v115, s[26:27]
	s_add_u32 s26, s26, 0x1800
	s_addc_u32 s27, s27, 0
	global_load_dword v150, v115, s[26:27]
	s_add_u32 s26, s26, 0x1800
	s_addc_u32 s27, s27, 0
	global_load_dword v151, v115, s[26:27]
	s_add_u32 s26, s26, 0x1800
	s_addc_u32 s27, s27, 0
	global_load_dword v152, v115, s[26:27]
	s_add_u32 s26, s26, 0x1800
	s_addc_u32 s27, s27, 0
	global_load_dword v153, v115, s[26:27]
	s_add_u32 s26, s26, 0x1800
	s_addc_u32 s27, s27, 0
	global_load_dword v154, v115, s[26:27]
	s_add_u32 s26, s26, 0x1800
	s_addc_u32 s27, s27, 0
	global_load_dword v155, v115, s[26:27]
	s_add_u32 s26, s26, 0x1800
	s_addc_u32 s27, s27, 0
	global_load_dword v156, v115, s[26:27]
	s_add_u32 s26, s26, 0x1800
	s_addc_u32 s27, s27, 0
	global_load_dword v157, v115, s[26:27]
	s_add_u32 s26, s26, 0x1800
	s_addc_u32 s27, s27, 0
	global_load_dword v158, v115, s[26:27]
	s_add_u32 s26, s26, 0x1800
	s_addc_u32 s27, s27, 0
	global_load_dword v159, v115, s[26:27]
	s_waitcnt vmcnt(56)
; __device__ __forceinline__ void kraw_items(const Args& a, int gw, int NGW, int lane) {
;     ...
;             for (int ci = 0; ci < 12; ++ci) { const int c = c0 + 12 * cb + ci;
;                 float acc = 0.f;
; #pragma unroll
;                 for (int jj = 0; jj < 64; ++jj) acc += h[jj] * __builtin_bit_cast(float, __builtin_amdgcn_readlane(__builtin_bit_cast(int, wv[ci]), jj));
;                 const int cm = c % 768;
;                 const float delta = fabsf(-3.0701134573253945f + (float)cm * ((-15.350567286626973f + 3.0701134573253945f) / 767.0f));
;                 KR[(size_t)c * (LP + LS) + p] = acc * __expf(-tt * delta); }
	v_mfma_f32_32x32x2_f32 v[96:111], v64, v0, 0
	v_mfma_f32_32x32x2_f32 v[96:111], v65, v1, v[96:111]
	v_mfma_f32_32x32x2_f32 v[96:111], v66, v2, v[96:111]
	v_mfma_f32_32x32x2_f32 v[96:111], v67, v3, v[96:111]
	v_mfma_f32_32x32x2_f32 v[96:111], v68, v4, v[96:111]
	v_mfma_f32_32x32x2_f32 v[96:111], v69, v5, v[96:111]
	v_mfma_f32_32x32x2_f32 v[96:111], v70, v6, v[96:111]
	v_mfma_f32_32x32x2_f32 v[96:111], v71, v7, v[96:111]
	v_mfma_f32_32x32x2_f32 v[96:111], v72, v8, v[96:111]
	v_mfma_f32_32x32x2_f32 v[96:111], v73, v9, v[96:111]
	v_mfma_f32_32x32x2_f32 v[96:111], v74, v10, v[96:111]
	v_mfma_f32_32x32x2_f32 v[96:111], v75, v11, v[96:111]
	v_mfma_f32_32x32x2_f32 v[96:111], v76, v12, v[96:111]
	v_mfma_f32_32x32x2_f32 v[96:111], v77, v13, v[96:111]
	v_mfma_f32_32x32x2_f32 v[96:111], v78, v14, v[96:111]
	v_mfma_f32_32x32x2_f32 v[96:111], v79, v15, v[96:111]
	v_mfma_f32_32x32x2_f32 v[96:111], v80, v16, v[96:111]
	v_mfma_f32_32x32x2_f32 v[96:111], v81, v17, v[96:111]
	v_mfma_f32_32x32x2_f32 v[96:111], v82, v18, v[96:111]
	v_mfma_f32_32x32x2_f32 v[96:111], v83, v19, v[96:111]
	v_mfma_f32_32x32x2_f32 v[96:111], v84, v20, v[96:111]
	v_mfma_f32_32x32x2_f32 v[96:111], v85, v21, v[96:111]
	v_mfma_f32_32x32x2_f32 v[96:111], v86, v22, v[96:111]
	v_mfma_f32_32x32x2_f32 v[96:111], v87, v23, v[96:111]
	v_mfma_f32_32x32x2_f32 v[96:111], v88, v24, v[96:111]
	v_mfma_f32_32x32x2_f32 v[96:111], v89, v25, v[96:111]
	v_mfma_f32_32x32x2_f32 v[96:111], v90, v26, v[96:111]
	v_mfma_f32_32x32x2_f32 v[96:111], v91, v27, v[96:111]
	v_mfma_f32_32x32x2_f32 v[96:111], v92, v28, v[96:111]
	v_mfma_f32_32x32x2_f32 v[96:111], v93, v29, v[96:111]
	v_mfma_f32_32x32x2_f32 v[96:111], v94, v30, v[96:111]
	v_mfma_f32_32x32x2_f32 v[96:111], v95, v31, v[96:111]
	s_add_i32 s30, s29, 0
	v_add_u32_e32 v119, s30, v118
	v_cvt_f32_u32_e32 v119, v119
	v_fmamk_f32 v119, v119, 0xbc83298c, v120
	v_mul_f32_e64 v119, v117, |v119|
	v_mul_f32_e32 v119, 0x3fb8aa3b, v119
	v_exp_f32_e32 v160, v119
	s_add_i32 s30, s29, 1
	v_add_u32_e32 v119, s30, v118
	v_cvt_f32_u32_e32 v119, v119
	v_fmamk_f32 v119, v119, 0xbc83298c, v120
	v_mul_f32_e64 v119, v117, |v119|
	v_mul_f32_e32 v119, 0x3fb8aa3b, v119
	v_exp_f32_e32 v161, v119
	s_add_i32 s30, s29, 2
	v_add_u32_e32 v119, s30, v118
	v_cvt_f32_u32_e32 v119, v119
	v_fmamk_f32 v119, v119, 0xbc83298c, v120
	v_mul_f32_e64 v119, v117, |v119|
	v_mul_f32_e32 v119, 0x3fb8aa3b, v119
	v_exp_f32_e32 v162, v119
	s_add_i32 s30, s29, 3
	v_add_u32_e32 v119, s30, v118
	v_cvt_f32_u32_e32 v119, v119
	v_fmamk_f32 v119, v119, 0xbc83298c, v120
	v_mul_f32_e64 v119, v117, |v119|
	v_mul_f32_e32 v119, 0x3fb8aa3b, v119
	v_exp_f32_e32 v163, v119
	s_add_i32 s30, s29, 8
	v_add_u32_e32 v119, s30, v118
	v_cvt_f32_u32_e32 v119, v119
	v_fmamk_f32 v119, v119, 0xbc83298c, v120
	v_mul_f32_e64 v119, v117, |v119|
	v_mul_f32_e32 v119, 0x3fb8aa3b, v119
	v_exp_f32_e32 v164, v119
	s_add_i32 s30, s29, 9
	v_add_u32_e32 v119, s30, v118
	v_cvt_f32_u32_e32 v119, v119
	v_fmamk_f32 v119, v119, 0xbc83298c, v120
	v_mul_f32_e64 v119, v117, |v119|
	v_mul_f32_e32 v119, 0x3fb8aa3b, v119
	v_exp_f32_e32 v165, v119
	s_add_i32 s30, s29, 10
	v_add_u32_e32 v119, s30, v118
	v_cvt_f32_u32_e32 v119, v119
	v_fmamk_f32 v119, v119, 0xbc83298c, v120
	v_mul_f32_e64 v119, v117, |v119|
	v_mul_f32_e32 v119, 0x3fb8aa3b, v119
	v_exp_f32_e32 v166, v119
	s_add_i32 s30, s29, 11
	v_add_u32_e32 v119, s30, v118
	v_cvt_f32_u32_e32 v119, v119
	v_fmamk_f32 v119, v119, 0xbc83298c, v120
	v_mul_f32_e64 v119, v117, |v119|
	v_mul_f32_e32 v119, 0x3fb8aa3b, v119
	v_exp_f32_e32 v167, v119
	s_add_i32 s30, s29, 16
	v_add_u32_e32 v119, s30, v118
	v_cvt_f32_u32_e32 v119, v119
	v_fmamk_f32 v119, v119, 0xbc83298c, v120
	v_mul_f32_e64 v119, v117, |v119|
	v_mul_f32_e32 v119, 0x3fb8aa3b, v119
	v_exp_f32_e32 v168, v119
	s_add_i32 s30, s29, 17
	v_add_u32_e32 v119, s30, v118
	v_cvt_f32_u32_e32 v119, v119
	v_fmamk_f32 v119, v119, 0xbc83298c, v120
	v_mul_f32_e64 v119, v117, |v119|
	v_mul_f32_e32 v119, 0x3fb8aa3b, v119
	v_exp_f32_e32 v169, v119
	s_add_i32 s30, s29, 18
	v_add_u32_e32 v119, s30, v118
	v_cvt_f32_u32_e32 v119, v119
	v_fmamk_f32 v119, v119, 0xbc83298c, v120
	v_mul_f32_e64 v119, v117, |v119|
	v_mul_f32_e32 v119, 0x3fb8aa3b, v119
	v_exp_f32_e32 v170, v119
	s_add_i32 s30, s29, 19
	v_add_u32_e32 v119, s30, v118
	v_cvt_f32_u32_e32 v119, v119
	v_fmamk_f32 v119, v119, 0xbc83298c, v120
	v_mul_f32_e64 v119, v117, |v119|
	v_mul_f32_e32 v119, 0x3fb8aa3b, v119
	v_exp_f32_e32 v171, v119
	s_add_i32 s30, s29, 24
	v_add_u32_e32 v119, s30, v118
	v_cvt_f32_u32_e32 v119, v119
	v_fmamk_f32 v119, v119, 0xbc83298c, v120
	v_mul_f32_e64 v119, v117, |v119|
	v_mul_f32_e32 v119, 0x3fb8aa3b, v119
	v_exp_f32_e32 v172, v119
	s_add_i32 s30, s29, 25
	v_add_u32_e32 v119, s30, v118
	v_cvt_f32_u32_e32 v119, v119
	v_fmamk_f32 v119, v119, 0xbc83298c, v120
	v_mul_f32_e64 v119, v117, |v119|
	v_mul_f32_e32 v119, 0x3fb8aa3b, v119
	v_exp_f32_e32 v173, v119
	s_add_i32 s30, s29, 26
	v_add_u32_e32 v119, s30, v118
	v_cvt_f32_u32_e32 v119, v119
	v_fmamk_f32 v119, v119, 0xbc83298c, v120
	v_mul_f32_e64 v119, v117, |v119|
	v_mul_f32_e32 v119, 0x3fb8aa3b, v119
	v_exp_f32_e32 v174, v119
	s_add_i32 s30, s29, 27
	v_add_u32_e32 v119, s30, v118
	v_cvt_f32_u32_e32 v119, v119
	v_fmamk_f32 v119, v119, 0xbc83298c, v120
	v_mul_f32_e64 v119, v117, |v119|
	v_mul_f32_e32 v119, 0x3fb8aa3b, v119
	v_exp_f32_e32 v175, v119
	s_nop 7
	v_mul_f32_e32 v176, v96, v160
	s_mov_b64 s[36:37], s[34:35]
	global_store_dword v115, v176, s[36:37]
	v_mul_f32_e32 v177, v97, v161
	s_add_u32 s36, s34, 0xc000
	s_addc_u32 s37, s35, 0
	global_store_dword v115, v177, s[36:37]
	v_mul_f32_e32 v178, v98, v162
	s_add_u32 s36, s34, 0x18000
; __device__ __forceinline__ void kraw_items(const Args& a, int gw, int NGW, int lane) {
;     ...
;         const int grp = p >= LP, tpos = p - grp * LP, L = grp ? LS : LP;
;         const float tt = (float)tpos * (1.0f / (float)(L - 1));
; #pragma unroll 1
;         for (int cb = 0; cb < 4; ++cb) {
;             const float* wr = a.in[I_FWOUT] + lane * 1536 + c0 + 12 * cb;
;             const f32x4 w0 = *(const f32x4*)(wr), w1 = *(const f32x4*)(wr + 4), w2 = *(const f32x4*)(wr + 8);
;     ...
;             for (int ci = 0; ci < 12; ++ci) { const int c = c0 + 12 * cb + ci;
;                 float acc = 0.f;
; #pragma unroll
;                 for (int jj = 0; jj < 64; ++jj) acc += h[jj] * __builtin_bit_cast(float, __builtin_amdgcn_readlane(__builtin_bit_cast(int, wv[ci]), jj));
;                 const int cm = c % 768;
;                 const float delta = fabsf(-3.0701134573253945f + (float)cm * ((-15.350567286626973f + 3.0701134573253945f) / 767.0f));
;                 KR[(size_t)c * (LP + LS) + p] = acc * __expf(-tt * delta); }
	s_addc_u32 s37, s35, 0
	global_store_dword v115, v178, s[36:37]
	v_mul_f32_e32 v179, v99, v163
	s_add_u32 s36, s34, 0x24000
	s_addc_u32 s37, s35, 0
	global_store_dword v115, v179, s[36:37]
	v_mul_f32_e32 v180, v100, v164
	s_add_u32 s36, s34, 0x60000
	s_addc_u32 s37, s35, 0
	global_store_dword v115, v180, s[36:37]
	v_mul_f32_e32 v181, v101, v165
	s_add_u32 s36, s34, 0x6c000
	s_addc_u32 s37, s35, 0
	global_store_dword v115, v181, s[36:37]
	v_mul_f32_e32 v182, v102, v166
	s_add_u32 s36, s34, 0x78000
	s_addc_u32 s37, s35, 0
	global_store_dword v115, v182, s[36:37]
	v_mul_f32_e32 v183, v103, v167
	s_add_u32 s36, s34, 0x84000
	s_addc_u32 s37, s35, 0
	global_store_dword v115, v183, s[36:37]
	v_mul_f32_e32 v184, v104, v168
	s_add_u32 s36, s34, 0xc0000
	s_addc_u32 s37, s35, 0
	global_store_dword v115, v184, s[36:37]
	v_mul_f32_e32 v185, v105, v169
	s_add_u32 s36, s34, 0xcc000
	s_addc_u32 s37, s35, 0
	global_store_dword v115, v185, s[36:37]
	v_mul_f32_e32 v186, v106, v170
	s_add_u32 s36, s34, 0xd8000
	s_addc_u32 s37, s35, 0
	global_store_dword v115, v186, s[36:37]
	v_mul_f32_e32 v187, v107, v171
	s_add_u32 s36, s34, 0xe4000
	s_addc_u32 s37, s35, 0
	global_store_dword v115, v187, s[36:37]
	v_mul_f32_e32 v188, v108, v172
	s_add_u32 s36, s34, 0x120000
	s_addc_u32 s37, s35, 0
	global_store_dword v115, v188, s[36:37]
	v_mul_f32_e32 v189, v109, v173
	s_add_u32 s36, s34, 0x12c000
	s_addc_u32 s37, s35, 0
	global_store_dword v115, v189, s[36:37]
	v_mul_f32_e32 v190, v110, v174
	s_add_u32 s36, s34, 0x138000
	s_addc_u32 s37, s35, 0
	global_store_dword v115, v190, s[36:37]
	v_mul_f32_e32 v191, v111, v175
	s_add_u32 s36, s34, 0x144000
	s_addc_u32 s37, s35, 0
	global_store_dword v115, v191, s[36:37]
	s_add_i32 s28, s21, 0
	s_sub_i32 s29, s28, 0x300
	s_cmp_ge_u32 s28, 0x300
	s_cselect_b32 s29, s29, s28
	s_mul_i32 s30, s28, 0xc000
	s_lshl_b32 s35, s20, 2
	s_add_u32 s30, s30, s35
	s_add_u32 s34, s14, s30
	s_addc_u32 s35, s15, 0
	s_mov_b32 s22, 0xb9000400
	s_cmp_ge_u32 s20, 0x2000
	s_cselect_b32 s22, 0xb9800801, s22
	s_and_b32 s30, s20, 0x1fff
	v_add_u32_e32 v119, s30, v112
	v_cvt_f32_u32_e32 v119, v119
	v_mul_f32_e32 v117, s22, v119
	s_add_i32 s30, s21, 32
	s_lshl_b32 s30, s30, 2
	s_add_u32 s26, s6, s30
	s_addc_u32 s27, s7, 0
	global_load_dword v64, v115, s[26:27]
	s_add_u32 s26, s26, 0x1800
	s_addc_u32 s27, s27, 0
	global_load_dword v65, v115, s[26:27]
	s_add_u32 s26, s26, 0x1800
	s_addc_u32 s27, s27, 0
	global_load_dword v66, v115, s[26:27]
	s_add_u32 s26, s26, 0x1800
	s_addc_u32 s27, s27, 0
	global_load_dword v67, v115, s[26:27]
	s_add_u32 s26, s26, 0x1800
	s_addc_u32 s27, s27, 0
	global_load_dword v68, v115, s[26:27]
	s_add_u32 s26, s26, 0x1800
	s_addc_u32 s27, s27, 0
	global_load_dword v69, v115, s[26:27]
	s_add_u32 s26, s26, 0x1800
	s_addc_u32 s27, s27, 0
	global_load_dword v70, v115, s[26:27]
	s_add_u32 s26, s26, 0x1800
	s_addc_u32 s27, s27, 0
	global_load_dword v71, v115, s[26:27]
	s_add_u32 s26, s26, 0x1800
	s_addc_u32 s27, s27, 0
	global_load_dword v72, v115, s[26:27]
	s_add_u32 s26, s26, 0x1800
	s_addc_u32 s27, s27, 0
	global_load_dword v73, v115, s[26:27]
	s_add_u32 s26, s26, 0x1800
	s_addc_u32 s27, s27, 0
	global_load_dword v74, v115, s[26:27]
	s_add_u32 s26, s26, 0x1800
	s_addc_u32 s27, s27, 0
	global_load_dword v75, v115, s[26:27]
	s_add_u32 s26, s26, 0x1800
	s_addc_u32 s27, s27, 0
	global_load_dword v76, v115, s[26:27]
	s_add_u32 s26, s26, 0x1800
	s_addc_u32 s27, s27, 0
	global_load_dword v77, v115, s[26:27]
	s_add_u32 s26, s26, 0x1800
	s_addc_u32 s27, s27, 0
	global_load_dword v78, v115, s[26:27]
	s_add_u32 s26, s26, 0x1800
	s_addc_u32 s27, s27, 0
	global_load_dword v79, v115, s[26:27]
	s_add_u32 s26, s26, 0x1800
	s_addc_u32 s27, s27, 0
	global_load_dword v80, v115, s[26:27]
	s_add_u32 s26, s26, 0x1800
	s_addc_u32 s27, s27, 0
	global_load_dword v81, v115, s[26:27]
	s_add_u32 s26, s26, 0x1800
	s_addc_u32 s27, s27, 0
	global_load_dword v82, v115, s[26:27]
	s_add_u32 s26, s26, 0x1800
	s_addc_u32 s27, s27, 0
	global_load_dword v83, v115, s[26:27]
	s_add_u32 s26, s26, 0x1800
	s_addc_u32 s27, s27, 0
	global_load_dword v84, v115, s[26:27]
	s_add_u32 s26, s26, 0x1800
	s_addc_u32 s27, s27, 0
	global_load_dword v85, v115, s[26:27]
	s_add_u32 s26, s26, 0x1800
	s_addc_u32 s27, s27, 0
	global_load_dword v86, v115, s[26:27]
	s_add_u32 s26, s26, 0x1800
	s_addc_u32 s27, s27, 0
	global_load_dword v87, v115, s[26:27]
	s_add_u32 s26, s26, 0x1800
	s_addc_u32 s27, s27, 0
	global_load_dword v88, v115, s[26:27]
	s_add_u32 s26, s26, 0x1800
	s_addc_u32 s27, s27, 0
	global_load_dword v89, v115, s[26:27]
	s_add_u32 s26, s26, 0x1800
	s_addc_u32 s27, s27, 0
	global_load_dword v90, v115, s[26:27]
	s_add_u32 s26, s26, 0x1800
	s_addc_u32 s27, s27, 0
	global_load_dword v91, v115, s[26:27]
	s_add_u32 s26, s26, 0x1800
	s_addc_u32 s27, s27, 0
	global_load_dword v92, v115, s[26:27]
	s_add_u32 s26, s26, 0x1800
	s_addc_u32 s27, s27, 0
	global_load_dword v93, v115, s[26:27]
	s_add_u32 s26, s26, 0x1800
	s_addc_u32 s27, s27, 0
	global_load_dword v94, v115, s[26:27]
	s_add_u32 s26, s26, 0x1800
	s_addc_u32 s27, s27, 0
	global_load_dword v95, v115, s[26:27]
	s_waitcnt vmcnt(48)
; __device__ __forceinline__ void kraw_items(const Args& a, int gw, int NGW, int lane) {
;     ...
;             for (int ci = 0; ci < 12; ++ci) { const int c = c0 + 12 * cb + ci;
;                 float acc = 0.f;
; #pragma unroll
;                 for (int jj = 0; jj < 64; ++jj) acc += h[jj] * __builtin_bit_cast(float, __builtin_amdgcn_readlane(__builtin_bit_cast(int, wv[ci]), jj));
;                 const int cm = c % 768;
;                 const float delta = fabsf(-3.0701134573253945f + (float)cm * ((-15.350567286626973f + 3.0701134573253945f) / 767.0f));
;                 KR[(size_t)c * (LP + LS) + p] = acc * __expf(-tt * delta); }
	v_mfma_f32_32x32x2_f32 v[96:111], v128, v32, 0
	v_mfma_f32_32x32x2_f32 v[96:111], v129, v33, v[96:111]
	v_mfma_f32_32x32x2_f32 v[96:111], v130, v34, v[96:111]
	v_mfma_f32_32x32x2_f32 v[96:111], v131, v35, v[96:111]
	v_mfma_f32_32x32x2_f32 v[96:111], v132, v36, v[96:111]
	v_mfma_f32_32x32x2_f32 v[96:111], v133, v37, v[96:111]
	v_mfma_f32_32x32x2_f32 v[96:111], v134, v38, v[96:111]
	v_mfma_f32_32x32x2_f32 v[96:111], v135, v39, v[96:111]
	v_mfma_f32_32x32x2_f32 v[96:111], v136, v40, v[96:111]
	v_mfma_f32_32x32x2_f32 v[96:111], v137, v41, v[96:111]
	v_mfma_f32_32x32x2_f32 v[96:111], v138, v42, v[96:111]
	v_mfma_f32_32x32x2_f32 v[96:111], v139, v43, v[96:111]
	v_mfma_f32_32x32x2_f32 v[96:111], v140, v44, v[96:111]
	v_mfma_f32_32x32x2_f32 v[96:111], v141, v45, v[96:111]
	v_mfma_f32_32x32x2_f32 v[96:111], v142, v46, v[96:111]
	v_mfma_f32_32x32x2_f32 v[96:111], v143, v47, v[96:111]
	v_mfma_f32_32x32x2_f32 v[96:111], v144, v48, v[96:111]
	v_mfma_f32_32x32x2_f32 v[96:111], v145, v49, v[96:111]
	v_mfma_f32_32x32x2_f32 v[96:111], v146, v50, v[96:111]
	v_mfma_f32_32x32x2_f32 v[96:111], v147, v51, v[96:111]
	v_mfma_f32_32x32x2_f32 v[96:111], v148, v52, v[96:111]
	v_mfma_f32_32x32x2_f32 v[96:111], v149, v53, v[96:111]
	v_mfma_f32_32x32x2_f32 v[96:111], v150, v54, v[96:111]
	v_mfma_f32_32x32x2_f32 v[96:111], v151, v55, v[96:111]
	v_mfma_f32_32x32x2_f32 v[96:111], v152, v56, v[96:111]
	v_mfma_f32_32x32x2_f32 v[96:111], v153, v57, v[96:111]
	v_mfma_f32_32x32x2_f32 v[96:111], v154, v58, v[96:111]
	v_mfma_f32_32x32x2_f32 v[96:111], v155, v59, v[96:111]
	v_mfma_f32_32x32x2_f32 v[96:111], v156, v60, v[96:111]
	v_mfma_f32_32x32x2_f32 v[96:111], v157, v61, v[96:111]
	v_mfma_f32_32x32x2_f32 v[96:111], v158, v62, v[96:111]
	v_mfma_f32_32x32x2_f32 v[96:111], v159, v63, v[96:111]
	s_add_i32 s30, s29, 0
	v_add_u32_e32 v119, s30, v118
	v_cvt_f32_u32_e32 v119, v119
	v_fmamk_f32 v119, v119, 0xbc83298c, v120
	v_mul_f32_e64 v119, v117, |v119|
	v_mul_f32_e32 v119, 0x3fb8aa3b, v119
	v_exp_f32_e32 v160, v119
	s_add_i32 s30, s29, 1
	v_add_u32_e32 v119, s30, v118
	v_cvt_f32_u32_e32 v119, v119
	v_fmamk_f32 v119, v119, 0xbc83298c, v120
	v_mul_f32_e64 v119, v117, |v119|
	v_mul_f32_e32 v119, 0x3fb8aa3b, v119
	v_exp_f32_e32 v161, v119
	s_add_i32 s30, s29, 2
	v_add_u32_e32 v119, s30, v118
	v_cvt_f32_u32_e32 v119, v119
	v_fmamk_f32 v119, v119, 0xbc83298c, v120
	v_mul_f32_e64 v119, v117, |v119|
	v_mul_f32_e32 v119, 0x3fb8aa3b, v119
	v_exp_f32_e32 v162, v119
	s_add_i32 s30, s29, 3
	v_add_u32_e32 v119, s30, v118
	v_cvt_f32_u32_e32 v119, v119
	v_fmamk_f32 v119, v119, 0xbc83298c, v120
	v_mul_f32_e64 v119, v117, |v119|
	v_mul_f32_e32 v119, 0x3fb8aa3b, v119
	v_exp_f32_e32 v163, v119
	s_add_i32 s30, s29, 8
	v_add_u32_e32 v119, s30, v118
	v_cvt_f32_u32_e32 v119, v119
	v_fmamk_f32 v119, v119, 0xbc83298c, v120
	v_mul_f32_e64 v119, v117, |v119|
	v_mul_f32_e32 v119, 0x3fb8aa3b, v119
	v_exp_f32_e32 v164, v119
	s_add_i32 s30, s29, 9
	v_add_u32_e32 v119, s30, v118
	v_cvt_f32_u32_e32 v119, v119
	v_fmamk_f32 v119, v119, 0xbc83298c, v120
	v_mul_f32_e64 v119, v117, |v119|
	v_mul_f32_e32 v119, 0x3fb8aa3b, v119
	v_exp_f32_e32 v165, v119
	s_add_i32 s30, s29, 10
	v_add_u32_e32 v119, s30, v118
	v_cvt_f32_u32_e32 v119, v119
	v_fmamk_f32 v119, v119, 0xbc83298c, v120
	v_mul_f32_e64 v119, v117, |v119|
	v_mul_f32_e32 v119, 0x3fb8aa3b, v119
	v_exp_f32_e32 v166, v119
	s_add_i32 s30, s29, 11
	v_add_u32_e32 v119, s30, v118
	v_cvt_f32_u32_e32 v119, v119
	v_fmamk_f32 v119, v119, 0xbc83298c, v120
	v_mul_f32_e64 v119, v117, |v119|
	v_mul_f32_e32 v119, 0x3fb8aa3b, v119
	v_exp_f32_e32 v167, v119
	s_add_i32 s30, s29, 16
	v_add_u32_e32 v119, s30, v118
	v_cvt_f32_u32_e32 v119, v119
	v_fmamk_f32 v119, v119, 0xbc83298c, v120
	v_mul_f32_e64 v119, v117, |v119|
	v_mul_f32_e32 v119, 0x3fb8aa3b, v119
	v_exp_f32_e32 v168, v119
	s_add_i32 s30, s29, 17
	v_add_u32_e32 v119, s30, v118
	v_cvt_f32_u32_e32 v119, v119
	v_fmamk_f32 v119, v119, 0xbc83298c, v120
	v_mul_f32_e64 v119, v117, |v119|
	v_mul_f32_e32 v119, 0x3fb8aa3b, v119
	v_exp_f32_e32 v169, v119
	s_add_i32 s30, s29, 18
	v_add_u32_e32 v119, s30, v118
	v_cvt_f32_u32_e32 v119, v119
	v_fmamk_f32 v119, v119, 0xbc83298c, v120
	v_mul_f32_e64 v119, v117, |v119|
	v_mul_f32_e32 v119, 0x3fb8aa3b, v119
	v_exp_f32_e32 v170, v119
	s_add_i32 s30, s29, 19
	v_add_u32_e32 v119, s30, v118
	v_cvt_f32_u32_e32 v119, v119
	v_fmamk_f32 v119, v119, 0xbc83298c, v120
	v_mul_f32_e64 v119, v117, |v119|
	v_mul_f32_e32 v119, 0x3fb8aa3b, v119
	v_exp_f32_e32 v171, v119
	s_add_i32 s30, s29, 24
	v_add_u32_e32 v119, s30, v118
	v_cvt_f32_u32_e32 v119, v119
	v_fmamk_f32 v119, v119, 0xbc83298c, v120
	v_mul_f32_e64 v119, v117, |v119|
	v_mul_f32_e32 v119, 0x3fb8aa3b, v119
	v_exp_f32_e32 v172, v119
	s_add_i32 s30, s29, 25
	v_add_u32_e32 v119, s30, v118
	v_cvt_f32_u32_e32 v119, v119
	v_fmamk_f32 v119, v119, 0xbc83298c, v120
	v_mul_f32_e64 v119, v117, |v119|
	v_mul_f32_e32 v119, 0x3fb8aa3b, v119
	v_exp_f32_e32 v173, v119
	s_add_i32 s30, s29, 26
	v_add_u32_e32 v119, s30, v118
	v_cvt_f32_u32_e32 v119, v119
	v_fmamk_f32 v119, v119, 0xbc83298c, v120
	v_mul_f32_e64 v119, v117, |v119|
	v_mul_f32_e32 v119, 0x3fb8aa3b, v119
	v_exp_f32_e32 v174, v119
	s_add_i32 s30, s29, 27
	v_add_u32_e32 v119, s30, v118
	v_cvt_f32_u32_e32 v119, v119
	v_fmamk_f32 v119, v119, 0xbc83298c, v120
	v_mul_f32_e64 v119, v117, |v119|
	v_mul_f32_e32 v119, 0x3fb8aa3b, v119
	v_exp_f32_e32 v175, v119
	s_nop 7
	v_mul_f32_e32 v176, v96, v160
	s_mov_b64 s[36:37], s[34:35]
	global_store_dword v115, v176, s[36:37]
	v_mul_f32_e32 v177, v97, v161
	s_add_u32 s36, s34, 0xc000
	s_addc_u32 s37, s35, 0
	global_store_dword v115, v177, s[36:37]
	v_mul_f32_e32 v178, v98, v162
; __device__ __forceinline__ void kraw_items(const Args& a, int gw, int NGW, int lane) {
;     ...
; #pragma unroll 1
;         for (int cb = 0; cb < 4; ++cb) {
;             const float* wr = a.in[I_FWOUT] + lane * 1536 + c0 + 12 * cb;
;             const f32x4 w0 = *(const f32x4*)(wr), w1 = *(const f32x4*)(wr + 4), w2 = *(const f32x4*)(wr + 8);
;             float wv[12] = {w0.x, w0.y, w0.z, w0.w, w1.x, w1.y, w1.z, w1.w, w2.x, w2.y, w2.z, w2.w};
; #pragma unroll
;             for (int ci = 0; ci < 12; ++ci) { const int c = c0 + 12 * cb + ci;
;                 float acc = 0.f;
; #pragma unroll
;                 for (int jj = 0; jj < 64; ++jj) acc += h[jj] * __builtin_bit_cast(float, __builtin_amdgcn_readlane(__builtin_bit_cast(int, wv[ci]), jj));
;                 const int cm = c % 768;
;                 const float delta = fabsf(-3.0701134573253945f + (float)cm * ((-15.350567286626973f + 3.0701134573253945f) / 767.0f));
;                 KR[(size_t)c * (LP + LS) + p] = acc * __expf(-tt * delta); }
	s_add_u32 s36, s34, 0x18000
	s_addc_u32 s37, s35, 0
	global_store_dword v115, v178, s[36:37]
	v_mul_f32_e32 v179, v99, v163
	s_add_u32 s36, s34, 0x24000
	s_addc_u32 s37, s35, 0
	global_store_dword v115, v179, s[36:37]
	v_mul_f32_e32 v180, v100, v164
	s_add_u32 s36, s34, 0x60000
	s_addc_u32 s37, s35, 0
	global_store_dword v115, v180, s[36:37]
	v_mul_f32_e32 v181, v101, v165
	s_add_u32 s36, s34, 0x6c000
	s_addc_u32 s37, s35, 0
	global_store_dword v115, v181, s[36:37]
	v_mul_f32_e32 v182, v102, v166
	s_add_u32 s36, s34, 0x78000
	s_addc_u32 s37, s35, 0
	global_store_dword v115, v182, s[36:37]
	v_mul_f32_e32 v183, v103, v167
	s_add_u32 s36, s34, 0x84000
	s_addc_u32 s37, s35, 0
	global_store_dword v115, v183, s[36:37]
	v_mul_f32_e32 v184, v104, v168
	s_add_u32 s36, s34, 0xc0000
	s_addc_u32 s37, s35, 0
	global_store_dword v115, v184, s[36:37]
	v_mul_f32_e32 v185, v105, v169
	s_add_u32 s36, s34, 0xcc000
	s_addc_u32 s37, s35, 0
	global_store_dword v115, v185, s[36:37]
	v_mul_f32_e32 v186, v106, v170
	s_add_u32 s36, s34, 0xd8000
	s_addc_u32 s37, s35, 0
	global_store_dword v115, v186, s[36:37]
	v_mul_f32_e32 v187, v107, v171
	s_add_u32 s36, s34, 0xe4000
	s_addc_u32 s37, s35, 0
	global_store_dword v115, v187, s[36:37]
	v_mul_f32_e32 v188, v108, v172
	s_add_u32 s36, s34, 0x120000
	s_addc_u32 s37, s35, 0
	global_store_dword v115, v188, s[36:37]
	v_mul_f32_e32 v189, v109, v173
	s_add_u32 s36, s34, 0x12c000
	s_addc_u32 s37, s35, 0
	global_store_dword v115, v189, s[36:37]
	v_mul_f32_e32 v190, v110, v174
	s_add_u32 s36, s34, 0x138000
	s_addc_u32 s37, s35, 0
	global_store_dword v115, v190, s[36:37]
	v_mul_f32_e32 v191, v111, v175
	s_add_u32 s36, s34, 0x144000
	s_addc_u32 s37, s35, 0
	global_store_dword v115, v191, s[36:37]
	s_add_i32 s28, s21, 32
	s_sub_i32 s29, s28, 0x300
	s_cmp_ge_u32 s28, 0x300
	s_cselect_b32 s29, s29, s28
	s_mul_i32 s30, s28, 0xc000
	s_lshl_b32 s35, s20, 2
	s_add_u32 s30, s30, s35
	s_add_u32 s34, s14, s30
	s_addc_u32 s35, s15, 0
	s_add_i32 s30, s21, 64
	s_lshl_b32 s30, s30, 2
	s_add_u32 s26, s6, s30
	s_addc_u32 s27, s7, 0
	global_load_dword v128, v115, s[26:27]
	s_add_u32 s26, s26, 0x1800
	s_addc_u32 s27, s27, 0
	global_load_dword v129, v115, s[26:27]
	s_add_u32 s26, s26, 0x1800
	s_addc_u32 s27, s27, 0
	global_load_dword v130, v115, s[26:27]
	s_add_u32 s26, s26, 0x1800
	s_addc_u32 s27, s27, 0
	global_load_dword v131, v115, s[26:27]
	s_add_u32 s26, s26, 0x1800
	s_addc_u32 s27, s27, 0
	global_load_dword v132, v115, s[26:27]
	s_add_u32 s26, s26, 0x1800
	s_addc_u32 s27, s27, 0
	global_load_dword v133, v115, s[26:27]
	s_add_u32 s26, s26, 0x1800
	s_addc_u32 s27, s27, 0
	global_load_dword v134, v115, s[26:27]
	s_add_u32 s26, s26, 0x1800
	s_addc_u32 s27, s27, 0
	global_load_dword v135, v115, s[26:27]
	s_add_u32 s26, s26, 0x1800
	s_addc_u32 s27, s27, 0
	global_load_dword v136, v115, s[26:27]
	s_add_u32 s26, s26, 0x1800
	s_addc_u32 s27, s27, 0
	global_load_dword v137, v115, s[26:27]
	s_add_u32 s26, s26, 0x1800
	s_addc_u32 s27, s27, 0
	global_load_dword v138, v115, s[26:27]
	s_add_u32 s26, s26, 0x1800
	s_addc_u32 s27, s27, 0
	global_load_dword v139, v115, s[26:27]
	s_add_u32 s26, s26, 0x1800
	s_addc_u32 s27, s27, 0
	global_load_dword v140, v115, s[26:27]
	s_add_u32 s26, s26, 0x1800
	s_addc_u32 s27, s27, 0
	global_load_dword v141, v115, s[26:27]
	s_add_u32 s26, s26, 0x1800
	s_addc_u32 s27, s27, 0
	global_load_dword v142, v115, s[26:27]
	s_add_u32 s26, s26, 0x1800
	s_addc_u32 s27, s27, 0
	global_load_dword v143, v115, s[26:27]
	s_add_u32 s26, s26, 0x1800
	s_addc_u32 s27, s27, 0
	global_load_dword v144, v115, s[26:27]
	s_add_u32 s26, s26, 0x1800
	s_addc_u32 s27, s27, 0
	global_load_dword v145, v115, s[26:27]
	s_add_u32 s26, s26, 0x1800
	s_addc_u32 s27, s27, 0
	global_load_dword v146, v115, s[26:27]
	s_add_u32 s26, s26, 0x1800
	s_addc_u32 s27, s27, 0
	global_load_dword v147, v115, s[26:27]
	s_add_u32 s26, s26, 0x1800
	s_addc_u32 s27, s27, 0
	global_load_dword v148, v115, s[26:27]
	s_add_u32 s26, s26, 0x1800
	s_addc_u32 s27, s27, 0
	global_load_dword v149, v115, s[26:27]
	s_add_u32 s26, s26, 0x1800
	s_addc_u32 s27, s27, 0
	global_load_dword v150, v115, s[26:27]
	s_add_u32 s26, s26, 0x1800
	s_addc_u32 s27, s27, 0
	global_load_dword v151, v115, s[26:27]
	s_add_u32 s26, s26, 0x1800
	s_addc_u32 s27, s27, 0
	global_load_dword v152, v115, s[26:27]
	s_add_u32 s26, s26, 0x1800
	s_addc_u32 s27, s27, 0
	global_load_dword v153, v115, s[26:27]
	s_add_u32 s26, s26, 0x1800
	s_addc_u32 s27, s27, 0
	global_load_dword v154, v115, s[26:27]
	s_add_u32 s26, s26, 0x1800
	s_addc_u32 s27, s27, 0
	global_load_dword v155, v115, s[26:27]
	s_add_u32 s26, s26, 0x1800
	s_addc_u32 s27, s27, 0
	global_load_dword v156, v115, s[26:27]
	s_add_u32 s26, s26, 0x1800
	s_addc_u32 s27, s27, 0
	global_load_dword v157, v115, s[26:27]
	s_add_u32 s26, s26, 0x1800
	s_addc_u32 s27, s27, 0
	global_load_dword v158, v115, s[26:27]
	s_add_u32 s26, s26, 0x1800
	s_addc_u32 s27, s27, 0
	global_load_dword v159, v115, s[26:27]
	s_waitcnt vmcnt(48)
; __device__ __forceinline__ void kraw_items(const Args& a, int gw, int NGW, int lane) {
;     ...
;             for (int ci = 0; ci < 12; ++ci) { const int c = c0 + 12 * cb + ci;
;                 float acc = 0.f;
; #pragma unroll
;                 for (int jj = 0; jj < 64; ++jj) acc += h[jj] * __builtin_bit_cast(float, __builtin_amdgcn_readlane(__builtin_bit_cast(int, wv[ci]), jj));
;                 const int cm = c % 768;
;                 const float delta = fabsf(-3.0701134573253945f + (float)cm * ((-15.350567286626973f + 3.0701134573253945f) / 767.0f));
;                 KR[(size_t)c * (LP + LS) + p] = acc * __expf(-tt * delta); }
	v_mfma_f32_32x32x2_f32 v[96:111], v64, v32, 0
	v_mfma_f32_32x32x2_f32 v[96:111], v65, v33, v[96:111]
	v_mfma_f32_32x32x2_f32 v[96:111], v66, v34, v[96:111]
	v_mfma_f32_32x32x2_f32 v[96:111], v67, v35, v[96:111]
	v_mfma_f32_32x32x2_f32 v[96:111], v68, v36, v[96:111]
	v_mfma_f32_32x32x2_f32 v[96:111], v69, v37, v[96:111]
	v_mfma_f32_32x32x2_f32 v[96:111], v70, v38, v[96:111]
	v_mfma_f32_32x32x2_f32 v[96:111], v71, v39, v[96:111]
	v_mfma_f32_32x32x2_f32 v[96:111], v72, v40, v[96:111]
	v_mfma_f32_32x32x2_f32 v[96:111], v73, v41, v[96:111]
	v_mfma_f32_32x32x2_f32 v[96:111], v74, v42, v[96:111]
	v_mfma_f32_32x32x2_f32 v[96:111], v75, v43, v[96:111]
	v_mfma_f32_32x32x2_f32 v[96:111], v76, v44, v[96:111]
	v_mfma_f32_32x32x2_f32 v[96:111], v77, v45, v[96:111]
	v_mfma_f32_32x32x2_f32 v[96:111], v78, v46, v[96:111]
	v_mfma_f32_32x32x2_f32 v[96:111], v79, v47, v[96:111]
	v_mfma_f32_32x32x2_f32 v[96:111], v80, v48, v[96:111]
	v_mfma_f32_32x32x2_f32 v[96:111], v81, v49, v[96:111]
	v_mfma_f32_32x32x2_f32 v[96:111], v82, v50, v[96:111]
	v_mfma_f32_32x32x2_f32 v[96:111], v83, v51, v[96:111]
	v_mfma_f32_32x32x2_f32 v[96:111], v84, v52, v[96:111]
	v_mfma_f32_32x32x2_f32 v[96:111], v85, v53, v[96:111]
	v_mfma_f32_32x32x2_f32 v[96:111], v86, v54, v[96:111]
	v_mfma_f32_32x32x2_f32 v[96:111], v87, v55, v[96:111]
	v_mfma_f32_32x32x2_f32 v[96:111], v88, v56, v[96:111]
	v_mfma_f32_32x32x2_f32 v[96:111], v89, v57, v[96:111]
	v_mfma_f32_32x32x2_f32 v[96:111], v90, v58, v[96:111]
	v_mfma_f32_32x32x2_f32 v[96:111], v91, v59, v[96:111]
	v_mfma_f32_32x32x2_f32 v[96:111], v92, v60, v[96:111]
	v_mfma_f32_32x32x2_f32 v[96:111], v93, v61, v[96:111]
	v_mfma_f32_32x32x2_f32 v[96:111], v94, v62, v[96:111]
	v_mfma_f32_32x32x2_f32 v[96:111], v95, v63, v[96:111]
	s_add_i32 s30, s29, 0
	v_add_u32_e32 v119, s30, v118
	v_cvt_f32_u32_e32 v119, v119
	v_fmamk_f32 v119, v119, 0xbc83298c, v120
	v_mul_f32_e64 v119, v117, |v119|
	v_mul_f32_e32 v119, 0x3fb8aa3b, v119
	v_exp_f32_e32 v160, v119
	s_add_i32 s30, s29, 1
	v_add_u32_e32 v119, s30, v118
	v_cvt_f32_u32_e32 v119, v119
	v_fmamk_f32 v119, v119, 0xbc83298c, v120
	v_mul_f32_e64 v119, v117, |v119|
	v_mul_f32_e32 v119, 0x3fb8aa3b, v119
	v_exp_f32_e32 v161, v119
	s_add_i32 s30, s29, 2
	v_add_u32_e32 v119, s30, v118
	v_cvt_f32_u32_e32 v119, v119
	v_fmamk_f32 v119, v119, 0xbc83298c, v120
	v_mul_f32_e64 v119, v117, |v119|
	v_mul_f32_e32 v119, 0x3fb8aa3b, v119
	v_exp_f32_e32 v162, v119
	s_add_i32 s30, s29, 3
	v_add_u32_e32 v119, s30, v118
	v_cvt_f32_u32_e32 v119, v119
	v_fmamk_f32 v119, v119, 0xbc83298c, v120
	v_mul_f32_e64 v119, v117, |v119|
	v_mul_f32_e32 v119, 0x3fb8aa3b, v119
	v_exp_f32_e32 v163, v119
	s_add_i32 s30, s29, 8
	v_add_u32_e32 v119, s30, v118
	v_cvt_f32_u32_e32 v119, v119
	v_fmamk_f32 v119, v119, 0xbc83298c, v120
	v_mul_f32_e64 v119, v117, |v119|
	v_mul_f32_e32 v119, 0x3fb8aa3b, v119
	v_exp_f32_e32 v164, v119
	s_add_i32 s30, s29, 9
	v_add_u32_e32 v119, s30, v118
	v_cvt_f32_u32_e32 v119, v119
	v_fmamk_f32 v119, v119, 0xbc83298c, v120
	v_mul_f32_e64 v119, v117, |v119|
	v_mul_f32_e32 v119, 0x3fb8aa3b, v119
	v_exp_f32_e32 v165, v119
	s_add_i32 s30, s29, 10
	v_add_u32_e32 v119, s30, v118
	v_cvt_f32_u32_e32 v119, v119
	v_fmamk_f32 v119, v119, 0xbc83298c, v120
	v_mul_f32_e64 v119, v117, |v119|
	v_mul_f32_e32 v119, 0x3fb8aa3b, v119
	v_exp_f32_e32 v166, v119
	s_add_i32 s30, s29, 11
	v_add_u32_e32 v119, s30, v118
	v_cvt_f32_u32_e32 v119, v119
	v_fmamk_f32 v119, v119, 0xbc83298c, v120
	v_mul_f32_e64 v119, v117, |v119|
	v_mul_f32_e32 v119, 0x3fb8aa3b, v119
	v_exp_f32_e32 v167, v119
	s_add_i32 s30, s29, 16
	v_add_u32_e32 v119, s30, v118
	v_cvt_f32_u32_e32 v119, v119
	v_fmamk_f32 v119, v119, 0xbc83298c, v120
	v_mul_f32_e64 v119, v117, |v119|
	v_mul_f32_e32 v119, 0x3fb8aa3b, v119
	v_exp_f32_e32 v168, v119
	s_add_i32 s30, s29, 17
	v_add_u32_e32 v119, s30, v118
	v_cvt_f32_u32_e32 v119, v119
	v_fmamk_f32 v119, v119, 0xbc83298c, v120
	v_mul_f32_e64 v119, v117, |v119|
	v_mul_f32_e32 v119, 0x3fb8aa3b, v119
	v_exp_f32_e32 v169, v119
	s_add_i32 s30, s29, 18
	v_add_u32_e32 v119, s30, v118
	v_cvt_f32_u32_e32 v119, v119
	v_fmamk_f32 v119, v119, 0xbc83298c, v120
	v_mul_f32_e64 v119, v117, |v119|
	v_mul_f32_e32 v119, 0x3fb8aa3b, v119
	v_exp_f32_e32 v170, v119
	s_add_i32 s30, s29, 19
	v_add_u32_e32 v119, s30, v118
	v_cvt_f32_u32_e32 v119, v119
	v_fmamk_f32 v119, v119, 0xbc83298c, v120
	v_mul_f32_e64 v119, v117, |v119|
	v_mul_f32_e32 v119, 0x3fb8aa3b, v119
	v_exp_f32_e32 v171, v119
	s_add_i32 s30, s29, 24
	v_add_u32_e32 v119, s30, v118
	v_cvt_f32_u32_e32 v119, v119
	v_fmamk_f32 v119, v119, 0xbc83298c, v120
	v_mul_f32_e64 v119, v117, |v119|
	v_mul_f32_e32 v119, 0x3fb8aa3b, v119
	v_exp_f32_e32 v172, v119
	s_add_i32 s30, s29, 25
	v_add_u32_e32 v119, s30, v118
	v_cvt_f32_u32_e32 v119, v119
	v_fmamk_f32 v119, v119, 0xbc83298c, v120
	v_mul_f32_e64 v119, v117, |v119|
	v_mul_f32_e32 v119, 0x3fb8aa3b, v119
	v_exp_f32_e32 v173, v119
	s_add_i32 s30, s29, 26
	v_add_u32_e32 v119, s30, v118
	v_cvt_f32_u32_e32 v119, v119
	v_fmamk_f32 v119, v119, 0xbc83298c, v120
	v_mul_f32_e64 v119, v117, |v119|
	v_mul_f32_e32 v119, 0x3fb8aa3b, v119
	v_exp_f32_e32 v174, v119
	s_add_i32 s30, s29, 27
	v_add_u32_e32 v119, s30, v118
	v_cvt_f32_u32_e32 v119, v119
	v_fmamk_f32 v119, v119, 0xbc83298c, v120
	v_mul_f32_e64 v119, v117, |v119|
	v_mul_f32_e32 v119, 0x3fb8aa3b, v119
	v_exp_f32_e32 v175, v119
	s_nop 7
	v_mul_f32_e32 v176, v96, v160
	s_mov_b64 s[36:37], s[34:35]
	global_store_dword v115, v176, s[36:37]
	v_mul_f32_e32 v177, v97, v161
	s_add_u32 s36, s34, 0xc000
	s_addc_u32 s37, s35, 0
	global_store_dword v115, v177, s[36:37]
	v_mul_f32_e32 v178, v98, v162
	s_add_u32 s36, s34, 0x18000
; __device__ __forceinline__ void kraw_items(const Args& a, int gw, int NGW, int lane) {
;     ...
;     for (int it = gw; it < 192 * 32; it += NGW) {
;         const int pg = it >> 5, cgp = it & 31, p = pg * 64 + lane, c0 = cgp * 48;
;         float h[64];
; #pragma unroll
;         for (int q = 0; q < 16; ++q) { const f32x4 t = *(const f32x4*)(H3 + (size_t)p * 64 + 4 * q); h[4 * q] = t.x; h[4 * q + 1] = t.y; h[4 * q + 2] = t.z; h[4 * q + 3] = t.w; }
;         const int grp = p >= LP, tpos = p - grp * LP, L = grp ? LS : LP;
;         const float tt = (float)tpos * (1.0f / (float)(L - 1));
; #pragma unroll 1
;         for (int cb = 0; cb < 4; ++cb) {
;             const float* wr = a.in[I_FWOUT] + lane * 1536 + c0 + 12 * cb;
;             const f32x4 w0 = *(const f32x4*)(wr), w1 = *(const f32x4*)(wr + 4), w2 = *(const f32x4*)(wr + 8);
;             float wv[12] = {w0.x, w0.y, w0.z, w0.w, w1.x, w1.y, w1.z, w1.w, w2.x, w2.y, w2.z, w2.w};
; #pragma unroll
;             for (int ci = 0; ci < 12; ++ci) { const int c = c0 + 12 * cb + ci;
;                 float acc = 0.f;
; #pragma unroll
;                 for (int jj = 0; jj < 64; ++jj) acc += h[jj] * __builtin_bit_cast(float, __builtin_amdgcn_readlane(__builtin_bit_cast(int, wv[ci]), jj));
;                 const int cm = c % 768;
;                 const float delta = fabsf(-3.0701134573253945f + (float)cm * ((-15.350567286626973f + 3.0701134573253945f) / 767.0f));
;                 KR[(size_t)c * (LP + LS) + p] = acc * __expf(-tt * delta); }
	s_addc_u32 s37, s35, 0
	global_store_dword v115, v178, s[36:37]
	v_mul_f32_e32 v179, v99, v163
	s_add_u32 s36, s34, 0x24000
	s_addc_u32 s37, s35, 0
	global_store_dword v115, v179, s[36:37]
	v_mul_f32_e32 v180, v100, v164
	s_add_u32 s36, s34, 0x60000
	s_addc_u32 s37, s35, 0
	global_store_dword v115, v180, s[36:37]
	v_mul_f32_e32 v181, v101, v165
	s_add_u32 s36, s34, 0x6c000
	s_addc_u32 s37, s35, 0
	global_store_dword v115, v181, s[36:37]
	v_mul_f32_e32 v182, v102, v166
	s_add_u32 s36, s34, 0x78000
	s_addc_u32 s37, s35, 0
	global_store_dword v115, v182, s[36:37]
	v_mul_f32_e32 v183, v103, v167
	s_add_u32 s36, s34, 0x84000
	s_addc_u32 s37, s35, 0
	global_store_dword v115, v183, s[36:37]
	v_mul_f32_e32 v184, v104, v168
	s_add_u32 s36, s34, 0xc0000
	s_addc_u32 s37, s35, 0
	global_store_dword v115, v184, s[36:37]
	v_mul_f32_e32 v185, v105, v169
	s_add_u32 s36, s34, 0xcc000
	s_addc_u32 s37, s35, 0
	global_store_dword v115, v185, s[36:37]
	v_mul_f32_e32 v186, v106, v170
	s_add_u32 s36, s34, 0xd8000
	s_addc_u32 s37, s35, 0
	global_store_dword v115, v186, s[36:37]
	v_mul_f32_e32 v187, v107, v171
	s_add_u32 s36, s34, 0xe4000
	s_addc_u32 s37, s35, 0
	global_store_dword v115, v187, s[36:37]
	v_mul_f32_e32 v188, v108, v172
	s_add_u32 s36, s34, 0x120000
	s_addc_u32 s37, s35, 0
	global_store_dword v115, v188, s[36:37]
	v_mul_f32_e32 v189, v109, v173
	s_add_u32 s36, s34, 0x12c000
	s_addc_u32 s37, s35, 0
	global_store_dword v115, v189, s[36:37]
	v_mul_f32_e32 v190, v110, v174
	s_add_u32 s36, s34, 0x138000
	s_addc_u32 s37, s35, 0
	global_store_dword v115, v190, s[36:37]
	v_mul_f32_e32 v191, v111, v175
	s_add_u32 s36, s34, 0x144000
	s_addc_u32 s37, s35, 0
	global_store_dword v115, v191, s[36:37]
	s_add_i32 s28, s21, 64
	s_sub_i32 s29, s28, 0x300
	s_cmp_ge_u32 s28, 0x300
	s_cselect_b32 s29, s29, s28
	s_mul_i32 s30, s28, 0xc000
	s_lshl_b32 s35, s20, 2
	s_add_u32 s30, s30, s35
	s_add_u32 s34, s14, s30
	s_addc_u32 s35, s15, 0
	s_add_i32 s17, s16, 0x1000
	s_lshr_b32 s18, s17, 4
	s_and_b32 s19, s17, 15
	s_lshl_b32 s20, s18, 5
	s_mul_i32 s21, s19, 0x60
	s_lshl_b32 s30, s20, 8
	s_add_u32 s24, s10, s30
	s_addc_u32 s25, s11, 0
	global_load_dwordx4 v[0:3], v114, s[24:25] offset:0
	global_load_dwordx4 v[4:7], v114, s[24:25] offset:16
	global_load_dwordx4 v[8:11], v114, s[24:25] offset:32
	global_load_dwordx4 v[12:15], v114, s[24:25] offset:48
	global_load_dwordx4 v[16:19], v114, s[24:25] offset:64
	global_load_dwordx4 v[20:23], v114, s[24:25] offset:80
	global_load_dwordx4 v[24:27], v114, s[24:25] offset:96
	global_load_dwordx4 v[28:31], v114, s[24:25] offset:112
	s_add_i32 s30, s21, 0
	s_lshl_b32 s30, s30, 2
	s_add_u32 s26, s6, s30
	s_addc_u32 s27, s7, 0
	global_load_dword v64, v115, s[26:27]
	s_add_u32 s26, s26, 0x1800
	s_addc_u32 s27, s27, 0
	global_load_dword v65, v115, s[26:27]
	s_add_u32 s26, s26, 0x1800
	s_addc_u32 s27, s27, 0
	global_load_dword v66, v115, s[26:27]
	s_add_u32 s26, s26, 0x1800
	s_addc_u32 s27, s27, 0
	global_load_dword v67, v115, s[26:27]
	s_add_u32 s26, s26, 0x1800
	s_addc_u32 s27, s27, 0
	global_load_dword v68, v115, s[26:27]
	s_add_u32 s26, s26, 0x1800
	s_addc_u32 s27, s27, 0
	global_load_dword v69, v115, s[26:27]
	s_add_u32 s26, s26, 0x1800
	s_addc_u32 s27, s27, 0
	global_load_dword v70, v115, s[26:27]
	s_add_u32 s26, s26, 0x1800
	s_addc_u32 s27, s27, 0
	global_load_dword v71, v115, s[26:27]
	s_add_u32 s26, s26, 0x1800
	s_addc_u32 s27, s27, 0
	global_load_dword v72, v115, s[26:27]
	s_add_u32 s26, s26, 0x1800
	s_addc_u32 s27, s27, 0
	global_load_dword v73, v115, s[26:27]
	s_add_u32 s26, s26, 0x1800
	s_addc_u32 s27, s27, 0
	global_load_dword v74, v115, s[26:27]
	s_add_u32 s26, s26, 0x1800
	s_addc_u32 s27, s27, 0
	global_load_dword v75, v115, s[26:27]
	s_add_u32 s26, s26, 0x1800
	s_addc_u32 s27, s27, 0
	global_load_dword v76, v115, s[26:27]
	s_add_u32 s26, s26, 0x1800
	s_addc_u32 s27, s27, 0
	global_load_dword v77, v115, s[26:27]
	s_add_u32 s26, s26, 0x1800
	s_addc_u32 s27, s27, 0
	global_load_dword v78, v115, s[26:27]
	s_add_u32 s26, s26, 0x1800
	s_addc_u32 s27, s27, 0
	global_load_dword v79, v115, s[26:27]
	s_add_u32 s26, s26, 0x1800
	s_addc_u32 s27, s27, 0
	global_load_dword v80, v115, s[26:27]
	s_add_u32 s26, s26, 0x1800
	s_addc_u32 s27, s27, 0
	global_load_dword v81, v115, s[26:27]
	s_add_u32 s26, s26, 0x1800
	s_addc_u32 s27, s27, 0
	global_load_dword v82, v115, s[26:27]
	s_add_u32 s26, s26, 0x1800
	s_addc_u32 s27, s27, 0
	global_load_dword v83, v115, s[26:27]
	s_add_u32 s26, s26, 0x1800
	s_addc_u32 s27, s27, 0
	global_load_dword v84, v115, s[26:27]
	s_add_u32 s26, s26, 0x1800
	s_addc_u32 s27, s27, 0
	global_load_dword v85, v115, s[26:27]
	s_add_u32 s26, s26, 0x1800
	s_addc_u32 s27, s27, 0
	global_load_dword v86, v115, s[26:27]
	s_add_u32 s26, s26, 0x1800
	s_addc_u32 s27, s27, 0
	global_load_dword v87, v115, s[26:27]
	s_add_u32 s26, s26, 0x1800
	s_addc_u32 s27, s27, 0
	global_load_dword v88, v115, s[26:27]
	s_add_u32 s26, s26, 0x1800
	s_addc_u32 s27, s27, 0
	global_load_dword v89, v115, s[26:27]
	s_add_u32 s26, s26, 0x1800
	s_addc_u32 s27, s27, 0
	global_load_dword v90, v115, s[26:27]
	s_add_u32 s26, s26, 0x1800
	s_addc_u32 s27, s27, 0
	global_load_dword v91, v115, s[26:27]
	s_add_u32 s26, s26, 0x1800
	s_addc_u32 s27, s27, 0
	global_load_dword v92, v115, s[26:27]
	s_add_u32 s26, s26, 0x1800
	s_addc_u32 s27, s27, 0
	global_load_dword v93, v115, s[26:27]
	s_add_u32 s26, s26, 0x1800
	s_addc_u32 s27, s27, 0
	global_load_dword v94, v115, s[26:27]
	s_add_u32 s26, s26, 0x1800
	s_addc_u32 s27, s27, 0
	global_load_dword v95, v115, s[26:27]
	s_waitcnt vmcnt(56)
; __device__ __forceinline__ void kraw_items(const Args& a, int gw, int NGW, int lane) {
;     ...
;             for (int ci = 0; ci < 12; ++ci) { const int c = c0 + 12 * cb + ci;
;                 float acc = 0.f;
; #pragma unroll
;                 for (int jj = 0; jj < 64; ++jj) acc += h[jj] * __builtin_bit_cast(float, __builtin_amdgcn_readlane(__builtin_bit_cast(int, wv[ci]), jj));
;                 const int cm = c % 768;
;                 const float delta = fabsf(-3.0701134573253945f + (float)cm * ((-15.350567286626973f + 3.0701134573253945f) / 767.0f));
;                 KR[(size_t)c * (LP + LS) + p] = acc * __expf(-tt * delta); }
	v_mfma_f32_32x32x2_f32 v[96:111], v128, v32, 0
	v_mfma_f32_32x32x2_f32 v[96:111], v129, v33, v[96:111]
	v_mfma_f32_32x32x2_f32 v[96:111], v130, v34, v[96:111]
	v_mfma_f32_32x32x2_f32 v[96:111], v131, v35, v[96:111]
	v_mfma_f32_32x32x2_f32 v[96:111], v132, v36, v[96:111]
	v_mfma_f32_32x32x2_f32 v[96:111], v133, v37, v[96:111]
	v_mfma_f32_32x32x2_f32 v[96:111], v134, v38, v[96:111]
	v_mfma_f32_32x32x2_f32 v[96:111], v135, v39, v[96:111]
	v_mfma_f32_32x32x2_f32 v[96:111], v136, v40, v[96:111]
	v_mfma_f32_32x32x2_f32 v[96:111], v137, v41, v[96:111]
	v_mfma_f32_32x32x2_f32 v[96:111], v138, v42, v[96:111]
	v_mfma_f32_32x32x2_f32 v[96:111], v139, v43, v[96:111]
	v_mfma_f32_32x32x2_f32 v[96:111], v140, v44, v[96:111]
	v_mfma_f32_32x32x2_f32 v[96:111], v141, v45, v[96:111]
	v_mfma_f32_32x32x2_f32 v[96:111], v142, v46, v[96:111]
	v_mfma_f32_32x32x2_f32 v[96:111], v143, v47, v[96:111]
	v_mfma_f32_32x32x2_f32 v[96:111], v144, v48, v[96:111]
	v_mfma_f32_32x32x2_f32 v[96:111], v145, v49, v[96:111]
	v_mfma_f32_32x32x2_f32 v[96:111], v146, v50, v[96:111]
	v_mfma_f32_32x32x2_f32 v[96:111], v147, v51, v[96:111]
	v_mfma_f32_32x32x2_f32 v[96:111], v148, v52, v[96:111]
	v_mfma_f32_32x32x2_f32 v[96:111], v149, v53, v[96:111]
	v_mfma_f32_32x32x2_f32 v[96:111], v150, v54, v[96:111]
	v_mfma_f32_32x32x2_f32 v[96:111], v151, v55, v[96:111]
	v_mfma_f32_32x32x2_f32 v[96:111], v152, v56, v[96:111]
	v_mfma_f32_32x32x2_f32 v[96:111], v153, v57, v[96:111]
	v_mfma_f32_32x32x2_f32 v[96:111], v154, v58, v[96:111]
	v_mfma_f32_32x32x2_f32 v[96:111], v155, v59, v[96:111]
	v_mfma_f32_32x32x2_f32 v[96:111], v156, v60, v[96:111]
	v_mfma_f32_32x32x2_f32 v[96:111], v157, v61, v[96:111]
	v_mfma_f32_32x32x2_f32 v[96:111], v158, v62, v[96:111]
	v_mfma_f32_32x32x2_f32 v[96:111], v159, v63, v[96:111]
	s_add_i32 s30, s29, 0
	v_add_u32_e32 v119, s30, v118
	v_cvt_f32_u32_e32 v119, v119
	v_fmamk_f32 v119, v119, 0xbc83298c, v120
	v_mul_f32_e64 v119, v117, |v119|
	v_mul_f32_e32 v119, 0x3fb8aa3b, v119
	v_exp_f32_e32 v160, v119
	s_add_i32 s30, s29, 1
	v_add_u32_e32 v119, s30, v118
	v_cvt_f32_u32_e32 v119, v119
	v_fmamk_f32 v119, v119, 0xbc83298c, v120
	v_mul_f32_e64 v119, v117, |v119|
	v_mul_f32_e32 v119, 0x3fb8aa3b, v119
	v_exp_f32_e32 v161, v119
	s_add_i32 s30, s29, 2
	v_add_u32_e32 v119, s30, v118
	v_cvt_f32_u32_e32 v119, v119
	v_fmamk_f32 v119, v119, 0xbc83298c, v120
	v_mul_f32_e64 v119, v117, |v119|
	v_mul_f32_e32 v119, 0x3fb8aa3b, v119
	v_exp_f32_e32 v162, v119
	s_add_i32 s30, s29, 3
	v_add_u32_e32 v119, s30, v118
	v_cvt_f32_u32_e32 v119, v119
	v_fmamk_f32 v119, v119, 0xbc83298c, v120
	v_mul_f32_e64 v119, v117, |v119|
	v_mul_f32_e32 v119, 0x3fb8aa3b, v119
	v_exp_f32_e32 v163, v119
	s_add_i32 s30, s29, 8
	v_add_u32_e32 v119, s30, v118
	v_cvt_f32_u32_e32 v119, v119
	v_fmamk_f32 v119, v119, 0xbc83298c, v120
	v_mul_f32_e64 v119, v117, |v119|
	v_mul_f32_e32 v119, 0x3fb8aa3b, v119
	v_exp_f32_e32 v164, v119
	s_add_i32 s30, s29, 9
	v_add_u32_e32 v119, s30, v118
	v_cvt_f32_u32_e32 v119, v119
	v_fmamk_f32 v119, v119, 0xbc83298c, v120
	v_mul_f32_e64 v119, v117, |v119|
	v_mul_f32_e32 v119, 0x3fb8aa3b, v119
	v_exp_f32_e32 v165, v119
	s_add_i32 s30, s29, 10
	v_add_u32_e32 v119, s30, v118
	v_cvt_f32_u32_e32 v119, v119
	v_fmamk_f32 v119, v119, 0xbc83298c, v120
	v_mul_f32_e64 v119, v117, |v119|
	v_mul_f32_e32 v119, 0x3fb8aa3b, v119
	v_exp_f32_e32 v166, v119
	s_add_i32 s30, s29, 11
	v_add_u32_e32 v119, s30, v118
	v_cvt_f32_u32_e32 v119, v119
	v_fmamk_f32 v119, v119, 0xbc83298c, v120
	v_mul_f32_e64 v119, v117, |v119|
	v_mul_f32_e32 v119, 0x3fb8aa3b, v119
	v_exp_f32_e32 v167, v119
	s_add_i32 s30, s29, 16
	v_add_u32_e32 v119, s30, v118
	v_cvt_f32_u32_e32 v119, v119
	v_fmamk_f32 v119, v119, 0xbc83298c, v120
	v_mul_f32_e64 v119, v117, |v119|
	v_mul_f32_e32 v119, 0x3fb8aa3b, v119
	v_exp_f32_e32 v168, v119
	s_add_i32 s30, s29, 17
	v_add_u32_e32 v119, s30, v118
	v_cvt_f32_u32_e32 v119, v119
	v_fmamk_f32 v119, v119, 0xbc83298c, v120
	v_mul_f32_e64 v119, v117, |v119|
	v_mul_f32_e32 v119, 0x3fb8aa3b, v119
	v_exp_f32_e32 v169, v119
	s_add_i32 s30, s29, 18
	v_add_u32_e32 v119, s30, v118
	v_cvt_f32_u32_e32 v119, v119
	v_fmamk_f32 v119, v119, 0xbc83298c, v120
	v_mul_f32_e64 v119, v117, |v119|
	v_mul_f32_e32 v119, 0x3fb8aa3b, v119
	v_exp_f32_e32 v170, v119
	s_add_i32 s30, s29, 19
	v_add_u32_e32 v119, s30, v118
	v_cvt_f32_u32_e32 v119, v119
	v_fmamk_f32 v119, v119, 0xbc83298c, v120
	v_mul_f32_e64 v119, v117, |v119|
	v_mul_f32_e32 v119, 0x3fb8aa3b, v119
	v_exp_f32_e32 v171, v119
	s_add_i32 s30, s29, 24
	v_add_u32_e32 v119, s30, v118
	v_cvt_f32_u32_e32 v119, v119
	v_fmamk_f32 v119, v119, 0xbc83298c, v120
	v_mul_f32_e64 v119, v117, |v119|
	v_mul_f32_e32 v119, 0x3fb8aa3b, v119
	v_exp_f32_e32 v172, v119
	s_add_i32 s30, s29, 25
	v_add_u32_e32 v119, s30, v118
	v_cvt_f32_u32_e32 v119, v119
	v_fmamk_f32 v119, v119, 0xbc83298c, v120
	v_mul_f32_e64 v119, v117, |v119|
	v_mul_f32_e32 v119, 0x3fb8aa3b, v119
	v_exp_f32_e32 v173, v119
	s_add_i32 s30, s29, 26
	v_add_u32_e32 v119, s30, v118
	v_cvt_f32_u32_e32 v119, v119
	v_fmamk_f32 v119, v119, 0xbc83298c, v120
	v_mul_f32_e64 v119, v117, |v119|
	v_mul_f32_e32 v119, 0x3fb8aa3b, v119
	v_exp_f32_e32 v174, v119
	s_add_i32 s30, s29, 27
	v_add_u32_e32 v119, s30, v118
	v_cvt_f32_u32_e32 v119, v119
	v_fmamk_f32 v119, v119, 0xbc83298c, v120
	v_mul_f32_e64 v119, v117, |v119|
	v_mul_f32_e32 v119, 0x3fb8aa3b, v119
	v_exp_f32_e32 v175, v119
	s_nop 7
	v_mul_f32_e32 v176, v96, v160
	s_mov_b64 s[36:37], s[34:35]
	global_store_dword v115, v176, s[36:37]
	v_mul_f32_e32 v177, v97, v161
	s_add_u32 s36, s34, 0xc000
	s_addc_u32 s37, s35, 0
	global_store_dword v115, v177, s[36:37]
	v_mul_f32_e32 v178, v98, v162
; __device__ __forceinline__ void kraw_items(const Args& a, int gw, int NGW, int lane) {
;     ...
;         const int grp = p >= LP, tpos = p - grp * LP, L = grp ? LS : LP;
;         const float tt = (float)tpos * (1.0f / (float)(L - 1));
; #pragma unroll 1
;         for (int cb = 0; cb < 4; ++cb) {
;             const float* wr = a.in[I_FWOUT] + lane * 1536 + c0 + 12 * cb;
;             const f32x4 w0 = *(const f32x4*)(wr), w1 = *(const f32x4*)(wr + 4), w2 = *(const f32x4*)(wr + 8);
;             float wv[12] = {w0.x, w0.y, w0.z, w0.w, w1.x, w1.y, w1.z, w1.w, w2.x, w2.y, w2.z, w2.w};
; #pragma unroll
;             for (int ci = 0; ci < 12; ++ci) { const int c = c0 + 12 * cb + ci;
;                 float acc = 0.f;
; #pragma unroll
;                 for (int jj = 0; jj < 64; ++jj) acc += h[jj] * __builtin_bit_cast(float, __builtin_amdgcn_readlane(__builtin_bit_cast(int, wv[ci]), jj));
;                 const int cm = c % 768;
;                 const float delta = fabsf(-3.0701134573253945f + (float)cm * ((-15.350567286626973f + 3.0701134573253945f) / 767.0f));
;                 KR[(size_t)c * (LP + LS) + p] = acc * __expf(-tt * delta); }
	s_add_u32 s36, s34, 0x18000
	s_addc_u32 s37, s35, 0
	global_store_dword v115, v178, s[36:37]
	v_mul_f32_e32 v179, v99, v163
	s_add_u32 s36, s34, 0x24000
	s_addc_u32 s37, s35, 0
	global_store_dword v115, v179, s[36:37]
	v_mul_f32_e32 v180, v100, v164
	s_add_u32 s36, s34, 0x60000
	s_addc_u32 s37, s35, 0
	global_store_dword v115, v180, s[36:37]
	v_mul_f32_e32 v181, v101, v165
	s_add_u32 s36, s34, 0x6c000
	s_addc_u32 s37, s35, 0
	global_store_dword v115, v181, s[36:37]
	v_mul_f32_e32 v182, v102, v166
	s_add_u32 s36, s34, 0x78000
	s_addc_u32 s37, s35, 0
	global_store_dword v115, v182, s[36:37]
	v_mul_f32_e32 v183, v103, v167
	s_add_u32 s36, s34, 0x84000
	s_addc_u32 s37, s35, 0
	global_store_dword v115, v183, s[36:37]
	v_mul_f32_e32 v184, v104, v168
	s_add_u32 s36, s34, 0xc0000
	s_addc_u32 s37, s35, 0
	global_store_dword v115, v184, s[36:37]
	v_mul_f32_e32 v185, v105, v169
	s_add_u32 s36, s34, 0xcc000
	s_addc_u32 s37, s35, 0
	global_store_dword v115, v185, s[36:37]
	v_mul_f32_e32 v186, v106, v170
	s_add_u32 s36, s34, 0xd8000
	s_addc_u32 s37, s35, 0
	global_store_dword v115, v186, s[36:37]
	v_mul_f32_e32 v187, v107, v171
	s_add_u32 s36, s34, 0xe4000
	s_addc_u32 s37, s35, 0
	global_store_dword v115, v187, s[36:37]
	v_mul_f32_e32 v188, v108, v172
	s_add_u32 s36, s34, 0x120000
	s_addc_u32 s37, s35, 0
	global_store_dword v115, v188, s[36:37]
	v_mul_f32_e32 v189, v109, v173
	s_add_u32 s36, s34, 0x12c000
	s_addc_u32 s37, s35, 0
	global_store_dword v115, v189, s[36:37]
	v_mul_f32_e32 v190, v110, v174
	s_add_u32 s36, s34, 0x138000
	s_addc_u32 s37, s35, 0
	global_store_dword v115, v190, s[36:37]
	v_mul_f32_e32 v191, v111, v175
	s_add_u32 s36, s34, 0x144000
	s_addc_u32 s37, s35, 0
	global_store_dword v115, v191, s[36:37]
	s_add_i32 s28, s21, 0
	s_sub_i32 s29, s28, 0x300
	s_cmp_ge_u32 s28, 0x300
	s_cselect_b32 s29, s29, s28
	s_mul_i32 s30, s28, 0xc000
	s_lshl_b32 s35, s20, 2
	s_add_u32 s30, s30, s35
	s_add_u32 s34, s14, s30
	s_addc_u32 s35, s15, 0
	s_mov_b32 s22, 0xb9000400
	s_cmp_ge_u32 s20, 0x2000
	s_cselect_b32 s22, 0xb9800801, s22
	s_and_b32 s30, s20, 0x1fff
	v_add_u32_e32 v119, s30, v112
	v_cvt_f32_u32_e32 v119, v119
	v_mul_f32_e32 v117, s22, v119
	s_add_i32 s30, s21, 32
	s_lshl_b32 s30, s30, 2
	s_add_u32 s26, s6, s30
	s_addc_u32 s27, s7, 0
	global_load_dword v128, v115, s[26:27]
	s_add_u32 s26, s26, 0x1800
	s_addc_u32 s27, s27, 0
	global_load_dword v129, v115, s[26:27]
	s_add_u32 s26, s26, 0x1800
	s_addc_u32 s27, s27, 0
	global_load_dword v130, v115, s[26:27]
	s_add_u32 s26, s26, 0x1800
	s_addc_u32 s27, s27, 0
	global_load_dword v131, v115, s[26:27]
	s_add_u32 s26, s26, 0x1800
	s_addc_u32 s27, s27, 0
	global_load_dword v132, v115, s[26:27]
	s_add_u32 s26, s26, 0x1800
	s_addc_u32 s27, s27, 0
	global_load_dword v133, v115, s[26:27]
	s_add_u32 s26, s26, 0x1800
	s_addc_u32 s27, s27, 0
	global_load_dword v134, v115, s[26:27]
	s_add_u32 s26, s26, 0x1800
	s_addc_u32 s27, s27, 0
	global_load_dword v135, v115, s[26:27]
	s_add_u32 s26, s26, 0x1800
	s_addc_u32 s27, s27, 0
	global_load_dword v136, v115, s[26:27]
	s_add_u32 s26, s26, 0x1800
	s_addc_u32 s27, s27, 0
	global_load_dword v137, v115, s[26:27]
	s_add_u32 s26, s26, 0x1800
	s_addc_u32 s27, s27, 0
	global_load_dword v138, v115, s[26:27]
	s_add_u32 s26, s26, 0x1800
	s_addc_u32 s27, s27, 0
	global_load_dword v139, v115, s[26:27]
	s_add_u32 s26, s26, 0x1800
	s_addc_u32 s27, s27, 0
	global_load_dword v140, v115, s[26:27]
	s_add_u32 s26, s26, 0x1800
	s_addc_u32 s27, s27, 0
	global_load_dword v141, v115, s[26:27]
	s_add_u32 s26, s26, 0x1800
	s_addc_u32 s27, s27, 0
	global_load_dword v142, v115, s[26:27]
	s_add_u32 s26, s26, 0x1800
	s_addc_u32 s27, s27, 0
	global_load_dword v143, v115, s[26:27]
	s_add_u32 s26, s26, 0x1800
	s_addc_u32 s27, s27, 0
	global_load_dword v144, v115, s[26:27]
	s_add_u32 s26, s26, 0x1800
	s_addc_u32 s27, s27, 0
	global_load_dword v145, v115, s[26:27]
	s_add_u32 s26, s26, 0x1800
	s_addc_u32 s27, s27, 0
	global_load_dword v146, v115, s[26:27]
	s_add_u32 s26, s26, 0x1800
	s_addc_u32 s27, s27, 0
	global_load_dword v147, v115, s[26:27]
	s_add_u32 s26, s26, 0x1800
	s_addc_u32 s27, s27, 0
	global_load_dword v148, v115, s[26:27]
	s_add_u32 s26, s26, 0x1800
	s_addc_u32 s27, s27, 0
	global_load_dword v149, v115, s[26:27]
	s_add_u32 s26, s26, 0x1800
	s_addc_u32 s27, s27, 0
	global_load_dword v150, v115, s[26:27]
	s_add_u32 s26, s26, 0x1800
	s_addc_u32 s27, s27, 0
	global_load_dword v151, v115, s[26:27]
	s_add_u32 s26, s26, 0x1800
	s_addc_u32 s27, s27, 0
	global_load_dword v152, v115, s[26:27]
	s_add_u32 s26, s26, 0x1800
	s_addc_u32 s27, s27, 0
	global_load_dword v153, v115, s[26:27]
	s_add_u32 s26, s26, 0x1800
	s_addc_u32 s27, s27, 0
	global_load_dword v154, v115, s[26:27]
	s_add_u32 s26, s26, 0x1800
	s_addc_u32 s27, s27, 0
	global_load_dword v155, v115, s[26:27]
	s_add_u32 s26, s26, 0x1800
	s_addc_u32 s27, s27, 0
	global_load_dword v156, v115, s[26:27]
	s_add_u32 s26, s26, 0x1800
	s_addc_u32 s27, s27, 0
	global_load_dword v157, v115, s[26:27]
	s_add_u32 s26, s26, 0x1800
	s_addc_u32 s27, s27, 0
	global_load_dword v158, v115, s[26:27]
	s_add_u32 s26, s26, 0x1800
	s_addc_u32 s27, s27, 0
	global_load_dword v159, v115, s[26:27]
	s_waitcnt vmcnt(48)
; __device__ __forceinline__ void kraw_items(const Args& a, int gw, int NGW, int lane) {
;     ...
;             for (int ci = 0; ci < 12; ++ci) { const int c = c0 + 12 * cb + ci;
;                 float acc = 0.f;
; #pragma unroll
;                 for (int jj = 0; jj < 64; ++jj) acc += h[jj] * __builtin_bit_cast(float, __builtin_amdgcn_readlane(__builtin_bit_cast(int, wv[ci]), jj));
;                 const int cm = c % 768;
;                 const float delta = fabsf(-3.0701134573253945f + (float)cm * ((-15.350567286626973f + 3.0701134573253945f) / 767.0f));
;                 KR[(size_t)c * (LP + LS) + p] = acc * __expf(-tt * delta); }
	v_mfma_f32_32x32x2_f32 v[96:111], v64, v0, 0
	v_mfma_f32_32x32x2_f32 v[96:111], v65, v1, v[96:111]
	v_mfma_f32_32x32x2_f32 v[96:111], v66, v2, v[96:111]
	v_mfma_f32_32x32x2_f32 v[96:111], v67, v3, v[96:111]
	v_mfma_f32_32x32x2_f32 v[96:111], v68, v4, v[96:111]
	v_mfma_f32_32x32x2_f32 v[96:111], v69, v5, v[96:111]
	v_mfma_f32_32x32x2_f32 v[96:111], v70, v6, v[96:111]
	v_mfma_f32_32x32x2_f32 v[96:111], v71, v7, v[96:111]
	v_mfma_f32_32x32x2_f32 v[96:111], v72, v8, v[96:111]
	v_mfma_f32_32x32x2_f32 v[96:111], v73, v9, v[96:111]
	v_mfma_f32_32x32x2_f32 v[96:111], v74, v10, v[96:111]
	v_mfma_f32_32x32x2_f32 v[96:111], v75, v11, v[96:111]
	v_mfma_f32_32x32x2_f32 v[96:111], v76, v12, v[96:111]
	v_mfma_f32_32x32x2_f32 v[96:111], v77, v13, v[96:111]
	v_mfma_f32_32x32x2_f32 v[96:111], v78, v14, v[96:111]
	v_mfma_f32_32x32x2_f32 v[96:111], v79, v15, v[96:111]
	v_mfma_f32_32x32x2_f32 v[96:111], v80, v16, v[96:111]
	v_mfma_f32_32x32x2_f32 v[96:111], v81, v17, v[96:111]
	v_mfma_f32_32x32x2_f32 v[96:111], v82, v18, v[96:111]
	v_mfma_f32_32x32x2_f32 v[96:111], v83, v19, v[96:111]
	v_mfma_f32_32x32x2_f32 v[96:111], v84, v20, v[96:111]
	v_mfma_f32_32x32x2_f32 v[96:111], v85, v21, v[96:111]
	v_mfma_f32_32x32x2_f32 v[96:111], v86, v22, v[96:111]
	v_mfma_f32_32x32x2_f32 v[96:111], v87, v23, v[96:111]
	v_mfma_f32_32x32x2_f32 v[96:111], v88, v24, v[96:111]
	v_mfma_f32_32x32x2_f32 v[96:111], v89, v25, v[96:111]
	v_mfma_f32_32x32x2_f32 v[96:111], v90, v26, v[96:111]
	v_mfma_f32_32x32x2_f32 v[96:111], v91, v27, v[96:111]
	v_mfma_f32_32x32x2_f32 v[96:111], v92, v28, v[96:111]
	v_mfma_f32_32x32x2_f32 v[96:111], v93, v29, v[96:111]
	v_mfma_f32_32x32x2_f32 v[96:111], v94, v30, v[96:111]
	v_mfma_f32_32x32x2_f32 v[96:111], v95, v31, v[96:111]
	s_add_i32 s30, s29, 0
	v_add_u32_e32 v119, s30, v118
	v_cvt_f32_u32_e32 v119, v119
	v_fmamk_f32 v119, v119, 0xbc83298c, v120
	v_mul_f32_e64 v119, v117, |v119|
	v_mul_f32_e32 v119, 0x3fb8aa3b, v119
	v_exp_f32_e32 v160, v119
	s_add_i32 s30, s29, 1
	v_add_u32_e32 v119, s30, v118
	v_cvt_f32_u32_e32 v119, v119
	v_fmamk_f32 v119, v119, 0xbc83298c, v120
	v_mul_f32_e64 v119, v117, |v119|
	v_mul_f32_e32 v119, 0x3fb8aa3b, v119
	v_exp_f32_e32 v161, v119
	s_add_i32 s30, s29, 2
	v_add_u32_e32 v119, s30, v118
	v_cvt_f32_u32_e32 v119, v119
	v_fmamk_f32 v119, v119, 0xbc83298c, v120
	v_mul_f32_e64 v119, v117, |v119|
	v_mul_f32_e32 v119, 0x3fb8aa3b, v119
	v_exp_f32_e32 v162, v119
	s_add_i32 s30, s29, 3
	v_add_u32_e32 v119, s30, v118
	v_cvt_f32_u32_e32 v119, v119
	v_fmamk_f32 v119, v119, 0xbc83298c, v120
	v_mul_f32_e64 v119, v117, |v119|
	v_mul_f32_e32 v119, 0x3fb8aa3b, v119
	v_exp_f32_e32 v163, v119
	s_add_i32 s30, s29, 8
	v_add_u32_e32 v119, s30, v118
	v_cvt_f32_u32_e32 v119, v119
	v_fmamk_f32 v119, v119, 0xbc83298c, v120
	v_mul_f32_e64 v119, v117, |v119|
	v_mul_f32_e32 v119, 0x3fb8aa3b, v119
	v_exp_f32_e32 v164, v119
	s_add_i32 s30, s29, 9
	v_add_u32_e32 v119, s30, v118
	v_cvt_f32_u32_e32 v119, v119
	v_fmamk_f32 v119, v119, 0xbc83298c, v120
	v_mul_f32_e64 v119, v117, |v119|
	v_mul_f32_e32 v119, 0x3fb8aa3b, v119
	v_exp_f32_e32 v165, v119
	s_add_i32 s30, s29, 10
	v_add_u32_e32 v119, s30, v118
	v_cvt_f32_u32_e32 v119, v119
	v_fmamk_f32 v119, v119, 0xbc83298c, v120
	v_mul_f32_e64 v119, v117, |v119|
	v_mul_f32_e32 v119, 0x3fb8aa3b, v119
	v_exp_f32_e32 v166, v119
	s_add_i32 s30, s29, 11
	v_add_u32_e32 v119, s30, v118
	v_cvt_f32_u32_e32 v119, v119
	v_fmamk_f32 v119, v119, 0xbc83298c, v120
	v_mul_f32_e64 v119, v117, |v119|
	v_mul_f32_e32 v119, 0x3fb8aa3b, v119
	v_exp_f32_e32 v167, v119
	s_add_i32 s30, s29, 16
	v_add_u32_e32 v119, s30, v118
	v_cvt_f32_u32_e32 v119, v119
	v_fmamk_f32 v119, v119, 0xbc83298c, v120
	v_mul_f32_e64 v119, v117, |v119|
	v_mul_f32_e32 v119, 0x3fb8aa3b, v119
	v_exp_f32_e32 v168, v119
	s_add_i32 s30, s29, 17
	v_add_u32_e32 v119, s30, v118
	v_cvt_f32_u32_e32 v119, v119
	v_fmamk_f32 v119, v119, 0xbc83298c, v120
	v_mul_f32_e64 v119, v117, |v119|
	v_mul_f32_e32 v119, 0x3fb8aa3b, v119
	v_exp_f32_e32 v169, v119
	s_add_i32 s30, s29, 18
	v_add_u32_e32 v119, s30, v118
	v_cvt_f32_u32_e32 v119, v119
	v_fmamk_f32 v119, v119, 0xbc83298c, v120
	v_mul_f32_e64 v119, v117, |v119|
	v_mul_f32_e32 v119, 0x3fb8aa3b, v119
	v_exp_f32_e32 v170, v119
	s_add_i32 s30, s29, 19
	v_add_u32_e32 v119, s30, v118
	v_cvt_f32_u32_e32 v119, v119
	v_fmamk_f32 v119, v119, 0xbc83298c, v120
	v_mul_f32_e64 v119, v117, |v119|
	v_mul_f32_e32 v119, 0x3fb8aa3b, v119
	v_exp_f32_e32 v171, v119
	s_add_i32 s30, s29, 24
	v_add_u32_e32 v119, s30, v118
	v_cvt_f32_u32_e32 v119, v119
	v_fmamk_f32 v119, v119, 0xbc83298c, v120
	v_mul_f32_e64 v119, v117, |v119|
	v_mul_f32_e32 v119, 0x3fb8aa3b, v119
	v_exp_f32_e32 v172, v119
	s_add_i32 s30, s29, 25
	v_add_u32_e32 v119, s30, v118
	v_cvt_f32_u32_e32 v119, v119
	v_fmamk_f32 v119, v119, 0xbc83298c, v120
	v_mul_f32_e64 v119, v117, |v119|
	v_mul_f32_e32 v119, 0x3fb8aa3b, v119
	v_exp_f32_e32 v173, v119
	s_add_i32 s30, s29, 26
	v_add_u32_e32 v119, s30, v118
	v_cvt_f32_u32_e32 v119, v119
	v_fmamk_f32 v119, v119, 0xbc83298c, v120
	v_mul_f32_e64 v119, v117, |v119|
	v_mul_f32_e32 v119, 0x3fb8aa3b, v119
	v_exp_f32_e32 v174, v119
	s_add_i32 s30, s29, 27
	v_add_u32_e32 v119, s30, v118
	v_cvt_f32_u32_e32 v119, v119
	v_fmamk_f32 v119, v119, 0xbc83298c, v120
	v_mul_f32_e64 v119, v117, |v119|
	v_mul_f32_e32 v119, 0x3fb8aa3b, v119
	v_exp_f32_e32 v175, v119
	s_nop 7
	v_mul_f32_e32 v176, v96, v160
	s_mov_b64 s[36:37], s[34:35]
	global_store_dword v115, v176, s[36:37]
	v_mul_f32_e32 v177, v97, v161
	s_add_u32 s36, s34, 0xc000
	s_addc_u32 s37, s35, 0
	global_store_dword v115, v177, s[36:37]
	v_mul_f32_e32 v178, v98, v162
	s_add_u32 s36, s34, 0x18000
; __device__ __forceinline__ void kraw_items(const Args& a, int gw, int NGW, int lane) {
;     ...
;             const float* wr = a.in[I_FWOUT] + lane * 1536 + c0 + 12 * cb;
;             const f32x4 w0 = *(const f32x4*)(wr), w1 = *(const f32x4*)(wr + 4), w2 = *(const f32x4*)(wr + 8);
;             float wv[12] = {w0.x, w0.y, w0.z, w0.w, w1.x, w1.y, w1.z, w1.w, w2.x, w2.y, w2.z, w2.w};
; #pragma unroll
;             for (int ci = 0; ci < 12; ++ci) { const int c = c0 + 12 * cb + ci;
;                 float acc = 0.f;
; #pragma unroll
;                 for (int jj = 0; jj < 64; ++jj) acc += h[jj] * __builtin_bit_cast(float, __builtin_amdgcn_readlane(__builtin_bit_cast(int, wv[ci]), jj));
;                 const int cm = c % 768;
;                 const float delta = fabsf(-3.0701134573253945f + (float)cm * ((-15.350567286626973f + 3.0701134573253945f) / 767.0f));
;                 KR[(size_t)c * (LP + LS) + p] = acc * __expf(-tt * delta); }
	s_addc_u32 s37, s35, 0
	global_store_dword v115, v178, s[36:37]
	v_mul_f32_e32 v179, v99, v163
	s_add_u32 s36, s34, 0x24000
	s_addc_u32 s37, s35, 0
	global_store_dword v115, v179, s[36:37]
	v_mul_f32_e32 v180, v100, v164
	s_add_u32 s36, s34, 0x60000
	s_addc_u32 s37, s35, 0
	global_store_dword v115, v180, s[36:37]
	v_mul_f32_e32 v181, v101, v165
	s_add_u32 s36, s34, 0x6c000
	s_addc_u32 s37, s35, 0
	global_store_dword v115, v181, s[36:37]
	v_mul_f32_e32 v182, v102, v166
	s_add_u32 s36, s34, 0x78000
	s_addc_u32 s37, s35, 0
	global_store_dword v115, v182, s[36:37]
	v_mul_f32_e32 v183, v103, v167
	s_add_u32 s36, s34, 0x84000
	s_addc_u32 s37, s35, 0
	global_store_dword v115, v183, s[36:37]
	v_mul_f32_e32 v184, v104, v168
	s_add_u32 s36, s34, 0xc0000
	s_addc_u32 s37, s35, 0
	global_store_dword v115, v184, s[36:37]
	v_mul_f32_e32 v185, v105, v169
	s_add_u32 s36, s34, 0xcc000
	s_addc_u32 s37, s35, 0
	global_store_dword v115, v185, s[36:37]
	v_mul_f32_e32 v186, v106, v170
	s_add_u32 s36, s34, 0xd8000
	s_addc_u32 s37, s35, 0
	global_store_dword v115, v186, s[36:37]
	v_mul_f32_e32 v187, v107, v171
	s_add_u32 s36, s34, 0xe4000
	s_addc_u32 s37, s35, 0
	global_store_dword v115, v187, s[36:37]
	v_mul_f32_e32 v188, v108, v172
	s_add_u32 s36, s34, 0x120000
	s_addc_u32 s37, s35, 0
	global_store_dword v115, v188, s[36:37]
	v_mul_f32_e32 v189, v109, v173
	s_add_u32 s36, s34, 0x12c000
	s_addc_u32 s37, s35, 0
	global_store_dword v115, v189, s[36:37]
	v_mul_f32_e32 v190, v110, v174
	s_add_u32 s36, s34, 0x138000
	s_addc_u32 s37, s35, 0
	global_store_dword v115, v190, s[36:37]
	v_mul_f32_e32 v191, v111, v175
	s_add_u32 s36, s34, 0x144000
	s_addc_u32 s37, s35, 0
	global_store_dword v115, v191, s[36:37]
	s_add_i32 s28, s21, 32
	s_sub_i32 s29, s28, 0x300
	s_cmp_ge_u32 s28, 0x300
	s_cselect_b32 s29, s29, s28
	s_mul_i32 s30, s28, 0xc000
	s_lshl_b32 s35, s20, 2
	s_add_u32 s30, s30, s35
	s_add_u32 s34, s14, s30
	s_addc_u32 s35, s15, 0
	s_add_i32 s30, s21, 64
	s_lshl_b32 s30, s30, 2
	s_add_u32 s26, s6, s30
	s_addc_u32 s27, s7, 0
	global_load_dword v64, v115, s[26:27]
	s_add_u32 s26, s26, 0x1800
	s_addc_u32 s27, s27, 0
	global_load_dword v65, v115, s[26:27]
	s_add_u32 s26, s26, 0x1800
	s_addc_u32 s27, s27, 0
	global_load_dword v66, v115, s[26:27]
	s_add_u32 s26, s26, 0x1800
	s_addc_u32 s27, s27, 0
	global_load_dword v67, v115, s[26:27]
	s_add_u32 s26, s26, 0x1800
	s_addc_u32 s27, s27, 0
	global_load_dword v68, v115, s[26:27]
	s_add_u32 s26, s26, 0x1800
	s_addc_u32 s27, s27, 0
	global_load_dword v69, v115, s[26:27]
	s_add_u32 s26, s26, 0x1800
	s_addc_u32 s27, s27, 0
	global_load_dword v70, v115, s[26:27]
	s_add_u32 s26, s26, 0x1800
	s_addc_u32 s27, s27, 0
	global_load_dword v71, v115, s[26:27]
	s_add_u32 s26, s26, 0x1800
	s_addc_u32 s27, s27, 0
	global_load_dword v72, v115, s[26:27]
	s_add_u32 s26, s26, 0x1800
	s_addc_u32 s27, s27, 0
	global_load_dword v73, v115, s[26:27]
	s_add_u32 s26, s26, 0x1800
	s_addc_u32 s27, s27, 0
	global_load_dword v74, v115, s[26:27]
	s_add_u32 s26, s26, 0x1800
	s_addc_u32 s27, s27, 0
	global_load_dword v75, v115, s[26:27]
	s_add_u32 s26, s26, 0x1800
	s_addc_u32 s27, s27, 0
	global_load_dword v76, v115, s[26:27]
	s_add_u32 s26, s26, 0x1800
	s_addc_u32 s27, s27, 0
	global_load_dword v77, v115, s[26:27]
	s_add_u32 s26, s26, 0x1800
	s_addc_u32 s27, s27, 0
	global_load_dword v78, v115, s[26:27]
	s_add_u32 s26, s26, 0x1800
	s_addc_u32 s27, s27, 0
	global_load_dword v79, v115, s[26:27]
	s_add_u32 s26, s26, 0x1800
	s_addc_u32 s27, s27, 0
	global_load_dword v80, v115, s[26:27]
	s_add_u32 s26, s26, 0x1800
	s_addc_u32 s27, s27, 0
	global_load_dword v81, v115, s[26:27]
	s_add_u32 s26, s26, 0x1800
	s_addc_u32 s27, s27, 0
	global_load_dword v82, v115, s[26:27]
	s_add_u32 s26, s26, 0x1800
	s_addc_u32 s27, s27, 0
	global_load_dword v83, v115, s[26:27]
	s_add_u32 s26, s26, 0x1800
	s_addc_u32 s27, s27, 0
	global_load_dword v84, v115, s[26:27]
	s_add_u32 s26, s26, 0x1800
	s_addc_u32 s27, s27, 0
	global_load_dword v85, v115, s[26:27]
	s_add_u32 s26, s26, 0x1800
	s_addc_u32 s27, s27, 0
	global_load_dword v86, v115, s[26:27]
	s_add_u32 s26, s26, 0x1800
	s_addc_u32 s27, s27, 0
	global_load_dword v87, v115, s[26:27]
	s_add_u32 s26, s26, 0x1800
	s_addc_u32 s27, s27, 0
	global_load_dword v88, v115, s[26:27]
	s_add_u32 s26, s26, 0x1800
	s_addc_u32 s27, s27, 0
	global_load_dword v89, v115, s[26:27]
	s_add_u32 s26, s26, 0x1800
	s_addc_u32 s27, s27, 0
	global_load_dword v90, v115, s[26:27]
	s_add_u32 s26, s26, 0x1800
	s_addc_u32 s27, s27, 0
	global_load_dword v91, v115, s[26:27]
	s_add_u32 s26, s26, 0x1800
	s_addc_u32 s27, s27, 0
	global_load_dword v92, v115, s[26:27]
	s_add_u32 s26, s26, 0x1800
	s_addc_u32 s27, s27, 0
	global_load_dword v93, v115, s[26:27]
	s_add_u32 s26, s26, 0x1800
	s_addc_u32 s27, s27, 0
	global_load_dword v94, v115, s[26:27]
	s_add_u32 s26, s26, 0x1800
	s_addc_u32 s27, s27, 0
	global_load_dword v95, v115, s[26:27]
	s_waitcnt vmcnt(48)
; __device__ __forceinline__ void kraw_items(const Args& a, int gw, int NGW, int lane) {
;     ...
;             for (int ci = 0; ci < 12; ++ci) { const int c = c0 + 12 * cb + ci;
;                 float acc = 0.f;
; #pragma unroll
;                 for (int jj = 0; jj < 64; ++jj) acc += h[jj] * __builtin_bit_cast(float, __builtin_amdgcn_readlane(__builtin_bit_cast(int, wv[ci]), jj));
;                 const int cm = c % 768;
;                 const float delta = fabsf(-3.0701134573253945f + (float)cm * ((-15.350567286626973f + 3.0701134573253945f) / 767.0f));
;                 KR[(size_t)c * (LP + LS) + p] = acc * __expf(-tt * delta); }
	v_mfma_f32_32x32x2_f32 v[96:111], v128, v0, 0
	v_mfma_f32_32x32x2_f32 v[96:111], v129, v1, v[96:111]
	v_mfma_f32_32x32x2_f32 v[96:111], v130, v2, v[96:111]
	v_mfma_f32_32x32x2_f32 v[96:111], v131, v3, v[96:111]
	v_mfma_f32_32x32x2_f32 v[96:111], v132, v4, v[96:111]
	v_mfma_f32_32x32x2_f32 v[96:111], v133, v5, v[96:111]
	v_mfma_f32_32x32x2_f32 v[96:111], v134, v6, v[96:111]
	v_mfma_f32_32x32x2_f32 v[96:111], v135, v7, v[96:111]
	v_mfma_f32_32x32x2_f32 v[96:111], v136, v8, v[96:111]
	v_mfma_f32_32x32x2_f32 v[96:111], v137, v9, v[96:111]
	v_mfma_f32_32x32x2_f32 v[96:111], v138, v10, v[96:111]
	v_mfma_f32_32x32x2_f32 v[96:111], v139, v11, v[96:111]
	v_mfma_f32_32x32x2_f32 v[96:111], v140, v12, v[96:111]
	v_mfma_f32_32x32x2_f32 v[96:111], v141, v13, v[96:111]
	v_mfma_f32_32x32x2_f32 v[96:111], v142, v14, v[96:111]
	v_mfma_f32_32x32x2_f32 v[96:111], v143, v15, v[96:111]
	v_mfma_f32_32x32x2_f32 v[96:111], v144, v16, v[96:111]
	v_mfma_f32_32x32x2_f32 v[96:111], v145, v17, v[96:111]
	v_mfma_f32_32x32x2_f32 v[96:111], v146, v18, v[96:111]
	v_mfma_f32_32x32x2_f32 v[96:111], v147, v19, v[96:111]
	v_mfma_f32_32x32x2_f32 v[96:111], v148, v20, v[96:111]
	v_mfma_f32_32x32x2_f32 v[96:111], v149, v21, v[96:111]
	v_mfma_f32_32x32x2_f32 v[96:111], v150, v22, v[96:111]
	v_mfma_f32_32x32x2_f32 v[96:111], v151, v23, v[96:111]
	v_mfma_f32_32x32x2_f32 v[96:111], v152, v24, v[96:111]
	v_mfma_f32_32x32x2_f32 v[96:111], v153, v25, v[96:111]
	v_mfma_f32_32x32x2_f32 v[96:111], v154, v26, v[96:111]
	v_mfma_f32_32x32x2_f32 v[96:111], v155, v27, v[96:111]
	v_mfma_f32_32x32x2_f32 v[96:111], v156, v28, v[96:111]
	v_mfma_f32_32x32x2_f32 v[96:111], v157, v29, v[96:111]
	v_mfma_f32_32x32x2_f32 v[96:111], v158, v30, v[96:111]
	v_mfma_f32_32x32x2_f32 v[96:111], v159, v31, v[96:111]
	s_add_i32 s30, s29, 0
	v_add_u32_e32 v119, s30, v118
	v_cvt_f32_u32_e32 v119, v119
	v_fmamk_f32 v119, v119, 0xbc83298c, v120
	v_mul_f32_e64 v119, v117, |v119|
	v_mul_f32_e32 v119, 0x3fb8aa3b, v119
	v_exp_f32_e32 v160, v119
	s_add_i32 s30, s29, 1
	v_add_u32_e32 v119, s30, v118
	v_cvt_f32_u32_e32 v119, v119
	v_fmamk_f32 v119, v119, 0xbc83298c, v120
	v_mul_f32_e64 v119, v117, |v119|
	v_mul_f32_e32 v119, 0x3fb8aa3b, v119
	v_exp_f32_e32 v161, v119
	s_add_i32 s30, s29, 2
	v_add_u32_e32 v119, s30, v118
	v_cvt_f32_u32_e32 v119, v119
	v_fmamk_f32 v119, v119, 0xbc83298c, v120
	v_mul_f32_e64 v119, v117, |v119|
	v_mul_f32_e32 v119, 0x3fb8aa3b, v119
	v_exp_f32_e32 v162, v119
	s_add_i32 s30, s29, 3
	v_add_u32_e32 v119, s30, v118
	v_cvt_f32_u32_e32 v119, v119
	v_fmamk_f32 v119, v119, 0xbc83298c, v120
	v_mul_f32_e64 v119, v117, |v119|
	v_mul_f32_e32 v119, 0x3fb8aa3b, v119
	v_exp_f32_e32 v163, v119
	s_add_i32 s30, s29, 8
	v_add_u32_e32 v119, s30, v118
	v_cvt_f32_u32_e32 v119, v119
	v_fmamk_f32 v119, v119, 0xbc83298c, v120
	v_mul_f32_e64 v119, v117, |v119|
	v_mul_f32_e32 v119, 0x3fb8aa3b, v119
	v_exp_f32_e32 v164, v119
	s_add_i32 s30, s29, 9
	v_add_u32_e32 v119, s30, v118
	v_cvt_f32_u32_e32 v119, v119
	v_fmamk_f32 v119, v119, 0xbc83298c, v120
	v_mul_f32_e64 v119, v117, |v119|
	v_mul_f32_e32 v119, 0x3fb8aa3b, v119
	v_exp_f32_e32 v165, v119
	s_add_i32 s30, s29, 10
	v_add_u32_e32 v119, s30, v118
	v_cvt_f32_u32_e32 v119, v119
	v_fmamk_f32 v119, v119, 0xbc83298c, v120
	v_mul_f32_e64 v119, v117, |v119|
	v_mul_f32_e32 v119, 0x3fb8aa3b, v119
	v_exp_f32_e32 v166, v119
	s_add_i32 s30, s29, 11
	v_add_u32_e32 v119, s30, v118
	v_cvt_f32_u32_e32 v119, v119
	v_fmamk_f32 v119, v119, 0xbc83298c, v120
	v_mul_f32_e64 v119, v117, |v119|
	v_mul_f32_e32 v119, 0x3fb8aa3b, v119
	v_exp_f32_e32 v167, v119
	s_add_i32 s30, s29, 16
	v_add_u32_e32 v119, s30, v118
	v_cvt_f32_u32_e32 v119, v119
	v_fmamk_f32 v119, v119, 0xbc83298c, v120
	v_mul_f32_e64 v119, v117, |v119|
	v_mul_f32_e32 v119, 0x3fb8aa3b, v119
	v_exp_f32_e32 v168, v119
	s_add_i32 s30, s29, 17
	v_add_u32_e32 v119, s30, v118
	v_cvt_f32_u32_e32 v119, v119
	v_fmamk_f32 v119, v119, 0xbc83298c, v120
	v_mul_f32_e64 v119, v117, |v119|
	v_mul_f32_e32 v119, 0x3fb8aa3b, v119
	v_exp_f32_e32 v169, v119
	s_add_i32 s30, s29, 18
	v_add_u32_e32 v119, s30, v118
	v_cvt_f32_u32_e32 v119, v119
	v_fmamk_f32 v119, v119, 0xbc83298c, v120
	v_mul_f32_e64 v119, v117, |v119|
	v_mul_f32_e32 v119, 0x3fb8aa3b, v119
	v_exp_f32_e32 v170, v119
	s_add_i32 s30, s29, 19
	v_add_u32_e32 v119, s30, v118
	v_cvt_f32_u32_e32 v119, v119
	v_fmamk_f32 v119, v119, 0xbc83298c, v120
	v_mul_f32_e64 v119, v117, |v119|
	v_mul_f32_e32 v119, 0x3fb8aa3b, v119
	v_exp_f32_e32 v171, v119
	s_add_i32 s30, s29, 24
	v_add_u32_e32 v119, s30, v118
	v_cvt_f32_u32_e32 v119, v119
	v_fmamk_f32 v119, v119, 0xbc83298c, v120
	v_mul_f32_e64 v119, v117, |v119|
	v_mul_f32_e32 v119, 0x3fb8aa3b, v119
	v_exp_f32_e32 v172, v119
	s_add_i32 s30, s29, 25
	v_add_u32_e32 v119, s30, v118
	v_cvt_f32_u32_e32 v119, v119
	v_fmamk_f32 v119, v119, 0xbc83298c, v120
	v_mul_f32_e64 v119, v117, |v119|
	v_mul_f32_e32 v119, 0x3fb8aa3b, v119
	v_exp_f32_e32 v173, v119
	s_add_i32 s30, s29, 26
	v_add_u32_e32 v119, s30, v118
	v_cvt_f32_u32_e32 v119, v119
	v_fmamk_f32 v119, v119, 0xbc83298c, v120
	v_mul_f32_e64 v119, v117, |v119|
	v_mul_f32_e32 v119, 0x3fb8aa3b, v119
	v_exp_f32_e32 v174, v119
	s_add_i32 s30, s29, 27
	v_add_u32_e32 v119, s30, v118
	v_cvt_f32_u32_e32 v119, v119
	v_fmamk_f32 v119, v119, 0xbc83298c, v120
	v_mul_f32_e64 v119, v117, |v119|
	v_mul_f32_e32 v119, 0x3fb8aa3b, v119
	v_exp_f32_e32 v175, v119
	s_nop 7
	v_mul_f32_e32 v176, v96, v160
	s_mov_b64 s[36:37], s[34:35]
	global_store_dword v115, v176, s[36:37]
	v_mul_f32_e32 v177, v97, v161
	s_add_u32 s36, s34, 0xc000
	s_addc_u32 s37, s35, 0
	global_store_dword v115, v177, s[36:37]
	v_mul_f32_e32 v178, v98, v162
; __device__ __forceinline__ void kraw_items(const Args& a, int gw, int NGW, int lane) {
;     ...
;             for (int ci = 0; ci < 12; ++ci) { const int c = c0 + 12 * cb + ci;
;                 float acc = 0.f;
; #pragma unroll
;                 for (int jj = 0; jj < 64; ++jj) acc += h[jj] * __builtin_bit_cast(float, __builtin_amdgcn_readlane(__builtin_bit_cast(int, wv[ci]), jj));
;                 const int cm = c % 768;
;                 const float delta = fabsf(-3.0701134573253945f + (float)cm * ((-15.350567286626973f + 3.0701134573253945f) / 767.0f));
;                 KR[(size_t)c * (LP + LS) + p] = acc * __expf(-tt * delta); }
	s_add_u32 s36, s34, 0x18000
	s_addc_u32 s37, s35, 0
	global_store_dword v115, v178, s[36:37]
	v_mul_f32_e32 v179, v99, v163
	s_add_u32 s36, s34, 0x24000
	s_addc_u32 s37, s35, 0
	global_store_dword v115, v179, s[36:37]
	v_mul_f32_e32 v180, v100, v164
	s_add_u32 s36, s34, 0x60000
	s_addc_u32 s37, s35, 0
	global_store_dword v115, v180, s[36:37]
	v_mul_f32_e32 v181, v101, v165
	s_add_u32 s36, s34, 0x6c000
	s_addc_u32 s37, s35, 0
	global_store_dword v115, v181, s[36:37]
	v_mul_f32_e32 v182, v102, v166
	s_add_u32 s36, s34, 0x78000
	s_addc_u32 s37, s35, 0
	global_store_dword v115, v182, s[36:37]
	v_mul_f32_e32 v183, v103, v167
	s_add_u32 s36, s34, 0x84000
	s_addc_u32 s37, s35, 0
	global_store_dword v115, v183, s[36:37]
	v_mul_f32_e32 v184, v104, v168
	s_add_u32 s36, s34, 0xc0000
	s_addc_u32 s37, s35, 0
	global_store_dword v115, v184, s[36:37]
	v_mul_f32_e32 v185, v105, v169
	s_add_u32 s36, s34, 0xcc000
	s_addc_u32 s37, s35, 0
	global_store_dword v115, v185, s[36:37]
	v_mul_f32_e32 v186, v106, v170
	s_add_u32 s36, s34, 0xd8000
	s_addc_u32 s37, s35, 0
	global_store_dword v115, v186, s[36:37]
	v_mul_f32_e32 v187, v107, v171
	s_add_u32 s36, s34, 0xe4000
	s_addc_u32 s37, s35, 0
	global_store_dword v115, v187, s[36:37]
	v_mul_f32_e32 v188, v108, v172
	s_add_u32 s36, s34, 0x120000
	s_addc_u32 s37, s35, 0
	global_store_dword v115, v188, s[36:37]
	v_mul_f32_e32 v189, v109, v173
	s_add_u32 s36, s34, 0x12c000
	s_addc_u32 s37, s35, 0
	global_store_dword v115, v189, s[36:37]
	v_mul_f32_e32 v190, v110, v174
	s_add_u32 s36, s34, 0x138000
	s_addc_u32 s37, s35, 0
	global_store_dword v115, v190, s[36:37]
	v_mul_f32_e32 v191, v111, v175
	s_add_u32 s36, s34, 0x144000
	s_addc_u32 s37, s35, 0
	global_store_dword v115, v191, s[36:37]
	s_add_i32 s28, s21, 64
	s_sub_i32 s29, s28, 0x300
	s_cmp_ge_u32 s28, 0x300
	s_cselect_b32 s29, s29, s28
	s_mul_i32 s30, s28, 0xc000
	s_lshl_b32 s35, s20, 2
	s_add_u32 s30, s30, s35
	s_add_u32 s34, s14, s30
	s_addc_u32 s35, s15, 0
	s_waitcnt vmcnt(16)
	v_mfma_f32_32x32x2_f32 v[96:111], v64, v0, 0
	v_mfma_f32_32x32x2_f32 v[96:111], v65, v1, v[96:111]
	v_mfma_f32_32x32x2_f32 v[96:111], v66, v2, v[96:111]
	v_mfma_f32_32x32x2_f32 v[96:111], v67, v3, v[96:111]
	v_mfma_f32_32x32x2_f32 v[96:111], v68, v4, v[96:111]
	v_mfma_f32_32x32x2_f32 v[96:111], v69, v5, v[96:111]
	v_mfma_f32_32x32x2_f32 v[96:111], v70, v6, v[96:111]
	v_mfma_f32_32x32x2_f32 v[96:111], v71, v7, v[96:111]
	v_mfma_f32_32x32x2_f32 v[96:111], v72, v8, v[96:111]
	v_mfma_f32_32x32x2_f32 v[96:111], v73, v9, v[96:111]
	v_mfma_f32_32x32x2_f32 v[96:111], v74, v10, v[96:111]
	v_mfma_f32_32x32x2_f32 v[96:111], v75, v11, v[96:111]
	v_mfma_f32_32x32x2_f32 v[96:111], v76, v12, v[96:111]
	v_mfma_f32_32x32x2_f32 v[96:111], v77, v13, v[96:111]
	v_mfma_f32_32x32x2_f32 v[96:111], v78, v14, v[96:111]
	v_mfma_f32_32x32x2_f32 v[96:111], v79, v15, v[96:111]
	v_mfma_f32_32x32x2_f32 v[96:111], v80, v16, v[96:111]
	v_mfma_f32_32x32x2_f32 v[96:111], v81, v17, v[96:111]
	v_mfma_f32_32x32x2_f32 v[96:111], v82, v18, v[96:111]
	v_mfma_f32_32x32x2_f32 v[96:111], v83, v19, v[96:111]
	v_mfma_f32_32x32x2_f32 v[96:111], v84, v20, v[96:111]
	v_mfma_f32_32x32x2_f32 v[96:111], v85, v21, v[96:111]
	v_mfma_f32_32x32x2_f32 v[96:111], v86, v22, v[96:111]
	v_mfma_f32_32x32x2_f32 v[96:111], v87, v23, v[96:111]
	v_mfma_f32_32x32x2_f32 v[96:111], v88, v24, v[96:111]
	v_mfma_f32_32x32x2_f32 v[96:111], v89, v25, v[96:111]
	v_mfma_f32_32x32x2_f32 v[96:111], v90, v26, v[96:111]
	v_mfma_f32_32x32x2_f32 v[96:111], v91, v27, v[96:111]
	v_mfma_f32_32x32x2_f32 v[96:111], v92, v28, v[96:111]
	v_mfma_f32_32x32x2_f32 v[96:111], v93, v29, v[96:111]
	v_mfma_f32_32x32x2_f32 v[96:111], v94, v30, v[96:111]
	v_mfma_f32_32x32x2_f32 v[96:111], v95, v31, v[96:111]
	s_add_i32 s30, s29, 0
	v_add_u32_e32 v119, s30, v118
	v_cvt_f32_u32_e32 v119, v119
	v_fmamk_f32 v119, v119, 0xbc83298c, v120
	v_mul_f32_e64 v119, v117, |v119|
	v_mul_f32_e32 v119, 0x3fb8aa3b, v119
	v_exp_f32_e32 v160, v119
	s_add_i32 s30, s29, 1
	v_add_u32_e32 v119, s30, v118
	v_cvt_f32_u32_e32 v119, v119
	v_fmamk_f32 v119, v119, 0xbc83298c, v120
	v_mul_f32_e64 v119, v117, |v119|
	v_mul_f32_e32 v119, 0x3fb8aa3b, v119
	v_exp_f32_e32 v161, v119
	s_add_i32 s30, s29, 2
	v_add_u32_e32 v119, s30, v118
	v_cvt_f32_u32_e32 v119, v119
	v_fmamk_f32 v119, v119, 0xbc83298c, v120
	v_mul_f32_e64 v119, v117, |v119|
	v_mul_f32_e32 v119, 0x3fb8aa3b, v119
	v_exp_f32_e32 v162, v119
	s_add_i32 s30, s29, 3
	v_add_u32_e32 v119, s30, v118
	v_cvt_f32_u32_e32 v119, v119
	v_fmamk_f32 v119, v119, 0xbc83298c, v120
	v_mul_f32_e64 v119, v117, |v119|
	v_mul_f32_e32 v119, 0x3fb8aa3b, v119
	v_exp_f32_e32 v163, v119
	s_add_i32 s30, s29, 8
	v_add_u32_e32 v119, s30, v118
; __device__ __forceinline__ void kraw_items(const Args& a, int gw, int NGW, int lane) {
;     ...
;             for (int ci = 0; ci < 12; ++ci) { const int c = c0 + 12 * cb + ci;
;                 float acc = 0.f;
; #pragma unroll
;                 for (int jj = 0; jj < 64; ++jj) acc += h[jj] * __builtin_bit_cast(float, __builtin_amdgcn_readlane(__builtin_bit_cast(int, wv[ci]), jj));
;                 const int cm = c % 768;
;                 const float delta = fabsf(-3.0701134573253945f + (float)cm * ((-15.350567286626973f + 3.0701134573253945f) / 767.0f));
;                 KR[(size_t)c * (LP + LS) + p] = acc * __expf(-tt * delta); }
	v_cvt_f32_u32_e32 v119, v119
	v_fmamk_f32 v119, v119, 0xbc83298c, v120
	v_mul_f32_e64 v119, v117, |v119|
	v_mul_f32_e32 v119, 0x3fb8aa3b, v119
	v_exp_f32_e32 v164, v119
	s_add_i32 s30, s29, 9
	v_add_u32_e32 v119, s30, v118
	v_cvt_f32_u32_e32 v119, v119
	v_fmamk_f32 v119, v119, 0xbc83298c, v120
	v_mul_f32_e64 v119, v117, |v119|
	v_mul_f32_e32 v119, 0x3fb8aa3b, v119
	v_exp_f32_e32 v165, v119
	s_add_i32 s30, s29, 10
	v_add_u32_e32 v119, s30, v118
	v_cvt_f32_u32_e32 v119, v119
	v_fmamk_f32 v119, v119, 0xbc83298c, v120
	v_mul_f32_e64 v119, v117, |v119|
	v_mul_f32_e32 v119, 0x3fb8aa3b, v119
	v_exp_f32_e32 v166, v119
	s_add_i32 s30, s29, 11
	v_add_u32_e32 v119, s30, v118
	v_cvt_f32_u32_e32 v119, v119
	v_fmamk_f32 v119, v119, 0xbc83298c, v120
	v_mul_f32_e64 v119, v117, |v119|
	v_mul_f32_e32 v119, 0x3fb8aa3b, v119
	v_exp_f32_e32 v167, v119
	s_add_i32 s30, s29, 16
	v_add_u32_e32 v119, s30, v118
	v_cvt_f32_u32_e32 v119, v119
	v_fmamk_f32 v119, v119, 0xbc83298c, v120
	v_mul_f32_e64 v119, v117, |v119|
	v_mul_f32_e32 v119, 0x3fb8aa3b, v119
	v_exp_f32_e32 v168, v119
	s_add_i32 s30, s29, 17
	v_add_u32_e32 v119, s30, v118
	v_cvt_f32_u32_e32 v119, v119
	v_fmamk_f32 v119, v119, 0xbc83298c, v120
	v_mul_f32_e64 v119, v117, |v119|
	v_mul_f32_e32 v119, 0x3fb8aa3b, v119
	v_exp_f32_e32 v169, v119
	s_add_i32 s30, s29, 18
	v_add_u32_e32 v119, s30, v118
	v_cvt_f32_u32_e32 v119, v119
	v_fmamk_f32 v119, v119, 0xbc83298c, v120
	v_mul_f32_e64 v119, v117, |v119|
	v_mul_f32_e32 v119, 0x3fb8aa3b, v119
	v_exp_f32_e32 v170, v119
	s_add_i32 s30, s29, 19
	v_add_u32_e32 v119, s30, v118
	v_cvt_f32_u32_e32 v119, v119
	v_fmamk_f32 v119, v119, 0xbc83298c, v120
	v_mul_f32_e64 v119, v117, |v119|
	v_mul_f32_e32 v119, 0x3fb8aa3b, v119
	v_exp_f32_e32 v171, v119
	s_add_i32 s30, s29, 24
	v_add_u32_e32 v119, s30, v118
	v_cvt_f32_u32_e32 v119, v119
	v_fmamk_f32 v119, v119, 0xbc83298c, v120
	v_mul_f32_e64 v119, v117, |v119|
	v_mul_f32_e32 v119, 0x3fb8aa3b, v119
	v_exp_f32_e32 v172, v119
	s_add_i32 s30, s29, 25
	v_add_u32_e32 v119, s30, v118
	v_cvt_f32_u32_e32 v119, v119
	v_fmamk_f32 v119, v119, 0xbc83298c, v120
	v_mul_f32_e64 v119, v117, |v119|
	v_mul_f32_e32 v119, 0x3fb8aa3b, v119
	v_exp_f32_e32 v173, v119
	s_add_i32 s30, s29, 26
	v_add_u32_e32 v119, s30, v118
	v_cvt_f32_u32_e32 v119, v119
	v_fmamk_f32 v119, v119, 0xbc83298c, v120
	v_mul_f32_e64 v119, v117, |v119|
	v_mul_f32_e32 v119, 0x3fb8aa3b, v119
	v_exp_f32_e32 v174, v119
	s_add_i32 s30, s29, 27
	v_add_u32_e32 v119, s30, v118
	v_cvt_f32_u32_e32 v119, v119
	v_fmamk_f32 v119, v119, 0xbc83298c, v120
	v_mul_f32_e64 v119, v117, |v119|
	v_mul_f32_e32 v119, 0x3fb8aa3b, v119
	v_exp_f32_e32 v175, v119
	s_nop 7
	v_mul_f32_e32 v176, v96, v160
	s_mov_b64 s[36:37], s[34:35]
	global_store_dword v115, v176, s[36:37]
	v_mul_f32_e32 v177, v97, v161
	s_add_u32 s36, s34, 0xc000
	s_addc_u32 s37, s35, 0
	global_store_dword v115, v177, s[36:37]
	v_mul_f32_e32 v178, v98, v162
	s_add_u32 s36, s34, 0x18000
	s_addc_u32 s37, s35, 0
	global_store_dword v115, v178, s[36:37]
	v_mul_f32_e32 v179, v99, v163
	s_add_u32 s36, s34, 0x24000
	s_addc_u32 s37, s35, 0
	global_store_dword v115, v179, s[36:37]
	v_mul_f32_e32 v180, v100, v164
	s_add_u32 s36, s34, 0x60000
	s_addc_u32 s37, s35, 0
	global_store_dword v115, v180, s[36:37]
	v_mul_f32_e32 v181, v101, v165
	s_add_u32 s36, s34, 0x6c000
	s_addc_u32 s37, s35, 0
	global_store_dword v115, v181, s[36:37]
	v_mul_f32_e32 v182, v102, v166
	s_add_u32 s36, s34, 0x78000
	s_addc_u32 s37, s35, 0
	global_store_dword v115, v182, s[36:37]
	v_mul_f32_e32 v183, v103, v167
	s_add_u32 s36, s34, 0x84000
	s_addc_u32 s37, s35, 0
	global_store_dword v115, v183, s[36:37]
	v_mul_f32_e32 v184, v104, v168
	s_add_u32 s36, s34, 0xc0000
	s_addc_u32 s37, s35, 0
	global_store_dword v115, v184, s[36:37]
	v_mul_f32_e32 v185, v105, v169
	s_add_u32 s36, s34, 0xcc000
	s_addc_u32 s37, s35, 0
	global_store_dword v115, v185, s[36:37]
	v_mul_f32_e32 v186, v106, v170
	s_add_u32 s36, s34, 0xd8000
	s_addc_u32 s37, s35, 0
	global_store_dword v115, v186, s[36:37]
	v_mul_f32_e32 v187, v107, v171
	s_add_u32 s36, s34, 0xe4000
	s_addc_u32 s37, s35, 0
	global_store_dword v115, v187, s[36:37]
	v_mul_f32_e32 v188, v108, v172
	s_add_u32 s36, s34, 0x120000
	s_addc_u32 s37, s35, 0
	global_store_dword v115, v188, s[36:37]
	v_mul_f32_e32 v189, v109, v173
	s_add_u32 s36, s34, 0x12c000
	s_addc_u32 s37, s35, 0
	global_store_dword v115, v189, s[36:37]
	v_mul_f32_e32 v190, v110, v174
	s_add_u32 s36, s34, 0x138000
	s_addc_u32 s37, s35, 0
	global_store_dword v115, v190, s[36:37]
	v_mul_f32_e32 v191, v111, v175
	s_add_u32 s36, s34, 0x144000
	s_addc_u32 s37, s35, 0
	global_store_dword v115, v191, s[36:37]
	s_branch .LBB0_122

; __device__ __forceinline__ float bf_lo(unsigned w) { return __uint_as_float(w << 16); }
; __device__ __forceinline__ float bf_hi(unsigned w) { return __uint_as_float(w & 0xffff0000u); }
; __device__ __forceinline__ unsigned pk2(float lo, float hi) { return pg8::cvt_pk_bf16(lo, hi); }
; #define PH_IDS() const int tid = lnd((int)threadIdx.x), lane = tid & 63, wave = __builtin_amdgcn_readfirstlane(tid >> 6), gw = bid * 8 + wave; (void)lane; (void)gw
; #define REPS(k) for (int rep_ = 0; rep_ < (((REP_MASK >> (k)) & 1) ? 2 : 1); ++rep_)
; __device__ __forceinline__ void merge_rows(const Args& a, int gw, int NGW, int lane) {
;     ...
;     for (int mb = gw; mb < MT; mb += 4 * NGW) {
;         float l[4][3]; v2u o[4][3];
; #pragma unroll
;         for (int r = 0; r < 4; ++r) { const int m = mb + r * NGW; const int mc = m < MT ? m : mb;
; #pragma unroll
;             for (int g = 0; g < 3; ++g) { l[r][g] = LSE[((size_t)g * MT + mc) * 4 + hh]; o[r][g] = *(const v2u*)(OG + ((size_t)g * MT + mc) * 256 + 4 * lane); } }
; #pragma unroll
;         for (int r = 0; r < 4; ++r) { const int m = mb + r * NGW; if (m < MT) {
;             const float mxl = fmaxf(l[r][0], fmaxf(l[r][1], l[r][2]));
;             float a0 = __expf(l[r][0] - mxl), a1 = __expf(l[r][1] - mxl), a2 = __expf(l[r][2] - mxl); const float is = 1.0f / (a0 + a1 + a2); a0 *= is; a1 *= is; a2 *= is;
;             const v2u o0 = o[r][0], o1 = o[r][1], o2 = o[r][2];
;             v2u w;
;             w.x = pk2(a0 * pg8::bf_lo(o0.x) + a1 * pg8::bf_lo(o1.x) + a2 * pg8::bf_lo(o2.x), a0 * pg8::bf_hi(o0.x) + a1 * pg8::bf_hi(o1.x) + a2 * pg8::bf_hi(o2.x));
;             w.y = pk2(a0 * pg8::bf_lo(o0.y) + a1 * pg8::bf_lo(o1.y) + a2 * pg8::bf_lo(o2.y), a0 * pg8::bf_hi(o0.y) + a1 * pg8::bf_hi(o1.y) + a2 * pg8::bf_hi(o2.y));
;             *(v2u*)(YAT + (size_t)m * 256 + 4 * lane) = w; } }
; template <int PHM> __global__ void __launch_bounds__(512, 2) mk_fwd(Args karg) {
;     ...
;     if (IN(4)) REPS(4) { PH_ARGS(); { PH_IDS();
;         merge_rows(a, gw, NGW, lane); }
.LBB0_457:
	s_cmp_lt_i32 s78, 5
	s_cselect_b64 s[2:3], -1, 0
	s_and_b64 s[10:11], s[2:3], s[0:1]
	s_andn2_b64 vcc, exec, s[10:11]
	s_cbranch_vccnz .LBB0_613
	s_mov_b64 s[0:1], s[72:73]
	s_load_dwordx4 s[12:15], s[0:1], 0xe0
	v_mov_b32_e32 v0, v254
	s_lshl_b32 s2, s96, 3
	v_readfirstlane_b32 s0, v0
	s_ashr_i32 s0, s0, 6
	s_add_i32 s18, s0, s2
	s_cmp_gt_i32 s18, 0x17fff
	s_cbranch_scc1 .LBB0_467
	s_cmp_eq_u32 s70, 0x100
	s_cbranch_scc0 .Lorig_merge
	v_and_b32_e32 v66, 63, v254
	v_lshrrev_b32_e32 v64, 5, v66
	v_and_b32_e32 v66, 31, v66
	v_lshlrev_b32_e32 v65, 15, v64
	v_lshlrev_b32_e32 v64, 20, v64
	v_lshl_add_u32 v64, v66, 4, v64
	v_lshrrev_b32_e32 v66, 3, v66
	v_lshl_add_u32 v65, v66, 2, v65
	v_readfirstlane_b32 s16, v254
	s_nop 3
	s_lshl_b32 s17, s96, 3
	s_lshr_b32 s16, s16, 6
	s_add_i32 s16, s16, s17
	s_waitcnt lgkmcnt(0)
	s_mov_b64 s[6:7], s[14:15]
	s_lshl_b32 s17, s16, 9
	s_add_u32 s20, s6, s17
	s_addc_u32 s21, s7, 0
	s_add_u32 s20, s20, 0x2a000000
	s_addc_u32 s21, s21, 0
	s_add_u32 s24, s6, s17
	s_addc_u32 s25, s7, 0
	s_add_u32 s24, s24, 0x3c000000
	s_addc_u32 s25, s25, 0
	s_lshl_b32 s17, s16, 4
	s_add_u32 s22, s6, s17
	s_addc_u32 s23, s7, 0
	s_add_u32 s22, s22, 0x33000000
	s_addc_u32 s23, s23, 0
	s_mov_b64 s[26:27], s[20:21]
	global_load_dwordx4 v[0:3], v64, s[26:27]
	s_add_u32 s26, s20, 0x3000000
	s_addc_u32 s27, s21, 0
	global_load_dwordx4 v[4:7], v64, s[26:27]
	s_add_u32 s26, s20, 0x6000000
	s_addc_u32 s27, s21, 0
	global_load_dwordx4 v[8:11], v64, s[26:27]
	s_mov_b64 s[26:27], s[22:23]
	global_load_dword v12, v65, s[26:27]
	s_add_u32 s26, s22, 0x180000
	s_addc_u32 s27, s23, 0
	global_load_dword v13, v65, s[26:27]
	s_add_u32 s26, s22, 0x300000
	s_addc_u32 s27, s23, 0
	global_load_dword v14, v65, s[26:27]
	s_add_u32 s26, s20, 0x200000
	s_addc_u32 s27, s21, 0
	global_load_dwordx4 v[16:19], v64, s[26:27]
	s_add_u32 s26, s20, 0x3200000
	s_addc_u32 s27, s21, 0
	global_load_dwordx4 v[20:23], v64, s[26:27]
	s_add_u32 s26, s20, 0x6200000
	s_addc_u32 s27, s21, 0
	global_load_dwordx4 v[24:27], v64, s[26:27]
	s_add_u32 s26, s22, 0x10000
	s_addc_u32 s27, s23, 0
	global_load_dword v28, v65, s[26:27]
	s_add_u32 s26, s22, 0x190000
	s_addc_u32 s27, s23, 0
	global_load_dword v29, v65, s[26:27]
	s_add_u32 s26, s22, 0x310000
	s_addc_u32 s27, s23, 0
	global_load_dword v30, v65, s[26:27]
	s_add_u32 s26, s20, 0x400000
	s_addc_u32 s27, s21, 0
	global_load_dwordx4 v[32:35], v64, s[26:27]
	s_add_u32 s26, s20, 0x3400000
	s_addc_u32 s27, s21, 0
	global_load_dwordx4 v[36:39], v64, s[26:27]
	s_add_u32 s26, s20, 0x6400000
	s_addc_u32 s27, s21, 0
	global_load_dwordx4 v[40:43], v64, s[26:27]
	s_add_u32 s26, s22, 0x20000
	s_addc_u32 s27, s23, 0
	global_load_dword v44, v65, s[26:27]
	s_add_u32 s26, s22, 0x1a0000
	s_addc_u32 s27, s23, 0
	global_load_dword v45, v65, s[26:27]
	s_add_u32 s26, s22, 0x320000
	s_addc_u32 s27, s23, 0
	global_load_dword v46, v65, s[26:27]
	s_add_u32 s26, s20, 0x600000
	s_addc_u32 s27, s21, 0
	global_load_dwordx4 v[48:51], v64, s[26:27]
	s_add_u32 s26, s20, 0x3600000
	s_addc_u32 s27, s21, 0
	global_load_dwordx4 v[52:55], v64, s[26:27]
	s_add_u32 s26, s20, 0x6600000
	s_addc_u32 s27, s21, 0
	global_load_dwordx4 v[56:59], v64, s[26:27]
	s_add_u32 s26, s22, 0x30000
	s_addc_u32 s27, s23, 0
	global_load_dword v60, v65, s[26:27]
	s_add_u32 s26, s22, 0x1b0000
	s_addc_u32 s27, s23, 0
	global_load_dword v61, v65, s[26:27]
	s_add_u32 s26, s22, 0x330000
	s_addc_u32 s27, s23, 0
	global_load_dword v62, v65, s[26:27]
	s_waitcnt vmcnt(18)
	v_max3_f32 v68, v12, v13, v14
	v_sub_f32_e32 v69, v12, v68
	v_sub_f32_e32 v70, v13, v68
	v_sub_f32_e32 v71, v14, v68
	v_mul_f32_e32 v69, 0x3fb8aa3b, v69
	v_mul_f32_e32 v70, 0x3fb8aa3b, v70
	v_mul_f32_e32 v71, 0x3fb8aa3b, v71
	v_exp_f32_e32 v69, v69
	v_exp_f32_e32 v70, v70
	v_exp_f32_e32 v71, v71
	s_nop 0
	v_add_f32_e32 v72, v69, v70
	v_add_f32_e32 v72, v71, v72
	v_div_scale_f32 v73, s[28:29], v72, v72, 1.0
	v_rcp_f32_e32 v74, v73
	v_div_scale_f32 v75, vcc, 1.0, v72, 1.0
	s_nop 0
	v_fma_f32 v76, -v73, v74, 1.0
	v_fmac_f32_e32 v74, v76, v74
	v_mul_f32_e32 v77, v75, v74
	v_fma_f32 v76, -v73, v77, v75
	v_fmac_f32_e32 v77, v76, v74
	v_fma_f32 v73, -v73, v77, v75
	v_div_fmas_f32 v73, v73, v74, v77
	v_div_fixup_f32 v72, v73, v72, 1.0
	v_mul_f32_e32 v69, v69, v72
	v_mul_f32_e32 v70, v70, v72
	v_mul_f32_e32 v71, v71, v72
	v_lshlrev_b32_e32 v78, 16, v0
	v_and_b32_e32 v81, 0xffff0000, v0
	v_lshlrev_b32_e32 v79, 16, v4
	v_and_b32_e32 v82, 0xffff0000, v4
	v_lshlrev_b32_e32 v80, 16, v8
	v_and_b32_e32 v83, 0xffff0000, v8
	v_mul_f32_e32 v84, v69, v78
	v_mul_f32_e32 v85, v69, v81
	v_fmac_f32_e32 v84, v70, v79
	v_fmac_f32_e32 v85, v70, v82
	v_fmac_f32_e32 v84, v71, v80
	v_fmac_f32_e32 v85, v71, v83
	v_cvt_pk_bf16_f32 v96, v84, v85
	v_lshlrev_b32_e32 v78, 16, v1
	v_and_b32_e32 v81, 0xffff0000, v1
	v_lshlrev_b32_e32 v79, 16, v5
	v_and_b32_e32 v82, 0xffff0000, v5
	v_lshlrev_b32_e32 v80, 16, v9
	v_and_b32_e32 v83, 0xffff0000, v9
	v_mul_f32_e32 v84, v69, v78
	v_mul_f32_e32 v85, v69, v81
	v_fmac_f32_e32 v84, v70, v79
	v_fmac_f32_e32 v85, v70, v82
	v_fmac_f32_e32 v84, v71, v80
	v_fmac_f32_e32 v85, v71, v83
	v_cvt_pk_bf16_f32 v97, v84, v85
	v_lshlrev_b32_e32 v78, 16, v2
	v_and_b32_e32 v81, 0xffff0000, v2
	v_lshlrev_b32_e32 v79, 16, v6
	v_and_b32_e32 v82, 0xffff0000, v6
	v_lshlrev_b32_e32 v80, 16, v10
	v_and_b32_e32 v83, 0xffff0000, v10
	v_mul_f32_e32 v84, v69, v78
	v_mul_f32_e32 v85, v69, v81
	v_fmac_f32_e32 v84, v70, v79
	v_fmac_f32_e32 v85, v70, v82
	v_fmac_f32_e32 v84, v71, v80
	v_fmac_f32_e32 v85, v71, v83
	v_cvt_pk_bf16_f32 v98, v84, v85
	v_lshlrev_b32_e32 v78, 16, v3
	v_and_b32_e32 v81, 0xffff0000, v3
	v_lshlrev_b32_e32 v79, 16, v7
	v_and_b32_e32 v82, 0xffff0000, v7
	v_lshlrev_b32_e32 v80, 16, v11
	v_and_b32_e32 v83, 0xffff0000, v11
	v_mul_f32_e32 v84, v69, v78
	v_mul_f32_e32 v85, v69, v81
	v_fmac_f32_e32 v84, v70, v79
	v_fmac_f32_e32 v85, v70, v82
	v_fmac_f32_e32 v84, v71, v80
	v_fmac_f32_e32 v85, v71, v83
	v_cvt_pk_bf16_f32 v99, v84, v85
	s_mov_b64 s[26:27], s[24:25]
	global_store_dwordx4 v64, v[96:99], s[26:27]
	s_add_u32 s26, s20, 0x800000
	s_addc_u32 s27, s21, 0
	global_load_dwordx4 v[0:3], v64, s[26:27]
	s_add_u32 s26, s20, 0x3800000
	s_addc_u32 s27, s21, 0
	global_load_dwordx4 v[4:7], v64, s[26:27]
	s_add_u32 s26, s20, 0x6800000
	s_addc_u32 s27, s21, 0
	global_load_dwordx4 v[8:11], v64, s[26:27]
	s_add_u32 s26, s22, 0x40000
	s_addc_u32 s27, s23, 0
	global_load_dword v12, v65, s[26:27]
	s_add_u32 s26, s22, 0x1c0000
	s_addc_u32 s27, s23, 0
	global_load_dword v13, v65, s[26:27]
	s_add_u32 s26, s22, 0x340000
	s_addc_u32 s27, s23, 0
	global_load_dword v14, v65, s[26:27]
	s_waitcnt vmcnt(19)
; __device__ __forceinline__ float bf_lo(unsigned w) { return __uint_as_float(w << 16); }
; __device__ __forceinline__ float bf_hi(unsigned w) { return __uint_as_float(w & 0xffff0000u); }
; __device__ __forceinline__ unsigned pk2(float lo, float hi) { return pg8::cvt_pk_bf16(lo, hi); }
; __device__ __forceinline__ void merge_rows(const Args& a, int gw, int NGW, int lane) {
;     ...
;         for (int r = 0; r < 4; ++r) { const int m = mb + r * NGW; if (m < MT) {
;             const float mxl = fmaxf(l[r][0], fmaxf(l[r][1], l[r][2]));
;             float a0 = __expf(l[r][0] - mxl), a1 = __expf(l[r][1] - mxl), a2 = __expf(l[r][2] - mxl); const float is = 1.0f / (a0 + a1 + a2); a0 *= is; a1 *= is; a2 *= is;
;             const v2u o0 = o[r][0], o1 = o[r][1], o2 = o[r][2];
;             v2u w;
;             w.x = pk2(a0 * pg8::bf_lo(o0.x) + a1 * pg8::bf_lo(o1.x) + a2 * pg8::bf_lo(o2.x), a0 * pg8::bf_hi(o0.x) + a1 * pg8::bf_hi(o1.x) + a2 * pg8::bf_hi(o2.x));
;             w.y = pk2(a0 * pg8::bf_lo(o0.y) + a1 * pg8::bf_lo(o1.y) + a2 * pg8::bf_lo(o2.y), a0 * pg8::bf_hi(o0.y) + a1 * pg8::bf_hi(o1.y) + a2 * pg8::bf_hi(o2.y));
;             *(v2u*)(YAT + (size_t)m * 256 + 4 * lane) = w; } }
	v_max3_f32 v68, v28, v29, v30
	v_sub_f32_e32 v69, v28, v68
	v_sub_f32_e32 v70, v29, v68
	v_sub_f32_e32 v71, v30, v68
	v_mul_f32_e32 v69, 0x3fb8aa3b, v69
	v_mul_f32_e32 v70, 0x3fb8aa3b, v70
	v_mul_f32_e32 v71, 0x3fb8aa3b, v71
	v_exp_f32_e32 v69, v69
	v_exp_f32_e32 v70, v70
	v_exp_f32_e32 v71, v71
	s_nop 0
	v_add_f32_e32 v72, v69, v70
	v_add_f32_e32 v72, v71, v72
	v_div_scale_f32 v73, s[28:29], v72, v72, 1.0
	v_rcp_f32_e32 v74, v73
	v_div_scale_f32 v75, vcc, 1.0, v72, 1.0
	s_nop 0
	v_fma_f32 v76, -v73, v74, 1.0
	v_fmac_f32_e32 v74, v76, v74
	v_mul_f32_e32 v77, v75, v74
	v_fma_f32 v76, -v73, v77, v75
	v_fmac_f32_e32 v77, v76, v74
	v_fma_f32 v73, -v73, v77, v75
	v_div_fmas_f32 v73, v73, v74, v77
	v_div_fixup_f32 v72, v73, v72, 1.0
	v_mul_f32_e32 v69, v69, v72
	v_mul_f32_e32 v70, v70, v72
	v_mul_f32_e32 v71, v71, v72
	v_lshlrev_b32_e32 v78, 16, v16
	v_and_b32_e32 v81, 0xffff0000, v16
	v_lshlrev_b32_e32 v79, 16, v20
	v_and_b32_e32 v82, 0xffff0000, v20
	v_lshlrev_b32_e32 v80, 16, v24
	v_and_b32_e32 v83, 0xffff0000, v24
	v_mul_f32_e32 v84, v69, v78
	v_mul_f32_e32 v85, v69, v81
	v_fmac_f32_e32 v84, v70, v79
	v_fmac_f32_e32 v85, v70, v82
	v_fmac_f32_e32 v84, v71, v80
	v_fmac_f32_e32 v85, v71, v83
	v_cvt_pk_bf16_f32 v100, v84, v85
	v_lshlrev_b32_e32 v78, 16, v17
	v_and_b32_e32 v81, 0xffff0000, v17
	v_lshlrev_b32_e32 v79, 16, v21
	v_and_b32_e32 v82, 0xffff0000, v21
	v_lshlrev_b32_e32 v80, 16, v25
	v_and_b32_e32 v83, 0xffff0000, v25
	v_mul_f32_e32 v84, v69, v78
	v_mul_f32_e32 v85, v69, v81
	v_fmac_f32_e32 v84, v70, v79
	v_fmac_f32_e32 v85, v70, v82
	v_fmac_f32_e32 v84, v71, v80
	v_fmac_f32_e32 v85, v71, v83
	v_cvt_pk_bf16_f32 v101, v84, v85
	v_lshlrev_b32_e32 v78, 16, v18
	v_and_b32_e32 v81, 0xffff0000, v18
	v_lshlrev_b32_e32 v79, 16, v22
	v_and_b32_e32 v82, 0xffff0000, v22
	v_lshlrev_b32_e32 v80, 16, v26
	v_and_b32_e32 v83, 0xffff0000, v26
	v_mul_f32_e32 v84, v69, v78
	v_mul_f32_e32 v85, v69, v81
	v_fmac_f32_e32 v84, v70, v79
	v_fmac_f32_e32 v85, v70, v82
	v_fmac_f32_e32 v84, v71, v80
	v_fmac_f32_e32 v85, v71, v83
	v_cvt_pk_bf16_f32 v102, v84, v85
	v_lshlrev_b32_e32 v78, 16, v19
	v_and_b32_e32 v81, 0xffff0000, v19
	v_lshlrev_b32_e32 v79, 16, v23
	v_and_b32_e32 v82, 0xffff0000, v23
	v_lshlrev_b32_e32 v80, 16, v27
	v_and_b32_e32 v83, 0xffff0000, v27
	v_mul_f32_e32 v84, v69, v78
	v_mul_f32_e32 v85, v69, v81
	v_fmac_f32_e32 v84, v70, v79
	v_fmac_f32_e32 v85, v70, v82
	v_fmac_f32_e32 v84, v71, v80
	v_fmac_f32_e32 v85, v71, v83
	v_cvt_pk_bf16_f32 v103, v84, v85
	s_add_u32 s26, s24, 0x200000
	s_addc_u32 s27, s25, 0
	global_store_dwordx4 v64, v[100:103], s[26:27]
	s_add_u32 s26, s20, 0xa00000
	s_addc_u32 s27, s21, 0
	global_load_dwordx4 v[16:19], v64, s[26:27]
	s_add_u32 s26, s20, 0x3a00000
	s_addc_u32 s27, s21, 0
	global_load_dwordx4 v[20:23], v64, s[26:27]
	s_add_u32 s26, s20, 0x6a00000
	s_addc_u32 s27, s21, 0
	global_load_dwordx4 v[24:27], v64, s[26:27]
	s_add_u32 s26, s22, 0x50000
	s_addc_u32 s27, s23, 0
	global_load_dword v28, v65, s[26:27]
	s_add_u32 s26, s22, 0x1d0000
	s_addc_u32 s27, s23, 0
	global_load_dword v29, v65, s[26:27]
	s_add_u32 s26, s22, 0x350000
	s_addc_u32 s27, s23, 0
	global_load_dword v30, v65, s[26:27]
	s_waitcnt vmcnt(20)
	v_max3_f32 v68, v44, v45, v46
	v_sub_f32_e32 v69, v44, v68
	v_sub_f32_e32 v70, v45, v68
	v_sub_f32_e32 v71, v46, v68
	v_mul_f32_e32 v69, 0x3fb8aa3b, v69
	v_mul_f32_e32 v70, 0x3fb8aa3b, v70
	v_mul_f32_e32 v71, 0x3fb8aa3b, v71
	v_exp_f32_e32 v69, v69
	v_exp_f32_e32 v70, v70
	v_exp_f32_e32 v71, v71
	s_nop 0
	v_add_f32_e32 v72, v69, v70
	v_add_f32_e32 v72, v71, v72
	v_div_scale_f32 v73, s[28:29], v72, v72, 1.0
	v_rcp_f32_e32 v74, v73
	v_div_scale_f32 v75, vcc, 1.0, v72, 1.0
	s_nop 0
	v_fma_f32 v76, -v73, v74, 1.0
	v_fmac_f32_e32 v74, v76, v74
	v_mul_f32_e32 v77, v75, v74
	v_fma_f32 v76, -v73, v77, v75
	v_fmac_f32_e32 v77, v76, v74
	v_fma_f32 v73, -v73, v77, v75
	v_div_fmas_f32 v73, v73, v74, v77
	v_div_fixup_f32 v72, v73, v72, 1.0
	v_mul_f32_e32 v69, v69, v72
	v_mul_f32_e32 v70, v70, v72
	v_mul_f32_e32 v71, v71, v72
	v_lshlrev_b32_e32 v78, 16, v32
	v_and_b32_e32 v81, 0xffff0000, v32
	v_lshlrev_b32_e32 v79, 16, v36
	v_and_b32_e32 v82, 0xffff0000, v36
	v_lshlrev_b32_e32 v80, 16, v40
	v_and_b32_e32 v83, 0xffff0000, v40
	v_mul_f32_e32 v84, v69, v78
	v_mul_f32_e32 v85, v69, v81
	v_fmac_f32_e32 v84, v70, v79
	v_fmac_f32_e32 v85, v70, v82
	v_fmac_f32_e32 v84, v71, v80
	v_fmac_f32_e32 v85, v71, v83
	v_cvt_pk_bf16_f32 v96, v84, v85
	v_lshlrev_b32_e32 v78, 16, v33
	v_and_b32_e32 v81, 0xffff0000, v33
	v_lshlrev_b32_e32 v79, 16, v37
	v_and_b32_e32 v82, 0xffff0000, v37
	v_lshlrev_b32_e32 v80, 16, v41
	v_and_b32_e32 v83, 0xffff0000, v41
	v_mul_f32_e32 v84, v69, v78
	v_mul_f32_e32 v85, v69, v81
	v_fmac_f32_e32 v84, v70, v79
	v_fmac_f32_e32 v85, v70, v82
	v_fmac_f32_e32 v84, v71, v80
	v_fmac_f32_e32 v85, v71, v83
	v_cvt_pk_bf16_f32 v97, v84, v85
	v_lshlrev_b32_e32 v78, 16, v34
	v_and_b32_e32 v81, 0xffff0000, v34
	v_lshlrev_b32_e32 v79, 16, v38
	v_and_b32_e32 v82, 0xffff0000, v38
	v_lshlrev_b32_e32 v80, 16, v42
	v_and_b32_e32 v83, 0xffff0000, v42
	v_mul_f32_e32 v84, v69, v78
	v_mul_f32_e32 v85, v69, v81
	v_fmac_f32_e32 v84, v70, v79
	v_fmac_f32_e32 v85, v70, v82
	v_fmac_f32_e32 v84, v71, v80
	v_fmac_f32_e32 v85, v71, v83
	v_cvt_pk_bf16_f32 v98, v84, v85
	v_lshlrev_b32_e32 v78, 16, v35
	v_and_b32_e32 v81, 0xffff0000, v35
	v_lshlrev_b32_e32 v79, 16, v39
	v_and_b32_e32 v82, 0xffff0000, v39
	v_lshlrev_b32_e32 v80, 16, v43
	v_and_b32_e32 v83, 0xffff0000, v43
	v_mul_f32_e32 v84, v69, v78
	v_mul_f32_e32 v85, v69, v81
	v_fmac_f32_e32 v84, v70, v79
	v_fmac_f32_e32 v85, v70, v82
	v_fmac_f32_e32 v84, v71, v80
	v_fmac_f32_e32 v85, v71, v83
	v_cvt_pk_bf16_f32 v99, v84, v85
	s_add_u32 s26, s24, 0x400000
	s_addc_u32 s27, s25, 0
	global_store_dwordx4 v64, v[96:99], s[26:27]
	s_add_u32 s26, s20, 0xc00000
	s_addc_u32 s27, s21, 0
	global_load_dwordx4 v[32:35], v64, s[26:27]
	s_add_u32 s26, s20, 0x3c00000
	s_addc_u32 s27, s21, 0
	global_load_dwordx4 v[36:39], v64, s[26:27]
	s_add_u32 s26, s20, 0x6c00000
	s_addc_u32 s27, s21, 0
	global_load_dwordx4 v[40:43], v64, s[26:27]
	s_add_u32 s26, s22, 0x60000
	s_addc_u32 s27, s23, 0
	global_load_dword v44, v65, s[26:27]
	s_add_u32 s26, s22, 0x1e0000
	s_addc_u32 s27, s23, 0
	global_load_dword v45, v65, s[26:27]
	s_add_u32 s26, s22, 0x360000
	s_addc_u32 s27, s23, 0
	global_load_dword v46, v65, s[26:27]
	s_waitcnt vmcnt(21)
; __device__ __forceinline__ float bf_lo(unsigned w) { return __uint_as_float(w << 16); }
; __device__ __forceinline__ float bf_hi(unsigned w) { return __uint_as_float(w & 0xffff0000u); }
; __device__ __forceinline__ unsigned pk2(float lo, float hi) { return pg8::cvt_pk_bf16(lo, hi); }
; __device__ __forceinline__ void merge_rows(const Args& a, int gw, int NGW, int lane) {
;     ...
;         for (int r = 0; r < 4; ++r) { const int m = mb + r * NGW; if (m < MT) {
;             const float mxl = fmaxf(l[r][0], fmaxf(l[r][1], l[r][2]));
;             float a0 = __expf(l[r][0] - mxl), a1 = __expf(l[r][1] - mxl), a2 = __expf(l[r][2] - mxl); const float is = 1.0f / (a0 + a1 + a2); a0 *= is; a1 *= is; a2 *= is;
;             const v2u o0 = o[r][0], o1 = o[r][1], o2 = o[r][2];
;             v2u w;
;             w.x = pk2(a0 * pg8::bf_lo(o0.x) + a1 * pg8::bf_lo(o1.x) + a2 * pg8::bf_lo(o2.x), a0 * pg8::bf_hi(o0.x) + a1 * pg8::bf_hi(o1.x) + a2 * pg8::bf_hi(o2.x));
;             w.y = pk2(a0 * pg8::bf_lo(o0.y) + a1 * pg8::bf_lo(o1.y) + a2 * pg8::bf_lo(o2.y), a0 * pg8::bf_hi(o0.y) + a1 * pg8::bf_hi(o1.y) + a2 * pg8::bf_hi(o2.y));
;             *(v2u*)(YAT + (size_t)m * 256 + 4 * lane) = w; } }
	v_max3_f32 v68, v60, v61, v62
	v_sub_f32_e32 v69, v60, v68
	v_sub_f32_e32 v70, v61, v68
	v_sub_f32_e32 v71, v62, v68
	v_mul_f32_e32 v69, 0x3fb8aa3b, v69
	v_mul_f32_e32 v70, 0x3fb8aa3b, v70
	v_mul_f32_e32 v71, 0x3fb8aa3b, v71
	v_exp_f32_e32 v69, v69
	v_exp_f32_e32 v70, v70
	v_exp_f32_e32 v71, v71
	s_nop 0
	v_add_f32_e32 v72, v69, v70
	v_add_f32_e32 v72, v71, v72
	v_div_scale_f32 v73, s[28:29], v72, v72, 1.0
	v_rcp_f32_e32 v74, v73
	v_div_scale_f32 v75, vcc, 1.0, v72, 1.0
	s_nop 0
	v_fma_f32 v76, -v73, v74, 1.0
	v_fmac_f32_e32 v74, v76, v74
	v_mul_f32_e32 v77, v75, v74
	v_fma_f32 v76, -v73, v77, v75
	v_fmac_f32_e32 v77, v76, v74
	v_fma_f32 v73, -v73, v77, v75
	v_div_fmas_f32 v73, v73, v74, v77
	v_div_fixup_f32 v72, v73, v72, 1.0
	v_mul_f32_e32 v69, v69, v72
	v_mul_f32_e32 v70, v70, v72
	v_mul_f32_e32 v71, v71, v72
	v_lshlrev_b32_e32 v78, 16, v48
	v_and_b32_e32 v81, 0xffff0000, v48
	v_lshlrev_b32_e32 v79, 16, v52
	v_and_b32_e32 v82, 0xffff0000, v52
	v_lshlrev_b32_e32 v80, 16, v56
	v_and_b32_e32 v83, 0xffff0000, v56
	v_mul_f32_e32 v84, v69, v78
	v_mul_f32_e32 v85, v69, v81
	v_fmac_f32_e32 v84, v70, v79
	v_fmac_f32_e32 v85, v70, v82
	v_fmac_f32_e32 v84, v71, v80
	v_fmac_f32_e32 v85, v71, v83
	v_cvt_pk_bf16_f32 v100, v84, v85
	v_lshlrev_b32_e32 v78, 16, v49
	v_and_b32_e32 v81, 0xffff0000, v49
	v_lshlrev_b32_e32 v79, 16, v53
	v_and_b32_e32 v82, 0xffff0000, v53
	v_lshlrev_b32_e32 v80, 16, v57
	v_and_b32_e32 v83, 0xffff0000, v57
	v_mul_f32_e32 v84, v69, v78
	v_mul_f32_e32 v85, v69, v81
	v_fmac_f32_e32 v84, v70, v79
	v_fmac_f32_e32 v85, v70, v82
	v_fmac_f32_e32 v84, v71, v80
	v_fmac_f32_e32 v85, v71, v83
	v_cvt_pk_bf16_f32 v101, v84, v85
	v_lshlrev_b32_e32 v78, 16, v50
	v_and_b32_e32 v81, 0xffff0000, v50
	v_lshlrev_b32_e32 v79, 16, v54
	v_and_b32_e32 v82, 0xffff0000, v54
	v_lshlrev_b32_e32 v80, 16, v58
	v_and_b32_e32 v83, 0xffff0000, v58
	v_mul_f32_e32 v84, v69, v78
	v_mul_f32_e32 v85, v69, v81
	v_fmac_f32_e32 v84, v70, v79
	v_fmac_f32_e32 v85, v70, v82
	v_fmac_f32_e32 v84, v71, v80
	v_fmac_f32_e32 v85, v71, v83
	v_cvt_pk_bf16_f32 v102, v84, v85
	v_lshlrev_b32_e32 v78, 16, v51
	v_and_b32_e32 v81, 0xffff0000, v51
	v_lshlrev_b32_e32 v79, 16, v55
	v_and_b32_e32 v82, 0xffff0000, v55
	v_lshlrev_b32_e32 v80, 16, v59
	v_and_b32_e32 v83, 0xffff0000, v59
	v_mul_f32_e32 v84, v69, v78
	v_mul_f32_e32 v85, v69, v81
	v_fmac_f32_e32 v84, v70, v79
	v_fmac_f32_e32 v85, v70, v82
	v_fmac_f32_e32 v84, v71, v80
	v_fmac_f32_e32 v85, v71, v83
	v_cvt_pk_bf16_f32 v103, v84, v85
	s_add_u32 s26, s24, 0x600000
	s_addc_u32 s27, s25, 0
	global_store_dwordx4 v64, v[100:103], s[26:27]
	s_add_u32 s26, s20, 0xe00000
	s_addc_u32 s27, s21, 0
	global_load_dwordx4 v[48:51], v64, s[26:27]
	s_add_u32 s26, s20, 0x3e00000
	s_addc_u32 s27, s21, 0
	global_load_dwordx4 v[52:55], v64, s[26:27]
	s_add_u32 s26, s20, 0x6e00000
	s_addc_u32 s27, s21, 0
	global_load_dwordx4 v[56:59], v64, s[26:27]
	s_add_u32 s26, s22, 0x70000
	s_addc_u32 s27, s23, 0
	global_load_dword v60, v65, s[26:27]
	s_add_u32 s26, s22, 0x1f0000
	s_addc_u32 s27, s23, 0
	global_load_dword v61, v65, s[26:27]
	s_add_u32 s26, s22, 0x370000
	s_addc_u32 s27, s23, 0
	global_load_dword v62, v65, s[26:27]
	s_waitcnt vmcnt(21)
	v_max3_f32 v68, v12, v13, v14
	v_sub_f32_e32 v69, v12, v68
	v_sub_f32_e32 v70, v13, v68
	v_sub_f32_e32 v71, v14, v68
	v_mul_f32_e32 v69, 0x3fb8aa3b, v69
	v_mul_f32_e32 v70, 0x3fb8aa3b, v70
	v_mul_f32_e32 v71, 0x3fb8aa3b, v71
	v_exp_f32_e32 v69, v69
	v_exp_f32_e32 v70, v70
	v_exp_f32_e32 v71, v71
	s_nop 0
	v_add_f32_e32 v72, v69, v70
	v_add_f32_e32 v72, v71, v72
	v_div_scale_f32 v73, s[28:29], v72, v72, 1.0
	v_rcp_f32_e32 v74, v73
	v_div_scale_f32 v75, vcc, 1.0, v72, 1.0
	s_nop 0
	v_fma_f32 v76, -v73, v74, 1.0
	v_fmac_f32_e32 v74, v76, v74
	v_mul_f32_e32 v77, v75, v74
	v_fma_f32 v76, -v73, v77, v75
	v_fmac_f32_e32 v77, v76, v74
	v_fma_f32 v73, -v73, v77, v75
	v_div_fmas_f32 v73, v73, v74, v77
	v_div_fixup_f32 v72, v73, v72, 1.0
	v_mul_f32_e32 v69, v69, v72
	v_mul_f32_e32 v70, v70, v72
	v_mul_f32_e32 v71, v71, v72
	v_lshlrev_b32_e32 v78, 16, v0
	v_and_b32_e32 v81, 0xffff0000, v0
	v_lshlrev_b32_e32 v79, 16, v4
	v_and_b32_e32 v82, 0xffff0000, v4
	v_lshlrev_b32_e32 v80, 16, v8
	v_and_b32_e32 v83, 0xffff0000, v8
	v_mul_f32_e32 v84, v69, v78
	v_mul_f32_e32 v85, v69, v81
	v_fmac_f32_e32 v84, v70, v79
	v_fmac_f32_e32 v85, v70, v82
	v_fmac_f32_e32 v84, v71, v80
	v_fmac_f32_e32 v85, v71, v83
	v_cvt_pk_bf16_f32 v96, v84, v85
	v_lshlrev_b32_e32 v78, 16, v1
	v_and_b32_e32 v81, 0xffff0000, v1
	v_lshlrev_b32_e32 v79, 16, v5
	v_and_b32_e32 v82, 0xffff0000, v5
	v_lshlrev_b32_e32 v80, 16, v9
	v_and_b32_e32 v83, 0xffff0000, v9
	v_mul_f32_e32 v84, v69, v78
	v_mul_f32_e32 v85, v69, v81
	v_fmac_f32_e32 v84, v70, v79
	v_fmac_f32_e32 v85, v70, v82
	v_fmac_f32_e32 v84, v71, v80
	v_fmac_f32_e32 v85, v71, v83
	v_cvt_pk_bf16_f32 v97, v84, v85
	v_lshlrev_b32_e32 v78, 16, v2
	v_and_b32_e32 v81, 0xffff0000, v2
	v_lshlrev_b32_e32 v79, 16, v6
	v_and_b32_e32 v82, 0xffff0000, v6
	v_lshlrev_b32_e32 v80, 16, v10
	v_and_b32_e32 v83, 0xffff0000, v10
	v_mul_f32_e32 v84, v69, v78
	v_mul_f32_e32 v85, v69, v81
	v_fmac_f32_e32 v84, v70, v79
	v_fmac_f32_e32 v85, v70, v82
	v_fmac_f32_e32 v84, v71, v80
	v_fmac_f32_e32 v85, v71, v83
	v_cvt_pk_bf16_f32 v98, v84, v85
	v_lshlrev_b32_e32 v78, 16, v3
	v_and_b32_e32 v81, 0xffff0000, v3
	v_lshlrev_b32_e32 v79, 16, v7
	v_and_b32_e32 v82, 0xffff0000, v7
	v_lshlrev_b32_e32 v80, 16, v11
	v_and_b32_e32 v83, 0xffff0000, v11
	v_mul_f32_e32 v84, v69, v78
	v_mul_f32_e32 v85, v69, v81
	v_fmac_f32_e32 v84, v70, v79
	v_fmac_f32_e32 v85, v70, v82
	v_fmac_f32_e32 v84, v71, v80
	v_fmac_f32_e32 v85, v71, v83
	v_cvt_pk_bf16_f32 v99, v84, v85
	s_add_u32 s26, s24, 0x800000
	s_addc_u32 s27, s25, 0
	global_store_dwordx4 v64, v[96:99], s[26:27]
	s_add_u32 s26, s20, 0x1000000
	s_addc_u32 s27, s21, 0
	global_load_dwordx4 v[0:3], v64, s[26:27]
	s_add_u32 s26, s20, 0x4000000
	s_addc_u32 s27, s21, 0
	global_load_dwordx4 v[4:7], v64, s[26:27]
	s_add_u32 s26, s20, 0x7000000
	s_addc_u32 s27, s21, 0
	global_load_dwordx4 v[8:11], v64, s[26:27]
	s_add_u32 s26, s22, 0x80000
	s_addc_u32 s27, s23, 0
	global_load_dword v12, v65, s[26:27]
	s_add_u32 s26, s22, 0x200000
	s_addc_u32 s27, s23, 0
	global_load_dword v13, v65, s[26:27]
	s_add_u32 s26, s22, 0x380000
	s_addc_u32 s27, s23, 0
	global_load_dword v14, v65, s[26:27]
	s_waitcnt vmcnt(21)
; __device__ __forceinline__ float bf_lo(unsigned w) { return __uint_as_float(w << 16); }
; __device__ __forceinline__ float bf_hi(unsigned w) { return __uint_as_float(w & 0xffff0000u); }
; __device__ __forceinline__ unsigned pk2(float lo, float hi) { return pg8::cvt_pk_bf16(lo, hi); }
; __device__ __forceinline__ void merge_rows(const Args& a, int gw, int NGW, int lane) {
;     ...
;         for (int r = 0; r < 4; ++r) { const int m = mb + r * NGW; if (m < MT) {
;             const float mxl = fmaxf(l[r][0], fmaxf(l[r][1], l[r][2]));
;             float a0 = __expf(l[r][0] - mxl), a1 = __expf(l[r][1] - mxl), a2 = __expf(l[r][2] - mxl); const float is = 1.0f / (a0 + a1 + a2); a0 *= is; a1 *= is; a2 *= is;
;             const v2u o0 = o[r][0], o1 = o[r][1], o2 = o[r][2];
;             v2u w;
;             w.x = pk2(a0 * pg8::bf_lo(o0.x) + a1 * pg8::bf_lo(o1.x) + a2 * pg8::bf_lo(o2.x), a0 * pg8::bf_hi(o0.x) + a1 * pg8::bf_hi(o1.x) + a2 * pg8::bf_hi(o2.x));
;             w.y = pk2(a0 * pg8::bf_lo(o0.y) + a1 * pg8::bf_lo(o1.y) + a2 * pg8::bf_lo(o2.y), a0 * pg8::bf_hi(o0.y) + a1 * pg8::bf_hi(o1.y) + a2 * pg8::bf_hi(o2.y));
;             *(v2u*)(YAT + (size_t)m * 256 + 4 * lane) = w; } }
	v_max3_f32 v68, v28, v29, v30
	v_sub_f32_e32 v69, v28, v68
	v_sub_f32_e32 v70, v29, v68
	v_sub_f32_e32 v71, v30, v68
	v_mul_f32_e32 v69, 0x3fb8aa3b, v69
	v_mul_f32_e32 v70, 0x3fb8aa3b, v70
	v_mul_f32_e32 v71, 0x3fb8aa3b, v71
	v_exp_f32_e32 v69, v69
	v_exp_f32_e32 v70, v70
	v_exp_f32_e32 v71, v71
	s_nop 0
	v_add_f32_e32 v72, v69, v70
	v_add_f32_e32 v72, v71, v72
	v_div_scale_f32 v73, s[28:29], v72, v72, 1.0
	v_rcp_f32_e32 v74, v73
	v_div_scale_f32 v75, vcc, 1.0, v72, 1.0
	s_nop 0
	v_fma_f32 v76, -v73, v74, 1.0
	v_fmac_f32_e32 v74, v76, v74
	v_mul_f32_e32 v77, v75, v74
	v_fma_f32 v76, -v73, v77, v75
	v_fmac_f32_e32 v77, v76, v74
	v_fma_f32 v73, -v73, v77, v75
	v_div_fmas_f32 v73, v73, v74, v77
	v_div_fixup_f32 v72, v73, v72, 1.0
	v_mul_f32_e32 v69, v69, v72
	v_mul_f32_e32 v70, v70, v72
	v_mul_f32_e32 v71, v71, v72
	v_lshlrev_b32_e32 v78, 16, v16
	v_and_b32_e32 v81, 0xffff0000, v16
	v_lshlrev_b32_e32 v79, 16, v20
	v_and_b32_e32 v82, 0xffff0000, v20
	v_lshlrev_b32_e32 v80, 16, v24
	v_and_b32_e32 v83, 0xffff0000, v24
	v_mul_f32_e32 v84, v69, v78
	v_mul_f32_e32 v85, v69, v81
	v_fmac_f32_e32 v84, v70, v79
	v_fmac_f32_e32 v85, v70, v82
	v_fmac_f32_e32 v84, v71, v80
	v_fmac_f32_e32 v85, v71, v83
	v_cvt_pk_bf16_f32 v100, v84, v85
	v_lshlrev_b32_e32 v78, 16, v17
	v_and_b32_e32 v81, 0xffff0000, v17
	v_lshlrev_b32_e32 v79, 16, v21
	v_and_b32_e32 v82, 0xffff0000, v21
	v_lshlrev_b32_e32 v80, 16, v25
	v_and_b32_e32 v83, 0xffff0000, v25
	v_mul_f32_e32 v84, v69, v78
	v_mul_f32_e32 v85, v69, v81
	v_fmac_f32_e32 v84, v70, v79
	v_fmac_f32_e32 v85, v70, v82
	v_fmac_f32_e32 v84, v71, v80
	v_fmac_f32_e32 v85, v71, v83
	v_cvt_pk_bf16_f32 v101, v84, v85
	v_lshlrev_b32_e32 v78, 16, v18
	v_and_b32_e32 v81, 0xffff0000, v18
	v_lshlrev_b32_e32 v79, 16, v22
	v_and_b32_e32 v82, 0xffff0000, v22
	v_lshlrev_b32_e32 v80, 16, v26
	v_and_b32_e32 v83, 0xffff0000, v26
	v_mul_f32_e32 v84, v69, v78
	v_mul_f32_e32 v85, v69, v81
	v_fmac_f32_e32 v84, v70, v79
	v_fmac_f32_e32 v85, v70, v82
	v_fmac_f32_e32 v84, v71, v80
	v_fmac_f32_e32 v85, v71, v83
	v_cvt_pk_bf16_f32 v102, v84, v85
	v_lshlrev_b32_e32 v78, 16, v19
	v_and_b32_e32 v81, 0xffff0000, v19
	v_lshlrev_b32_e32 v79, 16, v23
	v_and_b32_e32 v82, 0xffff0000, v23
	v_lshlrev_b32_e32 v80, 16, v27
	v_and_b32_e32 v83, 0xffff0000, v27
	v_mul_f32_e32 v84, v69, v78
	v_mul_f32_e32 v85, v69, v81
	v_fmac_f32_e32 v84, v70, v79
	v_fmac_f32_e32 v85, v70, v82
	v_fmac_f32_e32 v84, v71, v80
	v_fmac_f32_e32 v85, v71, v83
	v_cvt_pk_bf16_f32 v103, v84, v85
	s_add_u32 s26, s24, 0xa00000
	s_addc_u32 s27, s25, 0
	global_store_dwordx4 v64, v[100:103], s[26:27]
	s_add_u32 s26, s20, 0x1200000
	s_addc_u32 s27, s21, 0
	global_load_dwordx4 v[16:19], v64, s[26:27]
	s_add_u32 s26, s20, 0x4200000
	s_addc_u32 s27, s21, 0
	global_load_dwordx4 v[20:23], v64, s[26:27]
	s_add_u32 s26, s20, 0x7200000
	s_addc_u32 s27, s21, 0
	global_load_dwordx4 v[24:27], v64, s[26:27]
	s_add_u32 s26, s22, 0x90000
	s_addc_u32 s27, s23, 0
	global_load_dword v28, v65, s[26:27]
	s_add_u32 s26, s22, 0x210000
	s_addc_u32 s27, s23, 0
	global_load_dword v29, v65, s[26:27]
	s_add_u32 s26, s22, 0x390000
	s_addc_u32 s27, s23, 0
	global_load_dword v30, v65, s[26:27]
	s_waitcnt vmcnt(21)
	v_max3_f32 v68, v44, v45, v46
	v_sub_f32_e32 v69, v44, v68
	v_sub_f32_e32 v70, v45, v68
	v_sub_f32_e32 v71, v46, v68
	v_mul_f32_e32 v69, 0x3fb8aa3b, v69
	v_mul_f32_e32 v70, 0x3fb8aa3b, v70
	v_mul_f32_e32 v71, 0x3fb8aa3b, v71
	v_exp_f32_e32 v69, v69
	v_exp_f32_e32 v70, v70
	v_exp_f32_e32 v71, v71
	s_nop 0
	v_add_f32_e32 v72, v69, v70
	v_add_f32_e32 v72, v71, v72
	v_div_scale_f32 v73, s[28:29], v72, v72, 1.0
	v_rcp_f32_e32 v74, v73
	v_div_scale_f32 v75, vcc, 1.0, v72, 1.0
	s_nop 0
	v_fma_f32 v76, -v73, v74, 1.0
	v_fmac_f32_e32 v74, v76, v74
	v_mul_f32_e32 v77, v75, v74
	v_fma_f32 v76, -v73, v77, v75
	v_fmac_f32_e32 v77, v76, v74
	v_fma_f32 v73, -v73, v77, v75
	v_div_fmas_f32 v73, v73, v74, v77
	v_div_fixup_f32 v72, v73, v72, 1.0
	v_mul_f32_e32 v69, v69, v72
	v_mul_f32_e32 v70, v70, v72
	v_mul_f32_e32 v71, v71, v72
	v_lshlrev_b32_e32 v78, 16, v32
	v_and_b32_e32 v81, 0xffff0000, v32
	v_lshlrev_b32_e32 v79, 16, v36
	v_and_b32_e32 v82, 0xffff0000, v36
	v_lshlrev_b32_e32 v80, 16, v40
	v_and_b32_e32 v83, 0xffff0000, v40
	v_mul_f32_e32 v84, v69, v78
	v_mul_f32_e32 v85, v69, v81
	v_fmac_f32_e32 v84, v70, v79
	v_fmac_f32_e32 v85, v70, v82
	v_fmac_f32_e32 v84, v71, v80
	v_fmac_f32_e32 v85, v71, v83
	v_cvt_pk_bf16_f32 v96, v84, v85
	v_lshlrev_b32_e32 v78, 16, v33
	v_and_b32_e32 v81, 0xffff0000, v33
	v_lshlrev_b32_e32 v79, 16, v37
	v_and_b32_e32 v82, 0xffff0000, v37
	v_lshlrev_b32_e32 v80, 16, v41
	v_and_b32_e32 v83, 0xffff0000, v41
	v_mul_f32_e32 v84, v69, v78
	v_mul_f32_e32 v85, v69, v81
	v_fmac_f32_e32 v84, v70, v79
	v_fmac_f32_e32 v85, v70, v82
	v_fmac_f32_e32 v84, v71, v80
	v_fmac_f32_e32 v85, v71, v83
	v_cvt_pk_bf16_f32 v97, v84, v85
	v_lshlrev_b32_e32 v78, 16, v34
	v_and_b32_e32 v81, 0xffff0000, v34
	v_lshlrev_b32_e32 v79, 16, v38
	v_and_b32_e32 v82, 0xffff0000, v38
	v_lshlrev_b32_e32 v80, 16, v42
	v_and_b32_e32 v83, 0xffff0000, v42
	v_mul_f32_e32 v84, v69, v78
	v_mul_f32_e32 v85, v69, v81
	v_fmac_f32_e32 v84, v70, v79
	v_fmac_f32_e32 v85, v70, v82
	v_fmac_f32_e32 v84, v71, v80
	v_fmac_f32_e32 v85, v71, v83
	v_cvt_pk_bf16_f32 v98, v84, v85
	v_lshlrev_b32_e32 v78, 16, v35
	v_and_b32_e32 v81, 0xffff0000, v35
	v_lshlrev_b32_e32 v79, 16, v39
	v_and_b32_e32 v82, 0xffff0000, v39
	v_lshlrev_b32_e32 v80, 16, v43
	v_and_b32_e32 v83, 0xffff0000, v43
	v_mul_f32_e32 v84, v69, v78
	v_mul_f32_e32 v85, v69, v81
	v_fmac_f32_e32 v84, v70, v79
	v_fmac_f32_e32 v85, v70, v82
	v_fmac_f32_e32 v84, v71, v80
	v_fmac_f32_e32 v85, v71, v83
	v_cvt_pk_bf16_f32 v99, v84, v85
	s_add_u32 s26, s24, 0xc00000
	s_addc_u32 s27, s25, 0
	global_store_dwordx4 v64, v[96:99], s[26:27]
	s_add_u32 s26, s20, 0x1400000
	s_addc_u32 s27, s21, 0
	global_load_dwordx4 v[32:35], v64, s[26:27]
	s_add_u32 s26, s20, 0x4400000
	s_addc_u32 s27, s21, 0
	global_load_dwordx4 v[36:39], v64, s[26:27]
	s_add_u32 s26, s20, 0x7400000
	s_addc_u32 s27, s21, 0
	global_load_dwordx4 v[40:43], v64, s[26:27]
	s_add_u32 s26, s22, 0xa0000
	s_addc_u32 s27, s23, 0
	global_load_dword v44, v65, s[26:27]
	s_add_u32 s26, s22, 0x220000
	s_addc_u32 s27, s23, 0
	global_load_dword v45, v65, s[26:27]
	s_add_u32 s26, s22, 0x3a0000
	s_addc_u32 s27, s23, 0
	global_load_dword v46, v65, s[26:27]
	s_waitcnt vmcnt(21)
; __device__ __forceinline__ float bf_lo(unsigned w) { return __uint_as_float(w << 16); }
; __device__ __forceinline__ float bf_hi(unsigned w) { return __uint_as_float(w & 0xffff0000u); }
; __device__ __forceinline__ unsigned pk2(float lo, float hi) { return pg8::cvt_pk_bf16(lo, hi); }
; __device__ __forceinline__ void merge_rows(const Args& a, int gw, int NGW, int lane) {
;     ...
;         for (int r = 0; r < 4; ++r) { const int m = mb + r * NGW; if (m < MT) {
;             const float mxl = fmaxf(l[r][0], fmaxf(l[r][1], l[r][2]));
;             float a0 = __expf(l[r][0] - mxl), a1 = __expf(l[r][1] - mxl), a2 = __expf(l[r][2] - mxl); const float is = 1.0f / (a0 + a1 + a2); a0 *= is; a1 *= is; a2 *= is;
;             const v2u o0 = o[r][0], o1 = o[r][1], o2 = o[r][2];
;             v2u w;
;             w.x = pk2(a0 * pg8::bf_lo(o0.x) + a1 * pg8::bf_lo(o1.x) + a2 * pg8::bf_lo(o2.x), a0 * pg8::bf_hi(o0.x) + a1 * pg8::bf_hi(o1.x) + a2 * pg8::bf_hi(o2.x));
;             w.y = pk2(a0 * pg8::bf_lo(o0.y) + a1 * pg8::bf_lo(o1.y) + a2 * pg8::bf_lo(o2.y), a0 * pg8::bf_hi(o0.y) + a1 * pg8::bf_hi(o1.y) + a2 * pg8::bf_hi(o2.y));
;             *(v2u*)(YAT + (size_t)m * 256 + 4 * lane) = w; } }
	v_max3_f32 v68, v60, v61, v62
	v_sub_f32_e32 v69, v60, v68
	v_sub_f32_e32 v70, v61, v68
	v_sub_f32_e32 v71, v62, v68
	v_mul_f32_e32 v69, 0x3fb8aa3b, v69
	v_mul_f32_e32 v70, 0x3fb8aa3b, v70
	v_mul_f32_e32 v71, 0x3fb8aa3b, v71
	v_exp_f32_e32 v69, v69
	v_exp_f32_e32 v70, v70
	v_exp_f32_e32 v71, v71
	s_nop 0
	v_add_f32_e32 v72, v69, v70
	v_add_f32_e32 v72, v71, v72
	v_div_scale_f32 v73, s[28:29], v72, v72, 1.0
	v_rcp_f32_e32 v74, v73
	v_div_scale_f32 v75, vcc, 1.0, v72, 1.0
	s_nop 0
	v_fma_f32 v76, -v73, v74, 1.0
	v_fmac_f32_e32 v74, v76, v74
	v_mul_f32_e32 v77, v75, v74
	v_fma_f32 v76, -v73, v77, v75
	v_fmac_f32_e32 v77, v76, v74
	v_fma_f32 v73, -v73, v77, v75
	v_div_fmas_f32 v73, v73, v74, v77
	v_div_fixup_f32 v72, v73, v72, 1.0
	v_mul_f32_e32 v69, v69, v72
	v_mul_f32_e32 v70, v70, v72
	v_mul_f32_e32 v71, v71, v72
	v_lshlrev_b32_e32 v78, 16, v48
	v_and_b32_e32 v81, 0xffff0000, v48
	v_lshlrev_b32_e32 v79, 16, v52
	v_and_b32_e32 v82, 0xffff0000, v52
	v_lshlrev_b32_e32 v80, 16, v56
	v_and_b32_e32 v83, 0xffff0000, v56
	v_mul_f32_e32 v84, v69, v78
	v_mul_f32_e32 v85, v69, v81
	v_fmac_f32_e32 v84, v70, v79
	v_fmac_f32_e32 v85, v70, v82
	v_fmac_f32_e32 v84, v71, v80
	v_fmac_f32_e32 v85, v71, v83
	v_cvt_pk_bf16_f32 v100, v84, v85
	v_lshlrev_b32_e32 v78, 16, v49
	v_and_b32_e32 v81, 0xffff0000, v49
	v_lshlrev_b32_e32 v79, 16, v53
	v_and_b32_e32 v82, 0xffff0000, v53
	v_lshlrev_b32_e32 v80, 16, v57
	v_and_b32_e32 v83, 0xffff0000, v57
	v_mul_f32_e32 v84, v69, v78
	v_mul_f32_e32 v85, v69, v81
	v_fmac_f32_e32 v84, v70, v79
	v_fmac_f32_e32 v85, v70, v82
	v_fmac_f32_e32 v84, v71, v80
	v_fmac_f32_e32 v85, v71, v83
	v_cvt_pk_bf16_f32 v101, v84, v85
	v_lshlrev_b32_e32 v78, 16, v50
	v_and_b32_e32 v81, 0xffff0000, v50
	v_lshlrev_b32_e32 v79, 16, v54
	v_and_b32_e32 v82, 0xffff0000, v54
	v_lshlrev_b32_e32 v80, 16, v58
	v_and_b32_e32 v83, 0xffff0000, v58
	v_mul_f32_e32 v84, v69, v78
	v_mul_f32_e32 v85, v69, v81
	v_fmac_f32_e32 v84, v70, v79
	v_fmac_f32_e32 v85, v70, v82
	v_fmac_f32_e32 v84, v71, v80
	v_fmac_f32_e32 v85, v71, v83
	v_cvt_pk_bf16_f32 v102, v84, v85
	v_lshlrev_b32_e32 v78, 16, v51
	v_and_b32_e32 v81, 0xffff0000, v51
	v_lshlrev_b32_e32 v79, 16, v55
	v_and_b32_e32 v82, 0xffff0000, v55
	v_lshlrev_b32_e32 v80, 16, v59
	v_and_b32_e32 v83, 0xffff0000, v59
	v_mul_f32_e32 v84, v69, v78
	v_mul_f32_e32 v85, v69, v81
	v_fmac_f32_e32 v84, v70, v79
	v_fmac_f32_e32 v85, v70, v82
	v_fmac_f32_e32 v84, v71, v80
	v_fmac_f32_e32 v85, v71, v83
	v_cvt_pk_bf16_f32 v103, v84, v85
	s_add_u32 s26, s24, 0xe00000
	s_addc_u32 s27, s25, 0
	global_store_dwordx4 v64, v[100:103], s[26:27]
	s_add_u32 s26, s20, 0x1600000
	s_addc_u32 s27, s21, 0
	global_load_dwordx4 v[48:51], v64, s[26:27]
	s_add_u32 s26, s20, 0x4600000
	s_addc_u32 s27, s21, 0
	global_load_dwordx4 v[52:55], v64, s[26:27]
	s_add_u32 s26, s20, 0x7600000
	s_addc_u32 s27, s21, 0
	global_load_dwordx4 v[56:59], v64, s[26:27]
	s_add_u32 s26, s22, 0xb0000
	s_addc_u32 s27, s23, 0
	global_load_dword v60, v65, s[26:27]
	s_add_u32 s26, s22, 0x230000
	s_addc_u32 s27, s23, 0
	global_load_dword v61, v65, s[26:27]
	s_add_u32 s26, s22, 0x3b0000
	s_addc_u32 s27, s23, 0
	global_load_dword v62, v65, s[26:27]
	s_waitcnt vmcnt(21)
	v_max3_f32 v68, v12, v13, v14
	v_sub_f32_e32 v69, v12, v68
	v_sub_f32_e32 v70, v13, v68
	v_sub_f32_e32 v71, v14, v68
	v_mul_f32_e32 v69, 0x3fb8aa3b, v69
	v_mul_f32_e32 v70, 0x3fb8aa3b, v70
	v_mul_f32_e32 v71, 0x3fb8aa3b, v71
	v_exp_f32_e32 v69, v69
	v_exp_f32_e32 v70, v70
	v_exp_f32_e32 v71, v71
	s_nop 0
	v_add_f32_e32 v72, v69, v70
	v_add_f32_e32 v72, v71, v72
	v_div_scale_f32 v73, s[28:29], v72, v72, 1.0
	v_rcp_f32_e32 v74, v73
	v_div_scale_f32 v75, vcc, 1.0, v72, 1.0
	s_nop 0
	v_fma_f32 v76, -v73, v74, 1.0
	v_fmac_f32_e32 v74, v76, v74
	v_mul_f32_e32 v77, v75, v74
	v_fma_f32 v76, -v73, v77, v75
	v_fmac_f32_e32 v77, v76, v74
	v_fma_f32 v73, -v73, v77, v75
	v_div_fmas_f32 v73, v73, v74, v77
	v_div_fixup_f32 v72, v73, v72, 1.0
	v_mul_f32_e32 v69, v69, v72
	v_mul_f32_e32 v70, v70, v72
	v_mul_f32_e32 v71, v71, v72
	v_lshlrev_b32_e32 v78, 16, v0
	v_and_b32_e32 v81, 0xffff0000, v0
	v_lshlrev_b32_e32 v79, 16, v4
	v_and_b32_e32 v82, 0xffff0000, v4
	v_lshlrev_b32_e32 v80, 16, v8
	v_and_b32_e32 v83, 0xffff0000, v8
	v_mul_f32_e32 v84, v69, v78
	v_mul_f32_e32 v85, v69, v81
	v_fmac_f32_e32 v84, v70, v79
	v_fmac_f32_e32 v85, v70, v82
	v_fmac_f32_e32 v84, v71, v80
	v_fmac_f32_e32 v85, v71, v83
	v_cvt_pk_bf16_f32 v96, v84, v85
	v_lshlrev_b32_e32 v78, 16, v1
	v_and_b32_e32 v81, 0xffff0000, v1
	v_lshlrev_b32_e32 v79, 16, v5
	v_and_b32_e32 v82, 0xffff0000, v5
	v_lshlrev_b32_e32 v80, 16, v9
	v_and_b32_e32 v83, 0xffff0000, v9
	v_mul_f32_e32 v84, v69, v78
	v_mul_f32_e32 v85, v69, v81
	v_fmac_f32_e32 v84, v70, v79
	v_fmac_f32_e32 v85, v70, v82
	v_fmac_f32_e32 v84, v71, v80
	v_fmac_f32_e32 v85, v71, v83
	v_cvt_pk_bf16_f32 v97, v84, v85
	v_lshlrev_b32_e32 v78, 16, v2
	v_and_b32_e32 v81, 0xffff0000, v2
	v_lshlrev_b32_e32 v79, 16, v6
	v_and_b32_e32 v82, 0xffff0000, v6
	v_lshlrev_b32_e32 v80, 16, v10
	v_and_b32_e32 v83, 0xffff0000, v10
	v_mul_f32_e32 v84, v69, v78
	v_mul_f32_e32 v85, v69, v81
	v_fmac_f32_e32 v84, v70, v79
	v_fmac_f32_e32 v85, v70, v82
	v_fmac_f32_e32 v84, v71, v80
	v_fmac_f32_e32 v85, v71, v83
	v_cvt_pk_bf16_f32 v98, v84, v85
	v_lshlrev_b32_e32 v78, 16, v3
	v_and_b32_e32 v81, 0xffff0000, v3
	v_lshlrev_b32_e32 v79, 16, v7
	v_and_b32_e32 v82, 0xffff0000, v7
	v_lshlrev_b32_e32 v80, 16, v11
	v_and_b32_e32 v83, 0xffff0000, v11
	v_mul_f32_e32 v84, v69, v78
	v_mul_f32_e32 v85, v69, v81
	v_fmac_f32_e32 v84, v70, v79
	v_fmac_f32_e32 v85, v70, v82
	v_fmac_f32_e32 v84, v71, v80
	v_fmac_f32_e32 v85, v71, v83
	v_cvt_pk_bf16_f32 v99, v84, v85
	s_add_u32 s26, s24, 0x1000000
	s_addc_u32 s27, s25, 0
	global_store_dwordx4 v64, v[96:99], s[26:27]
	s_add_u32 s26, s20, 0x1800000
	s_addc_u32 s27, s21, 0
	global_load_dwordx4 v[0:3], v64, s[26:27]
	s_add_u32 s26, s20, 0x4800000
	s_addc_u32 s27, s21, 0
	global_load_dwordx4 v[4:7], v64, s[26:27]
	s_add_u32 s26, s20, 0x7800000
	s_addc_u32 s27, s21, 0
	global_load_dwordx4 v[8:11], v64, s[26:27]
	s_add_u32 s26, s22, 0xc0000
	s_addc_u32 s27, s23, 0
	global_load_dword v12, v65, s[26:27]
	s_add_u32 s26, s22, 0x240000
	s_addc_u32 s27, s23, 0
	global_load_dword v13, v65, s[26:27]
	s_add_u32 s26, s22, 0x3c0000
	s_addc_u32 s27, s23, 0
	global_load_dword v14, v65, s[26:27]
	s_waitcnt vmcnt(21)
; __device__ __forceinline__ float bf_lo(unsigned w) { return __uint_as_float(w << 16); }
; __device__ __forceinline__ float bf_hi(unsigned w) { return __uint_as_float(w & 0xffff0000u); }
; __device__ __forceinline__ unsigned pk2(float lo, float hi) { return pg8::cvt_pk_bf16(lo, hi); }
; __device__ __forceinline__ void merge_rows(const Args& a, int gw, int NGW, int lane) {
;     ...
;         for (int r = 0; r < 4; ++r) { const int m = mb + r * NGW; if (m < MT) {
;             const float mxl = fmaxf(l[r][0], fmaxf(l[r][1], l[r][2]));
;             float a0 = __expf(l[r][0] - mxl), a1 = __expf(l[r][1] - mxl), a2 = __expf(l[r][2] - mxl); const float is = 1.0f / (a0 + a1 + a2); a0 *= is; a1 *= is; a2 *= is;
;             const v2u o0 = o[r][0], o1 = o[r][1], o2 = o[r][2];
;             v2u w;
;             w.x = pk2(a0 * pg8::bf_lo(o0.x) + a1 * pg8::bf_lo(o1.x) + a2 * pg8::bf_lo(o2.x), a0 * pg8::bf_hi(o0.x) + a1 * pg8::bf_hi(o1.x) + a2 * pg8::bf_hi(o2.x));
;             w.y = pk2(a0 * pg8::bf_lo(o0.y) + a1 * pg8::bf_lo(o1.y) + a2 * pg8::bf_lo(o2.y), a0 * pg8::bf_hi(o0.y) + a1 * pg8::bf_hi(o1.y) + a2 * pg8::bf_hi(o2.y));
;             *(v2u*)(YAT + (size_t)m * 256 + 4 * lane) = w; } }
	v_max3_f32 v68, v28, v29, v30
	v_sub_f32_e32 v69, v28, v68
	v_sub_f32_e32 v70, v29, v68
	v_sub_f32_e32 v71, v30, v68
	v_mul_f32_e32 v69, 0x3fb8aa3b, v69
	v_mul_f32_e32 v70, 0x3fb8aa3b, v70
	v_mul_f32_e32 v71, 0x3fb8aa3b, v71
	v_exp_f32_e32 v69, v69
	v_exp_f32_e32 v70, v70
	v_exp_f32_e32 v71, v71
	s_nop 0
	v_add_f32_e32 v72, v69, v70
	v_add_f32_e32 v72, v71, v72
	v_div_scale_f32 v73, s[28:29], v72, v72, 1.0
	v_rcp_f32_e32 v74, v73
	v_div_scale_f32 v75, vcc, 1.0, v72, 1.0
	s_nop 0
	v_fma_f32 v76, -v73, v74, 1.0
	v_fmac_f32_e32 v74, v76, v74
	v_mul_f32_e32 v77, v75, v74
	v_fma_f32 v76, -v73, v77, v75
	v_fmac_f32_e32 v77, v76, v74
	v_fma_f32 v73, -v73, v77, v75
	v_div_fmas_f32 v73, v73, v74, v77
	v_div_fixup_f32 v72, v73, v72, 1.0
	v_mul_f32_e32 v69, v69, v72
	v_mul_f32_e32 v70, v70, v72
	v_mul_f32_e32 v71, v71, v72
	v_lshlrev_b32_e32 v78, 16, v16
	v_and_b32_e32 v81, 0xffff0000, v16
	v_lshlrev_b32_e32 v79, 16, v20
	v_and_b32_e32 v82, 0xffff0000, v20
	v_lshlrev_b32_e32 v80, 16, v24
	v_and_b32_e32 v83, 0xffff0000, v24
	v_mul_f32_e32 v84, v69, v78
	v_mul_f32_e32 v85, v69, v81
	v_fmac_f32_e32 v84, v70, v79
	v_fmac_f32_e32 v85, v70, v82
	v_fmac_f32_e32 v84, v71, v80
	v_fmac_f32_e32 v85, v71, v83
	v_cvt_pk_bf16_f32 v100, v84, v85
	v_lshlrev_b32_e32 v78, 16, v17
	v_and_b32_e32 v81, 0xffff0000, v17
	v_lshlrev_b32_e32 v79, 16, v21
	v_and_b32_e32 v82, 0xffff0000, v21
	v_lshlrev_b32_e32 v80, 16, v25
	v_and_b32_e32 v83, 0xffff0000, v25
	v_mul_f32_e32 v84, v69, v78
	v_mul_f32_e32 v85, v69, v81
	v_fmac_f32_e32 v84, v70, v79
	v_fmac_f32_e32 v85, v70, v82
	v_fmac_f32_e32 v84, v71, v80
	v_fmac_f32_e32 v85, v71, v83
	v_cvt_pk_bf16_f32 v101, v84, v85
	v_lshlrev_b32_e32 v78, 16, v18
	v_and_b32_e32 v81, 0xffff0000, v18
	v_lshlrev_b32_e32 v79, 16, v22
	v_and_b32_e32 v82, 0xffff0000, v22
	v_lshlrev_b32_e32 v80, 16, v26
	v_and_b32_e32 v83, 0xffff0000, v26
	v_mul_f32_e32 v84, v69, v78
	v_mul_f32_e32 v85, v69, v81
	v_fmac_f32_e32 v84, v70, v79
	v_fmac_f32_e32 v85, v70, v82
	v_fmac_f32_e32 v84, v71, v80
	v_fmac_f32_e32 v85, v71, v83
	v_cvt_pk_bf16_f32 v102, v84, v85
	v_lshlrev_b32_e32 v78, 16, v19
	v_and_b32_e32 v81, 0xffff0000, v19
	v_lshlrev_b32_e32 v79, 16, v23
	v_and_b32_e32 v82, 0xffff0000, v23
	v_lshlrev_b32_e32 v80, 16, v27
	v_and_b32_e32 v83, 0xffff0000, v27
	v_mul_f32_e32 v84, v69, v78
	v_mul_f32_e32 v85, v69, v81
	v_fmac_f32_e32 v84, v70, v79
	v_fmac_f32_e32 v85, v70, v82
	v_fmac_f32_e32 v84, v71, v80
	v_fmac_f32_e32 v85, v71, v83
	v_cvt_pk_bf16_f32 v103, v84, v85
	s_add_u32 s26, s24, 0x1200000
	s_addc_u32 s27, s25, 0
	global_store_dwordx4 v64, v[100:103], s[26:27]
	s_add_u32 s26, s20, 0x1a00000
	s_addc_u32 s27, s21, 0
	global_load_dwordx4 v[16:19], v64, s[26:27]
	s_add_u32 s26, s20, 0x4a00000
	s_addc_u32 s27, s21, 0
	global_load_dwordx4 v[20:23], v64, s[26:27]
	s_add_u32 s26, s20, 0x7a00000
	s_addc_u32 s27, s21, 0
	global_load_dwordx4 v[24:27], v64, s[26:27]
	s_add_u32 s26, s22, 0xd0000
	s_addc_u32 s27, s23, 0
	global_load_dword v28, v65, s[26:27]
	s_add_u32 s26, s22, 0x250000
	s_addc_u32 s27, s23, 0
	global_load_dword v29, v65, s[26:27]
	s_add_u32 s26, s22, 0x3d0000
	s_addc_u32 s27, s23, 0
	global_load_dword v30, v65, s[26:27]
	s_waitcnt vmcnt(21)
	v_max3_f32 v68, v44, v45, v46
	v_sub_f32_e32 v69, v44, v68
	v_sub_f32_e32 v70, v45, v68
	v_sub_f32_e32 v71, v46, v68
	v_mul_f32_e32 v69, 0x3fb8aa3b, v69
	v_mul_f32_e32 v70, 0x3fb8aa3b, v70
	v_mul_f32_e32 v71, 0x3fb8aa3b, v71
	v_exp_f32_e32 v69, v69
	v_exp_f32_e32 v70, v70
	v_exp_f32_e32 v71, v71
	s_nop 0
	v_add_f32_e32 v72, v69, v70
	v_add_f32_e32 v72, v71, v72
	v_div_scale_f32 v73, s[28:29], v72, v72, 1.0
	v_rcp_f32_e32 v74, v73
	v_div_scale_f32 v75, vcc, 1.0, v72, 1.0
	s_nop 0
	v_fma_f32 v76, -v73, v74, 1.0
	v_fmac_f32_e32 v74, v76, v74
	v_mul_f32_e32 v77, v75, v74
	v_fma_f32 v76, -v73, v77, v75
	v_fmac_f32_e32 v77, v76, v74
	v_fma_f32 v73, -v73, v77, v75
	v_div_fmas_f32 v73, v73, v74, v77
	v_div_fixup_f32 v72, v73, v72, 1.0
	v_mul_f32_e32 v69, v69, v72
	v_mul_f32_e32 v70, v70, v72
	v_mul_f32_e32 v71, v71, v72
	v_lshlrev_b32_e32 v78, 16, v32
	v_and_b32_e32 v81, 0xffff0000, v32
	v_lshlrev_b32_e32 v79, 16, v36
	v_and_b32_e32 v82, 0xffff0000, v36
	v_lshlrev_b32_e32 v80, 16, v40
	v_and_b32_e32 v83, 0xffff0000, v40
	v_mul_f32_e32 v84, v69, v78
	v_mul_f32_e32 v85, v69, v81
	v_fmac_f32_e32 v84, v70, v79
	v_fmac_f32_e32 v85, v70, v82
	v_fmac_f32_e32 v84, v71, v80
	v_fmac_f32_e32 v85, v71, v83
	v_cvt_pk_bf16_f32 v96, v84, v85
	v_lshlrev_b32_e32 v78, 16, v33
	v_and_b32_e32 v81, 0xffff0000, v33
	v_lshlrev_b32_e32 v79, 16, v37
	v_and_b32_e32 v82, 0xffff0000, v37
	v_lshlrev_b32_e32 v80, 16, v41
	v_and_b32_e32 v83, 0xffff0000, v41
	v_mul_f32_e32 v84, v69, v78
	v_mul_f32_e32 v85, v69, v81
	v_fmac_f32_e32 v84, v70, v79
	v_fmac_f32_e32 v85, v70, v82
	v_fmac_f32_e32 v84, v71, v80
	v_fmac_f32_e32 v85, v71, v83
	v_cvt_pk_bf16_f32 v97, v84, v85
	v_lshlrev_b32_e32 v78, 16, v34
	v_and_b32_e32 v81, 0xffff0000, v34
	v_lshlrev_b32_e32 v79, 16, v38
	v_and_b32_e32 v82, 0xffff0000, v38
	v_lshlrev_b32_e32 v80, 16, v42
	v_and_b32_e32 v83, 0xffff0000, v42
	v_mul_f32_e32 v84, v69, v78
	v_mul_f32_e32 v85, v69, v81
	v_fmac_f32_e32 v84, v70, v79
	v_fmac_f32_e32 v85, v70, v82
	v_fmac_f32_e32 v84, v71, v80
	v_fmac_f32_e32 v85, v71, v83
	v_cvt_pk_bf16_f32 v98, v84, v85
	v_lshlrev_b32_e32 v78, 16, v35
	v_and_b32_e32 v81, 0xffff0000, v35
	v_lshlrev_b32_e32 v79, 16, v39
	v_and_b32_e32 v82, 0xffff0000, v39
	v_lshlrev_b32_e32 v80, 16, v43
	v_and_b32_e32 v83, 0xffff0000, v43
	v_mul_f32_e32 v84, v69, v78
	v_mul_f32_e32 v85, v69, v81
	v_fmac_f32_e32 v84, v70, v79
	v_fmac_f32_e32 v85, v70, v82
	v_fmac_f32_e32 v84, v71, v80
	v_fmac_f32_e32 v85, v71, v83
	v_cvt_pk_bf16_f32 v99, v84, v85
	s_add_u32 s26, s24, 0x1400000
	s_addc_u32 s27, s25, 0
	global_store_dwordx4 v64, v[96:99], s[26:27]
	s_add_u32 s26, s20, 0x1c00000
	s_addc_u32 s27, s21, 0
	global_load_dwordx4 v[32:35], v64, s[26:27]
	s_add_u32 s26, s20, 0x4c00000
	s_addc_u32 s27, s21, 0
	global_load_dwordx4 v[36:39], v64, s[26:27]
	s_add_u32 s26, s20, 0x7c00000
	s_addc_u32 s27, s21, 0
	global_load_dwordx4 v[40:43], v64, s[26:27]
	s_add_u32 s26, s22, 0xe0000
	s_addc_u32 s27, s23, 0
	global_load_dword v44, v65, s[26:27]
	s_add_u32 s26, s22, 0x260000
	s_addc_u32 s27, s23, 0
	global_load_dword v45, v65, s[26:27]
	s_add_u32 s26, s22, 0x3e0000
	s_addc_u32 s27, s23, 0
	global_load_dword v46, v65, s[26:27]
	s_waitcnt vmcnt(21)
; __device__ __forceinline__ float bf_lo(unsigned w) { return __uint_as_float(w << 16); }
; __device__ __forceinline__ float bf_hi(unsigned w) { return __uint_as_float(w & 0xffff0000u); }
; __device__ __forceinline__ unsigned pk2(float lo, float hi) { return pg8::cvt_pk_bf16(lo, hi); }
; __device__ __forceinline__ void merge_rows(const Args& a, int gw, int NGW, int lane) {
;     ...
;         for (int r = 0; r < 4; ++r) { const int m = mb + r * NGW; if (m < MT) {
;             const float mxl = fmaxf(l[r][0], fmaxf(l[r][1], l[r][2]));
;             float a0 = __expf(l[r][0] - mxl), a1 = __expf(l[r][1] - mxl), a2 = __expf(l[r][2] - mxl); const float is = 1.0f / (a0 + a1 + a2); a0 *= is; a1 *= is; a2 *= is;
;             const v2u o0 = o[r][0], o1 = o[r][1], o2 = o[r][2];
;             v2u w;
;             w.x = pk2(a0 * pg8::bf_lo(o0.x) + a1 * pg8::bf_lo(o1.x) + a2 * pg8::bf_lo(o2.x), a0 * pg8::bf_hi(o0.x) + a1 * pg8::bf_hi(o1.x) + a2 * pg8::bf_hi(o2.x));
;             w.y = pk2(a0 * pg8::bf_lo(o0.y) + a1 * pg8::bf_lo(o1.y) + a2 * pg8::bf_lo(o2.y), a0 * pg8::bf_hi(o0.y) + a1 * pg8::bf_hi(o1.y) + a2 * pg8::bf_hi(o2.y));
;             *(v2u*)(YAT + (size_t)m * 256 + 4 * lane) = w; } }
	v_max3_f32 v68, v60, v61, v62
	v_sub_f32_e32 v69, v60, v68
	v_sub_f32_e32 v70, v61, v68
	v_sub_f32_e32 v71, v62, v68
	v_mul_f32_e32 v69, 0x3fb8aa3b, v69
	v_mul_f32_e32 v70, 0x3fb8aa3b, v70
	v_mul_f32_e32 v71, 0x3fb8aa3b, v71
	v_exp_f32_e32 v69, v69
	v_exp_f32_e32 v70, v70
	v_exp_f32_e32 v71, v71
	s_nop 0
	v_add_f32_e32 v72, v69, v70
	v_add_f32_e32 v72, v71, v72
	v_div_scale_f32 v73, s[28:29], v72, v72, 1.0
	v_rcp_f32_e32 v74, v73
	v_div_scale_f32 v75, vcc, 1.0, v72, 1.0
	s_nop 0
	v_fma_f32 v76, -v73, v74, 1.0
	v_fmac_f32_e32 v74, v76, v74
	v_mul_f32_e32 v77, v75, v74
	v_fma_f32 v76, -v73, v77, v75
	v_fmac_f32_e32 v77, v76, v74
	v_fma_f32 v73, -v73, v77, v75
	v_div_fmas_f32 v73, v73, v74, v77
	v_div_fixup_f32 v72, v73, v72, 1.0
	v_mul_f32_e32 v69, v69, v72
	v_mul_f32_e32 v70, v70, v72
	v_mul_f32_e32 v71, v71, v72
	v_lshlrev_b32_e32 v78, 16, v48
	v_and_b32_e32 v81, 0xffff0000, v48
	v_lshlrev_b32_e32 v79, 16, v52
	v_and_b32_e32 v82, 0xffff0000, v52
	v_lshlrev_b32_e32 v80, 16, v56
	v_and_b32_e32 v83, 0xffff0000, v56
	v_mul_f32_e32 v84, v69, v78
	v_mul_f32_e32 v85, v69, v81
	v_fmac_f32_e32 v84, v70, v79
	v_fmac_f32_e32 v85, v70, v82
	v_fmac_f32_e32 v84, v71, v80
	v_fmac_f32_e32 v85, v71, v83
	v_cvt_pk_bf16_f32 v100, v84, v85
	v_lshlrev_b32_e32 v78, 16, v49
	v_and_b32_e32 v81, 0xffff0000, v49
	v_lshlrev_b32_e32 v79, 16, v53
	v_and_b32_e32 v82, 0xffff0000, v53
	v_lshlrev_b32_e32 v80, 16, v57
	v_and_b32_e32 v83, 0xffff0000, v57
	v_mul_f32_e32 v84, v69, v78
	v_mul_f32_e32 v85, v69, v81
	v_fmac_f32_e32 v84, v70, v79
	v_fmac_f32_e32 v85, v70, v82
	v_fmac_f32_e32 v84, v71, v80
	v_fmac_f32_e32 v85, v71, v83
	v_cvt_pk_bf16_f32 v101, v84, v85
	v_lshlrev_b32_e32 v78, 16, v50
	v_and_b32_e32 v81, 0xffff0000, v50
	v_lshlrev_b32_e32 v79, 16, v54
	v_and_b32_e32 v82, 0xffff0000, v54
	v_lshlrev_b32_e32 v80, 16, v58
	v_and_b32_e32 v83, 0xffff0000, v58
	v_mul_f32_e32 v84, v69, v78
	v_mul_f32_e32 v85, v69, v81
	v_fmac_f32_e32 v84, v70, v79
	v_fmac_f32_e32 v85, v70, v82
	v_fmac_f32_e32 v84, v71, v80
	v_fmac_f32_e32 v85, v71, v83
	v_cvt_pk_bf16_f32 v102, v84, v85
	v_lshlrev_b32_e32 v78, 16, v51
	v_and_b32_e32 v81, 0xffff0000, v51
	v_lshlrev_b32_e32 v79, 16, v55
	v_and_b32_e32 v82, 0xffff0000, v55
	v_lshlrev_b32_e32 v80, 16, v59
	v_and_b32_e32 v83, 0xffff0000, v59
	v_mul_f32_e32 v84, v69, v78
	v_mul_f32_e32 v85, v69, v81
	v_fmac_f32_e32 v84, v70, v79
	v_fmac_f32_e32 v85, v70, v82
	v_fmac_f32_e32 v84, v71, v80
	v_fmac_f32_e32 v85, v71, v83
	v_cvt_pk_bf16_f32 v103, v84, v85
	s_add_u32 s26, s24, 0x1600000
	s_addc_u32 s27, s25, 0
	global_store_dwordx4 v64, v[100:103], s[26:27]
	s_add_u32 s26, s20, 0x1e00000
	s_addc_u32 s27, s21, 0
	global_load_dwordx4 v[48:51], v64, s[26:27]
	s_add_u32 s26, s20, 0x4e00000
	s_addc_u32 s27, s21, 0
	global_load_dwordx4 v[52:55], v64, s[26:27]
	s_add_u32 s26, s20, 0x7e00000
	s_addc_u32 s27, s21, 0
	global_load_dwordx4 v[56:59], v64, s[26:27]
	s_add_u32 s26, s22, 0xf0000
	s_addc_u32 s27, s23, 0
	global_load_dword v60, v65, s[26:27]
	s_add_u32 s26, s22, 0x270000
	s_addc_u32 s27, s23, 0
	global_load_dword v61, v65, s[26:27]
	s_add_u32 s26, s22, 0x3f0000
	s_addc_u32 s27, s23, 0
	global_load_dword v62, v65, s[26:27]
	s_waitcnt vmcnt(21)
	v_max3_f32 v68, v12, v13, v14
	v_sub_f32_e32 v69, v12, v68
	v_sub_f32_e32 v70, v13, v68
	v_sub_f32_e32 v71, v14, v68
	v_mul_f32_e32 v69, 0x3fb8aa3b, v69
	v_mul_f32_e32 v70, 0x3fb8aa3b, v70
	v_mul_f32_e32 v71, 0x3fb8aa3b, v71
	v_exp_f32_e32 v69, v69
	v_exp_f32_e32 v70, v70
	v_exp_f32_e32 v71, v71
	s_nop 0
	v_add_f32_e32 v72, v69, v70
	v_add_f32_e32 v72, v71, v72
	v_div_scale_f32 v73, s[28:29], v72, v72, 1.0
	v_rcp_f32_e32 v74, v73
	v_div_scale_f32 v75, vcc, 1.0, v72, 1.0
	s_nop 0
	v_fma_f32 v76, -v73, v74, 1.0
	v_fmac_f32_e32 v74, v76, v74
	v_mul_f32_e32 v77, v75, v74
	v_fma_f32 v76, -v73, v77, v75
	v_fmac_f32_e32 v77, v76, v74
	v_fma_f32 v73, -v73, v77, v75
	v_div_fmas_f32 v73, v73, v74, v77
	v_div_fixup_f32 v72, v73, v72, 1.0
	v_mul_f32_e32 v69, v69, v72
	v_mul_f32_e32 v70, v70, v72
	v_mul_f32_e32 v71, v71, v72
	v_lshlrev_b32_e32 v78, 16, v0
	v_and_b32_e32 v81, 0xffff0000, v0
	v_lshlrev_b32_e32 v79, 16, v4
	v_and_b32_e32 v82, 0xffff0000, v4
	v_lshlrev_b32_e32 v80, 16, v8
	v_and_b32_e32 v83, 0xffff0000, v8
	v_mul_f32_e32 v84, v69, v78
	v_mul_f32_e32 v85, v69, v81
	v_fmac_f32_e32 v84, v70, v79
	v_fmac_f32_e32 v85, v70, v82
	v_fmac_f32_e32 v84, v71, v80
	v_fmac_f32_e32 v85, v71, v83
	v_cvt_pk_bf16_f32 v96, v84, v85
	v_lshlrev_b32_e32 v78, 16, v1
	v_and_b32_e32 v81, 0xffff0000, v1
	v_lshlrev_b32_e32 v79, 16, v5
	v_and_b32_e32 v82, 0xffff0000, v5
	v_lshlrev_b32_e32 v80, 16, v9
	v_and_b32_e32 v83, 0xffff0000, v9
	v_mul_f32_e32 v84, v69, v78
	v_mul_f32_e32 v85, v69, v81
	v_fmac_f32_e32 v84, v70, v79
	v_fmac_f32_e32 v85, v70, v82
	v_fmac_f32_e32 v84, v71, v80
	v_fmac_f32_e32 v85, v71, v83
	v_cvt_pk_bf16_f32 v97, v84, v85
	v_lshlrev_b32_e32 v78, 16, v2
	v_and_b32_e32 v81, 0xffff0000, v2
	v_lshlrev_b32_e32 v79, 16, v6
	v_and_b32_e32 v82, 0xffff0000, v6
	v_lshlrev_b32_e32 v80, 16, v10
	v_and_b32_e32 v83, 0xffff0000, v10
	v_mul_f32_e32 v84, v69, v78
	v_mul_f32_e32 v85, v69, v81
	v_fmac_f32_e32 v84, v70, v79
	v_fmac_f32_e32 v85, v70, v82
	v_fmac_f32_e32 v84, v71, v80
	v_fmac_f32_e32 v85, v71, v83
	v_cvt_pk_bf16_f32 v98, v84, v85
	v_lshlrev_b32_e32 v78, 16, v3
	v_and_b32_e32 v81, 0xffff0000, v3
	v_lshlrev_b32_e32 v79, 16, v7
	v_and_b32_e32 v82, 0xffff0000, v7
	v_lshlrev_b32_e32 v80, 16, v11
	v_and_b32_e32 v83, 0xffff0000, v11
	v_mul_f32_e32 v84, v69, v78
	v_mul_f32_e32 v85, v69, v81
	v_fmac_f32_e32 v84, v70, v79
	v_fmac_f32_e32 v85, v70, v82
	v_fmac_f32_e32 v84, v71, v80
	v_fmac_f32_e32 v85, v71, v83
	v_cvt_pk_bf16_f32 v99, v84, v85
	s_add_u32 s26, s24, 0x1800000
	s_addc_u32 s27, s25, 0
	global_store_dwordx4 v64, v[96:99], s[26:27]
	s_add_u32 s26, s20, 0x2000000
	s_addc_u32 s27, s21, 0
	global_load_dwordx4 v[0:3], v64, s[26:27]
	s_add_u32 s26, s20, 0x5000000
	s_addc_u32 s27, s21, 0
	global_load_dwordx4 v[4:7], v64, s[26:27]
	s_add_u32 s26, s20, 0x8000000
	s_addc_u32 s27, s21, 0
	global_load_dwordx4 v[8:11], v64, s[26:27]
	s_add_u32 s26, s22, 0x100000
	s_addc_u32 s27, s23, 0
	global_load_dword v12, v65, s[26:27]
	s_add_u32 s26, s22, 0x280000
	s_addc_u32 s27, s23, 0
	global_load_dword v13, v65, s[26:27]
	s_add_u32 s26, s22, 0x400000
	s_addc_u32 s27, s23, 0
	global_load_dword v14, v65, s[26:27]
	s_waitcnt vmcnt(21)
; __device__ __forceinline__ float bf_lo(unsigned w) { return __uint_as_float(w << 16); }
; __device__ __forceinline__ float bf_hi(unsigned w) { return __uint_as_float(w & 0xffff0000u); }
; __device__ __forceinline__ unsigned pk2(float lo, float hi) { return pg8::cvt_pk_bf16(lo, hi); }
; __device__ __forceinline__ void merge_rows(const Args& a, int gw, int NGW, int lane) {
;     ...
;         for (int r = 0; r < 4; ++r) { const int m = mb + r * NGW; if (m < MT) {
;             const float mxl = fmaxf(l[r][0], fmaxf(l[r][1], l[r][2]));
;             float a0 = __expf(l[r][0] - mxl), a1 = __expf(l[r][1] - mxl), a2 = __expf(l[r][2] - mxl); const float is = 1.0f / (a0 + a1 + a2); a0 *= is; a1 *= is; a2 *= is;
;             const v2u o0 = o[r][0], o1 = o[r][1], o2 = o[r][2];
;             v2u w;
;             w.x = pk2(a0 * pg8::bf_lo(o0.x) + a1 * pg8::bf_lo(o1.x) + a2 * pg8::bf_lo(o2.x), a0 * pg8::bf_hi(o0.x) + a1 * pg8::bf_hi(o1.x) + a2 * pg8::bf_hi(o2.x));
;             w.y = pk2(a0 * pg8::bf_lo(o0.y) + a1 * pg8::bf_lo(o1.y) + a2 * pg8::bf_lo(o2.y), a0 * pg8::bf_hi(o0.y) + a1 * pg8::bf_hi(o1.y) + a2 * pg8::bf_hi(o2.y));
;             *(v2u*)(YAT + (size_t)m * 256 + 4 * lane) = w; } }
	v_max3_f32 v68, v28, v29, v30
	v_sub_f32_e32 v69, v28, v68
	v_sub_f32_e32 v70, v29, v68
	v_sub_f32_e32 v71, v30, v68
	v_mul_f32_e32 v69, 0x3fb8aa3b, v69
	v_mul_f32_e32 v70, 0x3fb8aa3b, v70
	v_mul_f32_e32 v71, 0x3fb8aa3b, v71
	v_exp_f32_e32 v69, v69
	v_exp_f32_e32 v70, v70
	v_exp_f32_e32 v71, v71
	s_nop 0
	v_add_f32_e32 v72, v69, v70
	v_add_f32_e32 v72, v71, v72
	v_div_scale_f32 v73, s[28:29], v72, v72, 1.0
	v_rcp_f32_e32 v74, v73
	v_div_scale_f32 v75, vcc, 1.0, v72, 1.0
	s_nop 0
	v_fma_f32 v76, -v73, v74, 1.0
	v_fmac_f32_e32 v74, v76, v74
	v_mul_f32_e32 v77, v75, v74
	v_fma_f32 v76, -v73, v77, v75
	v_fmac_f32_e32 v77, v76, v74
	v_fma_f32 v73, -v73, v77, v75
	v_div_fmas_f32 v73, v73, v74, v77
	v_div_fixup_f32 v72, v73, v72, 1.0
	v_mul_f32_e32 v69, v69, v72
	v_mul_f32_e32 v70, v70, v72
	v_mul_f32_e32 v71, v71, v72
	v_lshlrev_b32_e32 v78, 16, v16
	v_and_b32_e32 v81, 0xffff0000, v16
	v_lshlrev_b32_e32 v79, 16, v20
	v_and_b32_e32 v82, 0xffff0000, v20
	v_lshlrev_b32_e32 v80, 16, v24
	v_and_b32_e32 v83, 0xffff0000, v24
	v_mul_f32_e32 v84, v69, v78
	v_mul_f32_e32 v85, v69, v81
	v_fmac_f32_e32 v84, v70, v79
	v_fmac_f32_e32 v85, v70, v82
	v_fmac_f32_e32 v84, v71, v80
	v_fmac_f32_e32 v85, v71, v83
	v_cvt_pk_bf16_f32 v100, v84, v85
	v_lshlrev_b32_e32 v78, 16, v17
	v_and_b32_e32 v81, 0xffff0000, v17
	v_lshlrev_b32_e32 v79, 16, v21
	v_and_b32_e32 v82, 0xffff0000, v21
	v_lshlrev_b32_e32 v80, 16, v25
	v_and_b32_e32 v83, 0xffff0000, v25
	v_mul_f32_e32 v84, v69, v78
	v_mul_f32_e32 v85, v69, v81
	v_fmac_f32_e32 v84, v70, v79
	v_fmac_f32_e32 v85, v70, v82
	v_fmac_f32_e32 v84, v71, v80
	v_fmac_f32_e32 v85, v71, v83
	v_cvt_pk_bf16_f32 v101, v84, v85
	v_lshlrev_b32_e32 v78, 16, v18
	v_and_b32_e32 v81, 0xffff0000, v18
	v_lshlrev_b32_e32 v79, 16, v22
	v_and_b32_e32 v82, 0xffff0000, v22
	v_lshlrev_b32_e32 v80, 16, v26
	v_and_b32_e32 v83, 0xffff0000, v26
	v_mul_f32_e32 v84, v69, v78
	v_mul_f32_e32 v85, v69, v81
	v_fmac_f32_e32 v84, v70, v79
	v_fmac_f32_e32 v85, v70, v82
	v_fmac_f32_e32 v84, v71, v80
	v_fmac_f32_e32 v85, v71, v83
	v_cvt_pk_bf16_f32 v102, v84, v85
	v_lshlrev_b32_e32 v78, 16, v19
	v_and_b32_e32 v81, 0xffff0000, v19
	v_lshlrev_b32_e32 v79, 16, v23
	v_and_b32_e32 v82, 0xffff0000, v23
	v_lshlrev_b32_e32 v80, 16, v27
	v_and_b32_e32 v83, 0xffff0000, v27
	v_mul_f32_e32 v84, v69, v78
	v_mul_f32_e32 v85, v69, v81
	v_fmac_f32_e32 v84, v70, v79
	v_fmac_f32_e32 v85, v70, v82
	v_fmac_f32_e32 v84, v71, v80
	v_fmac_f32_e32 v85, v71, v83
	v_cvt_pk_bf16_f32 v103, v84, v85
	s_add_u32 s26, s24, 0x1a00000
	s_addc_u32 s27, s25, 0
	global_store_dwordx4 v64, v[100:103], s[26:27]
	s_add_u32 s26, s20, 0x2200000
	s_addc_u32 s27, s21, 0
	global_load_dwordx4 v[16:19], v64, s[26:27]
	s_add_u32 s26, s20, 0x5200000
	s_addc_u32 s27, s21, 0
	global_load_dwordx4 v[20:23], v64, s[26:27]
	s_add_u32 s26, s20, 0x8200000
	s_addc_u32 s27, s21, 0
	global_load_dwordx4 v[24:27], v64, s[26:27]
	s_add_u32 s26, s22, 0x110000
	s_addc_u32 s27, s23, 0
	global_load_dword v28, v65, s[26:27]
	s_add_u32 s26, s22, 0x290000
	s_addc_u32 s27, s23, 0
	global_load_dword v29, v65, s[26:27]
	s_add_u32 s26, s22, 0x410000
	s_addc_u32 s27, s23, 0
	global_load_dword v30, v65, s[26:27]
	s_waitcnt vmcnt(21)
	v_max3_f32 v68, v44, v45, v46
	v_sub_f32_e32 v69, v44, v68
	v_sub_f32_e32 v70, v45, v68
	v_sub_f32_e32 v71, v46, v68
	v_mul_f32_e32 v69, 0x3fb8aa3b, v69
	v_mul_f32_e32 v70, 0x3fb8aa3b, v70
	v_mul_f32_e32 v71, 0x3fb8aa3b, v71
	v_exp_f32_e32 v69, v69
	v_exp_f32_e32 v70, v70
	v_exp_f32_e32 v71, v71
	s_nop 0
	v_add_f32_e32 v72, v69, v70
	v_add_f32_e32 v72, v71, v72
	v_div_scale_f32 v73, s[28:29], v72, v72, 1.0
	v_rcp_f32_e32 v74, v73
	v_div_scale_f32 v75, vcc, 1.0, v72, 1.0
	s_nop 0
	v_fma_f32 v76, -v73, v74, 1.0
	v_fmac_f32_e32 v74, v76, v74
	v_mul_f32_e32 v77, v75, v74
	v_fma_f32 v76, -v73, v77, v75
	v_fmac_f32_e32 v77, v76, v74
	v_fma_f32 v73, -v73, v77, v75
	v_div_fmas_f32 v73, v73, v74, v77
	v_div_fixup_f32 v72, v73, v72, 1.0
	v_mul_f32_e32 v69, v69, v72
	v_mul_f32_e32 v70, v70, v72
	v_mul_f32_e32 v71, v71, v72
	v_lshlrev_b32_e32 v78, 16, v32
	v_and_b32_e32 v81, 0xffff0000, v32
	v_lshlrev_b32_e32 v79, 16, v36
	v_and_b32_e32 v82, 0xffff0000, v36
	v_lshlrev_b32_e32 v80, 16, v40
	v_and_b32_e32 v83, 0xffff0000, v40
	v_mul_f32_e32 v84, v69, v78
	v_mul_f32_e32 v85, v69, v81
	v_fmac_f32_e32 v84, v70, v79
	v_fmac_f32_e32 v85, v70, v82
	v_fmac_f32_e32 v84, v71, v80
	v_fmac_f32_e32 v85, v71, v83
	v_cvt_pk_bf16_f32 v96, v84, v85
	v_lshlrev_b32_e32 v78, 16, v33
	v_and_b32_e32 v81, 0xffff0000, v33
	v_lshlrev_b32_e32 v79, 16, v37
	v_and_b32_e32 v82, 0xffff0000, v37
	v_lshlrev_b32_e32 v80, 16, v41
	v_and_b32_e32 v83, 0xffff0000, v41
	v_mul_f32_e32 v84, v69, v78
	v_mul_f32_e32 v85, v69, v81
	v_fmac_f32_e32 v84, v70, v79
	v_fmac_f32_e32 v85, v70, v82
	v_fmac_f32_e32 v84, v71, v80
	v_fmac_f32_e32 v85, v71, v83
	v_cvt_pk_bf16_f32 v97, v84, v85
	v_lshlrev_b32_e32 v78, 16, v34
	v_and_b32_e32 v81, 0xffff0000, v34
	v_lshlrev_b32_e32 v79, 16, v38
	v_and_b32_e32 v82, 0xffff0000, v38
	v_lshlrev_b32_e32 v80, 16, v42
	v_and_b32_e32 v83, 0xffff0000, v42
	v_mul_f32_e32 v84, v69, v78
	v_mul_f32_e32 v85, v69, v81
	v_fmac_f32_e32 v84, v70, v79
	v_fmac_f32_e32 v85, v70, v82
	v_fmac_f32_e32 v84, v71, v80
	v_fmac_f32_e32 v85, v71, v83
	v_cvt_pk_bf16_f32 v98, v84, v85
	v_lshlrev_b32_e32 v78, 16, v35
	v_and_b32_e32 v81, 0xffff0000, v35
	v_lshlrev_b32_e32 v79, 16, v39
	v_and_b32_e32 v82, 0xffff0000, v39
	v_lshlrev_b32_e32 v80, 16, v43
	v_and_b32_e32 v83, 0xffff0000, v43
	v_mul_f32_e32 v84, v69, v78
	v_mul_f32_e32 v85, v69, v81
	v_fmac_f32_e32 v84, v70, v79
	v_fmac_f32_e32 v85, v70, v82
	v_fmac_f32_e32 v84, v71, v80
	v_fmac_f32_e32 v85, v71, v83
	v_cvt_pk_bf16_f32 v99, v84, v85
	s_add_u32 s26, s24, 0x1c00000
	s_addc_u32 s27, s25, 0
	global_store_dwordx4 v64, v[96:99], s[26:27]
	s_add_u32 s26, s20, 0x2400000
	s_addc_u32 s27, s21, 0
	global_load_dwordx4 v[32:35], v64, s[26:27]
	s_add_u32 s26, s20, 0x5400000
	s_addc_u32 s27, s21, 0
	global_load_dwordx4 v[36:39], v64, s[26:27]
	s_add_u32 s26, s20, 0x8400000
	s_addc_u32 s27, s21, 0
	global_load_dwordx4 v[40:43], v64, s[26:27]
	s_add_u32 s26, s22, 0x120000
	s_addc_u32 s27, s23, 0
	global_load_dword v44, v65, s[26:27]
	s_add_u32 s26, s22, 0x2a0000
	s_addc_u32 s27, s23, 0
	global_load_dword v45, v65, s[26:27]
	s_add_u32 s26, s22, 0x420000
	s_addc_u32 s27, s23, 0
	global_load_dword v46, v65, s[26:27]
	s_waitcnt vmcnt(21)
; __device__ __forceinline__ float bf_lo(unsigned w) { return __uint_as_float(w << 16); }
; __device__ __forceinline__ float bf_hi(unsigned w) { return __uint_as_float(w & 0xffff0000u); }
; __device__ __forceinline__ unsigned pk2(float lo, float hi) { return pg8::cvt_pk_bf16(lo, hi); }
; __device__ __forceinline__ void merge_rows(const Args& a, int gw, int NGW, int lane) {
;     ...
;         for (int r = 0; r < 4; ++r) { const int m = mb + r * NGW; if (m < MT) {
;             const float mxl = fmaxf(l[r][0], fmaxf(l[r][1], l[r][2]));
;             float a0 = __expf(l[r][0] - mxl), a1 = __expf(l[r][1] - mxl), a2 = __expf(l[r][2] - mxl); const float is = 1.0f / (a0 + a1 + a2); a0 *= is; a1 *= is; a2 *= is;
;             const v2u o0 = o[r][0], o1 = o[r][1], o2 = o[r][2];
;             v2u w;
;             w.x = pk2(a0 * pg8::bf_lo(o0.x) + a1 * pg8::bf_lo(o1.x) + a2 * pg8::bf_lo(o2.x), a0 * pg8::bf_hi(o0.x) + a1 * pg8::bf_hi(o1.x) + a2 * pg8::bf_hi(o2.x));
;             w.y = pk2(a0 * pg8::bf_lo(o0.y) + a1 * pg8::bf_lo(o1.y) + a2 * pg8::bf_lo(o2.y), a0 * pg8::bf_hi(o0.y) + a1 * pg8::bf_hi(o1.y) + a2 * pg8::bf_hi(o2.y));
;             *(v2u*)(YAT + (size_t)m * 256 + 4 * lane) = w; } }
	v_max3_f32 v68, v60, v61, v62
	v_sub_f32_e32 v69, v60, v68
	v_sub_f32_e32 v70, v61, v68
	v_sub_f32_e32 v71, v62, v68
	v_mul_f32_e32 v69, 0x3fb8aa3b, v69
	v_mul_f32_e32 v70, 0x3fb8aa3b, v70
	v_mul_f32_e32 v71, 0x3fb8aa3b, v71
	v_exp_f32_e32 v69, v69
	v_exp_f32_e32 v70, v70
	v_exp_f32_e32 v71, v71
	s_nop 0
	v_add_f32_e32 v72, v69, v70
	v_add_f32_e32 v72, v71, v72
	v_div_scale_f32 v73, s[28:29], v72, v72, 1.0
	v_rcp_f32_e32 v74, v73
	v_div_scale_f32 v75, vcc, 1.0, v72, 1.0
	s_nop 0
	v_fma_f32 v76, -v73, v74, 1.0
	v_fmac_f32_e32 v74, v76, v74
	v_mul_f32_e32 v77, v75, v74
	v_fma_f32 v76, -v73, v77, v75
	v_fmac_f32_e32 v77, v76, v74
	v_fma_f32 v73, -v73, v77, v75
	v_div_fmas_f32 v73, v73, v74, v77
	v_div_fixup_f32 v72, v73, v72, 1.0
	v_mul_f32_e32 v69, v69, v72
	v_mul_f32_e32 v70, v70, v72
	v_mul_f32_e32 v71, v71, v72
	v_lshlrev_b32_e32 v78, 16, v48
	v_and_b32_e32 v81, 0xffff0000, v48
	v_lshlrev_b32_e32 v79, 16, v52
	v_and_b32_e32 v82, 0xffff0000, v52
	v_lshlrev_b32_e32 v80, 16, v56
	v_and_b32_e32 v83, 0xffff0000, v56
	v_mul_f32_e32 v84, v69, v78
	v_mul_f32_e32 v85, v69, v81
	v_fmac_f32_e32 v84, v70, v79
	v_fmac_f32_e32 v85, v70, v82
	v_fmac_f32_e32 v84, v71, v80
	v_fmac_f32_e32 v85, v71, v83
	v_cvt_pk_bf16_f32 v100, v84, v85
	v_lshlrev_b32_e32 v78, 16, v49
	v_and_b32_e32 v81, 0xffff0000, v49
	v_lshlrev_b32_e32 v79, 16, v53
	v_and_b32_e32 v82, 0xffff0000, v53
	v_lshlrev_b32_e32 v80, 16, v57
	v_and_b32_e32 v83, 0xffff0000, v57
	v_mul_f32_e32 v84, v69, v78
	v_mul_f32_e32 v85, v69, v81
	v_fmac_f32_e32 v84, v70, v79
	v_fmac_f32_e32 v85, v70, v82
	v_fmac_f32_e32 v84, v71, v80
	v_fmac_f32_e32 v85, v71, v83
	v_cvt_pk_bf16_f32 v101, v84, v85
	v_lshlrev_b32_e32 v78, 16, v50
	v_and_b32_e32 v81, 0xffff0000, v50
	v_lshlrev_b32_e32 v79, 16, v54
	v_and_b32_e32 v82, 0xffff0000, v54
	v_lshlrev_b32_e32 v80, 16, v58
	v_and_b32_e32 v83, 0xffff0000, v58
	v_mul_f32_e32 v84, v69, v78
	v_mul_f32_e32 v85, v69, v81
	v_fmac_f32_e32 v84, v70, v79
	v_fmac_f32_e32 v85, v70, v82
	v_fmac_f32_e32 v84, v71, v80
	v_fmac_f32_e32 v85, v71, v83
	v_cvt_pk_bf16_f32 v102, v84, v85
	v_lshlrev_b32_e32 v78, 16, v51
	v_and_b32_e32 v81, 0xffff0000, v51
	v_lshlrev_b32_e32 v79, 16, v55
	v_and_b32_e32 v82, 0xffff0000, v55
	v_lshlrev_b32_e32 v80, 16, v59
	v_and_b32_e32 v83, 0xffff0000, v59
	v_mul_f32_e32 v84, v69, v78
	v_mul_f32_e32 v85, v69, v81
	v_fmac_f32_e32 v84, v70, v79
	v_fmac_f32_e32 v85, v70, v82
	v_fmac_f32_e32 v84, v71, v80
	v_fmac_f32_e32 v85, v71, v83
	v_cvt_pk_bf16_f32 v103, v84, v85
	s_add_u32 s26, s24, 0x1e00000
	s_addc_u32 s27, s25, 0
	global_store_dwordx4 v64, v[100:103], s[26:27]
	s_add_u32 s26, s20, 0x2600000
	s_addc_u32 s27, s21, 0
	global_load_dwordx4 v[48:51], v64, s[26:27]
	s_add_u32 s26, s20, 0x5600000
	s_addc_u32 s27, s21, 0
	global_load_dwordx4 v[52:55], v64, s[26:27]
	s_add_u32 s26, s20, 0x8600000
	s_addc_u32 s27, s21, 0
	global_load_dwordx4 v[56:59], v64, s[26:27]
	s_add_u32 s26, s22, 0x130000
	s_addc_u32 s27, s23, 0
	global_load_dword v60, v65, s[26:27]
	s_add_u32 s26, s22, 0x2b0000
	s_addc_u32 s27, s23, 0
	global_load_dword v61, v65, s[26:27]
	s_add_u32 s26, s22, 0x430000
	s_addc_u32 s27, s23, 0
	global_load_dword v62, v65, s[26:27]
	s_waitcnt vmcnt(21)
	v_max3_f32 v68, v12, v13, v14
	v_sub_f32_e32 v69, v12, v68
	v_sub_f32_e32 v70, v13, v68
	v_sub_f32_e32 v71, v14, v68
	v_mul_f32_e32 v69, 0x3fb8aa3b, v69
	v_mul_f32_e32 v70, 0x3fb8aa3b, v70
	v_mul_f32_e32 v71, 0x3fb8aa3b, v71
	v_exp_f32_e32 v69, v69
	v_exp_f32_e32 v70, v70
	v_exp_f32_e32 v71, v71
	s_nop 0
	v_add_f32_e32 v72, v69, v70
	v_add_f32_e32 v72, v71, v72
	v_div_scale_f32 v73, s[28:29], v72, v72, 1.0
	v_rcp_f32_e32 v74, v73
	v_div_scale_f32 v75, vcc, 1.0, v72, 1.0
	s_nop 0
	v_fma_f32 v76, -v73, v74, 1.0
	v_fmac_f32_e32 v74, v76, v74
	v_mul_f32_e32 v77, v75, v74
	v_fma_f32 v76, -v73, v77, v75
	v_fmac_f32_e32 v77, v76, v74
	v_fma_f32 v73, -v73, v77, v75
	v_div_fmas_f32 v73, v73, v74, v77
	v_div_fixup_f32 v72, v73, v72, 1.0
	v_mul_f32_e32 v69, v69, v72
	v_mul_f32_e32 v70, v70, v72
	v_mul_f32_e32 v71, v71, v72
	v_lshlrev_b32_e32 v78, 16, v0
	v_and_b32_e32 v81, 0xffff0000, v0
	v_lshlrev_b32_e32 v79, 16, v4
	v_and_b32_e32 v82, 0xffff0000, v4
	v_lshlrev_b32_e32 v80, 16, v8
	v_and_b32_e32 v83, 0xffff0000, v8
	v_mul_f32_e32 v84, v69, v78
	v_mul_f32_e32 v85, v69, v81
	v_fmac_f32_e32 v84, v70, v79
	v_fmac_f32_e32 v85, v70, v82
	v_fmac_f32_e32 v84, v71, v80
	v_fmac_f32_e32 v85, v71, v83
	v_cvt_pk_bf16_f32 v96, v84, v85
	v_lshlrev_b32_e32 v78, 16, v1
	v_and_b32_e32 v81, 0xffff0000, v1
	v_lshlrev_b32_e32 v79, 16, v5
	v_and_b32_e32 v82, 0xffff0000, v5
	v_lshlrev_b32_e32 v80, 16, v9
	v_and_b32_e32 v83, 0xffff0000, v9
	v_mul_f32_e32 v84, v69, v78
	v_mul_f32_e32 v85, v69, v81
	v_fmac_f32_e32 v84, v70, v79
	v_fmac_f32_e32 v85, v70, v82
	v_fmac_f32_e32 v84, v71, v80
	v_fmac_f32_e32 v85, v71, v83
	v_cvt_pk_bf16_f32 v97, v84, v85
	v_lshlrev_b32_e32 v78, 16, v2
	v_and_b32_e32 v81, 0xffff0000, v2
	v_lshlrev_b32_e32 v79, 16, v6
	v_and_b32_e32 v82, 0xffff0000, v6
	v_lshlrev_b32_e32 v80, 16, v10
	v_and_b32_e32 v83, 0xffff0000, v10
	v_mul_f32_e32 v84, v69, v78
	v_mul_f32_e32 v85, v69, v81
	v_fmac_f32_e32 v84, v70, v79
	v_fmac_f32_e32 v85, v70, v82
	v_fmac_f32_e32 v84, v71, v80
	v_fmac_f32_e32 v85, v71, v83
	v_cvt_pk_bf16_f32 v98, v84, v85
	v_lshlrev_b32_e32 v78, 16, v3
	v_and_b32_e32 v81, 0xffff0000, v3
	v_lshlrev_b32_e32 v79, 16, v7
	v_and_b32_e32 v82, 0xffff0000, v7
	v_lshlrev_b32_e32 v80, 16, v11
	v_and_b32_e32 v83, 0xffff0000, v11
	v_mul_f32_e32 v84, v69, v78
	v_mul_f32_e32 v85, v69, v81
	v_fmac_f32_e32 v84, v70, v79
	v_fmac_f32_e32 v85, v70, v82
	v_fmac_f32_e32 v84, v71, v80
	v_fmac_f32_e32 v85, v71, v83
	v_cvt_pk_bf16_f32 v99, v84, v85
	s_add_u32 s26, s24, 0x2000000
	s_addc_u32 s27, s25, 0
	global_store_dwordx4 v64, v[96:99], s[26:27]
	s_add_u32 s26, s20, 0x2800000
	s_addc_u32 s27, s21, 0
	global_load_dwordx4 v[0:3], v64, s[26:27]
	s_add_u32 s26, s20, 0x5800000
	s_addc_u32 s27, s21, 0
	global_load_dwordx4 v[4:7], v64, s[26:27]
	s_add_u32 s26, s20, 0x8800000
	s_addc_u32 s27, s21, 0
	global_load_dwordx4 v[8:11], v64, s[26:27]
	s_add_u32 s26, s22, 0x140000
	s_addc_u32 s27, s23, 0
	global_load_dword v12, v65, s[26:27]
	s_add_u32 s26, s22, 0x2c0000
	s_addc_u32 s27, s23, 0
	global_load_dword v13, v65, s[26:27]
	s_add_u32 s26, s22, 0x440000
	s_addc_u32 s27, s23, 0
	global_load_dword v14, v65, s[26:27]
	s_waitcnt vmcnt(21)
; __device__ __forceinline__ float bf_lo(unsigned w) { return __uint_as_float(w << 16); }
; __device__ __forceinline__ float bf_hi(unsigned w) { return __uint_as_float(w & 0xffff0000u); }
; __device__ __forceinline__ unsigned pk2(float lo, float hi) { return pg8::cvt_pk_bf16(lo, hi); }
; __device__ __forceinline__ void merge_rows(const Args& a, int gw, int NGW, int lane) {
;     ...
;         for (int r = 0; r < 4; ++r) { const int m = mb + r * NGW; if (m < MT) {
;             const float mxl = fmaxf(l[r][0], fmaxf(l[r][1], l[r][2]));
;             float a0 = __expf(l[r][0] - mxl), a1 = __expf(l[r][1] - mxl), a2 = __expf(l[r][2] - mxl); const float is = 1.0f / (a0 + a1 + a2); a0 *= is; a1 *= is; a2 *= is;
;             const v2u o0 = o[r][0], o1 = o[r][1], o2 = o[r][2];
;             v2u w;
;             w.x = pk2(a0 * pg8::bf_lo(o0.x) + a1 * pg8::bf_lo(o1.x) + a2 * pg8::bf_lo(o2.x), a0 * pg8::bf_hi(o0.x) + a1 * pg8::bf_hi(o1.x) + a2 * pg8::bf_hi(o2.x));
;             w.y = pk2(a0 * pg8::bf_lo(o0.y) + a1 * pg8::bf_lo(o1.y) + a2 * pg8::bf_lo(o2.y), a0 * pg8::bf_hi(o0.y) + a1 * pg8::bf_hi(o1.y) + a2 * pg8::bf_hi(o2.y));
;             *(v2u*)(YAT + (size_t)m * 256 + 4 * lane) = w; } }
	v_max3_f32 v68, v28, v29, v30
	v_sub_f32_e32 v69, v28, v68
	v_sub_f32_e32 v70, v29, v68
	v_sub_f32_e32 v71, v30, v68
	v_mul_f32_e32 v69, 0x3fb8aa3b, v69
	v_mul_f32_e32 v70, 0x3fb8aa3b, v70
	v_mul_f32_e32 v71, 0x3fb8aa3b, v71
	v_exp_f32_e32 v69, v69
	v_exp_f32_e32 v70, v70
	v_exp_f32_e32 v71, v71
	s_nop 0
	v_add_f32_e32 v72, v69, v70
	v_add_f32_e32 v72, v71, v72
	v_div_scale_f32 v73, s[28:29], v72, v72, 1.0
	v_rcp_f32_e32 v74, v73
	v_div_scale_f32 v75, vcc, 1.0, v72, 1.0
	s_nop 0
	v_fma_f32 v76, -v73, v74, 1.0
	v_fmac_f32_e32 v74, v76, v74
	v_mul_f32_e32 v77, v75, v74
	v_fma_f32 v76, -v73, v77, v75
	v_fmac_f32_e32 v77, v76, v74
	v_fma_f32 v73, -v73, v77, v75
	v_div_fmas_f32 v73, v73, v74, v77
	v_div_fixup_f32 v72, v73, v72, 1.0
	v_mul_f32_e32 v69, v69, v72
	v_mul_f32_e32 v70, v70, v72
	v_mul_f32_e32 v71, v71, v72
	v_lshlrev_b32_e32 v78, 16, v16
	v_and_b32_e32 v81, 0xffff0000, v16
	v_lshlrev_b32_e32 v79, 16, v20
	v_and_b32_e32 v82, 0xffff0000, v20
	v_lshlrev_b32_e32 v80, 16, v24
	v_and_b32_e32 v83, 0xffff0000, v24
	v_mul_f32_e32 v84, v69, v78
	v_mul_f32_e32 v85, v69, v81
	v_fmac_f32_e32 v84, v70, v79
	v_fmac_f32_e32 v85, v70, v82
	v_fmac_f32_e32 v84, v71, v80
	v_fmac_f32_e32 v85, v71, v83
	v_cvt_pk_bf16_f32 v100, v84, v85
	v_lshlrev_b32_e32 v78, 16, v17
	v_and_b32_e32 v81, 0xffff0000, v17
	v_lshlrev_b32_e32 v79, 16, v21
	v_and_b32_e32 v82, 0xffff0000, v21
	v_lshlrev_b32_e32 v80, 16, v25
	v_and_b32_e32 v83, 0xffff0000, v25
	v_mul_f32_e32 v84, v69, v78
	v_mul_f32_e32 v85, v69, v81
	v_fmac_f32_e32 v84, v70, v79
	v_fmac_f32_e32 v85, v70, v82
	v_fmac_f32_e32 v84, v71, v80
	v_fmac_f32_e32 v85, v71, v83
	v_cvt_pk_bf16_f32 v101, v84, v85
	v_lshlrev_b32_e32 v78, 16, v18
	v_and_b32_e32 v81, 0xffff0000, v18
	v_lshlrev_b32_e32 v79, 16, v22
	v_and_b32_e32 v82, 0xffff0000, v22
	v_lshlrev_b32_e32 v80, 16, v26
	v_and_b32_e32 v83, 0xffff0000, v26
	v_mul_f32_e32 v84, v69, v78
	v_mul_f32_e32 v85, v69, v81
	v_fmac_f32_e32 v84, v70, v79
	v_fmac_f32_e32 v85, v70, v82
	v_fmac_f32_e32 v84, v71, v80
	v_fmac_f32_e32 v85, v71, v83
	v_cvt_pk_bf16_f32 v102, v84, v85
	v_lshlrev_b32_e32 v78, 16, v19
	v_and_b32_e32 v81, 0xffff0000, v19
	v_lshlrev_b32_e32 v79, 16, v23
	v_and_b32_e32 v82, 0xffff0000, v23
	v_lshlrev_b32_e32 v80, 16, v27
	v_and_b32_e32 v83, 0xffff0000, v27
	v_mul_f32_e32 v84, v69, v78
	v_mul_f32_e32 v85, v69, v81
	v_fmac_f32_e32 v84, v70, v79
	v_fmac_f32_e32 v85, v70, v82
	v_fmac_f32_e32 v84, v71, v80
	v_fmac_f32_e32 v85, v71, v83
	v_cvt_pk_bf16_f32 v103, v84, v85
	s_add_u32 s26, s24, 0x2200000
	s_addc_u32 s27, s25, 0
	global_store_dwordx4 v64, v[100:103], s[26:27]
	s_add_u32 s26, s20, 0x2a00000
	s_addc_u32 s27, s21, 0
	global_load_dwordx4 v[16:19], v64, s[26:27]
	s_add_u32 s26, s20, 0x5a00000
	s_addc_u32 s27, s21, 0
	global_load_dwordx4 v[20:23], v64, s[26:27]
	s_add_u32 s26, s20, 0x8a00000
	s_addc_u32 s27, s21, 0
	global_load_dwordx4 v[24:27], v64, s[26:27]
	s_add_u32 s26, s22, 0x150000
	s_addc_u32 s27, s23, 0
	global_load_dword v28, v65, s[26:27]
	s_add_u32 s26, s22, 0x2d0000
	s_addc_u32 s27, s23, 0
	global_load_dword v29, v65, s[26:27]
	s_add_u32 s26, s22, 0x450000
	s_addc_u32 s27, s23, 0
	global_load_dword v30, v65, s[26:27]
	s_waitcnt vmcnt(21)
	v_max3_f32 v68, v44, v45, v46
	v_sub_f32_e32 v69, v44, v68
	v_sub_f32_e32 v70, v45, v68
	v_sub_f32_e32 v71, v46, v68
	v_mul_f32_e32 v69, 0x3fb8aa3b, v69
	v_mul_f32_e32 v70, 0x3fb8aa3b, v70
	v_mul_f32_e32 v71, 0x3fb8aa3b, v71
	v_exp_f32_e32 v69, v69
	v_exp_f32_e32 v70, v70
	v_exp_f32_e32 v71, v71
	s_nop 0
	v_add_f32_e32 v72, v69, v70
	v_add_f32_e32 v72, v71, v72
	v_div_scale_f32 v73, s[28:29], v72, v72, 1.0
	v_rcp_f32_e32 v74, v73
	v_div_scale_f32 v75, vcc, 1.0, v72, 1.0
	s_nop 0
	v_fma_f32 v76, -v73, v74, 1.0
	v_fmac_f32_e32 v74, v76, v74
	v_mul_f32_e32 v77, v75, v74
	v_fma_f32 v76, -v73, v77, v75
	v_fmac_f32_e32 v77, v76, v74
	v_fma_f32 v73, -v73, v77, v75
	v_div_fmas_f32 v73, v73, v74, v77
	v_div_fixup_f32 v72, v73, v72, 1.0
	v_mul_f32_e32 v69, v69, v72
	v_mul_f32_e32 v70, v70, v72
	v_mul_f32_e32 v71, v71, v72
	v_lshlrev_b32_e32 v78, 16, v32
	v_and_b32_e32 v81, 0xffff0000, v32
	v_lshlrev_b32_e32 v79, 16, v36
	v_and_b32_e32 v82, 0xffff0000, v36
	v_lshlrev_b32_e32 v80, 16, v40
	v_and_b32_e32 v83, 0xffff0000, v40
	v_mul_f32_e32 v84, v69, v78
	v_mul_f32_e32 v85, v69, v81
	v_fmac_f32_e32 v84, v70, v79
	v_fmac_f32_e32 v85, v70, v82
	v_fmac_f32_e32 v84, v71, v80
	v_fmac_f32_e32 v85, v71, v83
	v_cvt_pk_bf16_f32 v96, v84, v85
	v_lshlrev_b32_e32 v78, 16, v33
	v_and_b32_e32 v81, 0xffff0000, v33
	v_lshlrev_b32_e32 v79, 16, v37
	v_and_b32_e32 v82, 0xffff0000, v37
	v_lshlrev_b32_e32 v80, 16, v41
	v_and_b32_e32 v83, 0xffff0000, v41
	v_mul_f32_e32 v84, v69, v78
	v_mul_f32_e32 v85, v69, v81
	v_fmac_f32_e32 v84, v70, v79
	v_fmac_f32_e32 v85, v70, v82
	v_fmac_f32_e32 v84, v71, v80
	v_fmac_f32_e32 v85, v71, v83
	v_cvt_pk_bf16_f32 v97, v84, v85
	v_lshlrev_b32_e32 v78, 16, v34
	v_and_b32_e32 v81, 0xffff0000, v34
	v_lshlrev_b32_e32 v79, 16, v38
	v_and_b32_e32 v82, 0xffff0000, v38
	v_lshlrev_b32_e32 v80, 16, v42
	v_and_b32_e32 v83, 0xffff0000, v42
	v_mul_f32_e32 v84, v69, v78
	v_mul_f32_e32 v85, v69, v81
	v_fmac_f32_e32 v84, v70, v79
	v_fmac_f32_e32 v85, v70, v82
	v_fmac_f32_e32 v84, v71, v80
	v_fmac_f32_e32 v85, v71, v83
	v_cvt_pk_bf16_f32 v98, v84, v85
	v_lshlrev_b32_e32 v78, 16, v35
	v_and_b32_e32 v81, 0xffff0000, v35
	v_lshlrev_b32_e32 v79, 16, v39
	v_and_b32_e32 v82, 0xffff0000, v39
	v_lshlrev_b32_e32 v80, 16, v43
	v_and_b32_e32 v83, 0xffff0000, v43
	v_mul_f32_e32 v84, v69, v78
	v_mul_f32_e32 v85, v69, v81
	v_fmac_f32_e32 v84, v70, v79
	v_fmac_f32_e32 v85, v70, v82
	v_fmac_f32_e32 v84, v71, v80
	v_fmac_f32_e32 v85, v71, v83
	v_cvt_pk_bf16_f32 v99, v84, v85
	s_add_u32 s26, s24, 0x2400000
	s_addc_u32 s27, s25, 0
	global_store_dwordx4 v64, v[96:99], s[26:27]
	s_add_u32 s26, s20, 0x2c00000
	s_addc_u32 s27, s21, 0
	global_load_dwordx4 v[32:35], v64, s[26:27]
	s_add_u32 s26, s20, 0x5c00000
	s_addc_u32 s27, s21, 0
	global_load_dwordx4 v[36:39], v64, s[26:27]
	s_add_u32 s26, s20, 0x8c00000
	s_addc_u32 s27, s21, 0
	global_load_dwordx4 v[40:43], v64, s[26:27]
	s_add_u32 s26, s22, 0x160000
	s_addc_u32 s27, s23, 0
	global_load_dword v44, v65, s[26:27]
	s_add_u32 s26, s22, 0x2e0000
	s_addc_u32 s27, s23, 0
	global_load_dword v45, v65, s[26:27]
	s_add_u32 s26, s22, 0x460000
	s_addc_u32 s27, s23, 0
	global_load_dword v46, v65, s[26:27]
	s_waitcnt vmcnt(21)
; __device__ __forceinline__ float bf_lo(unsigned w) { return __uint_as_float(w << 16); }
; __device__ __forceinline__ float bf_hi(unsigned w) { return __uint_as_float(w & 0xffff0000u); }
; __device__ __forceinline__ unsigned pk2(float lo, float hi) { return pg8::cvt_pk_bf16(lo, hi); }
; __device__ __forceinline__ void merge_rows(const Args& a, int gw, int NGW, int lane) {
;     ...
;         for (int r = 0; r < 4; ++r) { const int m = mb + r * NGW; if (m < MT) {
;             const float mxl = fmaxf(l[r][0], fmaxf(l[r][1], l[r][2]));
;             float a0 = __expf(l[r][0] - mxl), a1 = __expf(l[r][1] - mxl), a2 = __expf(l[r][2] - mxl); const float is = 1.0f / (a0 + a1 + a2); a0 *= is; a1 *= is; a2 *= is;
;             const v2u o0 = o[r][0], o1 = o[r][1], o2 = o[r][2];
;             v2u w;
;             w.x = pk2(a0 * pg8::bf_lo(o0.x) + a1 * pg8::bf_lo(o1.x) + a2 * pg8::bf_lo(o2.x), a0 * pg8::bf_hi(o0.x) + a1 * pg8::bf_hi(o1.x) + a2 * pg8::bf_hi(o2.x));
;             w.y = pk2(a0 * pg8::bf_lo(o0.y) + a1 * pg8::bf_lo(o1.y) + a2 * pg8::bf_lo(o2.y), a0 * pg8::bf_hi(o0.y) + a1 * pg8::bf_hi(o1.y) + a2 * pg8::bf_hi(o2.y));
;             *(v2u*)(YAT + (size_t)m * 256 + 4 * lane) = w; } }
	v_max3_f32 v68, v60, v61, v62
	v_sub_f32_e32 v69, v60, v68
	v_sub_f32_e32 v70, v61, v68
	v_sub_f32_e32 v71, v62, v68
	v_mul_f32_e32 v69, 0x3fb8aa3b, v69
	v_mul_f32_e32 v70, 0x3fb8aa3b, v70
	v_mul_f32_e32 v71, 0x3fb8aa3b, v71
	v_exp_f32_e32 v69, v69
	v_exp_f32_e32 v70, v70
	v_exp_f32_e32 v71, v71
	s_nop 0
	v_add_f32_e32 v72, v69, v70
	v_add_f32_e32 v72, v71, v72
	v_div_scale_f32 v73, s[28:29], v72, v72, 1.0
	v_rcp_f32_e32 v74, v73
	v_div_scale_f32 v75, vcc, 1.0, v72, 1.0
	s_nop 0
	v_fma_f32 v76, -v73, v74, 1.0
	v_fmac_f32_e32 v74, v76, v74
	v_mul_f32_e32 v77, v75, v74
	v_fma_f32 v76, -v73, v77, v75
	v_fmac_f32_e32 v77, v76, v74
	v_fma_f32 v73, -v73, v77, v75
	v_div_fmas_f32 v73, v73, v74, v77
	v_div_fixup_f32 v72, v73, v72, 1.0
	v_mul_f32_e32 v69, v69, v72
	v_mul_f32_e32 v70, v70, v72
	v_mul_f32_e32 v71, v71, v72
	v_lshlrev_b32_e32 v78, 16, v48
	v_and_b32_e32 v81, 0xffff0000, v48
	v_lshlrev_b32_e32 v79, 16, v52
	v_and_b32_e32 v82, 0xffff0000, v52
	v_lshlrev_b32_e32 v80, 16, v56
	v_and_b32_e32 v83, 0xffff0000, v56
	v_mul_f32_e32 v84, v69, v78
	v_mul_f32_e32 v85, v69, v81
	v_fmac_f32_e32 v84, v70, v79
	v_fmac_f32_e32 v85, v70, v82
	v_fmac_f32_e32 v84, v71, v80
	v_fmac_f32_e32 v85, v71, v83
	v_cvt_pk_bf16_f32 v100, v84, v85
	v_lshlrev_b32_e32 v78, 16, v49
	v_and_b32_e32 v81, 0xffff0000, v49
	v_lshlrev_b32_e32 v79, 16, v53
	v_and_b32_e32 v82, 0xffff0000, v53
	v_lshlrev_b32_e32 v80, 16, v57
	v_and_b32_e32 v83, 0xffff0000, v57
	v_mul_f32_e32 v84, v69, v78
	v_mul_f32_e32 v85, v69, v81
	v_fmac_f32_e32 v84, v70, v79
	v_fmac_f32_e32 v85, v70, v82
	v_fmac_f32_e32 v84, v71, v80
	v_fmac_f32_e32 v85, v71, v83
	v_cvt_pk_bf16_f32 v101, v84, v85
	v_lshlrev_b32_e32 v78, 16, v50
	v_and_b32_e32 v81, 0xffff0000, v50
	v_lshlrev_b32_e32 v79, 16, v54
	v_and_b32_e32 v82, 0xffff0000, v54
	v_lshlrev_b32_e32 v80, 16, v58
	v_and_b32_e32 v83, 0xffff0000, v58
	v_mul_f32_e32 v84, v69, v78
	v_mul_f32_e32 v85, v69, v81
	v_fmac_f32_e32 v84, v70, v79
	v_fmac_f32_e32 v85, v70, v82
	v_fmac_f32_e32 v84, v71, v80
	v_fmac_f32_e32 v85, v71, v83
	v_cvt_pk_bf16_f32 v102, v84, v85
	v_lshlrev_b32_e32 v78, 16, v51
	v_and_b32_e32 v81, 0xffff0000, v51
	v_lshlrev_b32_e32 v79, 16, v55
	v_and_b32_e32 v82, 0xffff0000, v55
	v_lshlrev_b32_e32 v80, 16, v59
	v_and_b32_e32 v83, 0xffff0000, v59
	v_mul_f32_e32 v84, v69, v78
	v_mul_f32_e32 v85, v69, v81
	v_fmac_f32_e32 v84, v70, v79
	v_fmac_f32_e32 v85, v70, v82
	v_fmac_f32_e32 v84, v71, v80
	v_fmac_f32_e32 v85, v71, v83
	v_cvt_pk_bf16_f32 v103, v84, v85
	s_add_u32 s26, s24, 0x2600000
	s_addc_u32 s27, s25, 0
	global_store_dwordx4 v64, v[100:103], s[26:27]
	s_add_u32 s26, s20, 0x2e00000
	s_addc_u32 s27, s21, 0
	global_load_dwordx4 v[48:51], v64, s[26:27]
	s_add_u32 s26, s20, 0x5e00000
	s_addc_u32 s27, s21, 0
	global_load_dwordx4 v[52:55], v64, s[26:27]
	s_add_u32 s26, s20, 0x8e00000
	s_addc_u32 s27, s21, 0
	global_load_dwordx4 v[56:59], v64, s[26:27]
	s_add_u32 s26, s22, 0x170000
	s_addc_u32 s27, s23, 0
	global_load_dword v60, v65, s[26:27]
	s_add_u32 s26, s22, 0x2f0000
	s_addc_u32 s27, s23, 0
	global_load_dword v61, v65, s[26:27]
	s_add_u32 s26, s22, 0x470000
	s_addc_u32 s27, s23, 0
	global_load_dword v62, v65, s[26:27]
	s_waitcnt vmcnt(21)
	v_max3_f32 v68, v12, v13, v14
	v_sub_f32_e32 v69, v12, v68
	v_sub_f32_e32 v70, v13, v68
	v_sub_f32_e32 v71, v14, v68
	v_mul_f32_e32 v69, 0x3fb8aa3b, v69
	v_mul_f32_e32 v70, 0x3fb8aa3b, v70
	v_mul_f32_e32 v71, 0x3fb8aa3b, v71
	v_exp_f32_e32 v69, v69
	v_exp_f32_e32 v70, v70
	v_exp_f32_e32 v71, v71
	s_nop 0
	v_add_f32_e32 v72, v69, v70
	v_add_f32_e32 v72, v71, v72
	v_div_scale_f32 v73, s[28:29], v72, v72, 1.0
	v_rcp_f32_e32 v74, v73
	v_div_scale_f32 v75, vcc, 1.0, v72, 1.0
	s_nop 0
	v_fma_f32 v76, -v73, v74, 1.0
	v_fmac_f32_e32 v74, v76, v74
	v_mul_f32_e32 v77, v75, v74
	v_fma_f32 v76, -v73, v77, v75
	v_fmac_f32_e32 v77, v76, v74
	v_fma_f32 v73, -v73, v77, v75
	v_div_fmas_f32 v73, v73, v74, v77
	v_div_fixup_f32 v72, v73, v72, 1.0
	v_mul_f32_e32 v69, v69, v72
	v_mul_f32_e32 v70, v70, v72
	v_mul_f32_e32 v71, v71, v72
	v_lshlrev_b32_e32 v78, 16, v0
	v_and_b32_e32 v81, 0xffff0000, v0
	v_lshlrev_b32_e32 v79, 16, v4
	v_and_b32_e32 v82, 0xffff0000, v4
	v_lshlrev_b32_e32 v80, 16, v8
	v_and_b32_e32 v83, 0xffff0000, v8
	v_mul_f32_e32 v84, v69, v78
	v_mul_f32_e32 v85, v69, v81
	v_fmac_f32_e32 v84, v70, v79
	v_fmac_f32_e32 v85, v70, v82
	v_fmac_f32_e32 v84, v71, v80
	v_fmac_f32_e32 v85, v71, v83
	v_cvt_pk_bf16_f32 v96, v84, v85
	v_lshlrev_b32_e32 v78, 16, v1
	v_and_b32_e32 v81, 0xffff0000, v1
	v_lshlrev_b32_e32 v79, 16, v5
	v_and_b32_e32 v82, 0xffff0000, v5
	v_lshlrev_b32_e32 v80, 16, v9
	v_and_b32_e32 v83, 0xffff0000, v9
	v_mul_f32_e32 v84, v69, v78
	v_mul_f32_e32 v85, v69, v81
	v_fmac_f32_e32 v84, v70, v79
	v_fmac_f32_e32 v85, v70, v82
	v_fmac_f32_e32 v84, v71, v80
	v_fmac_f32_e32 v85, v71, v83
	v_cvt_pk_bf16_f32 v97, v84, v85
	v_lshlrev_b32_e32 v78, 16, v2
	v_and_b32_e32 v81, 0xffff0000, v2
	v_lshlrev_b32_e32 v79, 16, v6
	v_and_b32_e32 v82, 0xffff0000, v6
	v_lshlrev_b32_e32 v80, 16, v10
	v_and_b32_e32 v83, 0xffff0000, v10
	v_mul_f32_e32 v84, v69, v78
	v_mul_f32_e32 v85, v69, v81
	v_fmac_f32_e32 v84, v70, v79
	v_fmac_f32_e32 v85, v70, v82
	v_fmac_f32_e32 v84, v71, v80
	v_fmac_f32_e32 v85, v71, v83
	v_cvt_pk_bf16_f32 v98, v84, v85
	v_lshlrev_b32_e32 v78, 16, v3
	v_and_b32_e32 v81, 0xffff0000, v3
	v_lshlrev_b32_e32 v79, 16, v7
	v_and_b32_e32 v82, 0xffff0000, v7
	v_lshlrev_b32_e32 v80, 16, v11
	v_and_b32_e32 v83, 0xffff0000, v11
	v_mul_f32_e32 v84, v69, v78
	v_mul_f32_e32 v85, v69, v81
	v_fmac_f32_e32 v84, v70, v79
	v_fmac_f32_e32 v85, v70, v82
	v_fmac_f32_e32 v84, v71, v80
	v_fmac_f32_e32 v85, v71, v83
	v_cvt_pk_bf16_f32 v99, v84, v85
	s_add_u32 s26, s24, 0x2800000
	s_addc_u32 s27, s25, 0
	global_store_dwordx4 v64, v[96:99], s[26:27]
	s_waitcnt vmcnt(15)
; __device__ __forceinline__ float bf_lo(unsigned w) { return __uint_as_float(w << 16); }
; __device__ __forceinline__ float bf_hi(unsigned w) { return __uint_as_float(w & 0xffff0000u); }
; __device__ __forceinline__ unsigned pk2(float lo, float hi) { return pg8::cvt_pk_bf16(lo, hi); }
; __device__ __forceinline__ void merge_rows(const Args& a, int gw, int NGW, int lane) {
;     ...
;         for (int r = 0; r < 4; ++r) { const int m = mb + r * NGW; if (m < MT) {
;             const float mxl = fmaxf(l[r][0], fmaxf(l[r][1], l[r][2]));
;             float a0 = __expf(l[r][0] - mxl), a1 = __expf(l[r][1] - mxl), a2 = __expf(l[r][2] - mxl); const float is = 1.0f / (a0 + a1 + a2); a0 *= is; a1 *= is; a2 *= is;
;             const v2u o0 = o[r][0], o1 = o[r][1], o2 = o[r][2];
;             v2u w;
;             w.x = pk2(a0 * pg8::bf_lo(o0.x) + a1 * pg8::bf_lo(o1.x) + a2 * pg8::bf_lo(o2.x), a0 * pg8::bf_hi(o0.x) + a1 * pg8::bf_hi(o1.x) + a2 * pg8::bf_hi(o2.x));
;             w.y = pk2(a0 * pg8::bf_lo(o0.y) + a1 * pg8::bf_lo(o1.y) + a2 * pg8::bf_lo(o2.y), a0 * pg8::bf_hi(o0.y) + a1 * pg8::bf_hi(o1.y) + a2 * pg8::bf_hi(o2.y));
;             *(v2u*)(YAT + (size_t)m * 256 + 4 * lane) = w; } }
	v_max3_f32 v68, v28, v29, v30
	v_sub_f32_e32 v69, v28, v68
	v_sub_f32_e32 v70, v29, v68
	v_sub_f32_e32 v71, v30, v68
	v_mul_f32_e32 v69, 0x3fb8aa3b, v69
	v_mul_f32_e32 v70, 0x3fb8aa3b, v70
	v_mul_f32_e32 v71, 0x3fb8aa3b, v71
	v_exp_f32_e32 v69, v69
	v_exp_f32_e32 v70, v70
	v_exp_f32_e32 v71, v71
	s_nop 0
	v_add_f32_e32 v72, v69, v70
	v_add_f32_e32 v72, v71, v72
	v_div_scale_f32 v73, s[28:29], v72, v72, 1.0
	v_rcp_f32_e32 v74, v73
	v_div_scale_f32 v75, vcc, 1.0, v72, 1.0
	s_nop 0
	v_fma_f32 v76, -v73, v74, 1.0
	v_fmac_f32_e32 v74, v76, v74
	v_mul_f32_e32 v77, v75, v74
	v_fma_f32 v76, -v73, v77, v75
	v_fmac_f32_e32 v77, v76, v74
	v_fma_f32 v73, -v73, v77, v75
	v_div_fmas_f32 v73, v73, v74, v77
	v_div_fixup_f32 v72, v73, v72, 1.0
	v_mul_f32_e32 v69, v69, v72
	v_mul_f32_e32 v70, v70, v72
	v_mul_f32_e32 v71, v71, v72
	v_lshlrev_b32_e32 v78, 16, v16
	v_and_b32_e32 v81, 0xffff0000, v16
	v_lshlrev_b32_e32 v79, 16, v20
	v_and_b32_e32 v82, 0xffff0000, v20
	v_lshlrev_b32_e32 v80, 16, v24
	v_and_b32_e32 v83, 0xffff0000, v24
	v_mul_f32_e32 v84, v69, v78
	v_mul_f32_e32 v85, v69, v81
	v_fmac_f32_e32 v84, v70, v79
	v_fmac_f32_e32 v85, v70, v82
	v_fmac_f32_e32 v84, v71, v80
	v_fmac_f32_e32 v85, v71, v83
	v_cvt_pk_bf16_f32 v100, v84, v85
	v_lshlrev_b32_e32 v78, 16, v17
	v_and_b32_e32 v81, 0xffff0000, v17
	v_lshlrev_b32_e32 v79, 16, v21
	v_and_b32_e32 v82, 0xffff0000, v21
	v_lshlrev_b32_e32 v80, 16, v25
	v_and_b32_e32 v83, 0xffff0000, v25
	v_mul_f32_e32 v84, v69, v78
	v_mul_f32_e32 v85, v69, v81
	v_fmac_f32_e32 v84, v70, v79
	v_fmac_f32_e32 v85, v70, v82
	v_fmac_f32_e32 v84, v71, v80
	v_fmac_f32_e32 v85, v71, v83
	v_cvt_pk_bf16_f32 v101, v84, v85
	v_lshlrev_b32_e32 v78, 16, v18
	v_and_b32_e32 v81, 0xffff0000, v18
	v_lshlrev_b32_e32 v79, 16, v22
	v_and_b32_e32 v82, 0xffff0000, v22
	v_lshlrev_b32_e32 v80, 16, v26
	v_and_b32_e32 v83, 0xffff0000, v26
	v_mul_f32_e32 v84, v69, v78
	v_mul_f32_e32 v85, v69, v81
	v_fmac_f32_e32 v84, v70, v79
	v_fmac_f32_e32 v85, v70, v82
	v_fmac_f32_e32 v84, v71, v80
	v_fmac_f32_e32 v85, v71, v83
	v_cvt_pk_bf16_f32 v102, v84, v85
	v_lshlrev_b32_e32 v78, 16, v19
	v_and_b32_e32 v81, 0xffff0000, v19
	v_lshlrev_b32_e32 v79, 16, v23
	v_and_b32_e32 v82, 0xffff0000, v23
	v_lshlrev_b32_e32 v80, 16, v27
	v_and_b32_e32 v83, 0xffff0000, v27
	v_mul_f32_e32 v84, v69, v78
	v_mul_f32_e32 v85, v69, v81
	v_fmac_f32_e32 v84, v70, v79
	v_fmac_f32_e32 v85, v70, v82
	v_fmac_f32_e32 v84, v71, v80
	v_fmac_f32_e32 v85, v71, v83
	v_cvt_pk_bf16_f32 v103, v84, v85
	s_add_u32 s26, s24, 0x2a00000
	s_addc_u32 s27, s25, 0
	global_store_dwordx4 v64, v[100:103], s[26:27]
	s_waitcnt vmcnt(9)
	v_max3_f32 v68, v44, v45, v46
	v_sub_f32_e32 v69, v44, v68
	v_sub_f32_e32 v70, v45, v68
	v_sub_f32_e32 v71, v46, v68
	v_mul_f32_e32 v69, 0x3fb8aa3b, v69
	v_mul_f32_e32 v70, 0x3fb8aa3b, v70
	v_mul_f32_e32 v71, 0x3fb8aa3b, v71
	v_exp_f32_e32 v69, v69
	v_exp_f32_e32 v70, v70
	v_exp_f32_e32 v71, v71
	s_nop 0
	v_add_f32_e32 v72, v69, v70
	v_add_f32_e32 v72, v71, v72
	v_div_scale_f32 v73, s[28:29], v72, v72, 1.0
	v_rcp_f32_e32 v74, v73
	v_div_scale_f32 v75, vcc, 1.0, v72, 1.0
	s_nop 0
	v_fma_f32 v76, -v73, v74, 1.0
	v_fmac_f32_e32 v74, v76, v74
	v_mul_f32_e32 v77, v75, v74
	v_fma_f32 v76, -v73, v77, v75
	v_fmac_f32_e32 v77, v76, v74
	v_fma_f32 v73, -v73, v77, v75
	v_div_fmas_f32 v73, v73, v74, v77
	v_div_fixup_f32 v72, v73, v72, 1.0
	v_mul_f32_e32 v69, v69, v72
	v_mul_f32_e32 v70, v70, v72
	v_mul_f32_e32 v71, v71, v72
	v_lshlrev_b32_e32 v78, 16, v32
	v_and_b32_e32 v81, 0xffff0000, v32
	v_lshlrev_b32_e32 v79, 16, v36
	v_and_b32_e32 v82, 0xffff0000, v36
	v_lshlrev_b32_e32 v80, 16, v40
	v_and_b32_e32 v83, 0xffff0000, v40
	v_mul_f32_e32 v84, v69, v78
	v_mul_f32_e32 v85, v69, v81
	v_fmac_f32_e32 v84, v70, v79
	v_fmac_f32_e32 v85, v70, v82
	v_fmac_f32_e32 v84, v71, v80
	v_fmac_f32_e32 v85, v71, v83
	v_cvt_pk_bf16_f32 v96, v84, v85
	v_lshlrev_b32_e32 v78, 16, v33
	v_and_b32_e32 v81, 0xffff0000, v33
	v_lshlrev_b32_e32 v79, 16, v37
	v_and_b32_e32 v82, 0xffff0000, v37
	v_lshlrev_b32_e32 v80, 16, v41
	v_and_b32_e32 v83, 0xffff0000, v41
	v_mul_f32_e32 v84, v69, v78
	v_mul_f32_e32 v85, v69, v81
	v_fmac_f32_e32 v84, v70, v79
	v_fmac_f32_e32 v85, v70, v82
	v_fmac_f32_e32 v84, v71, v80
	v_fmac_f32_e32 v85, v71, v83
	v_cvt_pk_bf16_f32 v97, v84, v85
	v_lshlrev_b32_e32 v78, 16, v34
	v_and_b32_e32 v81, 0xffff0000, v34
	v_lshlrev_b32_e32 v79, 16, v38
	v_and_b32_e32 v82, 0xffff0000, v38
	v_lshlrev_b32_e32 v80, 16, v42
	v_and_b32_e32 v83, 0xffff0000, v42
	v_mul_f32_e32 v84, v69, v78
	v_mul_f32_e32 v85, v69, v81
	v_fmac_f32_e32 v84, v70, v79
	v_fmac_f32_e32 v85, v70, v82
	v_fmac_f32_e32 v84, v71, v80
	v_fmac_f32_e32 v85, v71, v83
	v_cvt_pk_bf16_f32 v98, v84, v85
	v_lshlrev_b32_e32 v78, 16, v35
	v_and_b32_e32 v81, 0xffff0000, v35
	v_lshlrev_b32_e32 v79, 16, v39
	v_and_b32_e32 v82, 0xffff0000, v39
	v_lshlrev_b32_e32 v80, 16, v43
	v_and_b32_e32 v83, 0xffff0000, v43
	v_mul_f32_e32 v84, v69, v78
	v_mul_f32_e32 v85, v69, v81
	v_fmac_f32_e32 v84, v70, v79
	v_fmac_f32_e32 v85, v70, v82
	v_fmac_f32_e32 v84, v71, v80
	v_fmac_f32_e32 v85, v71, v83
	v_cvt_pk_bf16_f32 v99, v84, v85
	s_add_u32 s26, s24, 0x2c00000
	s_addc_u32 s27, s25, 0
	global_store_dwordx4 v64, v[96:99], s[26:27]
	s_waitcnt vmcnt(3)
; __device__ __forceinline__ float bf_lo(unsigned w) { return __uint_as_float(w << 16); }
; __device__ __forceinline__ float bf_hi(unsigned w) { return __uint_as_float(w & 0xffff0000u); }
; __device__ __forceinline__ unsigned pk2(float lo, float hi) { return pg8::cvt_pk_bf16(lo, hi); }
; __device__ __forceinline__ void merge_rows(const Args& a, int gw, int NGW, int lane) {
;     const bf16* OG = (const bf16*)(a.ws + WS_OG); const float* LSE = (const float*)(a.ws + WS_LSE); bf16* YAT = (bf16*)(a.ws + WS_YAT);
;     const int hh = lane >> 4;
;     for (int mb = gw; mb < MT; mb += 4 * NGW) {
;         float l[4][3]; v2u o[4][3];
; #pragma unroll
;         for (int r = 0; r < 4; ++r) { const int m = mb + r * NGW; const int mc = m < MT ? m : mb;
; #pragma unroll
;             for (int g = 0; g < 3; ++g) { l[r][g] = LSE[((size_t)g * MT + mc) * 4 + hh]; o[r][g] = *(const v2u*)(OG + ((size_t)g * MT + mc) * 256 + 4 * lane); } }
;     ...
;         for (int r = 0; r < 4; ++r) { const int m = mb + r * NGW; if (m < MT) {
;             const float mxl = fmaxf(l[r][0], fmaxf(l[r][1], l[r][2]));
;             float a0 = __expf(l[r][0] - mxl), a1 = __expf(l[r][1] - mxl), a2 = __expf(l[r][2] - mxl); const float is = 1.0f / (a0 + a1 + a2); a0 *= is; a1 *= is; a2 *= is;
;             const v2u o0 = o[r][0], o1 = o[r][1], o2 = o[r][2];
;             v2u w;
;             w.x = pk2(a0 * pg8::bf_lo(o0.x) + a1 * pg8::bf_lo(o1.x) + a2 * pg8::bf_lo(o2.x), a0 * pg8::bf_hi(o0.x) + a1 * pg8::bf_hi(o1.x) + a2 * pg8::bf_hi(o2.x));
;             w.y = pk2(a0 * pg8::bf_lo(o0.y) + a1 * pg8::bf_lo(o1.y) + a2 * pg8::bf_lo(o2.y), a0 * pg8::bf_hi(o0.y) + a1 * pg8::bf_hi(o1.y) + a2 * pg8::bf_hi(o2.y));
;             *(v2u*)(YAT + (size_t)m * 256 + 4 * lane) = w; } }
	v_max3_f32 v68, v60, v61, v62
	v_sub_f32_e32 v69, v60, v68
	v_sub_f32_e32 v70, v61, v68
	v_sub_f32_e32 v71, v62, v68
	v_mul_f32_e32 v69, 0x3fb8aa3b, v69
	v_mul_f32_e32 v70, 0x3fb8aa3b, v70
	v_mul_f32_e32 v71, 0x3fb8aa3b, v71
	v_exp_f32_e32 v69, v69
	v_exp_f32_e32 v70, v70
	v_exp_f32_e32 v71, v71
	s_nop 0
	v_add_f32_e32 v72, v69, v70
	v_add_f32_e32 v72, v71, v72
	v_div_scale_f32 v73, s[28:29], v72, v72, 1.0
	v_rcp_f32_e32 v74, v73
	v_div_scale_f32 v75, vcc, 1.0, v72, 1.0
	s_nop 0
	v_fma_f32 v76, -v73, v74, 1.0
	v_fmac_f32_e32 v74, v76, v74
	v_mul_f32_e32 v77, v75, v74
	v_fma_f32 v76, -v73, v77, v75
	v_fmac_f32_e32 v77, v76, v74
	v_fma_f32 v73, -v73, v77, v75
	v_div_fmas_f32 v73, v73, v74, v77
	v_div_fixup_f32 v72, v73, v72, 1.0
	v_mul_f32_e32 v69, v69, v72
	v_mul_f32_e32 v70, v70, v72
	v_mul_f32_e32 v71, v71, v72
	v_lshlrev_b32_e32 v78, 16, v48
	v_and_b32_e32 v81, 0xffff0000, v48
	v_lshlrev_b32_e32 v79, 16, v52
	v_and_b32_e32 v82, 0xffff0000, v52
	v_lshlrev_b32_e32 v80, 16, v56
	v_and_b32_e32 v83, 0xffff0000, v56
	v_mul_f32_e32 v84, v69, v78
	v_mul_f32_e32 v85, v69, v81
	v_fmac_f32_e32 v84, v70, v79
	v_fmac_f32_e32 v85, v70, v82
	v_fmac_f32_e32 v84, v71, v80
	v_fmac_f32_e32 v85, v71, v83
	v_cvt_pk_bf16_f32 v100, v84, v85
	v_lshlrev_b32_e32 v78, 16, v49
	v_and_b32_e32 v81, 0xffff0000, v49
	v_lshlrev_b32_e32 v79, 16, v53
	v_and_b32_e32 v82, 0xffff0000, v53
	v_lshlrev_b32_e32 v80, 16, v57
	v_and_b32_e32 v83, 0xffff0000, v57
	v_mul_f32_e32 v84, v69, v78
	v_mul_f32_e32 v85, v69, v81
	v_fmac_f32_e32 v84, v70, v79
	v_fmac_f32_e32 v85, v70, v82
	v_fmac_f32_e32 v84, v71, v80
	v_fmac_f32_e32 v85, v71, v83
	v_cvt_pk_bf16_f32 v101, v84, v85
	v_lshlrev_b32_e32 v78, 16, v50
	v_and_b32_e32 v81, 0xffff0000, v50
	v_lshlrev_b32_e32 v79, 16, v54
	v_and_b32_e32 v82, 0xffff0000, v54
	v_lshlrev_b32_e32 v80, 16, v58
	v_and_b32_e32 v83, 0xffff0000, v58
	v_mul_f32_e32 v84, v69, v78
	v_mul_f32_e32 v85, v69, v81
	v_fmac_f32_e32 v84, v70, v79
	v_fmac_f32_e32 v85, v70, v82
	v_fmac_f32_e32 v84, v71, v80
	v_fmac_f32_e32 v85, v71, v83
	v_cvt_pk_bf16_f32 v102, v84, v85
	v_lshlrev_b32_e32 v78, 16, v51
	v_and_b32_e32 v81, 0xffff0000, v51
	v_lshlrev_b32_e32 v79, 16, v55
	v_and_b32_e32 v82, 0xffff0000, v55
	v_lshlrev_b32_e32 v80, 16, v59
	v_and_b32_e32 v83, 0xffff0000, v59
	v_mul_f32_e32 v84, v69, v78
	v_mul_f32_e32 v85, v69, v81
	v_fmac_f32_e32 v84, v70, v79
	v_fmac_f32_e32 v85, v70, v82
	v_fmac_f32_e32 v84, v71, v80
	v_fmac_f32_e32 v85, v71, v83
	v_cvt_pk_bf16_f32 v103, v84, v85
	s_add_u32 s26, s24, 0x2e00000
	s_addc_u32 s27, s25, 0
	global_store_dwordx4 v64, v[100:103], s[26:27]
	s_branch .LBB0_467
.Lorig_merge:
	v_and_b32_e32 v4, 63, v0
	v_lshrrev_b32_e32 v0, 2, v0
	v_and_b32_e32 v2, 12, v0
	v_mov_b32_e32 v3, 0
	s_waitcnt lgkmcnt(0)
	v_lshl_add_u64 v[0:1], s[14:15], 0, v[2:3]
	s_mov_b64 s[0:1], 0x33000000
	v_lshlrev_b32_e32 v2, 3, v4
	v_lshl_add_u64 v[0:1], v[0:1], 0, s[0:1]
	v_lshl_add_u64 v[4:5], s[14:15], 0, v[2:3]
	s_mov_b64 s[0:1], 0x2a000000
	v_lshl_add_u64 v[2:3], v[4:5], 0, s[0:1]
	s_mov_b64 s[0:1], 0x3c000000
	v_lshl_add_u64 v[4:5], v[4:5], 0, s[0:1]
	s_lshl_b32 s33, s70, 4
	s_mul_i32 s54, s70, 24
	s_branch .LBB0_461

; __device__ __forceinline__ float bf_lo(unsigned w) { return __uint_as_float(w << 16); }
; __device__ __forceinline__ float bf_hi(unsigned w) { return __uint_as_float(w & 0xffff0000u); }
; #define PH_IDS() const int tid = lnd((int)threadIdx.x), lane = tid & 63, wave = __builtin_amdgcn_readfirstlane(tid >> 6), gw = bid * 8 + wave; (void)lane; (void)gw
; #define REPS(k) for (int rep_ = 0; rep_ < (((REP_MASK >> (k)) & 1) ? 2 : 1); ++rep_)
; template <bool BF> __device__ __forceinline__ void prep_rows(const float* xp, const float* xs, const bf16* hb, const float* g, const float* MOD, int shoff, int scoff, bf16* U, int gw, int NGW, int lane) {
;     constexpr int R = 4;
;     for (int mb = gw; mb < MT; mb += R * NGW) {
;         f32x4 v[R][4]; float s[R];
; #pragma unroll
;         for (int r = 0; r < R; ++r) { const int m = mb + r * NGW; const int mc = m < MT ? m : mb;
; #pragma unroll
;             for (int j = 0; j < 4; ++j) {
;                 if (BF) { const v2u a0 = *(const v2u*)(hb + (size_t)mc * DM + 4 * lane + 256 * j);
;                     v[r][j].x = pg8::bf_lo(a0.x); v[r][j].y = pg8::bf_hi(a0.x); v[r][j].z = pg8::bf_lo(a0.y); v[r][j].w = pg8::bf_hi(a0.y); }
;                 else { const float* xr = mc < MP ? xp + (size_t)mc * DM : xs + (size_t)(mc - MP) * DM; v[r][j] = *(const f32x4*)(xr + 4 * lane + 256 * j); } } }
; template <int PHM> __global__ void __launch_bounds__(512, 2) mk_fwd(Args karg) {
;     ...
;     if (IN(11)) REPS(11) { PH_ARGS(); PH_IDS(); prep_rows<true>(nullptr, nullptr, (const bf16*)(ws + WS_H16), a.in[I_N2G], MOD, 3072, 4096, (bf16*)(ws + WS_U2), gw, NGW, lane); }
.LBB0_1168:
	s_cmp_lt_i32 s78, 12
	s_cselect_b64 s[0:1], -1, 0
	s_and_b64 s[0:1], s[0:1], s[4:5]
	s_andn2_b64 vcc, exec, s[0:1]
	s_cbranch_vccnz .LBB0_1178
	s_mov_b64 s[2:3], s[72:73]
	s_waitcnt vmcnt(0)
	v_mov_b32_e32 v8, v254
	s_lshl_b32 s6, s96, 3
	v_readfirstlane_b32 s4, v8
	s_ashr_i32 s7, s4, 6
	s_add_i32 s26, s7, s6
	s_cmp_gt_i32 s26, 0x17fff
	s_cbranch_scc1 .LBB0_1178
	s_cmp_eq_u32 s70, 0x100
	s_cbranch_scc0 .Lorig_prep11
	s_load_dwordx2 s[6:7], s[72:73], 0xc8
	s_load_dwordx2 s[8:9], s[72:73], 0xe8
	v_and_b32_e32 v82, 63, v254
	v_lshlrev_b32_e32 v80, 5, v82
	v_add_u32_e32 v81, 0x1000, v80
	v_xor_b32_e32 v83, 1, v82
	v_xor_b32_e32 v84, 2, v82
	v_xor_b32_e32 v85, 4, v82
	v_xor_b32_e32 v86, 8, v82
	v_xor_b32_e32 v87, 16, v82
	v_xor_b32_e32 v88, 32, v82
	v_lshlrev_b32_e32 v83, 2, v83
	v_lshlrev_b32_e32 v84, 2, v84
	v_lshlrev_b32_e32 v85, 2, v85
	v_lshlrev_b32_e32 v86, 2, v86
	v_lshlrev_b32_e32 v87, 2, v87
	v_lshlrev_b32_e32 v88, 2, v88
	v_lshlrev_b32_e32 v82, 4, v82
	v_mov_b32_e32 v89, 0x358637bd
	v_mov_b32_e32 v90, 0x260
	s_mov_b32 s54, 0xf800000
	v_readfirstlane_b32 s45, v254
	s_nop 3
	s_lshl_b32 s50, s96, 3
	s_lshr_b32 s45, s45, 6
	s_add_i32 s45, s45, s50
	s_waitcnt lgkmcnt(0)
	s_lshl_b32 s50, s45, 11
	s_add_u32 s16, s8, s50
	s_addc_u32 s17, s9, 0
	s_add_u32 s16, s16, 0xf000000
	s_addc_u32 s17, s17, 0
	s_add_u32 s20, s8, s50
	s_addc_u32 s21, s9, 0
	s_add_u32 s20, s20, 0x33000000
	s_addc_u32 s21, s21, 0
	global_load_dwordx4 v[64:67], v80, s[6:7] offset:0
	global_load_dwordx4 v[68:71], v80, s[6:7] offset:16
	global_load_dwordx4 v[72:75], v80, s[6:7] offset:2048
	global_load_dwordx4 v[76:79], v80, s[6:7] offset:2064
	s_mov_b64 s[24:25], s[16:17]
	s_add_u32 s26, s16, 0x400000
	s_addc_u32 s27, s17, 0
	s_add_u32 s28, s16, 0x800000
	s_addc_u32 s29, s17, 0
	s_add_u32 s30, s16, 0xc00000
	s_addc_u32 s31, s17, 0
	global_load_dwordx4 v[96:99], v82, s[24:25] offset:0
	global_load_dwordx4 v[100:103], v82, s[24:25] offset:1024
	global_load_dwordx4 v[104:107], v82, s[26:27] offset:0
	global_load_dwordx4 v[108:111], v82, s[26:27] offset:1024
	global_load_dwordx4 v[112:115], v82, s[28:29] offset:0
	global_load_dwordx4 v[116:119], v82, s[28:29] offset:1024
	global_load_dwordx4 v[120:123], v82, s[30:31] offset:0
	global_load_dwordx4 v[124:127], v82, s[30:31] offset:1024
	s_add_u32 s34, s8, 0x3000
	s_addc_u32 s35, s9, 0
	s_add_u32 s36, s8, 0x3000
	s_addc_u32 s37, s9, 0
	global_load_dwordx4 v[176:179], v80, s[34:35] offset:0
	global_load_dwordx4 v[180:183], v80, s[34:35] offset:16
	global_load_dwordx4 v[184:187], v80, s[34:35] offset:2048
	global_load_dwordx4 v[188:191], v80, s[34:35] offset:2064
	global_load_dwordx4 v[160:163], v81, s[34:35] offset:0
	global_load_dwordx4 v[164:167], v81, s[34:35] offset:16
	global_load_dwordx4 v[168:171], v81, s[34:35] offset:2048
	global_load_dwordx4 v[172:175], v81, s[34:35] offset:2064
	global_load_dwordx4 v[208:211], v80, s[36:37] offset:0
	global_load_dwordx4 v[212:215], v80, s[36:37] offset:16
	global_load_dwordx4 v[216:219], v80, s[36:37] offset:2048
	global_load_dwordx4 v[220:223], v80, s[36:37] offset:2064
	global_load_dwordx4 v[192:195], v81, s[36:37] offset:0
	global_load_dwordx4 v[196:199], v81, s[36:37] offset:16
	global_load_dwordx4 v[200:203], v81, s[36:37] offset:2048
	global_load_dwordx4 v[204:207], v81, s[36:37] offset:2064
	s_add_u32 s24, s16, 0x1000000
	s_addc_u32 s25, s17, 0
	s_add_u32 s26, s16, 0x1400000
	s_addc_u32 s27, s17, 0
	s_add_u32 s28, s16, 0x1800000
	s_addc_u32 s29, s17, 0
	s_add_u32 s30, s16, 0x1c00000
	s_addc_u32 s31, s17, 0
	global_load_dwordx4 v[128:131], v82, s[24:25] offset:0
	global_load_dwordx4 v[132:135], v82, s[24:25] offset:1024
	global_load_dwordx4 v[136:139], v82, s[26:27] offset:0
	global_load_dwordx4 v[140:143], v82, s[26:27] offset:1024
	global_load_dwordx4 v[144:147], v82, s[28:29] offset:0
	global_load_dwordx4 v[148:151], v82, s[28:29] offset:1024
	global_load_dwordx4 v[152:155], v82, s[30:31] offset:0
	global_load_dwordx4 v[156:159], v82, s[30:31] offset:1024
	s_waitcnt vmcnt(24)
	v_lshlrev_b32_e32 v0, 16, v96
	v_and_b32_e32 v1, 0xffff0000, v96
	v_lshlrev_b32_e32 v2, 16, v97
	v_and_b32_e32 v3, 0xffff0000, v97
	v_lshlrev_b32_e32 v4, 16, v98
	v_and_b32_e32 v5, 0xffff0000, v98
	v_lshlrev_b32_e32 v6, 16, v99
	v_and_b32_e32 v7, 0xffff0000, v99
	v_lshlrev_b32_e32 v8, 16, v100
	v_and_b32_e32 v9, 0xffff0000, v100
	v_lshlrev_b32_e32 v10, 16, v101
	v_and_b32_e32 v11, 0xffff0000, v101
	v_lshlrev_b32_e32 v12, 16, v102
	v_and_b32_e32 v13, 0xffff0000, v102
	v_lshlrev_b32_e32 v14, 16, v103
	v_and_b32_e32 v15, 0xffff0000, v103
	v_lshlrev_b32_e32 v16, 16, v104
	v_and_b32_e32 v17, 0xffff0000, v104
	v_lshlrev_b32_e32 v18, 16, v105
	v_and_b32_e32 v19, 0xffff0000, v105
	v_lshlrev_b32_e32 v20, 16, v106
	v_and_b32_e32 v21, 0xffff0000, v106
	v_lshlrev_b32_e32 v22, 16, v107
	v_and_b32_e32 v23, 0xffff0000, v107
	v_lshlrev_b32_e32 v24, 16, v108
	v_and_b32_e32 v25, 0xffff0000, v108
	v_lshlrev_b32_e32 v26, 16, v109
	v_and_b32_e32 v27, 0xffff0000, v109
	v_lshlrev_b32_e32 v28, 16, v110
	v_and_b32_e32 v29, 0xffff0000, v110
	v_lshlrev_b32_e32 v30, 16, v111
	v_and_b32_e32 v31, 0xffff0000, v111
	v_lshlrev_b32_e32 v32, 16, v112
	v_and_b32_e32 v33, 0xffff0000, v112
	v_lshlrev_b32_e32 v34, 16, v113
	v_and_b32_e32 v35, 0xffff0000, v113
	v_lshlrev_b32_e32 v36, 16, v114
	v_and_b32_e32 v37, 0xffff0000, v114
	v_lshlrev_b32_e32 v38, 16, v115
	v_and_b32_e32 v39, 0xffff0000, v115
	v_lshlrev_b32_e32 v40, 16, v116
	v_and_b32_e32 v41, 0xffff0000, v116
	v_lshlrev_b32_e32 v42, 16, v117
	v_and_b32_e32 v43, 0xffff0000, v117
	v_lshlrev_b32_e32 v44, 16, v118
	v_and_b32_e32 v45, 0xffff0000, v118
	v_lshlrev_b32_e32 v46, 16, v119
; template <bool BF> __device__ __forceinline__ void prep_rows(const float* xp, const float* xs, const bf16* hb, const float* g, const float* MOD, int shoff, int scoff, bf16* U, int gw, int NGW, int lane) {
;     ...
;         for (int r = 0; r < R; ++r) { float t = 0.f;
; #pragma unroll
;             for (int j = 0; j < 4; ++j) t += (v[r][j].x * v[r][j].x + v[r][j].y * v[r][j].y) + (v[r][j].z * v[r][j].z + v[r][j].w * v[r][j].w);
;             s[r] = t; }
; #pragma unroll
;         for (int o = 1; o < 64; o <<= 1) {
; #pragma unroll
;             for (int r = 0; r < R; ++r) s[r] += __shfl_xor(s[r], o); }
; #pragma unroll
;         for (int r = 0; r < R; ++r) { const int m = mb + r * NGW; if (m < MT) {
;             const float rstd = 1.0f / sqrtf(s[r] * (1.0f / DM) + RMS_EPS);
	v_and_b32_e32 v47, 0xffff0000, v119
	v_lshlrev_b32_e32 v48, 16, v120
	v_and_b32_e32 v49, 0xffff0000, v120
	v_lshlrev_b32_e32 v50, 16, v121
	v_and_b32_e32 v51, 0xffff0000, v121
	v_lshlrev_b32_e32 v52, 16, v122
	v_and_b32_e32 v53, 0xffff0000, v122
	v_lshlrev_b32_e32 v54, 16, v123
	v_and_b32_e32 v55, 0xffff0000, v123
	v_lshlrev_b32_e32 v56, 16, v124
	v_and_b32_e32 v57, 0xffff0000, v124
	v_lshlrev_b32_e32 v58, 16, v125
	v_and_b32_e32 v59, 0xffff0000, v125
	v_lshlrev_b32_e32 v60, 16, v126
	v_and_b32_e32 v61, 0xffff0000, v126
	v_lshlrev_b32_e32 v62, 16, v127
	v_and_b32_e32 v63, 0xffff0000, v127
	v_pk_mul_f32 v[240:241], v[0:1], v[0:1]
	v_pk_mul_f32 v[242:243], v[16:17], v[16:17]
	v_pk_mul_f32 v[244:245], v[32:33], v[32:33]
	v_pk_mul_f32 v[246:247], v[48:49], v[48:49]
	v_pk_fma_f32 v[240:241], v[2:3], v[2:3], v[240:241]
	v_pk_fma_f32 v[242:243], v[18:19], v[18:19], v[242:243]
	v_pk_fma_f32 v[244:245], v[34:35], v[34:35], v[244:245]
	v_pk_fma_f32 v[246:247], v[50:51], v[50:51], v[246:247]
	v_pk_fma_f32 v[240:241], v[4:5], v[4:5], v[240:241]
	v_pk_fma_f32 v[242:243], v[20:21], v[20:21], v[242:243]
	v_pk_fma_f32 v[244:245], v[36:37], v[36:37], v[244:245]
	v_pk_fma_f32 v[246:247], v[52:53], v[52:53], v[246:247]
	v_pk_fma_f32 v[240:241], v[6:7], v[6:7], v[240:241]
	v_pk_fma_f32 v[242:243], v[22:23], v[22:23], v[242:243]
	v_pk_fma_f32 v[244:245], v[38:39], v[38:39], v[244:245]
	v_pk_fma_f32 v[246:247], v[54:55], v[54:55], v[246:247]
	v_pk_fma_f32 v[240:241], v[8:9], v[8:9], v[240:241]
	v_pk_fma_f32 v[242:243], v[24:25], v[24:25], v[242:243]
	v_pk_fma_f32 v[244:245], v[40:41], v[40:41], v[244:245]
	v_pk_fma_f32 v[246:247], v[56:57], v[56:57], v[246:247]
	v_pk_fma_f32 v[240:241], v[10:11], v[10:11], v[240:241]
	v_pk_fma_f32 v[242:243], v[26:27], v[26:27], v[242:243]
	v_pk_fma_f32 v[244:245], v[42:43], v[42:43], v[244:245]
	v_pk_fma_f32 v[246:247], v[58:59], v[58:59], v[246:247]
	v_pk_fma_f32 v[240:241], v[12:13], v[12:13], v[240:241]
	v_pk_fma_f32 v[242:243], v[28:29], v[28:29], v[242:243]
	v_pk_fma_f32 v[244:245], v[44:45], v[44:45], v[244:245]
	v_pk_fma_f32 v[246:247], v[60:61], v[60:61], v[246:247]
	v_pk_fma_f32 v[240:241], v[14:15], v[14:15], v[240:241]
	v_pk_fma_f32 v[242:243], v[30:31], v[30:31], v[242:243]
	v_pk_fma_f32 v[244:245], v[46:47], v[46:47], v[244:245]
	v_pk_fma_f32 v[246:247], v[62:63], v[62:63], v[246:247]
	v_add_f32_e32 v224, v240, v241
	v_add_f32_e32 v225, v242, v243
	v_add_f32_e32 v226, v244, v245
	v_add_f32_e32 v227, v246, v247
	ds_bpermute_b32 v228, v83, v224
	ds_bpermute_b32 v229, v83, v225
	ds_bpermute_b32 v230, v83, v226
	ds_bpermute_b32 v231, v83, v227
	s_waitcnt lgkmcnt(0)
	v_add_f32_e32 v224, v224, v228
	v_add_f32_e32 v225, v225, v229
	v_add_f32_e32 v226, v226, v230
	v_add_f32_e32 v227, v227, v231
	ds_bpermute_b32 v228, v84, v224
	ds_bpermute_b32 v229, v84, v225
	ds_bpermute_b32 v230, v84, v226
	ds_bpermute_b32 v231, v84, v227
	s_waitcnt lgkmcnt(0)
	v_add_f32_e32 v224, v224, v228
	v_add_f32_e32 v225, v225, v229
	v_add_f32_e32 v226, v226, v230
	v_add_f32_e32 v227, v227, v231
	ds_bpermute_b32 v228, v85, v224
	ds_bpermute_b32 v229, v85, v225
	ds_bpermute_b32 v230, v85, v226
	ds_bpermute_b32 v231, v85, v227
	s_waitcnt lgkmcnt(0)
	v_add_f32_e32 v224, v224, v228
	v_add_f32_e32 v225, v225, v229
	v_add_f32_e32 v226, v226, v230
	v_add_f32_e32 v227, v227, v231
	ds_bpermute_b32 v228, v86, v224
	ds_bpermute_b32 v229, v86, v225
	ds_bpermute_b32 v230, v86, v226
	ds_bpermute_b32 v231, v86, v227
	s_waitcnt lgkmcnt(0)
	v_add_f32_e32 v224, v224, v228
	v_add_f32_e32 v225, v225, v229
	v_add_f32_e32 v226, v226, v230
	v_add_f32_e32 v227, v227, v231
	ds_bpermute_b32 v228, v87, v224
	ds_bpermute_b32 v229, v87, v225
	ds_bpermute_b32 v230, v87, v226
	ds_bpermute_b32 v231, v87, v227
	s_waitcnt lgkmcnt(0)
	v_add_f32_e32 v224, v224, v228
	v_add_f32_e32 v225, v225, v229
	v_add_f32_e32 v226, v226, v230
	v_add_f32_e32 v227, v227, v231
	ds_bpermute_b32 v228, v88, v224
	ds_bpermute_b32 v229, v88, v225
	ds_bpermute_b32 v230, v88, v226
	ds_bpermute_b32 v231, v88, v227
	s_waitcnt lgkmcnt(0)
	v_add_f32_e32 v224, v224, v228
	v_add_f32_e32 v225, v225, v229
	v_add_f32_e32 v226, v226, v230
	v_add_f32_e32 v227, v227, v231
	v_fmamk_f32 v240, v224, 0x3a800000, v89
	v_mul_f32_e32 v241, 0x4f800000, v240
	v_cmp_gt_f32_e32 vcc, s54, v240
	s_nop 1
	v_cndmask_b32_e32 v247, v240, v241, vcc
	v_sqrt_f32_e32 v242, v247
	s_nop 1
	v_add_u32_e32 v243, -1, v242
	v_add_u32_e32 v244, 1, v242
	v_fma_f32 v245, -v243, v242, v247
	v_fma_f32 v246, -v244, v242, v247
	v_cmp_ge_f32_e64 s[52:53], 0, v245
	s_nop 1
	v_cndmask_b32_e64 v242, v242, v243, s[52:53]
	v_cmp_lt_f32_e64 s[52:53], 0, v246
	s_nop 1
	v_cndmask_b32_e64 v242, v242, v244, s[52:53]
	v_mul_f32_e32 v243, 0x37800000, v242
	v_cndmask_b32_e32 v242, v242, v243, vcc
	v_cmp_class_f32_e32 vcc, v247, v90
	s_nop 1
	v_cndmask_b32_e32 v247, v242, v247, vcc
	v_div_scale_f32 v248, s[52:53], v247, v247, 1.0
	v_rcp_f32_e32 v249, v248
	v_div_scale_f32 v228, vcc, 1.0, v247, 1.0
	s_nop 0
	v_fma_f32 v229, -v248, v249, 1.0
	v_fmac_f32_e32 v249, v229, v249
	v_mul_f32_e32 v230, v228, v249
	v_fma_f32 v229, -v248, v230, v228
	v_fmac_f32_e32 v230, v229, v249
	v_fma_f32 v248, -v248, v230, v228
	v_div_fmas_f32 v248, v248, v249, v230
	v_div_fixup_f32 v232, v248, v247, 1.0
	v_fmamk_f32 v240, v225, 0x3a800000, v89
	v_mul_f32_e32 v241, 0x4f800000, v240
	v_cmp_gt_f32_e32 vcc, s54, v240
	s_nop 1
	v_cndmask_b32_e32 v247, v240, v241, vcc
	v_sqrt_f32_e32 v242, v247
	s_nop 1
	v_add_u32_e32 v243, -1, v242
	v_add_u32_e32 v244, 1, v242
	v_fma_f32 v245, -v243, v242, v247
	v_fma_f32 v246, -v244, v242, v247
	v_cmp_ge_f32_e64 s[52:53], 0, v245
	s_nop 1
; __device__ __forceinline__ unsigned pk2(float lo, float hi) { return pg8::cvt_pk_bf16(lo, hi); }
; template <bool BF> __device__ __forceinline__ void prep_rows(const float* xp, const float* xs, const bf16* hb, const float* g, const float* MOD, int shoff, int scoff, bf16* U, int gw, int NGW, int lane) {
;     ...
;             const float rstd = 1.0f / sqrtf(s[r] * (1.0f / DM) + RMS_EPS);
;             const float* mr = MOD + (size_t)(m < MP ? (m >> 13) : 8 + ((m - MP) >> 12)) * 6144;
; #pragma unroll
;             for (int j = 0; j < 4; ++j) { const int c = 4 * lane + 256 * j;
;                 const f32x4 gg = *(const f32x4*)(g + c), sc = *(const f32x4*)(mr + scoff + c), sh = *(const f32x4*)(mr + shoff + c);
;                 const f32x4 o = v[r][j] * rstd * gg * (sc + 1.0f) + sh; v2u w; w.x = pk2(o.x, o.y); w.y = pk2(o.z, o.w); *(v2u*)(U + (size_t)m * DM + c) = w; } } }
	v_cndmask_b32_e64 v242, v242, v243, s[52:53]
	v_cmp_lt_f32_e64 s[52:53], 0, v246
	s_nop 1
	v_cndmask_b32_e64 v242, v242, v244, s[52:53]
	v_mul_f32_e32 v243, 0x37800000, v242
	v_cndmask_b32_e32 v242, v242, v243, vcc
	v_cmp_class_f32_e32 vcc, v247, v90
	s_nop 1
	v_cndmask_b32_e32 v247, v242, v247, vcc
	v_div_scale_f32 v248, s[52:53], v247, v247, 1.0
	v_rcp_f32_e32 v249, v248
	v_div_scale_f32 v228, vcc, 1.0, v247, 1.0
	s_nop 0
	v_fma_f32 v229, -v248, v249, 1.0
	v_fmac_f32_e32 v249, v229, v249
	v_mul_f32_e32 v230, v228, v249
	v_fma_f32 v229, -v248, v230, v228
	v_fmac_f32_e32 v230, v229, v249
	v_fma_f32 v248, -v248, v230, v228
	v_div_fmas_f32 v248, v248, v249, v230
	v_div_fixup_f32 v234, v248, v247, 1.0
	v_fmamk_f32 v240, v226, 0x3a800000, v89
	v_mul_f32_e32 v241, 0x4f800000, v240
	v_cmp_gt_f32_e32 vcc, s54, v240
	s_nop 1
	v_cndmask_b32_e32 v247, v240, v241, vcc
	v_sqrt_f32_e32 v242, v247
	s_nop 1
	v_add_u32_e32 v243, -1, v242
	v_add_u32_e32 v244, 1, v242
	v_fma_f32 v245, -v243, v242, v247
	v_fma_f32 v246, -v244, v242, v247
	v_cmp_ge_f32_e64 s[52:53], 0, v245
	s_nop 1
	v_cndmask_b32_e64 v242, v242, v243, s[52:53]
	v_cmp_lt_f32_e64 s[52:53], 0, v246
	s_nop 1
	v_cndmask_b32_e64 v242, v242, v244, s[52:53]
	v_mul_f32_e32 v243, 0x37800000, v242
	v_cndmask_b32_e32 v242, v242, v243, vcc
	v_cmp_class_f32_e32 vcc, v247, v90
	s_nop 1
	v_cndmask_b32_e32 v247, v242, v247, vcc
	v_div_scale_f32 v248, s[52:53], v247, v247, 1.0
	v_rcp_f32_e32 v249, v248
	v_div_scale_f32 v228, vcc, 1.0, v247, 1.0
	s_nop 0
	v_fma_f32 v229, -v248, v249, 1.0
	v_fmac_f32_e32 v249, v229, v249
	v_mul_f32_e32 v230, v228, v249
	v_fma_f32 v229, -v248, v230, v228
	v_fmac_f32_e32 v230, v229, v249
	v_fma_f32 v248, -v248, v230, v228
	v_div_fmas_f32 v248, v248, v249, v230
	v_div_fixup_f32 v236, v248, v247, 1.0
	v_fmamk_f32 v240, v227, 0x3a800000, v89
	v_mul_f32_e32 v241, 0x4f800000, v240
	v_cmp_gt_f32_e32 vcc, s54, v240
	s_nop 1
	v_cndmask_b32_e32 v247, v240, v241, vcc
	v_sqrt_f32_e32 v242, v247
	s_nop 1
	v_add_u32_e32 v243, -1, v242
	v_add_u32_e32 v244, 1, v242
	v_fma_f32 v245, -v243, v242, v247
	v_fma_f32 v246, -v244, v242, v247
	v_cmp_ge_f32_e64 s[52:53], 0, v245
	s_nop 1
	v_cndmask_b32_e64 v242, v242, v243, s[52:53]
	v_cmp_lt_f32_e64 s[52:53], 0, v246
	s_nop 1
	v_cndmask_b32_e64 v242, v242, v244, s[52:53]
	v_mul_f32_e32 v243, 0x37800000, v242
	v_cndmask_b32_e32 v242, v242, v243, vcc
	v_cmp_class_f32_e32 vcc, v247, v90
	s_nop 1
	v_cndmask_b32_e32 v247, v242, v247, vcc
	v_div_scale_f32 v248, s[52:53], v247, v247, 1.0
	v_rcp_f32_e32 v249, v248
	v_div_scale_f32 v228, vcc, 1.0, v247, 1.0
	s_nop 0
	v_fma_f32 v229, -v248, v249, 1.0
	v_fmac_f32_e32 v249, v229, v249
	v_mul_f32_e32 v230, v228, v249
	v_fma_f32 v229, -v248, v230, v228
	v_fmac_f32_e32 v230, v229, v249
	v_fma_f32 v248, -v248, v230, v228
	v_div_fmas_f32 v248, v248, v249, v230
	v_div_fixup_f32 v238, v248, v247, 1.0
	s_waitcnt vmcnt(8)
	v_pk_add_f32 v[160:161], v[160:161], 1.0 op_sel_hi:[1,0]
	v_pk_add_f32 v[162:163], v[162:163], 1.0 op_sel_hi:[1,0]
	v_pk_add_f32 v[164:165], v[164:165], 1.0 op_sel_hi:[1,0]
	v_pk_add_f32 v[166:167], v[166:167], 1.0 op_sel_hi:[1,0]
	v_pk_add_f32 v[168:169], v[168:169], 1.0 op_sel_hi:[1,0]
	v_pk_add_f32 v[170:171], v[170:171], 1.0 op_sel_hi:[1,0]
	v_pk_add_f32 v[172:173], v[172:173], 1.0 op_sel_hi:[1,0]
	v_pk_add_f32 v[174:175], v[174:175], 1.0 op_sel_hi:[1,0]
	v_pk_add_f32 v[192:193], v[192:193], 1.0 op_sel_hi:[1,0]
	v_pk_add_f32 v[194:195], v[194:195], 1.0 op_sel_hi:[1,0]
	v_pk_add_f32 v[196:197], v[196:197], 1.0 op_sel_hi:[1,0]
	v_pk_add_f32 v[198:199], v[198:199], 1.0 op_sel_hi:[1,0]
	v_pk_add_f32 v[200:201], v[200:201], 1.0 op_sel_hi:[1,0]
	v_pk_add_f32 v[202:203], v[202:203], 1.0 op_sel_hi:[1,0]
	v_pk_add_f32 v[204:205], v[204:205], 1.0 op_sel_hi:[1,0]
	v_pk_add_f32 v[206:207], v[206:207], 1.0 op_sel_hi:[1,0]
	s_mov_b64 s[38:39], s[20:21]
	s_add_u32 s40, s20, 0x400000
	s_addc_u32 s41, s21, 0
	s_add_u32 s46, s20, 0x800000
	s_addc_u32 s47, s21, 0
	s_add_u32 s48, s20, 0xc00000
	s_addc_u32 s49, s21, 0
	v_pk_mul_f32 v[0:1], v[0:1], v[232:233] op_sel_hi:[1,0]
	v_pk_mul_f32 v[2:3], v[2:3], v[232:233] op_sel_hi:[1,0]
	v_pk_mul_f32 v[0:1], v[64:65], v[0:1]
	v_pk_mul_f32 v[2:3], v[66:67], v[2:3]
	v_pk_fma_f32 v[0:1], v[160:161], v[0:1], v[176:177]
	v_pk_fma_f32 v[2:3], v[162:163], v[2:3], v[178:179]
	v_cvt_pk_bf16_f32 v244, v0, v1
	v_cvt_pk_bf16_f32 v245, v2, v3
	v_pk_mul_f32 v[4:5], v[4:5], v[232:233] op_sel_hi:[1,0]
	v_pk_mul_f32 v[6:7], v[6:7], v[232:233] op_sel_hi:[1,0]
	v_pk_mul_f32 v[4:5], v[68:69], v[4:5]
	v_pk_mul_f32 v[6:7], v[70:71], v[6:7]
	v_pk_fma_f32 v[4:5], v[164:165], v[4:5], v[180:181]
	v_pk_fma_f32 v[6:7], v[166:167], v[6:7], v[182:183]
	v_cvt_pk_bf16_f32 v246, v4, v5
	v_cvt_pk_bf16_f32 v247, v6, v7
	global_store_dwordx4 v82, v[244:247], s[38:39] offset:0
	v_pk_mul_f32 v[8:9], v[8:9], v[232:233] op_sel_hi:[1,0]
	v_pk_mul_f32 v[10:11], v[10:11], v[232:233] op_sel_hi:[1,0]
	v_pk_mul_f32 v[8:9], v[72:73], v[8:9]
	v_pk_mul_f32 v[10:11], v[74:75], v[10:11]
	v_pk_fma_f32 v[8:9], v[168:169], v[8:9], v[184:185]
	v_pk_fma_f32 v[10:11], v[170:171], v[10:11], v[186:187]
	v_cvt_pk_bf16_f32 v240, v8, v9
	v_cvt_pk_bf16_f32 v241, v10, v11
	v_pk_mul_f32 v[12:13], v[12:13], v[232:233] op_sel_hi:[1,0]
	v_pk_mul_f32 v[14:15], v[14:15], v[232:233] op_sel_hi:[1,0]
	v_pk_mul_f32 v[12:13], v[76:77], v[12:13]
	v_pk_mul_f32 v[14:15], v[78:79], v[14:15]
	v_pk_fma_f32 v[12:13], v[172:173], v[12:13], v[188:189]
	v_pk_fma_f32 v[14:15], v[174:175], v[14:15], v[190:191]
	v_cvt_pk_bf16_f32 v242, v12, v13
	v_cvt_pk_bf16_f32 v243, v14, v15
	global_store_dwordx4 v82, v[240:243], s[38:39] offset:1024
; __device__ __forceinline__ float bf_lo(unsigned w) { return __uint_as_float(w << 16); }
; __device__ __forceinline__ float bf_hi(unsigned w) { return __uint_as_float(w & 0xffff0000u); }
; __device__ __forceinline__ unsigned pk2(float lo, float hi) { return pg8::cvt_pk_bf16(lo, hi); }
; template <bool BF> __device__ __forceinline__ void prep_rows(const float* xp, const float* xs, const bf16* hb, const float* g, const float* MOD, int shoff, int scoff, bf16* U, int gw, int NGW, int lane) {
;     ...
;         f32x4 v[R][4]; float s[R];
; #pragma unroll
;         for (int r = 0; r < R; ++r) { const int m = mb + r * NGW; const int mc = m < MT ? m : mb;
; #pragma unroll
;             for (int j = 0; j < 4; ++j) {
;                 if (BF) { const v2u a0 = *(const v2u*)(hb + (size_t)mc * DM + 4 * lane + 256 * j);
;                     v[r][j].x = pg8::bf_lo(a0.x); v[r][j].y = pg8::bf_hi(a0.x); v[r][j].z = pg8::bf_lo(a0.y); v[r][j].w = pg8::bf_hi(a0.y); }
;                 else { const float* xr = mc < MP ? xp + (size_t)mc * DM : xs + (size_t)(mc - MP) * DM; v[r][j] = *(const f32x4*)(xr + 4 * lane + 256 * j); } } }
;     ...
;             const float* mr = MOD + (size_t)(m < MP ? (m >> 13) : 8 + ((m - MP) >> 12)) * 6144;
; #pragma unroll
;             for (int j = 0; j < 4; ++j) { const int c = 4 * lane + 256 * j;
;                 const f32x4 gg = *(const f32x4*)(g + c), sc = *(const f32x4*)(mr + scoff + c), sh = *(const f32x4*)(mr + shoff + c);
;                 const f32x4 o = v[r][j] * rstd * gg * (sc + 1.0f) + sh; v2u w; w.x = pk2(o.x, o.y); w.y = pk2(o.z, o.w); *(v2u*)(U + (size_t)m * DM + c) = w; } } }
	v_pk_mul_f32 v[16:17], v[16:17], v[234:235] op_sel_hi:[1,0]
	v_pk_mul_f32 v[18:19], v[18:19], v[234:235] op_sel_hi:[1,0]
	v_pk_mul_f32 v[16:17], v[64:65], v[16:17]
	v_pk_mul_f32 v[18:19], v[66:67], v[18:19]
	v_pk_fma_f32 v[16:17], v[160:161], v[16:17], v[176:177]
	v_pk_fma_f32 v[18:19], v[162:163], v[18:19], v[178:179]
	v_cvt_pk_bf16_f32 v244, v16, v17
	v_cvt_pk_bf16_f32 v245, v18, v19
	v_pk_mul_f32 v[20:21], v[20:21], v[234:235] op_sel_hi:[1,0]
	v_pk_mul_f32 v[22:23], v[22:23], v[234:235] op_sel_hi:[1,0]
	v_pk_mul_f32 v[20:21], v[68:69], v[20:21]
	v_pk_mul_f32 v[22:23], v[70:71], v[22:23]
	v_pk_fma_f32 v[20:21], v[164:165], v[20:21], v[180:181]
	v_pk_fma_f32 v[22:23], v[166:167], v[22:23], v[182:183]
	v_cvt_pk_bf16_f32 v246, v20, v21
	v_cvt_pk_bf16_f32 v247, v22, v23
	global_store_dwordx4 v82, v[244:247], s[40:41] offset:0
	v_pk_mul_f32 v[24:25], v[24:25], v[234:235] op_sel_hi:[1,0]
	v_pk_mul_f32 v[26:27], v[26:27], v[234:235] op_sel_hi:[1,0]
	v_pk_mul_f32 v[24:25], v[72:73], v[24:25]
	v_pk_mul_f32 v[26:27], v[74:75], v[26:27]
	v_pk_fma_f32 v[24:25], v[168:169], v[24:25], v[184:185]
	v_pk_fma_f32 v[26:27], v[170:171], v[26:27], v[186:187]
	v_cvt_pk_bf16_f32 v240, v24, v25
	v_cvt_pk_bf16_f32 v241, v26, v27
	v_pk_mul_f32 v[28:29], v[28:29], v[234:235] op_sel_hi:[1,0]
	v_pk_mul_f32 v[30:31], v[30:31], v[234:235] op_sel_hi:[1,0]
	v_pk_mul_f32 v[28:29], v[76:77], v[28:29]
	v_pk_mul_f32 v[30:31], v[78:79], v[30:31]
	v_pk_fma_f32 v[28:29], v[172:173], v[28:29], v[188:189]
	v_pk_fma_f32 v[30:31], v[174:175], v[30:31], v[190:191]
	v_cvt_pk_bf16_f32 v242, v28, v29
	v_cvt_pk_bf16_f32 v243, v30, v31
	global_store_dwordx4 v82, v[240:243], s[40:41] offset:1024
	v_pk_mul_f32 v[32:33], v[32:33], v[236:237] op_sel_hi:[1,0]
	v_pk_mul_f32 v[34:35], v[34:35], v[236:237] op_sel_hi:[1,0]
	v_pk_mul_f32 v[32:33], v[64:65], v[32:33]
	v_pk_mul_f32 v[34:35], v[66:67], v[34:35]
	v_pk_fma_f32 v[32:33], v[192:193], v[32:33], v[208:209]
	v_pk_fma_f32 v[34:35], v[194:195], v[34:35], v[210:211]
	v_cvt_pk_bf16_f32 v244, v32, v33
	v_cvt_pk_bf16_f32 v245, v34, v35
	v_pk_mul_f32 v[36:37], v[36:37], v[236:237] op_sel_hi:[1,0]
	v_pk_mul_f32 v[38:39], v[38:39], v[236:237] op_sel_hi:[1,0]
	v_pk_mul_f32 v[36:37], v[68:69], v[36:37]
	v_pk_mul_f32 v[38:39], v[70:71], v[38:39]
	v_pk_fma_f32 v[36:37], v[196:197], v[36:37], v[212:213]
	v_pk_fma_f32 v[38:39], v[198:199], v[38:39], v[214:215]
	v_cvt_pk_bf16_f32 v246, v36, v37
	v_cvt_pk_bf16_f32 v247, v38, v39
	global_store_dwordx4 v82, v[244:247], s[46:47] offset:0
	v_pk_mul_f32 v[40:41], v[40:41], v[236:237] op_sel_hi:[1,0]
	v_pk_mul_f32 v[42:43], v[42:43], v[236:237] op_sel_hi:[1,0]
	v_pk_mul_f32 v[40:41], v[72:73], v[40:41]
	v_pk_mul_f32 v[42:43], v[74:75], v[42:43]
	v_pk_fma_f32 v[40:41], v[200:201], v[40:41], v[216:217]
	v_pk_fma_f32 v[42:43], v[202:203], v[42:43], v[218:219]
	v_cvt_pk_bf16_f32 v240, v40, v41
	v_cvt_pk_bf16_f32 v241, v42, v43
	v_pk_mul_f32 v[44:45], v[44:45], v[236:237] op_sel_hi:[1,0]
	v_pk_mul_f32 v[46:47], v[46:47], v[236:237] op_sel_hi:[1,0]
	v_pk_mul_f32 v[44:45], v[76:77], v[44:45]
	v_pk_mul_f32 v[46:47], v[78:79], v[46:47]
	v_pk_fma_f32 v[44:45], v[204:205], v[44:45], v[220:221]
	v_pk_fma_f32 v[46:47], v[206:207], v[46:47], v[222:223]
	v_cvt_pk_bf16_f32 v242, v44, v45
	v_cvt_pk_bf16_f32 v243, v46, v47
	global_store_dwordx4 v82, v[240:243], s[46:47] offset:1024
	v_pk_mul_f32 v[48:49], v[48:49], v[238:239] op_sel_hi:[1,0]
	v_pk_mul_f32 v[50:51], v[50:51], v[238:239] op_sel_hi:[1,0]
	v_pk_mul_f32 v[48:49], v[64:65], v[48:49]
	v_pk_mul_f32 v[50:51], v[66:67], v[50:51]
	v_pk_fma_f32 v[48:49], v[192:193], v[48:49], v[208:209]
	v_pk_fma_f32 v[50:51], v[194:195], v[50:51], v[210:211]
	v_cvt_pk_bf16_f32 v244, v48, v49
	v_cvt_pk_bf16_f32 v245, v50, v51
	v_pk_mul_f32 v[52:53], v[52:53], v[238:239] op_sel_hi:[1,0]
	v_pk_mul_f32 v[54:55], v[54:55], v[238:239] op_sel_hi:[1,0]
	v_pk_mul_f32 v[52:53], v[68:69], v[52:53]
	v_pk_mul_f32 v[54:55], v[70:71], v[54:55]
	v_pk_fma_f32 v[52:53], v[196:197], v[52:53], v[212:213]
	v_pk_fma_f32 v[54:55], v[198:199], v[54:55], v[214:215]
	v_cvt_pk_bf16_f32 v246, v52, v53
	v_cvt_pk_bf16_f32 v247, v54, v55
	global_store_dwordx4 v82, v[244:247], s[48:49] offset:0
	v_pk_mul_f32 v[56:57], v[56:57], v[238:239] op_sel_hi:[1,0]
	v_pk_mul_f32 v[58:59], v[58:59], v[238:239] op_sel_hi:[1,0]
	v_pk_mul_f32 v[56:57], v[72:73], v[56:57]
	v_pk_mul_f32 v[58:59], v[74:75], v[58:59]
	v_pk_fma_f32 v[56:57], v[200:201], v[56:57], v[216:217]
	v_pk_fma_f32 v[58:59], v[202:203], v[58:59], v[218:219]
	v_cvt_pk_bf16_f32 v240, v56, v57
	v_cvt_pk_bf16_f32 v241, v58, v59
	v_pk_mul_f32 v[60:61], v[60:61], v[238:239] op_sel_hi:[1,0]
	v_pk_mul_f32 v[62:63], v[62:63], v[238:239] op_sel_hi:[1,0]
	v_pk_mul_f32 v[60:61], v[76:77], v[60:61]
	v_pk_mul_f32 v[62:63], v[78:79], v[62:63]
	v_pk_fma_f32 v[60:61], v[204:205], v[60:61], v[220:221]
	v_pk_fma_f32 v[62:63], v[206:207], v[62:63], v[222:223]
	v_cvt_pk_bf16_f32 v242, v60, v61
	v_cvt_pk_bf16_f32 v243, v62, v63
	global_store_dwordx4 v82, v[240:243], s[48:49] offset:1024
	s_add_u32 s34, s8, 0x9000
	s_addc_u32 s35, s9, 0
	s_add_u32 s36, s8, 0x9000
	s_addc_u32 s37, s9, 0
	global_load_dwordx4 v[176:179], v80, s[34:35] offset:0
	global_load_dwordx4 v[180:183], v80, s[34:35] offset:16
	global_load_dwordx4 v[184:187], v80, s[34:35] offset:2048
	global_load_dwordx4 v[188:191], v80, s[34:35] offset:2064
	global_load_dwordx4 v[160:163], v81, s[34:35] offset:0
	global_load_dwordx4 v[164:167], v81, s[34:35] offset:16
	global_load_dwordx4 v[168:171], v81, s[34:35] offset:2048
	global_load_dwordx4 v[172:175], v81, s[34:35] offset:2064
	global_load_dwordx4 v[208:211], v80, s[36:37] offset:0
	global_load_dwordx4 v[212:215], v80, s[36:37] offset:16
	global_load_dwordx4 v[216:219], v80, s[36:37] offset:2048
	global_load_dwordx4 v[220:223], v80, s[36:37] offset:2064
	global_load_dwordx4 v[192:195], v81, s[36:37] offset:0
	global_load_dwordx4 v[196:199], v81, s[36:37] offset:16
	global_load_dwordx4 v[200:203], v81, s[36:37] offset:2048
	global_load_dwordx4 v[204:207], v81, s[36:37] offset:2064
	s_add_u32 s24, s16, 0x2000000
	s_addc_u32 s25, s17, 0
	s_add_u32 s26, s16, 0x2400000
	s_addc_u32 s27, s17, 0
	s_add_u32 s28, s16, 0x2800000
	s_addc_u32 s29, s17, 0
	s_add_u32 s30, s16, 0x2c00000
	s_addc_u32 s31, s17, 0
	global_load_dwordx4 v[96:99], v82, s[24:25] offset:0
	global_load_dwordx4 v[100:103], v82, s[24:25] offset:1024
	global_load_dwordx4 v[104:107], v82, s[26:27] offset:0
	global_load_dwordx4 v[108:111], v82, s[26:27] offset:1024
	global_load_dwordx4 v[112:115], v82, s[28:29] offset:0
	global_load_dwordx4 v[116:119], v82, s[28:29] offset:1024
	global_load_dwordx4 v[120:123], v82, s[30:31] offset:0
	global_load_dwordx4 v[124:127], v82, s[30:31] offset:1024
	s_waitcnt vmcnt(32)
; __device__ __forceinline__ float bf_lo(unsigned w) { return __uint_as_float(w << 16); }
; __device__ __forceinline__ float bf_hi(unsigned w) { return __uint_as_float(w & 0xffff0000u); }
; template <bool BF> __device__ __forceinline__ void prep_rows(const float* xp, const float* xs, const bf16* hb, const float* g, const float* MOD, int shoff, int scoff, bf16* U, int gw, int NGW, int lane) {
;     ...
;                 if (BF) { const v2u a0 = *(const v2u*)(hb + (size_t)mc * DM + 4 * lane + 256 * j);
;                     v[r][j].x = pg8::bf_lo(a0.x); v[r][j].y = pg8::bf_hi(a0.x); v[r][j].z = pg8::bf_lo(a0.y); v[r][j].w = pg8::bf_hi(a0.y); }
;                 else { const float* xr = mc < MP ? xp + (size_t)mc * DM : xs + (size_t)(mc - MP) * DM; v[r][j] = *(const f32x4*)(xr + 4 * lane + 256 * j); } } }
; #pragma unroll
;         for (int r = 0; r < R; ++r) { float t = 0.f;
; #pragma unroll
;             for (int j = 0; j < 4; ++j) t += (v[r][j].x * v[r][j].x + v[r][j].y * v[r][j].y) + (v[r][j].z * v[r][j].z + v[r][j].w * v[r][j].w);
;             s[r] = t; }
; #pragma unroll
;         for (int o = 1; o < 64; o <<= 1) {
; #pragma unroll
;             for (int r = 0; r < R; ++r) s[r] += __shfl_xor(s[r], o); }
; #pragma unroll
	v_lshlrev_b32_e32 v0, 16, v128
	v_and_b32_e32 v1, 0xffff0000, v128
	v_lshlrev_b32_e32 v2, 16, v129
	v_and_b32_e32 v3, 0xffff0000, v129
	v_lshlrev_b32_e32 v4, 16, v130
	v_and_b32_e32 v5, 0xffff0000, v130
	v_lshlrev_b32_e32 v6, 16, v131
	v_and_b32_e32 v7, 0xffff0000, v131
	v_lshlrev_b32_e32 v8, 16, v132
	v_and_b32_e32 v9, 0xffff0000, v132
	v_lshlrev_b32_e32 v10, 16, v133
	v_and_b32_e32 v11, 0xffff0000, v133
	v_lshlrev_b32_e32 v12, 16, v134
	v_and_b32_e32 v13, 0xffff0000, v134
	v_lshlrev_b32_e32 v14, 16, v135
	v_and_b32_e32 v15, 0xffff0000, v135
	v_lshlrev_b32_e32 v16, 16, v136
	v_and_b32_e32 v17, 0xffff0000, v136
	v_lshlrev_b32_e32 v18, 16, v137
	v_and_b32_e32 v19, 0xffff0000, v137
	v_lshlrev_b32_e32 v20, 16, v138
	v_and_b32_e32 v21, 0xffff0000, v138
	v_lshlrev_b32_e32 v22, 16, v139
	v_and_b32_e32 v23, 0xffff0000, v139
	v_lshlrev_b32_e32 v24, 16, v140
	v_and_b32_e32 v25, 0xffff0000, v140
	v_lshlrev_b32_e32 v26, 16, v141
	v_and_b32_e32 v27, 0xffff0000, v141
	v_lshlrev_b32_e32 v28, 16, v142
	v_and_b32_e32 v29, 0xffff0000, v142
	v_lshlrev_b32_e32 v30, 16, v143
	v_and_b32_e32 v31, 0xffff0000, v143
	v_lshlrev_b32_e32 v32, 16, v144
	v_and_b32_e32 v33, 0xffff0000, v144
	v_lshlrev_b32_e32 v34, 16, v145
	v_and_b32_e32 v35, 0xffff0000, v145
	v_lshlrev_b32_e32 v36, 16, v146
	v_and_b32_e32 v37, 0xffff0000, v146
	v_lshlrev_b32_e32 v38, 16, v147
	v_and_b32_e32 v39, 0xffff0000, v147
	v_lshlrev_b32_e32 v40, 16, v148
	v_and_b32_e32 v41, 0xffff0000, v148
	v_lshlrev_b32_e32 v42, 16, v149
	v_and_b32_e32 v43, 0xffff0000, v149
	v_lshlrev_b32_e32 v44, 16, v150
	v_and_b32_e32 v45, 0xffff0000, v150
	v_lshlrev_b32_e32 v46, 16, v151
	v_and_b32_e32 v47, 0xffff0000, v151
	v_lshlrev_b32_e32 v48, 16, v152
	v_and_b32_e32 v49, 0xffff0000, v152
	v_lshlrev_b32_e32 v50, 16, v153
	v_and_b32_e32 v51, 0xffff0000, v153
	v_lshlrev_b32_e32 v52, 16, v154
	v_and_b32_e32 v53, 0xffff0000, v154
	v_lshlrev_b32_e32 v54, 16, v155
	v_and_b32_e32 v55, 0xffff0000, v155
	v_lshlrev_b32_e32 v56, 16, v156
	v_and_b32_e32 v57, 0xffff0000, v156
	v_lshlrev_b32_e32 v58, 16, v157
	v_and_b32_e32 v59, 0xffff0000, v157
	v_lshlrev_b32_e32 v60, 16, v158
	v_and_b32_e32 v61, 0xffff0000, v158
	v_lshlrev_b32_e32 v62, 16, v159
	v_and_b32_e32 v63, 0xffff0000, v159
	v_pk_mul_f32 v[240:241], v[0:1], v[0:1]
	v_pk_mul_f32 v[242:243], v[16:17], v[16:17]
	v_pk_mul_f32 v[244:245], v[32:33], v[32:33]
	v_pk_mul_f32 v[246:247], v[48:49], v[48:49]
	v_pk_fma_f32 v[240:241], v[2:3], v[2:3], v[240:241]
	v_pk_fma_f32 v[242:243], v[18:19], v[18:19], v[242:243]
	v_pk_fma_f32 v[244:245], v[34:35], v[34:35], v[244:245]
	v_pk_fma_f32 v[246:247], v[50:51], v[50:51], v[246:247]
	v_pk_fma_f32 v[240:241], v[4:5], v[4:5], v[240:241]
	v_pk_fma_f32 v[242:243], v[20:21], v[20:21], v[242:243]
	v_pk_fma_f32 v[244:245], v[36:37], v[36:37], v[244:245]
	v_pk_fma_f32 v[246:247], v[52:53], v[52:53], v[246:247]
	v_pk_fma_f32 v[240:241], v[6:7], v[6:7], v[240:241]
	v_pk_fma_f32 v[242:243], v[22:23], v[22:23], v[242:243]
	v_pk_fma_f32 v[244:245], v[38:39], v[38:39], v[244:245]
	v_pk_fma_f32 v[246:247], v[54:55], v[54:55], v[246:247]
	v_pk_fma_f32 v[240:241], v[8:9], v[8:9], v[240:241]
	v_pk_fma_f32 v[242:243], v[24:25], v[24:25], v[242:243]
	v_pk_fma_f32 v[244:245], v[40:41], v[40:41], v[244:245]
	v_pk_fma_f32 v[246:247], v[56:57], v[56:57], v[246:247]
	v_pk_fma_f32 v[240:241], v[10:11], v[10:11], v[240:241]
	v_pk_fma_f32 v[242:243], v[26:27], v[26:27], v[242:243]
	v_pk_fma_f32 v[244:245], v[42:43], v[42:43], v[244:245]
	v_pk_fma_f32 v[246:247], v[58:59], v[58:59], v[246:247]
	v_pk_fma_f32 v[240:241], v[12:13], v[12:13], v[240:241]
	v_pk_fma_f32 v[242:243], v[28:29], v[28:29], v[242:243]
	v_pk_fma_f32 v[244:245], v[44:45], v[44:45], v[244:245]
	v_pk_fma_f32 v[246:247], v[60:61], v[60:61], v[246:247]
	v_pk_fma_f32 v[240:241], v[14:15], v[14:15], v[240:241]
	v_pk_fma_f32 v[242:243], v[30:31], v[30:31], v[242:243]
	v_pk_fma_f32 v[244:245], v[46:47], v[46:47], v[244:245]
	v_pk_fma_f32 v[246:247], v[62:63], v[62:63], v[246:247]
	v_add_f32_e32 v224, v240, v241
	v_add_f32_e32 v225, v242, v243
	v_add_f32_e32 v226, v244, v245
	v_add_f32_e32 v227, v246, v247
	ds_bpermute_b32 v228, v83, v224
	ds_bpermute_b32 v229, v83, v225
	ds_bpermute_b32 v230, v83, v226
	ds_bpermute_b32 v231, v83, v227
	s_waitcnt lgkmcnt(0)
	v_add_f32_e32 v224, v224, v228
	v_add_f32_e32 v225, v225, v229
	v_add_f32_e32 v226, v226, v230
	v_add_f32_e32 v227, v227, v231
	ds_bpermute_b32 v228, v84, v224
	ds_bpermute_b32 v229, v84, v225
	ds_bpermute_b32 v230, v84, v226
	ds_bpermute_b32 v231, v84, v227
	s_waitcnt lgkmcnt(0)
	v_add_f32_e32 v224, v224, v228
	v_add_f32_e32 v225, v225, v229
	v_add_f32_e32 v226, v226, v230
	v_add_f32_e32 v227, v227, v231
	ds_bpermute_b32 v228, v85, v224
	ds_bpermute_b32 v229, v85, v225
	ds_bpermute_b32 v230, v85, v226
	ds_bpermute_b32 v231, v85, v227
	s_waitcnt lgkmcnt(0)
	v_add_f32_e32 v224, v224, v228
	v_add_f32_e32 v225, v225, v229
	v_add_f32_e32 v226, v226, v230
	v_add_f32_e32 v227, v227, v231
	ds_bpermute_b32 v228, v86, v224
	ds_bpermute_b32 v229, v86, v225
	ds_bpermute_b32 v230, v86, v226
	ds_bpermute_b32 v231, v86, v227
	s_waitcnt lgkmcnt(0)
	v_add_f32_e32 v224, v224, v228
	v_add_f32_e32 v225, v225, v229
	v_add_f32_e32 v226, v226, v230
	v_add_f32_e32 v227, v227, v231
	ds_bpermute_b32 v228, v87, v224
	ds_bpermute_b32 v229, v87, v225
	ds_bpermute_b32 v230, v87, v226
	ds_bpermute_b32 v231, v87, v227
	s_waitcnt lgkmcnt(0)
	v_add_f32_e32 v224, v224, v228
	v_add_f32_e32 v225, v225, v229
	v_add_f32_e32 v226, v226, v230
	v_add_f32_e32 v227, v227, v231
	ds_bpermute_b32 v228, v88, v224
	ds_bpermute_b32 v229, v88, v225
	ds_bpermute_b32 v230, v88, v226
	ds_bpermute_b32 v231, v88, v227
	s_waitcnt lgkmcnt(0)
; template <bool BF> __device__ __forceinline__ void prep_rows(const float* xp, const float* xs, const bf16* hb, const float* g, const float* MOD, int shoff, int scoff, bf16* U, int gw, int NGW, int lane) {
;     ...
;             for (int r = 0; r < R; ++r) s[r] += __shfl_xor(s[r], o); }
; #pragma unroll
;         for (int r = 0; r < R; ++r) { const int m = mb + r * NGW; if (m < MT) {
;             const float rstd = 1.0f / sqrtf(s[r] * (1.0f / DM) + RMS_EPS);
	v_add_f32_e32 v224, v224, v228
	v_add_f32_e32 v225, v225, v229
	v_add_f32_e32 v226, v226, v230
	v_add_f32_e32 v227, v227, v231
	v_fmamk_f32 v240, v224, 0x3a800000, v89
	v_mul_f32_e32 v241, 0x4f800000, v240
	v_cmp_gt_f32_e32 vcc, s54, v240
	s_nop 1
	v_cndmask_b32_e32 v247, v240, v241, vcc
	v_sqrt_f32_e32 v242, v247
	s_nop 1
	v_add_u32_e32 v243, -1, v242
	v_add_u32_e32 v244, 1, v242
	v_fma_f32 v245, -v243, v242, v247
	v_fma_f32 v246, -v244, v242, v247
	v_cmp_ge_f32_e64 s[52:53], 0, v245
	s_nop 1
	v_cndmask_b32_e64 v242, v242, v243, s[52:53]
	v_cmp_lt_f32_e64 s[52:53], 0, v246
	s_nop 1
	v_cndmask_b32_e64 v242, v242, v244, s[52:53]
	v_mul_f32_e32 v243, 0x37800000, v242
	v_cndmask_b32_e32 v242, v242, v243, vcc
	v_cmp_class_f32_e32 vcc, v247, v90
	s_nop 1
	v_cndmask_b32_e32 v247, v242, v247, vcc
	v_div_scale_f32 v248, s[52:53], v247, v247, 1.0
	v_rcp_f32_e32 v249, v248
	v_div_scale_f32 v228, vcc, 1.0, v247, 1.0
	s_nop 0
	v_fma_f32 v229, -v248, v249, 1.0
	v_fmac_f32_e32 v249, v229, v249
	v_mul_f32_e32 v230, v228, v249
	v_fma_f32 v229, -v248, v230, v228
	v_fmac_f32_e32 v230, v229, v249
	v_fma_f32 v248, -v248, v230, v228
	v_div_fmas_f32 v248, v248, v249, v230
	v_div_fixup_f32 v232, v248, v247, 1.0
	v_fmamk_f32 v240, v225, 0x3a800000, v89
	v_mul_f32_e32 v241, 0x4f800000, v240
	v_cmp_gt_f32_e32 vcc, s54, v240
	s_nop 1
	v_cndmask_b32_e32 v247, v240, v241, vcc
	v_sqrt_f32_e32 v242, v247
	s_nop 1
	v_add_u32_e32 v243, -1, v242
	v_add_u32_e32 v244, 1, v242
	v_fma_f32 v245, -v243, v242, v247
	v_fma_f32 v246, -v244, v242, v247
	v_cmp_ge_f32_e64 s[52:53], 0, v245
	s_nop 1
	v_cndmask_b32_e64 v242, v242, v243, s[52:53]
	v_cmp_lt_f32_e64 s[52:53], 0, v246
	s_nop 1
	v_cndmask_b32_e64 v242, v242, v244, s[52:53]
	v_mul_f32_e32 v243, 0x37800000, v242
	v_cndmask_b32_e32 v242, v242, v243, vcc
	v_cmp_class_f32_e32 vcc, v247, v90
	s_nop 1
	v_cndmask_b32_e32 v247, v242, v247, vcc
	v_div_scale_f32 v248, s[52:53], v247, v247, 1.0
	v_rcp_f32_e32 v249, v248
	v_div_scale_f32 v228, vcc, 1.0, v247, 1.0
	s_nop 0
	v_fma_f32 v229, -v248, v249, 1.0
	v_fmac_f32_e32 v249, v229, v249
	v_mul_f32_e32 v230, v228, v249
	v_fma_f32 v229, -v248, v230, v228
	v_fmac_f32_e32 v230, v229, v249
	v_fma_f32 v248, -v248, v230, v228
	v_div_fmas_f32 v248, v248, v249, v230
	v_div_fixup_f32 v234, v248, v247, 1.0
	v_fmamk_f32 v240, v226, 0x3a800000, v89
	v_mul_f32_e32 v241, 0x4f800000, v240
	v_cmp_gt_f32_e32 vcc, s54, v240
	s_nop 1
	v_cndmask_b32_e32 v247, v240, v241, vcc
	v_sqrt_f32_e32 v242, v247
	s_nop 1
	v_add_u32_e32 v243, -1, v242
	v_add_u32_e32 v244, 1, v242
	v_fma_f32 v245, -v243, v242, v247
	v_fma_f32 v246, -v244, v242, v247
	v_cmp_ge_f32_e64 s[52:53], 0, v245
	s_nop 1
	v_cndmask_b32_e64 v242, v242, v243, s[52:53]
	v_cmp_lt_f32_e64 s[52:53], 0, v246
	s_nop 1
	v_cndmask_b32_e64 v242, v242, v244, s[52:53]
	v_mul_f32_e32 v243, 0x37800000, v242
	v_cndmask_b32_e32 v242, v242, v243, vcc
	v_cmp_class_f32_e32 vcc, v247, v90
	s_nop 1
	v_cndmask_b32_e32 v247, v242, v247, vcc
	v_div_scale_f32 v248, s[52:53], v247, v247, 1.0
	v_rcp_f32_e32 v249, v248
	v_div_scale_f32 v228, vcc, 1.0, v247, 1.0
	s_nop 0
	v_fma_f32 v229, -v248, v249, 1.0
	v_fmac_f32_e32 v249, v229, v249
	v_mul_f32_e32 v230, v228, v249
	v_fma_f32 v229, -v248, v230, v228
	v_fmac_f32_e32 v230, v229, v249
	v_fma_f32 v248, -v248, v230, v228
	v_div_fmas_f32 v248, v248, v249, v230
	v_div_fixup_f32 v236, v248, v247, 1.0
	v_fmamk_f32 v240, v227, 0x3a800000, v89
	v_mul_f32_e32 v241, 0x4f800000, v240
	v_cmp_gt_f32_e32 vcc, s54, v240
	s_nop 1
	v_cndmask_b32_e32 v247, v240, v241, vcc
	v_sqrt_f32_e32 v242, v247
	s_nop 1
	v_add_u32_e32 v243, -1, v242
	v_add_u32_e32 v244, 1, v242
	v_fma_f32 v245, -v243, v242, v247
	v_fma_f32 v246, -v244, v242, v247
	v_cmp_ge_f32_e64 s[52:53], 0, v245
	s_nop 1
	v_cndmask_b32_e64 v242, v242, v243, s[52:53]
	v_cmp_lt_f32_e64 s[52:53], 0, v246
	s_nop 1
	v_cndmask_b32_e64 v242, v242, v244, s[52:53]
	v_mul_f32_e32 v243, 0x37800000, v242
	v_cndmask_b32_e32 v242, v242, v243, vcc
	v_cmp_class_f32_e32 vcc, v247, v90
	s_nop 1
	v_cndmask_b32_e32 v247, v242, v247, vcc
	v_div_scale_f32 v248, s[52:53], v247, v247, 1.0
	v_rcp_f32_e32 v249, v248
	v_div_scale_f32 v228, vcc, 1.0, v247, 1.0
	s_nop 0
	v_fma_f32 v229, -v248, v249, 1.0
	v_fmac_f32_e32 v249, v229, v249
	v_mul_f32_e32 v230, v228, v249
	v_fma_f32 v229, -v248, v230, v228
	v_fmac_f32_e32 v230, v229, v249
	v_fma_f32 v248, -v248, v230, v228
	v_div_fmas_f32 v248, v248, v249, v230
	v_div_fixup_f32 v238, v248, v247, 1.0
	s_waitcnt vmcnt(8)
; __device__ __forceinline__ unsigned pk2(float lo, float hi) { return pg8::cvt_pk_bf16(lo, hi); }
; template <bool BF> __device__ __forceinline__ void prep_rows(const float* xp, const float* xs, const bf16* hb, const float* g, const float* MOD, int shoff, int scoff, bf16* U, int gw, int NGW, int lane) {
;     ...
;             const float* mr = MOD + (size_t)(m < MP ? (m >> 13) : 8 + ((m - MP) >> 12)) * 6144;
; #pragma unroll
;             for (int j = 0; j < 4; ++j) { const int c = 4 * lane + 256 * j;
;                 const f32x4 gg = *(const f32x4*)(g + c), sc = *(const f32x4*)(mr + scoff + c), sh = *(const f32x4*)(mr + shoff + c);
;                 const f32x4 o = v[r][j] * rstd * gg * (sc + 1.0f) + sh; v2u w; w.x = pk2(o.x, o.y); w.y = pk2(o.z, o.w); *(v2u*)(U + (size_t)m * DM + c) = w; } } }
	v_pk_add_f32 v[160:161], v[160:161], 1.0 op_sel_hi:[1,0]
	v_pk_add_f32 v[162:163], v[162:163], 1.0 op_sel_hi:[1,0]
	v_pk_add_f32 v[164:165], v[164:165], 1.0 op_sel_hi:[1,0]
	v_pk_add_f32 v[166:167], v[166:167], 1.0 op_sel_hi:[1,0]
	v_pk_add_f32 v[168:169], v[168:169], 1.0 op_sel_hi:[1,0]
	v_pk_add_f32 v[170:171], v[170:171], 1.0 op_sel_hi:[1,0]
	v_pk_add_f32 v[172:173], v[172:173], 1.0 op_sel_hi:[1,0]
	v_pk_add_f32 v[174:175], v[174:175], 1.0 op_sel_hi:[1,0]
	v_pk_add_f32 v[192:193], v[192:193], 1.0 op_sel_hi:[1,0]
	v_pk_add_f32 v[194:195], v[194:195], 1.0 op_sel_hi:[1,0]
	v_pk_add_f32 v[196:197], v[196:197], 1.0 op_sel_hi:[1,0]
	v_pk_add_f32 v[198:199], v[198:199], 1.0 op_sel_hi:[1,0]
	v_pk_add_f32 v[200:201], v[200:201], 1.0 op_sel_hi:[1,0]
	v_pk_add_f32 v[202:203], v[202:203], 1.0 op_sel_hi:[1,0]
	v_pk_add_f32 v[204:205], v[204:205], 1.0 op_sel_hi:[1,0]
	v_pk_add_f32 v[206:207], v[206:207], 1.0 op_sel_hi:[1,0]
	s_add_u32 s38, s20, 0x1000000
	s_addc_u32 s39, s21, 0
	s_add_u32 s40, s20, 0x1400000
	s_addc_u32 s41, s21, 0
	s_add_u32 s46, s20, 0x1800000
	s_addc_u32 s47, s21, 0
	s_add_u32 s48, s20, 0x1c00000
	s_addc_u32 s49, s21, 0
	v_pk_mul_f32 v[0:1], v[0:1], v[232:233] op_sel_hi:[1,0]
	v_pk_mul_f32 v[2:3], v[2:3], v[232:233] op_sel_hi:[1,0]
	v_pk_mul_f32 v[0:1], v[64:65], v[0:1]
	v_pk_mul_f32 v[2:3], v[66:67], v[2:3]
	v_pk_fma_f32 v[0:1], v[160:161], v[0:1], v[176:177]
	v_pk_fma_f32 v[2:3], v[162:163], v[2:3], v[178:179]
	v_cvt_pk_bf16_f32 v244, v0, v1
	v_cvt_pk_bf16_f32 v245, v2, v3
	v_pk_mul_f32 v[4:5], v[4:5], v[232:233] op_sel_hi:[1,0]
	v_pk_mul_f32 v[6:7], v[6:7], v[232:233] op_sel_hi:[1,0]
	v_pk_mul_f32 v[4:5], v[68:69], v[4:5]
	v_pk_mul_f32 v[6:7], v[70:71], v[6:7]
	v_pk_fma_f32 v[4:5], v[164:165], v[4:5], v[180:181]
	v_pk_fma_f32 v[6:7], v[166:167], v[6:7], v[182:183]
	v_cvt_pk_bf16_f32 v246, v4, v5
	v_cvt_pk_bf16_f32 v247, v6, v7
	global_store_dwordx4 v82, v[244:247], s[38:39] offset:0
	v_pk_mul_f32 v[8:9], v[8:9], v[232:233] op_sel_hi:[1,0]
	v_pk_mul_f32 v[10:11], v[10:11], v[232:233] op_sel_hi:[1,0]
	v_pk_mul_f32 v[8:9], v[72:73], v[8:9]
	v_pk_mul_f32 v[10:11], v[74:75], v[10:11]
	v_pk_fma_f32 v[8:9], v[168:169], v[8:9], v[184:185]
	v_pk_fma_f32 v[10:11], v[170:171], v[10:11], v[186:187]
	v_cvt_pk_bf16_f32 v240, v8, v9
	v_cvt_pk_bf16_f32 v241, v10, v11
	v_pk_mul_f32 v[12:13], v[12:13], v[232:233] op_sel_hi:[1,0]
	v_pk_mul_f32 v[14:15], v[14:15], v[232:233] op_sel_hi:[1,0]
	v_pk_mul_f32 v[12:13], v[76:77], v[12:13]
	v_pk_mul_f32 v[14:15], v[78:79], v[14:15]
	v_pk_fma_f32 v[12:13], v[172:173], v[12:13], v[188:189]
	v_pk_fma_f32 v[14:15], v[174:175], v[14:15], v[190:191]
	v_cvt_pk_bf16_f32 v242, v12, v13
	v_cvt_pk_bf16_f32 v243, v14, v15
	global_store_dwordx4 v82, v[240:243], s[38:39] offset:1024
	v_pk_mul_f32 v[16:17], v[16:17], v[234:235] op_sel_hi:[1,0]
	v_pk_mul_f32 v[18:19], v[18:19], v[234:235] op_sel_hi:[1,0]
	v_pk_mul_f32 v[16:17], v[64:65], v[16:17]
	v_pk_mul_f32 v[18:19], v[66:67], v[18:19]
	v_pk_fma_f32 v[16:17], v[160:161], v[16:17], v[176:177]
	v_pk_fma_f32 v[18:19], v[162:163], v[18:19], v[178:179]
	v_cvt_pk_bf16_f32 v244, v16, v17
	v_cvt_pk_bf16_f32 v245, v18, v19
	v_pk_mul_f32 v[20:21], v[20:21], v[234:235] op_sel_hi:[1,0]
	v_pk_mul_f32 v[22:23], v[22:23], v[234:235] op_sel_hi:[1,0]
	v_pk_mul_f32 v[20:21], v[68:69], v[20:21]
	v_pk_mul_f32 v[22:23], v[70:71], v[22:23]
	v_pk_fma_f32 v[20:21], v[164:165], v[20:21], v[180:181]
	v_pk_fma_f32 v[22:23], v[166:167], v[22:23], v[182:183]
	v_cvt_pk_bf16_f32 v246, v20, v21
	v_cvt_pk_bf16_f32 v247, v22, v23
	global_store_dwordx4 v82, v[244:247], s[40:41] offset:0
	v_pk_mul_f32 v[24:25], v[24:25], v[234:235] op_sel_hi:[1,0]
	v_pk_mul_f32 v[26:27], v[26:27], v[234:235] op_sel_hi:[1,0]
	v_pk_mul_f32 v[24:25], v[72:73], v[24:25]
	v_pk_mul_f32 v[26:27], v[74:75], v[26:27]
	v_pk_fma_f32 v[24:25], v[168:169], v[24:25], v[184:185]
	v_pk_fma_f32 v[26:27], v[170:171], v[26:27], v[186:187]
	v_cvt_pk_bf16_f32 v240, v24, v25
	v_cvt_pk_bf16_f32 v241, v26, v27
	v_pk_mul_f32 v[28:29], v[28:29], v[234:235] op_sel_hi:[1,0]
	v_pk_mul_f32 v[30:31], v[30:31], v[234:235] op_sel_hi:[1,0]
	v_pk_mul_f32 v[28:29], v[76:77], v[28:29]
	v_pk_mul_f32 v[30:31], v[78:79], v[30:31]
	v_pk_fma_f32 v[28:29], v[172:173], v[28:29], v[188:189]
	v_pk_fma_f32 v[30:31], v[174:175], v[30:31], v[190:191]
	v_cvt_pk_bf16_f32 v242, v28, v29
	v_cvt_pk_bf16_f32 v243, v30, v31
	global_store_dwordx4 v82, v[240:243], s[40:41] offset:1024
	v_pk_mul_f32 v[32:33], v[32:33], v[236:237] op_sel_hi:[1,0]
	v_pk_mul_f32 v[34:35], v[34:35], v[236:237] op_sel_hi:[1,0]
	v_pk_mul_f32 v[32:33], v[64:65], v[32:33]
	v_pk_mul_f32 v[34:35], v[66:67], v[34:35]
	v_pk_fma_f32 v[32:33], v[192:193], v[32:33], v[208:209]
	v_pk_fma_f32 v[34:35], v[194:195], v[34:35], v[210:211]
	v_cvt_pk_bf16_f32 v244, v32, v33
	v_cvt_pk_bf16_f32 v245, v34, v35
	v_pk_mul_f32 v[36:37], v[36:37], v[236:237] op_sel_hi:[1,0]
	v_pk_mul_f32 v[38:39], v[38:39], v[236:237] op_sel_hi:[1,0]
	v_pk_mul_f32 v[36:37], v[68:69], v[36:37]
	v_pk_mul_f32 v[38:39], v[70:71], v[38:39]
	v_pk_fma_f32 v[36:37], v[196:197], v[36:37], v[212:213]
	v_pk_fma_f32 v[38:39], v[198:199], v[38:39], v[214:215]
	v_cvt_pk_bf16_f32 v246, v36, v37
	v_cvt_pk_bf16_f32 v247, v38, v39
	global_store_dwordx4 v82, v[244:247], s[46:47] offset:0
	v_pk_mul_f32 v[40:41], v[40:41], v[236:237] op_sel_hi:[1,0]
	v_pk_mul_f32 v[42:43], v[42:43], v[236:237] op_sel_hi:[1,0]
	v_pk_mul_f32 v[40:41], v[72:73], v[40:41]
	v_pk_mul_f32 v[42:43], v[74:75], v[42:43]
	v_pk_fma_f32 v[40:41], v[200:201], v[40:41], v[216:217]
	v_pk_fma_f32 v[42:43], v[202:203], v[42:43], v[218:219]
	v_cvt_pk_bf16_f32 v240, v40, v41
; __device__ __forceinline__ float bf_lo(unsigned w) { return __uint_as_float(w << 16); }
; __device__ __forceinline__ float bf_hi(unsigned w) { return __uint_as_float(w & 0xffff0000u); }
; __device__ __forceinline__ unsigned pk2(float lo, float hi) { return pg8::cvt_pk_bf16(lo, hi); }
; template <bool BF> __device__ __forceinline__ void prep_rows(const float* xp, const float* xs, const bf16* hb, const float* g, const float* MOD, int shoff, int scoff, bf16* U, int gw, int NGW, int lane) {
;     ...
;         f32x4 v[R][4]; float s[R];
; #pragma unroll
;         for (int r = 0; r < R; ++r) { const int m = mb + r * NGW; const int mc = m < MT ? m : mb;
; #pragma unroll
;             for (int j = 0; j < 4; ++j) {
;                 if (BF) { const v2u a0 = *(const v2u*)(hb + (size_t)mc * DM + 4 * lane + 256 * j);
;                     v[r][j].x = pg8::bf_lo(a0.x); v[r][j].y = pg8::bf_hi(a0.x); v[r][j].z = pg8::bf_lo(a0.y); v[r][j].w = pg8::bf_hi(a0.y); }
;                 else { const float* xr = mc < MP ? xp + (size_t)mc * DM : xs + (size_t)(mc - MP) * DM; v[r][j] = *(const f32x4*)(xr + 4 * lane + 256 * j); } } }
; #pragma unroll
;         for (int r = 0; r < R; ++r) { float t = 0.f;
; #pragma unroll
;             for (int j = 0; j < 4; ++j) t += (v[r][j].x * v[r][j].x + v[r][j].y * v[r][j].y) + (v[r][j].z * v[r][j].z + v[r][j].w * v[r][j].w);
;     ...
; #pragma unroll
;             for (int j = 0; j < 4; ++j) { const int c = 4 * lane + 256 * j;
;                 const f32x4 gg = *(const f32x4*)(g + c), sc = *(const f32x4*)(mr + scoff + c), sh = *(const f32x4*)(mr + shoff + c);
;                 const f32x4 o = v[r][j] * rstd * gg * (sc + 1.0f) + sh; v2u w; w.x = pk2(o.x, o.y); w.y = pk2(o.z, o.w); *(v2u*)(U + (size_t)m * DM + c) = w; } } }
	v_cvt_pk_bf16_f32 v241, v42, v43
	v_pk_mul_f32 v[44:45], v[44:45], v[236:237] op_sel_hi:[1,0]
	v_pk_mul_f32 v[46:47], v[46:47], v[236:237] op_sel_hi:[1,0]
	v_pk_mul_f32 v[44:45], v[76:77], v[44:45]
	v_pk_mul_f32 v[46:47], v[78:79], v[46:47]
	v_pk_fma_f32 v[44:45], v[204:205], v[44:45], v[220:221]
	v_pk_fma_f32 v[46:47], v[206:207], v[46:47], v[222:223]
	v_cvt_pk_bf16_f32 v242, v44, v45
	v_cvt_pk_bf16_f32 v243, v46, v47
	global_store_dwordx4 v82, v[240:243], s[46:47] offset:1024
	v_pk_mul_f32 v[48:49], v[48:49], v[238:239] op_sel_hi:[1,0]
	v_pk_mul_f32 v[50:51], v[50:51], v[238:239] op_sel_hi:[1,0]
	v_pk_mul_f32 v[48:49], v[64:65], v[48:49]
	v_pk_mul_f32 v[50:51], v[66:67], v[50:51]
	v_pk_fma_f32 v[48:49], v[192:193], v[48:49], v[208:209]
	v_pk_fma_f32 v[50:51], v[194:195], v[50:51], v[210:211]
	v_cvt_pk_bf16_f32 v244, v48, v49
	v_cvt_pk_bf16_f32 v245, v50, v51
	v_pk_mul_f32 v[52:53], v[52:53], v[238:239] op_sel_hi:[1,0]
	v_pk_mul_f32 v[54:55], v[54:55], v[238:239] op_sel_hi:[1,0]
	v_pk_mul_f32 v[52:53], v[68:69], v[52:53]
	v_pk_mul_f32 v[54:55], v[70:71], v[54:55]
	v_pk_fma_f32 v[52:53], v[196:197], v[52:53], v[212:213]
	v_pk_fma_f32 v[54:55], v[198:199], v[54:55], v[214:215]
	v_cvt_pk_bf16_f32 v246, v52, v53
	v_cvt_pk_bf16_f32 v247, v54, v55
	global_store_dwordx4 v82, v[244:247], s[48:49] offset:0
	v_pk_mul_f32 v[56:57], v[56:57], v[238:239] op_sel_hi:[1,0]
	v_pk_mul_f32 v[58:59], v[58:59], v[238:239] op_sel_hi:[1,0]
	v_pk_mul_f32 v[56:57], v[72:73], v[56:57]
	v_pk_mul_f32 v[58:59], v[74:75], v[58:59]
	v_pk_fma_f32 v[56:57], v[200:201], v[56:57], v[216:217]
	v_pk_fma_f32 v[58:59], v[202:203], v[58:59], v[218:219]
	v_cvt_pk_bf16_f32 v240, v56, v57
	v_cvt_pk_bf16_f32 v241, v58, v59
	v_pk_mul_f32 v[60:61], v[60:61], v[238:239] op_sel_hi:[1,0]
	v_pk_mul_f32 v[62:63], v[62:63], v[238:239] op_sel_hi:[1,0]
	v_pk_mul_f32 v[60:61], v[76:77], v[60:61]
	v_pk_mul_f32 v[62:63], v[78:79], v[62:63]
	v_pk_fma_f32 v[60:61], v[204:205], v[60:61], v[220:221]
	v_pk_fma_f32 v[62:63], v[206:207], v[62:63], v[222:223]
	v_cvt_pk_bf16_f32 v242, v60, v61
	v_cvt_pk_bf16_f32 v243, v62, v63
	global_store_dwordx4 v82, v[240:243], s[48:49] offset:1024
	s_add_u32 s34, s8, 0xf000
	s_addc_u32 s35, s9, 0
	s_add_u32 s36, s8, 0xf000
	s_addc_u32 s37, s9, 0
	global_load_dwordx4 v[176:179], v80, s[34:35] offset:0
	global_load_dwordx4 v[180:183], v80, s[34:35] offset:16
	global_load_dwordx4 v[184:187], v80, s[34:35] offset:2048
	global_load_dwordx4 v[188:191], v80, s[34:35] offset:2064
	global_load_dwordx4 v[160:163], v81, s[34:35] offset:0
	global_load_dwordx4 v[164:167], v81, s[34:35] offset:16
	global_load_dwordx4 v[168:171], v81, s[34:35] offset:2048
	global_load_dwordx4 v[172:175], v81, s[34:35] offset:2064
	global_load_dwordx4 v[208:211], v80, s[36:37] offset:0
	global_load_dwordx4 v[212:215], v80, s[36:37] offset:16
	global_load_dwordx4 v[216:219], v80, s[36:37] offset:2048
	global_load_dwordx4 v[220:223], v80, s[36:37] offset:2064
	global_load_dwordx4 v[192:195], v81, s[36:37] offset:0
	global_load_dwordx4 v[196:199], v81, s[36:37] offset:16
	global_load_dwordx4 v[200:203], v81, s[36:37] offset:2048
	global_load_dwordx4 v[204:207], v81, s[36:37] offset:2064
	s_add_u32 s24, s16, 0x3000000
	s_addc_u32 s25, s17, 0
	s_add_u32 s26, s16, 0x3400000
	s_addc_u32 s27, s17, 0
	s_add_u32 s28, s16, 0x3800000
	s_addc_u32 s29, s17, 0
	s_add_u32 s30, s16, 0x3c00000
	s_addc_u32 s31, s17, 0
	global_load_dwordx4 v[128:131], v82, s[24:25] offset:0
	global_load_dwordx4 v[132:135], v82, s[24:25] offset:1024
	global_load_dwordx4 v[136:139], v82, s[26:27] offset:0
	global_load_dwordx4 v[140:143], v82, s[26:27] offset:1024
	global_load_dwordx4 v[144:147], v82, s[28:29] offset:0
	global_load_dwordx4 v[148:151], v82, s[28:29] offset:1024
	global_load_dwordx4 v[152:155], v82, s[30:31] offset:0
	global_load_dwordx4 v[156:159], v82, s[30:31] offset:1024
	s_waitcnt vmcnt(32)
	v_lshlrev_b32_e32 v0, 16, v96
	v_and_b32_e32 v1, 0xffff0000, v96
	v_lshlrev_b32_e32 v2, 16, v97
	v_and_b32_e32 v3, 0xffff0000, v97
	v_lshlrev_b32_e32 v4, 16, v98
	v_and_b32_e32 v5, 0xffff0000, v98
	v_lshlrev_b32_e32 v6, 16, v99
	v_and_b32_e32 v7, 0xffff0000, v99
	v_lshlrev_b32_e32 v8, 16, v100
	v_and_b32_e32 v9, 0xffff0000, v100
	v_lshlrev_b32_e32 v10, 16, v101
	v_and_b32_e32 v11, 0xffff0000, v101
	v_lshlrev_b32_e32 v12, 16, v102
	v_and_b32_e32 v13, 0xffff0000, v102
	v_lshlrev_b32_e32 v14, 16, v103
	v_and_b32_e32 v15, 0xffff0000, v103
	v_lshlrev_b32_e32 v16, 16, v104
	v_and_b32_e32 v17, 0xffff0000, v104
	v_lshlrev_b32_e32 v18, 16, v105
	v_and_b32_e32 v19, 0xffff0000, v105
	v_lshlrev_b32_e32 v20, 16, v106
	v_and_b32_e32 v21, 0xffff0000, v106
	v_lshlrev_b32_e32 v22, 16, v107
	v_and_b32_e32 v23, 0xffff0000, v107
	v_lshlrev_b32_e32 v24, 16, v108
	v_and_b32_e32 v25, 0xffff0000, v108
	v_lshlrev_b32_e32 v26, 16, v109
	v_and_b32_e32 v27, 0xffff0000, v109
	v_lshlrev_b32_e32 v28, 16, v110
	v_and_b32_e32 v29, 0xffff0000, v110
	v_lshlrev_b32_e32 v30, 16, v111
	v_and_b32_e32 v31, 0xffff0000, v111
	v_lshlrev_b32_e32 v32, 16, v112
	v_and_b32_e32 v33, 0xffff0000, v112
	v_lshlrev_b32_e32 v34, 16, v113
	v_and_b32_e32 v35, 0xffff0000, v113
	v_lshlrev_b32_e32 v36, 16, v114
	v_and_b32_e32 v37, 0xffff0000, v114
	v_lshlrev_b32_e32 v38, 16, v115
	v_and_b32_e32 v39, 0xffff0000, v115
	v_lshlrev_b32_e32 v40, 16, v116
	v_and_b32_e32 v41, 0xffff0000, v116
	v_lshlrev_b32_e32 v42, 16, v117
	v_and_b32_e32 v43, 0xffff0000, v117
	v_lshlrev_b32_e32 v44, 16, v118
	v_and_b32_e32 v45, 0xffff0000, v118
	v_lshlrev_b32_e32 v46, 16, v119
	v_and_b32_e32 v47, 0xffff0000, v119
	v_lshlrev_b32_e32 v48, 16, v120
	v_and_b32_e32 v49, 0xffff0000, v120
	v_lshlrev_b32_e32 v50, 16, v121
; __device__ __forceinline__ float bf_lo(unsigned w) { return __uint_as_float(w << 16); }
; __device__ __forceinline__ float bf_hi(unsigned w) { return __uint_as_float(w & 0xffff0000u); }
; template <bool BF> __device__ __forceinline__ void prep_rows(const float* xp, const float* xs, const bf16* hb, const float* g, const float* MOD, int shoff, int scoff, bf16* U, int gw, int NGW, int lane) {
;     ...
;                     v[r][j].x = pg8::bf_lo(a0.x); v[r][j].y = pg8::bf_hi(a0.x); v[r][j].z = pg8::bf_lo(a0.y); v[r][j].w = pg8::bf_hi(a0.y); }
;                 else { const float* xr = mc < MP ? xp + (size_t)mc * DM : xs + (size_t)(mc - MP) * DM; v[r][j] = *(const f32x4*)(xr + 4 * lane + 256 * j); } } }
; #pragma unroll
;         for (int r = 0; r < R; ++r) { float t = 0.f;
; #pragma unroll
;             for (int j = 0; j < 4; ++j) t += (v[r][j].x * v[r][j].x + v[r][j].y * v[r][j].y) + (v[r][j].z * v[r][j].z + v[r][j].w * v[r][j].w);
;             s[r] = t; }
; #pragma unroll
;         for (int o = 1; o < 64; o <<= 1) {
; #pragma unroll
;             for (int r = 0; r < R; ++r) s[r] += __shfl_xor(s[r], o); }
; #pragma unroll
;         for (int r = 0; r < R; ++r) { const int m = mb + r * NGW; if (m < MT) {
;             const float rstd = 1.0f / sqrtf(s[r] * (1.0f / DM) + RMS_EPS);
	v_and_b32_e32 v51, 0xffff0000, v121
	v_lshlrev_b32_e32 v52, 16, v122
	v_and_b32_e32 v53, 0xffff0000, v122
	v_lshlrev_b32_e32 v54, 16, v123
	v_and_b32_e32 v55, 0xffff0000, v123
	v_lshlrev_b32_e32 v56, 16, v124
	v_and_b32_e32 v57, 0xffff0000, v124
	v_lshlrev_b32_e32 v58, 16, v125
	v_and_b32_e32 v59, 0xffff0000, v125
	v_lshlrev_b32_e32 v60, 16, v126
	v_and_b32_e32 v61, 0xffff0000, v126
	v_lshlrev_b32_e32 v62, 16, v127
	v_and_b32_e32 v63, 0xffff0000, v127
	v_pk_mul_f32 v[240:241], v[0:1], v[0:1]
	v_pk_mul_f32 v[242:243], v[16:17], v[16:17]
	v_pk_mul_f32 v[244:245], v[32:33], v[32:33]
	v_pk_mul_f32 v[246:247], v[48:49], v[48:49]
	v_pk_fma_f32 v[240:241], v[2:3], v[2:3], v[240:241]
	v_pk_fma_f32 v[242:243], v[18:19], v[18:19], v[242:243]
	v_pk_fma_f32 v[244:245], v[34:35], v[34:35], v[244:245]
	v_pk_fma_f32 v[246:247], v[50:51], v[50:51], v[246:247]
	v_pk_fma_f32 v[240:241], v[4:5], v[4:5], v[240:241]
	v_pk_fma_f32 v[242:243], v[20:21], v[20:21], v[242:243]
	v_pk_fma_f32 v[244:245], v[36:37], v[36:37], v[244:245]
	v_pk_fma_f32 v[246:247], v[52:53], v[52:53], v[246:247]
	v_pk_fma_f32 v[240:241], v[6:7], v[6:7], v[240:241]
	v_pk_fma_f32 v[242:243], v[22:23], v[22:23], v[242:243]
	v_pk_fma_f32 v[244:245], v[38:39], v[38:39], v[244:245]
	v_pk_fma_f32 v[246:247], v[54:55], v[54:55], v[246:247]
	v_pk_fma_f32 v[240:241], v[8:9], v[8:9], v[240:241]
	v_pk_fma_f32 v[242:243], v[24:25], v[24:25], v[242:243]
	v_pk_fma_f32 v[244:245], v[40:41], v[40:41], v[244:245]
	v_pk_fma_f32 v[246:247], v[56:57], v[56:57], v[246:247]
	v_pk_fma_f32 v[240:241], v[10:11], v[10:11], v[240:241]
	v_pk_fma_f32 v[242:243], v[26:27], v[26:27], v[242:243]
	v_pk_fma_f32 v[244:245], v[42:43], v[42:43], v[244:245]
	v_pk_fma_f32 v[246:247], v[58:59], v[58:59], v[246:247]
	v_pk_fma_f32 v[240:241], v[12:13], v[12:13], v[240:241]
	v_pk_fma_f32 v[242:243], v[28:29], v[28:29], v[242:243]
	v_pk_fma_f32 v[244:245], v[44:45], v[44:45], v[244:245]
	v_pk_fma_f32 v[246:247], v[60:61], v[60:61], v[246:247]
	v_pk_fma_f32 v[240:241], v[14:15], v[14:15], v[240:241]
	v_pk_fma_f32 v[242:243], v[30:31], v[30:31], v[242:243]
	v_pk_fma_f32 v[244:245], v[46:47], v[46:47], v[244:245]
	v_pk_fma_f32 v[246:247], v[62:63], v[62:63], v[246:247]
	v_add_f32_e32 v224, v240, v241
	v_add_f32_e32 v225, v242, v243
	v_add_f32_e32 v226, v244, v245
	v_add_f32_e32 v227, v246, v247
	ds_bpermute_b32 v228, v83, v224
	ds_bpermute_b32 v229, v83, v225
	ds_bpermute_b32 v230, v83, v226
	ds_bpermute_b32 v231, v83, v227
	s_waitcnt lgkmcnt(0)
	v_add_f32_e32 v224, v224, v228
	v_add_f32_e32 v225, v225, v229
	v_add_f32_e32 v226, v226, v230
	v_add_f32_e32 v227, v227, v231
	ds_bpermute_b32 v228, v84, v224
	ds_bpermute_b32 v229, v84, v225
	ds_bpermute_b32 v230, v84, v226
	ds_bpermute_b32 v231, v84, v227
	s_waitcnt lgkmcnt(0)
	v_add_f32_e32 v224, v224, v228
	v_add_f32_e32 v225, v225, v229
	v_add_f32_e32 v226, v226, v230
	v_add_f32_e32 v227, v227, v231
	ds_bpermute_b32 v228, v85, v224
	ds_bpermute_b32 v229, v85, v225
	ds_bpermute_b32 v230, v85, v226
	ds_bpermute_b32 v231, v85, v227
	s_waitcnt lgkmcnt(0)
	v_add_f32_e32 v224, v224, v228
	v_add_f32_e32 v225, v225, v229
	v_add_f32_e32 v226, v226, v230
	v_add_f32_e32 v227, v227, v231
	ds_bpermute_b32 v228, v86, v224
	ds_bpermute_b32 v229, v86, v225
	ds_bpermute_b32 v230, v86, v226
	ds_bpermute_b32 v231, v86, v227
	s_waitcnt lgkmcnt(0)
	v_add_f32_e32 v224, v224, v228
	v_add_f32_e32 v225, v225, v229
	v_add_f32_e32 v226, v226, v230
	v_add_f32_e32 v227, v227, v231
	ds_bpermute_b32 v228, v87, v224
	ds_bpermute_b32 v229, v87, v225
	ds_bpermute_b32 v230, v87, v226
	ds_bpermute_b32 v231, v87, v227
	s_waitcnt lgkmcnt(0)
	v_add_f32_e32 v224, v224, v228
	v_add_f32_e32 v225, v225, v229
	v_add_f32_e32 v226, v226, v230
	v_add_f32_e32 v227, v227, v231
	ds_bpermute_b32 v228, v88, v224
	ds_bpermute_b32 v229, v88, v225
	ds_bpermute_b32 v230, v88, v226
	ds_bpermute_b32 v231, v88, v227
	s_waitcnt lgkmcnt(0)
	v_add_f32_e32 v224, v224, v228
	v_add_f32_e32 v225, v225, v229
	v_add_f32_e32 v226, v226, v230
	v_add_f32_e32 v227, v227, v231
	v_fmamk_f32 v240, v224, 0x3a800000, v89
	v_mul_f32_e32 v241, 0x4f800000, v240
	v_cmp_gt_f32_e32 vcc, s54, v240
	s_nop 1
	v_cndmask_b32_e32 v247, v240, v241, vcc
	v_sqrt_f32_e32 v242, v247
	s_nop 1
	v_add_u32_e32 v243, -1, v242
	v_add_u32_e32 v244, 1, v242
	v_fma_f32 v245, -v243, v242, v247
	v_fma_f32 v246, -v244, v242, v247
	v_cmp_ge_f32_e64 s[52:53], 0, v245
	s_nop 1
	v_cndmask_b32_e64 v242, v242, v243, s[52:53]
	v_cmp_lt_f32_e64 s[52:53], 0, v246
	s_nop 1
	v_cndmask_b32_e64 v242, v242, v244, s[52:53]
	v_mul_f32_e32 v243, 0x37800000, v242
	v_cndmask_b32_e32 v242, v242, v243, vcc
	v_cmp_class_f32_e32 vcc, v247, v90
	s_nop 1
	v_cndmask_b32_e32 v247, v242, v247, vcc
	v_div_scale_f32 v248, s[52:53], v247, v247, 1.0
	v_rcp_f32_e32 v249, v248
	v_div_scale_f32 v228, vcc, 1.0, v247, 1.0
	s_nop 0
	v_fma_f32 v229, -v248, v249, 1.0
	v_fmac_f32_e32 v249, v229, v249
	v_mul_f32_e32 v230, v228, v249
	v_fma_f32 v229, -v248, v230, v228
	v_fmac_f32_e32 v230, v229, v249
	v_fma_f32 v248, -v248, v230, v228
	v_div_fmas_f32 v248, v248, v249, v230
	v_div_fixup_f32 v232, v248, v247, 1.0
	v_fmamk_f32 v240, v225, 0x3a800000, v89
	v_mul_f32_e32 v241, 0x4f800000, v240
	v_cmp_gt_f32_e32 vcc, s54, v240
	s_nop 1
	v_cndmask_b32_e32 v247, v240, v241, vcc
	v_sqrt_f32_e32 v242, v247
	s_nop 1
	v_add_u32_e32 v243, -1, v242
	v_add_u32_e32 v244, 1, v242
	v_fma_f32 v245, -v243, v242, v247
	v_fma_f32 v246, -v244, v242, v247
	v_cmp_ge_f32_e64 s[52:53], 0, v245
	s_nop 1
	v_cndmask_b32_e64 v242, v242, v243, s[52:53]
	v_cmp_lt_f32_e64 s[52:53], 0, v246
	s_nop 1
	v_cndmask_b32_e64 v242, v242, v244, s[52:53]
; __device__ __forceinline__ unsigned pk2(float lo, float hi) { return pg8::cvt_pk_bf16(lo, hi); }
; template <bool BF> __device__ __forceinline__ void prep_rows(const float* xp, const float* xs, const bf16* hb, const float* g, const float* MOD, int shoff, int scoff, bf16* U, int gw, int NGW, int lane) {
;     ...
;             const float rstd = 1.0f / sqrtf(s[r] * (1.0f / DM) + RMS_EPS);
;             const float* mr = MOD + (size_t)(m < MP ? (m >> 13) : 8 + ((m - MP) >> 12)) * 6144;
; #pragma unroll
;             for (int j = 0; j < 4; ++j) { const int c = 4 * lane + 256 * j;
;                 const f32x4 gg = *(const f32x4*)(g + c), sc = *(const f32x4*)(mr + scoff + c), sh = *(const f32x4*)(mr + shoff + c);
;                 const f32x4 o = v[r][j] * rstd * gg * (sc + 1.0f) + sh; v2u w; w.x = pk2(o.x, o.y); w.y = pk2(o.z, o.w); *(v2u*)(U + (size_t)m * DM + c) = w; } } }
	v_mul_f32_e32 v243, 0x37800000, v242
	v_cndmask_b32_e32 v242, v242, v243, vcc
	v_cmp_class_f32_e32 vcc, v247, v90
	s_nop 1
	v_cndmask_b32_e32 v247, v242, v247, vcc
	v_div_scale_f32 v248, s[52:53], v247, v247, 1.0
	v_rcp_f32_e32 v249, v248
	v_div_scale_f32 v228, vcc, 1.0, v247, 1.0
	s_nop 0
	v_fma_f32 v229, -v248, v249, 1.0
	v_fmac_f32_e32 v249, v229, v249
	v_mul_f32_e32 v230, v228, v249
	v_fma_f32 v229, -v248, v230, v228
	v_fmac_f32_e32 v230, v229, v249
	v_fma_f32 v248, -v248, v230, v228
	v_div_fmas_f32 v248, v248, v249, v230
	v_div_fixup_f32 v234, v248, v247, 1.0
	v_fmamk_f32 v240, v226, 0x3a800000, v89
	v_mul_f32_e32 v241, 0x4f800000, v240
	v_cmp_gt_f32_e32 vcc, s54, v240
	s_nop 1
	v_cndmask_b32_e32 v247, v240, v241, vcc
	v_sqrt_f32_e32 v242, v247
	s_nop 1
	v_add_u32_e32 v243, -1, v242
	v_add_u32_e32 v244, 1, v242
	v_fma_f32 v245, -v243, v242, v247
	v_fma_f32 v246, -v244, v242, v247
	v_cmp_ge_f32_e64 s[52:53], 0, v245
	s_nop 1
	v_cndmask_b32_e64 v242, v242, v243, s[52:53]
	v_cmp_lt_f32_e64 s[52:53], 0, v246
	s_nop 1
	v_cndmask_b32_e64 v242, v242, v244, s[52:53]
	v_mul_f32_e32 v243, 0x37800000, v242
	v_cndmask_b32_e32 v242, v242, v243, vcc
	v_cmp_class_f32_e32 vcc, v247, v90
	s_nop 1
	v_cndmask_b32_e32 v247, v242, v247, vcc
	v_div_scale_f32 v248, s[52:53], v247, v247, 1.0
	v_rcp_f32_e32 v249, v248
	v_div_scale_f32 v228, vcc, 1.0, v247, 1.0
	s_nop 0
	v_fma_f32 v229, -v248, v249, 1.0
	v_fmac_f32_e32 v249, v229, v249
	v_mul_f32_e32 v230, v228, v249
	v_fma_f32 v229, -v248, v230, v228
	v_fmac_f32_e32 v230, v229, v249
	v_fma_f32 v248, -v248, v230, v228
	v_div_fmas_f32 v248, v248, v249, v230
	v_div_fixup_f32 v236, v248, v247, 1.0
	v_fmamk_f32 v240, v227, 0x3a800000, v89
	v_mul_f32_e32 v241, 0x4f800000, v240
	v_cmp_gt_f32_e32 vcc, s54, v240
	s_nop 1
	v_cndmask_b32_e32 v247, v240, v241, vcc
	v_sqrt_f32_e32 v242, v247
	s_nop 1
	v_add_u32_e32 v243, -1, v242
	v_add_u32_e32 v244, 1, v242
	v_fma_f32 v245, -v243, v242, v247
	v_fma_f32 v246, -v244, v242, v247
	v_cmp_ge_f32_e64 s[52:53], 0, v245
	s_nop 1
	v_cndmask_b32_e64 v242, v242, v243, s[52:53]
	v_cmp_lt_f32_e64 s[52:53], 0, v246
	s_nop 1
	v_cndmask_b32_e64 v242, v242, v244, s[52:53]
	v_mul_f32_e32 v243, 0x37800000, v242
	v_cndmask_b32_e32 v242, v242, v243, vcc
	v_cmp_class_f32_e32 vcc, v247, v90
	s_nop 1
	v_cndmask_b32_e32 v247, v242, v247, vcc
	v_div_scale_f32 v248, s[52:53], v247, v247, 1.0
	v_rcp_f32_e32 v249, v248
	v_div_scale_f32 v228, vcc, 1.0, v247, 1.0
	s_nop 0
	v_fma_f32 v229, -v248, v249, 1.0
	v_fmac_f32_e32 v249, v229, v249
	v_mul_f32_e32 v230, v228, v249
	v_fma_f32 v229, -v248, v230, v228
	v_fmac_f32_e32 v230, v229, v249
	v_fma_f32 v248, -v248, v230, v228
	v_div_fmas_f32 v248, v248, v249, v230
	v_div_fixup_f32 v238, v248, v247, 1.0
	s_waitcnt vmcnt(8)
	v_pk_add_f32 v[160:161], v[160:161], 1.0 op_sel_hi:[1,0]
	v_pk_add_f32 v[162:163], v[162:163], 1.0 op_sel_hi:[1,0]
	v_pk_add_f32 v[164:165], v[164:165], 1.0 op_sel_hi:[1,0]
	v_pk_add_f32 v[166:167], v[166:167], 1.0 op_sel_hi:[1,0]
	v_pk_add_f32 v[168:169], v[168:169], 1.0 op_sel_hi:[1,0]
	v_pk_add_f32 v[170:171], v[170:171], 1.0 op_sel_hi:[1,0]
	v_pk_add_f32 v[172:173], v[172:173], 1.0 op_sel_hi:[1,0]
	v_pk_add_f32 v[174:175], v[174:175], 1.0 op_sel_hi:[1,0]
	v_pk_add_f32 v[192:193], v[192:193], 1.0 op_sel_hi:[1,0]
	v_pk_add_f32 v[194:195], v[194:195], 1.0 op_sel_hi:[1,0]
	v_pk_add_f32 v[196:197], v[196:197], 1.0 op_sel_hi:[1,0]
	v_pk_add_f32 v[198:199], v[198:199], 1.0 op_sel_hi:[1,0]
	v_pk_add_f32 v[200:201], v[200:201], 1.0 op_sel_hi:[1,0]
	v_pk_add_f32 v[202:203], v[202:203], 1.0 op_sel_hi:[1,0]
	v_pk_add_f32 v[204:205], v[204:205], 1.0 op_sel_hi:[1,0]
	v_pk_add_f32 v[206:207], v[206:207], 1.0 op_sel_hi:[1,0]
	s_add_u32 s38, s20, 0x2000000
	s_addc_u32 s39, s21, 0
	s_add_u32 s40, s20, 0x2400000
	s_addc_u32 s41, s21, 0
	s_add_u32 s46, s20, 0x2800000
	s_addc_u32 s47, s21, 0
	s_add_u32 s48, s20, 0x2c00000
	s_addc_u32 s49, s21, 0
	v_pk_mul_f32 v[0:1], v[0:1], v[232:233] op_sel_hi:[1,0]
	v_pk_mul_f32 v[2:3], v[2:3], v[232:233] op_sel_hi:[1,0]
	v_pk_mul_f32 v[0:1], v[64:65], v[0:1]
	v_pk_mul_f32 v[2:3], v[66:67], v[2:3]
	v_pk_fma_f32 v[0:1], v[160:161], v[0:1], v[176:177]
	v_pk_fma_f32 v[2:3], v[162:163], v[2:3], v[178:179]
	v_cvt_pk_bf16_f32 v244, v0, v1
	v_cvt_pk_bf16_f32 v245, v2, v3
	v_pk_mul_f32 v[4:5], v[4:5], v[232:233] op_sel_hi:[1,0]
	v_pk_mul_f32 v[6:7], v[6:7], v[232:233] op_sel_hi:[1,0]
	v_pk_mul_f32 v[4:5], v[68:69], v[4:5]
	v_pk_mul_f32 v[6:7], v[70:71], v[6:7]
	v_pk_fma_f32 v[4:5], v[164:165], v[4:5], v[180:181]
	v_pk_fma_f32 v[6:7], v[166:167], v[6:7], v[182:183]
	v_cvt_pk_bf16_f32 v246, v4, v5
	v_cvt_pk_bf16_f32 v247, v6, v7
	global_store_dwordx4 v82, v[244:247], s[38:39] offset:0
	v_pk_mul_f32 v[8:9], v[8:9], v[232:233] op_sel_hi:[1,0]
	v_pk_mul_f32 v[10:11], v[10:11], v[232:233] op_sel_hi:[1,0]
	v_pk_mul_f32 v[8:9], v[72:73], v[8:9]
	v_pk_mul_f32 v[10:11], v[74:75], v[10:11]
	v_pk_fma_f32 v[8:9], v[168:169], v[8:9], v[184:185]
	v_pk_fma_f32 v[10:11], v[170:171], v[10:11], v[186:187]
	v_cvt_pk_bf16_f32 v240, v8, v9
	v_cvt_pk_bf16_f32 v241, v10, v11
	v_pk_mul_f32 v[12:13], v[12:13], v[232:233] op_sel_hi:[1,0]
	v_pk_mul_f32 v[14:15], v[14:15], v[232:233] op_sel_hi:[1,0]
	v_pk_mul_f32 v[12:13], v[76:77], v[12:13]
	v_pk_mul_f32 v[14:15], v[78:79], v[14:15]
	v_pk_fma_f32 v[12:13], v[172:173], v[12:13], v[188:189]
	v_pk_fma_f32 v[14:15], v[174:175], v[14:15], v[190:191]
	v_cvt_pk_bf16_f32 v242, v12, v13
	v_cvt_pk_bf16_f32 v243, v14, v15
	global_store_dwordx4 v82, v[240:243], s[38:39] offset:1024
	v_pk_mul_f32 v[16:17], v[16:17], v[234:235] op_sel_hi:[1,0]
	v_pk_mul_f32 v[18:19], v[18:19], v[234:235] op_sel_hi:[1,0]
; __device__ __forceinline__ float bf_lo(unsigned w) { return __uint_as_float(w << 16); }
; __device__ __forceinline__ float bf_hi(unsigned w) { return __uint_as_float(w & 0xffff0000u); }
; __device__ __forceinline__ unsigned pk2(float lo, float hi) { return pg8::cvt_pk_bf16(lo, hi); }
; template <bool BF> __device__ __forceinline__ void prep_rows(const float* xp, const float* xs, const bf16* hb, const float* g, const float* MOD, int shoff, int scoff, bf16* U, int gw, int NGW, int lane) {
;     ...
;         f32x4 v[R][4]; float s[R];
; #pragma unroll
;         for (int r = 0; r < R; ++r) { const int m = mb + r * NGW; const int mc = m < MT ? m : mb;
; #pragma unroll
;             for (int j = 0; j < 4; ++j) {
;                 if (BF) { const v2u a0 = *(const v2u*)(hb + (size_t)mc * DM + 4 * lane + 256 * j);
;                     v[r][j].x = pg8::bf_lo(a0.x); v[r][j].y = pg8::bf_hi(a0.x); v[r][j].z = pg8::bf_lo(a0.y); v[r][j].w = pg8::bf_hi(a0.y); }
;                 else { const float* xr = mc < MP ? xp + (size_t)mc * DM : xs + (size_t)(mc - MP) * DM; v[r][j] = *(const f32x4*)(xr + 4 * lane + 256 * j); } } }
;     ...
;             const float* mr = MOD + (size_t)(m < MP ? (m >> 13) : 8 + ((m - MP) >> 12)) * 6144;
; #pragma unroll
;             for (int j = 0; j < 4; ++j) { const int c = 4 * lane + 256 * j;
;                 const f32x4 gg = *(const f32x4*)(g + c), sc = *(const f32x4*)(mr + scoff + c), sh = *(const f32x4*)(mr + shoff + c);
;                 const f32x4 o = v[r][j] * rstd * gg * (sc + 1.0f) + sh; v2u w; w.x = pk2(o.x, o.y); w.y = pk2(o.z, o.w); *(v2u*)(U + (size_t)m * DM + c) = w; } } }
	v_pk_mul_f32 v[16:17], v[64:65], v[16:17]
	v_pk_mul_f32 v[18:19], v[66:67], v[18:19]
	v_pk_fma_f32 v[16:17], v[160:161], v[16:17], v[176:177]
	v_pk_fma_f32 v[18:19], v[162:163], v[18:19], v[178:179]
	v_cvt_pk_bf16_f32 v244, v16, v17
	v_cvt_pk_bf16_f32 v245, v18, v19
	v_pk_mul_f32 v[20:21], v[20:21], v[234:235] op_sel_hi:[1,0]
	v_pk_mul_f32 v[22:23], v[22:23], v[234:235] op_sel_hi:[1,0]
	v_pk_mul_f32 v[20:21], v[68:69], v[20:21]
	v_pk_mul_f32 v[22:23], v[70:71], v[22:23]
	v_pk_fma_f32 v[20:21], v[164:165], v[20:21], v[180:181]
	v_pk_fma_f32 v[22:23], v[166:167], v[22:23], v[182:183]
	v_cvt_pk_bf16_f32 v246, v20, v21
	v_cvt_pk_bf16_f32 v247, v22, v23
	global_store_dwordx4 v82, v[244:247], s[40:41] offset:0
	v_pk_mul_f32 v[24:25], v[24:25], v[234:235] op_sel_hi:[1,0]
	v_pk_mul_f32 v[26:27], v[26:27], v[234:235] op_sel_hi:[1,0]
	v_pk_mul_f32 v[24:25], v[72:73], v[24:25]
	v_pk_mul_f32 v[26:27], v[74:75], v[26:27]
	v_pk_fma_f32 v[24:25], v[168:169], v[24:25], v[184:185]
	v_pk_fma_f32 v[26:27], v[170:171], v[26:27], v[186:187]
	v_cvt_pk_bf16_f32 v240, v24, v25
	v_cvt_pk_bf16_f32 v241, v26, v27
	v_pk_mul_f32 v[28:29], v[28:29], v[234:235] op_sel_hi:[1,0]
	v_pk_mul_f32 v[30:31], v[30:31], v[234:235] op_sel_hi:[1,0]
	v_pk_mul_f32 v[28:29], v[76:77], v[28:29]
	v_pk_mul_f32 v[30:31], v[78:79], v[30:31]
	v_pk_fma_f32 v[28:29], v[172:173], v[28:29], v[188:189]
	v_pk_fma_f32 v[30:31], v[174:175], v[30:31], v[190:191]
	v_cvt_pk_bf16_f32 v242, v28, v29
	v_cvt_pk_bf16_f32 v243, v30, v31
	global_store_dwordx4 v82, v[240:243], s[40:41] offset:1024
	v_pk_mul_f32 v[32:33], v[32:33], v[236:237] op_sel_hi:[1,0]
	v_pk_mul_f32 v[34:35], v[34:35], v[236:237] op_sel_hi:[1,0]
	v_pk_mul_f32 v[32:33], v[64:65], v[32:33]
	v_pk_mul_f32 v[34:35], v[66:67], v[34:35]
	v_pk_fma_f32 v[32:33], v[192:193], v[32:33], v[208:209]
	v_pk_fma_f32 v[34:35], v[194:195], v[34:35], v[210:211]
	v_cvt_pk_bf16_f32 v244, v32, v33
	v_cvt_pk_bf16_f32 v245, v34, v35
	v_pk_mul_f32 v[36:37], v[36:37], v[236:237] op_sel_hi:[1,0]
	v_pk_mul_f32 v[38:39], v[38:39], v[236:237] op_sel_hi:[1,0]
	v_pk_mul_f32 v[36:37], v[68:69], v[36:37]
	v_pk_mul_f32 v[38:39], v[70:71], v[38:39]
	v_pk_fma_f32 v[36:37], v[196:197], v[36:37], v[212:213]
	v_pk_fma_f32 v[38:39], v[198:199], v[38:39], v[214:215]
	v_cvt_pk_bf16_f32 v246, v36, v37
	v_cvt_pk_bf16_f32 v247, v38, v39
	global_store_dwordx4 v82, v[244:247], s[46:47] offset:0
	v_pk_mul_f32 v[40:41], v[40:41], v[236:237] op_sel_hi:[1,0]
	v_pk_mul_f32 v[42:43], v[42:43], v[236:237] op_sel_hi:[1,0]
	v_pk_mul_f32 v[40:41], v[72:73], v[40:41]
	v_pk_mul_f32 v[42:43], v[74:75], v[42:43]
	v_pk_fma_f32 v[40:41], v[200:201], v[40:41], v[216:217]
	v_pk_fma_f32 v[42:43], v[202:203], v[42:43], v[218:219]
	v_cvt_pk_bf16_f32 v240, v40, v41
	v_cvt_pk_bf16_f32 v241, v42, v43
	v_pk_mul_f32 v[44:45], v[44:45], v[236:237] op_sel_hi:[1,0]
	v_pk_mul_f32 v[46:47], v[46:47], v[236:237] op_sel_hi:[1,0]
	v_pk_mul_f32 v[44:45], v[76:77], v[44:45]
	v_pk_mul_f32 v[46:47], v[78:79], v[46:47]
	v_pk_fma_f32 v[44:45], v[204:205], v[44:45], v[220:221]
	v_pk_fma_f32 v[46:47], v[206:207], v[46:47], v[222:223]
	v_cvt_pk_bf16_f32 v242, v44, v45
	v_cvt_pk_bf16_f32 v243, v46, v47
	global_store_dwordx4 v82, v[240:243], s[46:47] offset:1024
	v_pk_mul_f32 v[48:49], v[48:49], v[238:239] op_sel_hi:[1,0]
	v_pk_mul_f32 v[50:51], v[50:51], v[238:239] op_sel_hi:[1,0]
	v_pk_mul_f32 v[48:49], v[64:65], v[48:49]
	v_pk_mul_f32 v[50:51], v[66:67], v[50:51]
	v_pk_fma_f32 v[48:49], v[192:193], v[48:49], v[208:209]
	v_pk_fma_f32 v[50:51], v[194:195], v[50:51], v[210:211]
	v_cvt_pk_bf16_f32 v244, v48, v49
	v_cvt_pk_bf16_f32 v245, v50, v51
	v_pk_mul_f32 v[52:53], v[52:53], v[238:239] op_sel_hi:[1,0]
	v_pk_mul_f32 v[54:55], v[54:55], v[238:239] op_sel_hi:[1,0]
	v_pk_mul_f32 v[52:53], v[68:69], v[52:53]
	v_pk_mul_f32 v[54:55], v[70:71], v[54:55]
	v_pk_fma_f32 v[52:53], v[196:197], v[52:53], v[212:213]
	v_pk_fma_f32 v[54:55], v[198:199], v[54:55], v[214:215]
	v_cvt_pk_bf16_f32 v246, v52, v53
	v_cvt_pk_bf16_f32 v247, v54, v55
	global_store_dwordx4 v82, v[244:247], s[48:49] offset:0
	v_pk_mul_f32 v[56:57], v[56:57], v[238:239] op_sel_hi:[1,0]
	v_pk_mul_f32 v[58:59], v[58:59], v[238:239] op_sel_hi:[1,0]
	v_pk_mul_f32 v[56:57], v[72:73], v[56:57]
	v_pk_mul_f32 v[58:59], v[74:75], v[58:59]
	v_pk_fma_f32 v[56:57], v[200:201], v[56:57], v[216:217]
	v_pk_fma_f32 v[58:59], v[202:203], v[58:59], v[218:219]
	v_cvt_pk_bf16_f32 v240, v56, v57
	v_cvt_pk_bf16_f32 v241, v58, v59
	v_pk_mul_f32 v[60:61], v[60:61], v[238:239] op_sel_hi:[1,0]
	v_pk_mul_f32 v[62:63], v[62:63], v[238:239] op_sel_hi:[1,0]
	v_pk_mul_f32 v[60:61], v[76:77], v[60:61]
	v_pk_mul_f32 v[62:63], v[78:79], v[62:63]
	v_pk_fma_f32 v[60:61], v[204:205], v[60:61], v[220:221]
	v_pk_fma_f32 v[62:63], v[206:207], v[62:63], v[222:223]
	v_cvt_pk_bf16_f32 v242, v60, v61
	v_cvt_pk_bf16_f32 v243, v62, v63
	global_store_dwordx4 v82, v[240:243], s[48:49] offset:1024
	s_add_u32 s34, s8, 0x15000
	s_addc_u32 s35, s9, 0
	s_add_u32 s36, s8, 0x15000
	s_addc_u32 s37, s9, 0
	global_load_dwordx4 v[176:179], v80, s[34:35] offset:0
	global_load_dwordx4 v[180:183], v80, s[34:35] offset:16
	global_load_dwordx4 v[184:187], v80, s[34:35] offset:2048
	global_load_dwordx4 v[188:191], v80, s[34:35] offset:2064
	global_load_dwordx4 v[160:163], v81, s[34:35] offset:0
	global_load_dwordx4 v[164:167], v81, s[34:35] offset:16
	global_load_dwordx4 v[168:171], v81, s[34:35] offset:2048
	global_load_dwordx4 v[172:175], v81, s[34:35] offset:2064
	global_load_dwordx4 v[208:211], v80, s[36:37] offset:0
	global_load_dwordx4 v[212:215], v80, s[36:37] offset:16
	global_load_dwordx4 v[216:219], v80, s[36:37] offset:2048
	global_load_dwordx4 v[220:223], v80, s[36:37] offset:2064
	global_load_dwordx4 v[192:195], v81, s[36:37] offset:0
	global_load_dwordx4 v[196:199], v81, s[36:37] offset:16
	global_load_dwordx4 v[200:203], v81, s[36:37] offset:2048
	global_load_dwordx4 v[204:207], v81, s[36:37] offset:2064
	s_add_u32 s24, s16, 0x4000000
	s_addc_u32 s25, s17, 0
	s_add_u32 s26, s16, 0x4400000
	s_addc_u32 s27, s17, 0
	s_add_u32 s28, s16, 0x4800000
	s_addc_u32 s29, s17, 0
	s_add_u32 s30, s16, 0x4c00000
	s_addc_u32 s31, s17, 0
	global_load_dwordx4 v[96:99], v82, s[24:25] offset:0
	global_load_dwordx4 v[100:103], v82, s[24:25] offset:1024
	global_load_dwordx4 v[104:107], v82, s[26:27] offset:0
	global_load_dwordx4 v[108:111], v82, s[26:27] offset:1024
	global_load_dwordx4 v[112:115], v82, s[28:29] offset:0
	global_load_dwordx4 v[116:119], v82, s[28:29] offset:1024
	global_load_dwordx4 v[120:123], v82, s[30:31] offset:0
	global_load_dwordx4 v[124:127], v82, s[30:31] offset:1024
	s_waitcnt vmcnt(32)
; __device__ __forceinline__ float bf_lo(unsigned w) { return __uint_as_float(w << 16); }
; __device__ __forceinline__ float bf_hi(unsigned w) { return __uint_as_float(w & 0xffff0000u); }
; template <bool BF> __device__ __forceinline__ void prep_rows(const float* xp, const float* xs, const bf16* hb, const float* g, const float* MOD, int shoff, int scoff, bf16* U, int gw, int NGW, int lane) {
;     ...
;                 if (BF) { const v2u a0 = *(const v2u*)(hb + (size_t)mc * DM + 4 * lane + 256 * j);
;                     v[r][j].x = pg8::bf_lo(a0.x); v[r][j].y = pg8::bf_hi(a0.x); v[r][j].z = pg8::bf_lo(a0.y); v[r][j].w = pg8::bf_hi(a0.y); }
;                 else { const float* xr = mc < MP ? xp + (size_t)mc * DM : xs + (size_t)(mc - MP) * DM; v[r][j] = *(const f32x4*)(xr + 4 * lane + 256 * j); } } }
; #pragma unroll
;         for (int r = 0; r < R; ++r) { float t = 0.f;
; #pragma unroll
;             for (int j = 0; j < 4; ++j) t += (v[r][j].x * v[r][j].x + v[r][j].y * v[r][j].y) + (v[r][j].z * v[r][j].z + v[r][j].w * v[r][j].w);
;             s[r] = t; }
; #pragma unroll
;         for (int o = 1; o < 64; o <<= 1) {
; #pragma unroll
;             for (int r = 0; r < R; ++r) s[r] += __shfl_xor(s[r], o); }
; #pragma unroll
	v_lshlrev_b32_e32 v0, 16, v128
	v_and_b32_e32 v1, 0xffff0000, v128
	v_lshlrev_b32_e32 v2, 16, v129
	v_and_b32_e32 v3, 0xffff0000, v129
	v_lshlrev_b32_e32 v4, 16, v130
	v_and_b32_e32 v5, 0xffff0000, v130
	v_lshlrev_b32_e32 v6, 16, v131
	v_and_b32_e32 v7, 0xffff0000, v131
	v_lshlrev_b32_e32 v8, 16, v132
	v_and_b32_e32 v9, 0xffff0000, v132
	v_lshlrev_b32_e32 v10, 16, v133
	v_and_b32_e32 v11, 0xffff0000, v133
	v_lshlrev_b32_e32 v12, 16, v134
	v_and_b32_e32 v13, 0xffff0000, v134
	v_lshlrev_b32_e32 v14, 16, v135
	v_and_b32_e32 v15, 0xffff0000, v135
	v_lshlrev_b32_e32 v16, 16, v136
	v_and_b32_e32 v17, 0xffff0000, v136
	v_lshlrev_b32_e32 v18, 16, v137
	v_and_b32_e32 v19, 0xffff0000, v137
	v_lshlrev_b32_e32 v20, 16, v138
	v_and_b32_e32 v21, 0xffff0000, v138
	v_lshlrev_b32_e32 v22, 16, v139
	v_and_b32_e32 v23, 0xffff0000, v139
	v_lshlrev_b32_e32 v24, 16, v140
	v_and_b32_e32 v25, 0xffff0000, v140
	v_lshlrev_b32_e32 v26, 16, v141
	v_and_b32_e32 v27, 0xffff0000, v141
	v_lshlrev_b32_e32 v28, 16, v142
	v_and_b32_e32 v29, 0xffff0000, v142
	v_lshlrev_b32_e32 v30, 16, v143
	v_and_b32_e32 v31, 0xffff0000, v143
	v_lshlrev_b32_e32 v32, 16, v144
	v_and_b32_e32 v33, 0xffff0000, v144
	v_lshlrev_b32_e32 v34, 16, v145
	v_and_b32_e32 v35, 0xffff0000, v145
	v_lshlrev_b32_e32 v36, 16, v146
	v_and_b32_e32 v37, 0xffff0000, v146
	v_lshlrev_b32_e32 v38, 16, v147
	v_and_b32_e32 v39, 0xffff0000, v147
	v_lshlrev_b32_e32 v40, 16, v148
	v_and_b32_e32 v41, 0xffff0000, v148
	v_lshlrev_b32_e32 v42, 16, v149
	v_and_b32_e32 v43, 0xffff0000, v149
	v_lshlrev_b32_e32 v44, 16, v150
	v_and_b32_e32 v45, 0xffff0000, v150
	v_lshlrev_b32_e32 v46, 16, v151
	v_and_b32_e32 v47, 0xffff0000, v151
	v_lshlrev_b32_e32 v48, 16, v152
	v_and_b32_e32 v49, 0xffff0000, v152
	v_lshlrev_b32_e32 v50, 16, v153
	v_and_b32_e32 v51, 0xffff0000, v153
	v_lshlrev_b32_e32 v52, 16, v154
	v_and_b32_e32 v53, 0xffff0000, v154
	v_lshlrev_b32_e32 v54, 16, v155
	v_and_b32_e32 v55, 0xffff0000, v155
	v_lshlrev_b32_e32 v56, 16, v156
	v_and_b32_e32 v57, 0xffff0000, v156
	v_lshlrev_b32_e32 v58, 16, v157
	v_and_b32_e32 v59, 0xffff0000, v157
	v_lshlrev_b32_e32 v60, 16, v158
	v_and_b32_e32 v61, 0xffff0000, v158
	v_lshlrev_b32_e32 v62, 16, v159
	v_and_b32_e32 v63, 0xffff0000, v159
	v_pk_mul_f32 v[240:241], v[0:1], v[0:1]
	v_pk_mul_f32 v[242:243], v[16:17], v[16:17]
	v_pk_mul_f32 v[244:245], v[32:33], v[32:33]
	v_pk_mul_f32 v[246:247], v[48:49], v[48:49]
	v_pk_fma_f32 v[240:241], v[2:3], v[2:3], v[240:241]
	v_pk_fma_f32 v[242:243], v[18:19], v[18:19], v[242:243]
	v_pk_fma_f32 v[244:245], v[34:35], v[34:35], v[244:245]
	v_pk_fma_f32 v[246:247], v[50:51], v[50:51], v[246:247]
	v_pk_fma_f32 v[240:241], v[4:5], v[4:5], v[240:241]
	v_pk_fma_f32 v[242:243], v[20:21], v[20:21], v[242:243]
	v_pk_fma_f32 v[244:245], v[36:37], v[36:37], v[244:245]
	v_pk_fma_f32 v[246:247], v[52:53], v[52:53], v[246:247]
	v_pk_fma_f32 v[240:241], v[6:7], v[6:7], v[240:241]
	v_pk_fma_f32 v[242:243], v[22:23], v[22:23], v[242:243]
	v_pk_fma_f32 v[244:245], v[38:39], v[38:39], v[244:245]
	v_pk_fma_f32 v[246:247], v[54:55], v[54:55], v[246:247]
	v_pk_fma_f32 v[240:241], v[8:9], v[8:9], v[240:241]
	v_pk_fma_f32 v[242:243], v[24:25], v[24:25], v[242:243]
	v_pk_fma_f32 v[244:245], v[40:41], v[40:41], v[244:245]
	v_pk_fma_f32 v[246:247], v[56:57], v[56:57], v[246:247]
	v_pk_fma_f32 v[240:241], v[10:11], v[10:11], v[240:241]
	v_pk_fma_f32 v[242:243], v[26:27], v[26:27], v[242:243]
	v_pk_fma_f32 v[244:245], v[42:43], v[42:43], v[244:245]
	v_pk_fma_f32 v[246:247], v[58:59], v[58:59], v[246:247]
	v_pk_fma_f32 v[240:241], v[12:13], v[12:13], v[240:241]
	v_pk_fma_f32 v[242:243], v[28:29], v[28:29], v[242:243]
	v_pk_fma_f32 v[244:245], v[44:45], v[44:45], v[244:245]
	v_pk_fma_f32 v[246:247], v[60:61], v[60:61], v[246:247]
	v_pk_fma_f32 v[240:241], v[14:15], v[14:15], v[240:241]
	v_pk_fma_f32 v[242:243], v[30:31], v[30:31], v[242:243]
	v_pk_fma_f32 v[244:245], v[46:47], v[46:47], v[244:245]
	v_pk_fma_f32 v[246:247], v[62:63], v[62:63], v[246:247]
	v_add_f32_e32 v224, v240, v241
	v_add_f32_e32 v225, v242, v243
	v_add_f32_e32 v226, v244, v245
	v_add_f32_e32 v227, v246, v247
	ds_bpermute_b32 v228, v83, v224
	ds_bpermute_b32 v229, v83, v225
	ds_bpermute_b32 v230, v83, v226
	ds_bpermute_b32 v231, v83, v227
	s_waitcnt lgkmcnt(0)
	v_add_f32_e32 v224, v224, v228
	v_add_f32_e32 v225, v225, v229
	v_add_f32_e32 v226, v226, v230
	v_add_f32_e32 v227, v227, v231
	ds_bpermute_b32 v228, v84, v224
	ds_bpermute_b32 v229, v84, v225
	ds_bpermute_b32 v230, v84, v226
	ds_bpermute_b32 v231, v84, v227
	s_waitcnt lgkmcnt(0)
	v_add_f32_e32 v224, v224, v228
	v_add_f32_e32 v225, v225, v229
	v_add_f32_e32 v226, v226, v230
	v_add_f32_e32 v227, v227, v231
	ds_bpermute_b32 v228, v85, v224
	ds_bpermute_b32 v229, v85, v225
	ds_bpermute_b32 v230, v85, v226
	ds_bpermute_b32 v231, v85, v227
	s_waitcnt lgkmcnt(0)
	v_add_f32_e32 v224, v224, v228
	v_add_f32_e32 v225, v225, v229
	v_add_f32_e32 v226, v226, v230
	v_add_f32_e32 v227, v227, v231
	ds_bpermute_b32 v228, v86, v224
	ds_bpermute_b32 v229, v86, v225
	ds_bpermute_b32 v230, v86, v226
	ds_bpermute_b32 v231, v86, v227
	s_waitcnt lgkmcnt(0)
	v_add_f32_e32 v224, v224, v228
	v_add_f32_e32 v225, v225, v229
	v_add_f32_e32 v226, v226, v230
	v_add_f32_e32 v227, v227, v231
	ds_bpermute_b32 v228, v87, v224
	ds_bpermute_b32 v229, v87, v225
	ds_bpermute_b32 v230, v87, v226
	ds_bpermute_b32 v231, v87, v227
	s_waitcnt lgkmcnt(0)
	v_add_f32_e32 v224, v224, v228
	v_add_f32_e32 v225, v225, v229
	v_add_f32_e32 v226, v226, v230
	v_add_f32_e32 v227, v227, v231
	ds_bpermute_b32 v228, v88, v224
	ds_bpermute_b32 v229, v88, v225
	ds_bpermute_b32 v230, v88, v226
	ds_bpermute_b32 v231, v88, v227
	s_waitcnt lgkmcnt(0)
; template <bool BF> __device__ __forceinline__ void prep_rows(const float* xp, const float* xs, const bf16* hb, const float* g, const float* MOD, int shoff, int scoff, bf16* U, int gw, int NGW, int lane) {
;     ...
;             for (int r = 0; r < R; ++r) s[r] += __shfl_xor(s[r], o); }
; #pragma unroll
;         for (int r = 0; r < R; ++r) { const int m = mb + r * NGW; if (m < MT) {
;             const float rstd = 1.0f / sqrtf(s[r] * (1.0f / DM) + RMS_EPS);
	v_add_f32_e32 v224, v224, v228
	v_add_f32_e32 v225, v225, v229
	v_add_f32_e32 v226, v226, v230
	v_add_f32_e32 v227, v227, v231
	v_fmamk_f32 v240, v224, 0x3a800000, v89
	v_mul_f32_e32 v241, 0x4f800000, v240
	v_cmp_gt_f32_e32 vcc, s54, v240
	s_nop 1
	v_cndmask_b32_e32 v247, v240, v241, vcc
	v_sqrt_f32_e32 v242, v247
	s_nop 1
	v_add_u32_e32 v243, -1, v242
	v_add_u32_e32 v244, 1, v242
	v_fma_f32 v245, -v243, v242, v247
	v_fma_f32 v246, -v244, v242, v247
	v_cmp_ge_f32_e64 s[52:53], 0, v245
	s_nop 1
	v_cndmask_b32_e64 v242, v242, v243, s[52:53]
	v_cmp_lt_f32_e64 s[52:53], 0, v246
	s_nop 1
	v_cndmask_b32_e64 v242, v242, v244, s[52:53]
	v_mul_f32_e32 v243, 0x37800000, v242
	v_cndmask_b32_e32 v242, v242, v243, vcc
	v_cmp_class_f32_e32 vcc, v247, v90
	s_nop 1
	v_cndmask_b32_e32 v247, v242, v247, vcc
	v_div_scale_f32 v248, s[52:53], v247, v247, 1.0
	v_rcp_f32_e32 v249, v248
	v_div_scale_f32 v228, vcc, 1.0, v247, 1.0
	s_nop 0
	v_fma_f32 v229, -v248, v249, 1.0
	v_fmac_f32_e32 v249, v229, v249
	v_mul_f32_e32 v230, v228, v249
	v_fma_f32 v229, -v248, v230, v228
	v_fmac_f32_e32 v230, v229, v249
	v_fma_f32 v248, -v248, v230, v228
	v_div_fmas_f32 v248, v248, v249, v230
	v_div_fixup_f32 v232, v248, v247, 1.0
	v_fmamk_f32 v240, v225, 0x3a800000, v89
	v_mul_f32_e32 v241, 0x4f800000, v240
	v_cmp_gt_f32_e32 vcc, s54, v240
	s_nop 1
	v_cndmask_b32_e32 v247, v240, v241, vcc
	v_sqrt_f32_e32 v242, v247
	s_nop 1
	v_add_u32_e32 v243, -1, v242
	v_add_u32_e32 v244, 1, v242
	v_fma_f32 v245, -v243, v242, v247
	v_fma_f32 v246, -v244, v242, v247
	v_cmp_ge_f32_e64 s[52:53], 0, v245
	s_nop 1
	v_cndmask_b32_e64 v242, v242, v243, s[52:53]
	v_cmp_lt_f32_e64 s[52:53], 0, v246
	s_nop 1
	v_cndmask_b32_e64 v242, v242, v244, s[52:53]
	v_mul_f32_e32 v243, 0x37800000, v242
	v_cndmask_b32_e32 v242, v242, v243, vcc
	v_cmp_class_f32_e32 vcc, v247, v90
	s_nop 1
	v_cndmask_b32_e32 v247, v242, v247, vcc
	v_div_scale_f32 v248, s[52:53], v247, v247, 1.0
	v_rcp_f32_e32 v249, v248
	v_div_scale_f32 v228, vcc, 1.0, v247, 1.0
	s_nop 0
	v_fma_f32 v229, -v248, v249, 1.0
	v_fmac_f32_e32 v249, v229, v249
	v_mul_f32_e32 v230, v228, v249
	v_fma_f32 v229, -v248, v230, v228
	v_fmac_f32_e32 v230, v229, v249
	v_fma_f32 v248, -v248, v230, v228
	v_div_fmas_f32 v248, v248, v249, v230
	v_div_fixup_f32 v234, v248, v247, 1.0
	v_fmamk_f32 v240, v226, 0x3a800000, v89
	v_mul_f32_e32 v241, 0x4f800000, v240
	v_cmp_gt_f32_e32 vcc, s54, v240
	s_nop 1
	v_cndmask_b32_e32 v247, v240, v241, vcc
	v_sqrt_f32_e32 v242, v247
	s_nop 1
	v_add_u32_e32 v243, -1, v242
	v_add_u32_e32 v244, 1, v242
	v_fma_f32 v245, -v243, v242, v247
	v_fma_f32 v246, -v244, v242, v247
	v_cmp_ge_f32_e64 s[52:53], 0, v245
	s_nop 1
	v_cndmask_b32_e64 v242, v242, v243, s[52:53]
	v_cmp_lt_f32_e64 s[52:53], 0, v246
	s_nop 1
	v_cndmask_b32_e64 v242, v242, v244, s[52:53]
	v_mul_f32_e32 v243, 0x37800000, v242
	v_cndmask_b32_e32 v242, v242, v243, vcc
	v_cmp_class_f32_e32 vcc, v247, v90
	s_nop 1
	v_cndmask_b32_e32 v247, v242, v247, vcc
	v_div_scale_f32 v248, s[52:53], v247, v247, 1.0
	v_rcp_f32_e32 v249, v248
	v_div_scale_f32 v228, vcc, 1.0, v247, 1.0
	s_nop 0
	v_fma_f32 v229, -v248, v249, 1.0
	v_fmac_f32_e32 v249, v229, v249
	v_mul_f32_e32 v230, v228, v249
	v_fma_f32 v229, -v248, v230, v228
	v_fmac_f32_e32 v230, v229, v249
	v_fma_f32 v248, -v248, v230, v228
	v_div_fmas_f32 v248, v248, v249, v230
	v_div_fixup_f32 v236, v248, v247, 1.0
	v_fmamk_f32 v240, v227, 0x3a800000, v89
	v_mul_f32_e32 v241, 0x4f800000, v240
	v_cmp_gt_f32_e32 vcc, s54, v240
	s_nop 1
	v_cndmask_b32_e32 v247, v240, v241, vcc
	v_sqrt_f32_e32 v242, v247
	s_nop 1
	v_add_u32_e32 v243, -1, v242
	v_add_u32_e32 v244, 1, v242
	v_fma_f32 v245, -v243, v242, v247
	v_fma_f32 v246, -v244, v242, v247
	v_cmp_ge_f32_e64 s[52:53], 0, v245
	s_nop 1
	v_cndmask_b32_e64 v242, v242, v243, s[52:53]
	v_cmp_lt_f32_e64 s[52:53], 0, v246
	s_nop 1
	v_cndmask_b32_e64 v242, v242, v244, s[52:53]
	v_mul_f32_e32 v243, 0x37800000, v242
	v_cndmask_b32_e32 v242, v242, v243, vcc
	v_cmp_class_f32_e32 vcc, v247, v90
	s_nop 1
	v_cndmask_b32_e32 v247, v242, v247, vcc
	v_div_scale_f32 v248, s[52:53], v247, v247, 1.0
	v_rcp_f32_e32 v249, v248
	v_div_scale_f32 v228, vcc, 1.0, v247, 1.0
	s_nop 0
	v_fma_f32 v229, -v248, v249, 1.0
	v_fmac_f32_e32 v249, v229, v249
	v_mul_f32_e32 v230, v228, v249
	v_fma_f32 v229, -v248, v230, v228
	v_fmac_f32_e32 v230, v229, v249
	v_fma_f32 v248, -v248, v230, v228
	v_div_fmas_f32 v248, v248, v249, v230
	v_div_fixup_f32 v238, v248, v247, 1.0
	s_waitcnt vmcnt(8)
; __device__ __forceinline__ unsigned pk2(float lo, float hi) { return pg8::cvt_pk_bf16(lo, hi); }
; template <bool BF> __device__ __forceinline__ void prep_rows(const float* xp, const float* xs, const bf16* hb, const float* g, const float* MOD, int shoff, int scoff, bf16* U, int gw, int NGW, int lane) {
;     ...
;             const float* mr = MOD + (size_t)(m < MP ? (m >> 13) : 8 + ((m - MP) >> 12)) * 6144;
; #pragma unroll
;             for (int j = 0; j < 4; ++j) { const int c = 4 * lane + 256 * j;
;                 const f32x4 gg = *(const f32x4*)(g + c), sc = *(const f32x4*)(mr + scoff + c), sh = *(const f32x4*)(mr + shoff + c);
;                 const f32x4 o = v[r][j] * rstd * gg * (sc + 1.0f) + sh; v2u w; w.x = pk2(o.x, o.y); w.y = pk2(o.z, o.w); *(v2u*)(U + (size_t)m * DM + c) = w; } } }
	v_pk_add_f32 v[160:161], v[160:161], 1.0 op_sel_hi:[1,0]
	v_pk_add_f32 v[162:163], v[162:163], 1.0 op_sel_hi:[1,0]
	v_pk_add_f32 v[164:165], v[164:165], 1.0 op_sel_hi:[1,0]
	v_pk_add_f32 v[166:167], v[166:167], 1.0 op_sel_hi:[1,0]
	v_pk_add_f32 v[168:169], v[168:169], 1.0 op_sel_hi:[1,0]
	v_pk_add_f32 v[170:171], v[170:171], 1.0 op_sel_hi:[1,0]
	v_pk_add_f32 v[172:173], v[172:173], 1.0 op_sel_hi:[1,0]
	v_pk_add_f32 v[174:175], v[174:175], 1.0 op_sel_hi:[1,0]
	v_pk_add_f32 v[192:193], v[192:193], 1.0 op_sel_hi:[1,0]
	v_pk_add_f32 v[194:195], v[194:195], 1.0 op_sel_hi:[1,0]
	v_pk_add_f32 v[196:197], v[196:197], 1.0 op_sel_hi:[1,0]
	v_pk_add_f32 v[198:199], v[198:199], 1.0 op_sel_hi:[1,0]
	v_pk_add_f32 v[200:201], v[200:201], 1.0 op_sel_hi:[1,0]
	v_pk_add_f32 v[202:203], v[202:203], 1.0 op_sel_hi:[1,0]
	v_pk_add_f32 v[204:205], v[204:205], 1.0 op_sel_hi:[1,0]
	v_pk_add_f32 v[206:207], v[206:207], 1.0 op_sel_hi:[1,0]
	s_add_u32 s38, s20, 0x3000000
	s_addc_u32 s39, s21, 0
	s_add_u32 s40, s20, 0x3400000
	s_addc_u32 s41, s21, 0
	s_add_u32 s46, s20, 0x3800000
	s_addc_u32 s47, s21, 0
	s_add_u32 s48, s20, 0x3c00000
	s_addc_u32 s49, s21, 0
	v_pk_mul_f32 v[0:1], v[0:1], v[232:233] op_sel_hi:[1,0]
	v_pk_mul_f32 v[2:3], v[2:3], v[232:233] op_sel_hi:[1,0]
	v_pk_mul_f32 v[0:1], v[64:65], v[0:1]
	v_pk_mul_f32 v[2:3], v[66:67], v[2:3]
	v_pk_fma_f32 v[0:1], v[160:161], v[0:1], v[176:177]
	v_pk_fma_f32 v[2:3], v[162:163], v[2:3], v[178:179]
	v_cvt_pk_bf16_f32 v244, v0, v1
	v_cvt_pk_bf16_f32 v245, v2, v3
	v_pk_mul_f32 v[4:5], v[4:5], v[232:233] op_sel_hi:[1,0]
	v_pk_mul_f32 v[6:7], v[6:7], v[232:233] op_sel_hi:[1,0]
	v_pk_mul_f32 v[4:5], v[68:69], v[4:5]
	v_pk_mul_f32 v[6:7], v[70:71], v[6:7]
	v_pk_fma_f32 v[4:5], v[164:165], v[4:5], v[180:181]
	v_pk_fma_f32 v[6:7], v[166:167], v[6:7], v[182:183]
	v_cvt_pk_bf16_f32 v246, v4, v5
	v_cvt_pk_bf16_f32 v247, v6, v7
	global_store_dwordx4 v82, v[244:247], s[38:39] offset:0
	v_pk_mul_f32 v[8:9], v[8:9], v[232:233] op_sel_hi:[1,0]
	v_pk_mul_f32 v[10:11], v[10:11], v[232:233] op_sel_hi:[1,0]
	v_pk_mul_f32 v[8:9], v[72:73], v[8:9]
	v_pk_mul_f32 v[10:11], v[74:75], v[10:11]
	v_pk_fma_f32 v[8:9], v[168:169], v[8:9], v[184:185]
	v_pk_fma_f32 v[10:11], v[170:171], v[10:11], v[186:187]
	v_cvt_pk_bf16_f32 v240, v8, v9
	v_cvt_pk_bf16_f32 v241, v10, v11
	v_pk_mul_f32 v[12:13], v[12:13], v[232:233] op_sel_hi:[1,0]
	v_pk_mul_f32 v[14:15], v[14:15], v[232:233] op_sel_hi:[1,0]
	v_pk_mul_f32 v[12:13], v[76:77], v[12:13]
	v_pk_mul_f32 v[14:15], v[78:79], v[14:15]
	v_pk_fma_f32 v[12:13], v[172:173], v[12:13], v[188:189]
	v_pk_fma_f32 v[14:15], v[174:175], v[14:15], v[190:191]
	v_cvt_pk_bf16_f32 v242, v12, v13
	v_cvt_pk_bf16_f32 v243, v14, v15
	global_store_dwordx4 v82, v[240:243], s[38:39] offset:1024
	v_pk_mul_f32 v[16:17], v[16:17], v[234:235] op_sel_hi:[1,0]
	v_pk_mul_f32 v[18:19], v[18:19], v[234:235] op_sel_hi:[1,0]
	v_pk_mul_f32 v[16:17], v[64:65], v[16:17]
	v_pk_mul_f32 v[18:19], v[66:67], v[18:19]
	v_pk_fma_f32 v[16:17], v[160:161], v[16:17], v[176:177]
	v_pk_fma_f32 v[18:19], v[162:163], v[18:19], v[178:179]
	v_cvt_pk_bf16_f32 v244, v16, v17
	v_cvt_pk_bf16_f32 v245, v18, v19
	v_pk_mul_f32 v[20:21], v[20:21], v[234:235] op_sel_hi:[1,0]
	v_pk_mul_f32 v[22:23], v[22:23], v[234:235] op_sel_hi:[1,0]
	v_pk_mul_f32 v[20:21], v[68:69], v[20:21]
	v_pk_mul_f32 v[22:23], v[70:71], v[22:23]
	v_pk_fma_f32 v[20:21], v[164:165], v[20:21], v[180:181]
	v_pk_fma_f32 v[22:23], v[166:167], v[22:23], v[182:183]
	v_cvt_pk_bf16_f32 v246, v20, v21
	v_cvt_pk_bf16_f32 v247, v22, v23
	global_store_dwordx4 v82, v[244:247], s[40:41] offset:0
	v_pk_mul_f32 v[24:25], v[24:25], v[234:235] op_sel_hi:[1,0]
	v_pk_mul_f32 v[26:27], v[26:27], v[234:235] op_sel_hi:[1,0]
	v_pk_mul_f32 v[24:25], v[72:73], v[24:25]
	v_pk_mul_f32 v[26:27], v[74:75], v[26:27]
	v_pk_fma_f32 v[24:25], v[168:169], v[24:25], v[184:185]
	v_pk_fma_f32 v[26:27], v[170:171], v[26:27], v[186:187]
	v_cvt_pk_bf16_f32 v240, v24, v25
	v_cvt_pk_bf16_f32 v241, v26, v27
	v_pk_mul_f32 v[28:29], v[28:29], v[234:235] op_sel_hi:[1,0]
	v_pk_mul_f32 v[30:31], v[30:31], v[234:235] op_sel_hi:[1,0]
	v_pk_mul_f32 v[28:29], v[76:77], v[28:29]
	v_pk_mul_f32 v[30:31], v[78:79], v[30:31]
	v_pk_fma_f32 v[28:29], v[172:173], v[28:29], v[188:189]
	v_pk_fma_f32 v[30:31], v[174:175], v[30:31], v[190:191]
	v_cvt_pk_bf16_f32 v242, v28, v29
	v_cvt_pk_bf16_f32 v243, v30, v31
	global_store_dwordx4 v82, v[240:243], s[40:41] offset:1024
	v_pk_mul_f32 v[32:33], v[32:33], v[236:237] op_sel_hi:[1,0]
	v_pk_mul_f32 v[34:35], v[34:35], v[236:237] op_sel_hi:[1,0]
	v_pk_mul_f32 v[32:33], v[64:65], v[32:33]
	v_pk_mul_f32 v[34:35], v[66:67], v[34:35]
	v_pk_fma_f32 v[32:33], v[192:193], v[32:33], v[208:209]
	v_pk_fma_f32 v[34:35], v[194:195], v[34:35], v[210:211]
	v_cvt_pk_bf16_f32 v244, v32, v33
	v_cvt_pk_bf16_f32 v245, v34, v35
	v_pk_mul_f32 v[36:37], v[36:37], v[236:237] op_sel_hi:[1,0]
	v_pk_mul_f32 v[38:39], v[38:39], v[236:237] op_sel_hi:[1,0]
	v_pk_mul_f32 v[36:37], v[68:69], v[36:37]
	v_pk_mul_f32 v[38:39], v[70:71], v[38:39]
	v_pk_fma_f32 v[36:37], v[196:197], v[36:37], v[212:213]
	v_pk_fma_f32 v[38:39], v[198:199], v[38:39], v[214:215]
	v_cvt_pk_bf16_f32 v246, v36, v37
	v_cvt_pk_bf16_f32 v247, v38, v39
	global_store_dwordx4 v82, v[244:247], s[46:47] offset:0
	v_pk_mul_f32 v[40:41], v[40:41], v[236:237] op_sel_hi:[1,0]
	v_pk_mul_f32 v[42:43], v[42:43], v[236:237] op_sel_hi:[1,0]
	v_pk_mul_f32 v[40:41], v[72:73], v[40:41]
	v_pk_mul_f32 v[42:43], v[74:75], v[42:43]
	v_pk_fma_f32 v[40:41], v[200:201], v[40:41], v[216:217]
	v_pk_fma_f32 v[42:43], v[202:203], v[42:43], v[218:219]
	v_cvt_pk_bf16_f32 v240, v40, v41
; __device__ __forceinline__ float bf_lo(unsigned w) { return __uint_as_float(w << 16); }
; __device__ __forceinline__ float bf_hi(unsigned w) { return __uint_as_float(w & 0xffff0000u); }
; __device__ __forceinline__ unsigned pk2(float lo, float hi) { return pg8::cvt_pk_bf16(lo, hi); }
; template <bool BF> __device__ __forceinline__ void prep_rows(const float* xp, const float* xs, const bf16* hb, const float* g, const float* MOD, int shoff, int scoff, bf16* U, int gw, int NGW, int lane) {
;     ...
;         f32x4 v[R][4]; float s[R];
; #pragma unroll
;         for (int r = 0; r < R; ++r) { const int m = mb + r * NGW; const int mc = m < MT ? m : mb;
; #pragma unroll
;             for (int j = 0; j < 4; ++j) {
;                 if (BF) { const v2u a0 = *(const v2u*)(hb + (size_t)mc * DM + 4 * lane + 256 * j);
;                     v[r][j].x = pg8::bf_lo(a0.x); v[r][j].y = pg8::bf_hi(a0.x); v[r][j].z = pg8::bf_lo(a0.y); v[r][j].w = pg8::bf_hi(a0.y); }
;                 else { const float* xr = mc < MP ? xp + (size_t)mc * DM : xs + (size_t)(mc - MP) * DM; v[r][j] = *(const f32x4*)(xr + 4 * lane + 256 * j); } } }
; #pragma unroll
;         for (int r = 0; r < R; ++r) { float t = 0.f;
; #pragma unroll
;             for (int j = 0; j < 4; ++j) t += (v[r][j].x * v[r][j].x + v[r][j].y * v[r][j].y) + (v[r][j].z * v[r][j].z + v[r][j].w * v[r][j].w);
;     ...
;             for (int j = 0; j < 4; ++j) { const int c = 4 * lane + 256 * j;
;                 const f32x4 gg = *(const f32x4*)(g + c), sc = *(const f32x4*)(mr + scoff + c), sh = *(const f32x4*)(mr + shoff + c);
;                 const f32x4 o = v[r][j] * rstd * gg * (sc + 1.0f) + sh; v2u w; w.x = pk2(o.x, o.y); w.y = pk2(o.z, o.w); *(v2u*)(U + (size_t)m * DM + c) = w; } } }
	v_cvt_pk_bf16_f32 v241, v42, v43
	v_pk_mul_f32 v[44:45], v[44:45], v[236:237] op_sel_hi:[1,0]
	v_pk_mul_f32 v[46:47], v[46:47], v[236:237] op_sel_hi:[1,0]
	v_pk_mul_f32 v[44:45], v[76:77], v[44:45]
	v_pk_mul_f32 v[46:47], v[78:79], v[46:47]
	v_pk_fma_f32 v[44:45], v[204:205], v[44:45], v[220:221]
	v_pk_fma_f32 v[46:47], v[206:207], v[46:47], v[222:223]
	v_cvt_pk_bf16_f32 v242, v44, v45
	v_cvt_pk_bf16_f32 v243, v46, v47
	global_store_dwordx4 v82, v[240:243], s[46:47] offset:1024
	v_pk_mul_f32 v[48:49], v[48:49], v[238:239] op_sel_hi:[1,0]
	v_pk_mul_f32 v[50:51], v[50:51], v[238:239] op_sel_hi:[1,0]
	v_pk_mul_f32 v[48:49], v[64:65], v[48:49]
	v_pk_mul_f32 v[50:51], v[66:67], v[50:51]
	v_pk_fma_f32 v[48:49], v[192:193], v[48:49], v[208:209]
	v_pk_fma_f32 v[50:51], v[194:195], v[50:51], v[210:211]
	v_cvt_pk_bf16_f32 v244, v48, v49
	v_cvt_pk_bf16_f32 v245, v50, v51
	v_pk_mul_f32 v[52:53], v[52:53], v[238:239] op_sel_hi:[1,0]
	v_pk_mul_f32 v[54:55], v[54:55], v[238:239] op_sel_hi:[1,0]
	v_pk_mul_f32 v[52:53], v[68:69], v[52:53]
	v_pk_mul_f32 v[54:55], v[70:71], v[54:55]
	v_pk_fma_f32 v[52:53], v[196:197], v[52:53], v[212:213]
	v_pk_fma_f32 v[54:55], v[198:199], v[54:55], v[214:215]
	v_cvt_pk_bf16_f32 v246, v52, v53
	v_cvt_pk_bf16_f32 v247, v54, v55
	global_store_dwordx4 v82, v[244:247], s[48:49] offset:0
	v_pk_mul_f32 v[56:57], v[56:57], v[238:239] op_sel_hi:[1,0]
	v_pk_mul_f32 v[58:59], v[58:59], v[238:239] op_sel_hi:[1,0]
	v_pk_mul_f32 v[56:57], v[72:73], v[56:57]
	v_pk_mul_f32 v[58:59], v[74:75], v[58:59]
	v_pk_fma_f32 v[56:57], v[200:201], v[56:57], v[216:217]
	v_pk_fma_f32 v[58:59], v[202:203], v[58:59], v[218:219]
	v_cvt_pk_bf16_f32 v240, v56, v57
	v_cvt_pk_bf16_f32 v241, v58, v59
	v_pk_mul_f32 v[60:61], v[60:61], v[238:239] op_sel_hi:[1,0]
	v_pk_mul_f32 v[62:63], v[62:63], v[238:239] op_sel_hi:[1,0]
	v_pk_mul_f32 v[60:61], v[76:77], v[60:61]
	v_pk_mul_f32 v[62:63], v[78:79], v[62:63]
	v_pk_fma_f32 v[60:61], v[204:205], v[60:61], v[220:221]
	v_pk_fma_f32 v[62:63], v[206:207], v[62:63], v[222:223]
	v_cvt_pk_bf16_f32 v242, v60, v61
	v_cvt_pk_bf16_f32 v243, v62, v63
	global_store_dwordx4 v82, v[240:243], s[48:49] offset:1024
	s_add_u32 s34, s8, 0x1b000
	s_addc_u32 s35, s9, 0
	s_add_u32 s36, s8, 0x1b000
	s_addc_u32 s37, s9, 0
	global_load_dwordx4 v[176:179], v80, s[34:35] offset:0
	global_load_dwordx4 v[180:183], v80, s[34:35] offset:16
	global_load_dwordx4 v[184:187], v80, s[34:35] offset:2048
	global_load_dwordx4 v[188:191], v80, s[34:35] offset:2064
	global_load_dwordx4 v[160:163], v81, s[34:35] offset:0
	global_load_dwordx4 v[164:167], v81, s[34:35] offset:16
	global_load_dwordx4 v[168:171], v81, s[34:35] offset:2048
	global_load_dwordx4 v[172:175], v81, s[34:35] offset:2064
	global_load_dwordx4 v[208:211], v80, s[36:37] offset:0
	global_load_dwordx4 v[212:215], v80, s[36:37] offset:16
	global_load_dwordx4 v[216:219], v80, s[36:37] offset:2048
	global_load_dwordx4 v[220:223], v80, s[36:37] offset:2064
	global_load_dwordx4 v[192:195], v81, s[36:37] offset:0
	global_load_dwordx4 v[196:199], v81, s[36:37] offset:16
	global_load_dwordx4 v[200:203], v81, s[36:37] offset:2048
	global_load_dwordx4 v[204:207], v81, s[36:37] offset:2064
	s_add_u32 s24, s16, 0x5000000
	s_addc_u32 s25, s17, 0
	s_add_u32 s26, s16, 0x5400000
	s_addc_u32 s27, s17, 0
	s_add_u32 s28, s16, 0x5800000
	s_addc_u32 s29, s17, 0
	s_add_u32 s30, s16, 0x5c00000
	s_addc_u32 s31, s17, 0
	global_load_dwordx4 v[128:131], v82, s[24:25] offset:0
	global_load_dwordx4 v[132:135], v82, s[24:25] offset:1024
	global_load_dwordx4 v[136:139], v82, s[26:27] offset:0
	global_load_dwordx4 v[140:143], v82, s[26:27] offset:1024
	global_load_dwordx4 v[144:147], v82, s[28:29] offset:0
	global_load_dwordx4 v[148:151], v82, s[28:29] offset:1024
	global_load_dwordx4 v[152:155], v82, s[30:31] offset:0
	global_load_dwordx4 v[156:159], v82, s[30:31] offset:1024
	s_waitcnt vmcnt(32)
	v_lshlrev_b32_e32 v0, 16, v96
	v_and_b32_e32 v1, 0xffff0000, v96
	v_lshlrev_b32_e32 v2, 16, v97
	v_and_b32_e32 v3, 0xffff0000, v97
	v_lshlrev_b32_e32 v4, 16, v98
	v_and_b32_e32 v5, 0xffff0000, v98
	v_lshlrev_b32_e32 v6, 16, v99
	v_and_b32_e32 v7, 0xffff0000, v99
	v_lshlrev_b32_e32 v8, 16, v100
	v_and_b32_e32 v9, 0xffff0000, v100
	v_lshlrev_b32_e32 v10, 16, v101
	v_and_b32_e32 v11, 0xffff0000, v101
	v_lshlrev_b32_e32 v12, 16, v102
	v_and_b32_e32 v13, 0xffff0000, v102
	v_lshlrev_b32_e32 v14, 16, v103
	v_and_b32_e32 v15, 0xffff0000, v103
	v_lshlrev_b32_e32 v16, 16, v104
	v_and_b32_e32 v17, 0xffff0000, v104
	v_lshlrev_b32_e32 v18, 16, v105
	v_and_b32_e32 v19, 0xffff0000, v105
	v_lshlrev_b32_e32 v20, 16, v106
	v_and_b32_e32 v21, 0xffff0000, v106
	v_lshlrev_b32_e32 v22, 16, v107
	v_and_b32_e32 v23, 0xffff0000, v107
	v_lshlrev_b32_e32 v24, 16, v108
	v_and_b32_e32 v25, 0xffff0000, v108
	v_lshlrev_b32_e32 v26, 16, v109
	v_and_b32_e32 v27, 0xffff0000, v109
	v_lshlrev_b32_e32 v28, 16, v110
	v_and_b32_e32 v29, 0xffff0000, v110
	v_lshlrev_b32_e32 v30, 16, v111
	v_and_b32_e32 v31, 0xffff0000, v111
	v_lshlrev_b32_e32 v32, 16, v112
	v_and_b32_e32 v33, 0xffff0000, v112
	v_lshlrev_b32_e32 v34, 16, v113
	v_and_b32_e32 v35, 0xffff0000, v113
	v_lshlrev_b32_e32 v36, 16, v114
	v_and_b32_e32 v37, 0xffff0000, v114
	v_lshlrev_b32_e32 v38, 16, v115
	v_and_b32_e32 v39, 0xffff0000, v115
	v_lshlrev_b32_e32 v40, 16, v116
	v_and_b32_e32 v41, 0xffff0000, v116
	v_lshlrev_b32_e32 v42, 16, v117
	v_and_b32_e32 v43, 0xffff0000, v117
	v_lshlrev_b32_e32 v44, 16, v118
	v_and_b32_e32 v45, 0xffff0000, v118
	v_lshlrev_b32_e32 v46, 16, v119
	v_and_b32_e32 v47, 0xffff0000, v119
	v_lshlrev_b32_e32 v48, 16, v120
	v_and_b32_e32 v49, 0xffff0000, v120
	v_lshlrev_b32_e32 v50, 16, v121
; __device__ __forceinline__ float bf_lo(unsigned w) { return __uint_as_float(w << 16); }
; __device__ __forceinline__ float bf_hi(unsigned w) { return __uint_as_float(w & 0xffff0000u); }
; template <bool BF> __device__ __forceinline__ void prep_rows(const float* xp, const float* xs, const bf16* hb, const float* g, const float* MOD, int shoff, int scoff, bf16* U, int gw, int NGW, int lane) {
;     ...
;                     v[r][j].x = pg8::bf_lo(a0.x); v[r][j].y = pg8::bf_hi(a0.x); v[r][j].z = pg8::bf_lo(a0.y); v[r][j].w = pg8::bf_hi(a0.y); }
;                 else { const float* xr = mc < MP ? xp + (size_t)mc * DM : xs + (size_t)(mc - MP) * DM; v[r][j] = *(const f32x4*)(xr + 4 * lane + 256 * j); } } }
; #pragma unroll
;         for (int r = 0; r < R; ++r) { float t = 0.f;
; #pragma unroll
;             for (int j = 0; j < 4; ++j) t += (v[r][j].x * v[r][j].x + v[r][j].y * v[r][j].y) + (v[r][j].z * v[r][j].z + v[r][j].w * v[r][j].w);
;             s[r] = t; }
; #pragma unroll
;         for (int o = 1; o < 64; o <<= 1) {
; #pragma unroll
;             for (int r = 0; r < R; ++r) s[r] += __shfl_xor(s[r], o); }
; #pragma unroll
;         for (int r = 0; r < R; ++r) { const int m = mb + r * NGW; if (m < MT) {
;             const float rstd = 1.0f / sqrtf(s[r] * (1.0f / DM) + RMS_EPS);
	v_and_b32_e32 v51, 0xffff0000, v121
	v_lshlrev_b32_e32 v52, 16, v122
	v_and_b32_e32 v53, 0xffff0000, v122
	v_lshlrev_b32_e32 v54, 16, v123
	v_and_b32_e32 v55, 0xffff0000, v123
	v_lshlrev_b32_e32 v56, 16, v124
	v_and_b32_e32 v57, 0xffff0000, v124
	v_lshlrev_b32_e32 v58, 16, v125
	v_and_b32_e32 v59, 0xffff0000, v125
	v_lshlrev_b32_e32 v60, 16, v126
	v_and_b32_e32 v61, 0xffff0000, v126
	v_lshlrev_b32_e32 v62, 16, v127
	v_and_b32_e32 v63, 0xffff0000, v127
	v_pk_mul_f32 v[240:241], v[0:1], v[0:1]
	v_pk_mul_f32 v[242:243], v[16:17], v[16:17]
	v_pk_mul_f32 v[244:245], v[32:33], v[32:33]
	v_pk_mul_f32 v[246:247], v[48:49], v[48:49]
	v_pk_fma_f32 v[240:241], v[2:3], v[2:3], v[240:241]
	v_pk_fma_f32 v[242:243], v[18:19], v[18:19], v[242:243]
	v_pk_fma_f32 v[244:245], v[34:35], v[34:35], v[244:245]
	v_pk_fma_f32 v[246:247], v[50:51], v[50:51], v[246:247]
	v_pk_fma_f32 v[240:241], v[4:5], v[4:5], v[240:241]
	v_pk_fma_f32 v[242:243], v[20:21], v[20:21], v[242:243]
	v_pk_fma_f32 v[244:245], v[36:37], v[36:37], v[244:245]
	v_pk_fma_f32 v[246:247], v[52:53], v[52:53], v[246:247]
	v_pk_fma_f32 v[240:241], v[6:7], v[6:7], v[240:241]
	v_pk_fma_f32 v[242:243], v[22:23], v[22:23], v[242:243]
	v_pk_fma_f32 v[244:245], v[38:39], v[38:39], v[244:245]
	v_pk_fma_f32 v[246:247], v[54:55], v[54:55], v[246:247]
	v_pk_fma_f32 v[240:241], v[8:9], v[8:9], v[240:241]
	v_pk_fma_f32 v[242:243], v[24:25], v[24:25], v[242:243]
	v_pk_fma_f32 v[244:245], v[40:41], v[40:41], v[244:245]
	v_pk_fma_f32 v[246:247], v[56:57], v[56:57], v[246:247]
	v_pk_fma_f32 v[240:241], v[10:11], v[10:11], v[240:241]
	v_pk_fma_f32 v[242:243], v[26:27], v[26:27], v[242:243]
	v_pk_fma_f32 v[244:245], v[42:43], v[42:43], v[244:245]
	v_pk_fma_f32 v[246:247], v[58:59], v[58:59], v[246:247]
	v_pk_fma_f32 v[240:241], v[12:13], v[12:13], v[240:241]
	v_pk_fma_f32 v[242:243], v[28:29], v[28:29], v[242:243]
	v_pk_fma_f32 v[244:245], v[44:45], v[44:45], v[244:245]
	v_pk_fma_f32 v[246:247], v[60:61], v[60:61], v[246:247]
	v_pk_fma_f32 v[240:241], v[14:15], v[14:15], v[240:241]
	v_pk_fma_f32 v[242:243], v[30:31], v[30:31], v[242:243]
	v_pk_fma_f32 v[244:245], v[46:47], v[46:47], v[244:245]
	v_pk_fma_f32 v[246:247], v[62:63], v[62:63], v[246:247]
	v_add_f32_e32 v224, v240, v241
	v_add_f32_e32 v225, v242, v243
	v_add_f32_e32 v226, v244, v245
	v_add_f32_e32 v227, v246, v247
	ds_bpermute_b32 v228, v83, v224
	ds_bpermute_b32 v229, v83, v225
	ds_bpermute_b32 v230, v83, v226
	ds_bpermute_b32 v231, v83, v227
	s_waitcnt lgkmcnt(0)
	v_add_f32_e32 v224, v224, v228
	v_add_f32_e32 v225, v225, v229
	v_add_f32_e32 v226, v226, v230
	v_add_f32_e32 v227, v227, v231
	ds_bpermute_b32 v228, v84, v224
	ds_bpermute_b32 v229, v84, v225
	ds_bpermute_b32 v230, v84, v226
	ds_bpermute_b32 v231, v84, v227
	s_waitcnt lgkmcnt(0)
	v_add_f32_e32 v224, v224, v228
	v_add_f32_e32 v225, v225, v229
	v_add_f32_e32 v226, v226, v230
	v_add_f32_e32 v227, v227, v231
	ds_bpermute_b32 v228, v85, v224
	ds_bpermute_b32 v229, v85, v225
	ds_bpermute_b32 v230, v85, v226
	ds_bpermute_b32 v231, v85, v227
	s_waitcnt lgkmcnt(0)
	v_add_f32_e32 v224, v224, v228
	v_add_f32_e32 v225, v225, v229
	v_add_f32_e32 v226, v226, v230
	v_add_f32_e32 v227, v227, v231
	ds_bpermute_b32 v228, v86, v224
	ds_bpermute_b32 v229, v86, v225
	ds_bpermute_b32 v230, v86, v226
	ds_bpermute_b32 v231, v86, v227
	s_waitcnt lgkmcnt(0)
	v_add_f32_e32 v224, v224, v228
	v_add_f32_e32 v225, v225, v229
	v_add_f32_e32 v226, v226, v230
	v_add_f32_e32 v227, v227, v231
	ds_bpermute_b32 v228, v87, v224
	ds_bpermute_b32 v229, v87, v225
	ds_bpermute_b32 v230, v87, v226
	ds_bpermute_b32 v231, v87, v227
	s_waitcnt lgkmcnt(0)
	v_add_f32_e32 v224, v224, v228
	v_add_f32_e32 v225, v225, v229
	v_add_f32_e32 v226, v226, v230
	v_add_f32_e32 v227, v227, v231
	ds_bpermute_b32 v228, v88, v224
	ds_bpermute_b32 v229, v88, v225
	ds_bpermute_b32 v230, v88, v226
	ds_bpermute_b32 v231, v88, v227
	s_waitcnt lgkmcnt(0)
	v_add_f32_e32 v224, v224, v228
	v_add_f32_e32 v225, v225, v229
	v_add_f32_e32 v226, v226, v230
	v_add_f32_e32 v227, v227, v231
	v_fmamk_f32 v240, v224, 0x3a800000, v89
	v_mul_f32_e32 v241, 0x4f800000, v240
	v_cmp_gt_f32_e32 vcc, s54, v240
	s_nop 1
	v_cndmask_b32_e32 v247, v240, v241, vcc
	v_sqrt_f32_e32 v242, v247
	s_nop 1
	v_add_u32_e32 v243, -1, v242
	v_add_u32_e32 v244, 1, v242
	v_fma_f32 v245, -v243, v242, v247
	v_fma_f32 v246, -v244, v242, v247
	v_cmp_ge_f32_e64 s[52:53], 0, v245
	s_nop 1
	v_cndmask_b32_e64 v242, v242, v243, s[52:53]
	v_cmp_lt_f32_e64 s[52:53], 0, v246
	s_nop 1
	v_cndmask_b32_e64 v242, v242, v244, s[52:53]
	v_mul_f32_e32 v243, 0x37800000, v242
	v_cndmask_b32_e32 v242, v242, v243, vcc
	v_cmp_class_f32_e32 vcc, v247, v90
	s_nop 1
	v_cndmask_b32_e32 v247, v242, v247, vcc
	v_div_scale_f32 v248, s[52:53], v247, v247, 1.0
	v_rcp_f32_e32 v249, v248
	v_div_scale_f32 v228, vcc, 1.0, v247, 1.0
	s_nop 0
	v_fma_f32 v229, -v248, v249, 1.0
	v_fmac_f32_e32 v249, v229, v249
	v_mul_f32_e32 v230, v228, v249
	v_fma_f32 v229, -v248, v230, v228
	v_fmac_f32_e32 v230, v229, v249
	v_fma_f32 v248, -v248, v230, v228
	v_div_fmas_f32 v248, v248, v249, v230
	v_div_fixup_f32 v232, v248, v247, 1.0
	v_fmamk_f32 v240, v225, 0x3a800000, v89
	v_mul_f32_e32 v241, 0x4f800000, v240
	v_cmp_gt_f32_e32 vcc, s54, v240
	s_nop 1
	v_cndmask_b32_e32 v247, v240, v241, vcc
	v_sqrt_f32_e32 v242, v247
	s_nop 1
	v_add_u32_e32 v243, -1, v242
	v_add_u32_e32 v244, 1, v242
	v_fma_f32 v245, -v243, v242, v247
	v_fma_f32 v246, -v244, v242, v247
	v_cmp_ge_f32_e64 s[52:53], 0, v245
	s_nop 1
	v_cndmask_b32_e64 v242, v242, v243, s[52:53]
	v_cmp_lt_f32_e64 s[52:53], 0, v246
	s_nop 1
	v_cndmask_b32_e64 v242, v242, v244, s[52:53]
; __device__ __forceinline__ unsigned pk2(float lo, float hi) { return pg8::cvt_pk_bf16(lo, hi); }
; template <bool BF> __device__ __forceinline__ void prep_rows(const float* xp, const float* xs, const bf16* hb, const float* g, const float* MOD, int shoff, int scoff, bf16* U, int gw, int NGW, int lane) {
;     ...
;             const float rstd = 1.0f / sqrtf(s[r] * (1.0f / DM) + RMS_EPS);
;             const float* mr = MOD + (size_t)(m < MP ? (m >> 13) : 8 + ((m - MP) >> 12)) * 6144;
; #pragma unroll
;             for (int j = 0; j < 4; ++j) { const int c = 4 * lane + 256 * j;
;                 const f32x4 gg = *(const f32x4*)(g + c), sc = *(const f32x4*)(mr + scoff + c), sh = *(const f32x4*)(mr + shoff + c);
;                 const f32x4 o = v[r][j] * rstd * gg * (sc + 1.0f) + sh; v2u w; w.x = pk2(o.x, o.y); w.y = pk2(o.z, o.w); *(v2u*)(U + (size_t)m * DM + c) = w; } } }
	v_mul_f32_e32 v243, 0x37800000, v242
	v_cndmask_b32_e32 v242, v242, v243, vcc
	v_cmp_class_f32_e32 vcc, v247, v90
	s_nop 1
	v_cndmask_b32_e32 v247, v242, v247, vcc
	v_div_scale_f32 v248, s[52:53], v247, v247, 1.0
	v_rcp_f32_e32 v249, v248
	v_div_scale_f32 v228, vcc, 1.0, v247, 1.0
	s_nop 0
	v_fma_f32 v229, -v248, v249, 1.0
	v_fmac_f32_e32 v249, v229, v249
	v_mul_f32_e32 v230, v228, v249
	v_fma_f32 v229, -v248, v230, v228
	v_fmac_f32_e32 v230, v229, v249
	v_fma_f32 v248, -v248, v230, v228
	v_div_fmas_f32 v248, v248, v249, v230
	v_div_fixup_f32 v234, v248, v247, 1.0
	v_fmamk_f32 v240, v226, 0x3a800000, v89
	v_mul_f32_e32 v241, 0x4f800000, v240
	v_cmp_gt_f32_e32 vcc, s54, v240
	s_nop 1
	v_cndmask_b32_e32 v247, v240, v241, vcc
	v_sqrt_f32_e32 v242, v247
	s_nop 1
	v_add_u32_e32 v243, -1, v242
	v_add_u32_e32 v244, 1, v242
	v_fma_f32 v245, -v243, v242, v247
	v_fma_f32 v246, -v244, v242, v247
	v_cmp_ge_f32_e64 s[52:53], 0, v245
	s_nop 1
	v_cndmask_b32_e64 v242, v242, v243, s[52:53]
	v_cmp_lt_f32_e64 s[52:53], 0, v246
	s_nop 1
	v_cndmask_b32_e64 v242, v242, v244, s[52:53]
	v_mul_f32_e32 v243, 0x37800000, v242
	v_cndmask_b32_e32 v242, v242, v243, vcc
	v_cmp_class_f32_e32 vcc, v247, v90
	s_nop 1
	v_cndmask_b32_e32 v247, v242, v247, vcc
	v_div_scale_f32 v248, s[52:53], v247, v247, 1.0
	v_rcp_f32_e32 v249, v248
	v_div_scale_f32 v228, vcc, 1.0, v247, 1.0
	s_nop 0
	v_fma_f32 v229, -v248, v249, 1.0
	v_fmac_f32_e32 v249, v229, v249
	v_mul_f32_e32 v230, v228, v249
	v_fma_f32 v229, -v248, v230, v228
	v_fmac_f32_e32 v230, v229, v249
	v_fma_f32 v248, -v248, v230, v228
	v_div_fmas_f32 v248, v248, v249, v230
	v_div_fixup_f32 v236, v248, v247, 1.0
	v_fmamk_f32 v240, v227, 0x3a800000, v89
	v_mul_f32_e32 v241, 0x4f800000, v240
	v_cmp_gt_f32_e32 vcc, s54, v240
	s_nop 1
	v_cndmask_b32_e32 v247, v240, v241, vcc
	v_sqrt_f32_e32 v242, v247
	s_nop 1
	v_add_u32_e32 v243, -1, v242
	v_add_u32_e32 v244, 1, v242
	v_fma_f32 v245, -v243, v242, v247
	v_fma_f32 v246, -v244, v242, v247
	v_cmp_ge_f32_e64 s[52:53], 0, v245
	s_nop 1
	v_cndmask_b32_e64 v242, v242, v243, s[52:53]
	v_cmp_lt_f32_e64 s[52:53], 0, v246
	s_nop 1
	v_cndmask_b32_e64 v242, v242, v244, s[52:53]
	v_mul_f32_e32 v243, 0x37800000, v242
	v_cndmask_b32_e32 v242, v242, v243, vcc
	v_cmp_class_f32_e32 vcc, v247, v90
	s_nop 1
	v_cndmask_b32_e32 v247, v242, v247, vcc
	v_div_scale_f32 v248, s[52:53], v247, v247, 1.0
	v_rcp_f32_e32 v249, v248
	v_div_scale_f32 v228, vcc, 1.0, v247, 1.0
	s_nop 0
	v_fma_f32 v229, -v248, v249, 1.0
	v_fmac_f32_e32 v249, v229, v249
	v_mul_f32_e32 v230, v228, v249
	v_fma_f32 v229, -v248, v230, v228
	v_fmac_f32_e32 v230, v229, v249
	v_fma_f32 v248, -v248, v230, v228
	v_div_fmas_f32 v248, v248, v249, v230
	v_div_fixup_f32 v238, v248, v247, 1.0
	s_waitcnt vmcnt(8)
	v_pk_add_f32 v[160:161], v[160:161], 1.0 op_sel_hi:[1,0]
	v_pk_add_f32 v[162:163], v[162:163], 1.0 op_sel_hi:[1,0]
	v_pk_add_f32 v[164:165], v[164:165], 1.0 op_sel_hi:[1,0]
	v_pk_add_f32 v[166:167], v[166:167], 1.0 op_sel_hi:[1,0]
	v_pk_add_f32 v[168:169], v[168:169], 1.0 op_sel_hi:[1,0]
	v_pk_add_f32 v[170:171], v[170:171], 1.0 op_sel_hi:[1,0]
	v_pk_add_f32 v[172:173], v[172:173], 1.0 op_sel_hi:[1,0]
	v_pk_add_f32 v[174:175], v[174:175], 1.0 op_sel_hi:[1,0]
	v_pk_add_f32 v[192:193], v[192:193], 1.0 op_sel_hi:[1,0]
	v_pk_add_f32 v[194:195], v[194:195], 1.0 op_sel_hi:[1,0]
	v_pk_add_f32 v[196:197], v[196:197], 1.0 op_sel_hi:[1,0]
	v_pk_add_f32 v[198:199], v[198:199], 1.0 op_sel_hi:[1,0]
	v_pk_add_f32 v[200:201], v[200:201], 1.0 op_sel_hi:[1,0]
	v_pk_add_f32 v[202:203], v[202:203], 1.0 op_sel_hi:[1,0]
	v_pk_add_f32 v[204:205], v[204:205], 1.0 op_sel_hi:[1,0]
	v_pk_add_f32 v[206:207], v[206:207], 1.0 op_sel_hi:[1,0]
	s_add_u32 s38, s20, 0x4000000
	s_addc_u32 s39, s21, 0
	s_add_u32 s40, s20, 0x4400000
	s_addc_u32 s41, s21, 0
	s_add_u32 s46, s20, 0x4800000
	s_addc_u32 s47, s21, 0
	s_add_u32 s48, s20, 0x4c00000
	s_addc_u32 s49, s21, 0
	v_pk_mul_f32 v[0:1], v[0:1], v[232:233] op_sel_hi:[1,0]
	v_pk_mul_f32 v[2:3], v[2:3], v[232:233] op_sel_hi:[1,0]
	v_pk_mul_f32 v[0:1], v[64:65], v[0:1]
	v_pk_mul_f32 v[2:3], v[66:67], v[2:3]
	v_pk_fma_f32 v[0:1], v[160:161], v[0:1], v[176:177]
	v_pk_fma_f32 v[2:3], v[162:163], v[2:3], v[178:179]
	v_cvt_pk_bf16_f32 v244, v0, v1
	v_cvt_pk_bf16_f32 v245, v2, v3
	v_pk_mul_f32 v[4:5], v[4:5], v[232:233] op_sel_hi:[1,0]
	v_pk_mul_f32 v[6:7], v[6:7], v[232:233] op_sel_hi:[1,0]
	v_pk_mul_f32 v[4:5], v[68:69], v[4:5]
	v_pk_mul_f32 v[6:7], v[70:71], v[6:7]
	v_pk_fma_f32 v[4:5], v[164:165], v[4:5], v[180:181]
	v_pk_fma_f32 v[6:7], v[166:167], v[6:7], v[182:183]
	v_cvt_pk_bf16_f32 v246, v4, v5
	v_cvt_pk_bf16_f32 v247, v6, v7
	global_store_dwordx4 v82, v[244:247], s[38:39] offset:0
	v_pk_mul_f32 v[8:9], v[8:9], v[232:233] op_sel_hi:[1,0]
	v_pk_mul_f32 v[10:11], v[10:11], v[232:233] op_sel_hi:[1,0]
	v_pk_mul_f32 v[8:9], v[72:73], v[8:9]
	v_pk_mul_f32 v[10:11], v[74:75], v[10:11]
	v_pk_fma_f32 v[8:9], v[168:169], v[8:9], v[184:185]
	v_pk_fma_f32 v[10:11], v[170:171], v[10:11], v[186:187]
	v_cvt_pk_bf16_f32 v240, v8, v9
	v_cvt_pk_bf16_f32 v241, v10, v11
	v_pk_mul_f32 v[12:13], v[12:13], v[232:233] op_sel_hi:[1,0]
	v_pk_mul_f32 v[14:15], v[14:15], v[232:233] op_sel_hi:[1,0]
	v_pk_mul_f32 v[12:13], v[76:77], v[12:13]
	v_pk_mul_f32 v[14:15], v[78:79], v[14:15]
	v_pk_fma_f32 v[12:13], v[172:173], v[12:13], v[188:189]
	v_pk_fma_f32 v[14:15], v[174:175], v[14:15], v[190:191]
	v_cvt_pk_bf16_f32 v242, v12, v13
	v_cvt_pk_bf16_f32 v243, v14, v15
	global_store_dwordx4 v82, v[240:243], s[38:39] offset:1024
	v_pk_mul_f32 v[16:17], v[16:17], v[234:235] op_sel_hi:[1,0]
	v_pk_mul_f32 v[18:19], v[18:19], v[234:235] op_sel_hi:[1,0]
; __device__ __forceinline__ float bf_lo(unsigned w) { return __uint_as_float(w << 16); }
; __device__ __forceinline__ float bf_hi(unsigned w) { return __uint_as_float(w & 0xffff0000u); }
; __device__ __forceinline__ unsigned pk2(float lo, float hi) { return pg8::cvt_pk_bf16(lo, hi); }
; template <bool BF> __device__ __forceinline__ void prep_rows(const float* xp, const float* xs, const bf16* hb, const float* g, const float* MOD, int shoff, int scoff, bf16* U, int gw, int NGW, int lane) {
;     ...
;         f32x4 v[R][4]; float s[R];
; #pragma unroll
;         for (int r = 0; r < R; ++r) { const int m = mb + r * NGW; const int mc = m < MT ? m : mb;
; #pragma unroll
;             for (int j = 0; j < 4; ++j) {
;                 if (BF) { const v2u a0 = *(const v2u*)(hb + (size_t)mc * DM + 4 * lane + 256 * j);
;                     v[r][j].x = pg8::bf_lo(a0.x); v[r][j].y = pg8::bf_hi(a0.x); v[r][j].z = pg8::bf_lo(a0.y); v[r][j].w = pg8::bf_hi(a0.y); }
;                 else { const float* xr = mc < MP ? xp + (size_t)mc * DM : xs + (size_t)(mc - MP) * DM; v[r][j] = *(const f32x4*)(xr + 4 * lane + 256 * j); } } }
;     ...
;             const float* mr = MOD + (size_t)(m < MP ? (m >> 13) : 8 + ((m - MP) >> 12)) * 6144;
; #pragma unroll
;             for (int j = 0; j < 4; ++j) { const int c = 4 * lane + 256 * j;
;                 const f32x4 gg = *(const f32x4*)(g + c), sc = *(const f32x4*)(mr + scoff + c), sh = *(const f32x4*)(mr + shoff + c);
;                 const f32x4 o = v[r][j] * rstd * gg * (sc + 1.0f) + sh; v2u w; w.x = pk2(o.x, o.y); w.y = pk2(o.z, o.w); *(v2u*)(U + (size_t)m * DM + c) = w; } } }
	v_pk_mul_f32 v[16:17], v[64:65], v[16:17]
	v_pk_mul_f32 v[18:19], v[66:67], v[18:19]
	v_pk_fma_f32 v[16:17], v[160:161], v[16:17], v[176:177]
	v_pk_fma_f32 v[18:19], v[162:163], v[18:19], v[178:179]
	v_cvt_pk_bf16_f32 v244, v16, v17
	v_cvt_pk_bf16_f32 v245, v18, v19
	v_pk_mul_f32 v[20:21], v[20:21], v[234:235] op_sel_hi:[1,0]
	v_pk_mul_f32 v[22:23], v[22:23], v[234:235] op_sel_hi:[1,0]
	v_pk_mul_f32 v[20:21], v[68:69], v[20:21]
	v_pk_mul_f32 v[22:23], v[70:71], v[22:23]
	v_pk_fma_f32 v[20:21], v[164:165], v[20:21], v[180:181]
	v_pk_fma_f32 v[22:23], v[166:167], v[22:23], v[182:183]
	v_cvt_pk_bf16_f32 v246, v20, v21
	v_cvt_pk_bf16_f32 v247, v22, v23
	global_store_dwordx4 v82, v[244:247], s[40:41] offset:0
	v_pk_mul_f32 v[24:25], v[24:25], v[234:235] op_sel_hi:[1,0]
	v_pk_mul_f32 v[26:27], v[26:27], v[234:235] op_sel_hi:[1,0]
	v_pk_mul_f32 v[24:25], v[72:73], v[24:25]
	v_pk_mul_f32 v[26:27], v[74:75], v[26:27]
	v_pk_fma_f32 v[24:25], v[168:169], v[24:25], v[184:185]
	v_pk_fma_f32 v[26:27], v[170:171], v[26:27], v[186:187]
	v_cvt_pk_bf16_f32 v240, v24, v25
	v_cvt_pk_bf16_f32 v241, v26, v27
	v_pk_mul_f32 v[28:29], v[28:29], v[234:235] op_sel_hi:[1,0]
	v_pk_mul_f32 v[30:31], v[30:31], v[234:235] op_sel_hi:[1,0]
	v_pk_mul_f32 v[28:29], v[76:77], v[28:29]
	v_pk_mul_f32 v[30:31], v[78:79], v[30:31]
	v_pk_fma_f32 v[28:29], v[172:173], v[28:29], v[188:189]
	v_pk_fma_f32 v[30:31], v[174:175], v[30:31], v[190:191]
	v_cvt_pk_bf16_f32 v242, v28, v29
	v_cvt_pk_bf16_f32 v243, v30, v31
	global_store_dwordx4 v82, v[240:243], s[40:41] offset:1024
	v_pk_mul_f32 v[32:33], v[32:33], v[236:237] op_sel_hi:[1,0]
	v_pk_mul_f32 v[34:35], v[34:35], v[236:237] op_sel_hi:[1,0]
	v_pk_mul_f32 v[32:33], v[64:65], v[32:33]
	v_pk_mul_f32 v[34:35], v[66:67], v[34:35]
	v_pk_fma_f32 v[32:33], v[192:193], v[32:33], v[208:209]
	v_pk_fma_f32 v[34:35], v[194:195], v[34:35], v[210:211]
	v_cvt_pk_bf16_f32 v244, v32, v33
	v_cvt_pk_bf16_f32 v245, v34, v35
	v_pk_mul_f32 v[36:37], v[36:37], v[236:237] op_sel_hi:[1,0]
	v_pk_mul_f32 v[38:39], v[38:39], v[236:237] op_sel_hi:[1,0]
	v_pk_mul_f32 v[36:37], v[68:69], v[36:37]
	v_pk_mul_f32 v[38:39], v[70:71], v[38:39]
	v_pk_fma_f32 v[36:37], v[196:197], v[36:37], v[212:213]
	v_pk_fma_f32 v[38:39], v[198:199], v[38:39], v[214:215]
	v_cvt_pk_bf16_f32 v246, v36, v37
	v_cvt_pk_bf16_f32 v247, v38, v39
	global_store_dwordx4 v82, v[244:247], s[46:47] offset:0
	v_pk_mul_f32 v[40:41], v[40:41], v[236:237] op_sel_hi:[1,0]
	v_pk_mul_f32 v[42:43], v[42:43], v[236:237] op_sel_hi:[1,0]
	v_pk_mul_f32 v[40:41], v[72:73], v[40:41]
	v_pk_mul_f32 v[42:43], v[74:75], v[42:43]
	v_pk_fma_f32 v[40:41], v[200:201], v[40:41], v[216:217]
	v_pk_fma_f32 v[42:43], v[202:203], v[42:43], v[218:219]
	v_cvt_pk_bf16_f32 v240, v40, v41
	v_cvt_pk_bf16_f32 v241, v42, v43
	v_pk_mul_f32 v[44:45], v[44:45], v[236:237] op_sel_hi:[1,0]
	v_pk_mul_f32 v[46:47], v[46:47], v[236:237] op_sel_hi:[1,0]
	v_pk_mul_f32 v[44:45], v[76:77], v[44:45]
	v_pk_mul_f32 v[46:47], v[78:79], v[46:47]
	v_pk_fma_f32 v[44:45], v[204:205], v[44:45], v[220:221]
	v_pk_fma_f32 v[46:47], v[206:207], v[46:47], v[222:223]
	v_cvt_pk_bf16_f32 v242, v44, v45
	v_cvt_pk_bf16_f32 v243, v46, v47
	global_store_dwordx4 v82, v[240:243], s[46:47] offset:1024
	v_pk_mul_f32 v[48:49], v[48:49], v[238:239] op_sel_hi:[1,0]
	v_pk_mul_f32 v[50:51], v[50:51], v[238:239] op_sel_hi:[1,0]
	v_pk_mul_f32 v[48:49], v[64:65], v[48:49]
	v_pk_mul_f32 v[50:51], v[66:67], v[50:51]
	v_pk_fma_f32 v[48:49], v[192:193], v[48:49], v[208:209]
	v_pk_fma_f32 v[50:51], v[194:195], v[50:51], v[210:211]
	v_cvt_pk_bf16_f32 v244, v48, v49
	v_cvt_pk_bf16_f32 v245, v50, v51
	v_pk_mul_f32 v[52:53], v[52:53], v[238:239] op_sel_hi:[1,0]
	v_pk_mul_f32 v[54:55], v[54:55], v[238:239] op_sel_hi:[1,0]
	v_pk_mul_f32 v[52:53], v[68:69], v[52:53]
	v_pk_mul_f32 v[54:55], v[70:71], v[54:55]
	v_pk_fma_f32 v[52:53], v[196:197], v[52:53], v[212:213]
	v_pk_fma_f32 v[54:55], v[198:199], v[54:55], v[214:215]
	v_cvt_pk_bf16_f32 v246, v52, v53
	v_cvt_pk_bf16_f32 v247, v54, v55
	global_store_dwordx4 v82, v[244:247], s[48:49] offset:0
	v_pk_mul_f32 v[56:57], v[56:57], v[238:239] op_sel_hi:[1,0]
	v_pk_mul_f32 v[58:59], v[58:59], v[238:239] op_sel_hi:[1,0]
	v_pk_mul_f32 v[56:57], v[72:73], v[56:57]
	v_pk_mul_f32 v[58:59], v[74:75], v[58:59]
	v_pk_fma_f32 v[56:57], v[200:201], v[56:57], v[216:217]
	v_pk_fma_f32 v[58:59], v[202:203], v[58:59], v[218:219]
	v_cvt_pk_bf16_f32 v240, v56, v57
	v_cvt_pk_bf16_f32 v241, v58, v59
	v_pk_mul_f32 v[60:61], v[60:61], v[238:239] op_sel_hi:[1,0]
	v_pk_mul_f32 v[62:63], v[62:63], v[238:239] op_sel_hi:[1,0]
	v_pk_mul_f32 v[60:61], v[76:77], v[60:61]
	v_pk_mul_f32 v[62:63], v[78:79], v[62:63]
	v_pk_fma_f32 v[60:61], v[204:205], v[60:61], v[220:221]
	v_pk_fma_f32 v[62:63], v[206:207], v[62:63], v[222:223]
	v_cvt_pk_bf16_f32 v242, v60, v61
	v_cvt_pk_bf16_f32 v243, v62, v63
	global_store_dwordx4 v82, v[240:243], s[48:49] offset:1024
	s_add_u32 s34, s8, 0x21000
	s_addc_u32 s35, s9, 0
	s_add_u32 s36, s8, 0x21000
	s_addc_u32 s37, s9, 0
	global_load_dwordx4 v[176:179], v80, s[34:35] offset:0
	global_load_dwordx4 v[180:183], v80, s[34:35] offset:16
	global_load_dwordx4 v[184:187], v80, s[34:35] offset:2048
	global_load_dwordx4 v[188:191], v80, s[34:35] offset:2064
	global_load_dwordx4 v[160:163], v81, s[34:35] offset:0
	global_load_dwordx4 v[164:167], v81, s[34:35] offset:16
	global_load_dwordx4 v[168:171], v81, s[34:35] offset:2048
	global_load_dwordx4 v[172:175], v81, s[34:35] offset:2064
	global_load_dwordx4 v[208:211], v80, s[36:37] offset:0
	global_load_dwordx4 v[212:215], v80, s[36:37] offset:16
	global_load_dwordx4 v[216:219], v80, s[36:37] offset:2048
	global_load_dwordx4 v[220:223], v80, s[36:37] offset:2064
	global_load_dwordx4 v[192:195], v81, s[36:37] offset:0
	global_load_dwordx4 v[196:199], v81, s[36:37] offset:16
	global_load_dwordx4 v[200:203], v81, s[36:37] offset:2048
	global_load_dwordx4 v[204:207], v81, s[36:37] offset:2064
	s_add_u32 s24, s16, 0x6000000
	s_addc_u32 s25, s17, 0
	s_add_u32 s26, s16, 0x6400000
	s_addc_u32 s27, s17, 0
	s_add_u32 s28, s16, 0x6800000
	s_addc_u32 s29, s17, 0
	s_add_u32 s30, s16, 0x6c00000
	s_addc_u32 s31, s17, 0
	global_load_dwordx4 v[96:99], v82, s[24:25] offset:0
	global_load_dwordx4 v[100:103], v82, s[24:25] offset:1024
	global_load_dwordx4 v[104:107], v82, s[26:27] offset:0
	global_load_dwordx4 v[108:111], v82, s[26:27] offset:1024
	global_load_dwordx4 v[112:115], v82, s[28:29] offset:0
	global_load_dwordx4 v[116:119], v82, s[28:29] offset:1024
	global_load_dwordx4 v[120:123], v82, s[30:31] offset:0
	global_load_dwordx4 v[124:127], v82, s[30:31] offset:1024
	s_waitcnt vmcnt(32)
; __device__ __forceinline__ float bf_lo(unsigned w) { return __uint_as_float(w << 16); }
; __device__ __forceinline__ float bf_hi(unsigned w) { return __uint_as_float(w & 0xffff0000u); }
; template <bool BF> __device__ __forceinline__ void prep_rows(const float* xp, const float* xs, const bf16* hb, const float* g, const float* MOD, int shoff, int scoff, bf16* U, int gw, int NGW, int lane) {
;     ...
;                 if (BF) { const v2u a0 = *(const v2u*)(hb + (size_t)mc * DM + 4 * lane + 256 * j);
;                     v[r][j].x = pg8::bf_lo(a0.x); v[r][j].y = pg8::bf_hi(a0.x); v[r][j].z = pg8::bf_lo(a0.y); v[r][j].w = pg8::bf_hi(a0.y); }
;                 else { const float* xr = mc < MP ? xp + (size_t)mc * DM : xs + (size_t)(mc - MP) * DM; v[r][j] = *(const f32x4*)(xr + 4 * lane + 256 * j); } } }
; #pragma unroll
;         for (int r = 0; r < R; ++r) { float t = 0.f;
; #pragma unroll
;             for (int j = 0; j < 4; ++j) t += (v[r][j].x * v[r][j].x + v[r][j].y * v[r][j].y) + (v[r][j].z * v[r][j].z + v[r][j].w * v[r][j].w);
;             s[r] = t; }
; #pragma unroll
;         for (int o = 1; o < 64; o <<= 1) {
; #pragma unroll
;             for (int r = 0; r < R; ++r) s[r] += __shfl_xor(s[r], o); }
; #pragma unroll
	v_lshlrev_b32_e32 v0, 16, v128
	v_and_b32_e32 v1, 0xffff0000, v128
	v_lshlrev_b32_e32 v2, 16, v129
	v_and_b32_e32 v3, 0xffff0000, v129
	v_lshlrev_b32_e32 v4, 16, v130
	v_and_b32_e32 v5, 0xffff0000, v130
	v_lshlrev_b32_e32 v6, 16, v131
	v_and_b32_e32 v7, 0xffff0000, v131
	v_lshlrev_b32_e32 v8, 16, v132
	v_and_b32_e32 v9, 0xffff0000, v132
	v_lshlrev_b32_e32 v10, 16, v133
	v_and_b32_e32 v11, 0xffff0000, v133
	v_lshlrev_b32_e32 v12, 16, v134
	v_and_b32_e32 v13, 0xffff0000, v134
	v_lshlrev_b32_e32 v14, 16, v135
	v_and_b32_e32 v15, 0xffff0000, v135
	v_lshlrev_b32_e32 v16, 16, v136
	v_and_b32_e32 v17, 0xffff0000, v136
	v_lshlrev_b32_e32 v18, 16, v137
	v_and_b32_e32 v19, 0xffff0000, v137
	v_lshlrev_b32_e32 v20, 16, v138
	v_and_b32_e32 v21, 0xffff0000, v138
	v_lshlrev_b32_e32 v22, 16, v139
	v_and_b32_e32 v23, 0xffff0000, v139
	v_lshlrev_b32_e32 v24, 16, v140
	v_and_b32_e32 v25, 0xffff0000, v140
	v_lshlrev_b32_e32 v26, 16, v141
	v_and_b32_e32 v27, 0xffff0000, v141
	v_lshlrev_b32_e32 v28, 16, v142
	v_and_b32_e32 v29, 0xffff0000, v142
	v_lshlrev_b32_e32 v30, 16, v143
	v_and_b32_e32 v31, 0xffff0000, v143
	v_lshlrev_b32_e32 v32, 16, v144
	v_and_b32_e32 v33, 0xffff0000, v144
	v_lshlrev_b32_e32 v34, 16, v145
	v_and_b32_e32 v35, 0xffff0000, v145
	v_lshlrev_b32_e32 v36, 16, v146
	v_and_b32_e32 v37, 0xffff0000, v146
	v_lshlrev_b32_e32 v38, 16, v147
	v_and_b32_e32 v39, 0xffff0000, v147
	v_lshlrev_b32_e32 v40, 16, v148
	v_and_b32_e32 v41, 0xffff0000, v148
	v_lshlrev_b32_e32 v42, 16, v149
	v_and_b32_e32 v43, 0xffff0000, v149
	v_lshlrev_b32_e32 v44, 16, v150
	v_and_b32_e32 v45, 0xffff0000, v150
	v_lshlrev_b32_e32 v46, 16, v151
	v_and_b32_e32 v47, 0xffff0000, v151
	v_lshlrev_b32_e32 v48, 16, v152
	v_and_b32_e32 v49, 0xffff0000, v152
	v_lshlrev_b32_e32 v50, 16, v153
	v_and_b32_e32 v51, 0xffff0000, v153
	v_lshlrev_b32_e32 v52, 16, v154
	v_and_b32_e32 v53, 0xffff0000, v154
	v_lshlrev_b32_e32 v54, 16, v155
	v_and_b32_e32 v55, 0xffff0000, v155
	v_lshlrev_b32_e32 v56, 16, v156
	v_and_b32_e32 v57, 0xffff0000, v156
	v_lshlrev_b32_e32 v58, 16, v157
	v_and_b32_e32 v59, 0xffff0000, v157
	v_lshlrev_b32_e32 v60, 16, v158
	v_and_b32_e32 v61, 0xffff0000, v158
	v_lshlrev_b32_e32 v62, 16, v159
	v_and_b32_e32 v63, 0xffff0000, v159
	v_pk_mul_f32 v[240:241], v[0:1], v[0:1]
	v_pk_mul_f32 v[242:243], v[16:17], v[16:17]
	v_pk_mul_f32 v[244:245], v[32:33], v[32:33]
	v_pk_mul_f32 v[246:247], v[48:49], v[48:49]
	v_pk_fma_f32 v[240:241], v[2:3], v[2:3], v[240:241]
	v_pk_fma_f32 v[242:243], v[18:19], v[18:19], v[242:243]
	v_pk_fma_f32 v[244:245], v[34:35], v[34:35], v[244:245]
	v_pk_fma_f32 v[246:247], v[50:51], v[50:51], v[246:247]
	v_pk_fma_f32 v[240:241], v[4:5], v[4:5], v[240:241]
	v_pk_fma_f32 v[242:243], v[20:21], v[20:21], v[242:243]
	v_pk_fma_f32 v[244:245], v[36:37], v[36:37], v[244:245]
	v_pk_fma_f32 v[246:247], v[52:53], v[52:53], v[246:247]
	v_pk_fma_f32 v[240:241], v[6:7], v[6:7], v[240:241]
	v_pk_fma_f32 v[242:243], v[22:23], v[22:23], v[242:243]
	v_pk_fma_f32 v[244:245], v[38:39], v[38:39], v[244:245]
	v_pk_fma_f32 v[246:247], v[54:55], v[54:55], v[246:247]
	v_pk_fma_f32 v[240:241], v[8:9], v[8:9], v[240:241]
	v_pk_fma_f32 v[242:243], v[24:25], v[24:25], v[242:243]
	v_pk_fma_f32 v[244:245], v[40:41], v[40:41], v[244:245]
	v_pk_fma_f32 v[246:247], v[56:57], v[56:57], v[246:247]
	v_pk_fma_f32 v[240:241], v[10:11], v[10:11], v[240:241]
	v_pk_fma_f32 v[242:243], v[26:27], v[26:27], v[242:243]
	v_pk_fma_f32 v[244:245], v[42:43], v[42:43], v[244:245]
	v_pk_fma_f32 v[246:247], v[58:59], v[58:59], v[246:247]
	v_pk_fma_f32 v[240:241], v[12:13], v[12:13], v[240:241]
	v_pk_fma_f32 v[242:243], v[28:29], v[28:29], v[242:243]
	v_pk_fma_f32 v[244:245], v[44:45], v[44:45], v[244:245]
	v_pk_fma_f32 v[246:247], v[60:61], v[60:61], v[246:247]
	v_pk_fma_f32 v[240:241], v[14:15], v[14:15], v[240:241]
	v_pk_fma_f32 v[242:243], v[30:31], v[30:31], v[242:243]
	v_pk_fma_f32 v[244:245], v[46:47], v[46:47], v[244:245]
	v_pk_fma_f32 v[246:247], v[62:63], v[62:63], v[246:247]
	v_add_f32_e32 v224, v240, v241
	v_add_f32_e32 v225, v242, v243
	v_add_f32_e32 v226, v244, v245
	v_add_f32_e32 v227, v246, v247
	ds_bpermute_b32 v228, v83, v224
	ds_bpermute_b32 v229, v83, v225
	ds_bpermute_b32 v230, v83, v226
	ds_bpermute_b32 v231, v83, v227
	s_waitcnt lgkmcnt(0)
	v_add_f32_e32 v224, v224, v228
	v_add_f32_e32 v225, v225, v229
	v_add_f32_e32 v226, v226, v230
	v_add_f32_e32 v227, v227, v231
	ds_bpermute_b32 v228, v84, v224
	ds_bpermute_b32 v229, v84, v225
	ds_bpermute_b32 v230, v84, v226
	ds_bpermute_b32 v231, v84, v227
	s_waitcnt lgkmcnt(0)
	v_add_f32_e32 v224, v224, v228
	v_add_f32_e32 v225, v225, v229
	v_add_f32_e32 v226, v226, v230
	v_add_f32_e32 v227, v227, v231
	ds_bpermute_b32 v228, v85, v224
	ds_bpermute_b32 v229, v85, v225
	ds_bpermute_b32 v230, v85, v226
	ds_bpermute_b32 v231, v85, v227
	s_waitcnt lgkmcnt(0)
	v_add_f32_e32 v224, v224, v228
	v_add_f32_e32 v225, v225, v229
	v_add_f32_e32 v226, v226, v230
	v_add_f32_e32 v227, v227, v231
	ds_bpermute_b32 v228, v86, v224
	ds_bpermute_b32 v229, v86, v225
	ds_bpermute_b32 v230, v86, v226
	ds_bpermute_b32 v231, v86, v227
	s_waitcnt lgkmcnt(0)
	v_add_f32_e32 v224, v224, v228
	v_add_f32_e32 v225, v225, v229
	v_add_f32_e32 v226, v226, v230
	v_add_f32_e32 v227, v227, v231
	ds_bpermute_b32 v228, v87, v224
	ds_bpermute_b32 v229, v87, v225
	ds_bpermute_b32 v230, v87, v226
	ds_bpermute_b32 v231, v87, v227
	s_waitcnt lgkmcnt(0)
	v_add_f32_e32 v224, v224, v228
	v_add_f32_e32 v225, v225, v229
	v_add_f32_e32 v226, v226, v230
	v_add_f32_e32 v227, v227, v231
	ds_bpermute_b32 v228, v88, v224
	ds_bpermute_b32 v229, v88, v225
	ds_bpermute_b32 v230, v88, v226
	ds_bpermute_b32 v231, v88, v227
	s_waitcnt lgkmcnt(0)
; template <bool BF> __device__ __forceinline__ void prep_rows(const float* xp, const float* xs, const bf16* hb, const float* g, const float* MOD, int shoff, int scoff, bf16* U, int gw, int NGW, int lane) {
;     ...
;             for (int r = 0; r < R; ++r) s[r] += __shfl_xor(s[r], o); }
; #pragma unroll
;         for (int r = 0; r < R; ++r) { const int m = mb + r * NGW; if (m < MT) {
;             const float rstd = 1.0f / sqrtf(s[r] * (1.0f / DM) + RMS_EPS);
	v_add_f32_e32 v224, v224, v228
	v_add_f32_e32 v225, v225, v229
	v_add_f32_e32 v226, v226, v230
	v_add_f32_e32 v227, v227, v231
	v_fmamk_f32 v240, v224, 0x3a800000, v89
	v_mul_f32_e32 v241, 0x4f800000, v240
	v_cmp_gt_f32_e32 vcc, s54, v240
	s_nop 1
	v_cndmask_b32_e32 v247, v240, v241, vcc
	v_sqrt_f32_e32 v242, v247
	s_nop 1
	v_add_u32_e32 v243, -1, v242
	v_add_u32_e32 v244, 1, v242
	v_fma_f32 v245, -v243, v242, v247
	v_fma_f32 v246, -v244, v242, v247
	v_cmp_ge_f32_e64 s[52:53], 0, v245
	s_nop 1
	v_cndmask_b32_e64 v242, v242, v243, s[52:53]
	v_cmp_lt_f32_e64 s[52:53], 0, v246
	s_nop 1
	v_cndmask_b32_e64 v242, v242, v244, s[52:53]
	v_mul_f32_e32 v243, 0x37800000, v242
	v_cndmask_b32_e32 v242, v242, v243, vcc
	v_cmp_class_f32_e32 vcc, v247, v90
	s_nop 1
	v_cndmask_b32_e32 v247, v242, v247, vcc
	v_div_scale_f32 v248, s[52:53], v247, v247, 1.0
	v_rcp_f32_e32 v249, v248
	v_div_scale_f32 v228, vcc, 1.0, v247, 1.0
	s_nop 0
	v_fma_f32 v229, -v248, v249, 1.0
	v_fmac_f32_e32 v249, v229, v249
	v_mul_f32_e32 v230, v228, v249
	v_fma_f32 v229, -v248, v230, v228
	v_fmac_f32_e32 v230, v229, v249
	v_fma_f32 v248, -v248, v230, v228
	v_div_fmas_f32 v248, v248, v249, v230
	v_div_fixup_f32 v232, v248, v247, 1.0
	v_fmamk_f32 v240, v225, 0x3a800000, v89
	v_mul_f32_e32 v241, 0x4f800000, v240
	v_cmp_gt_f32_e32 vcc, s54, v240
	s_nop 1
	v_cndmask_b32_e32 v247, v240, v241, vcc
	v_sqrt_f32_e32 v242, v247
	s_nop 1
	v_add_u32_e32 v243, -1, v242
	v_add_u32_e32 v244, 1, v242
	v_fma_f32 v245, -v243, v242, v247
	v_fma_f32 v246, -v244, v242, v247
	v_cmp_ge_f32_e64 s[52:53], 0, v245
	s_nop 1
	v_cndmask_b32_e64 v242, v242, v243, s[52:53]
	v_cmp_lt_f32_e64 s[52:53], 0, v246
	s_nop 1
	v_cndmask_b32_e64 v242, v242, v244, s[52:53]
	v_mul_f32_e32 v243, 0x37800000, v242
	v_cndmask_b32_e32 v242, v242, v243, vcc
	v_cmp_class_f32_e32 vcc, v247, v90
	s_nop 1
	v_cndmask_b32_e32 v247, v242, v247, vcc
	v_div_scale_f32 v248, s[52:53], v247, v247, 1.0
	v_rcp_f32_e32 v249, v248
	v_div_scale_f32 v228, vcc, 1.0, v247, 1.0
	s_nop 0
	v_fma_f32 v229, -v248, v249, 1.0
	v_fmac_f32_e32 v249, v229, v249
	v_mul_f32_e32 v230, v228, v249
	v_fma_f32 v229, -v248, v230, v228
	v_fmac_f32_e32 v230, v229, v249
	v_fma_f32 v248, -v248, v230, v228
	v_div_fmas_f32 v248, v248, v249, v230
	v_div_fixup_f32 v234, v248, v247, 1.0
	v_fmamk_f32 v240, v226, 0x3a800000, v89
	v_mul_f32_e32 v241, 0x4f800000, v240
	v_cmp_gt_f32_e32 vcc, s54, v240
	s_nop 1
	v_cndmask_b32_e32 v247, v240, v241, vcc
	v_sqrt_f32_e32 v242, v247
	s_nop 1
	v_add_u32_e32 v243, -1, v242
	v_add_u32_e32 v244, 1, v242
	v_fma_f32 v245, -v243, v242, v247
	v_fma_f32 v246, -v244, v242, v247
	v_cmp_ge_f32_e64 s[52:53], 0, v245
	s_nop 1
	v_cndmask_b32_e64 v242, v242, v243, s[52:53]
	v_cmp_lt_f32_e64 s[52:53], 0, v246
	s_nop 1
	v_cndmask_b32_e64 v242, v242, v244, s[52:53]
	v_mul_f32_e32 v243, 0x37800000, v242
	v_cndmask_b32_e32 v242, v242, v243, vcc
	v_cmp_class_f32_e32 vcc, v247, v90
	s_nop 1
	v_cndmask_b32_e32 v247, v242, v247, vcc
	v_div_scale_f32 v248, s[52:53], v247, v247, 1.0
	v_rcp_f32_e32 v249, v248
	v_div_scale_f32 v228, vcc, 1.0, v247, 1.0
	s_nop 0
	v_fma_f32 v229, -v248, v249, 1.0
	v_fmac_f32_e32 v249, v229, v249
	v_mul_f32_e32 v230, v228, v249
	v_fma_f32 v229, -v248, v230, v228
	v_fmac_f32_e32 v230, v229, v249
	v_fma_f32 v248, -v248, v230, v228
	v_div_fmas_f32 v248, v248, v249, v230
	v_div_fixup_f32 v236, v248, v247, 1.0
	v_fmamk_f32 v240, v227, 0x3a800000, v89
	v_mul_f32_e32 v241, 0x4f800000, v240
	v_cmp_gt_f32_e32 vcc, s54, v240
	s_nop 1
	v_cndmask_b32_e32 v247, v240, v241, vcc
	v_sqrt_f32_e32 v242, v247
	s_nop 1
	v_add_u32_e32 v243, -1, v242
	v_add_u32_e32 v244, 1, v242
	v_fma_f32 v245, -v243, v242, v247
	v_fma_f32 v246, -v244, v242, v247
	v_cmp_ge_f32_e64 s[52:53], 0, v245
	s_nop 1
	v_cndmask_b32_e64 v242, v242, v243, s[52:53]
	v_cmp_lt_f32_e64 s[52:53], 0, v246
	s_nop 1
	v_cndmask_b32_e64 v242, v242, v244, s[52:53]
	v_mul_f32_e32 v243, 0x37800000, v242
	v_cndmask_b32_e32 v242, v242, v243, vcc
	v_cmp_class_f32_e32 vcc, v247, v90
	s_nop 1
	v_cndmask_b32_e32 v247, v242, v247, vcc
	v_div_scale_f32 v248, s[52:53], v247, v247, 1.0
	v_rcp_f32_e32 v249, v248
	v_div_scale_f32 v228, vcc, 1.0, v247, 1.0
	s_nop 0
	v_fma_f32 v229, -v248, v249, 1.0
	v_fmac_f32_e32 v249, v229, v249
	v_mul_f32_e32 v230, v228, v249
	v_fma_f32 v229, -v248, v230, v228
	v_fmac_f32_e32 v230, v229, v249
	v_fma_f32 v248, -v248, v230, v228
	v_div_fmas_f32 v248, v248, v249, v230
	v_div_fixup_f32 v238, v248, v247, 1.0
	s_waitcnt vmcnt(8)
; __device__ __forceinline__ unsigned pk2(float lo, float hi) { return pg8::cvt_pk_bf16(lo, hi); }
; template <bool BF> __device__ __forceinline__ void prep_rows(const float* xp, const float* xs, const bf16* hb, const float* g, const float* MOD, int shoff, int scoff, bf16* U, int gw, int NGW, int lane) {
;     ...
;         for (int r = 0; r < R; ++r) { const int m = mb + r * NGW; if (m < MT) {
;             const float rstd = 1.0f / sqrtf(s[r] * (1.0f / DM) + RMS_EPS);
;             const float* mr = MOD + (size_t)(m < MP ? (m >> 13) : 8 + ((m - MP) >> 12)) * 6144;
; #pragma unroll
;             for (int j = 0; j < 4; ++j) { const int c = 4 * lane + 256 * j;
;                 const f32x4 gg = *(const f32x4*)(g + c), sc = *(const f32x4*)(mr + scoff + c), sh = *(const f32x4*)(mr + shoff + c);
;                 const f32x4 o = v[r][j] * rstd * gg * (sc + 1.0f) + sh; v2u w; w.x = pk2(o.x, o.y); w.y = pk2(o.z, o.w); *(v2u*)(U + (size_t)m * DM + c) = w; } } }
	v_pk_add_f32 v[160:161], v[160:161], 1.0 op_sel_hi:[1,0]
	v_pk_add_f32 v[162:163], v[162:163], 1.0 op_sel_hi:[1,0]
	v_pk_add_f32 v[164:165], v[164:165], 1.0 op_sel_hi:[1,0]
	v_pk_add_f32 v[166:167], v[166:167], 1.0 op_sel_hi:[1,0]
	v_pk_add_f32 v[168:169], v[168:169], 1.0 op_sel_hi:[1,0]
	v_pk_add_f32 v[170:171], v[170:171], 1.0 op_sel_hi:[1,0]
	v_pk_add_f32 v[172:173], v[172:173], 1.0 op_sel_hi:[1,0]
	v_pk_add_f32 v[174:175], v[174:175], 1.0 op_sel_hi:[1,0]
	v_pk_add_f32 v[192:193], v[192:193], 1.0 op_sel_hi:[1,0]
	v_pk_add_f32 v[194:195], v[194:195], 1.0 op_sel_hi:[1,0]
	v_pk_add_f32 v[196:197], v[196:197], 1.0 op_sel_hi:[1,0]
	v_pk_add_f32 v[198:199], v[198:199], 1.0 op_sel_hi:[1,0]
	v_pk_add_f32 v[200:201], v[200:201], 1.0 op_sel_hi:[1,0]
	v_pk_add_f32 v[202:203], v[202:203], 1.0 op_sel_hi:[1,0]
	v_pk_add_f32 v[204:205], v[204:205], 1.0 op_sel_hi:[1,0]
	v_pk_add_f32 v[206:207], v[206:207], 1.0 op_sel_hi:[1,0]
	s_add_u32 s38, s20, 0x5000000
	s_addc_u32 s39, s21, 0
	s_add_u32 s40, s20, 0x5400000
	s_addc_u32 s41, s21, 0
	s_add_u32 s46, s20, 0x5800000
	s_addc_u32 s47, s21, 0
	s_add_u32 s48, s20, 0x5c00000
	s_addc_u32 s49, s21, 0
	v_pk_mul_f32 v[0:1], v[0:1], v[232:233] op_sel_hi:[1,0]
	v_pk_mul_f32 v[2:3], v[2:3], v[232:233] op_sel_hi:[1,0]
	v_pk_mul_f32 v[0:1], v[64:65], v[0:1]
	v_pk_mul_f32 v[2:3], v[66:67], v[2:3]
	v_pk_fma_f32 v[0:1], v[160:161], v[0:1], v[176:177]
	v_pk_fma_f32 v[2:3], v[162:163], v[2:3], v[178:179]
	v_cvt_pk_bf16_f32 v244, v0, v1
	v_cvt_pk_bf16_f32 v245, v2, v3
	v_pk_mul_f32 v[4:5], v[4:5], v[232:233] op_sel_hi:[1,0]
	v_pk_mul_f32 v[6:7], v[6:7], v[232:233] op_sel_hi:[1,0]
	v_pk_mul_f32 v[4:5], v[68:69], v[4:5]
	v_pk_mul_f32 v[6:7], v[70:71], v[6:7]
	v_pk_fma_f32 v[4:5], v[164:165], v[4:5], v[180:181]
	v_pk_fma_f32 v[6:7], v[166:167], v[6:7], v[182:183]
	v_cvt_pk_bf16_f32 v246, v4, v5
	v_cvt_pk_bf16_f32 v247, v6, v7
	global_store_dwordx4 v82, v[244:247], s[38:39] offset:0
	v_pk_mul_f32 v[8:9], v[8:9], v[232:233] op_sel_hi:[1,0]
	v_pk_mul_f32 v[10:11], v[10:11], v[232:233] op_sel_hi:[1,0]
	v_pk_mul_f32 v[8:9], v[72:73], v[8:9]
	v_pk_mul_f32 v[10:11], v[74:75], v[10:11]
	v_pk_fma_f32 v[8:9], v[168:169], v[8:9], v[184:185]
	v_pk_fma_f32 v[10:11], v[170:171], v[10:11], v[186:187]
	v_cvt_pk_bf16_f32 v240, v8, v9
	v_cvt_pk_bf16_f32 v241, v10, v11
	v_pk_mul_f32 v[12:13], v[12:13], v[232:233] op_sel_hi:[1,0]
	v_pk_mul_f32 v[14:15], v[14:15], v[232:233] op_sel_hi:[1,0]
	v_pk_mul_f32 v[12:13], v[76:77], v[12:13]
	v_pk_mul_f32 v[14:15], v[78:79], v[14:15]
	v_pk_fma_f32 v[12:13], v[172:173], v[12:13], v[188:189]
	v_pk_fma_f32 v[14:15], v[174:175], v[14:15], v[190:191]
	v_cvt_pk_bf16_f32 v242, v12, v13
	v_cvt_pk_bf16_f32 v243, v14, v15
	global_store_dwordx4 v82, v[240:243], s[38:39] offset:1024
	v_pk_mul_f32 v[16:17], v[16:17], v[234:235] op_sel_hi:[1,0]
	v_pk_mul_f32 v[18:19], v[18:19], v[234:235] op_sel_hi:[1,0]
	v_pk_mul_f32 v[16:17], v[64:65], v[16:17]
	v_pk_mul_f32 v[18:19], v[66:67], v[18:19]
	v_pk_fma_f32 v[16:17], v[160:161], v[16:17], v[176:177]
	v_pk_fma_f32 v[18:19], v[162:163], v[18:19], v[178:179]
	v_cvt_pk_bf16_f32 v244, v16, v17
	v_cvt_pk_bf16_f32 v245, v18, v19
	v_pk_mul_f32 v[20:21], v[20:21], v[234:235] op_sel_hi:[1,0]
	v_pk_mul_f32 v[22:23], v[22:23], v[234:235] op_sel_hi:[1,0]
	v_pk_mul_f32 v[20:21], v[68:69], v[20:21]
	v_pk_mul_f32 v[22:23], v[70:71], v[22:23]
	v_pk_fma_f32 v[20:21], v[164:165], v[20:21], v[180:181]
	v_pk_fma_f32 v[22:23], v[166:167], v[22:23], v[182:183]
	v_cvt_pk_bf16_f32 v246, v20, v21
	v_cvt_pk_bf16_f32 v247, v22, v23
	global_store_dwordx4 v82, v[244:247], s[40:41] offset:0
	v_pk_mul_f32 v[24:25], v[24:25], v[234:235] op_sel_hi:[1,0]
	v_pk_mul_f32 v[26:27], v[26:27], v[234:235] op_sel_hi:[1,0]
	v_pk_mul_f32 v[24:25], v[72:73], v[24:25]
	v_pk_mul_f32 v[26:27], v[74:75], v[26:27]
	v_pk_fma_f32 v[24:25], v[168:169], v[24:25], v[184:185]
	v_pk_fma_f32 v[26:27], v[170:171], v[26:27], v[186:187]
	v_cvt_pk_bf16_f32 v240, v24, v25
	v_cvt_pk_bf16_f32 v241, v26, v27
	v_pk_mul_f32 v[28:29], v[28:29], v[234:235] op_sel_hi:[1,0]
	v_pk_mul_f32 v[30:31], v[30:31], v[234:235] op_sel_hi:[1,0]
	v_pk_mul_f32 v[28:29], v[76:77], v[28:29]
	v_pk_mul_f32 v[30:31], v[78:79], v[30:31]
	v_pk_fma_f32 v[28:29], v[172:173], v[28:29], v[188:189]
	v_pk_fma_f32 v[30:31], v[174:175], v[30:31], v[190:191]
	v_cvt_pk_bf16_f32 v242, v28, v29
	v_cvt_pk_bf16_f32 v243, v30, v31
	global_store_dwordx4 v82, v[240:243], s[40:41] offset:1024
	v_pk_mul_f32 v[32:33], v[32:33], v[236:237] op_sel_hi:[1,0]
	v_pk_mul_f32 v[34:35], v[34:35], v[236:237] op_sel_hi:[1,0]
	v_pk_mul_f32 v[32:33], v[64:65], v[32:33]
	v_pk_mul_f32 v[34:35], v[66:67], v[34:35]
	v_pk_fma_f32 v[32:33], v[192:193], v[32:33], v[208:209]
	v_pk_fma_f32 v[34:35], v[194:195], v[34:35], v[210:211]
	v_cvt_pk_bf16_f32 v244, v32, v33
	v_cvt_pk_bf16_f32 v245, v34, v35
	v_pk_mul_f32 v[36:37], v[36:37], v[236:237] op_sel_hi:[1,0]
	v_pk_mul_f32 v[38:39], v[38:39], v[236:237] op_sel_hi:[1,0]
	v_pk_mul_f32 v[36:37], v[68:69], v[36:37]
	v_pk_mul_f32 v[38:39], v[70:71], v[38:39]
	v_pk_fma_f32 v[36:37], v[196:197], v[36:37], v[212:213]
	v_pk_fma_f32 v[38:39], v[198:199], v[38:39], v[214:215]
	v_cvt_pk_bf16_f32 v246, v36, v37
	v_cvt_pk_bf16_f32 v247, v38, v39
	global_store_dwordx4 v82, v[244:247], s[46:47] offset:0
	v_pk_mul_f32 v[40:41], v[40:41], v[236:237] op_sel_hi:[1,0]
	v_pk_mul_f32 v[42:43], v[42:43], v[236:237] op_sel_hi:[1,0]
	v_pk_mul_f32 v[40:41], v[72:73], v[40:41]
	v_pk_mul_f32 v[42:43], v[74:75], v[42:43]
	v_pk_fma_f32 v[40:41], v[200:201], v[40:41], v[216:217]
	v_pk_fma_f32 v[42:43], v[202:203], v[42:43], v[218:219]
	v_cvt_pk_bf16_f32 v240, v40, v41
; __device__ __forceinline__ float bf_lo(unsigned w) { return __uint_as_float(w << 16); }
; __device__ __forceinline__ float bf_hi(unsigned w) { return __uint_as_float(w & 0xffff0000u); }
; __device__ __forceinline__ unsigned pk2(float lo, float hi) { return pg8::cvt_pk_bf16(lo, hi); }
; template <bool BF> __device__ __forceinline__ void prep_rows(const float* xp, const float* xs, const bf16* hb, const float* g, const float* MOD, int shoff, int scoff, bf16* U, int gw, int NGW, int lane) {
;     ...
;         for (int r = 0; r < R; ++r) { const int m = mb + r * NGW; const int mc = m < MT ? m : mb;
; #pragma unroll
;             for (int j = 0; j < 4; ++j) {
;                 if (BF) { const v2u a0 = *(const v2u*)(hb + (size_t)mc * DM + 4 * lane + 256 * j);
;                     v[r][j].x = pg8::bf_lo(a0.x); v[r][j].y = pg8::bf_hi(a0.x); v[r][j].z = pg8::bf_lo(a0.y); v[r][j].w = pg8::bf_hi(a0.y); }
;                 else { const float* xr = mc < MP ? xp + (size_t)mc * DM : xs + (size_t)(mc - MP) * DM; v[r][j] = *(const f32x4*)(xr + 4 * lane + 256 * j); } } }
;     ...
;         for (int r = 0; r < R; ++r) { const int m = mb + r * NGW; if (m < MT) {
;             const float rstd = 1.0f / sqrtf(s[r] * (1.0f / DM) + RMS_EPS);
;             const float* mr = MOD + (size_t)(m < MP ? (m >> 13) : 8 + ((m - MP) >> 12)) * 6144;
; #pragma unroll
;             for (int j = 0; j < 4; ++j) { const int c = 4 * lane + 256 * j;
;                 const f32x4 gg = *(const f32x4*)(g + c), sc = *(const f32x4*)(mr + scoff + c), sh = *(const f32x4*)(mr + shoff + c);
;                 const f32x4 o = v[r][j] * rstd * gg * (sc + 1.0f) + sh; v2u w; w.x = pk2(o.x, o.y); w.y = pk2(o.z, o.w); *(v2u*)(U + (size_t)m * DM + c) = w; } } }
	v_cvt_pk_bf16_f32 v241, v42, v43
	v_pk_mul_f32 v[44:45], v[44:45], v[236:237] op_sel_hi:[1,0]
	v_pk_mul_f32 v[46:47], v[46:47], v[236:237] op_sel_hi:[1,0]
	v_pk_mul_f32 v[44:45], v[76:77], v[44:45]
	v_pk_mul_f32 v[46:47], v[78:79], v[46:47]
	v_pk_fma_f32 v[44:45], v[204:205], v[44:45], v[220:221]
	v_pk_fma_f32 v[46:47], v[206:207], v[46:47], v[222:223]
	v_cvt_pk_bf16_f32 v242, v44, v45
	v_cvt_pk_bf16_f32 v243, v46, v47
	global_store_dwordx4 v82, v[240:243], s[46:47] offset:1024
	v_pk_mul_f32 v[48:49], v[48:49], v[238:239] op_sel_hi:[1,0]
	v_pk_mul_f32 v[50:51], v[50:51], v[238:239] op_sel_hi:[1,0]
	v_pk_mul_f32 v[48:49], v[64:65], v[48:49]
	v_pk_mul_f32 v[50:51], v[66:67], v[50:51]
	v_pk_fma_f32 v[48:49], v[192:193], v[48:49], v[208:209]
	v_pk_fma_f32 v[50:51], v[194:195], v[50:51], v[210:211]
	v_cvt_pk_bf16_f32 v244, v48, v49
	v_cvt_pk_bf16_f32 v245, v50, v51
	v_pk_mul_f32 v[52:53], v[52:53], v[238:239] op_sel_hi:[1,0]
	v_pk_mul_f32 v[54:55], v[54:55], v[238:239] op_sel_hi:[1,0]
	v_pk_mul_f32 v[52:53], v[68:69], v[52:53]
	v_pk_mul_f32 v[54:55], v[70:71], v[54:55]
	v_pk_fma_f32 v[52:53], v[196:197], v[52:53], v[212:213]
	v_pk_fma_f32 v[54:55], v[198:199], v[54:55], v[214:215]
	v_cvt_pk_bf16_f32 v246, v52, v53
	v_cvt_pk_bf16_f32 v247, v54, v55
	global_store_dwordx4 v82, v[244:247], s[48:49] offset:0
	v_pk_mul_f32 v[56:57], v[56:57], v[238:239] op_sel_hi:[1,0]
	v_pk_mul_f32 v[58:59], v[58:59], v[238:239] op_sel_hi:[1,0]
	v_pk_mul_f32 v[56:57], v[72:73], v[56:57]
	v_pk_mul_f32 v[58:59], v[74:75], v[58:59]
	v_pk_fma_f32 v[56:57], v[200:201], v[56:57], v[216:217]
	v_pk_fma_f32 v[58:59], v[202:203], v[58:59], v[218:219]
	v_cvt_pk_bf16_f32 v240, v56, v57
	v_cvt_pk_bf16_f32 v241, v58, v59
	v_pk_mul_f32 v[60:61], v[60:61], v[238:239] op_sel_hi:[1,0]
	v_pk_mul_f32 v[62:63], v[62:63], v[238:239] op_sel_hi:[1,0]
	v_pk_mul_f32 v[60:61], v[76:77], v[60:61]
	v_pk_mul_f32 v[62:63], v[78:79], v[62:63]
	v_pk_fma_f32 v[60:61], v[204:205], v[60:61], v[220:221]
	v_pk_fma_f32 v[62:63], v[206:207], v[62:63], v[222:223]
	v_cvt_pk_bf16_f32 v242, v60, v61
	v_cvt_pk_bf16_f32 v243, v62, v63
	global_store_dwordx4 v82, v[240:243], s[48:49] offset:1024
	s_add_u32 s34, s8, 0x27000
	s_addc_u32 s35, s9, 0
	s_add_u32 s36, s8, 0x27000
	s_addc_u32 s37, s9, 0
	global_load_dwordx4 v[176:179], v80, s[34:35] offset:0
	global_load_dwordx4 v[180:183], v80, s[34:35] offset:16
	global_load_dwordx4 v[184:187], v80, s[34:35] offset:2048
	global_load_dwordx4 v[188:191], v80, s[34:35] offset:2064
	global_load_dwordx4 v[160:163], v81, s[34:35] offset:0
	global_load_dwordx4 v[164:167], v81, s[34:35] offset:16
	global_load_dwordx4 v[168:171], v81, s[34:35] offset:2048
	global_load_dwordx4 v[172:175], v81, s[34:35] offset:2064
	global_load_dwordx4 v[208:211], v80, s[36:37] offset:0
	global_load_dwordx4 v[212:215], v80, s[36:37] offset:16
	global_load_dwordx4 v[216:219], v80, s[36:37] offset:2048
	global_load_dwordx4 v[220:223], v80, s[36:37] offset:2064
	global_load_dwordx4 v[192:195], v81, s[36:37] offset:0
	global_load_dwordx4 v[196:199], v81, s[36:37] offset:16
	global_load_dwordx4 v[200:203], v81, s[36:37] offset:2048
	global_load_dwordx4 v[204:207], v81, s[36:37] offset:2064
	s_add_u32 s24, s16, 0x7000000
	s_addc_u32 s25, s17, 0
	s_add_u32 s26, s16, 0x7400000
	s_addc_u32 s27, s17, 0
	s_add_u32 s28, s16, 0x7800000
	s_addc_u32 s29, s17, 0
	s_add_u32 s30, s16, 0x7c00000
	s_addc_u32 s31, s17, 0
	global_load_dwordx4 v[128:131], v82, s[24:25] offset:0
	global_load_dwordx4 v[132:135], v82, s[24:25] offset:1024
	global_load_dwordx4 v[136:139], v82, s[26:27] offset:0
	global_load_dwordx4 v[140:143], v82, s[26:27] offset:1024
	global_load_dwordx4 v[144:147], v82, s[28:29] offset:0
	global_load_dwordx4 v[148:151], v82, s[28:29] offset:1024
	global_load_dwordx4 v[152:155], v82, s[30:31] offset:0
	global_load_dwordx4 v[156:159], v82, s[30:31] offset:1024
	s_waitcnt vmcnt(32)
	v_lshlrev_b32_e32 v0, 16, v96
	v_and_b32_e32 v1, 0xffff0000, v96
	v_lshlrev_b32_e32 v2, 16, v97
	v_and_b32_e32 v3, 0xffff0000, v97
	v_lshlrev_b32_e32 v4, 16, v98
	v_and_b32_e32 v5, 0xffff0000, v98
	v_lshlrev_b32_e32 v6, 16, v99
	v_and_b32_e32 v7, 0xffff0000, v99
	v_lshlrev_b32_e32 v8, 16, v100
	v_and_b32_e32 v9, 0xffff0000, v100
	v_lshlrev_b32_e32 v10, 16, v101
	v_and_b32_e32 v11, 0xffff0000, v101
	v_lshlrev_b32_e32 v12, 16, v102
	v_and_b32_e32 v13, 0xffff0000, v102
	v_lshlrev_b32_e32 v14, 16, v103
	v_and_b32_e32 v15, 0xffff0000, v103
	v_lshlrev_b32_e32 v16, 16, v104
	v_and_b32_e32 v17, 0xffff0000, v104
	v_lshlrev_b32_e32 v18, 16, v105
	v_and_b32_e32 v19, 0xffff0000, v105
	v_lshlrev_b32_e32 v20, 16, v106
	v_and_b32_e32 v21, 0xffff0000, v106
	v_lshlrev_b32_e32 v22, 16, v107
	v_and_b32_e32 v23, 0xffff0000, v107
	v_lshlrev_b32_e32 v24, 16, v108
	v_and_b32_e32 v25, 0xffff0000, v108
	v_lshlrev_b32_e32 v26, 16, v109
	v_and_b32_e32 v27, 0xffff0000, v109
	v_lshlrev_b32_e32 v28, 16, v110
	v_and_b32_e32 v29, 0xffff0000, v110
	v_lshlrev_b32_e32 v30, 16, v111
	v_and_b32_e32 v31, 0xffff0000, v111
	v_lshlrev_b32_e32 v32, 16, v112
	v_and_b32_e32 v33, 0xffff0000, v112
	v_lshlrev_b32_e32 v34, 16, v113
	v_and_b32_e32 v35, 0xffff0000, v113
	v_lshlrev_b32_e32 v36, 16, v114
	v_and_b32_e32 v37, 0xffff0000, v114
	v_lshlrev_b32_e32 v38, 16, v115
	v_and_b32_e32 v39, 0xffff0000, v115
	v_lshlrev_b32_e32 v40, 16, v116
	v_and_b32_e32 v41, 0xffff0000, v116
	v_lshlrev_b32_e32 v42, 16, v117
	v_and_b32_e32 v43, 0xffff0000, v117
	v_lshlrev_b32_e32 v44, 16, v118
	v_and_b32_e32 v45, 0xffff0000, v118
	v_lshlrev_b32_e32 v46, 16, v119
	v_and_b32_e32 v47, 0xffff0000, v119
	v_lshlrev_b32_e32 v48, 16, v120
	v_and_b32_e32 v49, 0xffff0000, v120
	v_lshlrev_b32_e32 v50, 16, v121
; __device__ __forceinline__ float bf_lo(unsigned w) { return __uint_as_float(w << 16); }
; __device__ __forceinline__ float bf_hi(unsigned w) { return __uint_as_float(w & 0xffff0000u); }
; template <bool BF> __device__ __forceinline__ void prep_rows(const float* xp, const float* xs, const bf16* hb, const float* g, const float* MOD, int shoff, int scoff, bf16* U, int gw, int NGW, int lane) {
;     ...
;                 if (BF) { const v2u a0 = *(const v2u*)(hb + (size_t)mc * DM + 4 * lane + 256 * j);
;                     v[r][j].x = pg8::bf_lo(a0.x); v[r][j].y = pg8::bf_hi(a0.x); v[r][j].z = pg8::bf_lo(a0.y); v[r][j].w = pg8::bf_hi(a0.y); }
;                 else { const float* xr = mc < MP ? xp + (size_t)mc * DM : xs + (size_t)(mc - MP) * DM; v[r][j] = *(const f32x4*)(xr + 4 * lane + 256 * j); } } }
; #pragma unroll
;         for (int r = 0; r < R; ++r) { float t = 0.f;
; #pragma unroll
;             for (int j = 0; j < 4; ++j) t += (v[r][j].x * v[r][j].x + v[r][j].y * v[r][j].y) + (v[r][j].z * v[r][j].z + v[r][j].w * v[r][j].w);
;             s[r] = t; }
; #pragma unroll
;         for (int o = 1; o < 64; o <<= 1) {
; #pragma unroll
;             for (int r = 0; r < R; ++r) s[r] += __shfl_xor(s[r], o); }
; #pragma unroll
;         for (int r = 0; r < R; ++r) { const int m = mb + r * NGW; if (m < MT) {
;             const float rstd = 1.0f / sqrtf(s[r] * (1.0f / DM) + RMS_EPS);
	v_and_b32_e32 v51, 0xffff0000, v121
	v_lshlrev_b32_e32 v52, 16, v122
	v_and_b32_e32 v53, 0xffff0000, v122
	v_lshlrev_b32_e32 v54, 16, v123
	v_and_b32_e32 v55, 0xffff0000, v123
	v_lshlrev_b32_e32 v56, 16, v124
	v_and_b32_e32 v57, 0xffff0000, v124
	v_lshlrev_b32_e32 v58, 16, v125
	v_and_b32_e32 v59, 0xffff0000, v125
	v_lshlrev_b32_e32 v60, 16, v126
	v_and_b32_e32 v61, 0xffff0000, v126
	v_lshlrev_b32_e32 v62, 16, v127
	v_and_b32_e32 v63, 0xffff0000, v127
	v_pk_mul_f32 v[240:241], v[0:1], v[0:1]
	v_pk_mul_f32 v[242:243], v[16:17], v[16:17]
	v_pk_mul_f32 v[244:245], v[32:33], v[32:33]
	v_pk_mul_f32 v[246:247], v[48:49], v[48:49]
	v_pk_fma_f32 v[240:241], v[2:3], v[2:3], v[240:241]
	v_pk_fma_f32 v[242:243], v[18:19], v[18:19], v[242:243]
	v_pk_fma_f32 v[244:245], v[34:35], v[34:35], v[244:245]
	v_pk_fma_f32 v[246:247], v[50:51], v[50:51], v[246:247]
	v_pk_fma_f32 v[240:241], v[4:5], v[4:5], v[240:241]
	v_pk_fma_f32 v[242:243], v[20:21], v[20:21], v[242:243]
	v_pk_fma_f32 v[244:245], v[36:37], v[36:37], v[244:245]
	v_pk_fma_f32 v[246:247], v[52:53], v[52:53], v[246:247]
	v_pk_fma_f32 v[240:241], v[6:7], v[6:7], v[240:241]
	v_pk_fma_f32 v[242:243], v[22:23], v[22:23], v[242:243]
	v_pk_fma_f32 v[244:245], v[38:39], v[38:39], v[244:245]
	v_pk_fma_f32 v[246:247], v[54:55], v[54:55], v[246:247]
	v_pk_fma_f32 v[240:241], v[8:9], v[8:9], v[240:241]
	v_pk_fma_f32 v[242:243], v[24:25], v[24:25], v[242:243]
	v_pk_fma_f32 v[244:245], v[40:41], v[40:41], v[244:245]
	v_pk_fma_f32 v[246:247], v[56:57], v[56:57], v[246:247]
	v_pk_fma_f32 v[240:241], v[10:11], v[10:11], v[240:241]
	v_pk_fma_f32 v[242:243], v[26:27], v[26:27], v[242:243]
	v_pk_fma_f32 v[244:245], v[42:43], v[42:43], v[244:245]
	v_pk_fma_f32 v[246:247], v[58:59], v[58:59], v[246:247]
	v_pk_fma_f32 v[240:241], v[12:13], v[12:13], v[240:241]
	v_pk_fma_f32 v[242:243], v[28:29], v[28:29], v[242:243]
	v_pk_fma_f32 v[244:245], v[44:45], v[44:45], v[244:245]
	v_pk_fma_f32 v[246:247], v[60:61], v[60:61], v[246:247]
	v_pk_fma_f32 v[240:241], v[14:15], v[14:15], v[240:241]
	v_pk_fma_f32 v[242:243], v[30:31], v[30:31], v[242:243]
	v_pk_fma_f32 v[244:245], v[46:47], v[46:47], v[244:245]
	v_pk_fma_f32 v[246:247], v[62:63], v[62:63], v[246:247]
	v_add_f32_e32 v224, v240, v241
	v_add_f32_e32 v225, v242, v243
	v_add_f32_e32 v226, v244, v245
	v_add_f32_e32 v227, v246, v247
	ds_bpermute_b32 v228, v83, v224
	ds_bpermute_b32 v229, v83, v225
	ds_bpermute_b32 v230, v83, v226
	ds_bpermute_b32 v231, v83, v227
	s_waitcnt lgkmcnt(0)
	v_add_f32_e32 v224, v224, v228
	v_add_f32_e32 v225, v225, v229
	v_add_f32_e32 v226, v226, v230
	v_add_f32_e32 v227, v227, v231
	ds_bpermute_b32 v228, v84, v224
	ds_bpermute_b32 v229, v84, v225
	ds_bpermute_b32 v230, v84, v226
	ds_bpermute_b32 v231, v84, v227
	s_waitcnt lgkmcnt(0)
	v_add_f32_e32 v224, v224, v228
	v_add_f32_e32 v225, v225, v229
	v_add_f32_e32 v226, v226, v230
	v_add_f32_e32 v227, v227, v231
	ds_bpermute_b32 v228, v85, v224
	ds_bpermute_b32 v229, v85, v225
	ds_bpermute_b32 v230, v85, v226
	ds_bpermute_b32 v231, v85, v227
	s_waitcnt lgkmcnt(0)
	v_add_f32_e32 v224, v224, v228
	v_add_f32_e32 v225, v225, v229
	v_add_f32_e32 v226, v226, v230
	v_add_f32_e32 v227, v227, v231
	ds_bpermute_b32 v228, v86, v224
	ds_bpermute_b32 v229, v86, v225
	ds_bpermute_b32 v230, v86, v226
	ds_bpermute_b32 v231, v86, v227
	s_waitcnt lgkmcnt(0)
	v_add_f32_e32 v224, v224, v228
	v_add_f32_e32 v225, v225, v229
	v_add_f32_e32 v226, v226, v230
	v_add_f32_e32 v227, v227, v231
	ds_bpermute_b32 v228, v87, v224
	ds_bpermute_b32 v229, v87, v225
	ds_bpermute_b32 v230, v87, v226
	ds_bpermute_b32 v231, v87, v227
	s_waitcnt lgkmcnt(0)
	v_add_f32_e32 v224, v224, v228
	v_add_f32_e32 v225, v225, v229
	v_add_f32_e32 v226, v226, v230
	v_add_f32_e32 v227, v227, v231
	ds_bpermute_b32 v228, v88, v224
	ds_bpermute_b32 v229, v88, v225
	ds_bpermute_b32 v230, v88, v226
	ds_bpermute_b32 v231, v88, v227
	s_waitcnt lgkmcnt(0)
	v_add_f32_e32 v224, v224, v228
	v_add_f32_e32 v225, v225, v229
	v_add_f32_e32 v226, v226, v230
	v_add_f32_e32 v227, v227, v231
	v_fmamk_f32 v240, v224, 0x3a800000, v89
	v_mul_f32_e32 v241, 0x4f800000, v240
	v_cmp_gt_f32_e32 vcc, s54, v240
	s_nop 1
	v_cndmask_b32_e32 v247, v240, v241, vcc
	v_sqrt_f32_e32 v242, v247
	s_nop 1
	v_add_u32_e32 v243, -1, v242
	v_add_u32_e32 v244, 1, v242
	v_fma_f32 v245, -v243, v242, v247
	v_fma_f32 v246, -v244, v242, v247
	v_cmp_ge_f32_e64 s[52:53], 0, v245
	s_nop 1
	v_cndmask_b32_e64 v242, v242, v243, s[52:53]
	v_cmp_lt_f32_e64 s[52:53], 0, v246
	s_nop 1
	v_cndmask_b32_e64 v242, v242, v244, s[52:53]
	v_mul_f32_e32 v243, 0x37800000, v242
	v_cndmask_b32_e32 v242, v242, v243, vcc
	v_cmp_class_f32_e32 vcc, v247, v90
	s_nop 1
	v_cndmask_b32_e32 v247, v242, v247, vcc
	v_div_scale_f32 v248, s[52:53], v247, v247, 1.0
	v_rcp_f32_e32 v249, v248
	v_div_scale_f32 v228, vcc, 1.0, v247, 1.0
	s_nop 0
	v_fma_f32 v229, -v248, v249, 1.0
	v_fmac_f32_e32 v249, v229, v249
	v_mul_f32_e32 v230, v228, v249
	v_fma_f32 v229, -v248, v230, v228
	v_fmac_f32_e32 v230, v229, v249
	v_fma_f32 v248, -v248, v230, v228
	v_div_fmas_f32 v248, v248, v249, v230
	v_div_fixup_f32 v232, v248, v247, 1.0
	v_fmamk_f32 v240, v225, 0x3a800000, v89
	v_mul_f32_e32 v241, 0x4f800000, v240
	v_cmp_gt_f32_e32 vcc, s54, v240
	s_nop 1
	v_cndmask_b32_e32 v247, v240, v241, vcc
	v_sqrt_f32_e32 v242, v247
	s_nop 1
	v_add_u32_e32 v243, -1, v242
	v_add_u32_e32 v244, 1, v242
	v_fma_f32 v245, -v243, v242, v247
	v_fma_f32 v246, -v244, v242, v247
	v_cmp_ge_f32_e64 s[52:53], 0, v245
	s_nop 1
	v_cndmask_b32_e64 v242, v242, v243, s[52:53]
	v_cmp_lt_f32_e64 s[52:53], 0, v246
	s_nop 1
	v_cndmask_b32_e64 v242, v242, v244, s[52:53]
; __device__ __forceinline__ unsigned pk2(float lo, float hi) { return pg8::cvt_pk_bf16(lo, hi); }
; template <bool BF> __device__ __forceinline__ void prep_rows(const float* xp, const float* xs, const bf16* hb, const float* g, const float* MOD, int shoff, int scoff, bf16* U, int gw, int NGW, int lane) {
;     ...
;         for (int r = 0; r < R; ++r) { const int m = mb + r * NGW; if (m < MT) {
;             const float rstd = 1.0f / sqrtf(s[r] * (1.0f / DM) + RMS_EPS);
;             const float* mr = MOD + (size_t)(m < MP ? (m >> 13) : 8 + ((m - MP) >> 12)) * 6144;
; #pragma unroll
;             for (int j = 0; j < 4; ++j) { const int c = 4 * lane + 256 * j;
;                 const f32x4 gg = *(const f32x4*)(g + c), sc = *(const f32x4*)(mr + scoff + c), sh = *(const f32x4*)(mr + shoff + c);
;                 const f32x4 o = v[r][j] * rstd * gg * (sc + 1.0f) + sh; v2u w; w.x = pk2(o.x, o.y); w.y = pk2(o.z, o.w); *(v2u*)(U + (size_t)m * DM + c) = w; } } }
	v_mul_f32_e32 v243, 0x37800000, v242
	v_cndmask_b32_e32 v242, v242, v243, vcc
	v_cmp_class_f32_e32 vcc, v247, v90
	s_nop 1
	v_cndmask_b32_e32 v247, v242, v247, vcc
	v_div_scale_f32 v248, s[52:53], v247, v247, 1.0
	v_rcp_f32_e32 v249, v248
	v_div_scale_f32 v228, vcc, 1.0, v247, 1.0
	s_nop 0
	v_fma_f32 v229, -v248, v249, 1.0
	v_fmac_f32_e32 v249, v229, v249
	v_mul_f32_e32 v230, v228, v249
	v_fma_f32 v229, -v248, v230, v228
	v_fmac_f32_e32 v230, v229, v249
	v_fma_f32 v248, -v248, v230, v228
	v_div_fmas_f32 v248, v248, v249, v230
	v_div_fixup_f32 v234, v248, v247, 1.0
	v_fmamk_f32 v240, v226, 0x3a800000, v89
	v_mul_f32_e32 v241, 0x4f800000, v240
	v_cmp_gt_f32_e32 vcc, s54, v240
	s_nop 1
	v_cndmask_b32_e32 v247, v240, v241, vcc
	v_sqrt_f32_e32 v242, v247
	s_nop 1
	v_add_u32_e32 v243, -1, v242
	v_add_u32_e32 v244, 1, v242
	v_fma_f32 v245, -v243, v242, v247
	v_fma_f32 v246, -v244, v242, v247
	v_cmp_ge_f32_e64 s[52:53], 0, v245
	s_nop 1
	v_cndmask_b32_e64 v242, v242, v243, s[52:53]
	v_cmp_lt_f32_e64 s[52:53], 0, v246
	s_nop 1
	v_cndmask_b32_e64 v242, v242, v244, s[52:53]
	v_mul_f32_e32 v243, 0x37800000, v242
	v_cndmask_b32_e32 v242, v242, v243, vcc
	v_cmp_class_f32_e32 vcc, v247, v90
	s_nop 1
	v_cndmask_b32_e32 v247, v242, v247, vcc
	v_div_scale_f32 v248, s[52:53], v247, v247, 1.0
	v_rcp_f32_e32 v249, v248
	v_div_scale_f32 v228, vcc, 1.0, v247, 1.0
	s_nop 0
	v_fma_f32 v229, -v248, v249, 1.0
	v_fmac_f32_e32 v249, v229, v249
	v_mul_f32_e32 v230, v228, v249
	v_fma_f32 v229, -v248, v230, v228
	v_fmac_f32_e32 v230, v229, v249
	v_fma_f32 v248, -v248, v230, v228
	v_div_fmas_f32 v248, v248, v249, v230
	v_div_fixup_f32 v236, v248, v247, 1.0
	v_fmamk_f32 v240, v227, 0x3a800000, v89
	v_mul_f32_e32 v241, 0x4f800000, v240
	v_cmp_gt_f32_e32 vcc, s54, v240
	s_nop 1
	v_cndmask_b32_e32 v247, v240, v241, vcc
	v_sqrt_f32_e32 v242, v247
	s_nop 1
	v_add_u32_e32 v243, -1, v242
	v_add_u32_e32 v244, 1, v242
	v_fma_f32 v245, -v243, v242, v247
	v_fma_f32 v246, -v244, v242, v247
	v_cmp_ge_f32_e64 s[52:53], 0, v245
	s_nop 1
	v_cndmask_b32_e64 v242, v242, v243, s[52:53]
	v_cmp_lt_f32_e64 s[52:53], 0, v246
	s_nop 1
	v_cndmask_b32_e64 v242, v242, v244, s[52:53]
	v_mul_f32_e32 v243, 0x37800000, v242
	v_cndmask_b32_e32 v242, v242, v243, vcc
	v_cmp_class_f32_e32 vcc, v247, v90
	s_nop 1
	v_cndmask_b32_e32 v247, v242, v247, vcc
	v_div_scale_f32 v248, s[52:53], v247, v247, 1.0
	v_rcp_f32_e32 v249, v248
	v_div_scale_f32 v228, vcc, 1.0, v247, 1.0
	s_nop 0
	v_fma_f32 v229, -v248, v249, 1.0
	v_fmac_f32_e32 v249, v229, v249
	v_mul_f32_e32 v230, v228, v249
	v_fma_f32 v229, -v248, v230, v228
	v_fmac_f32_e32 v230, v229, v249
	v_fma_f32 v248, -v248, v230, v228
	v_div_fmas_f32 v248, v248, v249, v230
	v_div_fixup_f32 v238, v248, v247, 1.0
	s_waitcnt vmcnt(8)
	v_pk_add_f32 v[160:161], v[160:161], 1.0 op_sel_hi:[1,0]
	v_pk_add_f32 v[162:163], v[162:163], 1.0 op_sel_hi:[1,0]
	v_pk_add_f32 v[164:165], v[164:165], 1.0 op_sel_hi:[1,0]
	v_pk_add_f32 v[166:167], v[166:167], 1.0 op_sel_hi:[1,0]
	v_pk_add_f32 v[168:169], v[168:169], 1.0 op_sel_hi:[1,0]
	v_pk_add_f32 v[170:171], v[170:171], 1.0 op_sel_hi:[1,0]
	v_pk_add_f32 v[172:173], v[172:173], 1.0 op_sel_hi:[1,0]
	v_pk_add_f32 v[174:175], v[174:175], 1.0 op_sel_hi:[1,0]
	v_pk_add_f32 v[192:193], v[192:193], 1.0 op_sel_hi:[1,0]
	v_pk_add_f32 v[194:195], v[194:195], 1.0 op_sel_hi:[1,0]
	v_pk_add_f32 v[196:197], v[196:197], 1.0 op_sel_hi:[1,0]
	v_pk_add_f32 v[198:199], v[198:199], 1.0 op_sel_hi:[1,0]
	v_pk_add_f32 v[200:201], v[200:201], 1.0 op_sel_hi:[1,0]
	v_pk_add_f32 v[202:203], v[202:203], 1.0 op_sel_hi:[1,0]
	v_pk_add_f32 v[204:205], v[204:205], 1.0 op_sel_hi:[1,0]
	v_pk_add_f32 v[206:207], v[206:207], 1.0 op_sel_hi:[1,0]
	s_add_u32 s38, s20, 0x6000000
	s_addc_u32 s39, s21, 0
	s_add_u32 s40, s20, 0x6400000
	s_addc_u32 s41, s21, 0
	s_add_u32 s46, s20, 0x6800000
	s_addc_u32 s47, s21, 0
	s_add_u32 s48, s20, 0x6c00000
	s_addc_u32 s49, s21, 0
	v_pk_mul_f32 v[0:1], v[0:1], v[232:233] op_sel_hi:[1,0]
	v_pk_mul_f32 v[2:3], v[2:3], v[232:233] op_sel_hi:[1,0]
	v_pk_mul_f32 v[0:1], v[64:65], v[0:1]
	v_pk_mul_f32 v[2:3], v[66:67], v[2:3]
	v_pk_fma_f32 v[0:1], v[160:161], v[0:1], v[176:177]
	v_pk_fma_f32 v[2:3], v[162:163], v[2:3], v[178:179]
	v_cvt_pk_bf16_f32 v244, v0, v1
	v_cvt_pk_bf16_f32 v245, v2, v3
	v_pk_mul_f32 v[4:5], v[4:5], v[232:233] op_sel_hi:[1,0]
	v_pk_mul_f32 v[6:7], v[6:7], v[232:233] op_sel_hi:[1,0]
	v_pk_mul_f32 v[4:5], v[68:69], v[4:5]
	v_pk_mul_f32 v[6:7], v[70:71], v[6:7]
	v_pk_fma_f32 v[4:5], v[164:165], v[4:5], v[180:181]
	v_pk_fma_f32 v[6:7], v[166:167], v[6:7], v[182:183]
	v_cvt_pk_bf16_f32 v246, v4, v5
	v_cvt_pk_bf16_f32 v247, v6, v7
	global_store_dwordx4 v82, v[244:247], s[38:39] offset:0
	v_pk_mul_f32 v[8:9], v[8:9], v[232:233] op_sel_hi:[1,0]
	v_pk_mul_f32 v[10:11], v[10:11], v[232:233] op_sel_hi:[1,0]
	v_pk_mul_f32 v[8:9], v[72:73], v[8:9]
	v_pk_mul_f32 v[10:11], v[74:75], v[10:11]
	v_pk_fma_f32 v[8:9], v[168:169], v[8:9], v[184:185]
	v_pk_fma_f32 v[10:11], v[170:171], v[10:11], v[186:187]
	v_cvt_pk_bf16_f32 v240, v8, v9
	v_cvt_pk_bf16_f32 v241, v10, v11
	v_pk_mul_f32 v[12:13], v[12:13], v[232:233] op_sel_hi:[1,0]
	v_pk_mul_f32 v[14:15], v[14:15], v[232:233] op_sel_hi:[1,0]
	v_pk_mul_f32 v[12:13], v[76:77], v[12:13]
	v_pk_mul_f32 v[14:15], v[78:79], v[14:15]
	v_pk_fma_f32 v[12:13], v[172:173], v[12:13], v[188:189]
	v_pk_fma_f32 v[14:15], v[174:175], v[14:15], v[190:191]
	v_cvt_pk_bf16_f32 v242, v12, v13
	v_cvt_pk_bf16_f32 v243, v14, v15
	global_store_dwordx4 v82, v[240:243], s[38:39] offset:1024
	v_pk_mul_f32 v[16:17], v[16:17], v[234:235] op_sel_hi:[1,0]
	v_pk_mul_f32 v[18:19], v[18:19], v[234:235] op_sel_hi:[1,0]
; __device__ __forceinline__ float bf_lo(unsigned w) { return __uint_as_float(w << 16); }
; __device__ __forceinline__ float bf_hi(unsigned w) { return __uint_as_float(w & 0xffff0000u); }
; __device__ __forceinline__ unsigned pk2(float lo, float hi) { return pg8::cvt_pk_bf16(lo, hi); }
; template <bool BF> __device__ __forceinline__ void prep_rows(const float* xp, const float* xs, const bf16* hb, const float* g, const float* MOD, int shoff, int scoff, bf16* U, int gw, int NGW, int lane) {
;     ...
;         for (int r = 0; r < R; ++r) { const int m = mb + r * NGW; const int mc = m < MT ? m : mb;
; #pragma unroll
;             for (int j = 0; j < 4; ++j) {
;                 if (BF) { const v2u a0 = *(const v2u*)(hb + (size_t)mc * DM + 4 * lane + 256 * j);
;                     v[r][j].x = pg8::bf_lo(a0.x); v[r][j].y = pg8::bf_hi(a0.x); v[r][j].z = pg8::bf_lo(a0.y); v[r][j].w = pg8::bf_hi(a0.y); }
;                 else { const float* xr = mc < MP ? xp + (size_t)mc * DM : xs + (size_t)(mc - MP) * DM; v[r][j] = *(const f32x4*)(xr + 4 * lane + 256 * j); } } }
;     ...
;         for (int r = 0; r < R; ++r) { const int m = mb + r * NGW; if (m < MT) {
;             const float rstd = 1.0f / sqrtf(s[r] * (1.0f / DM) + RMS_EPS);
;             const float* mr = MOD + (size_t)(m < MP ? (m >> 13) : 8 + ((m - MP) >> 12)) * 6144;
; #pragma unroll
;             for (int j = 0; j < 4; ++j) { const int c = 4 * lane + 256 * j;
;                 const f32x4 gg = *(const f32x4*)(g + c), sc = *(const f32x4*)(mr + scoff + c), sh = *(const f32x4*)(mr + shoff + c);
;                 const f32x4 o = v[r][j] * rstd * gg * (sc + 1.0f) + sh; v2u w; w.x = pk2(o.x, o.y); w.y = pk2(o.z, o.w); *(v2u*)(U + (size_t)m * DM + c) = w; } } }
	v_pk_mul_f32 v[16:17], v[64:65], v[16:17]
	v_pk_mul_f32 v[18:19], v[66:67], v[18:19]
	v_pk_fma_f32 v[16:17], v[160:161], v[16:17], v[176:177]
	v_pk_fma_f32 v[18:19], v[162:163], v[18:19], v[178:179]
	v_cvt_pk_bf16_f32 v244, v16, v17
	v_cvt_pk_bf16_f32 v245, v18, v19
	v_pk_mul_f32 v[20:21], v[20:21], v[234:235] op_sel_hi:[1,0]
	v_pk_mul_f32 v[22:23], v[22:23], v[234:235] op_sel_hi:[1,0]
	v_pk_mul_f32 v[20:21], v[68:69], v[20:21]
	v_pk_mul_f32 v[22:23], v[70:71], v[22:23]
	v_pk_fma_f32 v[20:21], v[164:165], v[20:21], v[180:181]
	v_pk_fma_f32 v[22:23], v[166:167], v[22:23], v[182:183]
	v_cvt_pk_bf16_f32 v246, v20, v21
	v_cvt_pk_bf16_f32 v247, v22, v23
	global_store_dwordx4 v82, v[244:247], s[40:41] offset:0
	v_pk_mul_f32 v[24:25], v[24:25], v[234:235] op_sel_hi:[1,0]
	v_pk_mul_f32 v[26:27], v[26:27], v[234:235] op_sel_hi:[1,0]
	v_pk_mul_f32 v[24:25], v[72:73], v[24:25]
	v_pk_mul_f32 v[26:27], v[74:75], v[26:27]
	v_pk_fma_f32 v[24:25], v[168:169], v[24:25], v[184:185]
	v_pk_fma_f32 v[26:27], v[170:171], v[26:27], v[186:187]
	v_cvt_pk_bf16_f32 v240, v24, v25
	v_cvt_pk_bf16_f32 v241, v26, v27
	v_pk_mul_f32 v[28:29], v[28:29], v[234:235] op_sel_hi:[1,0]
	v_pk_mul_f32 v[30:31], v[30:31], v[234:235] op_sel_hi:[1,0]
	v_pk_mul_f32 v[28:29], v[76:77], v[28:29]
	v_pk_mul_f32 v[30:31], v[78:79], v[30:31]
	v_pk_fma_f32 v[28:29], v[172:173], v[28:29], v[188:189]
	v_pk_fma_f32 v[30:31], v[174:175], v[30:31], v[190:191]
	v_cvt_pk_bf16_f32 v242, v28, v29
	v_cvt_pk_bf16_f32 v243, v30, v31
	global_store_dwordx4 v82, v[240:243], s[40:41] offset:1024
	v_pk_mul_f32 v[32:33], v[32:33], v[236:237] op_sel_hi:[1,0]
	v_pk_mul_f32 v[34:35], v[34:35], v[236:237] op_sel_hi:[1,0]
	v_pk_mul_f32 v[32:33], v[64:65], v[32:33]
	v_pk_mul_f32 v[34:35], v[66:67], v[34:35]
	v_pk_fma_f32 v[32:33], v[192:193], v[32:33], v[208:209]
	v_pk_fma_f32 v[34:35], v[194:195], v[34:35], v[210:211]
	v_cvt_pk_bf16_f32 v244, v32, v33
	v_cvt_pk_bf16_f32 v245, v34, v35
	v_pk_mul_f32 v[36:37], v[36:37], v[236:237] op_sel_hi:[1,0]
	v_pk_mul_f32 v[38:39], v[38:39], v[236:237] op_sel_hi:[1,0]
	v_pk_mul_f32 v[36:37], v[68:69], v[36:37]
	v_pk_mul_f32 v[38:39], v[70:71], v[38:39]
	v_pk_fma_f32 v[36:37], v[196:197], v[36:37], v[212:213]
	v_pk_fma_f32 v[38:39], v[198:199], v[38:39], v[214:215]
	v_cvt_pk_bf16_f32 v246, v36, v37
	v_cvt_pk_bf16_f32 v247, v38, v39
	global_store_dwordx4 v82, v[244:247], s[46:47] offset:0
	v_pk_mul_f32 v[40:41], v[40:41], v[236:237] op_sel_hi:[1,0]
	v_pk_mul_f32 v[42:43], v[42:43], v[236:237] op_sel_hi:[1,0]
	v_pk_mul_f32 v[40:41], v[72:73], v[40:41]
	v_pk_mul_f32 v[42:43], v[74:75], v[42:43]
	v_pk_fma_f32 v[40:41], v[200:201], v[40:41], v[216:217]
	v_pk_fma_f32 v[42:43], v[202:203], v[42:43], v[218:219]
	v_cvt_pk_bf16_f32 v240, v40, v41
	v_cvt_pk_bf16_f32 v241, v42, v43
	v_pk_mul_f32 v[44:45], v[44:45], v[236:237] op_sel_hi:[1,0]
	v_pk_mul_f32 v[46:47], v[46:47], v[236:237] op_sel_hi:[1,0]
	v_pk_mul_f32 v[44:45], v[76:77], v[44:45]
	v_pk_mul_f32 v[46:47], v[78:79], v[46:47]
	v_pk_fma_f32 v[44:45], v[204:205], v[44:45], v[220:221]
	v_pk_fma_f32 v[46:47], v[206:207], v[46:47], v[222:223]
	v_cvt_pk_bf16_f32 v242, v44, v45
	v_cvt_pk_bf16_f32 v243, v46, v47
	global_store_dwordx4 v82, v[240:243], s[46:47] offset:1024
	v_pk_mul_f32 v[48:49], v[48:49], v[238:239] op_sel_hi:[1,0]
	v_pk_mul_f32 v[50:51], v[50:51], v[238:239] op_sel_hi:[1,0]
	v_pk_mul_f32 v[48:49], v[64:65], v[48:49]
	v_pk_mul_f32 v[50:51], v[66:67], v[50:51]
	v_pk_fma_f32 v[48:49], v[192:193], v[48:49], v[208:209]
	v_pk_fma_f32 v[50:51], v[194:195], v[50:51], v[210:211]
	v_cvt_pk_bf16_f32 v244, v48, v49
	v_cvt_pk_bf16_f32 v245, v50, v51
	v_pk_mul_f32 v[52:53], v[52:53], v[238:239] op_sel_hi:[1,0]
	v_pk_mul_f32 v[54:55], v[54:55], v[238:239] op_sel_hi:[1,0]
	v_pk_mul_f32 v[52:53], v[68:69], v[52:53]
	v_pk_mul_f32 v[54:55], v[70:71], v[54:55]
	v_pk_fma_f32 v[52:53], v[196:197], v[52:53], v[212:213]
	v_pk_fma_f32 v[54:55], v[198:199], v[54:55], v[214:215]
	v_cvt_pk_bf16_f32 v246, v52, v53
	v_cvt_pk_bf16_f32 v247, v54, v55
	global_store_dwordx4 v82, v[244:247], s[48:49] offset:0
	v_pk_mul_f32 v[56:57], v[56:57], v[238:239] op_sel_hi:[1,0]
	v_pk_mul_f32 v[58:59], v[58:59], v[238:239] op_sel_hi:[1,0]
	v_pk_mul_f32 v[56:57], v[72:73], v[56:57]
	v_pk_mul_f32 v[58:59], v[74:75], v[58:59]
	v_pk_fma_f32 v[56:57], v[200:201], v[56:57], v[216:217]
	v_pk_fma_f32 v[58:59], v[202:203], v[58:59], v[218:219]
	v_cvt_pk_bf16_f32 v240, v56, v57
	v_cvt_pk_bf16_f32 v241, v58, v59
	v_pk_mul_f32 v[60:61], v[60:61], v[238:239] op_sel_hi:[1,0]
	v_pk_mul_f32 v[62:63], v[62:63], v[238:239] op_sel_hi:[1,0]
	v_pk_mul_f32 v[60:61], v[76:77], v[60:61]
	v_pk_mul_f32 v[62:63], v[78:79], v[62:63]
	v_pk_fma_f32 v[60:61], v[204:205], v[60:61], v[220:221]
	v_pk_fma_f32 v[62:63], v[206:207], v[62:63], v[222:223]
	v_cvt_pk_bf16_f32 v242, v60, v61
	v_cvt_pk_bf16_f32 v243, v62, v63
	global_store_dwordx4 v82, v[240:243], s[48:49] offset:1024
	s_add_u32 s34, s8, 0x2d000
	s_addc_u32 s35, s9, 0
	s_add_u32 s36, s8, 0x2d000
	s_addc_u32 s37, s9, 0
	global_load_dwordx4 v[176:179], v80, s[34:35] offset:0
	global_load_dwordx4 v[180:183], v80, s[34:35] offset:16
	global_load_dwordx4 v[184:187], v80, s[34:35] offset:2048
	global_load_dwordx4 v[188:191], v80, s[34:35] offset:2064
	global_load_dwordx4 v[160:163], v81, s[34:35] offset:0
	global_load_dwordx4 v[164:167], v81, s[34:35] offset:16
	global_load_dwordx4 v[168:171], v81, s[34:35] offset:2048
	global_load_dwordx4 v[172:175], v81, s[34:35] offset:2064
	global_load_dwordx4 v[208:211], v80, s[36:37] offset:0
	global_load_dwordx4 v[212:215], v80, s[36:37] offset:16
	global_load_dwordx4 v[216:219], v80, s[36:37] offset:2048
	global_load_dwordx4 v[220:223], v80, s[36:37] offset:2064
	global_load_dwordx4 v[192:195], v81, s[36:37] offset:0
	global_load_dwordx4 v[196:199], v81, s[36:37] offset:16
	global_load_dwordx4 v[200:203], v81, s[36:37] offset:2048
	global_load_dwordx4 v[204:207], v81, s[36:37] offset:2064
	s_add_u32 s24, s16, 0x8000000
	s_addc_u32 s25, s17, 0
	s_add_u32 s26, s16, 0x8400000
	s_addc_u32 s27, s17, 0
	s_add_u32 s28, s16, 0x8800000
	s_addc_u32 s29, s17, 0
	s_add_u32 s30, s16, 0x8c00000
	s_addc_u32 s31, s17, 0
	global_load_dwordx4 v[96:99], v82, s[24:25] offset:0
	global_load_dwordx4 v[100:103], v82, s[24:25] offset:1024
	global_load_dwordx4 v[104:107], v82, s[26:27] offset:0
	global_load_dwordx4 v[108:111], v82, s[26:27] offset:1024
	global_load_dwordx4 v[112:115], v82, s[28:29] offset:0
	global_load_dwordx4 v[116:119], v82, s[28:29] offset:1024
	global_load_dwordx4 v[120:123], v82, s[30:31] offset:0
	global_load_dwordx4 v[124:127], v82, s[30:31] offset:1024
	s_waitcnt vmcnt(32)
; __device__ __forceinline__ float bf_lo(unsigned w) { return __uint_as_float(w << 16); }
; __device__ __forceinline__ float bf_hi(unsigned w) { return __uint_as_float(w & 0xffff0000u); }
; template <bool BF> __device__ __forceinline__ void prep_rows(const float* xp, const float* xs, const bf16* hb, const float* g, const float* MOD, int shoff, int scoff, bf16* U, int gw, int NGW, int lane) {
;     ...
;                 if (BF) { const v2u a0 = *(const v2u*)(hb + (size_t)mc * DM + 4 * lane + 256 * j);
;                     v[r][j].x = pg8::bf_lo(a0.x); v[r][j].y = pg8::bf_hi(a0.x); v[r][j].z = pg8::bf_lo(a0.y); v[r][j].w = pg8::bf_hi(a0.y); }
;                 else { const float* xr = mc < MP ? xp + (size_t)mc * DM : xs + (size_t)(mc - MP) * DM; v[r][j] = *(const f32x4*)(xr + 4 * lane + 256 * j); } } }
; #pragma unroll
;         for (int r = 0; r < R; ++r) { float t = 0.f;
; #pragma unroll
;             for (int j = 0; j < 4; ++j) t += (v[r][j].x * v[r][j].x + v[r][j].y * v[r][j].y) + (v[r][j].z * v[r][j].z + v[r][j].w * v[r][j].w);
;             s[r] = t; }
; #pragma unroll
;         for (int o = 1; o < 64; o <<= 1) {
; #pragma unroll
;             for (int r = 0; r < R; ++r) s[r] += __shfl_xor(s[r], o); }
	v_lshlrev_b32_e32 v0, 16, v128
	v_and_b32_e32 v1, 0xffff0000, v128
	v_lshlrev_b32_e32 v2, 16, v129
	v_and_b32_e32 v3, 0xffff0000, v129
	v_lshlrev_b32_e32 v4, 16, v130
	v_and_b32_e32 v5, 0xffff0000, v130
	v_lshlrev_b32_e32 v6, 16, v131
	v_and_b32_e32 v7, 0xffff0000, v131
	v_lshlrev_b32_e32 v8, 16, v132
	v_and_b32_e32 v9, 0xffff0000, v132
	v_lshlrev_b32_e32 v10, 16, v133
	v_and_b32_e32 v11, 0xffff0000, v133
	v_lshlrev_b32_e32 v12, 16, v134
	v_and_b32_e32 v13, 0xffff0000, v134
	v_lshlrev_b32_e32 v14, 16, v135
	v_and_b32_e32 v15, 0xffff0000, v135
	v_lshlrev_b32_e32 v16, 16, v136
	v_and_b32_e32 v17, 0xffff0000, v136
	v_lshlrev_b32_e32 v18, 16, v137
	v_and_b32_e32 v19, 0xffff0000, v137
	v_lshlrev_b32_e32 v20, 16, v138
	v_and_b32_e32 v21, 0xffff0000, v138
	v_lshlrev_b32_e32 v22, 16, v139
	v_and_b32_e32 v23, 0xffff0000, v139
	v_lshlrev_b32_e32 v24, 16, v140
	v_and_b32_e32 v25, 0xffff0000, v140
	v_lshlrev_b32_e32 v26, 16, v141
	v_and_b32_e32 v27, 0xffff0000, v141
	v_lshlrev_b32_e32 v28, 16, v142
	v_and_b32_e32 v29, 0xffff0000, v142
	v_lshlrev_b32_e32 v30, 16, v143
	v_and_b32_e32 v31, 0xffff0000, v143
	v_lshlrev_b32_e32 v32, 16, v144
	v_and_b32_e32 v33, 0xffff0000, v144
	v_lshlrev_b32_e32 v34, 16, v145
	v_and_b32_e32 v35, 0xffff0000, v145
	v_lshlrev_b32_e32 v36, 16, v146
	v_and_b32_e32 v37, 0xffff0000, v146
	v_lshlrev_b32_e32 v38, 16, v147
	v_and_b32_e32 v39, 0xffff0000, v147
	v_lshlrev_b32_e32 v40, 16, v148
	v_and_b32_e32 v41, 0xffff0000, v148
	v_lshlrev_b32_e32 v42, 16, v149
	v_and_b32_e32 v43, 0xffff0000, v149
	v_lshlrev_b32_e32 v44, 16, v150
	v_and_b32_e32 v45, 0xffff0000, v150
	v_lshlrev_b32_e32 v46, 16, v151
	v_and_b32_e32 v47, 0xffff0000, v151
	v_lshlrev_b32_e32 v48, 16, v152
	v_and_b32_e32 v49, 0xffff0000, v152
	v_lshlrev_b32_e32 v50, 16, v153
	v_and_b32_e32 v51, 0xffff0000, v153
	v_lshlrev_b32_e32 v52, 16, v154
	v_and_b32_e32 v53, 0xffff0000, v154
	v_lshlrev_b32_e32 v54, 16, v155
	v_and_b32_e32 v55, 0xffff0000, v155
	v_lshlrev_b32_e32 v56, 16, v156
	v_and_b32_e32 v57, 0xffff0000, v156
	v_lshlrev_b32_e32 v58, 16, v157
	v_and_b32_e32 v59, 0xffff0000, v157
	v_lshlrev_b32_e32 v60, 16, v158
	v_and_b32_e32 v61, 0xffff0000, v158
	v_lshlrev_b32_e32 v62, 16, v159
	v_and_b32_e32 v63, 0xffff0000, v159
	v_pk_mul_f32 v[240:241], v[0:1], v[0:1]
	v_pk_mul_f32 v[242:243], v[16:17], v[16:17]
	v_pk_mul_f32 v[244:245], v[32:33], v[32:33]
	v_pk_mul_f32 v[246:247], v[48:49], v[48:49]
	v_pk_fma_f32 v[240:241], v[2:3], v[2:3], v[240:241]
	v_pk_fma_f32 v[242:243], v[18:19], v[18:19], v[242:243]
	v_pk_fma_f32 v[244:245], v[34:35], v[34:35], v[244:245]
	v_pk_fma_f32 v[246:247], v[50:51], v[50:51], v[246:247]
	v_pk_fma_f32 v[240:241], v[4:5], v[4:5], v[240:241]
	v_pk_fma_f32 v[242:243], v[20:21], v[20:21], v[242:243]
	v_pk_fma_f32 v[244:245], v[36:37], v[36:37], v[244:245]
	v_pk_fma_f32 v[246:247], v[52:53], v[52:53], v[246:247]
	v_pk_fma_f32 v[240:241], v[6:7], v[6:7], v[240:241]
	v_pk_fma_f32 v[242:243], v[22:23], v[22:23], v[242:243]
	v_pk_fma_f32 v[244:245], v[38:39], v[38:39], v[244:245]
	v_pk_fma_f32 v[246:247], v[54:55], v[54:55], v[246:247]
	v_pk_fma_f32 v[240:241], v[8:9], v[8:9], v[240:241]
	v_pk_fma_f32 v[242:243], v[24:25], v[24:25], v[242:243]
	v_pk_fma_f32 v[244:245], v[40:41], v[40:41], v[244:245]
	v_pk_fma_f32 v[246:247], v[56:57], v[56:57], v[246:247]
	v_pk_fma_f32 v[240:241], v[10:11], v[10:11], v[240:241]
	v_pk_fma_f32 v[242:243], v[26:27], v[26:27], v[242:243]
	v_pk_fma_f32 v[244:245], v[42:43], v[42:43], v[244:245]
	v_pk_fma_f32 v[246:247], v[58:59], v[58:59], v[246:247]
	v_pk_fma_f32 v[240:241], v[12:13], v[12:13], v[240:241]
	v_pk_fma_f32 v[242:243], v[28:29], v[28:29], v[242:243]
	v_pk_fma_f32 v[244:245], v[44:45], v[44:45], v[244:245]
	v_pk_fma_f32 v[246:247], v[60:61], v[60:61], v[246:247]
	v_pk_fma_f32 v[240:241], v[14:15], v[14:15], v[240:241]
	v_pk_fma_f32 v[242:243], v[30:31], v[30:31], v[242:243]
	v_pk_fma_f32 v[244:245], v[46:47], v[46:47], v[244:245]
	v_pk_fma_f32 v[246:247], v[62:63], v[62:63], v[246:247]
	v_add_f32_e32 v224, v240, v241
	v_add_f32_e32 v225, v242, v243
	v_add_f32_e32 v226, v244, v245
	v_add_f32_e32 v227, v246, v247
	ds_bpermute_b32 v228, v83, v224
	ds_bpermute_b32 v229, v83, v225
	ds_bpermute_b32 v230, v83, v226
	ds_bpermute_b32 v231, v83, v227
	s_waitcnt lgkmcnt(0)
	v_add_f32_e32 v224, v224, v228
	v_add_f32_e32 v225, v225, v229
	v_add_f32_e32 v226, v226, v230
	v_add_f32_e32 v227, v227, v231
	ds_bpermute_b32 v228, v84, v224
	ds_bpermute_b32 v229, v84, v225
	ds_bpermute_b32 v230, v84, v226
	ds_bpermute_b32 v231, v84, v227
	s_waitcnt lgkmcnt(0)
	v_add_f32_e32 v224, v224, v228
	v_add_f32_e32 v225, v225, v229
	v_add_f32_e32 v226, v226, v230
	v_add_f32_e32 v227, v227, v231
	ds_bpermute_b32 v228, v85, v224
	ds_bpermute_b32 v229, v85, v225
	ds_bpermute_b32 v230, v85, v226
	ds_bpermute_b32 v231, v85, v227
	s_waitcnt lgkmcnt(0)
	v_add_f32_e32 v224, v224, v228
	v_add_f32_e32 v225, v225, v229
	v_add_f32_e32 v226, v226, v230
	v_add_f32_e32 v227, v227, v231
	ds_bpermute_b32 v228, v86, v224
	ds_bpermute_b32 v229, v86, v225
	ds_bpermute_b32 v230, v86, v226
	ds_bpermute_b32 v231, v86, v227
	s_waitcnt lgkmcnt(0)
	v_add_f32_e32 v224, v224, v228
	v_add_f32_e32 v225, v225, v229
	v_add_f32_e32 v226, v226, v230
	v_add_f32_e32 v227, v227, v231
	ds_bpermute_b32 v228, v87, v224
	ds_bpermute_b32 v229, v87, v225
	ds_bpermute_b32 v230, v87, v226
	ds_bpermute_b32 v231, v87, v227
	s_waitcnt lgkmcnt(0)
	v_add_f32_e32 v224, v224, v228
	v_add_f32_e32 v225, v225, v229
	v_add_f32_e32 v226, v226, v230
	v_add_f32_e32 v227, v227, v231
	ds_bpermute_b32 v228, v88, v224
	ds_bpermute_b32 v229, v88, v225
	ds_bpermute_b32 v230, v88, v226
	ds_bpermute_b32 v231, v88, v227
	s_waitcnt lgkmcnt(0)
; template <bool BF> __device__ __forceinline__ void prep_rows(const float* xp, const float* xs, const bf16* hb, const float* g, const float* MOD, int shoff, int scoff, bf16* U, int gw, int NGW, int lane) {
;     ...
;             for (int r = 0; r < R; ++r) s[r] += __shfl_xor(s[r], o); }
; #pragma unroll
;         for (int r = 0; r < R; ++r) { const int m = mb + r * NGW; if (m < MT) {
;             const float rstd = 1.0f / sqrtf(s[r] * (1.0f / DM) + RMS_EPS);
	v_add_f32_e32 v224, v224, v228
	v_add_f32_e32 v225, v225, v229
	v_add_f32_e32 v226, v226, v230
	v_add_f32_e32 v227, v227, v231
	v_fmamk_f32 v240, v224, 0x3a800000, v89
	v_mul_f32_e32 v241, 0x4f800000, v240
	v_cmp_gt_f32_e32 vcc, s54, v240
	s_nop 1
	v_cndmask_b32_e32 v247, v240, v241, vcc
	v_sqrt_f32_e32 v242, v247
	s_nop 1
	v_add_u32_e32 v243, -1, v242
	v_add_u32_e32 v244, 1, v242
	v_fma_f32 v245, -v243, v242, v247
	v_fma_f32 v246, -v244, v242, v247
	v_cmp_ge_f32_e64 s[52:53], 0, v245
	s_nop 1
	v_cndmask_b32_e64 v242, v242, v243, s[52:53]
	v_cmp_lt_f32_e64 s[52:53], 0, v246
	s_nop 1
	v_cndmask_b32_e64 v242, v242, v244, s[52:53]
	v_mul_f32_e32 v243, 0x37800000, v242
	v_cndmask_b32_e32 v242, v242, v243, vcc
	v_cmp_class_f32_e32 vcc, v247, v90
	s_nop 1
	v_cndmask_b32_e32 v247, v242, v247, vcc
	v_div_scale_f32 v248, s[52:53], v247, v247, 1.0
	v_rcp_f32_e32 v249, v248
	v_div_scale_f32 v228, vcc, 1.0, v247, 1.0
	s_nop 0
	v_fma_f32 v229, -v248, v249, 1.0
	v_fmac_f32_e32 v249, v229, v249
	v_mul_f32_e32 v230, v228, v249
	v_fma_f32 v229, -v248, v230, v228
	v_fmac_f32_e32 v230, v229, v249
	v_fma_f32 v248, -v248, v230, v228
	v_div_fmas_f32 v248, v248, v249, v230
	v_div_fixup_f32 v232, v248, v247, 1.0
	v_fmamk_f32 v240, v225, 0x3a800000, v89
	v_mul_f32_e32 v241, 0x4f800000, v240
	v_cmp_gt_f32_e32 vcc, s54, v240
	s_nop 1
	v_cndmask_b32_e32 v247, v240, v241, vcc
	v_sqrt_f32_e32 v242, v247
	s_nop 1
	v_add_u32_e32 v243, -1, v242
	v_add_u32_e32 v244, 1, v242
	v_fma_f32 v245, -v243, v242, v247
	v_fma_f32 v246, -v244, v242, v247
	v_cmp_ge_f32_e64 s[52:53], 0, v245
	s_nop 1
	v_cndmask_b32_e64 v242, v242, v243, s[52:53]
	v_cmp_lt_f32_e64 s[52:53], 0, v246
	s_nop 1
	v_cndmask_b32_e64 v242, v242, v244, s[52:53]
	v_mul_f32_e32 v243, 0x37800000, v242
	v_cndmask_b32_e32 v242, v242, v243, vcc
	v_cmp_class_f32_e32 vcc, v247, v90
	s_nop 1
	v_cndmask_b32_e32 v247, v242, v247, vcc
	v_div_scale_f32 v248, s[52:53], v247, v247, 1.0
	v_rcp_f32_e32 v249, v248
	v_div_scale_f32 v228, vcc, 1.0, v247, 1.0
	s_nop 0
	v_fma_f32 v229, -v248, v249, 1.0
	v_fmac_f32_e32 v249, v229, v249
	v_mul_f32_e32 v230, v228, v249
	v_fma_f32 v229, -v248, v230, v228
	v_fmac_f32_e32 v230, v229, v249
	v_fma_f32 v248, -v248, v230, v228
	v_div_fmas_f32 v248, v248, v249, v230
	v_div_fixup_f32 v234, v248, v247, 1.0
	v_fmamk_f32 v240, v226, 0x3a800000, v89
	v_mul_f32_e32 v241, 0x4f800000, v240
	v_cmp_gt_f32_e32 vcc, s54, v240
	s_nop 1
	v_cndmask_b32_e32 v247, v240, v241, vcc
	v_sqrt_f32_e32 v242, v247
	s_nop 1
	v_add_u32_e32 v243, -1, v242
	v_add_u32_e32 v244, 1, v242
	v_fma_f32 v245, -v243, v242, v247
	v_fma_f32 v246, -v244, v242, v247
	v_cmp_ge_f32_e64 s[52:53], 0, v245
	s_nop 1
	v_cndmask_b32_e64 v242, v242, v243, s[52:53]
	v_cmp_lt_f32_e64 s[52:53], 0, v246
	s_nop 1
	v_cndmask_b32_e64 v242, v242, v244, s[52:53]
	v_mul_f32_e32 v243, 0x37800000, v242
	v_cndmask_b32_e32 v242, v242, v243, vcc
	v_cmp_class_f32_e32 vcc, v247, v90
	s_nop 1
	v_cndmask_b32_e32 v247, v242, v247, vcc
	v_div_scale_f32 v248, s[52:53], v247, v247, 1.0
	v_rcp_f32_e32 v249, v248
	v_div_scale_f32 v228, vcc, 1.0, v247, 1.0
	s_nop 0
	v_fma_f32 v229, -v248, v249, 1.0
	v_fmac_f32_e32 v249, v229, v249
	v_mul_f32_e32 v230, v228, v249
	v_fma_f32 v229, -v248, v230, v228
	v_fmac_f32_e32 v230, v229, v249
	v_fma_f32 v248, -v248, v230, v228
	v_div_fmas_f32 v248, v248, v249, v230
	v_div_fixup_f32 v236, v248, v247, 1.0
	v_fmamk_f32 v240, v227, 0x3a800000, v89
	v_mul_f32_e32 v241, 0x4f800000, v240
	v_cmp_gt_f32_e32 vcc, s54, v240
	s_nop 1
	v_cndmask_b32_e32 v247, v240, v241, vcc
	v_sqrt_f32_e32 v242, v247
	s_nop 1
	v_add_u32_e32 v243, -1, v242
	v_add_u32_e32 v244, 1, v242
	v_fma_f32 v245, -v243, v242, v247
	v_fma_f32 v246, -v244, v242, v247
	v_cmp_ge_f32_e64 s[52:53], 0, v245
	s_nop 1
	v_cndmask_b32_e64 v242, v242, v243, s[52:53]
	v_cmp_lt_f32_e64 s[52:53], 0, v246
	s_nop 1
	v_cndmask_b32_e64 v242, v242, v244, s[52:53]
	v_mul_f32_e32 v243, 0x37800000, v242
	v_cndmask_b32_e32 v242, v242, v243, vcc
	v_cmp_class_f32_e32 vcc, v247, v90
	s_nop 1
	v_cndmask_b32_e32 v247, v242, v247, vcc
	v_div_scale_f32 v248, s[52:53], v247, v247, 1.0
	v_rcp_f32_e32 v249, v248
	v_div_scale_f32 v228, vcc, 1.0, v247, 1.0
	s_nop 0
	v_fma_f32 v229, -v248, v249, 1.0
	v_fmac_f32_e32 v249, v229, v249
	v_mul_f32_e32 v230, v228, v249
	v_fma_f32 v229, -v248, v230, v228
	v_fmac_f32_e32 v230, v229, v249
	v_fma_f32 v248, -v248, v230, v228
	v_div_fmas_f32 v248, v248, v249, v230
	v_div_fixup_f32 v238, v248, v247, 1.0
	s_waitcnt vmcnt(8)
; __device__ __forceinline__ unsigned pk2(float lo, float hi) { return pg8::cvt_pk_bf16(lo, hi); }
; template <bool BF> __device__ __forceinline__ void prep_rows(const float* xp, const float* xs, const bf16* hb, const float* g, const float* MOD, int shoff, int scoff, bf16* U, int gw, int NGW, int lane) {
;     ...
;         for (int r = 0; r < R; ++r) { const int m = mb + r * NGW; if (m < MT) {
;             const float rstd = 1.0f / sqrtf(s[r] * (1.0f / DM) + RMS_EPS);
;             const float* mr = MOD + (size_t)(m < MP ? (m >> 13) : 8 + ((m - MP) >> 12)) * 6144;
; #pragma unroll
;             for (int j = 0; j < 4; ++j) { const int c = 4 * lane + 256 * j;
;                 const f32x4 gg = *(const f32x4*)(g + c), sc = *(const f32x4*)(mr + scoff + c), sh = *(const f32x4*)(mr + shoff + c);
;                 const f32x4 o = v[r][j] * rstd * gg * (sc + 1.0f) + sh; v2u w; w.x = pk2(o.x, o.y); w.y = pk2(o.z, o.w); *(v2u*)(U + (size_t)m * DM + c) = w; } } }
	v_pk_add_f32 v[160:161], v[160:161], 1.0 op_sel_hi:[1,0]
	v_pk_add_f32 v[162:163], v[162:163], 1.0 op_sel_hi:[1,0]
	v_pk_add_f32 v[164:165], v[164:165], 1.0 op_sel_hi:[1,0]
	v_pk_add_f32 v[166:167], v[166:167], 1.0 op_sel_hi:[1,0]
	v_pk_add_f32 v[168:169], v[168:169], 1.0 op_sel_hi:[1,0]
	v_pk_add_f32 v[170:171], v[170:171], 1.0 op_sel_hi:[1,0]
	v_pk_add_f32 v[172:173], v[172:173], 1.0 op_sel_hi:[1,0]
	v_pk_add_f32 v[174:175], v[174:175], 1.0 op_sel_hi:[1,0]
	v_pk_add_f32 v[192:193], v[192:193], 1.0 op_sel_hi:[1,0]
	v_pk_add_f32 v[194:195], v[194:195], 1.0 op_sel_hi:[1,0]
	v_pk_add_f32 v[196:197], v[196:197], 1.0 op_sel_hi:[1,0]
	v_pk_add_f32 v[198:199], v[198:199], 1.0 op_sel_hi:[1,0]
	v_pk_add_f32 v[200:201], v[200:201], 1.0 op_sel_hi:[1,0]
	v_pk_add_f32 v[202:203], v[202:203], 1.0 op_sel_hi:[1,0]
	v_pk_add_f32 v[204:205], v[204:205], 1.0 op_sel_hi:[1,0]
	v_pk_add_f32 v[206:207], v[206:207], 1.0 op_sel_hi:[1,0]
	s_add_u32 s38, s20, 0x7000000
	s_addc_u32 s39, s21, 0
	s_add_u32 s40, s20, 0x7400000
	s_addc_u32 s41, s21, 0
	s_add_u32 s46, s20, 0x7800000
	s_addc_u32 s47, s21, 0
	s_add_u32 s48, s20, 0x7c00000
	s_addc_u32 s49, s21, 0
	v_pk_mul_f32 v[0:1], v[0:1], v[232:233] op_sel_hi:[1,0]
	v_pk_mul_f32 v[2:3], v[2:3], v[232:233] op_sel_hi:[1,0]
	v_pk_mul_f32 v[0:1], v[64:65], v[0:1]
	v_pk_mul_f32 v[2:3], v[66:67], v[2:3]
	v_pk_fma_f32 v[0:1], v[160:161], v[0:1], v[176:177]
	v_pk_fma_f32 v[2:3], v[162:163], v[2:3], v[178:179]
	v_cvt_pk_bf16_f32 v244, v0, v1
	v_cvt_pk_bf16_f32 v245, v2, v3
	v_pk_mul_f32 v[4:5], v[4:5], v[232:233] op_sel_hi:[1,0]
	v_pk_mul_f32 v[6:7], v[6:7], v[232:233] op_sel_hi:[1,0]
	v_pk_mul_f32 v[4:5], v[68:69], v[4:5]
	v_pk_mul_f32 v[6:7], v[70:71], v[6:7]
	v_pk_fma_f32 v[4:5], v[164:165], v[4:5], v[180:181]
	v_pk_fma_f32 v[6:7], v[166:167], v[6:7], v[182:183]
	v_cvt_pk_bf16_f32 v246, v4, v5
	v_cvt_pk_bf16_f32 v247, v6, v7
	global_store_dwordx4 v82, v[244:247], s[38:39] offset:0
	v_pk_mul_f32 v[8:9], v[8:9], v[232:233] op_sel_hi:[1,0]
	v_pk_mul_f32 v[10:11], v[10:11], v[232:233] op_sel_hi:[1,0]
	v_pk_mul_f32 v[8:9], v[72:73], v[8:9]
	v_pk_mul_f32 v[10:11], v[74:75], v[10:11]
	v_pk_fma_f32 v[8:9], v[168:169], v[8:9], v[184:185]
	v_pk_fma_f32 v[10:11], v[170:171], v[10:11], v[186:187]
	v_cvt_pk_bf16_f32 v240, v8, v9
	v_cvt_pk_bf16_f32 v241, v10, v11
	v_pk_mul_f32 v[12:13], v[12:13], v[232:233] op_sel_hi:[1,0]
	v_pk_mul_f32 v[14:15], v[14:15], v[232:233] op_sel_hi:[1,0]
	v_pk_mul_f32 v[12:13], v[76:77], v[12:13]
	v_pk_mul_f32 v[14:15], v[78:79], v[14:15]
	v_pk_fma_f32 v[12:13], v[172:173], v[12:13], v[188:189]
	v_pk_fma_f32 v[14:15], v[174:175], v[14:15], v[190:191]
	v_cvt_pk_bf16_f32 v242, v12, v13
	v_cvt_pk_bf16_f32 v243, v14, v15
	global_store_dwordx4 v82, v[240:243], s[38:39] offset:1024
	v_pk_mul_f32 v[16:17], v[16:17], v[234:235] op_sel_hi:[1,0]
	v_pk_mul_f32 v[18:19], v[18:19], v[234:235] op_sel_hi:[1,0]
	v_pk_mul_f32 v[16:17], v[64:65], v[16:17]
	v_pk_mul_f32 v[18:19], v[66:67], v[18:19]
	v_pk_fma_f32 v[16:17], v[160:161], v[16:17], v[176:177]
	v_pk_fma_f32 v[18:19], v[162:163], v[18:19], v[178:179]
	v_cvt_pk_bf16_f32 v244, v16, v17
	v_cvt_pk_bf16_f32 v245, v18, v19
	v_pk_mul_f32 v[20:21], v[20:21], v[234:235] op_sel_hi:[1,0]
	v_pk_mul_f32 v[22:23], v[22:23], v[234:235] op_sel_hi:[1,0]
	v_pk_mul_f32 v[20:21], v[68:69], v[20:21]
	v_pk_mul_f32 v[22:23], v[70:71], v[22:23]
	v_pk_fma_f32 v[20:21], v[164:165], v[20:21], v[180:181]
	v_pk_fma_f32 v[22:23], v[166:167], v[22:23], v[182:183]
	v_cvt_pk_bf16_f32 v246, v20, v21
	v_cvt_pk_bf16_f32 v247, v22, v23
	global_store_dwordx4 v82, v[244:247], s[40:41] offset:0
	v_pk_mul_f32 v[24:25], v[24:25], v[234:235] op_sel_hi:[1,0]
	v_pk_mul_f32 v[26:27], v[26:27], v[234:235] op_sel_hi:[1,0]
	v_pk_mul_f32 v[24:25], v[72:73], v[24:25]
	v_pk_mul_f32 v[26:27], v[74:75], v[26:27]
	v_pk_fma_f32 v[24:25], v[168:169], v[24:25], v[184:185]
	v_pk_fma_f32 v[26:27], v[170:171], v[26:27], v[186:187]
	v_cvt_pk_bf16_f32 v240, v24, v25
	v_cvt_pk_bf16_f32 v241, v26, v27
	v_pk_mul_f32 v[28:29], v[28:29], v[234:235] op_sel_hi:[1,0]
	v_pk_mul_f32 v[30:31], v[30:31], v[234:235] op_sel_hi:[1,0]
	v_pk_mul_f32 v[28:29], v[76:77], v[28:29]
	v_pk_mul_f32 v[30:31], v[78:79], v[30:31]
	v_pk_fma_f32 v[28:29], v[172:173], v[28:29], v[188:189]
	v_pk_fma_f32 v[30:31], v[174:175], v[30:31], v[190:191]
	v_cvt_pk_bf16_f32 v242, v28, v29
	v_cvt_pk_bf16_f32 v243, v30, v31
	global_store_dwordx4 v82, v[240:243], s[40:41] offset:1024
	v_pk_mul_f32 v[32:33], v[32:33], v[236:237] op_sel_hi:[1,0]
	v_pk_mul_f32 v[34:35], v[34:35], v[236:237] op_sel_hi:[1,0]
	v_pk_mul_f32 v[32:33], v[64:65], v[32:33]
	v_pk_mul_f32 v[34:35], v[66:67], v[34:35]
	v_pk_fma_f32 v[32:33], v[192:193], v[32:33], v[208:209]
	v_pk_fma_f32 v[34:35], v[194:195], v[34:35], v[210:211]
	v_cvt_pk_bf16_f32 v244, v32, v33
	v_cvt_pk_bf16_f32 v245, v34, v35
	v_pk_mul_f32 v[36:37], v[36:37], v[236:237] op_sel_hi:[1,0]
	v_pk_mul_f32 v[38:39], v[38:39], v[236:237] op_sel_hi:[1,0]
	v_pk_mul_f32 v[36:37], v[68:69], v[36:37]
	v_pk_mul_f32 v[38:39], v[70:71], v[38:39]
	v_pk_fma_f32 v[36:37], v[196:197], v[36:37], v[212:213]
	v_pk_fma_f32 v[38:39], v[198:199], v[38:39], v[214:215]
	v_cvt_pk_bf16_f32 v246, v36, v37
	v_cvt_pk_bf16_f32 v247, v38, v39
	global_store_dwordx4 v82, v[244:247], s[46:47] offset:0
	v_pk_mul_f32 v[40:41], v[40:41], v[236:237] op_sel_hi:[1,0]
	v_pk_mul_f32 v[42:43], v[42:43], v[236:237] op_sel_hi:[1,0]
	v_pk_mul_f32 v[40:41], v[72:73], v[40:41]
	v_pk_mul_f32 v[42:43], v[74:75], v[42:43]
	v_pk_fma_f32 v[40:41], v[200:201], v[40:41], v[216:217]
	v_pk_fma_f32 v[42:43], v[202:203], v[42:43], v[218:219]
	v_cvt_pk_bf16_f32 v240, v40, v41
; __device__ __forceinline__ float bf_lo(unsigned w) { return __uint_as_float(w << 16); }
; __device__ __forceinline__ float bf_hi(unsigned w) { return __uint_as_float(w & 0xffff0000u); }
; __device__ __forceinline__ unsigned pk2(float lo, float hi) { return pg8::cvt_pk_bf16(lo, hi); }
; template <bool BF> __device__ __forceinline__ void prep_rows(const float* xp, const float* xs, const bf16* hb, const float* g, const float* MOD, int shoff, int scoff, bf16* U, int gw, int NGW, int lane) {
;     ...
;         for (int r = 0; r < R; ++r) { const int m = mb + r * NGW; const int mc = m < MT ? m : mb;
; #pragma unroll
;             for (int j = 0; j < 4; ++j) {
;                 if (BF) { const v2u a0 = *(const v2u*)(hb + (size_t)mc * DM + 4 * lane + 256 * j);
;                     v[r][j].x = pg8::bf_lo(a0.x); v[r][j].y = pg8::bf_hi(a0.x); v[r][j].z = pg8::bf_lo(a0.y); v[r][j].w = pg8::bf_hi(a0.y); }
;                 else { const float* xr = mc < MP ? xp + (size_t)mc * DM : xs + (size_t)(mc - MP) * DM; v[r][j] = *(const f32x4*)(xr + 4 * lane + 256 * j); } } }
;     ...
;         for (int r = 0; r < R; ++r) { const int m = mb + r * NGW; if (m < MT) {
;             const float rstd = 1.0f / sqrtf(s[r] * (1.0f / DM) + RMS_EPS);
;             const float* mr = MOD + (size_t)(m < MP ? (m >> 13) : 8 + ((m - MP) >> 12)) * 6144;
; #pragma unroll
;             for (int j = 0; j < 4; ++j) { const int c = 4 * lane + 256 * j;
;                 const f32x4 gg = *(const f32x4*)(g + c), sc = *(const f32x4*)(mr + scoff + c), sh = *(const f32x4*)(mr + shoff + c);
;                 const f32x4 o = v[r][j] * rstd * gg * (sc + 1.0f) + sh; v2u w; w.x = pk2(o.x, o.y); w.y = pk2(o.z, o.w); *(v2u*)(U + (size_t)m * DM + c) = w; } } }
	v_cvt_pk_bf16_f32 v241, v42, v43
	v_pk_mul_f32 v[44:45], v[44:45], v[236:237] op_sel_hi:[1,0]
	v_pk_mul_f32 v[46:47], v[46:47], v[236:237] op_sel_hi:[1,0]
	v_pk_mul_f32 v[44:45], v[76:77], v[44:45]
	v_pk_mul_f32 v[46:47], v[78:79], v[46:47]
	v_pk_fma_f32 v[44:45], v[204:205], v[44:45], v[220:221]
	v_pk_fma_f32 v[46:47], v[206:207], v[46:47], v[222:223]
	v_cvt_pk_bf16_f32 v242, v44, v45
	v_cvt_pk_bf16_f32 v243, v46, v47
	global_store_dwordx4 v82, v[240:243], s[46:47] offset:1024
	v_pk_mul_f32 v[48:49], v[48:49], v[238:239] op_sel_hi:[1,0]
	v_pk_mul_f32 v[50:51], v[50:51], v[238:239] op_sel_hi:[1,0]
	v_pk_mul_f32 v[48:49], v[64:65], v[48:49]
	v_pk_mul_f32 v[50:51], v[66:67], v[50:51]
	v_pk_fma_f32 v[48:49], v[192:193], v[48:49], v[208:209]
	v_pk_fma_f32 v[50:51], v[194:195], v[50:51], v[210:211]
	v_cvt_pk_bf16_f32 v244, v48, v49
	v_cvt_pk_bf16_f32 v245, v50, v51
	v_pk_mul_f32 v[52:53], v[52:53], v[238:239] op_sel_hi:[1,0]
	v_pk_mul_f32 v[54:55], v[54:55], v[238:239] op_sel_hi:[1,0]
	v_pk_mul_f32 v[52:53], v[68:69], v[52:53]
	v_pk_mul_f32 v[54:55], v[70:71], v[54:55]
	v_pk_fma_f32 v[52:53], v[196:197], v[52:53], v[212:213]
	v_pk_fma_f32 v[54:55], v[198:199], v[54:55], v[214:215]
	v_cvt_pk_bf16_f32 v246, v52, v53
	v_cvt_pk_bf16_f32 v247, v54, v55
	global_store_dwordx4 v82, v[244:247], s[48:49] offset:0
	v_pk_mul_f32 v[56:57], v[56:57], v[238:239] op_sel_hi:[1,0]
	v_pk_mul_f32 v[58:59], v[58:59], v[238:239] op_sel_hi:[1,0]
	v_pk_mul_f32 v[56:57], v[72:73], v[56:57]
	v_pk_mul_f32 v[58:59], v[74:75], v[58:59]
	v_pk_fma_f32 v[56:57], v[200:201], v[56:57], v[216:217]
	v_pk_fma_f32 v[58:59], v[202:203], v[58:59], v[218:219]
	v_cvt_pk_bf16_f32 v240, v56, v57
	v_cvt_pk_bf16_f32 v241, v58, v59
	v_pk_mul_f32 v[60:61], v[60:61], v[238:239] op_sel_hi:[1,0]
	v_pk_mul_f32 v[62:63], v[62:63], v[238:239] op_sel_hi:[1,0]
	v_pk_mul_f32 v[60:61], v[76:77], v[60:61]
	v_pk_mul_f32 v[62:63], v[78:79], v[62:63]
	v_pk_fma_f32 v[60:61], v[204:205], v[60:61], v[220:221]
	v_pk_fma_f32 v[62:63], v[206:207], v[62:63], v[222:223]
	v_cvt_pk_bf16_f32 v242, v60, v61
	v_cvt_pk_bf16_f32 v243, v62, v63
	global_store_dwordx4 v82, v[240:243], s[48:49] offset:1024
	s_add_u32 s34, s8, 0x33000
	s_addc_u32 s35, s9, 0
	s_add_u32 s36, s8, 0x39000
	s_addc_u32 s37, s9, 0
	global_load_dwordx4 v[176:179], v80, s[34:35] offset:0
	global_load_dwordx4 v[180:183], v80, s[34:35] offset:16
	global_load_dwordx4 v[184:187], v80, s[34:35] offset:2048
	global_load_dwordx4 v[188:191], v80, s[34:35] offset:2064
	global_load_dwordx4 v[160:163], v81, s[34:35] offset:0
	global_load_dwordx4 v[164:167], v81, s[34:35] offset:16
	global_load_dwordx4 v[168:171], v81, s[34:35] offset:2048
	global_load_dwordx4 v[172:175], v81, s[34:35] offset:2064
	global_load_dwordx4 v[208:211], v80, s[36:37] offset:0
	global_load_dwordx4 v[212:215], v80, s[36:37] offset:16
	global_load_dwordx4 v[216:219], v80, s[36:37] offset:2048
	global_load_dwordx4 v[220:223], v80, s[36:37] offset:2064
	global_load_dwordx4 v[192:195], v81, s[36:37] offset:0
	global_load_dwordx4 v[196:199], v81, s[36:37] offset:16
	global_load_dwordx4 v[200:203], v81, s[36:37] offset:2048
	global_load_dwordx4 v[204:207], v81, s[36:37] offset:2064
	s_add_u32 s24, s16, 0x9000000
	s_addc_u32 s25, s17, 0
	s_add_u32 s26, s16, 0x9400000
	s_addc_u32 s27, s17, 0
	s_add_u32 s28, s16, 0x9800000
	s_addc_u32 s29, s17, 0
	s_add_u32 s30, s16, 0x9c00000
	s_addc_u32 s31, s17, 0
	global_load_dwordx4 v[128:131], v82, s[24:25] offset:0
	global_load_dwordx4 v[132:135], v82, s[24:25] offset:1024
	global_load_dwordx4 v[136:139], v82, s[26:27] offset:0
	global_load_dwordx4 v[140:143], v82, s[26:27] offset:1024
	global_load_dwordx4 v[144:147], v82, s[28:29] offset:0
	global_load_dwordx4 v[148:151], v82, s[28:29] offset:1024
	global_load_dwordx4 v[152:155], v82, s[30:31] offset:0
	global_load_dwordx4 v[156:159], v82, s[30:31] offset:1024
	s_waitcnt vmcnt(32)
	v_lshlrev_b32_e32 v0, 16, v96
	v_and_b32_e32 v1, 0xffff0000, v96
	v_lshlrev_b32_e32 v2, 16, v97
	v_and_b32_e32 v3, 0xffff0000, v97
	v_lshlrev_b32_e32 v4, 16, v98
	v_and_b32_e32 v5, 0xffff0000, v98
	v_lshlrev_b32_e32 v6, 16, v99
	v_and_b32_e32 v7, 0xffff0000, v99
	v_lshlrev_b32_e32 v8, 16, v100
	v_and_b32_e32 v9, 0xffff0000, v100
	v_lshlrev_b32_e32 v10, 16, v101
	v_and_b32_e32 v11, 0xffff0000, v101
	v_lshlrev_b32_e32 v12, 16, v102
	v_and_b32_e32 v13, 0xffff0000, v102
	v_lshlrev_b32_e32 v14, 16, v103
	v_and_b32_e32 v15, 0xffff0000, v103
	v_lshlrev_b32_e32 v16, 16, v104
	v_and_b32_e32 v17, 0xffff0000, v104
	v_lshlrev_b32_e32 v18, 16, v105
	v_and_b32_e32 v19, 0xffff0000, v105
	v_lshlrev_b32_e32 v20, 16, v106
	v_and_b32_e32 v21, 0xffff0000, v106
	v_lshlrev_b32_e32 v22, 16, v107
	v_and_b32_e32 v23, 0xffff0000, v107
	v_lshlrev_b32_e32 v24, 16, v108
	v_and_b32_e32 v25, 0xffff0000, v108
	v_lshlrev_b32_e32 v26, 16, v109
	v_and_b32_e32 v27, 0xffff0000, v109
	v_lshlrev_b32_e32 v28, 16, v110
	v_and_b32_e32 v29, 0xffff0000, v110
	v_lshlrev_b32_e32 v30, 16, v111
	v_and_b32_e32 v31, 0xffff0000, v111
	v_lshlrev_b32_e32 v32, 16, v112
	v_and_b32_e32 v33, 0xffff0000, v112
	v_lshlrev_b32_e32 v34, 16, v113
	v_and_b32_e32 v35, 0xffff0000, v113
	v_lshlrev_b32_e32 v36, 16, v114
	v_and_b32_e32 v37, 0xffff0000, v114
	v_lshlrev_b32_e32 v38, 16, v115
	v_and_b32_e32 v39, 0xffff0000, v115
	v_lshlrev_b32_e32 v40, 16, v116
	v_and_b32_e32 v41, 0xffff0000, v116
	v_lshlrev_b32_e32 v42, 16, v117
	v_and_b32_e32 v43, 0xffff0000, v117
	v_lshlrev_b32_e32 v44, 16, v118
	v_and_b32_e32 v45, 0xffff0000, v118
	v_lshlrev_b32_e32 v46, 16, v119
	v_and_b32_e32 v47, 0xffff0000, v119
	v_lshlrev_b32_e32 v48, 16, v120
	v_and_b32_e32 v49, 0xffff0000, v120
	v_lshlrev_b32_e32 v50, 16, v121
; __device__ __forceinline__ float bf_lo(unsigned w) { return __uint_as_float(w << 16); }
; __device__ __forceinline__ float bf_hi(unsigned w) { return __uint_as_float(w & 0xffff0000u); }
; template <bool BF> __device__ __forceinline__ void prep_rows(const float* xp, const float* xs, const bf16* hb, const float* g, const float* MOD, int shoff, int scoff, bf16* U, int gw, int NGW, int lane) {
;     ...
;                 if (BF) { const v2u a0 = *(const v2u*)(hb + (size_t)mc * DM + 4 * lane + 256 * j);
;                     v[r][j].x = pg8::bf_lo(a0.x); v[r][j].y = pg8::bf_hi(a0.x); v[r][j].z = pg8::bf_lo(a0.y); v[r][j].w = pg8::bf_hi(a0.y); }
;                 else { const float* xr = mc < MP ? xp + (size_t)mc * DM : xs + (size_t)(mc - MP) * DM; v[r][j] = *(const f32x4*)(xr + 4 * lane + 256 * j); } } }
; #pragma unroll
;         for (int r = 0; r < R; ++r) { float t = 0.f;
; #pragma unroll
;             for (int j = 0; j < 4; ++j) t += (v[r][j].x * v[r][j].x + v[r][j].y * v[r][j].y) + (v[r][j].z * v[r][j].z + v[r][j].w * v[r][j].w);
;             s[r] = t; }
; #pragma unroll
;         for (int o = 1; o < 64; o <<= 1) {
; #pragma unroll
;             for (int r = 0; r < R; ++r) s[r] += __shfl_xor(s[r], o); }
; #pragma unroll
;         for (int r = 0; r < R; ++r) { const int m = mb + r * NGW; if (m < MT) {
;             const float rstd = 1.0f / sqrtf(s[r] * (1.0f / DM) + RMS_EPS);
	v_and_b32_e32 v51, 0xffff0000, v121
	v_lshlrev_b32_e32 v52, 16, v122
	v_and_b32_e32 v53, 0xffff0000, v122
	v_lshlrev_b32_e32 v54, 16, v123
	v_and_b32_e32 v55, 0xffff0000, v123
	v_lshlrev_b32_e32 v56, 16, v124
	v_and_b32_e32 v57, 0xffff0000, v124
	v_lshlrev_b32_e32 v58, 16, v125
	v_and_b32_e32 v59, 0xffff0000, v125
	v_lshlrev_b32_e32 v60, 16, v126
	v_and_b32_e32 v61, 0xffff0000, v126
	v_lshlrev_b32_e32 v62, 16, v127
	v_and_b32_e32 v63, 0xffff0000, v127
	v_pk_mul_f32 v[240:241], v[0:1], v[0:1]
	v_pk_mul_f32 v[242:243], v[16:17], v[16:17]
	v_pk_mul_f32 v[244:245], v[32:33], v[32:33]
	v_pk_mul_f32 v[246:247], v[48:49], v[48:49]
	v_pk_fma_f32 v[240:241], v[2:3], v[2:3], v[240:241]
	v_pk_fma_f32 v[242:243], v[18:19], v[18:19], v[242:243]
	v_pk_fma_f32 v[244:245], v[34:35], v[34:35], v[244:245]
	v_pk_fma_f32 v[246:247], v[50:51], v[50:51], v[246:247]
	v_pk_fma_f32 v[240:241], v[4:5], v[4:5], v[240:241]
	v_pk_fma_f32 v[242:243], v[20:21], v[20:21], v[242:243]
	v_pk_fma_f32 v[244:245], v[36:37], v[36:37], v[244:245]
	v_pk_fma_f32 v[246:247], v[52:53], v[52:53], v[246:247]
	v_pk_fma_f32 v[240:241], v[6:7], v[6:7], v[240:241]
	v_pk_fma_f32 v[242:243], v[22:23], v[22:23], v[242:243]
	v_pk_fma_f32 v[244:245], v[38:39], v[38:39], v[244:245]
	v_pk_fma_f32 v[246:247], v[54:55], v[54:55], v[246:247]
	v_pk_fma_f32 v[240:241], v[8:9], v[8:9], v[240:241]
	v_pk_fma_f32 v[242:243], v[24:25], v[24:25], v[242:243]
	v_pk_fma_f32 v[244:245], v[40:41], v[40:41], v[244:245]
	v_pk_fma_f32 v[246:247], v[56:57], v[56:57], v[246:247]
	v_pk_fma_f32 v[240:241], v[10:11], v[10:11], v[240:241]
	v_pk_fma_f32 v[242:243], v[26:27], v[26:27], v[242:243]
	v_pk_fma_f32 v[244:245], v[42:43], v[42:43], v[244:245]
	v_pk_fma_f32 v[246:247], v[58:59], v[58:59], v[246:247]
	v_pk_fma_f32 v[240:241], v[12:13], v[12:13], v[240:241]
	v_pk_fma_f32 v[242:243], v[28:29], v[28:29], v[242:243]
	v_pk_fma_f32 v[244:245], v[44:45], v[44:45], v[244:245]
	v_pk_fma_f32 v[246:247], v[60:61], v[60:61], v[246:247]
	v_pk_fma_f32 v[240:241], v[14:15], v[14:15], v[240:241]
	v_pk_fma_f32 v[242:243], v[30:31], v[30:31], v[242:243]
	v_pk_fma_f32 v[244:245], v[46:47], v[46:47], v[244:245]
	v_pk_fma_f32 v[246:247], v[62:63], v[62:63], v[246:247]
	v_add_f32_e32 v224, v240, v241
	v_add_f32_e32 v225, v242, v243
	v_add_f32_e32 v226, v244, v245
	v_add_f32_e32 v227, v246, v247
	ds_bpermute_b32 v228, v83, v224
	ds_bpermute_b32 v229, v83, v225
	ds_bpermute_b32 v230, v83, v226
	ds_bpermute_b32 v231, v83, v227
	s_waitcnt lgkmcnt(0)
	v_add_f32_e32 v224, v224, v228
	v_add_f32_e32 v225, v225, v229
	v_add_f32_e32 v226, v226, v230
	v_add_f32_e32 v227, v227, v231
	ds_bpermute_b32 v228, v84, v224
	ds_bpermute_b32 v229, v84, v225
	ds_bpermute_b32 v230, v84, v226
	ds_bpermute_b32 v231, v84, v227
	s_waitcnt lgkmcnt(0)
	v_add_f32_e32 v224, v224, v228
	v_add_f32_e32 v225, v225, v229
	v_add_f32_e32 v226, v226, v230
	v_add_f32_e32 v227, v227, v231
	ds_bpermute_b32 v228, v85, v224
	ds_bpermute_b32 v229, v85, v225
	ds_bpermute_b32 v230, v85, v226
	ds_bpermute_b32 v231, v85, v227
	s_waitcnt lgkmcnt(0)
	v_add_f32_e32 v224, v224, v228
	v_add_f32_e32 v225, v225, v229
	v_add_f32_e32 v226, v226, v230
	v_add_f32_e32 v227, v227, v231
	ds_bpermute_b32 v228, v86, v224
	ds_bpermute_b32 v229, v86, v225
	ds_bpermute_b32 v230, v86, v226
	ds_bpermute_b32 v231, v86, v227
	s_waitcnt lgkmcnt(0)
	v_add_f32_e32 v224, v224, v228
	v_add_f32_e32 v225, v225, v229
	v_add_f32_e32 v226, v226, v230
	v_add_f32_e32 v227, v227, v231
	ds_bpermute_b32 v228, v87, v224
	ds_bpermute_b32 v229, v87, v225
	ds_bpermute_b32 v230, v87, v226
	ds_bpermute_b32 v231, v87, v227
	s_waitcnt lgkmcnt(0)
	v_add_f32_e32 v224, v224, v228
	v_add_f32_e32 v225, v225, v229
	v_add_f32_e32 v226, v226, v230
	v_add_f32_e32 v227, v227, v231
	ds_bpermute_b32 v228, v88, v224
	ds_bpermute_b32 v229, v88, v225
	ds_bpermute_b32 v230, v88, v226
	ds_bpermute_b32 v231, v88, v227
	s_waitcnt lgkmcnt(0)
	v_add_f32_e32 v224, v224, v228
	v_add_f32_e32 v225, v225, v229
	v_add_f32_e32 v226, v226, v230
	v_add_f32_e32 v227, v227, v231
	v_fmamk_f32 v240, v224, 0x3a800000, v89
	v_mul_f32_e32 v241, 0x4f800000, v240
	v_cmp_gt_f32_e32 vcc, s54, v240
	s_nop 1
	v_cndmask_b32_e32 v247, v240, v241, vcc
	v_sqrt_f32_e32 v242, v247
	s_nop 1
	v_add_u32_e32 v243, -1, v242
	v_add_u32_e32 v244, 1, v242
	v_fma_f32 v245, -v243, v242, v247
	v_fma_f32 v246, -v244, v242, v247
	v_cmp_ge_f32_e64 s[52:53], 0, v245
	s_nop 1
	v_cndmask_b32_e64 v242, v242, v243, s[52:53]
	v_cmp_lt_f32_e64 s[52:53], 0, v246
	s_nop 1
	v_cndmask_b32_e64 v242, v242, v244, s[52:53]
	v_mul_f32_e32 v243, 0x37800000, v242
	v_cndmask_b32_e32 v242, v242, v243, vcc
	v_cmp_class_f32_e32 vcc, v247, v90
	s_nop 1
	v_cndmask_b32_e32 v247, v242, v247, vcc
	v_div_scale_f32 v248, s[52:53], v247, v247, 1.0
	v_rcp_f32_e32 v249, v248
	v_div_scale_f32 v228, vcc, 1.0, v247, 1.0
	s_nop 0
	v_fma_f32 v229, -v248, v249, 1.0
	v_fmac_f32_e32 v249, v229, v249
	v_mul_f32_e32 v230, v228, v249
	v_fma_f32 v229, -v248, v230, v228
	v_fmac_f32_e32 v230, v229, v249
	v_fma_f32 v248, -v248, v230, v228
	v_div_fmas_f32 v248, v248, v249, v230
	v_div_fixup_f32 v232, v248, v247, 1.0
	v_fmamk_f32 v240, v225, 0x3a800000, v89
	v_mul_f32_e32 v241, 0x4f800000, v240
	v_cmp_gt_f32_e32 vcc, s54, v240
	s_nop 1
	v_cndmask_b32_e32 v247, v240, v241, vcc
	v_sqrt_f32_e32 v242, v247
	s_nop 1
	v_add_u32_e32 v243, -1, v242
	v_add_u32_e32 v244, 1, v242
	v_fma_f32 v245, -v243, v242, v247
	v_fma_f32 v246, -v244, v242, v247
	v_cmp_ge_f32_e64 s[52:53], 0, v245
	s_nop 1
	v_cndmask_b32_e64 v242, v242, v243, s[52:53]
	v_cmp_lt_f32_e64 s[52:53], 0, v246
	s_nop 1
	v_cndmask_b32_e64 v242, v242, v244, s[52:53]
; __device__ __forceinline__ unsigned pk2(float lo, float hi) { return pg8::cvt_pk_bf16(lo, hi); }
; template <bool BF> __device__ __forceinline__ void prep_rows(const float* xp, const float* xs, const bf16* hb, const float* g, const float* MOD, int shoff, int scoff, bf16* U, int gw, int NGW, int lane) {
;     ...
;         for (int r = 0; r < R; ++r) { const int m = mb + r * NGW; if (m < MT) {
;             const float rstd = 1.0f / sqrtf(s[r] * (1.0f / DM) + RMS_EPS);
;             const float* mr = MOD + (size_t)(m < MP ? (m >> 13) : 8 + ((m - MP) >> 12)) * 6144;
; #pragma unroll
;             for (int j = 0; j < 4; ++j) { const int c = 4 * lane + 256 * j;
;                 const f32x4 gg = *(const f32x4*)(g + c), sc = *(const f32x4*)(mr + scoff + c), sh = *(const f32x4*)(mr + shoff + c);
;                 const f32x4 o = v[r][j] * rstd * gg * (sc + 1.0f) + sh; v2u w; w.x = pk2(o.x, o.y); w.y = pk2(o.z, o.w); *(v2u*)(U + (size_t)m * DM + c) = w; } } }
	v_mul_f32_e32 v243, 0x37800000, v242
	v_cndmask_b32_e32 v242, v242, v243, vcc
	v_cmp_class_f32_e32 vcc, v247, v90
	s_nop 1
	v_cndmask_b32_e32 v247, v242, v247, vcc
	v_div_scale_f32 v248, s[52:53], v247, v247, 1.0
	v_rcp_f32_e32 v249, v248
	v_div_scale_f32 v228, vcc, 1.0, v247, 1.0
	s_nop 0
	v_fma_f32 v229, -v248, v249, 1.0
	v_fmac_f32_e32 v249, v229, v249
	v_mul_f32_e32 v230, v228, v249
	v_fma_f32 v229, -v248, v230, v228
	v_fmac_f32_e32 v230, v229, v249
	v_fma_f32 v248, -v248, v230, v228
	v_div_fmas_f32 v248, v248, v249, v230
	v_div_fixup_f32 v234, v248, v247, 1.0
	v_fmamk_f32 v240, v226, 0x3a800000, v89
	v_mul_f32_e32 v241, 0x4f800000, v240
	v_cmp_gt_f32_e32 vcc, s54, v240
	s_nop 1
	v_cndmask_b32_e32 v247, v240, v241, vcc
	v_sqrt_f32_e32 v242, v247
	s_nop 1
	v_add_u32_e32 v243, -1, v242
	v_add_u32_e32 v244, 1, v242
	v_fma_f32 v245, -v243, v242, v247
	v_fma_f32 v246, -v244, v242, v247
	v_cmp_ge_f32_e64 s[52:53], 0, v245
	s_nop 1
	v_cndmask_b32_e64 v242, v242, v243, s[52:53]
	v_cmp_lt_f32_e64 s[52:53], 0, v246
	s_nop 1
	v_cndmask_b32_e64 v242, v242, v244, s[52:53]
	v_mul_f32_e32 v243, 0x37800000, v242
	v_cndmask_b32_e32 v242, v242, v243, vcc
	v_cmp_class_f32_e32 vcc, v247, v90
	s_nop 1
	v_cndmask_b32_e32 v247, v242, v247, vcc
	v_div_scale_f32 v248, s[52:53], v247, v247, 1.0
	v_rcp_f32_e32 v249, v248
	v_div_scale_f32 v228, vcc, 1.0, v247, 1.0
	s_nop 0
	v_fma_f32 v229, -v248, v249, 1.0
	v_fmac_f32_e32 v249, v229, v249
	v_mul_f32_e32 v230, v228, v249
	v_fma_f32 v229, -v248, v230, v228
	v_fmac_f32_e32 v230, v229, v249
	v_fma_f32 v248, -v248, v230, v228
	v_div_fmas_f32 v248, v248, v249, v230
	v_div_fixup_f32 v236, v248, v247, 1.0
	v_fmamk_f32 v240, v227, 0x3a800000, v89
	v_mul_f32_e32 v241, 0x4f800000, v240
	v_cmp_gt_f32_e32 vcc, s54, v240
	s_nop 1
	v_cndmask_b32_e32 v247, v240, v241, vcc
	v_sqrt_f32_e32 v242, v247
	s_nop 1
	v_add_u32_e32 v243, -1, v242
	v_add_u32_e32 v244, 1, v242
	v_fma_f32 v245, -v243, v242, v247
	v_fma_f32 v246, -v244, v242, v247
	v_cmp_ge_f32_e64 s[52:53], 0, v245
	s_nop 1
	v_cndmask_b32_e64 v242, v242, v243, s[52:53]
	v_cmp_lt_f32_e64 s[52:53], 0, v246
	s_nop 1
	v_cndmask_b32_e64 v242, v242, v244, s[52:53]
	v_mul_f32_e32 v243, 0x37800000, v242
	v_cndmask_b32_e32 v242, v242, v243, vcc
	v_cmp_class_f32_e32 vcc, v247, v90
	s_nop 1
	v_cndmask_b32_e32 v247, v242, v247, vcc
	v_div_scale_f32 v248, s[52:53], v247, v247, 1.0
	v_rcp_f32_e32 v249, v248
	v_div_scale_f32 v228, vcc, 1.0, v247, 1.0
	s_nop 0
	v_fma_f32 v229, -v248, v249, 1.0
	v_fmac_f32_e32 v249, v229, v249
	v_mul_f32_e32 v230, v228, v249
	v_fma_f32 v229, -v248, v230, v228
	v_fmac_f32_e32 v230, v229, v249
	v_fma_f32 v248, -v248, v230, v228
	v_div_fmas_f32 v248, v248, v249, v230
	v_div_fixup_f32 v238, v248, v247, 1.0
	s_waitcnt vmcnt(8)
	v_pk_add_f32 v[160:161], v[160:161], 1.0 op_sel_hi:[1,0]
	v_pk_add_f32 v[162:163], v[162:163], 1.0 op_sel_hi:[1,0]
	v_pk_add_f32 v[164:165], v[164:165], 1.0 op_sel_hi:[1,0]
	v_pk_add_f32 v[166:167], v[166:167], 1.0 op_sel_hi:[1,0]
	v_pk_add_f32 v[168:169], v[168:169], 1.0 op_sel_hi:[1,0]
	v_pk_add_f32 v[170:171], v[170:171], 1.0 op_sel_hi:[1,0]
	v_pk_add_f32 v[172:173], v[172:173], 1.0 op_sel_hi:[1,0]
	v_pk_add_f32 v[174:175], v[174:175], 1.0 op_sel_hi:[1,0]
	v_pk_add_f32 v[192:193], v[192:193], 1.0 op_sel_hi:[1,0]
	v_pk_add_f32 v[194:195], v[194:195], 1.0 op_sel_hi:[1,0]
	v_pk_add_f32 v[196:197], v[196:197], 1.0 op_sel_hi:[1,0]
	v_pk_add_f32 v[198:199], v[198:199], 1.0 op_sel_hi:[1,0]
	v_pk_add_f32 v[200:201], v[200:201], 1.0 op_sel_hi:[1,0]
	v_pk_add_f32 v[202:203], v[202:203], 1.0 op_sel_hi:[1,0]
	v_pk_add_f32 v[204:205], v[204:205], 1.0 op_sel_hi:[1,0]
	v_pk_add_f32 v[206:207], v[206:207], 1.0 op_sel_hi:[1,0]
	s_add_u32 s38, s20, 0x8000000
	s_addc_u32 s39, s21, 0
	s_add_u32 s40, s20, 0x8400000
	s_addc_u32 s41, s21, 0
	s_add_u32 s46, s20, 0x8800000
	s_addc_u32 s47, s21, 0
	s_add_u32 s48, s20, 0x8c00000
	s_addc_u32 s49, s21, 0
	v_pk_mul_f32 v[0:1], v[0:1], v[232:233] op_sel_hi:[1,0]
	v_pk_mul_f32 v[2:3], v[2:3], v[232:233] op_sel_hi:[1,0]
	v_pk_mul_f32 v[0:1], v[64:65], v[0:1]
	v_pk_mul_f32 v[2:3], v[66:67], v[2:3]
	v_pk_fma_f32 v[0:1], v[160:161], v[0:1], v[176:177]
	v_pk_fma_f32 v[2:3], v[162:163], v[2:3], v[178:179]
	v_cvt_pk_bf16_f32 v244, v0, v1
	v_cvt_pk_bf16_f32 v245, v2, v3
	v_pk_mul_f32 v[4:5], v[4:5], v[232:233] op_sel_hi:[1,0]
	v_pk_mul_f32 v[6:7], v[6:7], v[232:233] op_sel_hi:[1,0]
	v_pk_mul_f32 v[4:5], v[68:69], v[4:5]
	v_pk_mul_f32 v[6:7], v[70:71], v[6:7]
	v_pk_fma_f32 v[4:5], v[164:165], v[4:5], v[180:181]
	v_pk_fma_f32 v[6:7], v[166:167], v[6:7], v[182:183]
	v_cvt_pk_bf16_f32 v246, v4, v5
	v_cvt_pk_bf16_f32 v247, v6, v7
	global_store_dwordx4 v82, v[244:247], s[38:39] offset:0
	v_pk_mul_f32 v[8:9], v[8:9], v[232:233] op_sel_hi:[1,0]
	v_pk_mul_f32 v[10:11], v[10:11], v[232:233] op_sel_hi:[1,0]
	v_pk_mul_f32 v[8:9], v[72:73], v[8:9]
	v_pk_mul_f32 v[10:11], v[74:75], v[10:11]
	v_pk_fma_f32 v[8:9], v[168:169], v[8:9], v[184:185]
	v_pk_fma_f32 v[10:11], v[170:171], v[10:11], v[186:187]
	v_cvt_pk_bf16_f32 v240, v8, v9
	v_cvt_pk_bf16_f32 v241, v10, v11
	v_pk_mul_f32 v[12:13], v[12:13], v[232:233] op_sel_hi:[1,0]
	v_pk_mul_f32 v[14:15], v[14:15], v[232:233] op_sel_hi:[1,0]
	v_pk_mul_f32 v[12:13], v[76:77], v[12:13]
	v_pk_mul_f32 v[14:15], v[78:79], v[14:15]
	v_pk_fma_f32 v[12:13], v[172:173], v[12:13], v[188:189]
	v_pk_fma_f32 v[14:15], v[174:175], v[14:15], v[190:191]
	v_cvt_pk_bf16_f32 v242, v12, v13
	v_cvt_pk_bf16_f32 v243, v14, v15
	global_store_dwordx4 v82, v[240:243], s[38:39] offset:1024
	v_pk_mul_f32 v[16:17], v[16:17], v[234:235] op_sel_hi:[1,0]
	v_pk_mul_f32 v[18:19], v[18:19], v[234:235] op_sel_hi:[1,0]
; __device__ __forceinline__ float bf_lo(unsigned w) { return __uint_as_float(w << 16); }
; __device__ __forceinline__ float bf_hi(unsigned w) { return __uint_as_float(w & 0xffff0000u); }
; __device__ __forceinline__ unsigned pk2(float lo, float hi) { return pg8::cvt_pk_bf16(lo, hi); }
; template <bool BF> __device__ __forceinline__ void prep_rows(const float* xp, const float* xs, const bf16* hb, const float* g, const float* MOD, int shoff, int scoff, bf16* U, int gw, int NGW, int lane) {
;     ...
;         for (int r = 0; r < R; ++r) { const int m = mb + r * NGW; const int mc = m < MT ? m : mb;
; #pragma unroll
;             for (int j = 0; j < 4; ++j) {
;                 if (BF) { const v2u a0 = *(const v2u*)(hb + (size_t)mc * DM + 4 * lane + 256 * j);
;                     v[r][j].x = pg8::bf_lo(a0.x); v[r][j].y = pg8::bf_hi(a0.x); v[r][j].z = pg8::bf_lo(a0.y); v[r][j].w = pg8::bf_hi(a0.y); }
;                 else { const float* xr = mc < MP ? xp + (size_t)mc * DM : xs + (size_t)(mc - MP) * DM; v[r][j] = *(const f32x4*)(xr + 4 * lane + 256 * j); } } }
;     ...
;         for (int r = 0; r < R; ++r) { const int m = mb + r * NGW; if (m < MT) {
;             const float rstd = 1.0f / sqrtf(s[r] * (1.0f / DM) + RMS_EPS);
;             const float* mr = MOD + (size_t)(m < MP ? (m >> 13) : 8 + ((m - MP) >> 12)) * 6144;
; #pragma unroll
;             for (int j = 0; j < 4; ++j) { const int c = 4 * lane + 256 * j;
;                 const f32x4 gg = *(const f32x4*)(g + c), sc = *(const f32x4*)(mr + scoff + c), sh = *(const f32x4*)(mr + shoff + c);
;                 const f32x4 o = v[r][j] * rstd * gg * (sc + 1.0f) + sh; v2u w; w.x = pk2(o.x, o.y); w.y = pk2(o.z, o.w); *(v2u*)(U + (size_t)m * DM + c) = w; } } }
	v_pk_mul_f32 v[16:17], v[64:65], v[16:17]
	v_pk_mul_f32 v[18:19], v[66:67], v[18:19]
	v_pk_fma_f32 v[16:17], v[160:161], v[16:17], v[176:177]
	v_pk_fma_f32 v[18:19], v[162:163], v[18:19], v[178:179]
	v_cvt_pk_bf16_f32 v244, v16, v17
	v_cvt_pk_bf16_f32 v245, v18, v19
	v_pk_mul_f32 v[20:21], v[20:21], v[234:235] op_sel_hi:[1,0]
	v_pk_mul_f32 v[22:23], v[22:23], v[234:235] op_sel_hi:[1,0]
	v_pk_mul_f32 v[20:21], v[68:69], v[20:21]
	v_pk_mul_f32 v[22:23], v[70:71], v[22:23]
	v_pk_fma_f32 v[20:21], v[164:165], v[20:21], v[180:181]
	v_pk_fma_f32 v[22:23], v[166:167], v[22:23], v[182:183]
	v_cvt_pk_bf16_f32 v246, v20, v21
	v_cvt_pk_bf16_f32 v247, v22, v23
	global_store_dwordx4 v82, v[244:247], s[40:41] offset:0
	v_pk_mul_f32 v[24:25], v[24:25], v[234:235] op_sel_hi:[1,0]
	v_pk_mul_f32 v[26:27], v[26:27], v[234:235] op_sel_hi:[1,0]
	v_pk_mul_f32 v[24:25], v[72:73], v[24:25]
	v_pk_mul_f32 v[26:27], v[74:75], v[26:27]
	v_pk_fma_f32 v[24:25], v[168:169], v[24:25], v[184:185]
	v_pk_fma_f32 v[26:27], v[170:171], v[26:27], v[186:187]
	v_cvt_pk_bf16_f32 v240, v24, v25
	v_cvt_pk_bf16_f32 v241, v26, v27
	v_pk_mul_f32 v[28:29], v[28:29], v[234:235] op_sel_hi:[1,0]
	v_pk_mul_f32 v[30:31], v[30:31], v[234:235] op_sel_hi:[1,0]
	v_pk_mul_f32 v[28:29], v[76:77], v[28:29]
	v_pk_mul_f32 v[30:31], v[78:79], v[30:31]
	v_pk_fma_f32 v[28:29], v[172:173], v[28:29], v[188:189]
	v_pk_fma_f32 v[30:31], v[174:175], v[30:31], v[190:191]
	v_cvt_pk_bf16_f32 v242, v28, v29
	v_cvt_pk_bf16_f32 v243, v30, v31
	global_store_dwordx4 v82, v[240:243], s[40:41] offset:1024
	v_pk_mul_f32 v[32:33], v[32:33], v[236:237] op_sel_hi:[1,0]
	v_pk_mul_f32 v[34:35], v[34:35], v[236:237] op_sel_hi:[1,0]
	v_pk_mul_f32 v[32:33], v[64:65], v[32:33]
	v_pk_mul_f32 v[34:35], v[66:67], v[34:35]
	v_pk_fma_f32 v[32:33], v[192:193], v[32:33], v[208:209]
	v_pk_fma_f32 v[34:35], v[194:195], v[34:35], v[210:211]
	v_cvt_pk_bf16_f32 v244, v32, v33
	v_cvt_pk_bf16_f32 v245, v34, v35
	v_pk_mul_f32 v[36:37], v[36:37], v[236:237] op_sel_hi:[1,0]
	v_pk_mul_f32 v[38:39], v[38:39], v[236:237] op_sel_hi:[1,0]
	v_pk_mul_f32 v[36:37], v[68:69], v[36:37]
	v_pk_mul_f32 v[38:39], v[70:71], v[38:39]
	v_pk_fma_f32 v[36:37], v[196:197], v[36:37], v[212:213]
	v_pk_fma_f32 v[38:39], v[198:199], v[38:39], v[214:215]
	v_cvt_pk_bf16_f32 v246, v36, v37
	v_cvt_pk_bf16_f32 v247, v38, v39
	global_store_dwordx4 v82, v[244:247], s[46:47] offset:0
	v_pk_mul_f32 v[40:41], v[40:41], v[236:237] op_sel_hi:[1,0]
	v_pk_mul_f32 v[42:43], v[42:43], v[236:237] op_sel_hi:[1,0]
	v_pk_mul_f32 v[40:41], v[72:73], v[40:41]
	v_pk_mul_f32 v[42:43], v[74:75], v[42:43]
	v_pk_fma_f32 v[40:41], v[200:201], v[40:41], v[216:217]
	v_pk_fma_f32 v[42:43], v[202:203], v[42:43], v[218:219]
	v_cvt_pk_bf16_f32 v240, v40, v41
	v_cvt_pk_bf16_f32 v241, v42, v43
	v_pk_mul_f32 v[44:45], v[44:45], v[236:237] op_sel_hi:[1,0]
	v_pk_mul_f32 v[46:47], v[46:47], v[236:237] op_sel_hi:[1,0]
	v_pk_mul_f32 v[44:45], v[76:77], v[44:45]
	v_pk_mul_f32 v[46:47], v[78:79], v[46:47]
	v_pk_fma_f32 v[44:45], v[204:205], v[44:45], v[220:221]
	v_pk_fma_f32 v[46:47], v[206:207], v[46:47], v[222:223]
	v_cvt_pk_bf16_f32 v242, v44, v45
	v_cvt_pk_bf16_f32 v243, v46, v47
	global_store_dwordx4 v82, v[240:243], s[46:47] offset:1024
	v_pk_mul_f32 v[48:49], v[48:49], v[238:239] op_sel_hi:[1,0]
	v_pk_mul_f32 v[50:51], v[50:51], v[238:239] op_sel_hi:[1,0]
	v_pk_mul_f32 v[48:49], v[64:65], v[48:49]
	v_pk_mul_f32 v[50:51], v[66:67], v[50:51]
	v_pk_fma_f32 v[48:49], v[192:193], v[48:49], v[208:209]
	v_pk_fma_f32 v[50:51], v[194:195], v[50:51], v[210:211]
	v_cvt_pk_bf16_f32 v244, v48, v49
	v_cvt_pk_bf16_f32 v245, v50, v51
	v_pk_mul_f32 v[52:53], v[52:53], v[238:239] op_sel_hi:[1,0]
	v_pk_mul_f32 v[54:55], v[54:55], v[238:239] op_sel_hi:[1,0]
	v_pk_mul_f32 v[52:53], v[68:69], v[52:53]
	v_pk_mul_f32 v[54:55], v[70:71], v[54:55]
	v_pk_fma_f32 v[52:53], v[196:197], v[52:53], v[212:213]
	v_pk_fma_f32 v[54:55], v[198:199], v[54:55], v[214:215]
	v_cvt_pk_bf16_f32 v246, v52, v53
	v_cvt_pk_bf16_f32 v247, v54, v55
	global_store_dwordx4 v82, v[244:247], s[48:49] offset:0
	v_pk_mul_f32 v[56:57], v[56:57], v[238:239] op_sel_hi:[1,0]
	v_pk_mul_f32 v[58:59], v[58:59], v[238:239] op_sel_hi:[1,0]
	v_pk_mul_f32 v[56:57], v[72:73], v[56:57]
	v_pk_mul_f32 v[58:59], v[74:75], v[58:59]
	v_pk_fma_f32 v[56:57], v[200:201], v[56:57], v[216:217]
	v_pk_fma_f32 v[58:59], v[202:203], v[58:59], v[218:219]
	v_cvt_pk_bf16_f32 v240, v56, v57
	v_cvt_pk_bf16_f32 v241, v58, v59
	v_pk_mul_f32 v[60:61], v[60:61], v[238:239] op_sel_hi:[1,0]
	v_pk_mul_f32 v[62:63], v[62:63], v[238:239] op_sel_hi:[1,0]
	v_pk_mul_f32 v[60:61], v[76:77], v[60:61]
	v_pk_mul_f32 v[62:63], v[78:79], v[62:63]
	v_pk_fma_f32 v[60:61], v[204:205], v[60:61], v[220:221]
	v_pk_fma_f32 v[62:63], v[206:207], v[62:63], v[222:223]
	v_cvt_pk_bf16_f32 v242, v60, v61
	v_cvt_pk_bf16_f32 v243, v62, v63
	global_store_dwordx4 v82, v[240:243], s[48:49] offset:1024
	s_add_u32 s34, s8, 0x3f000
	s_addc_u32 s35, s9, 0
	s_add_u32 s36, s8, 0x45000
	s_addc_u32 s37, s9, 0
	global_load_dwordx4 v[176:179], v80, s[34:35] offset:0
	global_load_dwordx4 v[180:183], v80, s[34:35] offset:16
	global_load_dwordx4 v[184:187], v80, s[34:35] offset:2048
	global_load_dwordx4 v[188:191], v80, s[34:35] offset:2064
	global_load_dwordx4 v[160:163], v81, s[34:35] offset:0
	global_load_dwordx4 v[164:167], v81, s[34:35] offset:16
	global_load_dwordx4 v[168:171], v81, s[34:35] offset:2048
	global_load_dwordx4 v[172:175], v81, s[34:35] offset:2064
	global_load_dwordx4 v[208:211], v80, s[36:37] offset:0
	global_load_dwordx4 v[212:215], v80, s[36:37] offset:16
	global_load_dwordx4 v[216:219], v80, s[36:37] offset:2048
	global_load_dwordx4 v[220:223], v80, s[36:37] offset:2064
	global_load_dwordx4 v[192:195], v81, s[36:37] offset:0
	global_load_dwordx4 v[196:199], v81, s[36:37] offset:16
	global_load_dwordx4 v[200:203], v81, s[36:37] offset:2048
	global_load_dwordx4 v[204:207], v81, s[36:37] offset:2064
	s_add_u32 s24, s16, 0xa000000
	s_addc_u32 s25, s17, 0
	s_add_u32 s26, s16, 0xa400000
	s_addc_u32 s27, s17, 0
	s_add_u32 s28, s16, 0xa800000
	s_addc_u32 s29, s17, 0
	s_add_u32 s30, s16, 0xac00000
	s_addc_u32 s31, s17, 0
	global_load_dwordx4 v[96:99], v82, s[24:25] offset:0
	global_load_dwordx4 v[100:103], v82, s[24:25] offset:1024
	global_load_dwordx4 v[104:107], v82, s[26:27] offset:0
	global_load_dwordx4 v[108:111], v82, s[26:27] offset:1024
	global_load_dwordx4 v[112:115], v82, s[28:29] offset:0
	global_load_dwordx4 v[116:119], v82, s[28:29] offset:1024
	global_load_dwordx4 v[120:123], v82, s[30:31] offset:0
	global_load_dwordx4 v[124:127], v82, s[30:31] offset:1024
	s_waitcnt vmcnt(32)
; __device__ __forceinline__ float bf_lo(unsigned w) { return __uint_as_float(w << 16); }
; __device__ __forceinline__ float bf_hi(unsigned w) { return __uint_as_float(w & 0xffff0000u); }
; template <bool BF> __device__ __forceinline__ void prep_rows(const float* xp, const float* xs, const bf16* hb, const float* g, const float* MOD, int shoff, int scoff, bf16* U, int gw, int NGW, int lane) {
;     ...
;                 if (BF) { const v2u a0 = *(const v2u*)(hb + (size_t)mc * DM + 4 * lane + 256 * j);
;                     v[r][j].x = pg8::bf_lo(a0.x); v[r][j].y = pg8::bf_hi(a0.x); v[r][j].z = pg8::bf_lo(a0.y); v[r][j].w = pg8::bf_hi(a0.y); }
;                 else { const float* xr = mc < MP ? xp + (size_t)mc * DM : xs + (size_t)(mc - MP) * DM; v[r][j] = *(const f32x4*)(xr + 4 * lane + 256 * j); } } }
; #pragma unroll
;         for (int r = 0; r < R; ++r) { float t = 0.f;
; #pragma unroll
;             for (int j = 0; j < 4; ++j) t += (v[r][j].x * v[r][j].x + v[r][j].y * v[r][j].y) + (v[r][j].z * v[r][j].z + v[r][j].w * v[r][j].w);
;             s[r] = t; }
; #pragma unroll
;         for (int o = 1; o < 64; o <<= 1) {
; #pragma unroll
;             for (int r = 0; r < R; ++r) s[r] += __shfl_xor(s[r], o); }
	v_lshlrev_b32_e32 v0, 16, v128
	v_and_b32_e32 v1, 0xffff0000, v128
	v_lshlrev_b32_e32 v2, 16, v129
	v_and_b32_e32 v3, 0xffff0000, v129
	v_lshlrev_b32_e32 v4, 16, v130
	v_and_b32_e32 v5, 0xffff0000, v130
	v_lshlrev_b32_e32 v6, 16, v131
	v_and_b32_e32 v7, 0xffff0000, v131
	v_lshlrev_b32_e32 v8, 16, v132
	v_and_b32_e32 v9, 0xffff0000, v132
	v_lshlrev_b32_e32 v10, 16, v133
	v_and_b32_e32 v11, 0xffff0000, v133
	v_lshlrev_b32_e32 v12, 16, v134
	v_and_b32_e32 v13, 0xffff0000, v134
	v_lshlrev_b32_e32 v14, 16, v135
	v_and_b32_e32 v15, 0xffff0000, v135
	v_lshlrev_b32_e32 v16, 16, v136
	v_and_b32_e32 v17, 0xffff0000, v136
	v_lshlrev_b32_e32 v18, 16, v137
	v_and_b32_e32 v19, 0xffff0000, v137
	v_lshlrev_b32_e32 v20, 16, v138
	v_and_b32_e32 v21, 0xffff0000, v138
	v_lshlrev_b32_e32 v22, 16, v139
	v_and_b32_e32 v23, 0xffff0000, v139
	v_lshlrev_b32_e32 v24, 16, v140
	v_and_b32_e32 v25, 0xffff0000, v140
	v_lshlrev_b32_e32 v26, 16, v141
	v_and_b32_e32 v27, 0xffff0000, v141
	v_lshlrev_b32_e32 v28, 16, v142
	v_and_b32_e32 v29, 0xffff0000, v142
	v_lshlrev_b32_e32 v30, 16, v143
	v_and_b32_e32 v31, 0xffff0000, v143
	v_lshlrev_b32_e32 v32, 16, v144
	v_and_b32_e32 v33, 0xffff0000, v144
	v_lshlrev_b32_e32 v34, 16, v145
	v_and_b32_e32 v35, 0xffff0000, v145
	v_lshlrev_b32_e32 v36, 16, v146
	v_and_b32_e32 v37, 0xffff0000, v146
	v_lshlrev_b32_e32 v38, 16, v147
	v_and_b32_e32 v39, 0xffff0000, v147
	v_lshlrev_b32_e32 v40, 16, v148
	v_and_b32_e32 v41, 0xffff0000, v148
	v_lshlrev_b32_e32 v42, 16, v149
	v_and_b32_e32 v43, 0xffff0000, v149
	v_lshlrev_b32_e32 v44, 16, v150
	v_and_b32_e32 v45, 0xffff0000, v150
	v_lshlrev_b32_e32 v46, 16, v151
	v_and_b32_e32 v47, 0xffff0000, v151
	v_lshlrev_b32_e32 v48, 16, v152
	v_and_b32_e32 v49, 0xffff0000, v152
	v_lshlrev_b32_e32 v50, 16, v153
	v_and_b32_e32 v51, 0xffff0000, v153
	v_lshlrev_b32_e32 v52, 16, v154
	v_and_b32_e32 v53, 0xffff0000, v154
	v_lshlrev_b32_e32 v54, 16, v155
	v_and_b32_e32 v55, 0xffff0000, v155
	v_lshlrev_b32_e32 v56, 16, v156
	v_and_b32_e32 v57, 0xffff0000, v156
	v_lshlrev_b32_e32 v58, 16, v157
	v_and_b32_e32 v59, 0xffff0000, v157
	v_lshlrev_b32_e32 v60, 16, v158
	v_and_b32_e32 v61, 0xffff0000, v158
	v_lshlrev_b32_e32 v62, 16, v159
	v_and_b32_e32 v63, 0xffff0000, v159
	v_pk_mul_f32 v[240:241], v[0:1], v[0:1]
	v_pk_mul_f32 v[242:243], v[16:17], v[16:17]
	v_pk_mul_f32 v[244:245], v[32:33], v[32:33]
	v_pk_mul_f32 v[246:247], v[48:49], v[48:49]
	v_pk_fma_f32 v[240:241], v[2:3], v[2:3], v[240:241]
	v_pk_fma_f32 v[242:243], v[18:19], v[18:19], v[242:243]
	v_pk_fma_f32 v[244:245], v[34:35], v[34:35], v[244:245]
	v_pk_fma_f32 v[246:247], v[50:51], v[50:51], v[246:247]
	v_pk_fma_f32 v[240:241], v[4:5], v[4:5], v[240:241]
	v_pk_fma_f32 v[242:243], v[20:21], v[20:21], v[242:243]
	v_pk_fma_f32 v[244:245], v[36:37], v[36:37], v[244:245]
	v_pk_fma_f32 v[246:247], v[52:53], v[52:53], v[246:247]
	v_pk_fma_f32 v[240:241], v[6:7], v[6:7], v[240:241]
	v_pk_fma_f32 v[242:243], v[22:23], v[22:23], v[242:243]
	v_pk_fma_f32 v[244:245], v[38:39], v[38:39], v[244:245]
	v_pk_fma_f32 v[246:247], v[54:55], v[54:55], v[246:247]
	v_pk_fma_f32 v[240:241], v[8:9], v[8:9], v[240:241]
	v_pk_fma_f32 v[242:243], v[24:25], v[24:25], v[242:243]
	v_pk_fma_f32 v[244:245], v[40:41], v[40:41], v[244:245]
	v_pk_fma_f32 v[246:247], v[56:57], v[56:57], v[246:247]
	v_pk_fma_f32 v[240:241], v[10:11], v[10:11], v[240:241]
	v_pk_fma_f32 v[242:243], v[26:27], v[26:27], v[242:243]
	v_pk_fma_f32 v[244:245], v[42:43], v[42:43], v[244:245]
	v_pk_fma_f32 v[246:247], v[58:59], v[58:59], v[246:247]
	v_pk_fma_f32 v[240:241], v[12:13], v[12:13], v[240:241]
	v_pk_fma_f32 v[242:243], v[28:29], v[28:29], v[242:243]
	v_pk_fma_f32 v[244:245], v[44:45], v[44:45], v[244:245]
	v_pk_fma_f32 v[246:247], v[60:61], v[60:61], v[246:247]
	v_pk_fma_f32 v[240:241], v[14:15], v[14:15], v[240:241]
	v_pk_fma_f32 v[242:243], v[30:31], v[30:31], v[242:243]
	v_pk_fma_f32 v[244:245], v[46:47], v[46:47], v[244:245]
	v_pk_fma_f32 v[246:247], v[62:63], v[62:63], v[246:247]
	v_add_f32_e32 v224, v240, v241
	v_add_f32_e32 v225, v242, v243
	v_add_f32_e32 v226, v244, v245
	v_add_f32_e32 v227, v246, v247
	ds_bpermute_b32 v228, v83, v224
	ds_bpermute_b32 v229, v83, v225
	ds_bpermute_b32 v230, v83, v226
	ds_bpermute_b32 v231, v83, v227
	s_waitcnt lgkmcnt(0)
	v_add_f32_e32 v224, v224, v228
	v_add_f32_e32 v225, v225, v229
	v_add_f32_e32 v226, v226, v230
	v_add_f32_e32 v227, v227, v231
	ds_bpermute_b32 v228, v84, v224
	ds_bpermute_b32 v229, v84, v225
	ds_bpermute_b32 v230, v84, v226
	ds_bpermute_b32 v231, v84, v227
	s_waitcnt lgkmcnt(0)
	v_add_f32_e32 v224, v224, v228
	v_add_f32_e32 v225, v225, v229
	v_add_f32_e32 v226, v226, v230
	v_add_f32_e32 v227, v227, v231
	ds_bpermute_b32 v228, v85, v224
	ds_bpermute_b32 v229, v85, v225
	ds_bpermute_b32 v230, v85, v226
	ds_bpermute_b32 v231, v85, v227
	s_waitcnt lgkmcnt(0)
	v_add_f32_e32 v224, v224, v228
	v_add_f32_e32 v225, v225, v229
	v_add_f32_e32 v226, v226, v230
	v_add_f32_e32 v227, v227, v231
	ds_bpermute_b32 v228, v86, v224
	ds_bpermute_b32 v229, v86, v225
	ds_bpermute_b32 v230, v86, v226
	ds_bpermute_b32 v231, v86, v227
	s_waitcnt lgkmcnt(0)
	v_add_f32_e32 v224, v224, v228
	v_add_f32_e32 v225, v225, v229
	v_add_f32_e32 v226, v226, v230
	v_add_f32_e32 v227, v227, v231
	ds_bpermute_b32 v228, v87, v224
	ds_bpermute_b32 v229, v87, v225
	ds_bpermute_b32 v230, v87, v226
	ds_bpermute_b32 v231, v87, v227
	s_waitcnt lgkmcnt(0)
	v_add_f32_e32 v224, v224, v228
	v_add_f32_e32 v225, v225, v229
	v_add_f32_e32 v226, v226, v230
	v_add_f32_e32 v227, v227, v231
	ds_bpermute_b32 v228, v88, v224
	ds_bpermute_b32 v229, v88, v225
	ds_bpermute_b32 v230, v88, v226
	ds_bpermute_b32 v231, v88, v227
	s_waitcnt lgkmcnt(0)
; template <bool BF> __device__ __forceinline__ void prep_rows(const float* xp, const float* xs, const bf16* hb, const float* g, const float* MOD, int shoff, int scoff, bf16* U, int gw, int NGW, int lane) {
;     ...
;             for (int r = 0; r < R; ++r) s[r] += __shfl_xor(s[r], o); }
; #pragma unroll
;         for (int r = 0; r < R; ++r) { const int m = mb + r * NGW; if (m < MT) {
;             const float rstd = 1.0f / sqrtf(s[r] * (1.0f / DM) + RMS_EPS);
	v_add_f32_e32 v224, v224, v228
	v_add_f32_e32 v225, v225, v229
	v_add_f32_e32 v226, v226, v230
	v_add_f32_e32 v227, v227, v231
	v_fmamk_f32 v240, v224, 0x3a800000, v89
	v_mul_f32_e32 v241, 0x4f800000, v240
	v_cmp_gt_f32_e32 vcc, s54, v240
	s_nop 1
	v_cndmask_b32_e32 v247, v240, v241, vcc
	v_sqrt_f32_e32 v242, v247
	s_nop 1
	v_add_u32_e32 v243, -1, v242
	v_add_u32_e32 v244, 1, v242
	v_fma_f32 v245, -v243, v242, v247
	v_fma_f32 v246, -v244, v242, v247
	v_cmp_ge_f32_e64 s[52:53], 0, v245
	s_nop 1
	v_cndmask_b32_e64 v242, v242, v243, s[52:53]
	v_cmp_lt_f32_e64 s[52:53], 0, v246
	s_nop 1
	v_cndmask_b32_e64 v242, v242, v244, s[52:53]
	v_mul_f32_e32 v243, 0x37800000, v242
	v_cndmask_b32_e32 v242, v242, v243, vcc
	v_cmp_class_f32_e32 vcc, v247, v90
	s_nop 1
	v_cndmask_b32_e32 v247, v242, v247, vcc
	v_div_scale_f32 v248, s[52:53], v247, v247, 1.0
	v_rcp_f32_e32 v249, v248
	v_div_scale_f32 v228, vcc, 1.0, v247, 1.0
	s_nop 0
	v_fma_f32 v229, -v248, v249, 1.0
	v_fmac_f32_e32 v249, v229, v249
	v_mul_f32_e32 v230, v228, v249
	v_fma_f32 v229, -v248, v230, v228
	v_fmac_f32_e32 v230, v229, v249
	v_fma_f32 v248, -v248, v230, v228
	v_div_fmas_f32 v248, v248, v249, v230
	v_div_fixup_f32 v232, v248, v247, 1.0
	v_fmamk_f32 v240, v225, 0x3a800000, v89
	v_mul_f32_e32 v241, 0x4f800000, v240
	v_cmp_gt_f32_e32 vcc, s54, v240
	s_nop 1
	v_cndmask_b32_e32 v247, v240, v241, vcc
	v_sqrt_f32_e32 v242, v247
	s_nop 1
	v_add_u32_e32 v243, -1, v242
	v_add_u32_e32 v244, 1, v242
	v_fma_f32 v245, -v243, v242, v247
	v_fma_f32 v246, -v244, v242, v247
	v_cmp_ge_f32_e64 s[52:53], 0, v245
	s_nop 1
	v_cndmask_b32_e64 v242, v242, v243, s[52:53]
	v_cmp_lt_f32_e64 s[52:53], 0, v246
	s_nop 1
	v_cndmask_b32_e64 v242, v242, v244, s[52:53]
	v_mul_f32_e32 v243, 0x37800000, v242
	v_cndmask_b32_e32 v242, v242, v243, vcc
	v_cmp_class_f32_e32 vcc, v247, v90
	s_nop 1
	v_cndmask_b32_e32 v247, v242, v247, vcc
	v_div_scale_f32 v248, s[52:53], v247, v247, 1.0
	v_rcp_f32_e32 v249, v248
	v_div_scale_f32 v228, vcc, 1.0, v247, 1.0
	s_nop 0
	v_fma_f32 v229, -v248, v249, 1.0
	v_fmac_f32_e32 v249, v229, v249
	v_mul_f32_e32 v230, v228, v249
	v_fma_f32 v229, -v248, v230, v228
	v_fmac_f32_e32 v230, v229, v249
	v_fma_f32 v248, -v248, v230, v228
	v_div_fmas_f32 v248, v248, v249, v230
	v_div_fixup_f32 v234, v248, v247, 1.0
	v_fmamk_f32 v240, v226, 0x3a800000, v89
	v_mul_f32_e32 v241, 0x4f800000, v240
	v_cmp_gt_f32_e32 vcc, s54, v240
	s_nop 1
	v_cndmask_b32_e32 v247, v240, v241, vcc
	v_sqrt_f32_e32 v242, v247
	s_nop 1
	v_add_u32_e32 v243, -1, v242
	v_add_u32_e32 v244, 1, v242
	v_fma_f32 v245, -v243, v242, v247
	v_fma_f32 v246, -v244, v242, v247
	v_cmp_ge_f32_e64 s[52:53], 0, v245
	s_nop 1
	v_cndmask_b32_e64 v242, v242, v243, s[52:53]
	v_cmp_lt_f32_e64 s[52:53], 0, v246
	s_nop 1
	v_cndmask_b32_e64 v242, v242, v244, s[52:53]
	v_mul_f32_e32 v243, 0x37800000, v242
	v_cndmask_b32_e32 v242, v242, v243, vcc
	v_cmp_class_f32_e32 vcc, v247, v90
	s_nop 1
	v_cndmask_b32_e32 v247, v242, v247, vcc
	v_div_scale_f32 v248, s[52:53], v247, v247, 1.0
	v_rcp_f32_e32 v249, v248
	v_div_scale_f32 v228, vcc, 1.0, v247, 1.0
	s_nop 0
	v_fma_f32 v229, -v248, v249, 1.0
	v_fmac_f32_e32 v249, v229, v249
	v_mul_f32_e32 v230, v228, v249
	v_fma_f32 v229, -v248, v230, v228
	v_fmac_f32_e32 v230, v229, v249
	v_fma_f32 v248, -v248, v230, v228
	v_div_fmas_f32 v248, v248, v249, v230
	v_div_fixup_f32 v236, v248, v247, 1.0
	v_fmamk_f32 v240, v227, 0x3a800000, v89
	v_mul_f32_e32 v241, 0x4f800000, v240
	v_cmp_gt_f32_e32 vcc, s54, v240
	s_nop 1
	v_cndmask_b32_e32 v247, v240, v241, vcc
	v_sqrt_f32_e32 v242, v247
	s_nop 1
	v_add_u32_e32 v243, -1, v242
	v_add_u32_e32 v244, 1, v242
	v_fma_f32 v245, -v243, v242, v247
	v_fma_f32 v246, -v244, v242, v247
	v_cmp_ge_f32_e64 s[52:53], 0, v245
	s_nop 1
	v_cndmask_b32_e64 v242, v242, v243, s[52:53]
	v_cmp_lt_f32_e64 s[52:53], 0, v246
	s_nop 1
	v_cndmask_b32_e64 v242, v242, v244, s[52:53]
	v_mul_f32_e32 v243, 0x37800000, v242
	v_cndmask_b32_e32 v242, v242, v243, vcc
	v_cmp_class_f32_e32 vcc, v247, v90
	s_nop 1
	v_cndmask_b32_e32 v247, v242, v247, vcc
	v_div_scale_f32 v248, s[52:53], v247, v247, 1.0
	v_rcp_f32_e32 v249, v248
	v_div_scale_f32 v228, vcc, 1.0, v247, 1.0
	s_nop 0
	v_fma_f32 v229, -v248, v249, 1.0
	v_fmac_f32_e32 v249, v229, v249
	v_mul_f32_e32 v230, v228, v249
	v_fma_f32 v229, -v248, v230, v228
	v_fmac_f32_e32 v230, v229, v249
	v_fma_f32 v248, -v248, v230, v228
	v_div_fmas_f32 v248, v248, v249, v230
	v_div_fixup_f32 v238, v248, v247, 1.0
	s_waitcnt vmcnt(8)
; __device__ __forceinline__ unsigned pk2(float lo, float hi) { return pg8::cvt_pk_bf16(lo, hi); }
; template <bool BF> __device__ __forceinline__ void prep_rows(const float* xp, const float* xs, const bf16* hb, const float* g, const float* MOD, int shoff, int scoff, bf16* U, int gw, int NGW, int lane) {
;     ...
;         for (int r = 0; r < R; ++r) { const int m = mb + r * NGW; if (m < MT) {
;             const float rstd = 1.0f / sqrtf(s[r] * (1.0f / DM) + RMS_EPS);
;             const float* mr = MOD + (size_t)(m < MP ? (m >> 13) : 8 + ((m - MP) >> 12)) * 6144;
; #pragma unroll
;             for (int j = 0; j < 4; ++j) { const int c = 4 * lane + 256 * j;
;                 const f32x4 gg = *(const f32x4*)(g + c), sc = *(const f32x4*)(mr + scoff + c), sh = *(const f32x4*)(mr + shoff + c);
;                 const f32x4 o = v[r][j] * rstd * gg * (sc + 1.0f) + sh; v2u w; w.x = pk2(o.x, o.y); w.y = pk2(o.z, o.w); *(v2u*)(U + (size_t)m * DM + c) = w; } } }
	v_pk_add_f32 v[160:161], v[160:161], 1.0 op_sel_hi:[1,0]
	v_pk_add_f32 v[162:163], v[162:163], 1.0 op_sel_hi:[1,0]
	v_pk_add_f32 v[164:165], v[164:165], 1.0 op_sel_hi:[1,0]
	v_pk_add_f32 v[166:167], v[166:167], 1.0 op_sel_hi:[1,0]
	v_pk_add_f32 v[168:169], v[168:169], 1.0 op_sel_hi:[1,0]
	v_pk_add_f32 v[170:171], v[170:171], 1.0 op_sel_hi:[1,0]
	v_pk_add_f32 v[172:173], v[172:173], 1.0 op_sel_hi:[1,0]
	v_pk_add_f32 v[174:175], v[174:175], 1.0 op_sel_hi:[1,0]
	v_pk_add_f32 v[192:193], v[192:193], 1.0 op_sel_hi:[1,0]
	v_pk_add_f32 v[194:195], v[194:195], 1.0 op_sel_hi:[1,0]
	v_pk_add_f32 v[196:197], v[196:197], 1.0 op_sel_hi:[1,0]
	v_pk_add_f32 v[198:199], v[198:199], 1.0 op_sel_hi:[1,0]
	v_pk_add_f32 v[200:201], v[200:201], 1.0 op_sel_hi:[1,0]
	v_pk_add_f32 v[202:203], v[202:203], 1.0 op_sel_hi:[1,0]
	v_pk_add_f32 v[204:205], v[204:205], 1.0 op_sel_hi:[1,0]
	v_pk_add_f32 v[206:207], v[206:207], 1.0 op_sel_hi:[1,0]
	s_add_u32 s38, s20, 0x9000000
	s_addc_u32 s39, s21, 0
	s_add_u32 s40, s20, 0x9400000
	s_addc_u32 s41, s21, 0
	s_add_u32 s46, s20, 0x9800000
	s_addc_u32 s47, s21, 0
	s_add_u32 s48, s20, 0x9c00000
	s_addc_u32 s49, s21, 0
	v_pk_mul_f32 v[0:1], v[0:1], v[232:233] op_sel_hi:[1,0]
	v_pk_mul_f32 v[2:3], v[2:3], v[232:233] op_sel_hi:[1,0]
	v_pk_mul_f32 v[0:1], v[64:65], v[0:1]
	v_pk_mul_f32 v[2:3], v[66:67], v[2:3]
	v_pk_fma_f32 v[0:1], v[160:161], v[0:1], v[176:177]
	v_pk_fma_f32 v[2:3], v[162:163], v[2:3], v[178:179]
	v_cvt_pk_bf16_f32 v244, v0, v1
	v_cvt_pk_bf16_f32 v245, v2, v3
	v_pk_mul_f32 v[4:5], v[4:5], v[232:233] op_sel_hi:[1,0]
	v_pk_mul_f32 v[6:7], v[6:7], v[232:233] op_sel_hi:[1,0]
	v_pk_mul_f32 v[4:5], v[68:69], v[4:5]
	v_pk_mul_f32 v[6:7], v[70:71], v[6:7]
	v_pk_fma_f32 v[4:5], v[164:165], v[4:5], v[180:181]
	v_pk_fma_f32 v[6:7], v[166:167], v[6:7], v[182:183]
	v_cvt_pk_bf16_f32 v246, v4, v5
	v_cvt_pk_bf16_f32 v247, v6, v7
	global_store_dwordx4 v82, v[244:247], s[38:39] offset:0
	v_pk_mul_f32 v[8:9], v[8:9], v[232:233] op_sel_hi:[1,0]
	v_pk_mul_f32 v[10:11], v[10:11], v[232:233] op_sel_hi:[1,0]
	v_pk_mul_f32 v[8:9], v[72:73], v[8:9]
	v_pk_mul_f32 v[10:11], v[74:75], v[10:11]
	v_pk_fma_f32 v[8:9], v[168:169], v[8:9], v[184:185]
	v_pk_fma_f32 v[10:11], v[170:171], v[10:11], v[186:187]
	v_cvt_pk_bf16_f32 v240, v8, v9
	v_cvt_pk_bf16_f32 v241, v10, v11
	v_pk_mul_f32 v[12:13], v[12:13], v[232:233] op_sel_hi:[1,0]
	v_pk_mul_f32 v[14:15], v[14:15], v[232:233] op_sel_hi:[1,0]
	v_pk_mul_f32 v[12:13], v[76:77], v[12:13]
	v_pk_mul_f32 v[14:15], v[78:79], v[14:15]
	v_pk_fma_f32 v[12:13], v[172:173], v[12:13], v[188:189]
	v_pk_fma_f32 v[14:15], v[174:175], v[14:15], v[190:191]
	v_cvt_pk_bf16_f32 v242, v12, v13
	v_cvt_pk_bf16_f32 v243, v14, v15
	global_store_dwordx4 v82, v[240:243], s[38:39] offset:1024
	v_pk_mul_f32 v[16:17], v[16:17], v[234:235] op_sel_hi:[1,0]
	v_pk_mul_f32 v[18:19], v[18:19], v[234:235] op_sel_hi:[1,0]
	v_pk_mul_f32 v[16:17], v[64:65], v[16:17]
	v_pk_mul_f32 v[18:19], v[66:67], v[18:19]
	v_pk_fma_f32 v[16:17], v[160:161], v[16:17], v[176:177]
	v_pk_fma_f32 v[18:19], v[162:163], v[18:19], v[178:179]
	v_cvt_pk_bf16_f32 v244, v16, v17
	v_cvt_pk_bf16_f32 v245, v18, v19
	v_pk_mul_f32 v[20:21], v[20:21], v[234:235] op_sel_hi:[1,0]
	v_pk_mul_f32 v[22:23], v[22:23], v[234:235] op_sel_hi:[1,0]
	v_pk_mul_f32 v[20:21], v[68:69], v[20:21]
	v_pk_mul_f32 v[22:23], v[70:71], v[22:23]
	v_pk_fma_f32 v[20:21], v[164:165], v[20:21], v[180:181]
	v_pk_fma_f32 v[22:23], v[166:167], v[22:23], v[182:183]
	v_cvt_pk_bf16_f32 v246, v20, v21
	v_cvt_pk_bf16_f32 v247, v22, v23
	global_store_dwordx4 v82, v[244:247], s[40:41] offset:0
	v_pk_mul_f32 v[24:25], v[24:25], v[234:235] op_sel_hi:[1,0]
	v_pk_mul_f32 v[26:27], v[26:27], v[234:235] op_sel_hi:[1,0]
	v_pk_mul_f32 v[24:25], v[72:73], v[24:25]
	v_pk_mul_f32 v[26:27], v[74:75], v[26:27]
	v_pk_fma_f32 v[24:25], v[168:169], v[24:25], v[184:185]
	v_pk_fma_f32 v[26:27], v[170:171], v[26:27], v[186:187]
	v_cvt_pk_bf16_f32 v240, v24, v25
	v_cvt_pk_bf16_f32 v241, v26, v27
	v_pk_mul_f32 v[28:29], v[28:29], v[234:235] op_sel_hi:[1,0]
	v_pk_mul_f32 v[30:31], v[30:31], v[234:235] op_sel_hi:[1,0]
	v_pk_mul_f32 v[28:29], v[76:77], v[28:29]
	v_pk_mul_f32 v[30:31], v[78:79], v[30:31]
	v_pk_fma_f32 v[28:29], v[172:173], v[28:29], v[188:189]
	v_pk_fma_f32 v[30:31], v[174:175], v[30:31], v[190:191]
	v_cvt_pk_bf16_f32 v242, v28, v29
	v_cvt_pk_bf16_f32 v243, v30, v31
	global_store_dwordx4 v82, v[240:243], s[40:41] offset:1024
	v_pk_mul_f32 v[32:33], v[32:33], v[236:237] op_sel_hi:[1,0]
	v_pk_mul_f32 v[34:35], v[34:35], v[236:237] op_sel_hi:[1,0]
	v_pk_mul_f32 v[32:33], v[64:65], v[32:33]
	v_pk_mul_f32 v[34:35], v[66:67], v[34:35]
	v_pk_fma_f32 v[32:33], v[192:193], v[32:33], v[208:209]
	v_pk_fma_f32 v[34:35], v[194:195], v[34:35], v[210:211]
	v_cvt_pk_bf16_f32 v244, v32, v33
	v_cvt_pk_bf16_f32 v245, v34, v35
	v_pk_mul_f32 v[36:37], v[36:37], v[236:237] op_sel_hi:[1,0]
	v_pk_mul_f32 v[38:39], v[38:39], v[236:237] op_sel_hi:[1,0]
	v_pk_mul_f32 v[36:37], v[68:69], v[36:37]
	v_pk_mul_f32 v[38:39], v[70:71], v[38:39]
	v_pk_fma_f32 v[36:37], v[196:197], v[36:37], v[212:213]
	v_pk_fma_f32 v[38:39], v[198:199], v[38:39], v[214:215]
	v_cvt_pk_bf16_f32 v246, v36, v37
	v_cvt_pk_bf16_f32 v247, v38, v39
	global_store_dwordx4 v82, v[244:247], s[46:47] offset:0
	v_pk_mul_f32 v[40:41], v[40:41], v[236:237] op_sel_hi:[1,0]
	v_pk_mul_f32 v[42:43], v[42:43], v[236:237] op_sel_hi:[1,0]
	v_pk_mul_f32 v[40:41], v[72:73], v[40:41]
	v_pk_mul_f32 v[42:43], v[74:75], v[42:43]
	v_pk_fma_f32 v[40:41], v[200:201], v[40:41], v[216:217]
	v_pk_fma_f32 v[42:43], v[202:203], v[42:43], v[218:219]
	v_cvt_pk_bf16_f32 v240, v40, v41
; __device__ __forceinline__ float bf_lo(unsigned w) { return __uint_as_float(w << 16); }
; __device__ __forceinline__ float bf_hi(unsigned w) { return __uint_as_float(w & 0xffff0000u); }
; __device__ __forceinline__ unsigned pk2(float lo, float hi) { return pg8::cvt_pk_bf16(lo, hi); }
; template <bool BF> __device__ __forceinline__ void prep_rows(const float* xp, const float* xs, const bf16* hb, const float* g, const float* MOD, int shoff, int scoff, bf16* U, int gw, int NGW, int lane) {
;     ...
;         for (int r = 0; r < R; ++r) { const int m = mb + r * NGW; const int mc = m < MT ? m : mb;
; #pragma unroll
;             for (int j = 0; j < 4; ++j) {
;                 if (BF) { const v2u a0 = *(const v2u*)(hb + (size_t)mc * DM + 4 * lane + 256 * j);
;                     v[r][j].x = pg8::bf_lo(a0.x); v[r][j].y = pg8::bf_hi(a0.x); v[r][j].z = pg8::bf_lo(a0.y); v[r][j].w = pg8::bf_hi(a0.y); }
;                 else { const float* xr = mc < MP ? xp + (size_t)mc * DM : xs + (size_t)(mc - MP) * DM; v[r][j] = *(const f32x4*)(xr + 4 * lane + 256 * j); } } }
;     ...
;         for (int r = 0; r < R; ++r) { const int m = mb + r * NGW; if (m < MT) {
;             const float rstd = 1.0f / sqrtf(s[r] * (1.0f / DM) + RMS_EPS);
;             const float* mr = MOD + (size_t)(m < MP ? (m >> 13) : 8 + ((m - MP) >> 12)) * 6144;
; #pragma unroll
;             for (int j = 0; j < 4; ++j) { const int c = 4 * lane + 256 * j;
;                 const f32x4 gg = *(const f32x4*)(g + c), sc = *(const f32x4*)(mr + scoff + c), sh = *(const f32x4*)(mr + shoff + c);
;                 const f32x4 o = v[r][j] * rstd * gg * (sc + 1.0f) + sh; v2u w; w.x = pk2(o.x, o.y); w.y = pk2(o.z, o.w); *(v2u*)(U + (size_t)m * DM + c) = w; } } }
	v_cvt_pk_bf16_f32 v241, v42, v43
	v_pk_mul_f32 v[44:45], v[44:45], v[236:237] op_sel_hi:[1,0]
	v_pk_mul_f32 v[46:47], v[46:47], v[236:237] op_sel_hi:[1,0]
	v_pk_mul_f32 v[44:45], v[76:77], v[44:45]
	v_pk_mul_f32 v[46:47], v[78:79], v[46:47]
	v_pk_fma_f32 v[44:45], v[204:205], v[44:45], v[220:221]
	v_pk_fma_f32 v[46:47], v[206:207], v[46:47], v[222:223]
	v_cvt_pk_bf16_f32 v242, v44, v45
	v_cvt_pk_bf16_f32 v243, v46, v47
	global_store_dwordx4 v82, v[240:243], s[46:47] offset:1024
	v_pk_mul_f32 v[48:49], v[48:49], v[238:239] op_sel_hi:[1,0]
	v_pk_mul_f32 v[50:51], v[50:51], v[238:239] op_sel_hi:[1,0]
	v_pk_mul_f32 v[48:49], v[64:65], v[48:49]
	v_pk_mul_f32 v[50:51], v[66:67], v[50:51]
	v_pk_fma_f32 v[48:49], v[192:193], v[48:49], v[208:209]
	v_pk_fma_f32 v[50:51], v[194:195], v[50:51], v[210:211]
	v_cvt_pk_bf16_f32 v244, v48, v49
	v_cvt_pk_bf16_f32 v245, v50, v51
	v_pk_mul_f32 v[52:53], v[52:53], v[238:239] op_sel_hi:[1,0]
	v_pk_mul_f32 v[54:55], v[54:55], v[238:239] op_sel_hi:[1,0]
	v_pk_mul_f32 v[52:53], v[68:69], v[52:53]
	v_pk_mul_f32 v[54:55], v[70:71], v[54:55]
	v_pk_fma_f32 v[52:53], v[196:197], v[52:53], v[212:213]
	v_pk_fma_f32 v[54:55], v[198:199], v[54:55], v[214:215]
	v_cvt_pk_bf16_f32 v246, v52, v53
	v_cvt_pk_bf16_f32 v247, v54, v55
	global_store_dwordx4 v82, v[244:247], s[48:49] offset:0
	v_pk_mul_f32 v[56:57], v[56:57], v[238:239] op_sel_hi:[1,0]
	v_pk_mul_f32 v[58:59], v[58:59], v[238:239] op_sel_hi:[1,0]
	v_pk_mul_f32 v[56:57], v[72:73], v[56:57]
	v_pk_mul_f32 v[58:59], v[74:75], v[58:59]
	v_pk_fma_f32 v[56:57], v[200:201], v[56:57], v[216:217]
	v_pk_fma_f32 v[58:59], v[202:203], v[58:59], v[218:219]
	v_cvt_pk_bf16_f32 v240, v56, v57
	v_cvt_pk_bf16_f32 v241, v58, v59
	v_pk_mul_f32 v[60:61], v[60:61], v[238:239] op_sel_hi:[1,0]
	v_pk_mul_f32 v[62:63], v[62:63], v[238:239] op_sel_hi:[1,0]
	v_pk_mul_f32 v[60:61], v[76:77], v[60:61]
	v_pk_mul_f32 v[62:63], v[78:79], v[62:63]
	v_pk_fma_f32 v[60:61], v[204:205], v[60:61], v[220:221]
	v_pk_fma_f32 v[62:63], v[206:207], v[62:63], v[222:223]
	v_cvt_pk_bf16_f32 v242, v60, v61
	v_cvt_pk_bf16_f32 v243, v62, v63
	global_store_dwordx4 v82, v[240:243], s[48:49] offset:1024
	s_add_u32 s34, s8, 0x4b000
	s_addc_u32 s35, s9, 0
	s_add_u32 s36, s8, 0x51000
	s_addc_u32 s37, s9, 0
	global_load_dwordx4 v[176:179], v80, s[34:35] offset:0
	global_load_dwordx4 v[180:183], v80, s[34:35] offset:16
	global_load_dwordx4 v[184:187], v80, s[34:35] offset:2048
	global_load_dwordx4 v[188:191], v80, s[34:35] offset:2064
	global_load_dwordx4 v[160:163], v81, s[34:35] offset:0
	global_load_dwordx4 v[164:167], v81, s[34:35] offset:16
	global_load_dwordx4 v[168:171], v81, s[34:35] offset:2048
	global_load_dwordx4 v[172:175], v81, s[34:35] offset:2064
	global_load_dwordx4 v[208:211], v80, s[36:37] offset:0
	global_load_dwordx4 v[212:215], v80, s[36:37] offset:16
	global_load_dwordx4 v[216:219], v80, s[36:37] offset:2048
	global_load_dwordx4 v[220:223], v80, s[36:37] offset:2064
	global_load_dwordx4 v[192:195], v81, s[36:37] offset:0
	global_load_dwordx4 v[196:199], v81, s[36:37] offset:16
	global_load_dwordx4 v[200:203], v81, s[36:37] offset:2048
	global_load_dwordx4 v[204:207], v81, s[36:37] offset:2064
	s_add_u32 s24, s16, 0xb000000
	s_addc_u32 s25, s17, 0
	s_add_u32 s26, s16, 0xb400000
	s_addc_u32 s27, s17, 0
	s_add_u32 s28, s16, 0xb800000
	s_addc_u32 s29, s17, 0
	s_add_u32 s30, s16, 0xbc00000
	s_addc_u32 s31, s17, 0
	global_load_dwordx4 v[128:131], v82, s[24:25] offset:0
	global_load_dwordx4 v[132:135], v82, s[24:25] offset:1024
	global_load_dwordx4 v[136:139], v82, s[26:27] offset:0
	global_load_dwordx4 v[140:143], v82, s[26:27] offset:1024
	global_load_dwordx4 v[144:147], v82, s[28:29] offset:0
	global_load_dwordx4 v[148:151], v82, s[28:29] offset:1024
	global_load_dwordx4 v[152:155], v82, s[30:31] offset:0
	global_load_dwordx4 v[156:159], v82, s[30:31] offset:1024
	s_waitcnt vmcnt(32)
	v_lshlrev_b32_e32 v0, 16, v96
	v_and_b32_e32 v1, 0xffff0000, v96
	v_lshlrev_b32_e32 v2, 16, v97
	v_and_b32_e32 v3, 0xffff0000, v97
	v_lshlrev_b32_e32 v4, 16, v98
	v_and_b32_e32 v5, 0xffff0000, v98
	v_lshlrev_b32_e32 v6, 16, v99
	v_and_b32_e32 v7, 0xffff0000, v99
	v_lshlrev_b32_e32 v8, 16, v100
	v_and_b32_e32 v9, 0xffff0000, v100
	v_lshlrev_b32_e32 v10, 16, v101
	v_and_b32_e32 v11, 0xffff0000, v101
	v_lshlrev_b32_e32 v12, 16, v102
	v_and_b32_e32 v13, 0xffff0000, v102
	v_lshlrev_b32_e32 v14, 16, v103
	v_and_b32_e32 v15, 0xffff0000, v103
	v_lshlrev_b32_e32 v16, 16, v104
	v_and_b32_e32 v17, 0xffff0000, v104
	v_lshlrev_b32_e32 v18, 16, v105
	v_and_b32_e32 v19, 0xffff0000, v105
	v_lshlrev_b32_e32 v20, 16, v106
	v_and_b32_e32 v21, 0xffff0000, v106
	v_lshlrev_b32_e32 v22, 16, v107
	v_and_b32_e32 v23, 0xffff0000, v107
	v_lshlrev_b32_e32 v24, 16, v108
	v_and_b32_e32 v25, 0xffff0000, v108
	v_lshlrev_b32_e32 v26, 16, v109
	v_and_b32_e32 v27, 0xffff0000, v109
	v_lshlrev_b32_e32 v28, 16, v110
	v_and_b32_e32 v29, 0xffff0000, v110
	v_lshlrev_b32_e32 v30, 16, v111
	v_and_b32_e32 v31, 0xffff0000, v111
	v_lshlrev_b32_e32 v32, 16, v112
	v_and_b32_e32 v33, 0xffff0000, v112
	v_lshlrev_b32_e32 v34, 16, v113
	v_and_b32_e32 v35, 0xffff0000, v113
	v_lshlrev_b32_e32 v36, 16, v114
	v_and_b32_e32 v37, 0xffff0000, v114
	v_lshlrev_b32_e32 v38, 16, v115
	v_and_b32_e32 v39, 0xffff0000, v115
	v_lshlrev_b32_e32 v40, 16, v116
	v_and_b32_e32 v41, 0xffff0000, v116
	v_lshlrev_b32_e32 v42, 16, v117
	v_and_b32_e32 v43, 0xffff0000, v117
	v_lshlrev_b32_e32 v44, 16, v118
	v_and_b32_e32 v45, 0xffff0000, v118
	v_lshlrev_b32_e32 v46, 16, v119
	v_and_b32_e32 v47, 0xffff0000, v119
	v_lshlrev_b32_e32 v48, 16, v120
	v_and_b32_e32 v49, 0xffff0000, v120
	v_lshlrev_b32_e32 v50, 16, v121
; __device__ __forceinline__ float bf_lo(unsigned w) { return __uint_as_float(w << 16); }
; __device__ __forceinline__ float bf_hi(unsigned w) { return __uint_as_float(w & 0xffff0000u); }
; template <bool BF> __device__ __forceinline__ void prep_rows(const float* xp, const float* xs, const bf16* hb, const float* g, const float* MOD, int shoff, int scoff, bf16* U, int gw, int NGW, int lane) {
;     ...
;                 if (BF) { const v2u a0 = *(const v2u*)(hb + (size_t)mc * DM + 4 * lane + 256 * j);
;                     v[r][j].x = pg8::bf_lo(a0.x); v[r][j].y = pg8::bf_hi(a0.x); v[r][j].z = pg8::bf_lo(a0.y); v[r][j].w = pg8::bf_hi(a0.y); }
;                 else { const float* xr = mc < MP ? xp + (size_t)mc * DM : xs + (size_t)(mc - MP) * DM; v[r][j] = *(const f32x4*)(xr + 4 * lane + 256 * j); } } }
; #pragma unroll
;         for (int r = 0; r < R; ++r) { float t = 0.f;
; #pragma unroll
;             for (int j = 0; j < 4; ++j) t += (v[r][j].x * v[r][j].x + v[r][j].y * v[r][j].y) + (v[r][j].z * v[r][j].z + v[r][j].w * v[r][j].w);
;             s[r] = t; }
; #pragma unroll
;         for (int o = 1; o < 64; o <<= 1) {
; #pragma unroll
;             for (int r = 0; r < R; ++r) s[r] += __shfl_xor(s[r], o); }
; #pragma unroll
;         for (int r = 0; r < R; ++r) { const int m = mb + r * NGW; if (m < MT) {
;             const float rstd = 1.0f / sqrtf(s[r] * (1.0f / DM) + RMS_EPS);
	v_and_b32_e32 v51, 0xffff0000, v121
	v_lshlrev_b32_e32 v52, 16, v122
	v_and_b32_e32 v53, 0xffff0000, v122
	v_lshlrev_b32_e32 v54, 16, v123
	v_and_b32_e32 v55, 0xffff0000, v123
	v_lshlrev_b32_e32 v56, 16, v124
	v_and_b32_e32 v57, 0xffff0000, v124
	v_lshlrev_b32_e32 v58, 16, v125
	v_and_b32_e32 v59, 0xffff0000, v125
	v_lshlrev_b32_e32 v60, 16, v126
	v_and_b32_e32 v61, 0xffff0000, v126
	v_lshlrev_b32_e32 v62, 16, v127
	v_and_b32_e32 v63, 0xffff0000, v127
	v_pk_mul_f32 v[240:241], v[0:1], v[0:1]
	v_pk_mul_f32 v[242:243], v[16:17], v[16:17]
	v_pk_mul_f32 v[244:245], v[32:33], v[32:33]
	v_pk_mul_f32 v[246:247], v[48:49], v[48:49]
	v_pk_fma_f32 v[240:241], v[2:3], v[2:3], v[240:241]
	v_pk_fma_f32 v[242:243], v[18:19], v[18:19], v[242:243]
	v_pk_fma_f32 v[244:245], v[34:35], v[34:35], v[244:245]
	v_pk_fma_f32 v[246:247], v[50:51], v[50:51], v[246:247]
	v_pk_fma_f32 v[240:241], v[4:5], v[4:5], v[240:241]
	v_pk_fma_f32 v[242:243], v[20:21], v[20:21], v[242:243]
	v_pk_fma_f32 v[244:245], v[36:37], v[36:37], v[244:245]
	v_pk_fma_f32 v[246:247], v[52:53], v[52:53], v[246:247]
	v_pk_fma_f32 v[240:241], v[6:7], v[6:7], v[240:241]
	v_pk_fma_f32 v[242:243], v[22:23], v[22:23], v[242:243]
	v_pk_fma_f32 v[244:245], v[38:39], v[38:39], v[244:245]
	v_pk_fma_f32 v[246:247], v[54:55], v[54:55], v[246:247]
	v_pk_fma_f32 v[240:241], v[8:9], v[8:9], v[240:241]
	v_pk_fma_f32 v[242:243], v[24:25], v[24:25], v[242:243]
	v_pk_fma_f32 v[244:245], v[40:41], v[40:41], v[244:245]
	v_pk_fma_f32 v[246:247], v[56:57], v[56:57], v[246:247]
	v_pk_fma_f32 v[240:241], v[10:11], v[10:11], v[240:241]
	v_pk_fma_f32 v[242:243], v[26:27], v[26:27], v[242:243]
	v_pk_fma_f32 v[244:245], v[42:43], v[42:43], v[244:245]
	v_pk_fma_f32 v[246:247], v[58:59], v[58:59], v[246:247]
	v_pk_fma_f32 v[240:241], v[12:13], v[12:13], v[240:241]
	v_pk_fma_f32 v[242:243], v[28:29], v[28:29], v[242:243]
	v_pk_fma_f32 v[244:245], v[44:45], v[44:45], v[244:245]
	v_pk_fma_f32 v[246:247], v[60:61], v[60:61], v[246:247]
	v_pk_fma_f32 v[240:241], v[14:15], v[14:15], v[240:241]
	v_pk_fma_f32 v[242:243], v[30:31], v[30:31], v[242:243]
	v_pk_fma_f32 v[244:245], v[46:47], v[46:47], v[244:245]
	v_pk_fma_f32 v[246:247], v[62:63], v[62:63], v[246:247]
	v_add_f32_e32 v224, v240, v241
	v_add_f32_e32 v225, v242, v243
	v_add_f32_e32 v226, v244, v245
	v_add_f32_e32 v227, v246, v247
	ds_bpermute_b32 v228, v83, v224
	ds_bpermute_b32 v229, v83, v225
	ds_bpermute_b32 v230, v83, v226
	ds_bpermute_b32 v231, v83, v227
	s_waitcnt lgkmcnt(0)
	v_add_f32_e32 v224, v224, v228
	v_add_f32_e32 v225, v225, v229
	v_add_f32_e32 v226, v226, v230
	v_add_f32_e32 v227, v227, v231
	ds_bpermute_b32 v228, v84, v224
	ds_bpermute_b32 v229, v84, v225
	ds_bpermute_b32 v230, v84, v226
	ds_bpermute_b32 v231, v84, v227
	s_waitcnt lgkmcnt(0)
	v_add_f32_e32 v224, v224, v228
	v_add_f32_e32 v225, v225, v229
	v_add_f32_e32 v226, v226, v230
	v_add_f32_e32 v227, v227, v231
	ds_bpermute_b32 v228, v85, v224
	ds_bpermute_b32 v229, v85, v225
	ds_bpermute_b32 v230, v85, v226
	ds_bpermute_b32 v231, v85, v227
	s_waitcnt lgkmcnt(0)
	v_add_f32_e32 v224, v224, v228
	v_add_f32_e32 v225, v225, v229
	v_add_f32_e32 v226, v226, v230
	v_add_f32_e32 v227, v227, v231
	ds_bpermute_b32 v228, v86, v224
	ds_bpermute_b32 v229, v86, v225
	ds_bpermute_b32 v230, v86, v226
	ds_bpermute_b32 v231, v86, v227
	s_waitcnt lgkmcnt(0)
	v_add_f32_e32 v224, v224, v228
	v_add_f32_e32 v225, v225, v229
	v_add_f32_e32 v226, v226, v230
	v_add_f32_e32 v227, v227, v231
	ds_bpermute_b32 v228, v87, v224
	ds_bpermute_b32 v229, v87, v225
	ds_bpermute_b32 v230, v87, v226
	ds_bpermute_b32 v231, v87, v227
	s_waitcnt lgkmcnt(0)
	v_add_f32_e32 v224, v224, v228
	v_add_f32_e32 v225, v225, v229
	v_add_f32_e32 v226, v226, v230
	v_add_f32_e32 v227, v227, v231
	ds_bpermute_b32 v228, v88, v224
	ds_bpermute_b32 v229, v88, v225
	ds_bpermute_b32 v230, v88, v226
	ds_bpermute_b32 v231, v88, v227
	s_waitcnt lgkmcnt(0)
	v_add_f32_e32 v224, v224, v228
	v_add_f32_e32 v225, v225, v229
	v_add_f32_e32 v226, v226, v230
	v_add_f32_e32 v227, v227, v231
	v_fmamk_f32 v240, v224, 0x3a800000, v89
	v_mul_f32_e32 v241, 0x4f800000, v240
	v_cmp_gt_f32_e32 vcc, s54, v240
	s_nop 1
	v_cndmask_b32_e32 v247, v240, v241, vcc
	v_sqrt_f32_e32 v242, v247
	s_nop 1
	v_add_u32_e32 v243, -1, v242
	v_add_u32_e32 v244, 1, v242
	v_fma_f32 v245, -v243, v242, v247
	v_fma_f32 v246, -v244, v242, v247
	v_cmp_ge_f32_e64 s[52:53], 0, v245
	s_nop 1
	v_cndmask_b32_e64 v242, v242, v243, s[52:53]
	v_cmp_lt_f32_e64 s[52:53], 0, v246
	s_nop 1
	v_cndmask_b32_e64 v242, v242, v244, s[52:53]
	v_mul_f32_e32 v243, 0x37800000, v242
	v_cndmask_b32_e32 v242, v242, v243, vcc
	v_cmp_class_f32_e32 vcc, v247, v90
	s_nop 1
	v_cndmask_b32_e32 v247, v242, v247, vcc
	v_div_scale_f32 v248, s[52:53], v247, v247, 1.0
	v_rcp_f32_e32 v249, v248
	v_div_scale_f32 v228, vcc, 1.0, v247, 1.0
	s_nop 0
	v_fma_f32 v229, -v248, v249, 1.0
	v_fmac_f32_e32 v249, v229, v249
	v_mul_f32_e32 v230, v228, v249
	v_fma_f32 v229, -v248, v230, v228
	v_fmac_f32_e32 v230, v229, v249
	v_fma_f32 v248, -v248, v230, v228
	v_div_fmas_f32 v248, v248, v249, v230
	v_div_fixup_f32 v232, v248, v247, 1.0
	v_fmamk_f32 v240, v225, 0x3a800000, v89
	v_mul_f32_e32 v241, 0x4f800000, v240
	v_cmp_gt_f32_e32 vcc, s54, v240
	s_nop 1
	v_cndmask_b32_e32 v247, v240, v241, vcc
	v_sqrt_f32_e32 v242, v247
	s_nop 1
	v_add_u32_e32 v243, -1, v242
	v_add_u32_e32 v244, 1, v242
	v_fma_f32 v245, -v243, v242, v247
	v_fma_f32 v246, -v244, v242, v247
	v_cmp_ge_f32_e64 s[52:53], 0, v245
	s_nop 1
	v_cndmask_b32_e64 v242, v242, v243, s[52:53]
	v_cmp_lt_f32_e64 s[52:53], 0, v246
	s_nop 1
	v_cndmask_b32_e64 v242, v242, v244, s[52:53]
; __device__ __forceinline__ unsigned pk2(float lo, float hi) { return pg8::cvt_pk_bf16(lo, hi); }
; template <bool BF> __device__ __forceinline__ void prep_rows(const float* xp, const float* xs, const bf16* hb, const float* g, const float* MOD, int shoff, int scoff, bf16* U, int gw, int NGW, int lane) {
;     ...
;         for (int r = 0; r < R; ++r) { const int m = mb + r * NGW; if (m < MT) {
;             const float rstd = 1.0f / sqrtf(s[r] * (1.0f / DM) + RMS_EPS);
;             const float* mr = MOD + (size_t)(m < MP ? (m >> 13) : 8 + ((m - MP) >> 12)) * 6144;
; #pragma unroll
;             for (int j = 0; j < 4; ++j) { const int c = 4 * lane + 256 * j;
;                 const f32x4 gg = *(const f32x4*)(g + c), sc = *(const f32x4*)(mr + scoff + c), sh = *(const f32x4*)(mr + shoff + c);
;                 const f32x4 o = v[r][j] * rstd * gg * (sc + 1.0f) + sh; v2u w; w.x = pk2(o.x, o.y); w.y = pk2(o.z, o.w); *(v2u*)(U + (size_t)m * DM + c) = w; } } }
	v_mul_f32_e32 v243, 0x37800000, v242
	v_cndmask_b32_e32 v242, v242, v243, vcc
	v_cmp_class_f32_e32 vcc, v247, v90
	s_nop 1
	v_cndmask_b32_e32 v247, v242, v247, vcc
	v_div_scale_f32 v248, s[52:53], v247, v247, 1.0
	v_rcp_f32_e32 v249, v248
	v_div_scale_f32 v228, vcc, 1.0, v247, 1.0
	s_nop 0
	v_fma_f32 v229, -v248, v249, 1.0
	v_fmac_f32_e32 v249, v229, v249
	v_mul_f32_e32 v230, v228, v249
	v_fma_f32 v229, -v248, v230, v228
	v_fmac_f32_e32 v230, v229, v249
	v_fma_f32 v248, -v248, v230, v228
	v_div_fmas_f32 v248, v248, v249, v230
	v_div_fixup_f32 v234, v248, v247, 1.0
	v_fmamk_f32 v240, v226, 0x3a800000, v89
	v_mul_f32_e32 v241, 0x4f800000, v240
	v_cmp_gt_f32_e32 vcc, s54, v240
	s_nop 1
	v_cndmask_b32_e32 v247, v240, v241, vcc
	v_sqrt_f32_e32 v242, v247
	s_nop 1
	v_add_u32_e32 v243, -1, v242
	v_add_u32_e32 v244, 1, v242
	v_fma_f32 v245, -v243, v242, v247
	v_fma_f32 v246, -v244, v242, v247
	v_cmp_ge_f32_e64 s[52:53], 0, v245
	s_nop 1
	v_cndmask_b32_e64 v242, v242, v243, s[52:53]
	v_cmp_lt_f32_e64 s[52:53], 0, v246
	s_nop 1
	v_cndmask_b32_e64 v242, v242, v244, s[52:53]
	v_mul_f32_e32 v243, 0x37800000, v242
	v_cndmask_b32_e32 v242, v242, v243, vcc
	v_cmp_class_f32_e32 vcc, v247, v90
	s_nop 1
	v_cndmask_b32_e32 v247, v242, v247, vcc
	v_div_scale_f32 v248, s[52:53], v247, v247, 1.0
	v_rcp_f32_e32 v249, v248
	v_div_scale_f32 v228, vcc, 1.0, v247, 1.0
	s_nop 0
	v_fma_f32 v229, -v248, v249, 1.0
	v_fmac_f32_e32 v249, v229, v249
	v_mul_f32_e32 v230, v228, v249
	v_fma_f32 v229, -v248, v230, v228
	v_fmac_f32_e32 v230, v229, v249
	v_fma_f32 v248, -v248, v230, v228
	v_div_fmas_f32 v248, v248, v249, v230
	v_div_fixup_f32 v236, v248, v247, 1.0
	v_fmamk_f32 v240, v227, 0x3a800000, v89
	v_mul_f32_e32 v241, 0x4f800000, v240
	v_cmp_gt_f32_e32 vcc, s54, v240
	s_nop 1
	v_cndmask_b32_e32 v247, v240, v241, vcc
	v_sqrt_f32_e32 v242, v247
	s_nop 1
	v_add_u32_e32 v243, -1, v242
	v_add_u32_e32 v244, 1, v242
	v_fma_f32 v245, -v243, v242, v247
	v_fma_f32 v246, -v244, v242, v247
	v_cmp_ge_f32_e64 s[52:53], 0, v245
	s_nop 1
	v_cndmask_b32_e64 v242, v242, v243, s[52:53]
	v_cmp_lt_f32_e64 s[52:53], 0, v246
	s_nop 1
	v_cndmask_b32_e64 v242, v242, v244, s[52:53]
	v_mul_f32_e32 v243, 0x37800000, v242
	v_cndmask_b32_e32 v242, v242, v243, vcc
	v_cmp_class_f32_e32 vcc, v247, v90
	s_nop 1
	v_cndmask_b32_e32 v247, v242, v247, vcc
	v_div_scale_f32 v248, s[52:53], v247, v247, 1.0
	v_rcp_f32_e32 v249, v248
	v_div_scale_f32 v228, vcc, 1.0, v247, 1.0
	s_nop 0
	v_fma_f32 v229, -v248, v249, 1.0
	v_fmac_f32_e32 v249, v229, v249
	v_mul_f32_e32 v230, v228, v249
	v_fma_f32 v229, -v248, v230, v228
	v_fmac_f32_e32 v230, v229, v249
	v_fma_f32 v248, -v248, v230, v228
	v_div_fmas_f32 v248, v248, v249, v230
	v_div_fixup_f32 v238, v248, v247, 1.0
	s_waitcnt vmcnt(8)
	v_pk_add_f32 v[160:161], v[160:161], 1.0 op_sel_hi:[1,0]
	v_pk_add_f32 v[162:163], v[162:163], 1.0 op_sel_hi:[1,0]
	v_pk_add_f32 v[164:165], v[164:165], 1.0 op_sel_hi:[1,0]
	v_pk_add_f32 v[166:167], v[166:167], 1.0 op_sel_hi:[1,0]
	v_pk_add_f32 v[168:169], v[168:169], 1.0 op_sel_hi:[1,0]
	v_pk_add_f32 v[170:171], v[170:171], 1.0 op_sel_hi:[1,0]
	v_pk_add_f32 v[172:173], v[172:173], 1.0 op_sel_hi:[1,0]
	v_pk_add_f32 v[174:175], v[174:175], 1.0 op_sel_hi:[1,0]
	v_pk_add_f32 v[192:193], v[192:193], 1.0 op_sel_hi:[1,0]
	v_pk_add_f32 v[194:195], v[194:195], 1.0 op_sel_hi:[1,0]
	v_pk_add_f32 v[196:197], v[196:197], 1.0 op_sel_hi:[1,0]
	v_pk_add_f32 v[198:199], v[198:199], 1.0 op_sel_hi:[1,0]
	v_pk_add_f32 v[200:201], v[200:201], 1.0 op_sel_hi:[1,0]
	v_pk_add_f32 v[202:203], v[202:203], 1.0 op_sel_hi:[1,0]
	v_pk_add_f32 v[204:205], v[204:205], 1.0 op_sel_hi:[1,0]
	v_pk_add_f32 v[206:207], v[206:207], 1.0 op_sel_hi:[1,0]
	s_add_u32 s38, s20, 0xa000000
	s_addc_u32 s39, s21, 0
	s_add_u32 s40, s20, 0xa400000
	s_addc_u32 s41, s21, 0
	s_add_u32 s46, s20, 0xa800000
	s_addc_u32 s47, s21, 0
	s_add_u32 s48, s20, 0xac00000
	s_addc_u32 s49, s21, 0
	v_pk_mul_f32 v[0:1], v[0:1], v[232:233] op_sel_hi:[1,0]
	v_pk_mul_f32 v[2:3], v[2:3], v[232:233] op_sel_hi:[1,0]
	v_pk_mul_f32 v[0:1], v[64:65], v[0:1]
	v_pk_mul_f32 v[2:3], v[66:67], v[2:3]
	v_pk_fma_f32 v[0:1], v[160:161], v[0:1], v[176:177]
	v_pk_fma_f32 v[2:3], v[162:163], v[2:3], v[178:179]
	v_cvt_pk_bf16_f32 v244, v0, v1
	v_cvt_pk_bf16_f32 v245, v2, v3
	v_pk_mul_f32 v[4:5], v[4:5], v[232:233] op_sel_hi:[1,0]
	v_pk_mul_f32 v[6:7], v[6:7], v[232:233] op_sel_hi:[1,0]
	v_pk_mul_f32 v[4:5], v[68:69], v[4:5]
	v_pk_mul_f32 v[6:7], v[70:71], v[6:7]
	v_pk_fma_f32 v[4:5], v[164:165], v[4:5], v[180:181]
	v_pk_fma_f32 v[6:7], v[166:167], v[6:7], v[182:183]
	v_cvt_pk_bf16_f32 v246, v4, v5
	v_cvt_pk_bf16_f32 v247, v6, v7
	global_store_dwordx4 v82, v[244:247], s[38:39] offset:0
	v_pk_mul_f32 v[8:9], v[8:9], v[232:233] op_sel_hi:[1,0]
	v_pk_mul_f32 v[10:11], v[10:11], v[232:233] op_sel_hi:[1,0]
	v_pk_mul_f32 v[8:9], v[72:73], v[8:9]
	v_pk_mul_f32 v[10:11], v[74:75], v[10:11]
	v_pk_fma_f32 v[8:9], v[168:169], v[8:9], v[184:185]
	v_pk_fma_f32 v[10:11], v[170:171], v[10:11], v[186:187]
	v_cvt_pk_bf16_f32 v240, v8, v9
	v_cvt_pk_bf16_f32 v241, v10, v11
	v_pk_mul_f32 v[12:13], v[12:13], v[232:233] op_sel_hi:[1,0]
	v_pk_mul_f32 v[14:15], v[14:15], v[232:233] op_sel_hi:[1,0]
	v_pk_mul_f32 v[12:13], v[76:77], v[12:13]
	v_pk_mul_f32 v[14:15], v[78:79], v[14:15]
	v_pk_fma_f32 v[12:13], v[172:173], v[12:13], v[188:189]
	v_pk_fma_f32 v[14:15], v[174:175], v[14:15], v[190:191]
	v_cvt_pk_bf16_f32 v242, v12, v13
	v_cvt_pk_bf16_f32 v243, v14, v15
	global_store_dwordx4 v82, v[240:243], s[38:39] offset:1024
	v_pk_mul_f32 v[16:17], v[16:17], v[234:235] op_sel_hi:[1,0]
	v_pk_mul_f32 v[18:19], v[18:19], v[234:235] op_sel_hi:[1,0]
; __device__ __forceinline__ unsigned pk2(float lo, float hi) { return pg8::cvt_pk_bf16(lo, hi); }
; template <bool BF> __device__ __forceinline__ void prep_rows(const float* xp, const float* xs, const bf16* hb, const float* g, const float* MOD, int shoff, int scoff, bf16* U, int gw, int NGW, int lane) {
;     ...
;         for (int r = 0; r < R; ++r) { const int m = mb + r * NGW; if (m < MT) {
;             const float rstd = 1.0f / sqrtf(s[r] * (1.0f / DM) + RMS_EPS);
;             const float* mr = MOD + (size_t)(m < MP ? (m >> 13) : 8 + ((m - MP) >> 12)) * 6144;
; #pragma unroll
;             for (int j = 0; j < 4; ++j) { const int c = 4 * lane + 256 * j;
;                 const f32x4 gg = *(const f32x4*)(g + c), sc = *(const f32x4*)(mr + scoff + c), sh = *(const f32x4*)(mr + shoff + c);
;                 const f32x4 o = v[r][j] * rstd * gg * (sc + 1.0f) + sh; v2u w; w.x = pk2(o.x, o.y); w.y = pk2(o.z, o.w); *(v2u*)(U + (size_t)m * DM + c) = w; } } }
	v_pk_mul_f32 v[16:17], v[64:65], v[16:17]
	v_pk_mul_f32 v[18:19], v[66:67], v[18:19]
	v_pk_fma_f32 v[16:17], v[160:161], v[16:17], v[176:177]
	v_pk_fma_f32 v[18:19], v[162:163], v[18:19], v[178:179]
	v_cvt_pk_bf16_f32 v244, v16, v17
	v_cvt_pk_bf16_f32 v245, v18, v19
	v_pk_mul_f32 v[20:21], v[20:21], v[234:235] op_sel_hi:[1,0]
	v_pk_mul_f32 v[22:23], v[22:23], v[234:235] op_sel_hi:[1,0]
	v_pk_mul_f32 v[20:21], v[68:69], v[20:21]
	v_pk_mul_f32 v[22:23], v[70:71], v[22:23]
	v_pk_fma_f32 v[20:21], v[164:165], v[20:21], v[180:181]
	v_pk_fma_f32 v[22:23], v[166:167], v[22:23], v[182:183]
	v_cvt_pk_bf16_f32 v246, v20, v21
	v_cvt_pk_bf16_f32 v247, v22, v23
	global_store_dwordx4 v82, v[244:247], s[40:41] offset:0
	v_pk_mul_f32 v[24:25], v[24:25], v[234:235] op_sel_hi:[1,0]
	v_pk_mul_f32 v[26:27], v[26:27], v[234:235] op_sel_hi:[1,0]
	v_pk_mul_f32 v[24:25], v[72:73], v[24:25]
	v_pk_mul_f32 v[26:27], v[74:75], v[26:27]
	v_pk_fma_f32 v[24:25], v[168:169], v[24:25], v[184:185]
	v_pk_fma_f32 v[26:27], v[170:171], v[26:27], v[186:187]
	v_cvt_pk_bf16_f32 v240, v24, v25
	v_cvt_pk_bf16_f32 v241, v26, v27
	v_pk_mul_f32 v[28:29], v[28:29], v[234:235] op_sel_hi:[1,0]
	v_pk_mul_f32 v[30:31], v[30:31], v[234:235] op_sel_hi:[1,0]
	v_pk_mul_f32 v[28:29], v[76:77], v[28:29]
	v_pk_mul_f32 v[30:31], v[78:79], v[30:31]
	v_pk_fma_f32 v[28:29], v[172:173], v[28:29], v[188:189]
	v_pk_fma_f32 v[30:31], v[174:175], v[30:31], v[190:191]
	v_cvt_pk_bf16_f32 v242, v28, v29
	v_cvt_pk_bf16_f32 v243, v30, v31
	global_store_dwordx4 v82, v[240:243], s[40:41] offset:1024
	v_pk_mul_f32 v[32:33], v[32:33], v[236:237] op_sel_hi:[1,0]
	v_pk_mul_f32 v[34:35], v[34:35], v[236:237] op_sel_hi:[1,0]
	v_pk_mul_f32 v[32:33], v[64:65], v[32:33]
	v_pk_mul_f32 v[34:35], v[66:67], v[34:35]
	v_pk_fma_f32 v[32:33], v[192:193], v[32:33], v[208:209]
	v_pk_fma_f32 v[34:35], v[194:195], v[34:35], v[210:211]
	v_cvt_pk_bf16_f32 v244, v32, v33
	v_cvt_pk_bf16_f32 v245, v34, v35
	v_pk_mul_f32 v[36:37], v[36:37], v[236:237] op_sel_hi:[1,0]
	v_pk_mul_f32 v[38:39], v[38:39], v[236:237] op_sel_hi:[1,0]
	v_pk_mul_f32 v[36:37], v[68:69], v[36:37]
	v_pk_mul_f32 v[38:39], v[70:71], v[38:39]
	v_pk_fma_f32 v[36:37], v[196:197], v[36:37], v[212:213]
	v_pk_fma_f32 v[38:39], v[198:199], v[38:39], v[214:215]
	v_cvt_pk_bf16_f32 v246, v36, v37
	v_cvt_pk_bf16_f32 v247, v38, v39
	global_store_dwordx4 v82, v[244:247], s[46:47] offset:0
	v_pk_mul_f32 v[40:41], v[40:41], v[236:237] op_sel_hi:[1,0]
	v_pk_mul_f32 v[42:43], v[42:43], v[236:237] op_sel_hi:[1,0]
	v_pk_mul_f32 v[40:41], v[72:73], v[40:41]
	v_pk_mul_f32 v[42:43], v[74:75], v[42:43]
	v_pk_fma_f32 v[40:41], v[200:201], v[40:41], v[216:217]
	v_pk_fma_f32 v[42:43], v[202:203], v[42:43], v[218:219]
	v_cvt_pk_bf16_f32 v240, v40, v41
	v_cvt_pk_bf16_f32 v241, v42, v43
	v_pk_mul_f32 v[44:45], v[44:45], v[236:237] op_sel_hi:[1,0]
	v_pk_mul_f32 v[46:47], v[46:47], v[236:237] op_sel_hi:[1,0]
	v_pk_mul_f32 v[44:45], v[76:77], v[44:45]
	v_pk_mul_f32 v[46:47], v[78:79], v[46:47]
	v_pk_fma_f32 v[44:45], v[204:205], v[44:45], v[220:221]
	v_pk_fma_f32 v[46:47], v[206:207], v[46:47], v[222:223]
	v_cvt_pk_bf16_f32 v242, v44, v45
	v_cvt_pk_bf16_f32 v243, v46, v47
	global_store_dwordx4 v82, v[240:243], s[46:47] offset:1024
	v_pk_mul_f32 v[48:49], v[48:49], v[238:239] op_sel_hi:[1,0]
	v_pk_mul_f32 v[50:51], v[50:51], v[238:239] op_sel_hi:[1,0]
	v_pk_mul_f32 v[48:49], v[64:65], v[48:49]
	v_pk_mul_f32 v[50:51], v[66:67], v[50:51]
	v_pk_fma_f32 v[48:49], v[192:193], v[48:49], v[208:209]
	v_pk_fma_f32 v[50:51], v[194:195], v[50:51], v[210:211]
	v_cvt_pk_bf16_f32 v244, v48, v49
	v_cvt_pk_bf16_f32 v245, v50, v51
	v_pk_mul_f32 v[52:53], v[52:53], v[238:239] op_sel_hi:[1,0]
	v_pk_mul_f32 v[54:55], v[54:55], v[238:239] op_sel_hi:[1,0]
	v_pk_mul_f32 v[52:53], v[68:69], v[52:53]
	v_pk_mul_f32 v[54:55], v[70:71], v[54:55]
	v_pk_fma_f32 v[52:53], v[196:197], v[52:53], v[212:213]
	v_pk_fma_f32 v[54:55], v[198:199], v[54:55], v[214:215]
	v_cvt_pk_bf16_f32 v246, v52, v53
	v_cvt_pk_bf16_f32 v247, v54, v55
	global_store_dwordx4 v82, v[244:247], s[48:49] offset:0
	v_pk_mul_f32 v[56:57], v[56:57], v[238:239] op_sel_hi:[1,0]
	v_pk_mul_f32 v[58:59], v[58:59], v[238:239] op_sel_hi:[1,0]
	v_pk_mul_f32 v[56:57], v[72:73], v[56:57]
	v_pk_mul_f32 v[58:59], v[74:75], v[58:59]
	v_pk_fma_f32 v[56:57], v[200:201], v[56:57], v[216:217]
	v_pk_fma_f32 v[58:59], v[202:203], v[58:59], v[218:219]
	v_cvt_pk_bf16_f32 v240, v56, v57
	v_cvt_pk_bf16_f32 v241, v58, v59
	v_pk_mul_f32 v[60:61], v[60:61], v[238:239] op_sel_hi:[1,0]
	v_pk_mul_f32 v[62:63], v[62:63], v[238:239] op_sel_hi:[1,0]
	v_pk_mul_f32 v[60:61], v[76:77], v[60:61]
	v_pk_mul_f32 v[62:63], v[78:79], v[62:63]
	v_pk_fma_f32 v[60:61], v[204:205], v[60:61], v[220:221]
	v_pk_fma_f32 v[62:63], v[206:207], v[62:63], v[222:223]
	v_cvt_pk_bf16_f32 v242, v60, v61
	v_cvt_pk_bf16_f32 v243, v62, v63
	global_store_dwordx4 v82, v[240:243], s[48:49] offset:1024
	s_add_u32 s34, s8, 0x57000
	s_addc_u32 s35, s9, 0
	s_add_u32 s36, s8, 0x5d000
	s_addc_u32 s37, s9, 0
	global_load_dwordx4 v[176:179], v80, s[34:35] offset:0
	global_load_dwordx4 v[180:183], v80, s[34:35] offset:16
	global_load_dwordx4 v[184:187], v80, s[34:35] offset:2048
	global_load_dwordx4 v[188:191], v80, s[34:35] offset:2064
	global_load_dwordx4 v[160:163], v81, s[34:35] offset:0
	global_load_dwordx4 v[164:167], v81, s[34:35] offset:16
	global_load_dwordx4 v[168:171], v81, s[34:35] offset:2048
	global_load_dwordx4 v[172:175], v81, s[34:35] offset:2064
	global_load_dwordx4 v[208:211], v80, s[36:37] offset:0
	global_load_dwordx4 v[212:215], v80, s[36:37] offset:16
	global_load_dwordx4 v[216:219], v80, s[36:37] offset:2048
	global_load_dwordx4 v[220:223], v80, s[36:37] offset:2064
	global_load_dwordx4 v[192:195], v81, s[36:37] offset:0
	global_load_dwordx4 v[196:199], v81, s[36:37] offset:16
	global_load_dwordx4 v[200:203], v81, s[36:37] offset:2048
	global_load_dwordx4 v[204:207], v81, s[36:37] offset:2064
	s_waitcnt vmcnt(24)
; __device__ __forceinline__ float bf_lo(unsigned w) { return __uint_as_float(w << 16); }
; __device__ __forceinline__ float bf_hi(unsigned w) { return __uint_as_float(w & 0xffff0000u); }
; template <bool BF> __device__ __forceinline__ void prep_rows(const float* xp, const float* xs, const bf16* hb, const float* g, const float* MOD, int shoff, int scoff, bf16* U, int gw, int NGW, int lane) {
;     ...
;                 if (BF) { const v2u a0 = *(const v2u*)(hb + (size_t)mc * DM + 4 * lane + 256 * j);
;                     v[r][j].x = pg8::bf_lo(a0.x); v[r][j].y = pg8::bf_hi(a0.x); v[r][j].z = pg8::bf_lo(a0.y); v[r][j].w = pg8::bf_hi(a0.y); }
;                 else { const float* xr = mc < MP ? xp + (size_t)mc * DM : xs + (size_t)(mc - MP) * DM; v[r][j] = *(const f32x4*)(xr + 4 * lane + 256 * j); } } }
; #pragma unroll
;         for (int r = 0; r < R; ++r) { float t = 0.f;
; #pragma unroll
;             for (int j = 0; j < 4; ++j) t += (v[r][j].x * v[r][j].x + v[r][j].y * v[r][j].y) + (v[r][j].z * v[r][j].z + v[r][j].w * v[r][j].w);
;             s[r] = t; }
; #pragma unroll
;         for (int o = 1; o < 64; o <<= 1) {
; #pragma unroll
;             for (int r = 0; r < R; ++r) s[r] += __shfl_xor(s[r], o); }
	v_lshlrev_b32_e32 v0, 16, v128
	v_and_b32_e32 v1, 0xffff0000, v128
	v_lshlrev_b32_e32 v2, 16, v129
	v_and_b32_e32 v3, 0xffff0000, v129
	v_lshlrev_b32_e32 v4, 16, v130
	v_and_b32_e32 v5, 0xffff0000, v130
	v_lshlrev_b32_e32 v6, 16, v131
	v_and_b32_e32 v7, 0xffff0000, v131
	v_lshlrev_b32_e32 v8, 16, v132
	v_and_b32_e32 v9, 0xffff0000, v132
	v_lshlrev_b32_e32 v10, 16, v133
	v_and_b32_e32 v11, 0xffff0000, v133
	v_lshlrev_b32_e32 v12, 16, v134
	v_and_b32_e32 v13, 0xffff0000, v134
	v_lshlrev_b32_e32 v14, 16, v135
	v_and_b32_e32 v15, 0xffff0000, v135
	v_lshlrev_b32_e32 v16, 16, v136
	v_and_b32_e32 v17, 0xffff0000, v136
	v_lshlrev_b32_e32 v18, 16, v137
	v_and_b32_e32 v19, 0xffff0000, v137
	v_lshlrev_b32_e32 v20, 16, v138
	v_and_b32_e32 v21, 0xffff0000, v138
	v_lshlrev_b32_e32 v22, 16, v139
	v_and_b32_e32 v23, 0xffff0000, v139
	v_lshlrev_b32_e32 v24, 16, v140
	v_and_b32_e32 v25, 0xffff0000, v140
	v_lshlrev_b32_e32 v26, 16, v141
	v_and_b32_e32 v27, 0xffff0000, v141
	v_lshlrev_b32_e32 v28, 16, v142
	v_and_b32_e32 v29, 0xffff0000, v142
	v_lshlrev_b32_e32 v30, 16, v143
	v_and_b32_e32 v31, 0xffff0000, v143
	v_lshlrev_b32_e32 v32, 16, v144
	v_and_b32_e32 v33, 0xffff0000, v144
	v_lshlrev_b32_e32 v34, 16, v145
	v_and_b32_e32 v35, 0xffff0000, v145
	v_lshlrev_b32_e32 v36, 16, v146
	v_and_b32_e32 v37, 0xffff0000, v146
	v_lshlrev_b32_e32 v38, 16, v147
	v_and_b32_e32 v39, 0xffff0000, v147
	v_lshlrev_b32_e32 v40, 16, v148
	v_and_b32_e32 v41, 0xffff0000, v148
	v_lshlrev_b32_e32 v42, 16, v149
	v_and_b32_e32 v43, 0xffff0000, v149
	v_lshlrev_b32_e32 v44, 16, v150
	v_and_b32_e32 v45, 0xffff0000, v150
	v_lshlrev_b32_e32 v46, 16, v151
	v_and_b32_e32 v47, 0xffff0000, v151
	v_lshlrev_b32_e32 v48, 16, v152
	v_and_b32_e32 v49, 0xffff0000, v152
	v_lshlrev_b32_e32 v50, 16, v153
	v_and_b32_e32 v51, 0xffff0000, v153
	v_lshlrev_b32_e32 v52, 16, v154
	v_and_b32_e32 v53, 0xffff0000, v154
	v_lshlrev_b32_e32 v54, 16, v155
	v_and_b32_e32 v55, 0xffff0000, v155
	v_lshlrev_b32_e32 v56, 16, v156
	v_and_b32_e32 v57, 0xffff0000, v156
	v_lshlrev_b32_e32 v58, 16, v157
	v_and_b32_e32 v59, 0xffff0000, v157
	v_lshlrev_b32_e32 v60, 16, v158
	v_and_b32_e32 v61, 0xffff0000, v158
	v_lshlrev_b32_e32 v62, 16, v159
	v_and_b32_e32 v63, 0xffff0000, v159
	v_pk_mul_f32 v[240:241], v[0:1], v[0:1]
	v_pk_mul_f32 v[242:243], v[16:17], v[16:17]
	v_pk_mul_f32 v[244:245], v[32:33], v[32:33]
	v_pk_mul_f32 v[246:247], v[48:49], v[48:49]
	v_pk_fma_f32 v[240:241], v[2:3], v[2:3], v[240:241]
	v_pk_fma_f32 v[242:243], v[18:19], v[18:19], v[242:243]
	v_pk_fma_f32 v[244:245], v[34:35], v[34:35], v[244:245]
	v_pk_fma_f32 v[246:247], v[50:51], v[50:51], v[246:247]
	v_pk_fma_f32 v[240:241], v[4:5], v[4:5], v[240:241]
	v_pk_fma_f32 v[242:243], v[20:21], v[20:21], v[242:243]
	v_pk_fma_f32 v[244:245], v[36:37], v[36:37], v[244:245]
	v_pk_fma_f32 v[246:247], v[52:53], v[52:53], v[246:247]
	v_pk_fma_f32 v[240:241], v[6:7], v[6:7], v[240:241]
	v_pk_fma_f32 v[242:243], v[22:23], v[22:23], v[242:243]
	v_pk_fma_f32 v[244:245], v[38:39], v[38:39], v[244:245]
	v_pk_fma_f32 v[246:247], v[54:55], v[54:55], v[246:247]
	v_pk_fma_f32 v[240:241], v[8:9], v[8:9], v[240:241]
	v_pk_fma_f32 v[242:243], v[24:25], v[24:25], v[242:243]
	v_pk_fma_f32 v[244:245], v[40:41], v[40:41], v[244:245]
	v_pk_fma_f32 v[246:247], v[56:57], v[56:57], v[246:247]
	v_pk_fma_f32 v[240:241], v[10:11], v[10:11], v[240:241]
	v_pk_fma_f32 v[242:243], v[26:27], v[26:27], v[242:243]
	v_pk_fma_f32 v[244:245], v[42:43], v[42:43], v[244:245]
	v_pk_fma_f32 v[246:247], v[58:59], v[58:59], v[246:247]
	v_pk_fma_f32 v[240:241], v[12:13], v[12:13], v[240:241]
	v_pk_fma_f32 v[242:243], v[28:29], v[28:29], v[242:243]
	v_pk_fma_f32 v[244:245], v[44:45], v[44:45], v[244:245]
	v_pk_fma_f32 v[246:247], v[60:61], v[60:61], v[246:247]
	v_pk_fma_f32 v[240:241], v[14:15], v[14:15], v[240:241]
	v_pk_fma_f32 v[242:243], v[30:31], v[30:31], v[242:243]
	v_pk_fma_f32 v[244:245], v[46:47], v[46:47], v[244:245]
	v_pk_fma_f32 v[246:247], v[62:63], v[62:63], v[246:247]
	v_add_f32_e32 v224, v240, v241
	v_add_f32_e32 v225, v242, v243
	v_add_f32_e32 v226, v244, v245
	v_add_f32_e32 v227, v246, v247
	ds_bpermute_b32 v228, v83, v224
	ds_bpermute_b32 v229, v83, v225
	ds_bpermute_b32 v230, v83, v226
	ds_bpermute_b32 v231, v83, v227
	s_waitcnt lgkmcnt(0)
	v_add_f32_e32 v224, v224, v228
	v_add_f32_e32 v225, v225, v229
	v_add_f32_e32 v226, v226, v230
	v_add_f32_e32 v227, v227, v231
	ds_bpermute_b32 v228, v84, v224
	ds_bpermute_b32 v229, v84, v225
	ds_bpermute_b32 v230, v84, v226
	ds_bpermute_b32 v231, v84, v227
	s_waitcnt lgkmcnt(0)
	v_add_f32_e32 v224, v224, v228
	v_add_f32_e32 v225, v225, v229
	v_add_f32_e32 v226, v226, v230
	v_add_f32_e32 v227, v227, v231
	ds_bpermute_b32 v228, v85, v224
	ds_bpermute_b32 v229, v85, v225
	ds_bpermute_b32 v230, v85, v226
	ds_bpermute_b32 v231, v85, v227
	s_waitcnt lgkmcnt(0)
	v_add_f32_e32 v224, v224, v228
	v_add_f32_e32 v225, v225, v229
	v_add_f32_e32 v226, v226, v230
	v_add_f32_e32 v227, v227, v231
	ds_bpermute_b32 v228, v86, v224
	ds_bpermute_b32 v229, v86, v225
	ds_bpermute_b32 v230, v86, v226
	ds_bpermute_b32 v231, v86, v227
	s_waitcnt lgkmcnt(0)
	v_add_f32_e32 v224, v224, v228
	v_add_f32_e32 v225, v225, v229
	v_add_f32_e32 v226, v226, v230
	v_add_f32_e32 v227, v227, v231
	ds_bpermute_b32 v228, v87, v224
	ds_bpermute_b32 v229, v87, v225
	ds_bpermute_b32 v230, v87, v226
	ds_bpermute_b32 v231, v87, v227
	s_waitcnt lgkmcnt(0)
	v_add_f32_e32 v224, v224, v228
	v_add_f32_e32 v225, v225, v229
	v_add_f32_e32 v226, v226, v230
	v_add_f32_e32 v227, v227, v231
	ds_bpermute_b32 v228, v88, v224
	ds_bpermute_b32 v229, v88, v225
	ds_bpermute_b32 v230, v88, v226
	ds_bpermute_b32 v231, v88, v227
	s_waitcnt lgkmcnt(0)
; template <bool BF> __device__ __forceinline__ void prep_rows(const float* xp, const float* xs, const bf16* hb, const float* g, const float* MOD, int shoff, int scoff, bf16* U, int gw, int NGW, int lane) {
;     ...
;             for (int r = 0; r < R; ++r) s[r] += __shfl_xor(s[r], o); }
; #pragma unroll
;         for (int r = 0; r < R; ++r) { const int m = mb + r * NGW; if (m < MT) {
;             const float rstd = 1.0f / sqrtf(s[r] * (1.0f / DM) + RMS_EPS);
	v_add_f32_e32 v224, v224, v228
	v_add_f32_e32 v225, v225, v229
	v_add_f32_e32 v226, v226, v230
	v_add_f32_e32 v227, v227, v231
	v_fmamk_f32 v240, v224, 0x3a800000, v89
	v_mul_f32_e32 v241, 0x4f800000, v240
	v_cmp_gt_f32_e32 vcc, s54, v240
	s_nop 1
	v_cndmask_b32_e32 v247, v240, v241, vcc
	v_sqrt_f32_e32 v242, v247
	s_nop 1
	v_add_u32_e32 v243, -1, v242
	v_add_u32_e32 v244, 1, v242
	v_fma_f32 v245, -v243, v242, v247
	v_fma_f32 v246, -v244, v242, v247
	v_cmp_ge_f32_e64 s[52:53], 0, v245
	s_nop 1
	v_cndmask_b32_e64 v242, v242, v243, s[52:53]
	v_cmp_lt_f32_e64 s[52:53], 0, v246
	s_nop 1
	v_cndmask_b32_e64 v242, v242, v244, s[52:53]
	v_mul_f32_e32 v243, 0x37800000, v242
	v_cndmask_b32_e32 v242, v242, v243, vcc
	v_cmp_class_f32_e32 vcc, v247, v90
	s_nop 1
	v_cndmask_b32_e32 v247, v242, v247, vcc
	v_div_scale_f32 v248, s[52:53], v247, v247, 1.0
	v_rcp_f32_e32 v249, v248
	v_div_scale_f32 v228, vcc, 1.0, v247, 1.0
	s_nop 0
	v_fma_f32 v229, -v248, v249, 1.0
	v_fmac_f32_e32 v249, v229, v249
	v_mul_f32_e32 v230, v228, v249
	v_fma_f32 v229, -v248, v230, v228
	v_fmac_f32_e32 v230, v229, v249
	v_fma_f32 v248, -v248, v230, v228
	v_div_fmas_f32 v248, v248, v249, v230
	v_div_fixup_f32 v232, v248, v247, 1.0
	v_fmamk_f32 v240, v225, 0x3a800000, v89
	v_mul_f32_e32 v241, 0x4f800000, v240
	v_cmp_gt_f32_e32 vcc, s54, v240
	s_nop 1
	v_cndmask_b32_e32 v247, v240, v241, vcc
	v_sqrt_f32_e32 v242, v247
	s_nop 1
	v_add_u32_e32 v243, -1, v242
	v_add_u32_e32 v244, 1, v242
	v_fma_f32 v245, -v243, v242, v247
	v_fma_f32 v246, -v244, v242, v247
	v_cmp_ge_f32_e64 s[52:53], 0, v245
	s_nop 1
	v_cndmask_b32_e64 v242, v242, v243, s[52:53]
	v_cmp_lt_f32_e64 s[52:53], 0, v246
	s_nop 1
	v_cndmask_b32_e64 v242, v242, v244, s[52:53]
	v_mul_f32_e32 v243, 0x37800000, v242
	v_cndmask_b32_e32 v242, v242, v243, vcc
	v_cmp_class_f32_e32 vcc, v247, v90
	s_nop 1
	v_cndmask_b32_e32 v247, v242, v247, vcc
	v_div_scale_f32 v248, s[52:53], v247, v247, 1.0
	v_rcp_f32_e32 v249, v248
	v_div_scale_f32 v228, vcc, 1.0, v247, 1.0
	s_nop 0
	v_fma_f32 v229, -v248, v249, 1.0
	v_fmac_f32_e32 v249, v229, v249
	v_mul_f32_e32 v230, v228, v249
	v_fma_f32 v229, -v248, v230, v228
	v_fmac_f32_e32 v230, v229, v249
	v_fma_f32 v248, -v248, v230, v228
	v_div_fmas_f32 v248, v248, v249, v230
	v_div_fixup_f32 v234, v248, v247, 1.0
	v_fmamk_f32 v240, v226, 0x3a800000, v89
	v_mul_f32_e32 v241, 0x4f800000, v240
	v_cmp_gt_f32_e32 vcc, s54, v240
	s_nop 1
	v_cndmask_b32_e32 v247, v240, v241, vcc
	v_sqrt_f32_e32 v242, v247
	s_nop 1
	v_add_u32_e32 v243, -1, v242
	v_add_u32_e32 v244, 1, v242
	v_fma_f32 v245, -v243, v242, v247
	v_fma_f32 v246, -v244, v242, v247
	v_cmp_ge_f32_e64 s[52:53], 0, v245
	s_nop 1
	v_cndmask_b32_e64 v242, v242, v243, s[52:53]
	v_cmp_lt_f32_e64 s[52:53], 0, v246
	s_nop 1
	v_cndmask_b32_e64 v242, v242, v244, s[52:53]
	v_mul_f32_e32 v243, 0x37800000, v242
	v_cndmask_b32_e32 v242, v242, v243, vcc
	v_cmp_class_f32_e32 vcc, v247, v90
	s_nop 1
	v_cndmask_b32_e32 v247, v242, v247, vcc
	v_div_scale_f32 v248, s[52:53], v247, v247, 1.0
	v_rcp_f32_e32 v249, v248
	v_div_scale_f32 v228, vcc, 1.0, v247, 1.0
	s_nop 0
	v_fma_f32 v229, -v248, v249, 1.0
	v_fmac_f32_e32 v249, v229, v249
	v_mul_f32_e32 v230, v228, v249
	v_fma_f32 v229, -v248, v230, v228
	v_fmac_f32_e32 v230, v229, v249
	v_fma_f32 v248, -v248, v230, v228
	v_div_fmas_f32 v248, v248, v249, v230
	v_div_fixup_f32 v236, v248, v247, 1.0
	v_fmamk_f32 v240, v227, 0x3a800000, v89
	v_mul_f32_e32 v241, 0x4f800000, v240
	v_cmp_gt_f32_e32 vcc, s54, v240
	s_nop 1
	v_cndmask_b32_e32 v247, v240, v241, vcc
	v_sqrt_f32_e32 v242, v247
	s_nop 1
	v_add_u32_e32 v243, -1, v242
	v_add_u32_e32 v244, 1, v242
	v_fma_f32 v245, -v243, v242, v247
	v_fma_f32 v246, -v244, v242, v247
	v_cmp_ge_f32_e64 s[52:53], 0, v245
	s_nop 1
	v_cndmask_b32_e64 v242, v242, v243, s[52:53]
	v_cmp_lt_f32_e64 s[52:53], 0, v246
	s_nop 1
	v_cndmask_b32_e64 v242, v242, v244, s[52:53]
	v_mul_f32_e32 v243, 0x37800000, v242
	v_cndmask_b32_e32 v242, v242, v243, vcc
	v_cmp_class_f32_e32 vcc, v247, v90
	s_nop 1
	v_cndmask_b32_e32 v247, v242, v247, vcc
	v_div_scale_f32 v248, s[52:53], v247, v247, 1.0
	v_rcp_f32_e32 v249, v248
	v_div_scale_f32 v228, vcc, 1.0, v247, 1.0
	s_nop 0
	v_fma_f32 v229, -v248, v249, 1.0
	v_fmac_f32_e32 v249, v229, v249
	v_mul_f32_e32 v230, v228, v249
	v_fma_f32 v229, -v248, v230, v228
	v_fmac_f32_e32 v230, v229, v249
	v_fma_f32 v248, -v248, v230, v228
	v_div_fmas_f32 v248, v248, v249, v230
	v_div_fixup_f32 v238, v248, v247, 1.0
	s_waitcnt vmcnt(0)
; __device__ __forceinline__ unsigned pk2(float lo, float hi) { return pg8::cvt_pk_bf16(lo, hi); }
; template <bool BF> __device__ __forceinline__ void prep_rows(const float* xp, const float* xs, const bf16* hb, const float* g, const float* MOD, int shoff, int scoff, bf16* U, int gw, int NGW, int lane) {
;     ...
;         for (int r = 0; r < R; ++r) { const int m = mb + r * NGW; if (m < MT) {
;             const float rstd = 1.0f / sqrtf(s[r] * (1.0f / DM) + RMS_EPS);
;             const float* mr = MOD + (size_t)(m < MP ? (m >> 13) : 8 + ((m - MP) >> 12)) * 6144;
; #pragma unroll
;             for (int j = 0; j < 4; ++j) { const int c = 4 * lane + 256 * j;
;                 const f32x4 gg = *(const f32x4*)(g + c), sc = *(const f32x4*)(mr + scoff + c), sh = *(const f32x4*)(mr + shoff + c);
;                 const f32x4 o = v[r][j] * rstd * gg * (sc + 1.0f) + sh; v2u w; w.x = pk2(o.x, o.y); w.y = pk2(o.z, o.w); *(v2u*)(U + (size_t)m * DM + c) = w; } } }
	v_pk_add_f32 v[160:161], v[160:161], 1.0 op_sel_hi:[1,0]
	v_pk_add_f32 v[162:163], v[162:163], 1.0 op_sel_hi:[1,0]
	v_pk_add_f32 v[164:165], v[164:165], 1.0 op_sel_hi:[1,0]
	v_pk_add_f32 v[166:167], v[166:167], 1.0 op_sel_hi:[1,0]
	v_pk_add_f32 v[168:169], v[168:169], 1.0 op_sel_hi:[1,0]
	v_pk_add_f32 v[170:171], v[170:171], 1.0 op_sel_hi:[1,0]
	v_pk_add_f32 v[172:173], v[172:173], 1.0 op_sel_hi:[1,0]
	v_pk_add_f32 v[174:175], v[174:175], 1.0 op_sel_hi:[1,0]
	v_pk_add_f32 v[192:193], v[192:193], 1.0 op_sel_hi:[1,0]
	v_pk_add_f32 v[194:195], v[194:195], 1.0 op_sel_hi:[1,0]
	v_pk_add_f32 v[196:197], v[196:197], 1.0 op_sel_hi:[1,0]
	v_pk_add_f32 v[198:199], v[198:199], 1.0 op_sel_hi:[1,0]
	v_pk_add_f32 v[200:201], v[200:201], 1.0 op_sel_hi:[1,0]
	v_pk_add_f32 v[202:203], v[202:203], 1.0 op_sel_hi:[1,0]
	v_pk_add_f32 v[204:205], v[204:205], 1.0 op_sel_hi:[1,0]
	v_pk_add_f32 v[206:207], v[206:207], 1.0 op_sel_hi:[1,0]
	s_add_u32 s38, s20, 0xb000000
	s_addc_u32 s39, s21, 0
	s_add_u32 s40, s20, 0xb400000
	s_addc_u32 s41, s21, 0
	s_add_u32 s46, s20, 0xb800000
	s_addc_u32 s47, s21, 0
	s_add_u32 s48, s20, 0xbc00000
	s_addc_u32 s49, s21, 0
	v_pk_mul_f32 v[0:1], v[0:1], v[232:233] op_sel_hi:[1,0]
	v_pk_mul_f32 v[2:3], v[2:3], v[232:233] op_sel_hi:[1,0]
	v_pk_mul_f32 v[0:1], v[64:65], v[0:1]
	v_pk_mul_f32 v[2:3], v[66:67], v[2:3]
	v_pk_fma_f32 v[0:1], v[160:161], v[0:1], v[176:177]
	v_pk_fma_f32 v[2:3], v[162:163], v[2:3], v[178:179]
	v_cvt_pk_bf16_f32 v244, v0, v1
	v_cvt_pk_bf16_f32 v245, v2, v3
	v_pk_mul_f32 v[4:5], v[4:5], v[232:233] op_sel_hi:[1,0]
	v_pk_mul_f32 v[6:7], v[6:7], v[232:233] op_sel_hi:[1,0]
	v_pk_mul_f32 v[4:5], v[68:69], v[4:5]
	v_pk_mul_f32 v[6:7], v[70:71], v[6:7]
	v_pk_fma_f32 v[4:5], v[164:165], v[4:5], v[180:181]
	v_pk_fma_f32 v[6:7], v[166:167], v[6:7], v[182:183]
	v_cvt_pk_bf16_f32 v246, v4, v5
	v_cvt_pk_bf16_f32 v247, v6, v7
	global_store_dwordx4 v82, v[244:247], s[38:39] offset:0
	v_pk_mul_f32 v[8:9], v[8:9], v[232:233] op_sel_hi:[1,0]
	v_pk_mul_f32 v[10:11], v[10:11], v[232:233] op_sel_hi:[1,0]
	v_pk_mul_f32 v[8:9], v[72:73], v[8:9]
	v_pk_mul_f32 v[10:11], v[74:75], v[10:11]
	v_pk_fma_f32 v[8:9], v[168:169], v[8:9], v[184:185]
	v_pk_fma_f32 v[10:11], v[170:171], v[10:11], v[186:187]
	v_cvt_pk_bf16_f32 v240, v8, v9
	v_cvt_pk_bf16_f32 v241, v10, v11
	v_pk_mul_f32 v[12:13], v[12:13], v[232:233] op_sel_hi:[1,0]
	v_pk_mul_f32 v[14:15], v[14:15], v[232:233] op_sel_hi:[1,0]
	v_pk_mul_f32 v[12:13], v[76:77], v[12:13]
	v_pk_mul_f32 v[14:15], v[78:79], v[14:15]
	v_pk_fma_f32 v[12:13], v[172:173], v[12:13], v[188:189]
	v_pk_fma_f32 v[14:15], v[174:175], v[14:15], v[190:191]
	v_cvt_pk_bf16_f32 v242, v12, v13
	v_cvt_pk_bf16_f32 v243, v14, v15
	global_store_dwordx4 v82, v[240:243], s[38:39] offset:1024
	v_pk_mul_f32 v[16:17], v[16:17], v[234:235] op_sel_hi:[1,0]
	v_pk_mul_f32 v[18:19], v[18:19], v[234:235] op_sel_hi:[1,0]
	v_pk_mul_f32 v[16:17], v[64:65], v[16:17]
	v_pk_mul_f32 v[18:19], v[66:67], v[18:19]
	v_pk_fma_f32 v[16:17], v[160:161], v[16:17], v[176:177]
	v_pk_fma_f32 v[18:19], v[162:163], v[18:19], v[178:179]
	v_cvt_pk_bf16_f32 v244, v16, v17
	v_cvt_pk_bf16_f32 v245, v18, v19
	v_pk_mul_f32 v[20:21], v[20:21], v[234:235] op_sel_hi:[1,0]
	v_pk_mul_f32 v[22:23], v[22:23], v[234:235] op_sel_hi:[1,0]
	v_pk_mul_f32 v[20:21], v[68:69], v[20:21]
	v_pk_mul_f32 v[22:23], v[70:71], v[22:23]
	v_pk_fma_f32 v[20:21], v[164:165], v[20:21], v[180:181]
	v_pk_fma_f32 v[22:23], v[166:167], v[22:23], v[182:183]
	v_cvt_pk_bf16_f32 v246, v20, v21
	v_cvt_pk_bf16_f32 v247, v22, v23
	global_store_dwordx4 v82, v[244:247], s[40:41] offset:0
	v_pk_mul_f32 v[24:25], v[24:25], v[234:235] op_sel_hi:[1,0]
	v_pk_mul_f32 v[26:27], v[26:27], v[234:235] op_sel_hi:[1,0]
	v_pk_mul_f32 v[24:25], v[72:73], v[24:25]
	v_pk_mul_f32 v[26:27], v[74:75], v[26:27]
	v_pk_fma_f32 v[24:25], v[168:169], v[24:25], v[184:185]
	v_pk_fma_f32 v[26:27], v[170:171], v[26:27], v[186:187]
	v_cvt_pk_bf16_f32 v240, v24, v25
	v_cvt_pk_bf16_f32 v241, v26, v27
	v_pk_mul_f32 v[28:29], v[28:29], v[234:235] op_sel_hi:[1,0]
	v_pk_mul_f32 v[30:31], v[30:31], v[234:235] op_sel_hi:[1,0]
	v_pk_mul_f32 v[28:29], v[76:77], v[28:29]
	v_pk_mul_f32 v[30:31], v[78:79], v[30:31]
	v_pk_fma_f32 v[28:29], v[172:173], v[28:29], v[188:189]
	v_pk_fma_f32 v[30:31], v[174:175], v[30:31], v[190:191]
	v_cvt_pk_bf16_f32 v242, v28, v29
	v_cvt_pk_bf16_f32 v243, v30, v31
	global_store_dwordx4 v82, v[240:243], s[40:41] offset:1024
	v_pk_mul_f32 v[32:33], v[32:33], v[236:237] op_sel_hi:[1,0]
	v_pk_mul_f32 v[34:35], v[34:35], v[236:237] op_sel_hi:[1,0]
	v_pk_mul_f32 v[32:33], v[64:65], v[32:33]
	v_pk_mul_f32 v[34:35], v[66:67], v[34:35]
	v_pk_fma_f32 v[32:33], v[192:193], v[32:33], v[208:209]
	v_pk_fma_f32 v[34:35], v[194:195], v[34:35], v[210:211]
	v_cvt_pk_bf16_f32 v244, v32, v33
	v_cvt_pk_bf16_f32 v245, v34, v35
	v_pk_mul_f32 v[36:37], v[36:37], v[236:237] op_sel_hi:[1,0]
	v_pk_mul_f32 v[38:39], v[38:39], v[236:237] op_sel_hi:[1,0]
	v_pk_mul_f32 v[36:37], v[68:69], v[36:37]
; __device__ __forceinline__ float bf_lo(unsigned w) { return __uint_as_float(w << 16); }
; __device__ __forceinline__ float bf_hi(unsigned w) { return __uint_as_float(w & 0xffff0000u); }
; __device__ __forceinline__ unsigned pk2(float lo, float hi) { return pg8::cvt_pk_bf16(lo, hi); }
; template <bool BF> __device__ __forceinline__ void prep_rows(const float* xp, const float* xs, const bf16* hb, const float* g, const float* MOD, int shoff, int scoff, bf16* U, int gw, int NGW, int lane) {
;     constexpr int R = 4;
;     for (int mb = gw; mb < MT; mb += R * NGW) {
;         f32x4 v[R][4]; float s[R];
; #pragma unroll
;         for (int r = 0; r < R; ++r) { const int m = mb + r * NGW; const int mc = m < MT ? m : mb;
; #pragma unroll
;             for (int j = 0; j < 4; ++j) {
;                 if (BF) { const v2u a0 = *(const v2u*)(hb + (size_t)mc * DM + 4 * lane + 256 * j);
;                     v[r][j].x = pg8::bf_lo(a0.x); v[r][j].y = pg8::bf_hi(a0.x); v[r][j].z = pg8::bf_lo(a0.y); v[r][j].w = pg8::bf_hi(a0.y); }
;                 else { const float* xr = mc < MP ? xp + (size_t)mc * DM : xs + (size_t)(mc - MP) * DM; v[r][j] = *(const f32x4*)(xr + 4 * lane + 256 * j); } } }
; #pragma unroll
;         for (int r = 0; r < R; ++r) { float t = 0.f;
; #pragma unroll
;             for (int j = 0; j < 4; ++j) t += (v[r][j].x * v[r][j].x + v[r][j].y * v[r][j].y) + (v[r][j].z * v[r][j].z + v[r][j].w * v[r][j].w);
;             s[r] = t; }
; #pragma unroll
;         for (int o = 1; o < 64; o <<= 1) {
; #pragma unroll
;             for (int r = 0; r < R; ++r) s[r] += __shfl_xor(s[r], o); }
; #pragma unroll
;         for (int r = 0; r < R; ++r) { const int m = mb + r * NGW; if (m < MT) {
;             const float rstd = 1.0f / sqrtf(s[r] * (1.0f / DM) + RMS_EPS);
;             const float* mr = MOD + (size_t)(m < MP ? (m >> 13) : 8 + ((m - MP) >> 12)) * 6144;
; #pragma unroll
;             for (int j = 0; j < 4; ++j) { const int c = 4 * lane + 256 * j;
;                 const f32x4 gg = *(const f32x4*)(g + c), sc = *(const f32x4*)(mr + scoff + c), sh = *(const f32x4*)(mr + shoff + c);
;                 const f32x4 o = v[r][j] * rstd * gg * (sc + 1.0f) + sh; v2u w; w.x = pk2(o.x, o.y); w.y = pk2(o.z, o.w); *(v2u*)(U + (size_t)m * DM + c) = w; } } }
	v_pk_mul_f32 v[38:39], v[70:71], v[38:39]
	v_pk_fma_f32 v[36:37], v[196:197], v[36:37], v[212:213]
	v_pk_fma_f32 v[38:39], v[198:199], v[38:39], v[214:215]
	v_cvt_pk_bf16_f32 v246, v36, v37
	v_cvt_pk_bf16_f32 v247, v38, v39
	global_store_dwordx4 v82, v[244:247], s[46:47] offset:0
	v_pk_mul_f32 v[40:41], v[40:41], v[236:237] op_sel_hi:[1,0]
	v_pk_mul_f32 v[42:43], v[42:43], v[236:237] op_sel_hi:[1,0]
	v_pk_mul_f32 v[40:41], v[72:73], v[40:41]
	v_pk_mul_f32 v[42:43], v[74:75], v[42:43]
	v_pk_fma_f32 v[40:41], v[200:201], v[40:41], v[216:217]
	v_pk_fma_f32 v[42:43], v[202:203], v[42:43], v[218:219]
	v_cvt_pk_bf16_f32 v240, v40, v41
	v_cvt_pk_bf16_f32 v241, v42, v43
	v_pk_mul_f32 v[44:45], v[44:45], v[236:237] op_sel_hi:[1,0]
	v_pk_mul_f32 v[46:47], v[46:47], v[236:237] op_sel_hi:[1,0]
	v_pk_mul_f32 v[44:45], v[76:77], v[44:45]
	v_pk_mul_f32 v[46:47], v[78:79], v[46:47]
	v_pk_fma_f32 v[44:45], v[204:205], v[44:45], v[220:221]
	v_pk_fma_f32 v[46:47], v[206:207], v[46:47], v[222:223]
	v_cvt_pk_bf16_f32 v242, v44, v45
	v_cvt_pk_bf16_f32 v243, v46, v47
	global_store_dwordx4 v82, v[240:243], s[46:47] offset:1024
	v_pk_mul_f32 v[48:49], v[48:49], v[238:239] op_sel_hi:[1,0]
	v_pk_mul_f32 v[50:51], v[50:51], v[238:239] op_sel_hi:[1,0]
	v_pk_mul_f32 v[48:49], v[64:65], v[48:49]
	v_pk_mul_f32 v[50:51], v[66:67], v[50:51]
	v_pk_fma_f32 v[48:49], v[192:193], v[48:49], v[208:209]
	v_pk_fma_f32 v[50:51], v[194:195], v[50:51], v[210:211]
	v_cvt_pk_bf16_f32 v244, v48, v49
	v_cvt_pk_bf16_f32 v245, v50, v51
	v_pk_mul_f32 v[52:53], v[52:53], v[238:239] op_sel_hi:[1,0]
	v_pk_mul_f32 v[54:55], v[54:55], v[238:239] op_sel_hi:[1,0]
	v_pk_mul_f32 v[52:53], v[68:69], v[52:53]
	v_pk_mul_f32 v[54:55], v[70:71], v[54:55]
	v_pk_fma_f32 v[52:53], v[196:197], v[52:53], v[212:213]
	v_pk_fma_f32 v[54:55], v[198:199], v[54:55], v[214:215]
	v_cvt_pk_bf16_f32 v246, v52, v53
	v_cvt_pk_bf16_f32 v247, v54, v55
	global_store_dwordx4 v82, v[244:247], s[48:49] offset:0
	v_pk_mul_f32 v[56:57], v[56:57], v[238:239] op_sel_hi:[1,0]
	v_pk_mul_f32 v[58:59], v[58:59], v[238:239] op_sel_hi:[1,0]
	v_pk_mul_f32 v[56:57], v[72:73], v[56:57]
	v_pk_mul_f32 v[58:59], v[74:75], v[58:59]
	v_pk_fma_f32 v[56:57], v[200:201], v[56:57], v[216:217]
	v_pk_fma_f32 v[58:59], v[202:203], v[58:59], v[218:219]
	v_cvt_pk_bf16_f32 v240, v56, v57
	v_cvt_pk_bf16_f32 v241, v58, v59
	v_pk_mul_f32 v[60:61], v[60:61], v[238:239] op_sel_hi:[1,0]
	v_pk_mul_f32 v[62:63], v[62:63], v[238:239] op_sel_hi:[1,0]
	v_pk_mul_f32 v[60:61], v[76:77], v[60:61]
	v_pk_mul_f32 v[62:63], v[78:79], v[62:63]
	v_pk_fma_f32 v[60:61], v[204:205], v[60:61], v[220:221]
	v_pk_fma_f32 v[62:63], v[206:207], v[62:63], v[222:223]
	v_cvt_pk_bf16_f32 v242, v60, v61
	v_cvt_pk_bf16_f32 v243, v62, v63
	global_store_dwordx4 v82, v[240:243], s[48:49] offset:1024
	s_branch .LBB0_1178
.Lorig_prep11:
	s_load_dwordx2 s[10:11], s[2:3], 0xc8
	s_load_dwordx2 s[8:9], s[2:3], 0xe8
	v_lshlrev_b32_e32 v0, 2, v8
	v_and_b32_e32 v10, 0xfc, v0
	v_mov_b32_e32 v1, 0
	v_lshlrev_b32_e32 v0, 1, v10
	s_waitcnt lgkmcnt(0)
	v_lshl_add_u64 v[6:7], s[8:9], 0, v[0:1]
	v_mbcnt_lo_u32_b32 v0, -1, 0
	v_mbcnt_hi_u32_b32 v0, -1, v0
	v_and_b32_e32 v4, 64, v0
	v_add_u32_e32 v4, 64, v4
	v_xor_b32_e32 v5, 1, v0
	v_cmp_lt_i32_e32 vcc, v5, v4
	s_mov_b64 s[2:3], 0xf000000
	v_lshl_add_u64 v[2:3], v[6:7], 0, s[2:3]
	v_cndmask_b32_e32 v5, v0, v5, vcc
	v_lshlrev_b32_e32 v63, 2, v5
	v_xor_b32_e32 v5, 2, v0
	v_cmp_lt_i32_e32 vcc, v5, v4
	s_mov_b64 s[2:3], 0x33000000
	v_lshl_add_u64 v[6:7], v[6:7], 0, s[2:3]
	v_cndmask_b32_e32 v5, v0, v5, vcc
	v_lshlrev_b32_e32 v64, 2, v5
	v_xor_b32_e32 v5, 4, v0
	v_cmp_lt_i32_e32 vcc, v5, v4
	s_add_i32 s2, s26, s81
	s_ashr_i32 s3, s2, 31
	v_cndmask_b32_e32 v5, v0, v5, vcc
	v_lshlrev_b32_e32 v65, 2, v5
	v_xor_b32_e32 v5, 8, v0
	v_cmp_lt_i32_e32 vcc, v5, v4
	s_lshl_b32 s4, s70, 5
	s_lshl_b32 s27, s70, 4
	v_cndmask_b32_e32 v5, v0, v5, vcc
	v_lshlrev_b32_e32 v66, 2, v5
	v_xor_b32_e32 v5, 16, v0
	v_cmp_lt_i32_e32 vcc, v5, v4
	s_lshl_b64 s[2:3], s[2:3], 11
	v_or_b32_e32 v12, 0x100, v10
	v_cndmask_b32_e32 v5, v0, v5, vcc
	v_lshlrev_b32_e32 v67, 2, v5
	v_xor_b32_e32 v5, 32, v0
	v_cmp_lt_i32_e32 vcc, v5, v4
	v_or_b32_e32 v14, 0x200, v10
	v_or_b32_e32 v16, 0x300, v10
	v_cndmask_b32_e32 v0, v0, v5, vcc
	v_lshlrev_b32_e32 v68, 2, v0
	v_lshlrev_b32_e32 v0, 2, v10
	v_lshl_add_u64 v[4:5], s[10:11], 0, v[0:1]
	s_add_u32 s10, s8, s2
	s_addc_u32 s11, s9, s3
	s_ashr_i32 s5, s4, 31
	s_lshl_b64 s[12:13], s[4:5], 11
	s_ashr_i32 s3, s7, 31
	s_ashr_i32 s5, s6, 31
	s_add_u32 s2, s7, s6
	s_addc_u32 s3, s3, s5
	s_lshl_b64 s[2:3], s[2:3], 11
	v_and_b32_e32 v0, 63, v8
	s_add_u32 s14, s8, s2
	s_mul_i32 s28, s70, 24
	v_lshlrev_b32_e32 v0, 3, v0
	s_addc_u32 s15, s9, s3
	v_mov_b32_e32 v69, 0x358637bd
	s_mov_b32 s5, 0xf800000
	v_mov_b32_e32 v70, 0x260
	v_lshlrev_b32_e32 v71, 2, v10
	s_mov_b32 s29, 0x33000000
	v_lshlrev_b32_e32 v72, 2, v12
	v_lshlrev_b32_e32 v73, 2, v14
	v_lshlrev_b32_e32 v74, 2, v16
	s_branch .LBB0_1172
